# x-update v2: r==0 wave of each 4-wave group does sample row + 2 prompt rows (sample loads first), others 10 rows
# baseline (speedup 1.0000x reference)
.LBB0_446:
	s_waitcnt lgkmcnt(0)
	v_cndmask_b32_e64 v0, 0, 1, s[24:25]
	v_cmp_ne_u32_e64 s[0:1], 1, v0
	s_andn2_b64 vcc, exec, s[24:25]
	s_nop 0
	v_writelane_b32 v235, s0, 52
	s_barrier
	s_nop 0
	v_writelane_b32 v235, s1, 53
	v_mbcnt_lo_u32_b32 v0, -1, 0
	v_mbcnt_hi_u32_b32 v0, -1, v0
	s_cbranch_vccnz .LBB0_465
	v_lshlrev_b32_e32 v2, 3, v0
	v_ashrrev_i32_e32 v3, 31, v2
	v_readlane_b32 s4, v235, 4
	v_lshlrev_b64 v[4:5], 1, v[2:3]
	v_lshlrev_b64 v[2:3], 2, v[2:3]
	v_readlane_b32 s5, v235, 5
	v_readlane_b32 s6, v235, 6
	v_readlane_b32 s7, v235, 7
	v_readlane_b32 s8, v235, 8
	v_readlane_b32 s9, v235, 9
	v_readlane_b32 s10, v235, 10
	v_readlane_b32 s11, v235, 11
	v_readlane_b32 s12, v235, 12
	v_readlane_b32 s13, v235, 13
	v_readlane_b32 s14, v235, 14
	v_readlane_b32 s15, v235, 15
	v_readlane_b32 s16, v235, 16
	v_readlane_b32 s17, v235, 17
	v_readlane_b32 s18, v235, 18
	v_readlane_b32 s19, v235, 19
	v_lshl_add_u64 v[60:61], s[86:87], 0, v[4:5]
	v_lshl_add_u64 v[62:63], s[90:91], 0, v[2:3]
	v_lshl_add_u64 v[64:65], s[54:55], 0, v[4:5]
	v_lshl_add_u64 v[66:67], s[14:15], 0, v[2:3]
	s_mov_b32 s1, 0
	v_cmp_eq_u32_e64 s[4:5], 0, v0
	s_mov_b64 s[6:7], 0x200000
	s_mov_b64 s[8:9], 0x200800
	s_mov_b64 s[10:11], 0x400000
	s_mov_b64 s[12:13], 0x400800
	s_mov_b64 s[14:15], 0x600000
	s_mov_b64 s[16:17], 0x600800
	s_mov_b64 s[18:19], 0x800000
	s_mov_b32 s48, 0x800000
	s_mov_b64 s[20:21], 0x800800
	s_mov_b64 s[22:23], 0xa00000
	s_mov_b64 s[24:25], 0xa00800
	s_mov_b64 s[26:27], 0xc00000
	s_mov_b64 s[28:29], 0xc00800
	s_mov_b64 s[34:35], 0xe00000
	s_mov_b64 s[36:37], 0xe00800
	v_mov_b32_e32 v104, 0
	v_mov_b32_e32 v105, 0x358637bd
	s_mov_b32 s40, s80
	v_mbcnt_lo_u32_b32 v176, -1, 0
	v_mbcnt_hi_u32_b32 v176, -1, v176
	v_readlane_b32 s98, v235, 49
	v_readlane_b32 s99, v235, 20
	v_readlane_b32 s100, v235, 14
	v_readlane_b32 s101, v235, 15
	s_nop 3
	s_lshr_b32 vcc_lo, s98, 3
	s_and_b32 vcc_hi, vcc_lo, 7
	s_lshr_b32 vcc_lo, vcc_lo, 3
	s_lshl_b32 vcc_lo, vcc_lo, 3
	s_add_i32 vcc_lo, vcc_lo, s99
	s_lshl_b32 s98, vcc_hi, 8
	s_add_i32 s98, s98, vcc_lo
	v_mov_b32_e32 v179, s98
	v_lshlrev_b32_e32 v177, 4, v176
	s_lshl_b32 s99, s98, 11
	v_add_u32_e32 v177, s99, v177
	v_lshlrev_b32_e32 v180, 5, v176
	global_load_dwordx4 v[160:163], v180, s[100:101]
	global_load_dwordx4 v[164:167], v180, s[100:101] offset:16
	global_load_dwordx4 v[168:171], v180, s[100:101] offset:2048
	global_load_dwordx4 v[172:175], v180, s[100:101] offset:2064
	v_mov_b32_e32 v182, 0x358637bd
	v_lshlrev_b32_e32 v237, 2, v179
	v_add_u32_e32 v237, 0x10000, v237
	s_and_b32 s99, s98, 3
	s_cmp_eq_u32 s99, 0
	s_cbranch_scc1 .Lmyxupd_s_0
	s_mul_i32 s100, s99, 0x7ff800
	v_add_u32_e32 v210, s100, v177
	s_mul_i32 s100, s99, 16380
	v_add_u32_e32 v211, s100, v237
	v_add_u32_e32 v178, 0x1800000, v177
	v_add_u32_e32 v181, 0x9e00000, v177
	global_load_dwordx4 v[0:3], v178, s[78:79]
	global_load_dwordx4 v[4:7], v178, s[78:79] offset:1024
	global_load_dwordx4 v[8:11], v181, s[78:79]
	global_load_dwordx4 v[12:15], v181, s[78:79] offset:1024
	v_add_u32_e32 v178, 0x1c00000, v177
	v_add_u32_e32 v181, 0xa200000, v177
	global_load_dwordx4 v[16:19], v178, s[78:79]
	global_load_dwordx4 v[20:23], v178, s[78:79] offset:1024
	global_load_dwordx4 v[24:27], v181, s[78:79]
	global_load_dwordx4 v[28:31], v181, s[78:79] offset:1024
	v_add_u32_e32 v178, 0x2000000, v177
	v_add_u32_e32 v181, 0xa600000, v177
	global_load_dwordx4 v[32:35], v178, s[78:79]
	global_load_dwordx4 v[36:39], v178, s[78:79] offset:1024
	global_load_dwordx4 v[40:43], v181, s[78:79]
	global_load_dwordx4 v[44:47], v181, s[78:79] offset:1024
	v_add_u32_e32 v178, 0x2400000, v177
	v_add_u32_e32 v181, 0xaa00000, v177
	global_load_dwordx4 v[48:51], v178, s[78:79]
	global_load_dwordx4 v[52:55], v178, s[78:79] offset:1024
	global_load_dwordx4 v[56:59], v181, s[78:79]
	global_load_dwordx4 v[60:63], v181, s[78:79] offset:1024
	v_add_u32_e32 v178, 0x2800000, v177
	v_add_u32_e32 v181, 0xae00000, v177
	global_load_dwordx4 v[64:67], v178, s[78:79]
	global_load_dwordx4 v[68:71], v178, s[78:79] offset:1024
	global_load_dwordx4 v[72:75], v181, s[78:79]
	global_load_dwordx4 v[76:79], v181, s[78:79] offset:1024
	v_add_u32_e32 v178, 0x2c00000, v177
	v_add_u32_e32 v181, 0xb200000, v177
	global_load_dwordx4 v[80:83], v178, s[78:79]
	global_load_dwordx4 v[84:87], v178, s[78:79] offset:1024
	global_load_dwordx4 v[88:91], v181, s[78:79]
	global_load_dwordx4 v[92:95], v181, s[78:79] offset:1024
	v_add_u32_e32 v178, 0x3000000, v177
	v_add_u32_e32 v181, 0xb600000, v177
	global_load_dwordx4 v[96:99], v178, s[78:79]
	global_load_dwordx4 v[100:103], v178, s[78:79] offset:1024
	global_load_dwordx4 v[104:107], v181, s[78:79]
	global_load_dwordx4 v[108:111], v181, s[78:79] offset:1024
	v_add_u32_e32 v178, 0x3400000, v177
	v_add_u32_e32 v181, 0xba00000, v177
	global_load_dwordx4 v[112:115], v178, s[78:79]
	global_load_dwordx4 v[116:119], v178, s[78:79] offset:1024
	global_load_dwordx4 v[120:123], v181, s[78:79]
	global_load_dwordx4 v[124:127], v181, s[78:79] offset:1024
	v_add_u32_e32 v178, 0x1800000, v210
	v_add_u32_e32 v181, 0x9e00000, v210
	global_load_dwordx4 v[128:131], v178, s[78:79]
	global_load_dwordx4 v[132:135], v178, s[78:79] offset:1024
	global_load_dwordx4 v[136:139], v181, s[78:79]
	global_load_dwordx4 v[140:143], v181, s[78:79] offset:1024
	v_add_u32_e32 v178, 0x1c00000, v210
	v_add_u32_e32 v181, 0xa200000, v210
	global_load_dwordx4 v[144:147], v178, s[78:79]
	global_load_dwordx4 v[148:151], v178, s[78:79] offset:1024
	global_load_dwordx4 v[152:155], v181, s[78:79]
	global_load_dwordx4 v[156:159], v181, s[78:79] offset:1024
	s_waitcnt vmcnt(36)
	v_lshlrev_b32_e32 v194, 16, v0
	v_and_b32_e32 v195, 0xffff0000, v0
	v_lshlrev_b32_e32 v196, 16, v1
	v_and_b32_e32 v197, 0xffff0000, v1
	v_lshlrev_b32_e32 v198, 16, v2
	v_and_b32_e32 v199, 0xffff0000, v2
	v_lshlrev_b32_e32 v200, 16, v3
	v_and_b32_e32 v201, 0xffff0000, v3
	v_lshlrev_b32_e32 v202, 16, v4
	v_and_b32_e32 v203, 0xffff0000, v4
	v_lshlrev_b32_e32 v204, 16, v5
	v_and_b32_e32 v205, 0xffff0000, v5
	v_lshlrev_b32_e32 v206, 16, v6
	v_and_b32_e32 v207, 0xffff0000, v6
	v_lshlrev_b32_e32 v208, 16, v7
	v_and_b32_e32 v209, 0xffff0000, v7
	v_lshlrev_b32_e32 v216, 16, v8
	v_and_b32_e32 v217, 0xffff0000, v8
	v_lshlrev_b32_e32 v218, 16, v9
	v_and_b32_e32 v219, 0xffff0000, v9
	v_lshlrev_b32_e32 v220, 16, v10
	v_and_b32_e32 v221, 0xffff0000, v10
	v_lshlrev_b32_e32 v222, 16, v11
	v_and_b32_e32 v223, 0xffff0000, v11
	v_lshlrev_b32_e32 v224, 16, v12
	v_and_b32_e32 v225, 0xffff0000, v12
	v_lshlrev_b32_e32 v226, 16, v13
	v_and_b32_e32 v227, 0xffff0000, v13
	v_lshlrev_b32_e32 v228, 16, v14
	v_and_b32_e32 v229, 0xffff0000, v14
	v_lshlrev_b32_e32 v230, 16, v15
	v_and_b32_e32 v231, 0xffff0000, v15
	v_pk_mul_f32 v[252:253], v[216:217], v[216:217]
	v_pk_mul_f32 v[254:255], v[218:219], v[218:219]
	v_pk_fma_f32 v[252:253], v[220:221], v[220:221], v[252:253]
	v_pk_fma_f32 v[254:255], v[222:223], v[222:223], v[254:255]
	v_pk_fma_f32 v[252:253], v[224:225], v[224:225], v[252:253]
	v_pk_fma_f32 v[254:255], v[226:227], v[226:227], v[254:255]
	v_pk_fma_f32 v[252:253], v[228:229], v[228:229], v[252:253]
	v_pk_fma_f32 v[254:255], v[230:231], v[230:231], v[254:255]
	v_pk_add_f32 v[252:253], v[252:253], v[254:255]
	s_nop 0
	v_add_f32_e32 v183, v252, v253
	s_nop 1
	v_add_f32_dpp v183, v183, v183 quad_perm:[1,0,3,2] row_mask:0xf bank_mask:0xf bound_ctrl:1
	s_nop 1
	v_add_f32_dpp v183, v183, v183 quad_perm:[2,3,0,1] row_mask:0xf bank_mask:0xf bound_ctrl:1
	s_nop 1
	v_add_f32_dpp v183, v183, v183 row_half_mirror row_mask:0xf bank_mask:0xf bound_ctrl:1
	s_nop 1
	v_add_f32_dpp v183, v183, v183 row_mirror row_mask:0xf bank_mask:0xf bound_ctrl:1
	s_nop 1
	v_readlane_b32 s98, v183, 0
	v_readlane_b32 s99, v183, 16
	v_readlane_b32 s100, v183, 32
	v_readlane_b32 s101, v183, 48
	s_nop 1
	v_mov_b32_e32 v183, s98
	v_add_f32_e32 v183, s99, v183
	v_add_f32_e32 v183, s100, v183
	v_add_f32_e32 v183, s101, v183
	v_fmamk_f32 v183, v183, 0x3a800000, v182
	v_cmp_gt_f32_e32 vcc, 0x800000, v183
	v_mul_f32_e32 v181, 0x4b800000, v183
	s_nop 1
	v_cndmask_b32_e32 v183, v183, v181, vcc
	v_rsq_f32_e32 v183, v183
	s_nop 0
	v_mul_f32_e32 v181, 0x45800000, v183
	v_cndmask_b32_e32 v184, v183, v181, vcc
	v_mov_b32_e32 v185, v184
	v_pk_mul_f32 v[216:217], v[216:217], v[184:185]
	v_pk_mul_f32 v[218:219], v[218:219], v[184:185]
	v_pk_mul_f32 v[220:221], v[220:221], v[184:185]
	v_pk_mul_f32 v[222:223], v[222:223], v[184:185]
	v_pk_mul_f32 v[224:225], v[224:225], v[184:185]
	v_pk_mul_f32 v[226:227], v[226:227], v[184:185]
	v_pk_mul_f32 v[228:229], v[228:229], v[184:185]
	v_pk_mul_f32 v[230:231], v[230:231], v[184:185]
	v_pk_fma_f32 v[194:195], v[216:217], v[160:161], v[194:195]
	v_pk_fma_f32 v[196:197], v[218:219], v[162:163], v[196:197]
	v_pk_fma_f32 v[198:199], v[220:221], v[164:165], v[198:199]
	v_pk_fma_f32 v[200:201], v[222:223], v[166:167], v[200:201]
	v_pk_fma_f32 v[202:203], v[224:225], v[168:169], v[202:203]
	v_pk_fma_f32 v[204:205], v[226:227], v[170:171], v[204:205]
	v_pk_fma_f32 v[206:207], v[228:229], v[172:173], v[206:207]
	v_pk_fma_f32 v[208:209], v[230:231], v[174:175], v[208:209]
	v_pk_mul_f32 v[252:253], v[194:195], v[194:195]
	v_pk_mul_f32 v[254:255], v[196:197], v[196:197]
	v_pk_fma_f32 v[252:253], v[198:199], v[198:199], v[252:253]
	v_pk_fma_f32 v[254:255], v[200:201], v[200:201], v[254:255]
	v_pk_fma_f32 v[252:253], v[202:203], v[202:203], v[252:253]
	v_pk_fma_f32 v[254:255], v[204:205], v[204:205], v[254:255]
	v_pk_fma_f32 v[252:253], v[206:207], v[206:207], v[252:253]
	v_pk_fma_f32 v[254:255], v[208:209], v[208:209], v[254:255]
	v_pk_add_f32 v[252:253], v[252:253], v[254:255]
	s_nop 0
	v_add_f32_e32 v183, v252, v253
	s_nop 1
	v_add_f32_dpp v183, v183, v183 quad_perm:[1,0,3,2] row_mask:0xf bank_mask:0xf bound_ctrl:1
	s_nop 1
	v_add_f32_dpp v183, v183, v183 quad_perm:[2,3,0,1] row_mask:0xf bank_mask:0xf bound_ctrl:1
	s_nop 1
	v_add_f32_dpp v183, v183, v183 row_half_mirror row_mask:0xf bank_mask:0xf bound_ctrl:1
	s_nop 1
	v_add_f32_dpp v183, v183, v183 row_mirror row_mask:0xf bank_mask:0xf bound_ctrl:1
	s_nop 1
	v_readlane_b32 s98, v183, 0
	v_readlane_b32 s99, v183, 16
	v_readlane_b32 s100, v183, 32
	v_readlane_b32 s101, v183, 48
	s_nop 1
	v_mov_b32_e32 v183, s98
	v_add_f32_e32 v183, s99, v183
	v_add_f32_e32 v183, s100, v183
	v_add_f32_e32 v183, s101, v183
	v_fmamk_f32 v183, v183, 0x3a800000, v182
	v_cmp_gt_f32_e32 vcc, 0x800000, v183
	v_mul_f32_e32 v181, 0x4b800000, v183
	s_nop 1
	v_cndmask_b32_e32 v183, v183, v181, vcc
	v_rsq_f32_e32 v183, v183
	s_nop 0
	v_mul_f32_e32 v181, 0x45800000, v183
	v_cndmask_b32_e32 v184, v183, v181, vcc
	v_mov_b32_e32 v185, v184
	v_cvt_pk_bf16_f32 v0, v194, v195
	v_cvt_pk_bf16_f32 v1, v196, v197
	v_cvt_pk_bf16_f32 v2, v198, v199
	v_cvt_pk_bf16_f32 v3, v200, v201
	v_cvt_pk_bf16_f32 v4, v202, v203
	v_cvt_pk_bf16_f32 v5, v204, v205
	v_cvt_pk_bf16_f32 v6, v206, v207
	v_cvt_pk_bf16_f32 v7, v208, v209
	v_add_u32_e32 v181, 0x1800000, v177
	global_store_dwordx4 v181, v[0:3], s[78:79]
	global_store_dwordx4 v181, v[4:7], s[78:79] offset:1024
	v_add_u32_e32 v236, 0x0, v237
	s_mov_b64 exec, 1
	global_store_dword v236, v184, s[78:79]
	s_mov_b64 exec, -1
	s_waitcnt vmcnt(32)
	v_lshlrev_b32_e32 v194, 16, v16
	v_and_b32_e32 v195, 0xffff0000, v16
	v_lshlrev_b32_e32 v196, 16, v17
	v_and_b32_e32 v197, 0xffff0000, v17
	v_lshlrev_b32_e32 v198, 16, v18
	v_and_b32_e32 v199, 0xffff0000, v18
	v_lshlrev_b32_e32 v200, 16, v19
	v_and_b32_e32 v201, 0xffff0000, v19
	v_lshlrev_b32_e32 v202, 16, v20
	v_and_b32_e32 v203, 0xffff0000, v20
	v_lshlrev_b32_e32 v204, 16, v21
	v_and_b32_e32 v205, 0xffff0000, v21
	v_lshlrev_b32_e32 v206, 16, v22
	v_and_b32_e32 v207, 0xffff0000, v22
	v_lshlrev_b32_e32 v208, 16, v23
	v_and_b32_e32 v209, 0xffff0000, v23
	v_lshlrev_b32_e32 v216, 16, v24
	v_and_b32_e32 v217, 0xffff0000, v24
	v_lshlrev_b32_e32 v218, 16, v25
	v_and_b32_e32 v219, 0xffff0000, v25
	v_lshlrev_b32_e32 v220, 16, v26
	v_and_b32_e32 v221, 0xffff0000, v26
	v_lshlrev_b32_e32 v222, 16, v27
	v_and_b32_e32 v223, 0xffff0000, v27
	v_lshlrev_b32_e32 v224, 16, v28
	v_and_b32_e32 v225, 0xffff0000, v28
	v_lshlrev_b32_e32 v226, 16, v29
	v_and_b32_e32 v227, 0xffff0000, v29
	v_lshlrev_b32_e32 v228, 16, v30
	v_and_b32_e32 v229, 0xffff0000, v30
	v_lshlrev_b32_e32 v230, 16, v31
	v_and_b32_e32 v231, 0xffff0000, v31
	v_pk_mul_f32 v[252:253], v[216:217], v[216:217]
	v_pk_mul_f32 v[254:255], v[218:219], v[218:219]
	v_pk_fma_f32 v[252:253], v[220:221], v[220:221], v[252:253]
	v_pk_fma_f32 v[254:255], v[222:223], v[222:223], v[254:255]
	v_pk_fma_f32 v[252:253], v[224:225], v[224:225], v[252:253]
	v_pk_fma_f32 v[254:255], v[226:227], v[226:227], v[254:255]
	v_pk_fma_f32 v[252:253], v[228:229], v[228:229], v[252:253]
	v_pk_fma_f32 v[254:255], v[230:231], v[230:231], v[254:255]
	v_pk_add_f32 v[252:253], v[252:253], v[254:255]
	s_nop 0
	v_add_f32_e32 v183, v252, v253
	s_nop 1
	v_add_f32_dpp v183, v183, v183 quad_perm:[1,0,3,2] row_mask:0xf bank_mask:0xf bound_ctrl:1
	s_nop 1
	v_add_f32_dpp v183, v183, v183 quad_perm:[2,3,0,1] row_mask:0xf bank_mask:0xf bound_ctrl:1
	s_nop 1
	v_add_f32_dpp v183, v183, v183 row_half_mirror row_mask:0xf bank_mask:0xf bound_ctrl:1
	s_nop 1
	v_add_f32_dpp v183, v183, v183 row_mirror row_mask:0xf bank_mask:0xf bound_ctrl:1
	s_nop 1
	v_readlane_b32 s98, v183, 0
	v_readlane_b32 s99, v183, 16
	v_readlane_b32 s100, v183, 32
	v_readlane_b32 s101, v183, 48
	s_nop 1
	v_mov_b32_e32 v183, s98
	v_add_f32_e32 v183, s99, v183
	v_add_f32_e32 v183, s100, v183
	v_add_f32_e32 v183, s101, v183
	v_fmamk_f32 v183, v183, 0x3a800000, v182
	v_cmp_gt_f32_e32 vcc, 0x800000, v183
	v_mul_f32_e32 v181, 0x4b800000, v183
	s_nop 1
	v_cndmask_b32_e32 v183, v183, v181, vcc
	v_rsq_f32_e32 v183, v183
	s_nop 0
	v_mul_f32_e32 v181, 0x45800000, v183
	v_cndmask_b32_e32 v184, v183, v181, vcc
	v_mov_b32_e32 v185, v184
	v_pk_mul_f32 v[216:217], v[216:217], v[184:185]
	v_pk_mul_f32 v[218:219], v[218:219], v[184:185]
	v_pk_mul_f32 v[220:221], v[220:221], v[184:185]
	v_pk_mul_f32 v[222:223], v[222:223], v[184:185]
	v_pk_mul_f32 v[224:225], v[224:225], v[184:185]
	v_pk_mul_f32 v[226:227], v[226:227], v[184:185]
	v_pk_mul_f32 v[228:229], v[228:229], v[184:185]
	v_pk_mul_f32 v[230:231], v[230:231], v[184:185]
	v_pk_fma_f32 v[194:195], v[216:217], v[160:161], v[194:195]
	v_pk_fma_f32 v[196:197], v[218:219], v[162:163], v[196:197]
	v_pk_fma_f32 v[198:199], v[220:221], v[164:165], v[198:199]
	v_pk_fma_f32 v[200:201], v[222:223], v[166:167], v[200:201]
	v_pk_fma_f32 v[202:203], v[224:225], v[168:169], v[202:203]
	v_pk_fma_f32 v[204:205], v[226:227], v[170:171], v[204:205]
	v_pk_fma_f32 v[206:207], v[228:229], v[172:173], v[206:207]
	v_pk_fma_f32 v[208:209], v[230:231], v[174:175], v[208:209]
	v_pk_mul_f32 v[252:253], v[194:195], v[194:195]
	v_pk_mul_f32 v[254:255], v[196:197], v[196:197]
	v_pk_fma_f32 v[252:253], v[198:199], v[198:199], v[252:253]
	v_pk_fma_f32 v[254:255], v[200:201], v[200:201], v[254:255]
	v_pk_fma_f32 v[252:253], v[202:203], v[202:203], v[252:253]
	v_pk_fma_f32 v[254:255], v[204:205], v[204:205], v[254:255]
	v_pk_fma_f32 v[252:253], v[206:207], v[206:207], v[252:253]
	v_pk_fma_f32 v[254:255], v[208:209], v[208:209], v[254:255]
	v_pk_add_f32 v[252:253], v[252:253], v[254:255]
	s_nop 0
	v_add_f32_e32 v183, v252, v253
	s_nop 1
	v_add_f32_dpp v183, v183, v183 quad_perm:[1,0,3,2] row_mask:0xf bank_mask:0xf bound_ctrl:1
	s_nop 1
	v_add_f32_dpp v183, v183, v183 quad_perm:[2,3,0,1] row_mask:0xf bank_mask:0xf bound_ctrl:1
	s_nop 1
	v_add_f32_dpp v183, v183, v183 row_half_mirror row_mask:0xf bank_mask:0xf bound_ctrl:1
	s_nop 1
	v_add_f32_dpp v183, v183, v183 row_mirror row_mask:0xf bank_mask:0xf bound_ctrl:1
	s_nop 1
	v_readlane_b32 s98, v183, 0
	v_readlane_b32 s99, v183, 16
	v_readlane_b32 s100, v183, 32
	v_readlane_b32 s101, v183, 48
	s_nop 1
	v_mov_b32_e32 v183, s98
	v_add_f32_e32 v183, s99, v183
	v_add_f32_e32 v183, s100, v183
	v_add_f32_e32 v183, s101, v183
	v_fmamk_f32 v183, v183, 0x3a800000, v182
	v_cmp_gt_f32_e32 vcc, 0x800000, v183
	v_mul_f32_e32 v181, 0x4b800000, v183
	s_nop 1
	v_cndmask_b32_e32 v183, v183, v181, vcc
	v_rsq_f32_e32 v183, v183
	s_nop 0
	v_mul_f32_e32 v181, 0x45800000, v183
	v_cndmask_b32_e32 v184, v183, v181, vcc
	v_mov_b32_e32 v185, v184
	v_cvt_pk_bf16_f32 v16, v194, v195
	v_cvt_pk_bf16_f32 v17, v196, v197
	v_cvt_pk_bf16_f32 v18, v198, v199
	v_cvt_pk_bf16_f32 v19, v200, v201
	v_cvt_pk_bf16_f32 v20, v202, v203
	v_cvt_pk_bf16_f32 v21, v204, v205
	v_cvt_pk_bf16_f32 v22, v206, v207
	v_cvt_pk_bf16_f32 v23, v208, v209
	v_add_u32_e32 v181, 0x1c00000, v177
	global_store_dwordx4 v181, v[16:19], s[78:79]
	global_store_dwordx4 v181, v[20:23], s[78:79] offset:1024
	v_add_u32_e32 v236, 0x2000, v237
	s_mov_b64 exec, 1
	global_store_dword v236, v184, s[78:79]
	s_mov_b64 exec, -1
	s_waitcnt vmcnt(28)
	v_lshlrev_b32_e32 v194, 16, v32
	v_and_b32_e32 v195, 0xffff0000, v32
	v_lshlrev_b32_e32 v196, 16, v33
	v_and_b32_e32 v197, 0xffff0000, v33
	v_lshlrev_b32_e32 v198, 16, v34
	v_and_b32_e32 v199, 0xffff0000, v34
	v_lshlrev_b32_e32 v200, 16, v35
	v_and_b32_e32 v201, 0xffff0000, v35
	v_lshlrev_b32_e32 v202, 16, v36
	v_and_b32_e32 v203, 0xffff0000, v36
	v_lshlrev_b32_e32 v204, 16, v37
	v_and_b32_e32 v205, 0xffff0000, v37
	v_lshlrev_b32_e32 v206, 16, v38
	v_and_b32_e32 v207, 0xffff0000, v38
	v_lshlrev_b32_e32 v208, 16, v39
	v_and_b32_e32 v209, 0xffff0000, v39
	v_lshlrev_b32_e32 v216, 16, v40
	v_and_b32_e32 v217, 0xffff0000, v40
	v_lshlrev_b32_e32 v218, 16, v41
	v_and_b32_e32 v219, 0xffff0000, v41
	v_lshlrev_b32_e32 v220, 16, v42
	v_and_b32_e32 v221, 0xffff0000, v42
	v_lshlrev_b32_e32 v222, 16, v43
	v_and_b32_e32 v223, 0xffff0000, v43
	v_lshlrev_b32_e32 v224, 16, v44
	v_and_b32_e32 v225, 0xffff0000, v44
	v_lshlrev_b32_e32 v226, 16, v45
	v_and_b32_e32 v227, 0xffff0000, v45
	v_lshlrev_b32_e32 v228, 16, v46
	v_and_b32_e32 v229, 0xffff0000, v46
	v_lshlrev_b32_e32 v230, 16, v47
	v_and_b32_e32 v231, 0xffff0000, v47
	v_pk_mul_f32 v[252:253], v[216:217], v[216:217]
	v_pk_mul_f32 v[254:255], v[218:219], v[218:219]
	v_pk_fma_f32 v[252:253], v[220:221], v[220:221], v[252:253]
	v_pk_fma_f32 v[254:255], v[222:223], v[222:223], v[254:255]
	v_pk_fma_f32 v[252:253], v[224:225], v[224:225], v[252:253]
	v_pk_fma_f32 v[254:255], v[226:227], v[226:227], v[254:255]
	v_pk_fma_f32 v[252:253], v[228:229], v[228:229], v[252:253]
	v_pk_fma_f32 v[254:255], v[230:231], v[230:231], v[254:255]
	v_pk_add_f32 v[252:253], v[252:253], v[254:255]
	s_nop 0
	v_add_f32_e32 v183, v252, v253
	s_nop 1
	v_add_f32_dpp v183, v183, v183 quad_perm:[1,0,3,2] row_mask:0xf bank_mask:0xf bound_ctrl:1
	s_nop 1
	v_add_f32_dpp v183, v183, v183 quad_perm:[2,3,0,1] row_mask:0xf bank_mask:0xf bound_ctrl:1
	s_nop 1
	v_add_f32_dpp v183, v183, v183 row_half_mirror row_mask:0xf bank_mask:0xf bound_ctrl:1
	s_nop 1
	v_add_f32_dpp v183, v183, v183 row_mirror row_mask:0xf bank_mask:0xf bound_ctrl:1
	s_nop 1
	v_readlane_b32 s98, v183, 0
	v_readlane_b32 s99, v183, 16
	v_readlane_b32 s100, v183, 32
	v_readlane_b32 s101, v183, 48
	s_nop 1
	v_mov_b32_e32 v183, s98
	v_add_f32_e32 v183, s99, v183
	v_add_f32_e32 v183, s100, v183
	v_add_f32_e32 v183, s101, v183
	v_fmamk_f32 v183, v183, 0x3a800000, v182
	v_cmp_gt_f32_e32 vcc, 0x800000, v183
	v_mul_f32_e32 v181, 0x4b800000, v183
	s_nop 1
	v_cndmask_b32_e32 v183, v183, v181, vcc
	v_rsq_f32_e32 v183, v183
	s_nop 0
	v_mul_f32_e32 v181, 0x45800000, v183
	v_cndmask_b32_e32 v184, v183, v181, vcc
	v_mov_b32_e32 v185, v184
	v_pk_mul_f32 v[216:217], v[216:217], v[184:185]
	v_pk_mul_f32 v[218:219], v[218:219], v[184:185]
	v_pk_mul_f32 v[220:221], v[220:221], v[184:185]
	v_pk_mul_f32 v[222:223], v[222:223], v[184:185]
	v_pk_mul_f32 v[224:225], v[224:225], v[184:185]
	v_pk_mul_f32 v[226:227], v[226:227], v[184:185]
	v_pk_mul_f32 v[228:229], v[228:229], v[184:185]
	v_pk_mul_f32 v[230:231], v[230:231], v[184:185]
	v_pk_fma_f32 v[194:195], v[216:217], v[160:161], v[194:195]
	v_pk_fma_f32 v[196:197], v[218:219], v[162:163], v[196:197]
	v_pk_fma_f32 v[198:199], v[220:221], v[164:165], v[198:199]
	v_pk_fma_f32 v[200:201], v[222:223], v[166:167], v[200:201]
	v_pk_fma_f32 v[202:203], v[224:225], v[168:169], v[202:203]
	v_pk_fma_f32 v[204:205], v[226:227], v[170:171], v[204:205]
	v_pk_fma_f32 v[206:207], v[228:229], v[172:173], v[206:207]
	v_pk_fma_f32 v[208:209], v[230:231], v[174:175], v[208:209]
	v_pk_mul_f32 v[252:253], v[194:195], v[194:195]
	v_pk_mul_f32 v[254:255], v[196:197], v[196:197]
	v_pk_fma_f32 v[252:253], v[198:199], v[198:199], v[252:253]
	v_pk_fma_f32 v[254:255], v[200:201], v[200:201], v[254:255]
	v_pk_fma_f32 v[252:253], v[202:203], v[202:203], v[252:253]
	v_pk_fma_f32 v[254:255], v[204:205], v[204:205], v[254:255]
	v_pk_fma_f32 v[252:253], v[206:207], v[206:207], v[252:253]
	v_pk_fma_f32 v[254:255], v[208:209], v[208:209], v[254:255]
	v_pk_add_f32 v[252:253], v[252:253], v[254:255]
	s_nop 0
	v_add_f32_e32 v183, v252, v253
	s_nop 1
	v_add_f32_dpp v183, v183, v183 quad_perm:[1,0,3,2] row_mask:0xf bank_mask:0xf bound_ctrl:1
	s_nop 1
	v_add_f32_dpp v183, v183, v183 quad_perm:[2,3,0,1] row_mask:0xf bank_mask:0xf bound_ctrl:1
	s_nop 1
	v_add_f32_dpp v183, v183, v183 row_half_mirror row_mask:0xf bank_mask:0xf bound_ctrl:1
	s_nop 1
	v_add_f32_dpp v183, v183, v183 row_mirror row_mask:0xf bank_mask:0xf bound_ctrl:1
	s_nop 1
	v_readlane_b32 s98, v183, 0
	v_readlane_b32 s99, v183, 16
	v_readlane_b32 s100, v183, 32
	v_readlane_b32 s101, v183, 48
	s_nop 1
	v_mov_b32_e32 v183, s98
	v_add_f32_e32 v183, s99, v183
	v_add_f32_e32 v183, s100, v183
	v_add_f32_e32 v183, s101, v183
	v_fmamk_f32 v183, v183, 0x3a800000, v182
	v_cmp_gt_f32_e32 vcc, 0x800000, v183
	v_mul_f32_e32 v181, 0x4b800000, v183
	s_nop 1
	v_cndmask_b32_e32 v183, v183, v181, vcc
	v_rsq_f32_e32 v183, v183
	s_nop 0
	v_mul_f32_e32 v181, 0x45800000, v183
	v_cndmask_b32_e32 v184, v183, v181, vcc
	v_mov_b32_e32 v185, v184
	v_cvt_pk_bf16_f32 v32, v194, v195
	v_cvt_pk_bf16_f32 v33, v196, v197
	v_cvt_pk_bf16_f32 v34, v198, v199
	v_cvt_pk_bf16_f32 v35, v200, v201
	v_cvt_pk_bf16_f32 v36, v202, v203
	v_cvt_pk_bf16_f32 v37, v204, v205
	v_cvt_pk_bf16_f32 v38, v206, v207
	v_cvt_pk_bf16_f32 v39, v208, v209
	v_add_u32_e32 v181, 0x2000000, v177
	global_store_dwordx4 v181, v[32:35], s[78:79]
	global_store_dwordx4 v181, v[36:39], s[78:79] offset:1024
	v_add_u32_e32 v236, 0x4000, v237
	s_mov_b64 exec, 1
	global_store_dword v236, v184, s[78:79]
	s_mov_b64 exec, -1
	s_waitcnt vmcnt(24)
	v_lshlrev_b32_e32 v194, 16, v48
	v_and_b32_e32 v195, 0xffff0000, v48
	v_lshlrev_b32_e32 v196, 16, v49
	v_and_b32_e32 v197, 0xffff0000, v49
	v_lshlrev_b32_e32 v198, 16, v50
	v_and_b32_e32 v199, 0xffff0000, v50
	v_lshlrev_b32_e32 v200, 16, v51
	v_and_b32_e32 v201, 0xffff0000, v51
	v_lshlrev_b32_e32 v202, 16, v52
	v_and_b32_e32 v203, 0xffff0000, v52
	v_lshlrev_b32_e32 v204, 16, v53
	v_and_b32_e32 v205, 0xffff0000, v53
	v_lshlrev_b32_e32 v206, 16, v54
	v_and_b32_e32 v207, 0xffff0000, v54
	v_lshlrev_b32_e32 v208, 16, v55
	v_and_b32_e32 v209, 0xffff0000, v55
	v_lshlrev_b32_e32 v216, 16, v56
	v_and_b32_e32 v217, 0xffff0000, v56
	v_lshlrev_b32_e32 v218, 16, v57
	v_and_b32_e32 v219, 0xffff0000, v57
	v_lshlrev_b32_e32 v220, 16, v58
	v_and_b32_e32 v221, 0xffff0000, v58
	v_lshlrev_b32_e32 v222, 16, v59
	v_and_b32_e32 v223, 0xffff0000, v59
	v_lshlrev_b32_e32 v224, 16, v60
	v_and_b32_e32 v225, 0xffff0000, v60
	v_lshlrev_b32_e32 v226, 16, v61
	v_and_b32_e32 v227, 0xffff0000, v61
	v_lshlrev_b32_e32 v228, 16, v62
	v_and_b32_e32 v229, 0xffff0000, v62
	v_lshlrev_b32_e32 v230, 16, v63
	v_and_b32_e32 v231, 0xffff0000, v63
	v_pk_mul_f32 v[252:253], v[216:217], v[216:217]
	v_pk_mul_f32 v[254:255], v[218:219], v[218:219]
	v_pk_fma_f32 v[252:253], v[220:221], v[220:221], v[252:253]
	v_pk_fma_f32 v[254:255], v[222:223], v[222:223], v[254:255]
	v_pk_fma_f32 v[252:253], v[224:225], v[224:225], v[252:253]
	v_pk_fma_f32 v[254:255], v[226:227], v[226:227], v[254:255]
	v_pk_fma_f32 v[252:253], v[228:229], v[228:229], v[252:253]
	v_pk_fma_f32 v[254:255], v[230:231], v[230:231], v[254:255]
	v_pk_add_f32 v[252:253], v[252:253], v[254:255]
	s_nop 0
	v_add_f32_e32 v183, v252, v253
	s_nop 1
	v_add_f32_dpp v183, v183, v183 quad_perm:[1,0,3,2] row_mask:0xf bank_mask:0xf bound_ctrl:1
	s_nop 1
	v_add_f32_dpp v183, v183, v183 quad_perm:[2,3,0,1] row_mask:0xf bank_mask:0xf bound_ctrl:1
	s_nop 1
	v_add_f32_dpp v183, v183, v183 row_half_mirror row_mask:0xf bank_mask:0xf bound_ctrl:1
	s_nop 1
	v_add_f32_dpp v183, v183, v183 row_mirror row_mask:0xf bank_mask:0xf bound_ctrl:1
	s_nop 1
	v_readlane_b32 s98, v183, 0
	v_readlane_b32 s99, v183, 16
	v_readlane_b32 s100, v183, 32
	v_readlane_b32 s101, v183, 48
	s_nop 1
	v_mov_b32_e32 v183, s98
	v_add_f32_e32 v183, s99, v183
	v_add_f32_e32 v183, s100, v183
	v_add_f32_e32 v183, s101, v183
	v_fmamk_f32 v183, v183, 0x3a800000, v182
	v_cmp_gt_f32_e32 vcc, 0x800000, v183
	v_mul_f32_e32 v181, 0x4b800000, v183
	s_nop 1
	v_cndmask_b32_e32 v183, v183, v181, vcc
	v_rsq_f32_e32 v183, v183
	s_nop 0
	v_mul_f32_e32 v181, 0x45800000, v183
	v_cndmask_b32_e32 v184, v183, v181, vcc
	v_mov_b32_e32 v185, v184
	v_pk_mul_f32 v[216:217], v[216:217], v[184:185]
	v_pk_mul_f32 v[218:219], v[218:219], v[184:185]
	v_pk_mul_f32 v[220:221], v[220:221], v[184:185]
	v_pk_mul_f32 v[222:223], v[222:223], v[184:185]
	v_pk_mul_f32 v[224:225], v[224:225], v[184:185]
	v_pk_mul_f32 v[226:227], v[226:227], v[184:185]
	v_pk_mul_f32 v[228:229], v[228:229], v[184:185]
	v_pk_mul_f32 v[230:231], v[230:231], v[184:185]
	v_pk_fma_f32 v[194:195], v[216:217], v[160:161], v[194:195]
	v_pk_fma_f32 v[196:197], v[218:219], v[162:163], v[196:197]
	v_pk_fma_f32 v[198:199], v[220:221], v[164:165], v[198:199]
	v_pk_fma_f32 v[200:201], v[222:223], v[166:167], v[200:201]
	v_pk_fma_f32 v[202:203], v[224:225], v[168:169], v[202:203]
	v_pk_fma_f32 v[204:205], v[226:227], v[170:171], v[204:205]
	v_pk_fma_f32 v[206:207], v[228:229], v[172:173], v[206:207]
	v_pk_fma_f32 v[208:209], v[230:231], v[174:175], v[208:209]
	v_pk_mul_f32 v[252:253], v[194:195], v[194:195]
	v_pk_mul_f32 v[254:255], v[196:197], v[196:197]
	v_pk_fma_f32 v[252:253], v[198:199], v[198:199], v[252:253]
	v_pk_fma_f32 v[254:255], v[200:201], v[200:201], v[254:255]
	v_pk_fma_f32 v[252:253], v[202:203], v[202:203], v[252:253]
	v_pk_fma_f32 v[254:255], v[204:205], v[204:205], v[254:255]
	v_pk_fma_f32 v[252:253], v[206:207], v[206:207], v[252:253]
	v_pk_fma_f32 v[254:255], v[208:209], v[208:209], v[254:255]
	v_pk_add_f32 v[252:253], v[252:253], v[254:255]
	s_nop 0
	v_add_f32_e32 v183, v252, v253
	s_nop 1
	v_add_f32_dpp v183, v183, v183 quad_perm:[1,0,3,2] row_mask:0xf bank_mask:0xf bound_ctrl:1
	s_nop 1
	v_add_f32_dpp v183, v183, v183 quad_perm:[2,3,0,1] row_mask:0xf bank_mask:0xf bound_ctrl:1
	s_nop 1
	v_add_f32_dpp v183, v183, v183 row_half_mirror row_mask:0xf bank_mask:0xf bound_ctrl:1
	s_nop 1
	v_add_f32_dpp v183, v183, v183 row_mirror row_mask:0xf bank_mask:0xf bound_ctrl:1
	s_nop 1
	v_readlane_b32 s98, v183, 0
	v_readlane_b32 s99, v183, 16
	v_readlane_b32 s100, v183, 32
	v_readlane_b32 s101, v183, 48
	s_nop 1
	v_mov_b32_e32 v183, s98
	v_add_f32_e32 v183, s99, v183
	v_add_f32_e32 v183, s100, v183
	v_add_f32_e32 v183, s101, v183
	v_fmamk_f32 v183, v183, 0x3a800000, v182
	v_cmp_gt_f32_e32 vcc, 0x800000, v183
	v_mul_f32_e32 v181, 0x4b800000, v183
	s_nop 1
	v_cndmask_b32_e32 v183, v183, v181, vcc
	v_rsq_f32_e32 v183, v183
	s_nop 0
	v_mul_f32_e32 v181, 0x45800000, v183
	v_cndmask_b32_e32 v184, v183, v181, vcc
	v_mov_b32_e32 v185, v184
	v_cvt_pk_bf16_f32 v48, v194, v195
	v_cvt_pk_bf16_f32 v49, v196, v197
	v_cvt_pk_bf16_f32 v50, v198, v199
	v_cvt_pk_bf16_f32 v51, v200, v201
	v_cvt_pk_bf16_f32 v52, v202, v203
	v_cvt_pk_bf16_f32 v53, v204, v205
	v_cvt_pk_bf16_f32 v54, v206, v207
	v_cvt_pk_bf16_f32 v55, v208, v209
	v_add_u32_e32 v181, 0x2400000, v177
	global_store_dwordx4 v181, v[48:51], s[78:79]
	global_store_dwordx4 v181, v[52:55], s[78:79] offset:1024
	v_add_u32_e32 v236, 0x6000, v237
	s_mov_b64 exec, 1
	global_store_dword v236, v184, s[78:79]
	s_mov_b64 exec, -1
	s_waitcnt vmcnt(20)
	v_lshlrev_b32_e32 v194, 16, v64
	v_and_b32_e32 v195, 0xffff0000, v64
	v_lshlrev_b32_e32 v196, 16, v65
	v_and_b32_e32 v197, 0xffff0000, v65
	v_lshlrev_b32_e32 v198, 16, v66
	v_and_b32_e32 v199, 0xffff0000, v66
	v_lshlrev_b32_e32 v200, 16, v67
	v_and_b32_e32 v201, 0xffff0000, v67
	v_lshlrev_b32_e32 v202, 16, v68
	v_and_b32_e32 v203, 0xffff0000, v68
	v_lshlrev_b32_e32 v204, 16, v69
	v_and_b32_e32 v205, 0xffff0000, v69
	v_lshlrev_b32_e32 v206, 16, v70
	v_and_b32_e32 v207, 0xffff0000, v70
	v_lshlrev_b32_e32 v208, 16, v71
	v_and_b32_e32 v209, 0xffff0000, v71
	v_lshlrev_b32_e32 v216, 16, v72
	v_and_b32_e32 v217, 0xffff0000, v72
	v_lshlrev_b32_e32 v218, 16, v73
	v_and_b32_e32 v219, 0xffff0000, v73
	v_lshlrev_b32_e32 v220, 16, v74
	v_and_b32_e32 v221, 0xffff0000, v74
	v_lshlrev_b32_e32 v222, 16, v75
	v_and_b32_e32 v223, 0xffff0000, v75
	v_lshlrev_b32_e32 v224, 16, v76
	v_and_b32_e32 v225, 0xffff0000, v76
	v_lshlrev_b32_e32 v226, 16, v77
	v_and_b32_e32 v227, 0xffff0000, v77
	v_lshlrev_b32_e32 v228, 16, v78
	v_and_b32_e32 v229, 0xffff0000, v78
	v_lshlrev_b32_e32 v230, 16, v79
	v_and_b32_e32 v231, 0xffff0000, v79
	v_pk_mul_f32 v[252:253], v[216:217], v[216:217]
	v_pk_mul_f32 v[254:255], v[218:219], v[218:219]
	v_pk_fma_f32 v[252:253], v[220:221], v[220:221], v[252:253]
	v_pk_fma_f32 v[254:255], v[222:223], v[222:223], v[254:255]
	v_pk_fma_f32 v[252:253], v[224:225], v[224:225], v[252:253]
	v_pk_fma_f32 v[254:255], v[226:227], v[226:227], v[254:255]
	v_pk_fma_f32 v[252:253], v[228:229], v[228:229], v[252:253]
	v_pk_fma_f32 v[254:255], v[230:231], v[230:231], v[254:255]
	v_pk_add_f32 v[252:253], v[252:253], v[254:255]
	s_nop 0
	v_add_f32_e32 v183, v252, v253
	s_nop 1
	v_add_f32_dpp v183, v183, v183 quad_perm:[1,0,3,2] row_mask:0xf bank_mask:0xf bound_ctrl:1
	s_nop 1
	v_add_f32_dpp v183, v183, v183 quad_perm:[2,3,0,1] row_mask:0xf bank_mask:0xf bound_ctrl:1
	s_nop 1
	v_add_f32_dpp v183, v183, v183 row_half_mirror row_mask:0xf bank_mask:0xf bound_ctrl:1
	s_nop 1
	v_add_f32_dpp v183, v183, v183 row_mirror row_mask:0xf bank_mask:0xf bound_ctrl:1
	s_nop 1
	v_readlane_b32 s98, v183, 0
	v_readlane_b32 s99, v183, 16
	v_readlane_b32 s100, v183, 32
	v_readlane_b32 s101, v183, 48
	s_nop 1
	v_mov_b32_e32 v183, s98
	v_add_f32_e32 v183, s99, v183
	v_add_f32_e32 v183, s100, v183
	v_add_f32_e32 v183, s101, v183
	v_fmamk_f32 v183, v183, 0x3a800000, v182
	v_cmp_gt_f32_e32 vcc, 0x800000, v183
	v_mul_f32_e32 v181, 0x4b800000, v183
	s_nop 1
	v_cndmask_b32_e32 v183, v183, v181, vcc
	v_rsq_f32_e32 v183, v183
	s_nop 0
	v_mul_f32_e32 v181, 0x45800000, v183
	v_cndmask_b32_e32 v184, v183, v181, vcc
	v_mov_b32_e32 v185, v184
	v_pk_mul_f32 v[216:217], v[216:217], v[184:185]
	v_pk_mul_f32 v[218:219], v[218:219], v[184:185]
	v_pk_mul_f32 v[220:221], v[220:221], v[184:185]
	v_pk_mul_f32 v[222:223], v[222:223], v[184:185]
	v_pk_mul_f32 v[224:225], v[224:225], v[184:185]
	v_pk_mul_f32 v[226:227], v[226:227], v[184:185]
	v_pk_mul_f32 v[228:229], v[228:229], v[184:185]
	v_pk_mul_f32 v[230:231], v[230:231], v[184:185]
	v_pk_fma_f32 v[194:195], v[216:217], v[160:161], v[194:195]
	v_pk_fma_f32 v[196:197], v[218:219], v[162:163], v[196:197]
	v_pk_fma_f32 v[198:199], v[220:221], v[164:165], v[198:199]
	v_pk_fma_f32 v[200:201], v[222:223], v[166:167], v[200:201]
	v_pk_fma_f32 v[202:203], v[224:225], v[168:169], v[202:203]
	v_pk_fma_f32 v[204:205], v[226:227], v[170:171], v[204:205]
	v_pk_fma_f32 v[206:207], v[228:229], v[172:173], v[206:207]
	v_pk_fma_f32 v[208:209], v[230:231], v[174:175], v[208:209]
	v_pk_mul_f32 v[252:253], v[194:195], v[194:195]
	v_pk_mul_f32 v[254:255], v[196:197], v[196:197]
	v_pk_fma_f32 v[252:253], v[198:199], v[198:199], v[252:253]
	v_pk_fma_f32 v[254:255], v[200:201], v[200:201], v[254:255]
	v_pk_fma_f32 v[252:253], v[202:203], v[202:203], v[252:253]
	v_pk_fma_f32 v[254:255], v[204:205], v[204:205], v[254:255]
	v_pk_fma_f32 v[252:253], v[206:207], v[206:207], v[252:253]
	v_pk_fma_f32 v[254:255], v[208:209], v[208:209], v[254:255]
	v_pk_add_f32 v[252:253], v[252:253], v[254:255]
	s_nop 0
	v_add_f32_e32 v183, v252, v253
	s_nop 1
	v_add_f32_dpp v183, v183, v183 quad_perm:[1,0,3,2] row_mask:0xf bank_mask:0xf bound_ctrl:1
	s_nop 1
	v_add_f32_dpp v183, v183, v183 quad_perm:[2,3,0,1] row_mask:0xf bank_mask:0xf bound_ctrl:1
	s_nop 1
	v_add_f32_dpp v183, v183, v183 row_half_mirror row_mask:0xf bank_mask:0xf bound_ctrl:1
	s_nop 1
	v_add_f32_dpp v183, v183, v183 row_mirror row_mask:0xf bank_mask:0xf bound_ctrl:1
	s_nop 1
	v_readlane_b32 s98, v183, 0
	v_readlane_b32 s99, v183, 16
	v_readlane_b32 s100, v183, 32
	v_readlane_b32 s101, v183, 48
	s_nop 1
	v_mov_b32_e32 v183, s98
	v_add_f32_e32 v183, s99, v183
	v_add_f32_e32 v183, s100, v183
	v_add_f32_e32 v183, s101, v183
	v_fmamk_f32 v183, v183, 0x3a800000, v182
	v_cmp_gt_f32_e32 vcc, 0x800000, v183
	v_mul_f32_e32 v181, 0x4b800000, v183
	s_nop 1
	v_cndmask_b32_e32 v183, v183, v181, vcc
	v_rsq_f32_e32 v183, v183
	s_nop 0
	v_mul_f32_e32 v181, 0x45800000, v183
	v_cndmask_b32_e32 v184, v183, v181, vcc
	v_mov_b32_e32 v185, v184
	v_cvt_pk_bf16_f32 v64, v194, v195
	v_cvt_pk_bf16_f32 v65, v196, v197
	v_cvt_pk_bf16_f32 v66, v198, v199
	v_cvt_pk_bf16_f32 v67, v200, v201
	v_cvt_pk_bf16_f32 v68, v202, v203
	v_cvt_pk_bf16_f32 v69, v204, v205
	v_cvt_pk_bf16_f32 v70, v206, v207
	v_cvt_pk_bf16_f32 v71, v208, v209
	v_add_u32_e32 v181, 0x2800000, v177
	global_store_dwordx4 v181, v[64:67], s[78:79]
	global_store_dwordx4 v181, v[68:71], s[78:79] offset:1024
	v_add_u32_e32 v236, 0x8000, v237
	s_mov_b64 exec, 1
	global_store_dword v236, v184, s[78:79]
	s_mov_b64 exec, -1
	s_waitcnt vmcnt(16)
	v_lshlrev_b32_e32 v194, 16, v80
	v_and_b32_e32 v195, 0xffff0000, v80
	v_lshlrev_b32_e32 v196, 16, v81
	v_and_b32_e32 v197, 0xffff0000, v81
	v_lshlrev_b32_e32 v198, 16, v82
	v_and_b32_e32 v199, 0xffff0000, v82
	v_lshlrev_b32_e32 v200, 16, v83
	v_and_b32_e32 v201, 0xffff0000, v83
	v_lshlrev_b32_e32 v202, 16, v84
	v_and_b32_e32 v203, 0xffff0000, v84
	v_lshlrev_b32_e32 v204, 16, v85
	v_and_b32_e32 v205, 0xffff0000, v85
	v_lshlrev_b32_e32 v206, 16, v86
	v_and_b32_e32 v207, 0xffff0000, v86
	v_lshlrev_b32_e32 v208, 16, v87
	v_and_b32_e32 v209, 0xffff0000, v87
	v_lshlrev_b32_e32 v216, 16, v88
	v_and_b32_e32 v217, 0xffff0000, v88
	v_lshlrev_b32_e32 v218, 16, v89
	v_and_b32_e32 v219, 0xffff0000, v89
	v_lshlrev_b32_e32 v220, 16, v90
	v_and_b32_e32 v221, 0xffff0000, v90
	v_lshlrev_b32_e32 v222, 16, v91
	v_and_b32_e32 v223, 0xffff0000, v91
	v_lshlrev_b32_e32 v224, 16, v92
	v_and_b32_e32 v225, 0xffff0000, v92
	v_lshlrev_b32_e32 v226, 16, v93
	v_and_b32_e32 v227, 0xffff0000, v93
	v_lshlrev_b32_e32 v228, 16, v94
	v_and_b32_e32 v229, 0xffff0000, v94
	v_lshlrev_b32_e32 v230, 16, v95
	v_and_b32_e32 v231, 0xffff0000, v95
	v_pk_mul_f32 v[252:253], v[216:217], v[216:217]
	v_pk_mul_f32 v[254:255], v[218:219], v[218:219]
	v_pk_fma_f32 v[252:253], v[220:221], v[220:221], v[252:253]
	v_pk_fma_f32 v[254:255], v[222:223], v[222:223], v[254:255]
	v_pk_fma_f32 v[252:253], v[224:225], v[224:225], v[252:253]
	v_pk_fma_f32 v[254:255], v[226:227], v[226:227], v[254:255]
	v_pk_fma_f32 v[252:253], v[228:229], v[228:229], v[252:253]
	v_pk_fma_f32 v[254:255], v[230:231], v[230:231], v[254:255]
	v_pk_add_f32 v[252:253], v[252:253], v[254:255]
	s_nop 0
	v_add_f32_e32 v183, v252, v253
	s_nop 1
	v_add_f32_dpp v183, v183, v183 quad_perm:[1,0,3,2] row_mask:0xf bank_mask:0xf bound_ctrl:1
	s_nop 1
	v_add_f32_dpp v183, v183, v183 quad_perm:[2,3,0,1] row_mask:0xf bank_mask:0xf bound_ctrl:1
	s_nop 1
	v_add_f32_dpp v183, v183, v183 row_half_mirror row_mask:0xf bank_mask:0xf bound_ctrl:1
	s_nop 1
	v_add_f32_dpp v183, v183, v183 row_mirror row_mask:0xf bank_mask:0xf bound_ctrl:1
	s_nop 1
	v_readlane_b32 s98, v183, 0
	v_readlane_b32 s99, v183, 16
	v_readlane_b32 s100, v183, 32
	v_readlane_b32 s101, v183, 48
	s_nop 1
	v_mov_b32_e32 v183, s98
	v_add_f32_e32 v183, s99, v183
	v_add_f32_e32 v183, s100, v183
	v_add_f32_e32 v183, s101, v183
	v_fmamk_f32 v183, v183, 0x3a800000, v182
	v_cmp_gt_f32_e32 vcc, 0x800000, v183
	v_mul_f32_e32 v181, 0x4b800000, v183
	s_nop 1
	v_cndmask_b32_e32 v183, v183, v181, vcc
	v_rsq_f32_e32 v183, v183
	s_nop 0
	v_mul_f32_e32 v181, 0x45800000, v183
	v_cndmask_b32_e32 v184, v183, v181, vcc
	v_mov_b32_e32 v185, v184
	v_pk_mul_f32 v[216:217], v[216:217], v[184:185]
	v_pk_mul_f32 v[218:219], v[218:219], v[184:185]
	v_pk_mul_f32 v[220:221], v[220:221], v[184:185]
	v_pk_mul_f32 v[222:223], v[222:223], v[184:185]
	v_pk_mul_f32 v[224:225], v[224:225], v[184:185]
	v_pk_mul_f32 v[226:227], v[226:227], v[184:185]
	v_pk_mul_f32 v[228:229], v[228:229], v[184:185]
	v_pk_mul_f32 v[230:231], v[230:231], v[184:185]
	v_pk_fma_f32 v[194:195], v[216:217], v[160:161], v[194:195]
	v_pk_fma_f32 v[196:197], v[218:219], v[162:163], v[196:197]
	v_pk_fma_f32 v[198:199], v[220:221], v[164:165], v[198:199]
	v_pk_fma_f32 v[200:201], v[222:223], v[166:167], v[200:201]
	v_pk_fma_f32 v[202:203], v[224:225], v[168:169], v[202:203]
	v_pk_fma_f32 v[204:205], v[226:227], v[170:171], v[204:205]
	v_pk_fma_f32 v[206:207], v[228:229], v[172:173], v[206:207]
	v_pk_fma_f32 v[208:209], v[230:231], v[174:175], v[208:209]
	v_pk_mul_f32 v[252:253], v[194:195], v[194:195]
	v_pk_mul_f32 v[254:255], v[196:197], v[196:197]
	v_pk_fma_f32 v[252:253], v[198:199], v[198:199], v[252:253]
	v_pk_fma_f32 v[254:255], v[200:201], v[200:201], v[254:255]
	v_pk_fma_f32 v[252:253], v[202:203], v[202:203], v[252:253]
	v_pk_fma_f32 v[254:255], v[204:205], v[204:205], v[254:255]
	v_pk_fma_f32 v[252:253], v[206:207], v[206:207], v[252:253]
	v_pk_fma_f32 v[254:255], v[208:209], v[208:209], v[254:255]
	v_pk_add_f32 v[252:253], v[252:253], v[254:255]
	s_nop 0
	v_add_f32_e32 v183, v252, v253
	s_nop 1
	v_add_f32_dpp v183, v183, v183 quad_perm:[1,0,3,2] row_mask:0xf bank_mask:0xf bound_ctrl:1
	s_nop 1
	v_add_f32_dpp v183, v183, v183 quad_perm:[2,3,0,1] row_mask:0xf bank_mask:0xf bound_ctrl:1
	s_nop 1
	v_add_f32_dpp v183, v183, v183 row_half_mirror row_mask:0xf bank_mask:0xf bound_ctrl:1
	s_nop 1
	v_add_f32_dpp v183, v183, v183 row_mirror row_mask:0xf bank_mask:0xf bound_ctrl:1
	s_nop 1
	v_readlane_b32 s98, v183, 0
	v_readlane_b32 s99, v183, 16
	v_readlane_b32 s100, v183, 32
	v_readlane_b32 s101, v183, 48
	s_nop 1
	v_mov_b32_e32 v183, s98
	v_add_f32_e32 v183, s99, v183
	v_add_f32_e32 v183, s100, v183
	v_add_f32_e32 v183, s101, v183
	v_fmamk_f32 v183, v183, 0x3a800000, v182
	v_cmp_gt_f32_e32 vcc, 0x800000, v183
	v_mul_f32_e32 v181, 0x4b800000, v183
	s_nop 1
	v_cndmask_b32_e32 v183, v183, v181, vcc
	v_rsq_f32_e32 v183, v183
	s_nop 0
	v_mul_f32_e32 v181, 0x45800000, v183
	v_cndmask_b32_e32 v184, v183, v181, vcc
	v_mov_b32_e32 v185, v184
	v_cvt_pk_bf16_f32 v80, v194, v195
	v_cvt_pk_bf16_f32 v81, v196, v197
	v_cvt_pk_bf16_f32 v82, v198, v199
	v_cvt_pk_bf16_f32 v83, v200, v201
	v_cvt_pk_bf16_f32 v84, v202, v203
	v_cvt_pk_bf16_f32 v85, v204, v205
	v_cvt_pk_bf16_f32 v86, v206, v207
	v_cvt_pk_bf16_f32 v87, v208, v209
	v_add_u32_e32 v181, 0x2c00000, v177
	global_store_dwordx4 v181, v[80:83], s[78:79]
	global_store_dwordx4 v181, v[84:87], s[78:79] offset:1024
	v_add_u32_e32 v236, 0xa000, v237
	s_mov_b64 exec, 1
	global_store_dword v236, v184, s[78:79]
	s_mov_b64 exec, -1
	s_waitcnt vmcnt(12)
	v_lshlrev_b32_e32 v194, 16, v96
	v_and_b32_e32 v195, 0xffff0000, v96
	v_lshlrev_b32_e32 v196, 16, v97
	v_and_b32_e32 v197, 0xffff0000, v97
	v_lshlrev_b32_e32 v198, 16, v98
	v_and_b32_e32 v199, 0xffff0000, v98
	v_lshlrev_b32_e32 v200, 16, v99
	v_and_b32_e32 v201, 0xffff0000, v99
	v_lshlrev_b32_e32 v202, 16, v100
	v_and_b32_e32 v203, 0xffff0000, v100
	v_lshlrev_b32_e32 v204, 16, v101
	v_and_b32_e32 v205, 0xffff0000, v101
	v_lshlrev_b32_e32 v206, 16, v102
	v_and_b32_e32 v207, 0xffff0000, v102
	v_lshlrev_b32_e32 v208, 16, v103
	v_and_b32_e32 v209, 0xffff0000, v103
	v_lshlrev_b32_e32 v216, 16, v104
	v_and_b32_e32 v217, 0xffff0000, v104
	v_lshlrev_b32_e32 v218, 16, v105
	v_and_b32_e32 v219, 0xffff0000, v105
	v_lshlrev_b32_e32 v220, 16, v106
	v_and_b32_e32 v221, 0xffff0000, v106
	v_lshlrev_b32_e32 v222, 16, v107
	v_and_b32_e32 v223, 0xffff0000, v107
	v_lshlrev_b32_e32 v224, 16, v108
	v_and_b32_e32 v225, 0xffff0000, v108
	v_lshlrev_b32_e32 v226, 16, v109
	v_and_b32_e32 v227, 0xffff0000, v109
	v_lshlrev_b32_e32 v228, 16, v110
	v_and_b32_e32 v229, 0xffff0000, v110
	v_lshlrev_b32_e32 v230, 16, v111
	v_and_b32_e32 v231, 0xffff0000, v111
	v_pk_mul_f32 v[252:253], v[216:217], v[216:217]
	v_pk_mul_f32 v[254:255], v[218:219], v[218:219]
	v_pk_fma_f32 v[252:253], v[220:221], v[220:221], v[252:253]
	v_pk_fma_f32 v[254:255], v[222:223], v[222:223], v[254:255]
	v_pk_fma_f32 v[252:253], v[224:225], v[224:225], v[252:253]
	v_pk_fma_f32 v[254:255], v[226:227], v[226:227], v[254:255]
	v_pk_fma_f32 v[252:253], v[228:229], v[228:229], v[252:253]
	v_pk_fma_f32 v[254:255], v[230:231], v[230:231], v[254:255]
	v_pk_add_f32 v[252:253], v[252:253], v[254:255]
	s_nop 0
	v_add_f32_e32 v183, v252, v253
	s_nop 1
	v_add_f32_dpp v183, v183, v183 quad_perm:[1,0,3,2] row_mask:0xf bank_mask:0xf bound_ctrl:1
	s_nop 1
	v_add_f32_dpp v183, v183, v183 quad_perm:[2,3,0,1] row_mask:0xf bank_mask:0xf bound_ctrl:1
	s_nop 1
	v_add_f32_dpp v183, v183, v183 row_half_mirror row_mask:0xf bank_mask:0xf bound_ctrl:1
	s_nop 1
	v_add_f32_dpp v183, v183, v183 row_mirror row_mask:0xf bank_mask:0xf bound_ctrl:1
	s_nop 1
	v_readlane_b32 s98, v183, 0
	v_readlane_b32 s99, v183, 16
	v_readlane_b32 s100, v183, 32
	v_readlane_b32 s101, v183, 48
	s_nop 1
	v_mov_b32_e32 v183, s98
	v_add_f32_e32 v183, s99, v183
	v_add_f32_e32 v183, s100, v183
	v_add_f32_e32 v183, s101, v183
	v_fmamk_f32 v183, v183, 0x3a800000, v182
	v_cmp_gt_f32_e32 vcc, 0x800000, v183
	v_mul_f32_e32 v181, 0x4b800000, v183
	s_nop 1
	v_cndmask_b32_e32 v183, v183, v181, vcc
	v_rsq_f32_e32 v183, v183
	s_nop 0
	v_mul_f32_e32 v181, 0x45800000, v183
	v_cndmask_b32_e32 v184, v183, v181, vcc
	v_mov_b32_e32 v185, v184
	v_pk_mul_f32 v[216:217], v[216:217], v[184:185]
	v_pk_mul_f32 v[218:219], v[218:219], v[184:185]
	v_pk_mul_f32 v[220:221], v[220:221], v[184:185]
	v_pk_mul_f32 v[222:223], v[222:223], v[184:185]
	v_pk_mul_f32 v[224:225], v[224:225], v[184:185]
	v_pk_mul_f32 v[226:227], v[226:227], v[184:185]
	v_pk_mul_f32 v[228:229], v[228:229], v[184:185]
	v_pk_mul_f32 v[230:231], v[230:231], v[184:185]
	v_pk_fma_f32 v[194:195], v[216:217], v[160:161], v[194:195]
	v_pk_fma_f32 v[196:197], v[218:219], v[162:163], v[196:197]
	v_pk_fma_f32 v[198:199], v[220:221], v[164:165], v[198:199]
	v_pk_fma_f32 v[200:201], v[222:223], v[166:167], v[200:201]
	v_pk_fma_f32 v[202:203], v[224:225], v[168:169], v[202:203]
	v_pk_fma_f32 v[204:205], v[226:227], v[170:171], v[204:205]
	v_pk_fma_f32 v[206:207], v[228:229], v[172:173], v[206:207]
	v_pk_fma_f32 v[208:209], v[230:231], v[174:175], v[208:209]
	v_pk_mul_f32 v[252:253], v[194:195], v[194:195]
	v_pk_mul_f32 v[254:255], v[196:197], v[196:197]
	v_pk_fma_f32 v[252:253], v[198:199], v[198:199], v[252:253]
	v_pk_fma_f32 v[254:255], v[200:201], v[200:201], v[254:255]
	v_pk_fma_f32 v[252:253], v[202:203], v[202:203], v[252:253]
	v_pk_fma_f32 v[254:255], v[204:205], v[204:205], v[254:255]
	v_pk_fma_f32 v[252:253], v[206:207], v[206:207], v[252:253]
	v_pk_fma_f32 v[254:255], v[208:209], v[208:209], v[254:255]
	v_pk_add_f32 v[252:253], v[252:253], v[254:255]
	s_nop 0
	v_add_f32_e32 v183, v252, v253
	s_nop 1
	v_add_f32_dpp v183, v183, v183 quad_perm:[1,0,3,2] row_mask:0xf bank_mask:0xf bound_ctrl:1
	s_nop 1
	v_add_f32_dpp v183, v183, v183 quad_perm:[2,3,0,1] row_mask:0xf bank_mask:0xf bound_ctrl:1
	s_nop 1
	v_add_f32_dpp v183, v183, v183 row_half_mirror row_mask:0xf bank_mask:0xf bound_ctrl:1
	s_nop 1
	v_add_f32_dpp v183, v183, v183 row_mirror row_mask:0xf bank_mask:0xf bound_ctrl:1
	s_nop 1
	v_readlane_b32 s98, v183, 0
	v_readlane_b32 s99, v183, 16
	v_readlane_b32 s100, v183, 32
	v_readlane_b32 s101, v183, 48
	s_nop 1
	v_mov_b32_e32 v183, s98
	v_add_f32_e32 v183, s99, v183
	v_add_f32_e32 v183, s100, v183
	v_add_f32_e32 v183, s101, v183
	v_fmamk_f32 v183, v183, 0x3a800000, v182
	v_cmp_gt_f32_e32 vcc, 0x800000, v183
	v_mul_f32_e32 v181, 0x4b800000, v183
	s_nop 1
	v_cndmask_b32_e32 v183, v183, v181, vcc
	v_rsq_f32_e32 v183, v183
	s_nop 0
	v_mul_f32_e32 v181, 0x45800000, v183
	v_cndmask_b32_e32 v184, v183, v181, vcc
	v_mov_b32_e32 v185, v184
	v_cvt_pk_bf16_f32 v96, v194, v195
	v_cvt_pk_bf16_f32 v97, v196, v197
	v_cvt_pk_bf16_f32 v98, v198, v199
	v_cvt_pk_bf16_f32 v99, v200, v201
	v_cvt_pk_bf16_f32 v100, v202, v203
	v_cvt_pk_bf16_f32 v101, v204, v205
	v_cvt_pk_bf16_f32 v102, v206, v207
	v_cvt_pk_bf16_f32 v103, v208, v209
	v_add_u32_e32 v181, 0x3000000, v177
	global_store_dwordx4 v181, v[96:99], s[78:79]
	global_store_dwordx4 v181, v[100:103], s[78:79] offset:1024
	v_add_u32_e32 v236, 0xc000, v237
	s_mov_b64 exec, 1
	global_store_dword v236, v184, s[78:79]
	s_mov_b64 exec, -1
	s_waitcnt vmcnt(8)
	v_lshlrev_b32_e32 v194, 16, v112
	v_and_b32_e32 v195, 0xffff0000, v112
	v_lshlrev_b32_e32 v196, 16, v113
	v_and_b32_e32 v197, 0xffff0000, v113
	v_lshlrev_b32_e32 v198, 16, v114
	v_and_b32_e32 v199, 0xffff0000, v114
	v_lshlrev_b32_e32 v200, 16, v115
	v_and_b32_e32 v201, 0xffff0000, v115
	v_lshlrev_b32_e32 v202, 16, v116
	v_and_b32_e32 v203, 0xffff0000, v116
	v_lshlrev_b32_e32 v204, 16, v117
	v_and_b32_e32 v205, 0xffff0000, v117
	v_lshlrev_b32_e32 v206, 16, v118
	v_and_b32_e32 v207, 0xffff0000, v118
	v_lshlrev_b32_e32 v208, 16, v119
	v_and_b32_e32 v209, 0xffff0000, v119
	v_lshlrev_b32_e32 v216, 16, v120
	v_and_b32_e32 v217, 0xffff0000, v120
	v_lshlrev_b32_e32 v218, 16, v121
	v_and_b32_e32 v219, 0xffff0000, v121
	v_lshlrev_b32_e32 v220, 16, v122
	v_and_b32_e32 v221, 0xffff0000, v122
	v_lshlrev_b32_e32 v222, 16, v123
	v_and_b32_e32 v223, 0xffff0000, v123
	v_lshlrev_b32_e32 v224, 16, v124
	v_and_b32_e32 v225, 0xffff0000, v124
	v_lshlrev_b32_e32 v226, 16, v125
	v_and_b32_e32 v227, 0xffff0000, v125
	v_lshlrev_b32_e32 v228, 16, v126
	v_and_b32_e32 v229, 0xffff0000, v126
	v_lshlrev_b32_e32 v230, 16, v127
	v_and_b32_e32 v231, 0xffff0000, v127
	v_pk_mul_f32 v[252:253], v[216:217], v[216:217]
	v_pk_mul_f32 v[254:255], v[218:219], v[218:219]
	v_pk_fma_f32 v[252:253], v[220:221], v[220:221], v[252:253]
	v_pk_fma_f32 v[254:255], v[222:223], v[222:223], v[254:255]
	v_pk_fma_f32 v[252:253], v[224:225], v[224:225], v[252:253]
	v_pk_fma_f32 v[254:255], v[226:227], v[226:227], v[254:255]
	v_pk_fma_f32 v[252:253], v[228:229], v[228:229], v[252:253]
	v_pk_fma_f32 v[254:255], v[230:231], v[230:231], v[254:255]
	v_pk_add_f32 v[252:253], v[252:253], v[254:255]
	s_nop 0
	v_add_f32_e32 v183, v252, v253
	s_nop 1
	v_add_f32_dpp v183, v183, v183 quad_perm:[1,0,3,2] row_mask:0xf bank_mask:0xf bound_ctrl:1
	s_nop 1
	v_add_f32_dpp v183, v183, v183 quad_perm:[2,3,0,1] row_mask:0xf bank_mask:0xf bound_ctrl:1
	s_nop 1
	v_add_f32_dpp v183, v183, v183 row_half_mirror row_mask:0xf bank_mask:0xf bound_ctrl:1
	s_nop 1
	v_add_f32_dpp v183, v183, v183 row_mirror row_mask:0xf bank_mask:0xf bound_ctrl:1
	s_nop 1
	v_readlane_b32 s98, v183, 0
	v_readlane_b32 s99, v183, 16
	v_readlane_b32 s100, v183, 32
	v_readlane_b32 s101, v183, 48
	s_nop 1
	v_mov_b32_e32 v183, s98
	v_add_f32_e32 v183, s99, v183
	v_add_f32_e32 v183, s100, v183
	v_add_f32_e32 v183, s101, v183
	v_fmamk_f32 v183, v183, 0x3a800000, v182
	v_cmp_gt_f32_e32 vcc, 0x800000, v183
	v_mul_f32_e32 v181, 0x4b800000, v183
	s_nop 1
	v_cndmask_b32_e32 v183, v183, v181, vcc
	v_rsq_f32_e32 v183, v183
	s_nop 0
	v_mul_f32_e32 v181, 0x45800000, v183
	v_cndmask_b32_e32 v184, v183, v181, vcc
	v_mov_b32_e32 v185, v184
	v_pk_mul_f32 v[216:217], v[216:217], v[184:185]
	v_pk_mul_f32 v[218:219], v[218:219], v[184:185]
	v_pk_mul_f32 v[220:221], v[220:221], v[184:185]
	v_pk_mul_f32 v[222:223], v[222:223], v[184:185]
	v_pk_mul_f32 v[224:225], v[224:225], v[184:185]
	v_pk_mul_f32 v[226:227], v[226:227], v[184:185]
	v_pk_mul_f32 v[228:229], v[228:229], v[184:185]
	v_pk_mul_f32 v[230:231], v[230:231], v[184:185]
	v_pk_fma_f32 v[194:195], v[216:217], v[160:161], v[194:195]
	v_pk_fma_f32 v[196:197], v[218:219], v[162:163], v[196:197]
	v_pk_fma_f32 v[198:199], v[220:221], v[164:165], v[198:199]
	v_pk_fma_f32 v[200:201], v[222:223], v[166:167], v[200:201]
	v_pk_fma_f32 v[202:203], v[224:225], v[168:169], v[202:203]
	v_pk_fma_f32 v[204:205], v[226:227], v[170:171], v[204:205]
	v_pk_fma_f32 v[206:207], v[228:229], v[172:173], v[206:207]
	v_pk_fma_f32 v[208:209], v[230:231], v[174:175], v[208:209]
	v_pk_mul_f32 v[252:253], v[194:195], v[194:195]
	v_pk_mul_f32 v[254:255], v[196:197], v[196:197]
	v_pk_fma_f32 v[252:253], v[198:199], v[198:199], v[252:253]
	v_pk_fma_f32 v[254:255], v[200:201], v[200:201], v[254:255]
	v_pk_fma_f32 v[252:253], v[202:203], v[202:203], v[252:253]
	v_pk_fma_f32 v[254:255], v[204:205], v[204:205], v[254:255]
	v_pk_fma_f32 v[252:253], v[206:207], v[206:207], v[252:253]
	v_pk_fma_f32 v[254:255], v[208:209], v[208:209], v[254:255]
	v_pk_add_f32 v[252:253], v[252:253], v[254:255]
	s_nop 0
	v_add_f32_e32 v183, v252, v253
	s_nop 1
	v_add_f32_dpp v183, v183, v183 quad_perm:[1,0,3,2] row_mask:0xf bank_mask:0xf bound_ctrl:1
	s_nop 1
	v_add_f32_dpp v183, v183, v183 quad_perm:[2,3,0,1] row_mask:0xf bank_mask:0xf bound_ctrl:1
	s_nop 1
	v_add_f32_dpp v183, v183, v183 row_half_mirror row_mask:0xf bank_mask:0xf bound_ctrl:1
	s_nop 1
	v_add_f32_dpp v183, v183, v183 row_mirror row_mask:0xf bank_mask:0xf bound_ctrl:1
	s_nop 1
	v_readlane_b32 s98, v183, 0
	v_readlane_b32 s99, v183, 16
	v_readlane_b32 s100, v183, 32
	v_readlane_b32 s101, v183, 48
	s_nop 1
	v_mov_b32_e32 v183, s98
	v_add_f32_e32 v183, s99, v183
	v_add_f32_e32 v183, s100, v183
	v_add_f32_e32 v183, s101, v183
	v_fmamk_f32 v183, v183, 0x3a800000, v182
	v_cmp_gt_f32_e32 vcc, 0x800000, v183
	v_mul_f32_e32 v181, 0x4b800000, v183
	s_nop 1
	v_cndmask_b32_e32 v183, v183, v181, vcc
	v_rsq_f32_e32 v183, v183
	s_nop 0
	v_mul_f32_e32 v181, 0x45800000, v183
	v_cndmask_b32_e32 v184, v183, v181, vcc
	v_mov_b32_e32 v185, v184
	v_cvt_pk_bf16_f32 v112, v194, v195
	v_cvt_pk_bf16_f32 v113, v196, v197
	v_cvt_pk_bf16_f32 v114, v198, v199
	v_cvt_pk_bf16_f32 v115, v200, v201
	v_cvt_pk_bf16_f32 v116, v202, v203
	v_cvt_pk_bf16_f32 v117, v204, v205
	v_cvt_pk_bf16_f32 v118, v206, v207
	v_cvt_pk_bf16_f32 v119, v208, v209
	v_add_u32_e32 v181, 0x3400000, v177
	global_store_dwordx4 v181, v[112:115], s[78:79]
	global_store_dwordx4 v181, v[116:119], s[78:79] offset:1024
	v_add_u32_e32 v236, 0xe000, v237
	s_mov_b64 exec, 1
	global_store_dword v236, v184, s[78:79]
	s_mov_b64 exec, -1
	s_waitcnt vmcnt(4)
	v_lshlrev_b32_e32 v194, 16, v128
	v_and_b32_e32 v195, 0xffff0000, v128
	v_lshlrev_b32_e32 v196, 16, v129
	v_and_b32_e32 v197, 0xffff0000, v129
	v_lshlrev_b32_e32 v198, 16, v130
	v_and_b32_e32 v199, 0xffff0000, v130
	v_lshlrev_b32_e32 v200, 16, v131
	v_and_b32_e32 v201, 0xffff0000, v131
	v_lshlrev_b32_e32 v202, 16, v132
	v_and_b32_e32 v203, 0xffff0000, v132
	v_lshlrev_b32_e32 v204, 16, v133
	v_and_b32_e32 v205, 0xffff0000, v133
	v_lshlrev_b32_e32 v206, 16, v134
	v_and_b32_e32 v207, 0xffff0000, v134
	v_lshlrev_b32_e32 v208, 16, v135
	v_and_b32_e32 v209, 0xffff0000, v135
	v_lshlrev_b32_e32 v216, 16, v136
	v_and_b32_e32 v217, 0xffff0000, v136
	v_lshlrev_b32_e32 v218, 16, v137
	v_and_b32_e32 v219, 0xffff0000, v137
	v_lshlrev_b32_e32 v220, 16, v138
	v_and_b32_e32 v221, 0xffff0000, v138
	v_lshlrev_b32_e32 v222, 16, v139
	v_and_b32_e32 v223, 0xffff0000, v139
	v_lshlrev_b32_e32 v224, 16, v140
	v_and_b32_e32 v225, 0xffff0000, v140
	v_lshlrev_b32_e32 v226, 16, v141
	v_and_b32_e32 v227, 0xffff0000, v141
	v_lshlrev_b32_e32 v228, 16, v142
	v_and_b32_e32 v229, 0xffff0000, v142
	v_lshlrev_b32_e32 v230, 16, v143
	v_and_b32_e32 v231, 0xffff0000, v143
	v_pk_mul_f32 v[252:253], v[216:217], v[216:217]
	v_pk_mul_f32 v[254:255], v[218:219], v[218:219]
	v_pk_fma_f32 v[252:253], v[220:221], v[220:221], v[252:253]
	v_pk_fma_f32 v[254:255], v[222:223], v[222:223], v[254:255]
	v_pk_fma_f32 v[252:253], v[224:225], v[224:225], v[252:253]
	v_pk_fma_f32 v[254:255], v[226:227], v[226:227], v[254:255]
	v_pk_fma_f32 v[252:253], v[228:229], v[228:229], v[252:253]
	v_pk_fma_f32 v[254:255], v[230:231], v[230:231], v[254:255]
	v_pk_add_f32 v[252:253], v[252:253], v[254:255]
	s_nop 0
	v_add_f32_e32 v183, v252, v253
	s_nop 1
	v_add_f32_dpp v183, v183, v183 quad_perm:[1,0,3,2] row_mask:0xf bank_mask:0xf bound_ctrl:1
	s_nop 1
	v_add_f32_dpp v183, v183, v183 quad_perm:[2,3,0,1] row_mask:0xf bank_mask:0xf bound_ctrl:1
	s_nop 1
	v_add_f32_dpp v183, v183, v183 row_half_mirror row_mask:0xf bank_mask:0xf bound_ctrl:1
	s_nop 1
	v_add_f32_dpp v183, v183, v183 row_mirror row_mask:0xf bank_mask:0xf bound_ctrl:1
	s_nop 1
	v_readlane_b32 s98, v183, 0
	v_readlane_b32 s99, v183, 16
	v_readlane_b32 s100, v183, 32
	v_readlane_b32 s101, v183, 48
	s_nop 1
	v_mov_b32_e32 v183, s98
	v_add_f32_e32 v183, s99, v183
	v_add_f32_e32 v183, s100, v183
	v_add_f32_e32 v183, s101, v183
	v_fmamk_f32 v183, v183, 0x3a800000, v182
	v_cmp_gt_f32_e32 vcc, 0x800000, v183
	v_mul_f32_e32 v181, 0x4b800000, v183
	s_nop 1
	v_cndmask_b32_e32 v183, v183, v181, vcc
	v_rsq_f32_e32 v183, v183
	s_nop 0
	v_mul_f32_e32 v181, 0x45800000, v183
	v_cndmask_b32_e32 v184, v183, v181, vcc
	v_mov_b32_e32 v185, v184
	v_pk_mul_f32 v[216:217], v[216:217], v[184:185]
	v_pk_mul_f32 v[218:219], v[218:219], v[184:185]
	v_pk_mul_f32 v[220:221], v[220:221], v[184:185]
	v_pk_mul_f32 v[222:223], v[222:223], v[184:185]
	v_pk_mul_f32 v[224:225], v[224:225], v[184:185]
	v_pk_mul_f32 v[226:227], v[226:227], v[184:185]
	v_pk_mul_f32 v[228:229], v[228:229], v[184:185]
	v_pk_mul_f32 v[230:231], v[230:231], v[184:185]
	v_pk_fma_f32 v[194:195], v[216:217], v[160:161], v[194:195]
	v_pk_fma_f32 v[196:197], v[218:219], v[162:163], v[196:197]
	v_pk_fma_f32 v[198:199], v[220:221], v[164:165], v[198:199]
	v_pk_fma_f32 v[200:201], v[222:223], v[166:167], v[200:201]
	v_pk_fma_f32 v[202:203], v[224:225], v[168:169], v[202:203]
	v_pk_fma_f32 v[204:205], v[226:227], v[170:171], v[204:205]
	v_pk_fma_f32 v[206:207], v[228:229], v[172:173], v[206:207]
	v_pk_fma_f32 v[208:209], v[230:231], v[174:175], v[208:209]
	v_pk_mul_f32 v[252:253], v[194:195], v[194:195]
	v_pk_mul_f32 v[254:255], v[196:197], v[196:197]
	v_pk_fma_f32 v[252:253], v[198:199], v[198:199], v[252:253]
	v_pk_fma_f32 v[254:255], v[200:201], v[200:201], v[254:255]
	v_pk_fma_f32 v[252:253], v[202:203], v[202:203], v[252:253]
	v_pk_fma_f32 v[254:255], v[204:205], v[204:205], v[254:255]
	v_pk_fma_f32 v[252:253], v[206:207], v[206:207], v[252:253]
	v_pk_fma_f32 v[254:255], v[208:209], v[208:209], v[254:255]
	v_pk_add_f32 v[252:253], v[252:253], v[254:255]
	s_nop 0
	v_add_f32_e32 v183, v252, v253
	s_nop 1
	v_add_f32_dpp v183, v183, v183 quad_perm:[1,0,3,2] row_mask:0xf bank_mask:0xf bound_ctrl:1
	s_nop 1
	v_add_f32_dpp v183, v183, v183 quad_perm:[2,3,0,1] row_mask:0xf bank_mask:0xf bound_ctrl:1
	s_nop 1
	v_add_f32_dpp v183, v183, v183 row_half_mirror row_mask:0xf bank_mask:0xf bound_ctrl:1
	s_nop 1
	v_add_f32_dpp v183, v183, v183 row_mirror row_mask:0xf bank_mask:0xf bound_ctrl:1
	s_nop 1
	v_readlane_b32 s98, v183, 0
	v_readlane_b32 s99, v183, 16
	v_readlane_b32 s100, v183, 32
	v_readlane_b32 s101, v183, 48
	s_nop 1
	v_mov_b32_e32 v183, s98
	v_add_f32_e32 v183, s99, v183
	v_add_f32_e32 v183, s100, v183
	v_add_f32_e32 v183, s101, v183
	v_fmamk_f32 v183, v183, 0x3a800000, v182
	v_cmp_gt_f32_e32 vcc, 0x800000, v183
	v_mul_f32_e32 v181, 0x4b800000, v183
	s_nop 1
	v_cndmask_b32_e32 v183, v183, v181, vcc
	v_rsq_f32_e32 v183, v183
	s_nop 0
	v_mul_f32_e32 v181, 0x45800000, v183
	v_cndmask_b32_e32 v184, v183, v181, vcc
	v_mov_b32_e32 v185, v184
	v_cvt_pk_bf16_f32 v128, v194, v195
	v_cvt_pk_bf16_f32 v129, v196, v197
	v_cvt_pk_bf16_f32 v130, v198, v199
	v_cvt_pk_bf16_f32 v131, v200, v201
	v_cvt_pk_bf16_f32 v132, v202, v203
	v_cvt_pk_bf16_f32 v133, v204, v205
	v_cvt_pk_bf16_f32 v134, v206, v207
	v_cvt_pk_bf16_f32 v135, v208, v209
	v_add_u32_e32 v181, 0x1800000, v210
	global_store_dwordx4 v181, v[128:131], s[78:79]
	global_store_dwordx4 v181, v[132:135], s[78:79] offset:1024
	v_add_u32_e32 v236, 0x0, v211
	s_mov_b64 exec, 1
	global_store_dword v236, v184, s[78:79]
	s_mov_b64 exec, -1
	s_waitcnt vmcnt(0)
	v_lshlrev_b32_e32 v194, 16, v144
	v_and_b32_e32 v195, 0xffff0000, v144
	v_lshlrev_b32_e32 v196, 16, v145
	v_and_b32_e32 v197, 0xffff0000, v145
	v_lshlrev_b32_e32 v198, 16, v146
	v_and_b32_e32 v199, 0xffff0000, v146
	v_lshlrev_b32_e32 v200, 16, v147
	v_and_b32_e32 v201, 0xffff0000, v147
	v_lshlrev_b32_e32 v202, 16, v148
	v_and_b32_e32 v203, 0xffff0000, v148
	v_lshlrev_b32_e32 v204, 16, v149
	v_and_b32_e32 v205, 0xffff0000, v149
	v_lshlrev_b32_e32 v206, 16, v150
	v_and_b32_e32 v207, 0xffff0000, v150
	v_lshlrev_b32_e32 v208, 16, v151
	v_and_b32_e32 v209, 0xffff0000, v151
	v_lshlrev_b32_e32 v216, 16, v152
	v_and_b32_e32 v217, 0xffff0000, v152
	v_lshlrev_b32_e32 v218, 16, v153
	v_and_b32_e32 v219, 0xffff0000, v153
	v_lshlrev_b32_e32 v220, 16, v154
	v_and_b32_e32 v221, 0xffff0000, v154
	v_lshlrev_b32_e32 v222, 16, v155
	v_and_b32_e32 v223, 0xffff0000, v155
	v_lshlrev_b32_e32 v224, 16, v156
	v_and_b32_e32 v225, 0xffff0000, v156
	v_lshlrev_b32_e32 v226, 16, v157
	v_and_b32_e32 v227, 0xffff0000, v157
	v_lshlrev_b32_e32 v228, 16, v158
	v_and_b32_e32 v229, 0xffff0000, v158
	v_lshlrev_b32_e32 v230, 16, v159
	v_and_b32_e32 v231, 0xffff0000, v159
	v_pk_mul_f32 v[252:253], v[216:217], v[216:217]
	v_pk_mul_f32 v[254:255], v[218:219], v[218:219]
	v_pk_fma_f32 v[252:253], v[220:221], v[220:221], v[252:253]
	v_pk_fma_f32 v[254:255], v[222:223], v[222:223], v[254:255]
	v_pk_fma_f32 v[252:253], v[224:225], v[224:225], v[252:253]
	v_pk_fma_f32 v[254:255], v[226:227], v[226:227], v[254:255]
	v_pk_fma_f32 v[252:253], v[228:229], v[228:229], v[252:253]
	v_pk_fma_f32 v[254:255], v[230:231], v[230:231], v[254:255]
	v_pk_add_f32 v[252:253], v[252:253], v[254:255]
	s_nop 0
	v_add_f32_e32 v183, v252, v253
	s_nop 1
	v_add_f32_dpp v183, v183, v183 quad_perm:[1,0,3,2] row_mask:0xf bank_mask:0xf bound_ctrl:1
	s_nop 1
	v_add_f32_dpp v183, v183, v183 quad_perm:[2,3,0,1] row_mask:0xf bank_mask:0xf bound_ctrl:1
	s_nop 1
	v_add_f32_dpp v183, v183, v183 row_half_mirror row_mask:0xf bank_mask:0xf bound_ctrl:1
	s_nop 1
	v_add_f32_dpp v183, v183, v183 row_mirror row_mask:0xf bank_mask:0xf bound_ctrl:1
	s_nop 1
	v_readlane_b32 s98, v183, 0
	v_readlane_b32 s99, v183, 16
	v_readlane_b32 s100, v183, 32
	v_readlane_b32 s101, v183, 48
	s_nop 1
	v_mov_b32_e32 v183, s98
	v_add_f32_e32 v183, s99, v183
	v_add_f32_e32 v183, s100, v183
	v_add_f32_e32 v183, s101, v183
	v_fmamk_f32 v183, v183, 0x3a800000, v182
	v_cmp_gt_f32_e32 vcc, 0x800000, v183
	v_mul_f32_e32 v181, 0x4b800000, v183
	s_nop 1
	v_cndmask_b32_e32 v183, v183, v181, vcc
	v_rsq_f32_e32 v183, v183
	s_nop 0
	v_mul_f32_e32 v181, 0x45800000, v183
	v_cndmask_b32_e32 v184, v183, v181, vcc
	v_mov_b32_e32 v185, v184
	v_pk_mul_f32 v[216:217], v[216:217], v[184:185]
	v_pk_mul_f32 v[218:219], v[218:219], v[184:185]
	v_pk_mul_f32 v[220:221], v[220:221], v[184:185]
	v_pk_mul_f32 v[222:223], v[222:223], v[184:185]
	v_pk_mul_f32 v[224:225], v[224:225], v[184:185]
	v_pk_mul_f32 v[226:227], v[226:227], v[184:185]
	v_pk_mul_f32 v[228:229], v[228:229], v[184:185]
	v_pk_mul_f32 v[230:231], v[230:231], v[184:185]
	v_pk_fma_f32 v[194:195], v[216:217], v[160:161], v[194:195]
	v_pk_fma_f32 v[196:197], v[218:219], v[162:163], v[196:197]
	v_pk_fma_f32 v[198:199], v[220:221], v[164:165], v[198:199]
	v_pk_fma_f32 v[200:201], v[222:223], v[166:167], v[200:201]
	v_pk_fma_f32 v[202:203], v[224:225], v[168:169], v[202:203]
	v_pk_fma_f32 v[204:205], v[226:227], v[170:171], v[204:205]
	v_pk_fma_f32 v[206:207], v[228:229], v[172:173], v[206:207]
	v_pk_fma_f32 v[208:209], v[230:231], v[174:175], v[208:209]
	v_pk_mul_f32 v[252:253], v[194:195], v[194:195]
	v_pk_mul_f32 v[254:255], v[196:197], v[196:197]
	v_pk_fma_f32 v[252:253], v[198:199], v[198:199], v[252:253]
	v_pk_fma_f32 v[254:255], v[200:201], v[200:201], v[254:255]
	v_pk_fma_f32 v[252:253], v[202:203], v[202:203], v[252:253]
	v_pk_fma_f32 v[254:255], v[204:205], v[204:205], v[254:255]
	v_pk_fma_f32 v[252:253], v[206:207], v[206:207], v[252:253]
	v_pk_fma_f32 v[254:255], v[208:209], v[208:209], v[254:255]
	v_pk_add_f32 v[252:253], v[252:253], v[254:255]
	s_nop 0
	v_add_f32_e32 v183, v252, v253
	s_nop 1
	v_add_f32_dpp v183, v183, v183 quad_perm:[1,0,3,2] row_mask:0xf bank_mask:0xf bound_ctrl:1
	s_nop 1
	v_add_f32_dpp v183, v183, v183 quad_perm:[2,3,0,1] row_mask:0xf bank_mask:0xf bound_ctrl:1
	s_nop 1
	v_add_f32_dpp v183, v183, v183 row_half_mirror row_mask:0xf bank_mask:0xf bound_ctrl:1
	s_nop 1
	v_add_f32_dpp v183, v183, v183 row_mirror row_mask:0xf bank_mask:0xf bound_ctrl:1
	s_nop 1
	v_readlane_b32 s98, v183, 0
	v_readlane_b32 s99, v183, 16
	v_readlane_b32 s100, v183, 32
	v_readlane_b32 s101, v183, 48
	s_nop 1
	v_mov_b32_e32 v183, s98
	v_add_f32_e32 v183, s99, v183
	v_add_f32_e32 v183, s100, v183
	v_add_f32_e32 v183, s101, v183
	v_fmamk_f32 v183, v183, 0x3a800000, v182
	v_cmp_gt_f32_e32 vcc, 0x800000, v183
	v_mul_f32_e32 v181, 0x4b800000, v183
	s_nop 1
	v_cndmask_b32_e32 v183, v183, v181, vcc
	v_rsq_f32_e32 v183, v183
	s_nop 0
	v_mul_f32_e32 v181, 0x45800000, v183
	v_cndmask_b32_e32 v184, v183, v181, vcc
	v_mov_b32_e32 v185, v184
	v_cvt_pk_bf16_f32 v144, v194, v195
	v_cvt_pk_bf16_f32 v145, v196, v197
	v_cvt_pk_bf16_f32 v146, v198, v199
	v_cvt_pk_bf16_f32 v147, v200, v201
	v_cvt_pk_bf16_f32 v148, v202, v203
	v_cvt_pk_bf16_f32 v149, v204, v205
	v_cvt_pk_bf16_f32 v150, v206, v207
	v_cvt_pk_bf16_f32 v151, v208, v209
	v_add_u32_e32 v181, 0x1c00000, v210
	global_store_dwordx4 v181, v[144:147], s[78:79]
	global_store_dwordx4 v181, v[148:151], s[78:79] offset:1024
	v_add_u32_e32 v236, 0x2000, v211
	s_mov_b64 exec, 1
	global_store_dword v236, v184, s[78:79]
	s_mov_b64 exec, -1
	s_branch .Lmyxupd_done_0
.Lmyxupd_s_0:
	v_add_u32_e32 v178, 0x1800000, v177
	v_add_u32_e32 v181, 0x9e00000, v177
	global_load_dwordx4 v[0:3], v178, s[78:79]
	global_load_dwordx4 v[4:7], v178, s[78:79] offset:1024
	global_load_dwordx4 v[8:11], v181, s[78:79]
	global_load_dwordx4 v[12:15], v181, s[78:79] offset:1024
	v_add_u32_e32 v178, 0x1c00000, v177
	v_add_u32_e32 v181, 0xa200000, v177
	global_load_dwordx4 v[16:19], v178, s[78:79]
	global_load_dwordx4 v[20:23], v178, s[78:79] offset:1024
	global_load_dwordx4 v[24:27], v181, s[78:79]
	global_load_dwordx4 v[28:31], v181, s[78:79] offset:1024
	v_lshrrev_b32_e32 v179, 2, v179
	v_lshlrev_b32_e32 v210, 4, v176
	v_lshl_add_u32 v210, v179, 11, v210
	v_lshlrev_b32_e32 v211, 2, v179
	v_add_u32_e32 v211, 0x10000, v211
	v_add_u32_e32 v181, 0x3800000, v210
	global_load_dwordx4 v[32:35], v181, s[78:79]
	global_load_dwordx4 v[36:39], v181, s[78:79] offset:1024
	v_lshl_add_u32 v183, v179, 12, v180
	v_add_u32_e32 v183, 0xbf00000, v183
	v_add_u32_e32 v181, 0x0, v183
	global_load_dwordx4 v[40:43], v181, s[78:79]
	global_load_dwordx4 v[44:47], v181, s[78:79] offset:16
	global_load_dwordx4 v[48:51], v181, s[78:79] offset:2048
	global_load_dwordx4 v[52:55], v181, s[78:79] offset:2064
	v_add_u32_e32 v181, 0x200000, v183
	global_load_dwordx4 v[56:59], v181, s[78:79]
	global_load_dwordx4 v[60:63], v181, s[78:79] offset:16
	global_load_dwordx4 v[64:67], v181, s[78:79] offset:2048
	global_load_dwordx4 v[68:71], v181, s[78:79] offset:2064
	v_add_u32_e32 v181, 0x400000, v183
	global_load_dwordx4 v[72:75], v181, s[78:79]
	global_load_dwordx4 v[76:79], v181, s[78:79] offset:16
	global_load_dwordx4 v[80:83], v181, s[78:79] offset:2048
	global_load_dwordx4 v[84:87], v181, s[78:79] offset:2064
	v_add_u32_e32 v181, 0x600000, v183
	global_load_dwordx4 v[88:91], v181, s[78:79]
	global_load_dwordx4 v[92:95], v181, s[78:79] offset:16
	global_load_dwordx4 v[96:99], v181, s[78:79] offset:2048
	global_load_dwordx4 v[100:103], v181, s[78:79] offset:2064
	v_add_u32_e32 v181, 0x800000, v183
	global_load_dwordx4 v[104:107], v181, s[78:79]
	global_load_dwordx4 v[108:111], v181, s[78:79] offset:16
	global_load_dwordx4 v[112:115], v181, s[78:79] offset:2048
	global_load_dwordx4 v[116:119], v181, s[78:79] offset:2064
	v_add_u32_e32 v181, 0xa00000, v183
	global_load_dwordx4 v[120:123], v181, s[78:79]
	global_load_dwordx4 v[124:127], v181, s[78:79] offset:16
	global_load_dwordx4 v[128:131], v181, s[78:79] offset:2048
	global_load_dwordx4 v[132:135], v181, s[78:79] offset:2064
	v_add_u32_e32 v181, 0xc00000, v183
	global_load_dwordx4 v[136:139], v181, s[78:79]
	global_load_dwordx4 v[140:143], v181, s[78:79] offset:16
	global_load_dwordx4 v[144:147], v181, s[78:79] offset:2048
	global_load_dwordx4 v[148:151], v181, s[78:79] offset:2064
	v_mov_b32_e32 v178, v183
	s_waitcnt vmcnt(34)
	v_lshlrev_b32_e32 v194, 16, v0
	v_and_b32_e32 v195, 0xffff0000, v0
	v_lshlrev_b32_e32 v196, 16, v1
	v_and_b32_e32 v197, 0xffff0000, v1
	v_lshlrev_b32_e32 v198, 16, v2
	v_and_b32_e32 v199, 0xffff0000, v2
	v_lshlrev_b32_e32 v200, 16, v3
	v_and_b32_e32 v201, 0xffff0000, v3
	v_lshlrev_b32_e32 v202, 16, v4
	v_and_b32_e32 v203, 0xffff0000, v4
	v_lshlrev_b32_e32 v204, 16, v5
	v_and_b32_e32 v205, 0xffff0000, v5
	v_lshlrev_b32_e32 v206, 16, v6
	v_and_b32_e32 v207, 0xffff0000, v6
	v_lshlrev_b32_e32 v208, 16, v7
	v_and_b32_e32 v209, 0xffff0000, v7
	v_lshlrev_b32_e32 v216, 16, v8
	v_and_b32_e32 v217, 0xffff0000, v8
	v_lshlrev_b32_e32 v218, 16, v9
	v_and_b32_e32 v219, 0xffff0000, v9
	v_lshlrev_b32_e32 v220, 16, v10
	v_and_b32_e32 v221, 0xffff0000, v10
	v_lshlrev_b32_e32 v222, 16, v11
	v_and_b32_e32 v223, 0xffff0000, v11
	v_lshlrev_b32_e32 v224, 16, v12
	v_and_b32_e32 v225, 0xffff0000, v12
	v_lshlrev_b32_e32 v226, 16, v13
	v_and_b32_e32 v227, 0xffff0000, v13
	v_lshlrev_b32_e32 v228, 16, v14
	v_and_b32_e32 v229, 0xffff0000, v14
	v_lshlrev_b32_e32 v230, 16, v15
	v_and_b32_e32 v231, 0xffff0000, v15
	v_pk_mul_f32 v[252:253], v[216:217], v[216:217]
	v_pk_mul_f32 v[254:255], v[218:219], v[218:219]
	v_pk_fma_f32 v[252:253], v[220:221], v[220:221], v[252:253]
	v_pk_fma_f32 v[254:255], v[222:223], v[222:223], v[254:255]
	v_pk_fma_f32 v[252:253], v[224:225], v[224:225], v[252:253]
	v_pk_fma_f32 v[254:255], v[226:227], v[226:227], v[254:255]
	v_pk_fma_f32 v[252:253], v[228:229], v[228:229], v[252:253]
	v_pk_fma_f32 v[254:255], v[230:231], v[230:231], v[254:255]
	v_pk_add_f32 v[252:253], v[252:253], v[254:255]
	s_nop 0
	v_add_f32_e32 v183, v252, v253
	s_nop 1
	v_add_f32_dpp v183, v183, v183 quad_perm:[1,0,3,2] row_mask:0xf bank_mask:0xf bound_ctrl:1
	s_nop 1
	v_add_f32_dpp v183, v183, v183 quad_perm:[2,3,0,1] row_mask:0xf bank_mask:0xf bound_ctrl:1
	s_nop 1
	v_add_f32_dpp v183, v183, v183 row_half_mirror row_mask:0xf bank_mask:0xf bound_ctrl:1
	s_nop 1
	v_add_f32_dpp v183, v183, v183 row_mirror row_mask:0xf bank_mask:0xf bound_ctrl:1
	s_nop 1
	v_readlane_b32 s98, v183, 0
	v_readlane_b32 s99, v183, 16
	v_readlane_b32 s100, v183, 32
	v_readlane_b32 s101, v183, 48
	s_nop 1
	v_mov_b32_e32 v183, s98
	v_add_f32_e32 v183, s99, v183
	v_add_f32_e32 v183, s100, v183
	v_add_f32_e32 v183, s101, v183
	v_fmamk_f32 v183, v183, 0x3a800000, v182
	v_cmp_gt_f32_e32 vcc, 0x800000, v183
	v_mul_f32_e32 v181, 0x4b800000, v183
	s_nop 1
	v_cndmask_b32_e32 v183, v183, v181, vcc
	v_rsq_f32_e32 v183, v183
	s_nop 0
	v_mul_f32_e32 v181, 0x45800000, v183
	v_cndmask_b32_e32 v184, v183, v181, vcc
	v_mov_b32_e32 v185, v184
	v_pk_mul_f32 v[216:217], v[216:217], v[184:185]
	v_pk_mul_f32 v[218:219], v[218:219], v[184:185]
	v_pk_mul_f32 v[220:221], v[220:221], v[184:185]
	v_pk_mul_f32 v[222:223], v[222:223], v[184:185]
	v_pk_mul_f32 v[224:225], v[224:225], v[184:185]
	v_pk_mul_f32 v[226:227], v[226:227], v[184:185]
	v_pk_mul_f32 v[228:229], v[228:229], v[184:185]
	v_pk_mul_f32 v[230:231], v[230:231], v[184:185]
	v_pk_fma_f32 v[194:195], v[216:217], v[160:161], v[194:195]
	v_pk_fma_f32 v[196:197], v[218:219], v[162:163], v[196:197]
	v_pk_fma_f32 v[198:199], v[220:221], v[164:165], v[198:199]
	v_pk_fma_f32 v[200:201], v[222:223], v[166:167], v[200:201]
	v_pk_fma_f32 v[202:203], v[224:225], v[168:169], v[202:203]
	v_pk_fma_f32 v[204:205], v[226:227], v[170:171], v[204:205]
	v_pk_fma_f32 v[206:207], v[228:229], v[172:173], v[206:207]
	v_pk_fma_f32 v[208:209], v[230:231], v[174:175], v[208:209]
	v_pk_mul_f32 v[252:253], v[194:195], v[194:195]
	v_pk_mul_f32 v[254:255], v[196:197], v[196:197]
	v_pk_fma_f32 v[252:253], v[198:199], v[198:199], v[252:253]
	v_pk_fma_f32 v[254:255], v[200:201], v[200:201], v[254:255]
	v_pk_fma_f32 v[252:253], v[202:203], v[202:203], v[252:253]
	v_pk_fma_f32 v[254:255], v[204:205], v[204:205], v[254:255]
	v_pk_fma_f32 v[252:253], v[206:207], v[206:207], v[252:253]
	v_pk_fma_f32 v[254:255], v[208:209], v[208:209], v[254:255]
	v_pk_add_f32 v[252:253], v[252:253], v[254:255]
	s_nop 0
	v_add_f32_e32 v183, v252, v253
	s_nop 1
	v_add_f32_dpp v183, v183, v183 quad_perm:[1,0,3,2] row_mask:0xf bank_mask:0xf bound_ctrl:1
	s_nop 1
	v_add_f32_dpp v183, v183, v183 quad_perm:[2,3,0,1] row_mask:0xf bank_mask:0xf bound_ctrl:1
	s_nop 1
	v_add_f32_dpp v183, v183, v183 row_half_mirror row_mask:0xf bank_mask:0xf bound_ctrl:1
	s_nop 1
	v_add_f32_dpp v183, v183, v183 row_mirror row_mask:0xf bank_mask:0xf bound_ctrl:1
	s_nop 1
	v_readlane_b32 s98, v183, 0
	v_readlane_b32 s99, v183, 16
	v_readlane_b32 s100, v183, 32
	v_readlane_b32 s101, v183, 48
	s_nop 1
	v_mov_b32_e32 v183, s98
	v_add_f32_e32 v183, s99, v183
	v_add_f32_e32 v183, s100, v183
	v_add_f32_e32 v183, s101, v183
	v_fmamk_f32 v183, v183, 0x3a800000, v182
	v_cmp_gt_f32_e32 vcc, 0x800000, v183
	v_mul_f32_e32 v181, 0x4b800000, v183
	s_nop 1
	v_cndmask_b32_e32 v183, v183, v181, vcc
	v_rsq_f32_e32 v183, v183
	s_nop 0
	v_mul_f32_e32 v181, 0x45800000, v183
	v_cndmask_b32_e32 v184, v183, v181, vcc
	v_mov_b32_e32 v185, v184
	v_cvt_pk_bf16_f32 v0, v194, v195
	v_cvt_pk_bf16_f32 v1, v196, v197
	v_cvt_pk_bf16_f32 v2, v198, v199
	v_cvt_pk_bf16_f32 v3, v200, v201
	v_cvt_pk_bf16_f32 v4, v202, v203
	v_cvt_pk_bf16_f32 v5, v204, v205
	v_cvt_pk_bf16_f32 v6, v206, v207
	v_cvt_pk_bf16_f32 v7, v208, v209
	v_add_u32_e32 v181, 0x1800000, v177
	global_store_dwordx4 v181, v[0:3], s[78:79]
	global_store_dwordx4 v181, v[4:7], s[78:79] offset:1024
	v_add_u32_e32 v236, 0x0, v237
	s_mov_b64 exec, 1
	global_store_dword v236, v184, s[78:79]
	s_mov_b64 exec, -1
	s_waitcnt vmcnt(30)
	v_lshlrev_b32_e32 v194, 16, v16
	v_and_b32_e32 v195, 0xffff0000, v16
	v_lshlrev_b32_e32 v196, 16, v17
	v_and_b32_e32 v197, 0xffff0000, v17
	v_lshlrev_b32_e32 v198, 16, v18
	v_and_b32_e32 v199, 0xffff0000, v18
	v_lshlrev_b32_e32 v200, 16, v19
	v_and_b32_e32 v201, 0xffff0000, v19
	v_lshlrev_b32_e32 v202, 16, v20
	v_and_b32_e32 v203, 0xffff0000, v20
	v_lshlrev_b32_e32 v204, 16, v21
	v_and_b32_e32 v205, 0xffff0000, v21
	v_lshlrev_b32_e32 v206, 16, v22
	v_and_b32_e32 v207, 0xffff0000, v22
	v_lshlrev_b32_e32 v208, 16, v23
	v_and_b32_e32 v209, 0xffff0000, v23
	v_lshlrev_b32_e32 v216, 16, v24
	v_and_b32_e32 v217, 0xffff0000, v24
	v_lshlrev_b32_e32 v218, 16, v25
	v_and_b32_e32 v219, 0xffff0000, v25
	v_lshlrev_b32_e32 v220, 16, v26
	v_and_b32_e32 v221, 0xffff0000, v26
	v_lshlrev_b32_e32 v222, 16, v27
	v_and_b32_e32 v223, 0xffff0000, v27
	v_lshlrev_b32_e32 v224, 16, v28
	v_and_b32_e32 v225, 0xffff0000, v28
	v_lshlrev_b32_e32 v226, 16, v29
	v_and_b32_e32 v227, 0xffff0000, v29
	v_lshlrev_b32_e32 v228, 16, v30
	v_and_b32_e32 v229, 0xffff0000, v30
	v_lshlrev_b32_e32 v230, 16, v31
	v_and_b32_e32 v231, 0xffff0000, v31
	v_pk_mul_f32 v[252:253], v[216:217], v[216:217]
	v_pk_mul_f32 v[254:255], v[218:219], v[218:219]
	v_pk_fma_f32 v[252:253], v[220:221], v[220:221], v[252:253]
	v_pk_fma_f32 v[254:255], v[222:223], v[222:223], v[254:255]
	v_pk_fma_f32 v[252:253], v[224:225], v[224:225], v[252:253]
	v_pk_fma_f32 v[254:255], v[226:227], v[226:227], v[254:255]
	v_pk_fma_f32 v[252:253], v[228:229], v[228:229], v[252:253]
	v_pk_fma_f32 v[254:255], v[230:231], v[230:231], v[254:255]
	v_pk_add_f32 v[252:253], v[252:253], v[254:255]
	s_nop 0
	v_add_f32_e32 v183, v252, v253
	s_nop 1
	v_add_f32_dpp v183, v183, v183 quad_perm:[1,0,3,2] row_mask:0xf bank_mask:0xf bound_ctrl:1
	s_nop 1
	v_add_f32_dpp v183, v183, v183 quad_perm:[2,3,0,1] row_mask:0xf bank_mask:0xf bound_ctrl:1
	s_nop 1
	v_add_f32_dpp v183, v183, v183 row_half_mirror row_mask:0xf bank_mask:0xf bound_ctrl:1
	s_nop 1
	v_add_f32_dpp v183, v183, v183 row_mirror row_mask:0xf bank_mask:0xf bound_ctrl:1
	s_nop 1
	v_readlane_b32 s98, v183, 0
	v_readlane_b32 s99, v183, 16
	v_readlane_b32 s100, v183, 32
	v_readlane_b32 s101, v183, 48
	s_nop 1
	v_mov_b32_e32 v183, s98
	v_add_f32_e32 v183, s99, v183
	v_add_f32_e32 v183, s100, v183
	v_add_f32_e32 v183, s101, v183
	v_fmamk_f32 v183, v183, 0x3a800000, v182
	v_cmp_gt_f32_e32 vcc, 0x800000, v183
	v_mul_f32_e32 v181, 0x4b800000, v183
	s_nop 1
	v_cndmask_b32_e32 v183, v183, v181, vcc
	v_rsq_f32_e32 v183, v183
	s_nop 0
	v_mul_f32_e32 v181, 0x45800000, v183
	v_cndmask_b32_e32 v184, v183, v181, vcc
	v_mov_b32_e32 v185, v184
	v_pk_mul_f32 v[216:217], v[216:217], v[184:185]
	v_pk_mul_f32 v[218:219], v[218:219], v[184:185]
	v_pk_mul_f32 v[220:221], v[220:221], v[184:185]
	v_pk_mul_f32 v[222:223], v[222:223], v[184:185]
	v_pk_mul_f32 v[224:225], v[224:225], v[184:185]
	v_pk_mul_f32 v[226:227], v[226:227], v[184:185]
	v_pk_mul_f32 v[228:229], v[228:229], v[184:185]
	v_pk_mul_f32 v[230:231], v[230:231], v[184:185]
	v_pk_fma_f32 v[194:195], v[216:217], v[160:161], v[194:195]
	v_pk_fma_f32 v[196:197], v[218:219], v[162:163], v[196:197]
	v_pk_fma_f32 v[198:199], v[220:221], v[164:165], v[198:199]
	v_pk_fma_f32 v[200:201], v[222:223], v[166:167], v[200:201]
	v_pk_fma_f32 v[202:203], v[224:225], v[168:169], v[202:203]
	v_pk_fma_f32 v[204:205], v[226:227], v[170:171], v[204:205]
	v_pk_fma_f32 v[206:207], v[228:229], v[172:173], v[206:207]
	v_pk_fma_f32 v[208:209], v[230:231], v[174:175], v[208:209]
	v_pk_mul_f32 v[252:253], v[194:195], v[194:195]
	v_pk_mul_f32 v[254:255], v[196:197], v[196:197]
	v_pk_fma_f32 v[252:253], v[198:199], v[198:199], v[252:253]
	v_pk_fma_f32 v[254:255], v[200:201], v[200:201], v[254:255]
	v_pk_fma_f32 v[252:253], v[202:203], v[202:203], v[252:253]
	v_pk_fma_f32 v[254:255], v[204:205], v[204:205], v[254:255]
	v_pk_fma_f32 v[252:253], v[206:207], v[206:207], v[252:253]
	v_pk_fma_f32 v[254:255], v[208:209], v[208:209], v[254:255]
	v_pk_add_f32 v[252:253], v[252:253], v[254:255]
	s_nop 0
	v_add_f32_e32 v183, v252, v253
	s_nop 1
	v_add_f32_dpp v183, v183, v183 quad_perm:[1,0,3,2] row_mask:0xf bank_mask:0xf bound_ctrl:1
	s_nop 1
	v_add_f32_dpp v183, v183, v183 quad_perm:[2,3,0,1] row_mask:0xf bank_mask:0xf bound_ctrl:1
	s_nop 1
	v_add_f32_dpp v183, v183, v183 row_half_mirror row_mask:0xf bank_mask:0xf bound_ctrl:1
	s_nop 1
	v_add_f32_dpp v183, v183, v183 row_mirror row_mask:0xf bank_mask:0xf bound_ctrl:1
	s_nop 1
	v_readlane_b32 s98, v183, 0
	v_readlane_b32 s99, v183, 16
	v_readlane_b32 s100, v183, 32
	v_readlane_b32 s101, v183, 48
	s_nop 1
	v_mov_b32_e32 v183, s98
	v_add_f32_e32 v183, s99, v183
	v_add_f32_e32 v183, s100, v183
	v_add_f32_e32 v183, s101, v183
	v_fmamk_f32 v183, v183, 0x3a800000, v182
	v_cmp_gt_f32_e32 vcc, 0x800000, v183
	v_mul_f32_e32 v181, 0x4b800000, v183
	s_nop 1
	v_cndmask_b32_e32 v183, v183, v181, vcc
	v_rsq_f32_e32 v183, v183
	s_nop 0
	v_mul_f32_e32 v181, 0x45800000, v183
	v_cndmask_b32_e32 v184, v183, v181, vcc
	v_mov_b32_e32 v185, v184
	v_cvt_pk_bf16_f32 v16, v194, v195
	v_cvt_pk_bf16_f32 v17, v196, v197
	v_cvt_pk_bf16_f32 v18, v198, v199
	v_cvt_pk_bf16_f32 v19, v200, v201
	v_cvt_pk_bf16_f32 v20, v202, v203
	v_cvt_pk_bf16_f32 v21, v204, v205
	v_cvt_pk_bf16_f32 v22, v206, v207
	v_cvt_pk_bf16_f32 v23, v208, v209
	v_add_u32_e32 v181, 0x1c00000, v177
	global_store_dwordx4 v181, v[16:19], s[78:79]
	global_store_dwordx4 v181, v[20:23], s[78:79] offset:1024
	v_add_u32_e32 v236, 0x2000, v237
	s_mov_b64 exec, 1
	global_store_dword v236, v184, s[78:79]
	s_mov_b64 exec, -1
	s_waitcnt vmcnt(24)
	v_pk_add_f32 v[216:217], v[40:41], 0 op_sel_hi:[1,0]
	v_pk_add_f32 v[218:219], v[42:43], 0 op_sel_hi:[1,0]
	v_pk_add_f32 v[220:221], v[44:45], 0 op_sel_hi:[1,0]
	v_pk_add_f32 v[222:223], v[46:47], 0 op_sel_hi:[1,0]
	v_pk_add_f32 v[224:225], v[48:49], 0 op_sel_hi:[1,0]
	v_pk_add_f32 v[226:227], v[50:51], 0 op_sel_hi:[1,0]
	v_pk_add_f32 v[228:229], v[52:53], 0 op_sel_hi:[1,0]
	v_pk_add_f32 v[230:231], v[54:55], 0 op_sel_hi:[1,0]
	s_waitcnt vmcnt(20)
	v_pk_add_f32 v[216:217], v[216:217], v[56:57]
	v_pk_add_f32 v[218:219], v[218:219], v[58:59]
	v_pk_add_f32 v[220:221], v[220:221], v[60:61]
	v_pk_add_f32 v[222:223], v[222:223], v[62:63]
	v_pk_add_f32 v[224:225], v[224:225], v[64:65]
	v_pk_add_f32 v[226:227], v[226:227], v[66:67]
	v_pk_add_f32 v[228:229], v[228:229], v[68:69]
	v_pk_add_f32 v[230:231], v[230:231], v[70:71]
	v_lshlrev_b32_e32 v194, 16, v32
	v_and_b32_e32 v195, 0xffff0000, v32
	v_lshlrev_b32_e32 v196, 16, v33
	v_and_b32_e32 v197, 0xffff0000, v33
	v_lshlrev_b32_e32 v198, 16, v34
	v_and_b32_e32 v199, 0xffff0000, v34
	v_lshlrev_b32_e32 v200, 16, v35
	v_and_b32_e32 v201, 0xffff0000, v35
	v_lshlrev_b32_e32 v202, 16, v36
	v_and_b32_e32 v203, 0xffff0000, v36
	v_lshlrev_b32_e32 v204, 16, v37
	v_and_b32_e32 v205, 0xffff0000, v37
	v_lshlrev_b32_e32 v206, 16, v38
	v_and_b32_e32 v207, 0xffff0000, v38
	v_lshlrev_b32_e32 v208, 16, v39
	v_and_b32_e32 v209, 0xffff0000, v39
	v_add_u32_e32 v181, 0xe00000, v178
	global_load_dwordx4 v[0:3], v181, s[78:79]
	global_load_dwordx4 v[4:7], v181, s[78:79] offset:16
	global_load_dwordx4 v[8:11], v181, s[78:79] offset:2048
	global_load_dwordx4 v[12:15], v181, s[78:79] offset:2064
	s_waitcnt vmcnt(20)
	v_pk_add_f32 v[216:217], v[216:217], v[72:73]
	v_pk_add_f32 v[218:219], v[218:219], v[74:75]
	v_pk_add_f32 v[220:221], v[220:221], v[76:77]
	v_pk_add_f32 v[222:223], v[222:223], v[78:79]
	v_pk_add_f32 v[224:225], v[224:225], v[80:81]
	v_pk_add_f32 v[226:227], v[226:227], v[82:83]
	v_pk_add_f32 v[228:229], v[228:229], v[84:85]
	v_pk_add_f32 v[230:231], v[230:231], v[86:87]
	s_waitcnt vmcnt(16)
	v_pk_add_f32 v[216:217], v[216:217], v[88:89]
	v_pk_add_f32 v[218:219], v[218:219], v[90:91]
	v_pk_add_f32 v[220:221], v[220:221], v[92:93]
	v_pk_add_f32 v[222:223], v[222:223], v[94:95]
	v_pk_add_f32 v[224:225], v[224:225], v[96:97]
	v_pk_add_f32 v[226:227], v[226:227], v[98:99]
	v_pk_add_f32 v[228:229], v[228:229], v[100:101]
	v_pk_add_f32 v[230:231], v[230:231], v[102:103]
	s_waitcnt vmcnt(12)
	v_pk_add_f32 v[216:217], v[216:217], v[104:105]
	v_pk_add_f32 v[218:219], v[218:219], v[106:107]
	v_pk_add_f32 v[220:221], v[220:221], v[108:109]
	v_pk_add_f32 v[222:223], v[222:223], v[110:111]
	v_pk_add_f32 v[224:225], v[224:225], v[112:113]
	v_pk_add_f32 v[226:227], v[226:227], v[114:115]
	v_pk_add_f32 v[228:229], v[228:229], v[116:117]
	v_pk_add_f32 v[230:231], v[230:231], v[118:119]
	s_waitcnt vmcnt(8)
	v_pk_add_f32 v[216:217], v[216:217], v[120:121]
	v_pk_add_f32 v[218:219], v[218:219], v[122:123]
	v_pk_add_f32 v[220:221], v[220:221], v[124:125]
	v_pk_add_f32 v[222:223], v[222:223], v[126:127]
	v_pk_add_f32 v[224:225], v[224:225], v[128:129]
	v_pk_add_f32 v[226:227], v[226:227], v[130:131]
	v_pk_add_f32 v[228:229], v[228:229], v[132:133]
	v_pk_add_f32 v[230:231], v[230:231], v[134:135]
	s_waitcnt vmcnt(4)
	v_pk_add_f32 v[216:217], v[216:217], v[136:137]
	v_pk_add_f32 v[218:219], v[218:219], v[138:139]
	v_pk_add_f32 v[220:221], v[220:221], v[140:141]
	v_pk_add_f32 v[222:223], v[222:223], v[142:143]
	v_pk_add_f32 v[224:225], v[224:225], v[144:145]
	v_pk_add_f32 v[226:227], v[226:227], v[146:147]
	v_pk_add_f32 v[228:229], v[228:229], v[148:149]
	v_pk_add_f32 v[230:231], v[230:231], v[150:151]
	s_waitcnt vmcnt(0)
	v_pk_add_f32 v[216:217], v[216:217], v[0:1]
	v_pk_add_f32 v[218:219], v[218:219], v[2:3]
	v_pk_add_f32 v[220:221], v[220:221], v[4:5]
	v_pk_add_f32 v[222:223], v[222:223], v[6:7]
	v_pk_add_f32 v[224:225], v[224:225], v[8:9]
	v_pk_add_f32 v[226:227], v[226:227], v[10:11]
	v_pk_add_f32 v[228:229], v[228:229], v[12:13]
	v_pk_add_f32 v[230:231], v[230:231], v[14:15]
	v_pk_mul_f32 v[252:253], v[216:217], v[216:217]
	v_pk_mul_f32 v[254:255], v[218:219], v[218:219]
	v_pk_fma_f32 v[252:253], v[220:221], v[220:221], v[252:253]
	v_pk_fma_f32 v[254:255], v[222:223], v[222:223], v[254:255]
	v_pk_fma_f32 v[252:253], v[224:225], v[224:225], v[252:253]
	v_pk_fma_f32 v[254:255], v[226:227], v[226:227], v[254:255]
	v_pk_fma_f32 v[252:253], v[228:229], v[228:229], v[252:253]
	v_pk_fma_f32 v[254:255], v[230:231], v[230:231], v[254:255]
	v_pk_add_f32 v[252:253], v[252:253], v[254:255]
	s_nop 0
	v_add_f32_e32 v183, v252, v253
	s_nop 1
	v_add_f32_dpp v183, v183, v183 quad_perm:[1,0,3,2] row_mask:0xf bank_mask:0xf bound_ctrl:1
	s_nop 1
	v_add_f32_dpp v183, v183, v183 quad_perm:[2,3,0,1] row_mask:0xf bank_mask:0xf bound_ctrl:1
	s_nop 1
	v_add_f32_dpp v183, v183, v183 row_half_mirror row_mask:0xf bank_mask:0xf bound_ctrl:1
	s_nop 1
	v_add_f32_dpp v183, v183, v183 row_mirror row_mask:0xf bank_mask:0xf bound_ctrl:1
	s_nop 1
	v_readlane_b32 s98, v183, 0
	v_readlane_b32 s99, v183, 16
	v_readlane_b32 s100, v183, 32
	v_readlane_b32 s101, v183, 48
	s_nop 1
	v_mov_b32_e32 v183, s98
	v_add_f32_e32 v183, s99, v183
	v_add_f32_e32 v183, s100, v183
	v_add_f32_e32 v183, s101, v183
	v_fmamk_f32 v183, v183, 0x3a800000, v182
	v_cmp_gt_f32_e32 vcc, 0x800000, v183
	v_mul_f32_e32 v181, 0x4b800000, v183
	s_nop 1
	v_cndmask_b32_e32 v183, v183, v181, vcc
	v_rsq_f32_e32 v183, v183
	s_nop 0
	v_mul_f32_e32 v181, 0x45800000, v183
	v_cndmask_b32_e32 v184, v183, v181, vcc
	v_mov_b32_e32 v185, v184
	v_pk_mul_f32 v[216:217], v[216:217], v[184:185]
	v_pk_mul_f32 v[218:219], v[218:219], v[184:185]
	v_pk_mul_f32 v[220:221], v[220:221], v[184:185]
	v_pk_mul_f32 v[222:223], v[222:223], v[184:185]
	v_pk_mul_f32 v[224:225], v[224:225], v[184:185]
	v_pk_mul_f32 v[226:227], v[226:227], v[184:185]
	v_pk_mul_f32 v[228:229], v[228:229], v[184:185]
	v_pk_mul_f32 v[230:231], v[230:231], v[184:185]
	v_pk_fma_f32 v[194:195], v[216:217], v[160:161], v[194:195]
	v_pk_fma_f32 v[196:197], v[218:219], v[162:163], v[196:197]
	v_pk_fma_f32 v[198:199], v[220:221], v[164:165], v[198:199]
	v_pk_fma_f32 v[200:201], v[222:223], v[166:167], v[200:201]
	v_pk_fma_f32 v[202:203], v[224:225], v[168:169], v[202:203]
	v_pk_fma_f32 v[204:205], v[226:227], v[170:171], v[204:205]
	v_pk_fma_f32 v[206:207], v[228:229], v[172:173], v[206:207]
	v_pk_fma_f32 v[208:209], v[230:231], v[174:175], v[208:209]
	v_pk_mul_f32 v[252:253], v[194:195], v[194:195]
	v_pk_mul_f32 v[254:255], v[196:197], v[196:197]
	v_pk_fma_f32 v[252:253], v[198:199], v[198:199], v[252:253]
	v_pk_fma_f32 v[254:255], v[200:201], v[200:201], v[254:255]
	v_pk_fma_f32 v[252:253], v[202:203], v[202:203], v[252:253]
	v_pk_fma_f32 v[254:255], v[204:205], v[204:205], v[254:255]
	v_pk_fma_f32 v[252:253], v[206:207], v[206:207], v[252:253]
	v_pk_fma_f32 v[254:255], v[208:209], v[208:209], v[254:255]
	v_pk_add_f32 v[252:253], v[252:253], v[254:255]
	s_nop 0
	v_add_f32_e32 v183, v252, v253
	s_nop 1
	v_add_f32_dpp v183, v183, v183 quad_perm:[1,0,3,2] row_mask:0xf bank_mask:0xf bound_ctrl:1
	s_nop 1
	v_add_f32_dpp v183, v183, v183 quad_perm:[2,3,0,1] row_mask:0xf bank_mask:0xf bound_ctrl:1
	s_nop 1
	v_add_f32_dpp v183, v183, v183 row_half_mirror row_mask:0xf bank_mask:0xf bound_ctrl:1
	s_nop 1
	v_add_f32_dpp v183, v183, v183 row_mirror row_mask:0xf bank_mask:0xf bound_ctrl:1
	s_nop 1
	v_readlane_b32 s98, v183, 0
	v_readlane_b32 s99, v183, 16
	v_readlane_b32 s100, v183, 32
	v_readlane_b32 s101, v183, 48
	s_nop 1
	v_mov_b32_e32 v183, s98
	v_add_f32_e32 v183, s99, v183
	v_add_f32_e32 v183, s100, v183
	v_add_f32_e32 v183, s101, v183
	v_fmamk_f32 v183, v183, 0x3a800000, v182
	v_cmp_gt_f32_e32 vcc, 0x800000, v183
	v_mul_f32_e32 v181, 0x4b800000, v183
	s_nop 1
	v_cndmask_b32_e32 v183, v183, v181, vcc
	v_rsq_f32_e32 v183, v183
	s_nop 0
	v_mul_f32_e32 v181, 0x45800000, v183
	v_cndmask_b32_e32 v184, v183, v181, vcc
	v_mov_b32_e32 v185, v184
	v_cvt_pk_bf16_f32 v32, v194, v195
	v_cvt_pk_bf16_f32 v33, v196, v197
	v_cvt_pk_bf16_f32 v34, v198, v199
	v_cvt_pk_bf16_f32 v35, v200, v201
	v_cvt_pk_bf16_f32 v36, v202, v203
	v_cvt_pk_bf16_f32 v37, v204, v205
	v_cvt_pk_bf16_f32 v38, v206, v207
	v_cvt_pk_bf16_f32 v39, v208, v209
	v_add_u32_e32 v181, 0x3800000, v210
	global_store_dwordx4 v181, v[32:35], s[78:79]
	global_store_dwordx4 v181, v[36:39], s[78:79] offset:1024
	v_add_u32_e32 v236, 0x10000, v211
	s_mov_b64 exec, 1
	global_store_dword v236, v184, s[78:79]
	s_mov_b64 exec, -1

.LBB0_721:
	v_readlane_b32 s0, v235, 52
	v_readlane_b32 s1, v235, 53
	s_and_b64 vcc, exec, s[0:1]
	s_waitcnt lgkmcnt(0)
	s_barrier
	v_mbcnt_lo_u32_b32 v0, -1, 0
	v_mbcnt_hi_u32_b32 v0, -1, v0
	v_writelane_b32 v234, s93, 4
	s_cbranch_vccnz .LBB0_741
	v_readlane_b32 s4, v235, 4
	v_readlane_b32 s8, v235, 8
	v_readlane_b32 s9, v235, 9
	v_readlane_b32 s6, v235, 6
	v_readlane_b32 s7, v235, 7
	v_readlane_b32 s12, v235, 12
	v_readlane_b32 s13, v235, 13
	v_readlane_b32 s8, v235, 61
	v_readlane_b32 s10, v235, 10
	v_readlane_b32 s6, v235, 0
	v_readlane_b32 s9, v235, 62
	s_mov_b32 s12, s8
	s_ashr_i32 s13, s8, 31
	v_lshlrev_b32_e32 v2, 3, v0
	v_readlane_b32 s11, v235, 11
	s_lshl_b32 s6, s6, 4
	s_add_i32 s0, s8, 0xffffc000
	s_lshl_b64 s[8:9], s[12:13], 2
	s_mov_b32 s10, s12
	v_ashrrev_i32_e32 v3, 31, v2
	v_readlane_b32 s5, v235, 5
	v_readlane_b32 s14, v235, 14
	v_readlane_b32 s15, v235, 15
	v_readlane_b32 s16, v235, 16
	v_readlane_b32 s17, v235, 17
	v_readlane_b32 s18, v235, 18
	v_readlane_b32 s19, v235, 19
	v_readlane_b32 s7, v235, 1
	s_add_u32 s80, s8, 0x10000
	v_writelane_b32 v235, s10, 61
	v_lshlrev_b64 v[4:5], 1, v[2:3]
	v_lshlrev_b64 v[2:3], 2, v[2:3]
	s_addc_u32 s14, s9, 0
	s_ashr_i32 s7, s6, 31
	v_writelane_b32 v235, s11, 62
	s_lshl_b64 s[10:11], s[12:13], 11
	v_lshl_add_u64 v[152:153], s[86:87], 0, v[4:5]
	v_lshl_add_u64 v[154:155], s[90:91], 0, v[2:3]
	v_lshl_add_u64 v[156:157], s[54:55], 0, v[4:5]
	v_lshl_add_u64 v[158:159], s[18:19], 0, v[2:3]
	s_mov_b32 s1, 0
	v_cmp_eq_u32_e64 s[4:5], 0, v0
	s_lshl_b64 s[8:9], s[6:7], 2
	v_lshl_add_u64 v[160:161], s[10:11], 0, v[4:5]
	s_lshl_b64 s[10:11], s[6:7], 11
	s_mov_b64 s[24:25], 0x600000
	s_mov_b64 s[26:27], 0x600800
	s_mov_b64 s[28:29], 0x800000
	s_mov_b32 s7, 0x800000
	s_mov_b64 s[36:37], 0x800800
	s_mov_b64 s[38:39], 0xa00000
	s_mov_b64 s[40:41], 0xa00800
	s_mov_b64 s[42:43], 0xc00000
	s_mov_b64 s[44:45], 0xc00800
	s_mov_b64 s[46:47], 0xe00000
	s_mov_b64 s[48:49], 0xe00800
	s_mov_b64 s[50:51], 0x1000000
	s_mov_b32 s15, 0x1000000
	s_mov_b64 s[12:13], 0x1000800
	s_mov_b64 s[82:83], 0x1200000
	s_mov_b32 s16, 0x1200000
	s_mov_b64 s[90:91], 0x1200800
	s_mov_b64 s[20:21], 0x1400000
	s_mov_b32 s17, 0x1400000
	s_mov_b64 s[22:23], 0x1400800
	v_mov_b32_e32 v215, 0
	v_mov_b32_e32 v216, 0x358637bd
	v_mbcnt_lo_u32_b32 v176, -1, 0
	v_mbcnt_hi_u32_b32 v176, -1, v176
	v_readlane_b32 s98, v235, 49
	v_readlane_b32 s99, v235, 20
	v_readlane_b32 s100, v235, 18
	v_readlane_b32 s101, v235, 19
	s_nop 3
	s_lshr_b32 vcc_lo, s98, 3
	s_and_b32 vcc_hi, vcc_lo, 7
	s_lshr_b32 vcc_lo, vcc_lo, 3
	s_lshl_b32 vcc_lo, vcc_lo, 3
	s_add_i32 vcc_lo, vcc_lo, s99
	s_lshl_b32 s98, vcc_hi, 8
	s_add_i32 s98, s98, vcc_lo
	v_mov_b32_e32 v179, s98
	v_lshlrev_b32_e32 v177, 4, v176
	s_lshl_b32 s99, s98, 11
	v_add_u32_e32 v177, s99, v177
	v_lshlrev_b32_e32 v180, 5, v176
	global_load_dwordx4 v[160:163], v180, s[100:101]
	global_load_dwordx4 v[164:167], v180, s[100:101] offset:16
	global_load_dwordx4 v[168:171], v180, s[100:101] offset:2048
	global_load_dwordx4 v[172:175], v180, s[100:101] offset:2064
	v_mov_b32_e32 v182, 0x358637bd
	v_lshlrev_b32_e32 v237, 2, v179
	v_add_u32_e32 v237, 0x10000, v237
	s_and_b32 s99, s98, 3
	s_cmp_eq_u32 s99, 0
	s_cbranch_scc1 .Lmyxupd_s_1
	s_mul_i32 s100, s99, 0x7ff800
	v_add_u32_e32 v210, s100, v177
	s_mul_i32 s100, s99, 16380
	v_add_u32_e32 v211, s100, v237
	v_add_u32_e32 v178, 0x1800000, v177
	v_add_u32_e32 v181, 0x9e00000, v177
	global_load_dwordx4 v[0:3], v178, s[78:79]
	global_load_dwordx4 v[4:7], v178, s[78:79] offset:1024
	global_load_dwordx4 v[8:11], v181, s[78:79]
	global_load_dwordx4 v[12:15], v181, s[78:79] offset:1024
	v_add_u32_e32 v178, 0x1c00000, v177
	v_add_u32_e32 v181, 0xa200000, v177
	global_load_dwordx4 v[16:19], v178, s[78:79]
	global_load_dwordx4 v[20:23], v178, s[78:79] offset:1024
	global_load_dwordx4 v[24:27], v181, s[78:79]
	global_load_dwordx4 v[28:31], v181, s[78:79] offset:1024
	v_add_u32_e32 v178, 0x2000000, v177
	v_add_u32_e32 v181, 0xa600000, v177
	global_load_dwordx4 v[32:35], v178, s[78:79]
	global_load_dwordx4 v[36:39], v178, s[78:79] offset:1024
	global_load_dwordx4 v[40:43], v181, s[78:79]
	global_load_dwordx4 v[44:47], v181, s[78:79] offset:1024
	v_add_u32_e32 v178, 0x2400000, v177
	v_add_u32_e32 v181, 0xaa00000, v177
	global_load_dwordx4 v[48:51], v178, s[78:79]
	global_load_dwordx4 v[52:55], v178, s[78:79] offset:1024
	global_load_dwordx4 v[56:59], v181, s[78:79]
	global_load_dwordx4 v[60:63], v181, s[78:79] offset:1024
	v_add_u32_e32 v178, 0x2800000, v177
	v_add_u32_e32 v181, 0xae00000, v177
	global_load_dwordx4 v[64:67], v178, s[78:79]
	global_load_dwordx4 v[68:71], v178, s[78:79] offset:1024
	global_load_dwordx4 v[72:75], v181, s[78:79]
	global_load_dwordx4 v[76:79], v181, s[78:79] offset:1024
	v_add_u32_e32 v178, 0x2c00000, v177
	v_add_u32_e32 v181, 0xb200000, v177
	global_load_dwordx4 v[80:83], v178, s[78:79]
	global_load_dwordx4 v[84:87], v178, s[78:79] offset:1024
	global_load_dwordx4 v[88:91], v181, s[78:79]
	global_load_dwordx4 v[92:95], v181, s[78:79] offset:1024
	v_add_u32_e32 v178, 0x3000000, v177
	v_add_u32_e32 v181, 0xb600000, v177
	global_load_dwordx4 v[96:99], v178, s[78:79]
	global_load_dwordx4 v[100:103], v178, s[78:79] offset:1024
	global_load_dwordx4 v[104:107], v181, s[78:79]
	global_load_dwordx4 v[108:111], v181, s[78:79] offset:1024
	v_add_u32_e32 v178, 0x3400000, v177
	v_add_u32_e32 v181, 0xba00000, v177
	global_load_dwordx4 v[112:115], v178, s[78:79]
	global_load_dwordx4 v[116:119], v178, s[78:79] offset:1024
	global_load_dwordx4 v[120:123], v181, s[78:79]
	global_load_dwordx4 v[124:127], v181, s[78:79] offset:1024
	v_add_u32_e32 v178, 0x1800000, v210
	v_add_u32_e32 v181, 0x9e00000, v210
	global_load_dwordx4 v[128:131], v178, s[78:79]
	global_load_dwordx4 v[132:135], v178, s[78:79] offset:1024
	global_load_dwordx4 v[136:139], v181, s[78:79]
	global_load_dwordx4 v[140:143], v181, s[78:79] offset:1024
	v_add_u32_e32 v178, 0x1c00000, v210
	v_add_u32_e32 v181, 0xa200000, v210
	global_load_dwordx4 v[144:147], v178, s[78:79]
	global_load_dwordx4 v[148:151], v178, s[78:79] offset:1024
	global_load_dwordx4 v[152:155], v181, s[78:79]
	global_load_dwordx4 v[156:159], v181, s[78:79] offset:1024
	s_waitcnt vmcnt(36)
	v_lshlrev_b32_e32 v194, 16, v0
	v_and_b32_e32 v195, 0xffff0000, v0
	v_lshlrev_b32_e32 v196, 16, v1
	v_and_b32_e32 v197, 0xffff0000, v1
	v_lshlrev_b32_e32 v198, 16, v2
	v_and_b32_e32 v199, 0xffff0000, v2
	v_lshlrev_b32_e32 v200, 16, v3
	v_and_b32_e32 v201, 0xffff0000, v3
	v_lshlrev_b32_e32 v202, 16, v4
	v_and_b32_e32 v203, 0xffff0000, v4
	v_lshlrev_b32_e32 v204, 16, v5
	v_and_b32_e32 v205, 0xffff0000, v5
	v_lshlrev_b32_e32 v206, 16, v6
	v_and_b32_e32 v207, 0xffff0000, v6
	v_lshlrev_b32_e32 v208, 16, v7
	v_and_b32_e32 v209, 0xffff0000, v7
	v_lshlrev_b32_e32 v216, 16, v8
	v_and_b32_e32 v217, 0xffff0000, v8
	v_lshlrev_b32_e32 v218, 16, v9
	v_and_b32_e32 v219, 0xffff0000, v9
	v_lshlrev_b32_e32 v220, 16, v10
	v_and_b32_e32 v221, 0xffff0000, v10
	v_lshlrev_b32_e32 v222, 16, v11
	v_and_b32_e32 v223, 0xffff0000, v11
	v_lshlrev_b32_e32 v224, 16, v12
	v_and_b32_e32 v225, 0xffff0000, v12
	v_lshlrev_b32_e32 v226, 16, v13
	v_and_b32_e32 v227, 0xffff0000, v13
	v_lshlrev_b32_e32 v228, 16, v14
	v_and_b32_e32 v229, 0xffff0000, v14
	v_lshlrev_b32_e32 v230, 16, v15
	v_and_b32_e32 v231, 0xffff0000, v15
	v_pk_mul_f32 v[252:253], v[216:217], v[216:217]
	v_pk_mul_f32 v[254:255], v[218:219], v[218:219]
	v_pk_fma_f32 v[252:253], v[220:221], v[220:221], v[252:253]
	v_pk_fma_f32 v[254:255], v[222:223], v[222:223], v[254:255]
	v_pk_fma_f32 v[252:253], v[224:225], v[224:225], v[252:253]
	v_pk_fma_f32 v[254:255], v[226:227], v[226:227], v[254:255]
	v_pk_fma_f32 v[252:253], v[228:229], v[228:229], v[252:253]
	v_pk_fma_f32 v[254:255], v[230:231], v[230:231], v[254:255]
	v_pk_add_f32 v[252:253], v[252:253], v[254:255]
	s_nop 0
	v_add_f32_e32 v183, v252, v253
	s_nop 1
	v_add_f32_dpp v183, v183, v183 quad_perm:[1,0,3,2] row_mask:0xf bank_mask:0xf bound_ctrl:1
	s_nop 1
	v_add_f32_dpp v183, v183, v183 quad_perm:[2,3,0,1] row_mask:0xf bank_mask:0xf bound_ctrl:1
	s_nop 1
	v_add_f32_dpp v183, v183, v183 row_half_mirror row_mask:0xf bank_mask:0xf bound_ctrl:1
	s_nop 1
	v_add_f32_dpp v183, v183, v183 row_mirror row_mask:0xf bank_mask:0xf bound_ctrl:1
	s_nop 1
	v_readlane_b32 s98, v183, 0
	v_readlane_b32 s99, v183, 16
	v_readlane_b32 s100, v183, 32
	v_readlane_b32 s101, v183, 48
	s_nop 1
	v_mov_b32_e32 v183, s98
	v_add_f32_e32 v183, s99, v183
	v_add_f32_e32 v183, s100, v183
	v_add_f32_e32 v183, s101, v183
	v_fmamk_f32 v183, v183, 0x3a800000, v182
	v_cmp_gt_f32_e32 vcc, 0x800000, v183
	v_mul_f32_e32 v181, 0x4b800000, v183
	s_nop 1
	v_cndmask_b32_e32 v183, v183, v181, vcc
	v_rsq_f32_e32 v183, v183
	s_nop 0
	v_mul_f32_e32 v181, 0x45800000, v183
	v_cndmask_b32_e32 v184, v183, v181, vcc
	v_mov_b32_e32 v185, v184
	v_pk_mul_f32 v[216:217], v[216:217], v[184:185]
	v_pk_mul_f32 v[218:219], v[218:219], v[184:185]
	v_pk_mul_f32 v[220:221], v[220:221], v[184:185]
	v_pk_mul_f32 v[222:223], v[222:223], v[184:185]
	v_pk_mul_f32 v[224:225], v[224:225], v[184:185]
	v_pk_mul_f32 v[226:227], v[226:227], v[184:185]
	v_pk_mul_f32 v[228:229], v[228:229], v[184:185]
	v_pk_mul_f32 v[230:231], v[230:231], v[184:185]
	v_pk_fma_f32 v[194:195], v[216:217], v[160:161], v[194:195]
	v_pk_fma_f32 v[196:197], v[218:219], v[162:163], v[196:197]
	v_pk_fma_f32 v[198:199], v[220:221], v[164:165], v[198:199]
	v_pk_fma_f32 v[200:201], v[222:223], v[166:167], v[200:201]
	v_pk_fma_f32 v[202:203], v[224:225], v[168:169], v[202:203]
	v_pk_fma_f32 v[204:205], v[226:227], v[170:171], v[204:205]
	v_pk_fma_f32 v[206:207], v[228:229], v[172:173], v[206:207]
	v_pk_fma_f32 v[208:209], v[230:231], v[174:175], v[208:209]
	v_pk_mul_f32 v[252:253], v[194:195], v[194:195]
	v_pk_mul_f32 v[254:255], v[196:197], v[196:197]
	v_pk_fma_f32 v[252:253], v[198:199], v[198:199], v[252:253]
	v_pk_fma_f32 v[254:255], v[200:201], v[200:201], v[254:255]
	v_pk_fma_f32 v[252:253], v[202:203], v[202:203], v[252:253]
	v_pk_fma_f32 v[254:255], v[204:205], v[204:205], v[254:255]
	v_pk_fma_f32 v[252:253], v[206:207], v[206:207], v[252:253]
	v_pk_fma_f32 v[254:255], v[208:209], v[208:209], v[254:255]
	v_pk_add_f32 v[252:253], v[252:253], v[254:255]
	s_nop 0
	v_add_f32_e32 v183, v252, v253
	s_nop 1
	v_add_f32_dpp v183, v183, v183 quad_perm:[1,0,3,2] row_mask:0xf bank_mask:0xf bound_ctrl:1
	s_nop 1
	v_add_f32_dpp v183, v183, v183 quad_perm:[2,3,0,1] row_mask:0xf bank_mask:0xf bound_ctrl:1
	s_nop 1
	v_add_f32_dpp v183, v183, v183 row_half_mirror row_mask:0xf bank_mask:0xf bound_ctrl:1
	s_nop 1
	v_add_f32_dpp v183, v183, v183 row_mirror row_mask:0xf bank_mask:0xf bound_ctrl:1
	s_nop 1
	v_readlane_b32 s98, v183, 0
	v_readlane_b32 s99, v183, 16
	v_readlane_b32 s100, v183, 32
	v_readlane_b32 s101, v183, 48
	s_nop 1
	v_mov_b32_e32 v183, s98
	v_add_f32_e32 v183, s99, v183
	v_add_f32_e32 v183, s100, v183
	v_add_f32_e32 v183, s101, v183
	v_fmamk_f32 v183, v183, 0x3a800000, v182
	v_cmp_gt_f32_e32 vcc, 0x800000, v183
	v_mul_f32_e32 v181, 0x4b800000, v183
	s_nop 1
	v_cndmask_b32_e32 v183, v183, v181, vcc
	v_rsq_f32_e32 v183, v183
	s_nop 0
	v_mul_f32_e32 v181, 0x45800000, v183
	v_cndmask_b32_e32 v184, v183, v181, vcc
	v_mov_b32_e32 v185, v184
	v_cvt_pk_bf16_f32 v0, v194, v195
	v_cvt_pk_bf16_f32 v1, v196, v197
	v_cvt_pk_bf16_f32 v2, v198, v199
	v_cvt_pk_bf16_f32 v3, v200, v201
	v_cvt_pk_bf16_f32 v4, v202, v203
	v_cvt_pk_bf16_f32 v5, v204, v205
	v_cvt_pk_bf16_f32 v6, v206, v207
	v_cvt_pk_bf16_f32 v7, v208, v209
	v_add_u32_e32 v181, 0x1800000, v177
	global_store_dwordx4 v181, v[0:3], s[78:79]
	global_store_dwordx4 v181, v[4:7], s[78:79] offset:1024
	v_add_u32_e32 v236, 0x0, v237
	s_mov_b64 exec, 1
	global_store_dword v236, v184, s[78:79]
	s_mov_b64 exec, -1
	s_waitcnt vmcnt(32)
	v_lshlrev_b32_e32 v194, 16, v16
	v_and_b32_e32 v195, 0xffff0000, v16
	v_lshlrev_b32_e32 v196, 16, v17
	v_and_b32_e32 v197, 0xffff0000, v17
	v_lshlrev_b32_e32 v198, 16, v18
	v_and_b32_e32 v199, 0xffff0000, v18
	v_lshlrev_b32_e32 v200, 16, v19
	v_and_b32_e32 v201, 0xffff0000, v19
	v_lshlrev_b32_e32 v202, 16, v20
	v_and_b32_e32 v203, 0xffff0000, v20
	v_lshlrev_b32_e32 v204, 16, v21
	v_and_b32_e32 v205, 0xffff0000, v21
	v_lshlrev_b32_e32 v206, 16, v22
	v_and_b32_e32 v207, 0xffff0000, v22
	v_lshlrev_b32_e32 v208, 16, v23
	v_and_b32_e32 v209, 0xffff0000, v23
	v_lshlrev_b32_e32 v216, 16, v24
	v_and_b32_e32 v217, 0xffff0000, v24
	v_lshlrev_b32_e32 v218, 16, v25
	v_and_b32_e32 v219, 0xffff0000, v25
	v_lshlrev_b32_e32 v220, 16, v26
	v_and_b32_e32 v221, 0xffff0000, v26
	v_lshlrev_b32_e32 v222, 16, v27
	v_and_b32_e32 v223, 0xffff0000, v27
	v_lshlrev_b32_e32 v224, 16, v28
	v_and_b32_e32 v225, 0xffff0000, v28
	v_lshlrev_b32_e32 v226, 16, v29
	v_and_b32_e32 v227, 0xffff0000, v29
	v_lshlrev_b32_e32 v228, 16, v30
	v_and_b32_e32 v229, 0xffff0000, v30
	v_lshlrev_b32_e32 v230, 16, v31
	v_and_b32_e32 v231, 0xffff0000, v31
	v_pk_mul_f32 v[252:253], v[216:217], v[216:217]
	v_pk_mul_f32 v[254:255], v[218:219], v[218:219]
	v_pk_fma_f32 v[252:253], v[220:221], v[220:221], v[252:253]
	v_pk_fma_f32 v[254:255], v[222:223], v[222:223], v[254:255]
	v_pk_fma_f32 v[252:253], v[224:225], v[224:225], v[252:253]
	v_pk_fma_f32 v[254:255], v[226:227], v[226:227], v[254:255]
	v_pk_fma_f32 v[252:253], v[228:229], v[228:229], v[252:253]
	v_pk_fma_f32 v[254:255], v[230:231], v[230:231], v[254:255]
	v_pk_add_f32 v[252:253], v[252:253], v[254:255]
	s_nop 0
	v_add_f32_e32 v183, v252, v253
	s_nop 1
	v_add_f32_dpp v183, v183, v183 quad_perm:[1,0,3,2] row_mask:0xf bank_mask:0xf bound_ctrl:1
	s_nop 1
	v_add_f32_dpp v183, v183, v183 quad_perm:[2,3,0,1] row_mask:0xf bank_mask:0xf bound_ctrl:1
	s_nop 1
	v_add_f32_dpp v183, v183, v183 row_half_mirror row_mask:0xf bank_mask:0xf bound_ctrl:1
	s_nop 1
	v_add_f32_dpp v183, v183, v183 row_mirror row_mask:0xf bank_mask:0xf bound_ctrl:1
	s_nop 1
	v_readlane_b32 s98, v183, 0
	v_readlane_b32 s99, v183, 16
	v_readlane_b32 s100, v183, 32
	v_readlane_b32 s101, v183, 48
	s_nop 1
	v_mov_b32_e32 v183, s98
	v_add_f32_e32 v183, s99, v183
	v_add_f32_e32 v183, s100, v183
	v_add_f32_e32 v183, s101, v183
	v_fmamk_f32 v183, v183, 0x3a800000, v182
	v_cmp_gt_f32_e32 vcc, 0x800000, v183
	v_mul_f32_e32 v181, 0x4b800000, v183
	s_nop 1
	v_cndmask_b32_e32 v183, v183, v181, vcc
	v_rsq_f32_e32 v183, v183
	s_nop 0
	v_mul_f32_e32 v181, 0x45800000, v183
	v_cndmask_b32_e32 v184, v183, v181, vcc
	v_mov_b32_e32 v185, v184
	v_pk_mul_f32 v[216:217], v[216:217], v[184:185]
	v_pk_mul_f32 v[218:219], v[218:219], v[184:185]
	v_pk_mul_f32 v[220:221], v[220:221], v[184:185]
	v_pk_mul_f32 v[222:223], v[222:223], v[184:185]
	v_pk_mul_f32 v[224:225], v[224:225], v[184:185]
	v_pk_mul_f32 v[226:227], v[226:227], v[184:185]
	v_pk_mul_f32 v[228:229], v[228:229], v[184:185]
	v_pk_mul_f32 v[230:231], v[230:231], v[184:185]
	v_pk_fma_f32 v[194:195], v[216:217], v[160:161], v[194:195]
	v_pk_fma_f32 v[196:197], v[218:219], v[162:163], v[196:197]
	v_pk_fma_f32 v[198:199], v[220:221], v[164:165], v[198:199]
	v_pk_fma_f32 v[200:201], v[222:223], v[166:167], v[200:201]
	v_pk_fma_f32 v[202:203], v[224:225], v[168:169], v[202:203]
	v_pk_fma_f32 v[204:205], v[226:227], v[170:171], v[204:205]
	v_pk_fma_f32 v[206:207], v[228:229], v[172:173], v[206:207]
	v_pk_fma_f32 v[208:209], v[230:231], v[174:175], v[208:209]
	v_pk_mul_f32 v[252:253], v[194:195], v[194:195]
	v_pk_mul_f32 v[254:255], v[196:197], v[196:197]
	v_pk_fma_f32 v[252:253], v[198:199], v[198:199], v[252:253]
	v_pk_fma_f32 v[254:255], v[200:201], v[200:201], v[254:255]
	v_pk_fma_f32 v[252:253], v[202:203], v[202:203], v[252:253]
	v_pk_fma_f32 v[254:255], v[204:205], v[204:205], v[254:255]
	v_pk_fma_f32 v[252:253], v[206:207], v[206:207], v[252:253]
	v_pk_fma_f32 v[254:255], v[208:209], v[208:209], v[254:255]
	v_pk_add_f32 v[252:253], v[252:253], v[254:255]
	s_nop 0
	v_add_f32_e32 v183, v252, v253
	s_nop 1
	v_add_f32_dpp v183, v183, v183 quad_perm:[1,0,3,2] row_mask:0xf bank_mask:0xf bound_ctrl:1
	s_nop 1
	v_add_f32_dpp v183, v183, v183 quad_perm:[2,3,0,1] row_mask:0xf bank_mask:0xf bound_ctrl:1
	s_nop 1
	v_add_f32_dpp v183, v183, v183 row_half_mirror row_mask:0xf bank_mask:0xf bound_ctrl:1
	s_nop 1
	v_add_f32_dpp v183, v183, v183 row_mirror row_mask:0xf bank_mask:0xf bound_ctrl:1
	s_nop 1
	v_readlane_b32 s98, v183, 0
	v_readlane_b32 s99, v183, 16
	v_readlane_b32 s100, v183, 32
	v_readlane_b32 s101, v183, 48
	s_nop 1
	v_mov_b32_e32 v183, s98
	v_add_f32_e32 v183, s99, v183
	v_add_f32_e32 v183, s100, v183
	v_add_f32_e32 v183, s101, v183
	v_fmamk_f32 v183, v183, 0x3a800000, v182
	v_cmp_gt_f32_e32 vcc, 0x800000, v183
	v_mul_f32_e32 v181, 0x4b800000, v183
	s_nop 1
	v_cndmask_b32_e32 v183, v183, v181, vcc
	v_rsq_f32_e32 v183, v183
	s_nop 0
	v_mul_f32_e32 v181, 0x45800000, v183
	v_cndmask_b32_e32 v184, v183, v181, vcc
	v_mov_b32_e32 v185, v184
	v_cvt_pk_bf16_f32 v16, v194, v195
	v_cvt_pk_bf16_f32 v17, v196, v197
	v_cvt_pk_bf16_f32 v18, v198, v199
	v_cvt_pk_bf16_f32 v19, v200, v201
	v_cvt_pk_bf16_f32 v20, v202, v203
	v_cvt_pk_bf16_f32 v21, v204, v205
	v_cvt_pk_bf16_f32 v22, v206, v207
	v_cvt_pk_bf16_f32 v23, v208, v209
	v_add_u32_e32 v181, 0x1c00000, v177
	global_store_dwordx4 v181, v[16:19], s[78:79]
	global_store_dwordx4 v181, v[20:23], s[78:79] offset:1024
	v_add_u32_e32 v236, 0x2000, v237
	s_mov_b64 exec, 1
	global_store_dword v236, v184, s[78:79]
	s_mov_b64 exec, -1
	s_waitcnt vmcnt(28)
	v_lshlrev_b32_e32 v194, 16, v32
	v_and_b32_e32 v195, 0xffff0000, v32
	v_lshlrev_b32_e32 v196, 16, v33
	v_and_b32_e32 v197, 0xffff0000, v33
	v_lshlrev_b32_e32 v198, 16, v34
	v_and_b32_e32 v199, 0xffff0000, v34
	v_lshlrev_b32_e32 v200, 16, v35
	v_and_b32_e32 v201, 0xffff0000, v35
	v_lshlrev_b32_e32 v202, 16, v36
	v_and_b32_e32 v203, 0xffff0000, v36
	v_lshlrev_b32_e32 v204, 16, v37
	v_and_b32_e32 v205, 0xffff0000, v37
	v_lshlrev_b32_e32 v206, 16, v38
	v_and_b32_e32 v207, 0xffff0000, v38
	v_lshlrev_b32_e32 v208, 16, v39
	v_and_b32_e32 v209, 0xffff0000, v39
	v_lshlrev_b32_e32 v216, 16, v40
	v_and_b32_e32 v217, 0xffff0000, v40
	v_lshlrev_b32_e32 v218, 16, v41
	v_and_b32_e32 v219, 0xffff0000, v41
	v_lshlrev_b32_e32 v220, 16, v42
	v_and_b32_e32 v221, 0xffff0000, v42
	v_lshlrev_b32_e32 v222, 16, v43
	v_and_b32_e32 v223, 0xffff0000, v43
	v_lshlrev_b32_e32 v224, 16, v44
	v_and_b32_e32 v225, 0xffff0000, v44
	v_lshlrev_b32_e32 v226, 16, v45
	v_and_b32_e32 v227, 0xffff0000, v45
	v_lshlrev_b32_e32 v228, 16, v46
	v_and_b32_e32 v229, 0xffff0000, v46
	v_lshlrev_b32_e32 v230, 16, v47
	v_and_b32_e32 v231, 0xffff0000, v47
	v_pk_mul_f32 v[252:253], v[216:217], v[216:217]
	v_pk_mul_f32 v[254:255], v[218:219], v[218:219]
	v_pk_fma_f32 v[252:253], v[220:221], v[220:221], v[252:253]
	v_pk_fma_f32 v[254:255], v[222:223], v[222:223], v[254:255]
	v_pk_fma_f32 v[252:253], v[224:225], v[224:225], v[252:253]
	v_pk_fma_f32 v[254:255], v[226:227], v[226:227], v[254:255]
	v_pk_fma_f32 v[252:253], v[228:229], v[228:229], v[252:253]
	v_pk_fma_f32 v[254:255], v[230:231], v[230:231], v[254:255]
	v_pk_add_f32 v[252:253], v[252:253], v[254:255]
	s_nop 0
	v_add_f32_e32 v183, v252, v253
	s_nop 1
	v_add_f32_dpp v183, v183, v183 quad_perm:[1,0,3,2] row_mask:0xf bank_mask:0xf bound_ctrl:1
	s_nop 1
	v_add_f32_dpp v183, v183, v183 quad_perm:[2,3,0,1] row_mask:0xf bank_mask:0xf bound_ctrl:1
	s_nop 1
	v_add_f32_dpp v183, v183, v183 row_half_mirror row_mask:0xf bank_mask:0xf bound_ctrl:1
	s_nop 1
	v_add_f32_dpp v183, v183, v183 row_mirror row_mask:0xf bank_mask:0xf bound_ctrl:1
	s_nop 1
	v_readlane_b32 s98, v183, 0
	v_readlane_b32 s99, v183, 16
	v_readlane_b32 s100, v183, 32
	v_readlane_b32 s101, v183, 48
	s_nop 1
	v_mov_b32_e32 v183, s98
	v_add_f32_e32 v183, s99, v183
	v_add_f32_e32 v183, s100, v183
	v_add_f32_e32 v183, s101, v183
	v_fmamk_f32 v183, v183, 0x3a800000, v182
	v_cmp_gt_f32_e32 vcc, 0x800000, v183
	v_mul_f32_e32 v181, 0x4b800000, v183
	s_nop 1
	v_cndmask_b32_e32 v183, v183, v181, vcc
	v_rsq_f32_e32 v183, v183
	s_nop 0
	v_mul_f32_e32 v181, 0x45800000, v183
	v_cndmask_b32_e32 v184, v183, v181, vcc
	v_mov_b32_e32 v185, v184
	v_pk_mul_f32 v[216:217], v[216:217], v[184:185]
	v_pk_mul_f32 v[218:219], v[218:219], v[184:185]
	v_pk_mul_f32 v[220:221], v[220:221], v[184:185]
	v_pk_mul_f32 v[222:223], v[222:223], v[184:185]
	v_pk_mul_f32 v[224:225], v[224:225], v[184:185]
	v_pk_mul_f32 v[226:227], v[226:227], v[184:185]
	v_pk_mul_f32 v[228:229], v[228:229], v[184:185]
	v_pk_mul_f32 v[230:231], v[230:231], v[184:185]
	v_pk_fma_f32 v[194:195], v[216:217], v[160:161], v[194:195]
	v_pk_fma_f32 v[196:197], v[218:219], v[162:163], v[196:197]
	v_pk_fma_f32 v[198:199], v[220:221], v[164:165], v[198:199]
	v_pk_fma_f32 v[200:201], v[222:223], v[166:167], v[200:201]
	v_pk_fma_f32 v[202:203], v[224:225], v[168:169], v[202:203]
	v_pk_fma_f32 v[204:205], v[226:227], v[170:171], v[204:205]
	v_pk_fma_f32 v[206:207], v[228:229], v[172:173], v[206:207]
	v_pk_fma_f32 v[208:209], v[230:231], v[174:175], v[208:209]
	v_pk_mul_f32 v[252:253], v[194:195], v[194:195]
	v_pk_mul_f32 v[254:255], v[196:197], v[196:197]
	v_pk_fma_f32 v[252:253], v[198:199], v[198:199], v[252:253]
	v_pk_fma_f32 v[254:255], v[200:201], v[200:201], v[254:255]
	v_pk_fma_f32 v[252:253], v[202:203], v[202:203], v[252:253]
	v_pk_fma_f32 v[254:255], v[204:205], v[204:205], v[254:255]
	v_pk_fma_f32 v[252:253], v[206:207], v[206:207], v[252:253]
	v_pk_fma_f32 v[254:255], v[208:209], v[208:209], v[254:255]
	v_pk_add_f32 v[252:253], v[252:253], v[254:255]
	s_nop 0
	v_add_f32_e32 v183, v252, v253
	s_nop 1
	v_add_f32_dpp v183, v183, v183 quad_perm:[1,0,3,2] row_mask:0xf bank_mask:0xf bound_ctrl:1
	s_nop 1
	v_add_f32_dpp v183, v183, v183 quad_perm:[2,3,0,1] row_mask:0xf bank_mask:0xf bound_ctrl:1
	s_nop 1
	v_add_f32_dpp v183, v183, v183 row_half_mirror row_mask:0xf bank_mask:0xf bound_ctrl:1
	s_nop 1
	v_add_f32_dpp v183, v183, v183 row_mirror row_mask:0xf bank_mask:0xf bound_ctrl:1
	s_nop 1
	v_readlane_b32 s98, v183, 0
	v_readlane_b32 s99, v183, 16
	v_readlane_b32 s100, v183, 32
	v_readlane_b32 s101, v183, 48
	s_nop 1
	v_mov_b32_e32 v183, s98
	v_add_f32_e32 v183, s99, v183
	v_add_f32_e32 v183, s100, v183
	v_add_f32_e32 v183, s101, v183
	v_fmamk_f32 v183, v183, 0x3a800000, v182
	v_cmp_gt_f32_e32 vcc, 0x800000, v183
	v_mul_f32_e32 v181, 0x4b800000, v183
	s_nop 1
	v_cndmask_b32_e32 v183, v183, v181, vcc
	v_rsq_f32_e32 v183, v183
	s_nop 0
	v_mul_f32_e32 v181, 0x45800000, v183
	v_cndmask_b32_e32 v184, v183, v181, vcc
	v_mov_b32_e32 v185, v184
	v_cvt_pk_bf16_f32 v32, v194, v195
	v_cvt_pk_bf16_f32 v33, v196, v197
	v_cvt_pk_bf16_f32 v34, v198, v199
	v_cvt_pk_bf16_f32 v35, v200, v201
	v_cvt_pk_bf16_f32 v36, v202, v203
	v_cvt_pk_bf16_f32 v37, v204, v205
	v_cvt_pk_bf16_f32 v38, v206, v207
	v_cvt_pk_bf16_f32 v39, v208, v209
	v_add_u32_e32 v181, 0x2000000, v177
	global_store_dwordx4 v181, v[32:35], s[78:79]
	global_store_dwordx4 v181, v[36:39], s[78:79] offset:1024
	v_add_u32_e32 v236, 0x4000, v237
	s_mov_b64 exec, 1
	global_store_dword v236, v184, s[78:79]
	s_mov_b64 exec, -1
	s_waitcnt vmcnt(24)
	v_lshlrev_b32_e32 v194, 16, v48
	v_and_b32_e32 v195, 0xffff0000, v48
	v_lshlrev_b32_e32 v196, 16, v49
	v_and_b32_e32 v197, 0xffff0000, v49
	v_lshlrev_b32_e32 v198, 16, v50
	v_and_b32_e32 v199, 0xffff0000, v50
	v_lshlrev_b32_e32 v200, 16, v51
	v_and_b32_e32 v201, 0xffff0000, v51
	v_lshlrev_b32_e32 v202, 16, v52
	v_and_b32_e32 v203, 0xffff0000, v52
	v_lshlrev_b32_e32 v204, 16, v53
	v_and_b32_e32 v205, 0xffff0000, v53
	v_lshlrev_b32_e32 v206, 16, v54
	v_and_b32_e32 v207, 0xffff0000, v54
	v_lshlrev_b32_e32 v208, 16, v55
	v_and_b32_e32 v209, 0xffff0000, v55
	v_lshlrev_b32_e32 v216, 16, v56
	v_and_b32_e32 v217, 0xffff0000, v56
	v_lshlrev_b32_e32 v218, 16, v57
	v_and_b32_e32 v219, 0xffff0000, v57
	v_lshlrev_b32_e32 v220, 16, v58
	v_and_b32_e32 v221, 0xffff0000, v58
	v_lshlrev_b32_e32 v222, 16, v59
	v_and_b32_e32 v223, 0xffff0000, v59
	v_lshlrev_b32_e32 v224, 16, v60
	v_and_b32_e32 v225, 0xffff0000, v60
	v_lshlrev_b32_e32 v226, 16, v61
	v_and_b32_e32 v227, 0xffff0000, v61
	v_lshlrev_b32_e32 v228, 16, v62
	v_and_b32_e32 v229, 0xffff0000, v62
	v_lshlrev_b32_e32 v230, 16, v63
	v_and_b32_e32 v231, 0xffff0000, v63
	v_pk_mul_f32 v[252:253], v[216:217], v[216:217]
	v_pk_mul_f32 v[254:255], v[218:219], v[218:219]
	v_pk_fma_f32 v[252:253], v[220:221], v[220:221], v[252:253]
	v_pk_fma_f32 v[254:255], v[222:223], v[222:223], v[254:255]
	v_pk_fma_f32 v[252:253], v[224:225], v[224:225], v[252:253]
	v_pk_fma_f32 v[254:255], v[226:227], v[226:227], v[254:255]
	v_pk_fma_f32 v[252:253], v[228:229], v[228:229], v[252:253]
	v_pk_fma_f32 v[254:255], v[230:231], v[230:231], v[254:255]
	v_pk_add_f32 v[252:253], v[252:253], v[254:255]
	s_nop 0
	v_add_f32_e32 v183, v252, v253
	s_nop 1
	v_add_f32_dpp v183, v183, v183 quad_perm:[1,0,3,2] row_mask:0xf bank_mask:0xf bound_ctrl:1
	s_nop 1
	v_add_f32_dpp v183, v183, v183 quad_perm:[2,3,0,1] row_mask:0xf bank_mask:0xf bound_ctrl:1
	s_nop 1
	v_add_f32_dpp v183, v183, v183 row_half_mirror row_mask:0xf bank_mask:0xf bound_ctrl:1
	s_nop 1
	v_add_f32_dpp v183, v183, v183 row_mirror row_mask:0xf bank_mask:0xf bound_ctrl:1
	s_nop 1
	v_readlane_b32 s98, v183, 0
	v_readlane_b32 s99, v183, 16
	v_readlane_b32 s100, v183, 32
	v_readlane_b32 s101, v183, 48
	s_nop 1
	v_mov_b32_e32 v183, s98
	v_add_f32_e32 v183, s99, v183
	v_add_f32_e32 v183, s100, v183
	v_add_f32_e32 v183, s101, v183
	v_fmamk_f32 v183, v183, 0x3a800000, v182
	v_cmp_gt_f32_e32 vcc, 0x800000, v183
	v_mul_f32_e32 v181, 0x4b800000, v183
	s_nop 1
	v_cndmask_b32_e32 v183, v183, v181, vcc
	v_rsq_f32_e32 v183, v183
	s_nop 0
	v_mul_f32_e32 v181, 0x45800000, v183
	v_cndmask_b32_e32 v184, v183, v181, vcc
	v_mov_b32_e32 v185, v184
	v_pk_mul_f32 v[216:217], v[216:217], v[184:185]
	v_pk_mul_f32 v[218:219], v[218:219], v[184:185]
	v_pk_mul_f32 v[220:221], v[220:221], v[184:185]
	v_pk_mul_f32 v[222:223], v[222:223], v[184:185]
	v_pk_mul_f32 v[224:225], v[224:225], v[184:185]
	v_pk_mul_f32 v[226:227], v[226:227], v[184:185]
	v_pk_mul_f32 v[228:229], v[228:229], v[184:185]
	v_pk_mul_f32 v[230:231], v[230:231], v[184:185]
	v_pk_fma_f32 v[194:195], v[216:217], v[160:161], v[194:195]
	v_pk_fma_f32 v[196:197], v[218:219], v[162:163], v[196:197]
	v_pk_fma_f32 v[198:199], v[220:221], v[164:165], v[198:199]
	v_pk_fma_f32 v[200:201], v[222:223], v[166:167], v[200:201]
	v_pk_fma_f32 v[202:203], v[224:225], v[168:169], v[202:203]
	v_pk_fma_f32 v[204:205], v[226:227], v[170:171], v[204:205]
	v_pk_fma_f32 v[206:207], v[228:229], v[172:173], v[206:207]
	v_pk_fma_f32 v[208:209], v[230:231], v[174:175], v[208:209]
	v_pk_mul_f32 v[252:253], v[194:195], v[194:195]
	v_pk_mul_f32 v[254:255], v[196:197], v[196:197]
	v_pk_fma_f32 v[252:253], v[198:199], v[198:199], v[252:253]
	v_pk_fma_f32 v[254:255], v[200:201], v[200:201], v[254:255]
	v_pk_fma_f32 v[252:253], v[202:203], v[202:203], v[252:253]
	v_pk_fma_f32 v[254:255], v[204:205], v[204:205], v[254:255]
	v_pk_fma_f32 v[252:253], v[206:207], v[206:207], v[252:253]
	v_pk_fma_f32 v[254:255], v[208:209], v[208:209], v[254:255]
	v_pk_add_f32 v[252:253], v[252:253], v[254:255]
	s_nop 0
	v_add_f32_e32 v183, v252, v253
	s_nop 1
	v_add_f32_dpp v183, v183, v183 quad_perm:[1,0,3,2] row_mask:0xf bank_mask:0xf bound_ctrl:1
	s_nop 1
	v_add_f32_dpp v183, v183, v183 quad_perm:[2,3,0,1] row_mask:0xf bank_mask:0xf bound_ctrl:1
	s_nop 1
	v_add_f32_dpp v183, v183, v183 row_half_mirror row_mask:0xf bank_mask:0xf bound_ctrl:1
	s_nop 1
	v_add_f32_dpp v183, v183, v183 row_mirror row_mask:0xf bank_mask:0xf bound_ctrl:1
	s_nop 1
	v_readlane_b32 s98, v183, 0
	v_readlane_b32 s99, v183, 16
	v_readlane_b32 s100, v183, 32
	v_readlane_b32 s101, v183, 48
	s_nop 1
	v_mov_b32_e32 v183, s98
	v_add_f32_e32 v183, s99, v183
	v_add_f32_e32 v183, s100, v183
	v_add_f32_e32 v183, s101, v183
	v_fmamk_f32 v183, v183, 0x3a800000, v182
	v_cmp_gt_f32_e32 vcc, 0x800000, v183
	v_mul_f32_e32 v181, 0x4b800000, v183
	s_nop 1
	v_cndmask_b32_e32 v183, v183, v181, vcc
	v_rsq_f32_e32 v183, v183
	s_nop 0
	v_mul_f32_e32 v181, 0x45800000, v183
	v_cndmask_b32_e32 v184, v183, v181, vcc
	v_mov_b32_e32 v185, v184
	v_cvt_pk_bf16_f32 v48, v194, v195
	v_cvt_pk_bf16_f32 v49, v196, v197
	v_cvt_pk_bf16_f32 v50, v198, v199
	v_cvt_pk_bf16_f32 v51, v200, v201
	v_cvt_pk_bf16_f32 v52, v202, v203
	v_cvt_pk_bf16_f32 v53, v204, v205
	v_cvt_pk_bf16_f32 v54, v206, v207
	v_cvt_pk_bf16_f32 v55, v208, v209
	v_add_u32_e32 v181, 0x2400000, v177
	global_store_dwordx4 v181, v[48:51], s[78:79]
	global_store_dwordx4 v181, v[52:55], s[78:79] offset:1024
	v_add_u32_e32 v236, 0x6000, v237
	s_mov_b64 exec, 1
	global_store_dword v236, v184, s[78:79]
	s_mov_b64 exec, -1
	s_waitcnt vmcnt(20)
	v_lshlrev_b32_e32 v194, 16, v64
	v_and_b32_e32 v195, 0xffff0000, v64
	v_lshlrev_b32_e32 v196, 16, v65
	v_and_b32_e32 v197, 0xffff0000, v65
	v_lshlrev_b32_e32 v198, 16, v66
	v_and_b32_e32 v199, 0xffff0000, v66
	v_lshlrev_b32_e32 v200, 16, v67
	v_and_b32_e32 v201, 0xffff0000, v67
	v_lshlrev_b32_e32 v202, 16, v68
	v_and_b32_e32 v203, 0xffff0000, v68
	v_lshlrev_b32_e32 v204, 16, v69
	v_and_b32_e32 v205, 0xffff0000, v69
	v_lshlrev_b32_e32 v206, 16, v70
	v_and_b32_e32 v207, 0xffff0000, v70
	v_lshlrev_b32_e32 v208, 16, v71
	v_and_b32_e32 v209, 0xffff0000, v71
	v_lshlrev_b32_e32 v216, 16, v72
	v_and_b32_e32 v217, 0xffff0000, v72
	v_lshlrev_b32_e32 v218, 16, v73
	v_and_b32_e32 v219, 0xffff0000, v73
	v_lshlrev_b32_e32 v220, 16, v74
	v_and_b32_e32 v221, 0xffff0000, v74
	v_lshlrev_b32_e32 v222, 16, v75
	v_and_b32_e32 v223, 0xffff0000, v75
	v_lshlrev_b32_e32 v224, 16, v76
	v_and_b32_e32 v225, 0xffff0000, v76
	v_lshlrev_b32_e32 v226, 16, v77
	v_and_b32_e32 v227, 0xffff0000, v77
	v_lshlrev_b32_e32 v228, 16, v78
	v_and_b32_e32 v229, 0xffff0000, v78
	v_lshlrev_b32_e32 v230, 16, v79
	v_and_b32_e32 v231, 0xffff0000, v79
	v_pk_mul_f32 v[252:253], v[216:217], v[216:217]
	v_pk_mul_f32 v[254:255], v[218:219], v[218:219]
	v_pk_fma_f32 v[252:253], v[220:221], v[220:221], v[252:253]
	v_pk_fma_f32 v[254:255], v[222:223], v[222:223], v[254:255]
	v_pk_fma_f32 v[252:253], v[224:225], v[224:225], v[252:253]
	v_pk_fma_f32 v[254:255], v[226:227], v[226:227], v[254:255]
	v_pk_fma_f32 v[252:253], v[228:229], v[228:229], v[252:253]
	v_pk_fma_f32 v[254:255], v[230:231], v[230:231], v[254:255]
	v_pk_add_f32 v[252:253], v[252:253], v[254:255]
	s_nop 0
	v_add_f32_e32 v183, v252, v253
	s_nop 1
	v_add_f32_dpp v183, v183, v183 quad_perm:[1,0,3,2] row_mask:0xf bank_mask:0xf bound_ctrl:1
	s_nop 1
	v_add_f32_dpp v183, v183, v183 quad_perm:[2,3,0,1] row_mask:0xf bank_mask:0xf bound_ctrl:1
	s_nop 1
	v_add_f32_dpp v183, v183, v183 row_half_mirror row_mask:0xf bank_mask:0xf bound_ctrl:1
	s_nop 1
	v_add_f32_dpp v183, v183, v183 row_mirror row_mask:0xf bank_mask:0xf bound_ctrl:1
	s_nop 1
	v_readlane_b32 s98, v183, 0
	v_readlane_b32 s99, v183, 16
	v_readlane_b32 s100, v183, 32
	v_readlane_b32 s101, v183, 48
	s_nop 1
	v_mov_b32_e32 v183, s98
	v_add_f32_e32 v183, s99, v183
	v_add_f32_e32 v183, s100, v183
	v_add_f32_e32 v183, s101, v183
	v_fmamk_f32 v183, v183, 0x3a800000, v182
	v_cmp_gt_f32_e32 vcc, 0x800000, v183
	v_mul_f32_e32 v181, 0x4b800000, v183
	s_nop 1
	v_cndmask_b32_e32 v183, v183, v181, vcc
	v_rsq_f32_e32 v183, v183
	s_nop 0
	v_mul_f32_e32 v181, 0x45800000, v183
	v_cndmask_b32_e32 v184, v183, v181, vcc
	v_mov_b32_e32 v185, v184
	v_pk_mul_f32 v[216:217], v[216:217], v[184:185]
	v_pk_mul_f32 v[218:219], v[218:219], v[184:185]
	v_pk_mul_f32 v[220:221], v[220:221], v[184:185]
	v_pk_mul_f32 v[222:223], v[222:223], v[184:185]
	v_pk_mul_f32 v[224:225], v[224:225], v[184:185]
	v_pk_mul_f32 v[226:227], v[226:227], v[184:185]
	v_pk_mul_f32 v[228:229], v[228:229], v[184:185]
	v_pk_mul_f32 v[230:231], v[230:231], v[184:185]
	v_pk_fma_f32 v[194:195], v[216:217], v[160:161], v[194:195]
	v_pk_fma_f32 v[196:197], v[218:219], v[162:163], v[196:197]
	v_pk_fma_f32 v[198:199], v[220:221], v[164:165], v[198:199]
	v_pk_fma_f32 v[200:201], v[222:223], v[166:167], v[200:201]
	v_pk_fma_f32 v[202:203], v[224:225], v[168:169], v[202:203]
	v_pk_fma_f32 v[204:205], v[226:227], v[170:171], v[204:205]
	v_pk_fma_f32 v[206:207], v[228:229], v[172:173], v[206:207]
	v_pk_fma_f32 v[208:209], v[230:231], v[174:175], v[208:209]
	v_pk_mul_f32 v[252:253], v[194:195], v[194:195]
	v_pk_mul_f32 v[254:255], v[196:197], v[196:197]
	v_pk_fma_f32 v[252:253], v[198:199], v[198:199], v[252:253]
	v_pk_fma_f32 v[254:255], v[200:201], v[200:201], v[254:255]
	v_pk_fma_f32 v[252:253], v[202:203], v[202:203], v[252:253]
	v_pk_fma_f32 v[254:255], v[204:205], v[204:205], v[254:255]
	v_pk_fma_f32 v[252:253], v[206:207], v[206:207], v[252:253]
	v_pk_fma_f32 v[254:255], v[208:209], v[208:209], v[254:255]
	v_pk_add_f32 v[252:253], v[252:253], v[254:255]
	s_nop 0
	v_add_f32_e32 v183, v252, v253
	s_nop 1
	v_add_f32_dpp v183, v183, v183 quad_perm:[1,0,3,2] row_mask:0xf bank_mask:0xf bound_ctrl:1
	s_nop 1
	v_add_f32_dpp v183, v183, v183 quad_perm:[2,3,0,1] row_mask:0xf bank_mask:0xf bound_ctrl:1
	s_nop 1
	v_add_f32_dpp v183, v183, v183 row_half_mirror row_mask:0xf bank_mask:0xf bound_ctrl:1
	s_nop 1
	v_add_f32_dpp v183, v183, v183 row_mirror row_mask:0xf bank_mask:0xf bound_ctrl:1
	s_nop 1
	v_readlane_b32 s98, v183, 0
	v_readlane_b32 s99, v183, 16
	v_readlane_b32 s100, v183, 32
	v_readlane_b32 s101, v183, 48
	s_nop 1
	v_mov_b32_e32 v183, s98
	v_add_f32_e32 v183, s99, v183
	v_add_f32_e32 v183, s100, v183
	v_add_f32_e32 v183, s101, v183
	v_fmamk_f32 v183, v183, 0x3a800000, v182
	v_cmp_gt_f32_e32 vcc, 0x800000, v183
	v_mul_f32_e32 v181, 0x4b800000, v183
	s_nop 1
	v_cndmask_b32_e32 v183, v183, v181, vcc
	v_rsq_f32_e32 v183, v183
	s_nop 0
	v_mul_f32_e32 v181, 0x45800000, v183
	v_cndmask_b32_e32 v184, v183, v181, vcc
	v_mov_b32_e32 v185, v184
	v_cvt_pk_bf16_f32 v64, v194, v195
	v_cvt_pk_bf16_f32 v65, v196, v197
	v_cvt_pk_bf16_f32 v66, v198, v199
	v_cvt_pk_bf16_f32 v67, v200, v201
	v_cvt_pk_bf16_f32 v68, v202, v203
	v_cvt_pk_bf16_f32 v69, v204, v205
	v_cvt_pk_bf16_f32 v70, v206, v207
	v_cvt_pk_bf16_f32 v71, v208, v209
	v_add_u32_e32 v181, 0x2800000, v177
	global_store_dwordx4 v181, v[64:67], s[78:79]
	global_store_dwordx4 v181, v[68:71], s[78:79] offset:1024
	v_add_u32_e32 v236, 0x8000, v237
	s_mov_b64 exec, 1
	global_store_dword v236, v184, s[78:79]
	s_mov_b64 exec, -1
	s_waitcnt vmcnt(16)
	v_lshlrev_b32_e32 v194, 16, v80
	v_and_b32_e32 v195, 0xffff0000, v80
	v_lshlrev_b32_e32 v196, 16, v81
	v_and_b32_e32 v197, 0xffff0000, v81
	v_lshlrev_b32_e32 v198, 16, v82
	v_and_b32_e32 v199, 0xffff0000, v82
	v_lshlrev_b32_e32 v200, 16, v83
	v_and_b32_e32 v201, 0xffff0000, v83
	v_lshlrev_b32_e32 v202, 16, v84
	v_and_b32_e32 v203, 0xffff0000, v84
	v_lshlrev_b32_e32 v204, 16, v85
	v_and_b32_e32 v205, 0xffff0000, v85
	v_lshlrev_b32_e32 v206, 16, v86
	v_and_b32_e32 v207, 0xffff0000, v86
	v_lshlrev_b32_e32 v208, 16, v87
	v_and_b32_e32 v209, 0xffff0000, v87
	v_lshlrev_b32_e32 v216, 16, v88
	v_and_b32_e32 v217, 0xffff0000, v88
	v_lshlrev_b32_e32 v218, 16, v89
	v_and_b32_e32 v219, 0xffff0000, v89
	v_lshlrev_b32_e32 v220, 16, v90
	v_and_b32_e32 v221, 0xffff0000, v90
	v_lshlrev_b32_e32 v222, 16, v91
	v_and_b32_e32 v223, 0xffff0000, v91
	v_lshlrev_b32_e32 v224, 16, v92
	v_and_b32_e32 v225, 0xffff0000, v92
	v_lshlrev_b32_e32 v226, 16, v93
	v_and_b32_e32 v227, 0xffff0000, v93
	v_lshlrev_b32_e32 v228, 16, v94
	v_and_b32_e32 v229, 0xffff0000, v94
	v_lshlrev_b32_e32 v230, 16, v95
	v_and_b32_e32 v231, 0xffff0000, v95
	v_pk_mul_f32 v[252:253], v[216:217], v[216:217]
	v_pk_mul_f32 v[254:255], v[218:219], v[218:219]
	v_pk_fma_f32 v[252:253], v[220:221], v[220:221], v[252:253]
	v_pk_fma_f32 v[254:255], v[222:223], v[222:223], v[254:255]
	v_pk_fma_f32 v[252:253], v[224:225], v[224:225], v[252:253]
	v_pk_fma_f32 v[254:255], v[226:227], v[226:227], v[254:255]
	v_pk_fma_f32 v[252:253], v[228:229], v[228:229], v[252:253]
	v_pk_fma_f32 v[254:255], v[230:231], v[230:231], v[254:255]
	v_pk_add_f32 v[252:253], v[252:253], v[254:255]
	s_nop 0
	v_add_f32_e32 v183, v252, v253
	s_nop 1
	v_add_f32_dpp v183, v183, v183 quad_perm:[1,0,3,2] row_mask:0xf bank_mask:0xf bound_ctrl:1
	s_nop 1
	v_add_f32_dpp v183, v183, v183 quad_perm:[2,3,0,1] row_mask:0xf bank_mask:0xf bound_ctrl:1
	s_nop 1
	v_add_f32_dpp v183, v183, v183 row_half_mirror row_mask:0xf bank_mask:0xf bound_ctrl:1
	s_nop 1
	v_add_f32_dpp v183, v183, v183 row_mirror row_mask:0xf bank_mask:0xf bound_ctrl:1
	s_nop 1
	v_readlane_b32 s98, v183, 0
	v_readlane_b32 s99, v183, 16
	v_readlane_b32 s100, v183, 32
	v_readlane_b32 s101, v183, 48
	s_nop 1
	v_mov_b32_e32 v183, s98
	v_add_f32_e32 v183, s99, v183
	v_add_f32_e32 v183, s100, v183
	v_add_f32_e32 v183, s101, v183
	v_fmamk_f32 v183, v183, 0x3a800000, v182
	v_cmp_gt_f32_e32 vcc, 0x800000, v183
	v_mul_f32_e32 v181, 0x4b800000, v183
	s_nop 1
	v_cndmask_b32_e32 v183, v183, v181, vcc
	v_rsq_f32_e32 v183, v183
	s_nop 0
	v_mul_f32_e32 v181, 0x45800000, v183
	v_cndmask_b32_e32 v184, v183, v181, vcc
	v_mov_b32_e32 v185, v184
	v_pk_mul_f32 v[216:217], v[216:217], v[184:185]
	v_pk_mul_f32 v[218:219], v[218:219], v[184:185]
	v_pk_mul_f32 v[220:221], v[220:221], v[184:185]
	v_pk_mul_f32 v[222:223], v[222:223], v[184:185]
	v_pk_mul_f32 v[224:225], v[224:225], v[184:185]
	v_pk_mul_f32 v[226:227], v[226:227], v[184:185]
	v_pk_mul_f32 v[228:229], v[228:229], v[184:185]
	v_pk_mul_f32 v[230:231], v[230:231], v[184:185]
	v_pk_fma_f32 v[194:195], v[216:217], v[160:161], v[194:195]
	v_pk_fma_f32 v[196:197], v[218:219], v[162:163], v[196:197]
	v_pk_fma_f32 v[198:199], v[220:221], v[164:165], v[198:199]
	v_pk_fma_f32 v[200:201], v[222:223], v[166:167], v[200:201]
	v_pk_fma_f32 v[202:203], v[224:225], v[168:169], v[202:203]
	v_pk_fma_f32 v[204:205], v[226:227], v[170:171], v[204:205]
	v_pk_fma_f32 v[206:207], v[228:229], v[172:173], v[206:207]
	v_pk_fma_f32 v[208:209], v[230:231], v[174:175], v[208:209]
	v_pk_mul_f32 v[252:253], v[194:195], v[194:195]
	v_pk_mul_f32 v[254:255], v[196:197], v[196:197]
	v_pk_fma_f32 v[252:253], v[198:199], v[198:199], v[252:253]
	v_pk_fma_f32 v[254:255], v[200:201], v[200:201], v[254:255]
	v_pk_fma_f32 v[252:253], v[202:203], v[202:203], v[252:253]
	v_pk_fma_f32 v[254:255], v[204:205], v[204:205], v[254:255]
	v_pk_fma_f32 v[252:253], v[206:207], v[206:207], v[252:253]
	v_pk_fma_f32 v[254:255], v[208:209], v[208:209], v[254:255]
	v_pk_add_f32 v[252:253], v[252:253], v[254:255]
	s_nop 0
	v_add_f32_e32 v183, v252, v253
	s_nop 1
	v_add_f32_dpp v183, v183, v183 quad_perm:[1,0,3,2] row_mask:0xf bank_mask:0xf bound_ctrl:1
	s_nop 1
	v_add_f32_dpp v183, v183, v183 quad_perm:[2,3,0,1] row_mask:0xf bank_mask:0xf bound_ctrl:1
	s_nop 1
	v_add_f32_dpp v183, v183, v183 row_half_mirror row_mask:0xf bank_mask:0xf bound_ctrl:1
	s_nop 1
	v_add_f32_dpp v183, v183, v183 row_mirror row_mask:0xf bank_mask:0xf bound_ctrl:1
	s_nop 1
	v_readlane_b32 s98, v183, 0
	v_readlane_b32 s99, v183, 16
	v_readlane_b32 s100, v183, 32
	v_readlane_b32 s101, v183, 48
	s_nop 1
	v_mov_b32_e32 v183, s98
	v_add_f32_e32 v183, s99, v183
	v_add_f32_e32 v183, s100, v183
	v_add_f32_e32 v183, s101, v183
	v_fmamk_f32 v183, v183, 0x3a800000, v182
	v_cmp_gt_f32_e32 vcc, 0x800000, v183
	v_mul_f32_e32 v181, 0x4b800000, v183
	s_nop 1
	v_cndmask_b32_e32 v183, v183, v181, vcc
	v_rsq_f32_e32 v183, v183
	s_nop 0
	v_mul_f32_e32 v181, 0x45800000, v183
	v_cndmask_b32_e32 v184, v183, v181, vcc
	v_mov_b32_e32 v185, v184
	v_cvt_pk_bf16_f32 v80, v194, v195
	v_cvt_pk_bf16_f32 v81, v196, v197
	v_cvt_pk_bf16_f32 v82, v198, v199
	v_cvt_pk_bf16_f32 v83, v200, v201
	v_cvt_pk_bf16_f32 v84, v202, v203
	v_cvt_pk_bf16_f32 v85, v204, v205
	v_cvt_pk_bf16_f32 v86, v206, v207
	v_cvt_pk_bf16_f32 v87, v208, v209
	v_add_u32_e32 v181, 0x2c00000, v177
	global_store_dwordx4 v181, v[80:83], s[78:79]
	global_store_dwordx4 v181, v[84:87], s[78:79] offset:1024
	v_add_u32_e32 v236, 0xa000, v237
	s_mov_b64 exec, 1
	global_store_dword v236, v184, s[78:79]
	s_mov_b64 exec, -1
	s_waitcnt vmcnt(12)
	v_lshlrev_b32_e32 v194, 16, v96
	v_and_b32_e32 v195, 0xffff0000, v96
	v_lshlrev_b32_e32 v196, 16, v97
	v_and_b32_e32 v197, 0xffff0000, v97
	v_lshlrev_b32_e32 v198, 16, v98
	v_and_b32_e32 v199, 0xffff0000, v98
	v_lshlrev_b32_e32 v200, 16, v99
	v_and_b32_e32 v201, 0xffff0000, v99
	v_lshlrev_b32_e32 v202, 16, v100
	v_and_b32_e32 v203, 0xffff0000, v100
	v_lshlrev_b32_e32 v204, 16, v101
	v_and_b32_e32 v205, 0xffff0000, v101
	v_lshlrev_b32_e32 v206, 16, v102
	v_and_b32_e32 v207, 0xffff0000, v102
	v_lshlrev_b32_e32 v208, 16, v103
	v_and_b32_e32 v209, 0xffff0000, v103
	v_lshlrev_b32_e32 v216, 16, v104
	v_and_b32_e32 v217, 0xffff0000, v104
	v_lshlrev_b32_e32 v218, 16, v105
	v_and_b32_e32 v219, 0xffff0000, v105
	v_lshlrev_b32_e32 v220, 16, v106
	v_and_b32_e32 v221, 0xffff0000, v106
	v_lshlrev_b32_e32 v222, 16, v107
	v_and_b32_e32 v223, 0xffff0000, v107
	v_lshlrev_b32_e32 v224, 16, v108
	v_and_b32_e32 v225, 0xffff0000, v108
	v_lshlrev_b32_e32 v226, 16, v109
	v_and_b32_e32 v227, 0xffff0000, v109
	v_lshlrev_b32_e32 v228, 16, v110
	v_and_b32_e32 v229, 0xffff0000, v110
	v_lshlrev_b32_e32 v230, 16, v111
	v_and_b32_e32 v231, 0xffff0000, v111
	v_pk_mul_f32 v[252:253], v[216:217], v[216:217]
	v_pk_mul_f32 v[254:255], v[218:219], v[218:219]
	v_pk_fma_f32 v[252:253], v[220:221], v[220:221], v[252:253]
	v_pk_fma_f32 v[254:255], v[222:223], v[222:223], v[254:255]
	v_pk_fma_f32 v[252:253], v[224:225], v[224:225], v[252:253]
	v_pk_fma_f32 v[254:255], v[226:227], v[226:227], v[254:255]
	v_pk_fma_f32 v[252:253], v[228:229], v[228:229], v[252:253]
	v_pk_fma_f32 v[254:255], v[230:231], v[230:231], v[254:255]
	v_pk_add_f32 v[252:253], v[252:253], v[254:255]
	s_nop 0
	v_add_f32_e32 v183, v252, v253
	s_nop 1
	v_add_f32_dpp v183, v183, v183 quad_perm:[1,0,3,2] row_mask:0xf bank_mask:0xf bound_ctrl:1
	s_nop 1
	v_add_f32_dpp v183, v183, v183 quad_perm:[2,3,0,1] row_mask:0xf bank_mask:0xf bound_ctrl:1
	s_nop 1
	v_add_f32_dpp v183, v183, v183 row_half_mirror row_mask:0xf bank_mask:0xf bound_ctrl:1
	s_nop 1
	v_add_f32_dpp v183, v183, v183 row_mirror row_mask:0xf bank_mask:0xf bound_ctrl:1
	s_nop 1
	v_readlane_b32 s98, v183, 0
	v_readlane_b32 s99, v183, 16
	v_readlane_b32 s100, v183, 32
	v_readlane_b32 s101, v183, 48
	s_nop 1
	v_mov_b32_e32 v183, s98
	v_add_f32_e32 v183, s99, v183
	v_add_f32_e32 v183, s100, v183
	v_add_f32_e32 v183, s101, v183
	v_fmamk_f32 v183, v183, 0x3a800000, v182
	v_cmp_gt_f32_e32 vcc, 0x800000, v183
	v_mul_f32_e32 v181, 0x4b800000, v183
	s_nop 1
	v_cndmask_b32_e32 v183, v183, v181, vcc
	v_rsq_f32_e32 v183, v183
	s_nop 0
	v_mul_f32_e32 v181, 0x45800000, v183
	v_cndmask_b32_e32 v184, v183, v181, vcc
	v_mov_b32_e32 v185, v184
	v_pk_mul_f32 v[216:217], v[216:217], v[184:185]
	v_pk_mul_f32 v[218:219], v[218:219], v[184:185]
	v_pk_mul_f32 v[220:221], v[220:221], v[184:185]
	v_pk_mul_f32 v[222:223], v[222:223], v[184:185]
	v_pk_mul_f32 v[224:225], v[224:225], v[184:185]
	v_pk_mul_f32 v[226:227], v[226:227], v[184:185]
	v_pk_mul_f32 v[228:229], v[228:229], v[184:185]
	v_pk_mul_f32 v[230:231], v[230:231], v[184:185]
	v_pk_fma_f32 v[194:195], v[216:217], v[160:161], v[194:195]
	v_pk_fma_f32 v[196:197], v[218:219], v[162:163], v[196:197]
	v_pk_fma_f32 v[198:199], v[220:221], v[164:165], v[198:199]
	v_pk_fma_f32 v[200:201], v[222:223], v[166:167], v[200:201]
	v_pk_fma_f32 v[202:203], v[224:225], v[168:169], v[202:203]
	v_pk_fma_f32 v[204:205], v[226:227], v[170:171], v[204:205]
	v_pk_fma_f32 v[206:207], v[228:229], v[172:173], v[206:207]
	v_pk_fma_f32 v[208:209], v[230:231], v[174:175], v[208:209]
	v_pk_mul_f32 v[252:253], v[194:195], v[194:195]
	v_pk_mul_f32 v[254:255], v[196:197], v[196:197]
	v_pk_fma_f32 v[252:253], v[198:199], v[198:199], v[252:253]
	v_pk_fma_f32 v[254:255], v[200:201], v[200:201], v[254:255]
	v_pk_fma_f32 v[252:253], v[202:203], v[202:203], v[252:253]
	v_pk_fma_f32 v[254:255], v[204:205], v[204:205], v[254:255]
	v_pk_fma_f32 v[252:253], v[206:207], v[206:207], v[252:253]
	v_pk_fma_f32 v[254:255], v[208:209], v[208:209], v[254:255]
	v_pk_add_f32 v[252:253], v[252:253], v[254:255]
	s_nop 0
	v_add_f32_e32 v183, v252, v253
	s_nop 1
	v_add_f32_dpp v183, v183, v183 quad_perm:[1,0,3,2] row_mask:0xf bank_mask:0xf bound_ctrl:1
	s_nop 1
	v_add_f32_dpp v183, v183, v183 quad_perm:[2,3,0,1] row_mask:0xf bank_mask:0xf bound_ctrl:1
	s_nop 1
	v_add_f32_dpp v183, v183, v183 row_half_mirror row_mask:0xf bank_mask:0xf bound_ctrl:1
	s_nop 1
	v_add_f32_dpp v183, v183, v183 row_mirror row_mask:0xf bank_mask:0xf bound_ctrl:1
	s_nop 1
	v_readlane_b32 s98, v183, 0
	v_readlane_b32 s99, v183, 16
	v_readlane_b32 s100, v183, 32
	v_readlane_b32 s101, v183, 48
	s_nop 1
	v_mov_b32_e32 v183, s98
	v_add_f32_e32 v183, s99, v183
	v_add_f32_e32 v183, s100, v183
	v_add_f32_e32 v183, s101, v183
	v_fmamk_f32 v183, v183, 0x3a800000, v182
	v_cmp_gt_f32_e32 vcc, 0x800000, v183
	v_mul_f32_e32 v181, 0x4b800000, v183
	s_nop 1
	v_cndmask_b32_e32 v183, v183, v181, vcc
	v_rsq_f32_e32 v183, v183
	s_nop 0
	v_mul_f32_e32 v181, 0x45800000, v183
	v_cndmask_b32_e32 v184, v183, v181, vcc
	v_mov_b32_e32 v185, v184
	v_cvt_pk_bf16_f32 v96, v194, v195
	v_cvt_pk_bf16_f32 v97, v196, v197
	v_cvt_pk_bf16_f32 v98, v198, v199
	v_cvt_pk_bf16_f32 v99, v200, v201
	v_cvt_pk_bf16_f32 v100, v202, v203
	v_cvt_pk_bf16_f32 v101, v204, v205
	v_cvt_pk_bf16_f32 v102, v206, v207
	v_cvt_pk_bf16_f32 v103, v208, v209
	v_add_u32_e32 v181, 0x3000000, v177
	global_store_dwordx4 v181, v[96:99], s[78:79]
	global_store_dwordx4 v181, v[100:103], s[78:79] offset:1024
	v_add_u32_e32 v236, 0xc000, v237
	s_mov_b64 exec, 1
	global_store_dword v236, v184, s[78:79]
	s_mov_b64 exec, -1
	s_waitcnt vmcnt(8)
	v_lshlrev_b32_e32 v194, 16, v112
	v_and_b32_e32 v195, 0xffff0000, v112
	v_lshlrev_b32_e32 v196, 16, v113
	v_and_b32_e32 v197, 0xffff0000, v113
	v_lshlrev_b32_e32 v198, 16, v114
	v_and_b32_e32 v199, 0xffff0000, v114
	v_lshlrev_b32_e32 v200, 16, v115
	v_and_b32_e32 v201, 0xffff0000, v115
	v_lshlrev_b32_e32 v202, 16, v116
	v_and_b32_e32 v203, 0xffff0000, v116
	v_lshlrev_b32_e32 v204, 16, v117
	v_and_b32_e32 v205, 0xffff0000, v117
	v_lshlrev_b32_e32 v206, 16, v118
	v_and_b32_e32 v207, 0xffff0000, v118
	v_lshlrev_b32_e32 v208, 16, v119
	v_and_b32_e32 v209, 0xffff0000, v119
	v_lshlrev_b32_e32 v216, 16, v120
	v_and_b32_e32 v217, 0xffff0000, v120
	v_lshlrev_b32_e32 v218, 16, v121
	v_and_b32_e32 v219, 0xffff0000, v121
	v_lshlrev_b32_e32 v220, 16, v122
	v_and_b32_e32 v221, 0xffff0000, v122
	v_lshlrev_b32_e32 v222, 16, v123
	v_and_b32_e32 v223, 0xffff0000, v123
	v_lshlrev_b32_e32 v224, 16, v124
	v_and_b32_e32 v225, 0xffff0000, v124
	v_lshlrev_b32_e32 v226, 16, v125
	v_and_b32_e32 v227, 0xffff0000, v125
	v_lshlrev_b32_e32 v228, 16, v126
	v_and_b32_e32 v229, 0xffff0000, v126
	v_lshlrev_b32_e32 v230, 16, v127
	v_and_b32_e32 v231, 0xffff0000, v127
	v_pk_mul_f32 v[252:253], v[216:217], v[216:217]
	v_pk_mul_f32 v[254:255], v[218:219], v[218:219]
	v_pk_fma_f32 v[252:253], v[220:221], v[220:221], v[252:253]
	v_pk_fma_f32 v[254:255], v[222:223], v[222:223], v[254:255]
	v_pk_fma_f32 v[252:253], v[224:225], v[224:225], v[252:253]
	v_pk_fma_f32 v[254:255], v[226:227], v[226:227], v[254:255]
	v_pk_fma_f32 v[252:253], v[228:229], v[228:229], v[252:253]
	v_pk_fma_f32 v[254:255], v[230:231], v[230:231], v[254:255]
	v_pk_add_f32 v[252:253], v[252:253], v[254:255]
	s_nop 0
	v_add_f32_e32 v183, v252, v253
	s_nop 1
	v_add_f32_dpp v183, v183, v183 quad_perm:[1,0,3,2] row_mask:0xf bank_mask:0xf bound_ctrl:1
	s_nop 1
	v_add_f32_dpp v183, v183, v183 quad_perm:[2,3,0,1] row_mask:0xf bank_mask:0xf bound_ctrl:1
	s_nop 1
	v_add_f32_dpp v183, v183, v183 row_half_mirror row_mask:0xf bank_mask:0xf bound_ctrl:1
	s_nop 1
	v_add_f32_dpp v183, v183, v183 row_mirror row_mask:0xf bank_mask:0xf bound_ctrl:1
	s_nop 1
	v_readlane_b32 s98, v183, 0
	v_readlane_b32 s99, v183, 16
	v_readlane_b32 s100, v183, 32
	v_readlane_b32 s101, v183, 48
	s_nop 1
	v_mov_b32_e32 v183, s98
	v_add_f32_e32 v183, s99, v183
	v_add_f32_e32 v183, s100, v183
	v_add_f32_e32 v183, s101, v183
	v_fmamk_f32 v183, v183, 0x3a800000, v182
	v_cmp_gt_f32_e32 vcc, 0x800000, v183
	v_mul_f32_e32 v181, 0x4b800000, v183
	s_nop 1
	v_cndmask_b32_e32 v183, v183, v181, vcc
	v_rsq_f32_e32 v183, v183
	s_nop 0
	v_mul_f32_e32 v181, 0x45800000, v183
	v_cndmask_b32_e32 v184, v183, v181, vcc
	v_mov_b32_e32 v185, v184
	v_pk_mul_f32 v[216:217], v[216:217], v[184:185]
	v_pk_mul_f32 v[218:219], v[218:219], v[184:185]
	v_pk_mul_f32 v[220:221], v[220:221], v[184:185]
	v_pk_mul_f32 v[222:223], v[222:223], v[184:185]
	v_pk_mul_f32 v[224:225], v[224:225], v[184:185]
	v_pk_mul_f32 v[226:227], v[226:227], v[184:185]
	v_pk_mul_f32 v[228:229], v[228:229], v[184:185]
	v_pk_mul_f32 v[230:231], v[230:231], v[184:185]
	v_pk_fma_f32 v[194:195], v[216:217], v[160:161], v[194:195]
	v_pk_fma_f32 v[196:197], v[218:219], v[162:163], v[196:197]
	v_pk_fma_f32 v[198:199], v[220:221], v[164:165], v[198:199]
	v_pk_fma_f32 v[200:201], v[222:223], v[166:167], v[200:201]
	v_pk_fma_f32 v[202:203], v[224:225], v[168:169], v[202:203]
	v_pk_fma_f32 v[204:205], v[226:227], v[170:171], v[204:205]
	v_pk_fma_f32 v[206:207], v[228:229], v[172:173], v[206:207]
	v_pk_fma_f32 v[208:209], v[230:231], v[174:175], v[208:209]
	v_pk_mul_f32 v[252:253], v[194:195], v[194:195]
	v_pk_mul_f32 v[254:255], v[196:197], v[196:197]
	v_pk_fma_f32 v[252:253], v[198:199], v[198:199], v[252:253]
	v_pk_fma_f32 v[254:255], v[200:201], v[200:201], v[254:255]
	v_pk_fma_f32 v[252:253], v[202:203], v[202:203], v[252:253]
	v_pk_fma_f32 v[254:255], v[204:205], v[204:205], v[254:255]
	v_pk_fma_f32 v[252:253], v[206:207], v[206:207], v[252:253]
	v_pk_fma_f32 v[254:255], v[208:209], v[208:209], v[254:255]
	v_pk_add_f32 v[252:253], v[252:253], v[254:255]
	s_nop 0
	v_add_f32_e32 v183, v252, v253
	s_nop 1
	v_add_f32_dpp v183, v183, v183 quad_perm:[1,0,3,2] row_mask:0xf bank_mask:0xf bound_ctrl:1
	s_nop 1
	v_add_f32_dpp v183, v183, v183 quad_perm:[2,3,0,1] row_mask:0xf bank_mask:0xf bound_ctrl:1
	s_nop 1
	v_add_f32_dpp v183, v183, v183 row_half_mirror row_mask:0xf bank_mask:0xf bound_ctrl:1
	s_nop 1
	v_add_f32_dpp v183, v183, v183 row_mirror row_mask:0xf bank_mask:0xf bound_ctrl:1
	s_nop 1
	v_readlane_b32 s98, v183, 0
	v_readlane_b32 s99, v183, 16
	v_readlane_b32 s100, v183, 32
	v_readlane_b32 s101, v183, 48
	s_nop 1
	v_mov_b32_e32 v183, s98
	v_add_f32_e32 v183, s99, v183
	v_add_f32_e32 v183, s100, v183
	v_add_f32_e32 v183, s101, v183
	v_fmamk_f32 v183, v183, 0x3a800000, v182
	v_cmp_gt_f32_e32 vcc, 0x800000, v183
	v_mul_f32_e32 v181, 0x4b800000, v183
	s_nop 1
	v_cndmask_b32_e32 v183, v183, v181, vcc
	v_rsq_f32_e32 v183, v183
	s_nop 0
	v_mul_f32_e32 v181, 0x45800000, v183
	v_cndmask_b32_e32 v184, v183, v181, vcc
	v_mov_b32_e32 v185, v184
	v_cvt_pk_bf16_f32 v112, v194, v195
	v_cvt_pk_bf16_f32 v113, v196, v197
	v_cvt_pk_bf16_f32 v114, v198, v199
	v_cvt_pk_bf16_f32 v115, v200, v201
	v_cvt_pk_bf16_f32 v116, v202, v203
	v_cvt_pk_bf16_f32 v117, v204, v205
	v_cvt_pk_bf16_f32 v118, v206, v207
	v_cvt_pk_bf16_f32 v119, v208, v209
	v_add_u32_e32 v181, 0x3400000, v177
	global_store_dwordx4 v181, v[112:115], s[78:79]
	global_store_dwordx4 v181, v[116:119], s[78:79] offset:1024
	v_add_u32_e32 v236, 0xe000, v237
	s_mov_b64 exec, 1
	global_store_dword v236, v184, s[78:79]
	s_mov_b64 exec, -1
	s_waitcnt vmcnt(4)
	v_lshlrev_b32_e32 v194, 16, v128
	v_and_b32_e32 v195, 0xffff0000, v128
	v_lshlrev_b32_e32 v196, 16, v129
	v_and_b32_e32 v197, 0xffff0000, v129
	v_lshlrev_b32_e32 v198, 16, v130
	v_and_b32_e32 v199, 0xffff0000, v130
	v_lshlrev_b32_e32 v200, 16, v131
	v_and_b32_e32 v201, 0xffff0000, v131
	v_lshlrev_b32_e32 v202, 16, v132
	v_and_b32_e32 v203, 0xffff0000, v132
	v_lshlrev_b32_e32 v204, 16, v133
	v_and_b32_e32 v205, 0xffff0000, v133
	v_lshlrev_b32_e32 v206, 16, v134
	v_and_b32_e32 v207, 0xffff0000, v134
	v_lshlrev_b32_e32 v208, 16, v135
	v_and_b32_e32 v209, 0xffff0000, v135
	v_lshlrev_b32_e32 v216, 16, v136
	v_and_b32_e32 v217, 0xffff0000, v136
	v_lshlrev_b32_e32 v218, 16, v137
	v_and_b32_e32 v219, 0xffff0000, v137
	v_lshlrev_b32_e32 v220, 16, v138
	v_and_b32_e32 v221, 0xffff0000, v138
	v_lshlrev_b32_e32 v222, 16, v139
	v_and_b32_e32 v223, 0xffff0000, v139
	v_lshlrev_b32_e32 v224, 16, v140
	v_and_b32_e32 v225, 0xffff0000, v140
	v_lshlrev_b32_e32 v226, 16, v141
	v_and_b32_e32 v227, 0xffff0000, v141
	v_lshlrev_b32_e32 v228, 16, v142
	v_and_b32_e32 v229, 0xffff0000, v142
	v_lshlrev_b32_e32 v230, 16, v143
	v_and_b32_e32 v231, 0xffff0000, v143
	v_pk_mul_f32 v[252:253], v[216:217], v[216:217]
	v_pk_mul_f32 v[254:255], v[218:219], v[218:219]
	v_pk_fma_f32 v[252:253], v[220:221], v[220:221], v[252:253]
	v_pk_fma_f32 v[254:255], v[222:223], v[222:223], v[254:255]
	v_pk_fma_f32 v[252:253], v[224:225], v[224:225], v[252:253]
	v_pk_fma_f32 v[254:255], v[226:227], v[226:227], v[254:255]
	v_pk_fma_f32 v[252:253], v[228:229], v[228:229], v[252:253]
	v_pk_fma_f32 v[254:255], v[230:231], v[230:231], v[254:255]
	v_pk_add_f32 v[252:253], v[252:253], v[254:255]
	s_nop 0
	v_add_f32_e32 v183, v252, v253
	s_nop 1
	v_add_f32_dpp v183, v183, v183 quad_perm:[1,0,3,2] row_mask:0xf bank_mask:0xf bound_ctrl:1
	s_nop 1
	v_add_f32_dpp v183, v183, v183 quad_perm:[2,3,0,1] row_mask:0xf bank_mask:0xf bound_ctrl:1
	s_nop 1
	v_add_f32_dpp v183, v183, v183 row_half_mirror row_mask:0xf bank_mask:0xf bound_ctrl:1
	s_nop 1
	v_add_f32_dpp v183, v183, v183 row_mirror row_mask:0xf bank_mask:0xf bound_ctrl:1
	s_nop 1
	v_readlane_b32 s98, v183, 0
	v_readlane_b32 s99, v183, 16
	v_readlane_b32 s100, v183, 32
	v_readlane_b32 s101, v183, 48
	s_nop 1
	v_mov_b32_e32 v183, s98
	v_add_f32_e32 v183, s99, v183
	v_add_f32_e32 v183, s100, v183
	v_add_f32_e32 v183, s101, v183
	v_fmamk_f32 v183, v183, 0x3a800000, v182
	v_cmp_gt_f32_e32 vcc, 0x800000, v183
	v_mul_f32_e32 v181, 0x4b800000, v183
	s_nop 1
	v_cndmask_b32_e32 v183, v183, v181, vcc
	v_rsq_f32_e32 v183, v183
	s_nop 0
	v_mul_f32_e32 v181, 0x45800000, v183
	v_cndmask_b32_e32 v184, v183, v181, vcc
	v_mov_b32_e32 v185, v184
	v_pk_mul_f32 v[216:217], v[216:217], v[184:185]
	v_pk_mul_f32 v[218:219], v[218:219], v[184:185]
	v_pk_mul_f32 v[220:221], v[220:221], v[184:185]
	v_pk_mul_f32 v[222:223], v[222:223], v[184:185]
	v_pk_mul_f32 v[224:225], v[224:225], v[184:185]
	v_pk_mul_f32 v[226:227], v[226:227], v[184:185]
	v_pk_mul_f32 v[228:229], v[228:229], v[184:185]
	v_pk_mul_f32 v[230:231], v[230:231], v[184:185]
	v_pk_fma_f32 v[194:195], v[216:217], v[160:161], v[194:195]
	v_pk_fma_f32 v[196:197], v[218:219], v[162:163], v[196:197]
	v_pk_fma_f32 v[198:199], v[220:221], v[164:165], v[198:199]
	v_pk_fma_f32 v[200:201], v[222:223], v[166:167], v[200:201]
	v_pk_fma_f32 v[202:203], v[224:225], v[168:169], v[202:203]
	v_pk_fma_f32 v[204:205], v[226:227], v[170:171], v[204:205]
	v_pk_fma_f32 v[206:207], v[228:229], v[172:173], v[206:207]
	v_pk_fma_f32 v[208:209], v[230:231], v[174:175], v[208:209]
	v_pk_mul_f32 v[252:253], v[194:195], v[194:195]
	v_pk_mul_f32 v[254:255], v[196:197], v[196:197]
	v_pk_fma_f32 v[252:253], v[198:199], v[198:199], v[252:253]
	v_pk_fma_f32 v[254:255], v[200:201], v[200:201], v[254:255]
	v_pk_fma_f32 v[252:253], v[202:203], v[202:203], v[252:253]
	v_pk_fma_f32 v[254:255], v[204:205], v[204:205], v[254:255]
	v_pk_fma_f32 v[252:253], v[206:207], v[206:207], v[252:253]
	v_pk_fma_f32 v[254:255], v[208:209], v[208:209], v[254:255]
	v_pk_add_f32 v[252:253], v[252:253], v[254:255]
	s_nop 0
	v_add_f32_e32 v183, v252, v253
	s_nop 1
	v_add_f32_dpp v183, v183, v183 quad_perm:[1,0,3,2] row_mask:0xf bank_mask:0xf bound_ctrl:1
	s_nop 1
	v_add_f32_dpp v183, v183, v183 quad_perm:[2,3,0,1] row_mask:0xf bank_mask:0xf bound_ctrl:1
	s_nop 1
	v_add_f32_dpp v183, v183, v183 row_half_mirror row_mask:0xf bank_mask:0xf bound_ctrl:1
	s_nop 1
	v_add_f32_dpp v183, v183, v183 row_mirror row_mask:0xf bank_mask:0xf bound_ctrl:1
	s_nop 1
	v_readlane_b32 s98, v183, 0
	v_readlane_b32 s99, v183, 16
	v_readlane_b32 s100, v183, 32
	v_readlane_b32 s101, v183, 48
	s_nop 1
	v_mov_b32_e32 v183, s98
	v_add_f32_e32 v183, s99, v183
	v_add_f32_e32 v183, s100, v183
	v_add_f32_e32 v183, s101, v183
	v_fmamk_f32 v183, v183, 0x3a800000, v182
	v_cmp_gt_f32_e32 vcc, 0x800000, v183
	v_mul_f32_e32 v181, 0x4b800000, v183
	s_nop 1
	v_cndmask_b32_e32 v183, v183, v181, vcc
	v_rsq_f32_e32 v183, v183
	s_nop 0
	v_mul_f32_e32 v181, 0x45800000, v183
	v_cndmask_b32_e32 v184, v183, v181, vcc
	v_mov_b32_e32 v185, v184
	v_cvt_pk_bf16_f32 v128, v194, v195
	v_cvt_pk_bf16_f32 v129, v196, v197
	v_cvt_pk_bf16_f32 v130, v198, v199
	v_cvt_pk_bf16_f32 v131, v200, v201
	v_cvt_pk_bf16_f32 v132, v202, v203
	v_cvt_pk_bf16_f32 v133, v204, v205
	v_cvt_pk_bf16_f32 v134, v206, v207
	v_cvt_pk_bf16_f32 v135, v208, v209
	v_add_u32_e32 v181, 0x1800000, v210
	global_store_dwordx4 v181, v[128:131], s[78:79]
	global_store_dwordx4 v181, v[132:135], s[78:79] offset:1024
	v_add_u32_e32 v236, 0x0, v211
	s_mov_b64 exec, 1
	global_store_dword v236, v184, s[78:79]
	s_mov_b64 exec, -1
	s_waitcnt vmcnt(0)
	v_lshlrev_b32_e32 v194, 16, v144
	v_and_b32_e32 v195, 0xffff0000, v144
	v_lshlrev_b32_e32 v196, 16, v145
	v_and_b32_e32 v197, 0xffff0000, v145
	v_lshlrev_b32_e32 v198, 16, v146
	v_and_b32_e32 v199, 0xffff0000, v146
	v_lshlrev_b32_e32 v200, 16, v147
	v_and_b32_e32 v201, 0xffff0000, v147
	v_lshlrev_b32_e32 v202, 16, v148
	v_and_b32_e32 v203, 0xffff0000, v148
	v_lshlrev_b32_e32 v204, 16, v149
	v_and_b32_e32 v205, 0xffff0000, v149
	v_lshlrev_b32_e32 v206, 16, v150
	v_and_b32_e32 v207, 0xffff0000, v150
	v_lshlrev_b32_e32 v208, 16, v151
	v_and_b32_e32 v209, 0xffff0000, v151
	v_lshlrev_b32_e32 v216, 16, v152
	v_and_b32_e32 v217, 0xffff0000, v152
	v_lshlrev_b32_e32 v218, 16, v153
	v_and_b32_e32 v219, 0xffff0000, v153
	v_lshlrev_b32_e32 v220, 16, v154
	v_and_b32_e32 v221, 0xffff0000, v154
	v_lshlrev_b32_e32 v222, 16, v155
	v_and_b32_e32 v223, 0xffff0000, v155
	v_lshlrev_b32_e32 v224, 16, v156
	v_and_b32_e32 v225, 0xffff0000, v156
	v_lshlrev_b32_e32 v226, 16, v157
	v_and_b32_e32 v227, 0xffff0000, v157
	v_lshlrev_b32_e32 v228, 16, v158
	v_and_b32_e32 v229, 0xffff0000, v158
	v_lshlrev_b32_e32 v230, 16, v159
	v_and_b32_e32 v231, 0xffff0000, v159
	v_pk_mul_f32 v[252:253], v[216:217], v[216:217]
	v_pk_mul_f32 v[254:255], v[218:219], v[218:219]
	v_pk_fma_f32 v[252:253], v[220:221], v[220:221], v[252:253]
	v_pk_fma_f32 v[254:255], v[222:223], v[222:223], v[254:255]
	v_pk_fma_f32 v[252:253], v[224:225], v[224:225], v[252:253]
	v_pk_fma_f32 v[254:255], v[226:227], v[226:227], v[254:255]
	v_pk_fma_f32 v[252:253], v[228:229], v[228:229], v[252:253]
	v_pk_fma_f32 v[254:255], v[230:231], v[230:231], v[254:255]
	v_pk_add_f32 v[252:253], v[252:253], v[254:255]
	s_nop 0
	v_add_f32_e32 v183, v252, v253
	s_nop 1
	v_add_f32_dpp v183, v183, v183 quad_perm:[1,0,3,2] row_mask:0xf bank_mask:0xf bound_ctrl:1
	s_nop 1
	v_add_f32_dpp v183, v183, v183 quad_perm:[2,3,0,1] row_mask:0xf bank_mask:0xf bound_ctrl:1
	s_nop 1
	v_add_f32_dpp v183, v183, v183 row_half_mirror row_mask:0xf bank_mask:0xf bound_ctrl:1
	s_nop 1
	v_add_f32_dpp v183, v183, v183 row_mirror row_mask:0xf bank_mask:0xf bound_ctrl:1
	s_nop 1
	v_readlane_b32 s98, v183, 0
	v_readlane_b32 s99, v183, 16
	v_readlane_b32 s100, v183, 32
	v_readlane_b32 s101, v183, 48
	s_nop 1
	v_mov_b32_e32 v183, s98
	v_add_f32_e32 v183, s99, v183
	v_add_f32_e32 v183, s100, v183
	v_add_f32_e32 v183, s101, v183
	v_fmamk_f32 v183, v183, 0x3a800000, v182
	v_cmp_gt_f32_e32 vcc, 0x800000, v183
	v_mul_f32_e32 v181, 0x4b800000, v183
	s_nop 1
	v_cndmask_b32_e32 v183, v183, v181, vcc
	v_rsq_f32_e32 v183, v183
	s_nop 0
	v_mul_f32_e32 v181, 0x45800000, v183
	v_cndmask_b32_e32 v184, v183, v181, vcc
	v_mov_b32_e32 v185, v184
	v_pk_mul_f32 v[216:217], v[216:217], v[184:185]
	v_pk_mul_f32 v[218:219], v[218:219], v[184:185]
	v_pk_mul_f32 v[220:221], v[220:221], v[184:185]
	v_pk_mul_f32 v[222:223], v[222:223], v[184:185]
	v_pk_mul_f32 v[224:225], v[224:225], v[184:185]
	v_pk_mul_f32 v[226:227], v[226:227], v[184:185]
	v_pk_mul_f32 v[228:229], v[228:229], v[184:185]
	v_pk_mul_f32 v[230:231], v[230:231], v[184:185]
	v_pk_fma_f32 v[194:195], v[216:217], v[160:161], v[194:195]
	v_pk_fma_f32 v[196:197], v[218:219], v[162:163], v[196:197]
	v_pk_fma_f32 v[198:199], v[220:221], v[164:165], v[198:199]
	v_pk_fma_f32 v[200:201], v[222:223], v[166:167], v[200:201]
	v_pk_fma_f32 v[202:203], v[224:225], v[168:169], v[202:203]
	v_pk_fma_f32 v[204:205], v[226:227], v[170:171], v[204:205]
	v_pk_fma_f32 v[206:207], v[228:229], v[172:173], v[206:207]
	v_pk_fma_f32 v[208:209], v[230:231], v[174:175], v[208:209]
	v_pk_mul_f32 v[252:253], v[194:195], v[194:195]
	v_pk_mul_f32 v[254:255], v[196:197], v[196:197]
	v_pk_fma_f32 v[252:253], v[198:199], v[198:199], v[252:253]
	v_pk_fma_f32 v[254:255], v[200:201], v[200:201], v[254:255]
	v_pk_fma_f32 v[252:253], v[202:203], v[202:203], v[252:253]
	v_pk_fma_f32 v[254:255], v[204:205], v[204:205], v[254:255]
	v_pk_fma_f32 v[252:253], v[206:207], v[206:207], v[252:253]
	v_pk_fma_f32 v[254:255], v[208:209], v[208:209], v[254:255]
	v_pk_add_f32 v[252:253], v[252:253], v[254:255]
	s_nop 0
	v_add_f32_e32 v183, v252, v253
	s_nop 1
	v_add_f32_dpp v183, v183, v183 quad_perm:[1,0,3,2] row_mask:0xf bank_mask:0xf bound_ctrl:1
	s_nop 1
	v_add_f32_dpp v183, v183, v183 quad_perm:[2,3,0,1] row_mask:0xf bank_mask:0xf bound_ctrl:1
	s_nop 1
	v_add_f32_dpp v183, v183, v183 row_half_mirror row_mask:0xf bank_mask:0xf bound_ctrl:1
	s_nop 1
	v_add_f32_dpp v183, v183, v183 row_mirror row_mask:0xf bank_mask:0xf bound_ctrl:1
	s_nop 1
	v_readlane_b32 s98, v183, 0
	v_readlane_b32 s99, v183, 16
	v_readlane_b32 s100, v183, 32
	v_readlane_b32 s101, v183, 48
	s_nop 1
	v_mov_b32_e32 v183, s98
	v_add_f32_e32 v183, s99, v183
	v_add_f32_e32 v183, s100, v183
	v_add_f32_e32 v183, s101, v183
	v_fmamk_f32 v183, v183, 0x3a800000, v182
	v_cmp_gt_f32_e32 vcc, 0x800000, v183
	v_mul_f32_e32 v181, 0x4b800000, v183
	s_nop 1
	v_cndmask_b32_e32 v183, v183, v181, vcc
	v_rsq_f32_e32 v183, v183
	s_nop 0
	v_mul_f32_e32 v181, 0x45800000, v183
	v_cndmask_b32_e32 v184, v183, v181, vcc
	v_mov_b32_e32 v185, v184
	v_cvt_pk_bf16_f32 v144, v194, v195
	v_cvt_pk_bf16_f32 v145, v196, v197
	v_cvt_pk_bf16_f32 v146, v198, v199
	v_cvt_pk_bf16_f32 v147, v200, v201
	v_cvt_pk_bf16_f32 v148, v202, v203
	v_cvt_pk_bf16_f32 v149, v204, v205
	v_cvt_pk_bf16_f32 v150, v206, v207
	v_cvt_pk_bf16_f32 v151, v208, v209
	v_add_u32_e32 v181, 0x1c00000, v210
	global_store_dwordx4 v181, v[144:147], s[78:79]
	global_store_dwordx4 v181, v[148:151], s[78:79] offset:1024
	v_add_u32_e32 v236, 0x2000, v211
	s_mov_b64 exec, 1
	global_store_dword v236, v184, s[78:79]
	s_mov_b64 exec, -1
	s_branch .Lmyxupd_done_1
.Lmyxupd_s_1:
	v_add_u32_e32 v178, 0x1800000, v177
	v_add_u32_e32 v181, 0x9e00000, v177
	global_load_dwordx4 v[0:3], v178, s[78:79]
	global_load_dwordx4 v[4:7], v178, s[78:79] offset:1024
	global_load_dwordx4 v[8:11], v181, s[78:79]
	global_load_dwordx4 v[12:15], v181, s[78:79] offset:1024
	v_add_u32_e32 v178, 0x1c00000, v177
	v_add_u32_e32 v181, 0xa200000, v177
	global_load_dwordx4 v[16:19], v178, s[78:79]
	global_load_dwordx4 v[20:23], v178, s[78:79] offset:1024
	global_load_dwordx4 v[24:27], v181, s[78:79]
	global_load_dwordx4 v[28:31], v181, s[78:79] offset:1024
	v_lshrrev_b32_e32 v179, 2, v179
	v_lshlrev_b32_e32 v210, 4, v176
	v_lshl_add_u32 v210, v179, 11, v210
	v_lshlrev_b32_e32 v211, 2, v179
	v_add_u32_e32 v211, 0x10000, v211
	v_add_u32_e32 v181, 0x3800000, v210
	global_load_dwordx4 v[32:35], v181, s[78:79]
	global_load_dwordx4 v[36:39], v181, s[78:79] offset:1024
	v_lshl_add_u32 v183, v179, 12, v180
	v_add_u32_e32 v183, 0xbf00000, v183
	v_add_u32_e32 v181, 0x0, v183
	global_load_dwordx4 v[40:43], v181, s[78:79]
	global_load_dwordx4 v[44:47], v181, s[78:79] offset:16
	global_load_dwordx4 v[48:51], v181, s[78:79] offset:2048
	global_load_dwordx4 v[52:55], v181, s[78:79] offset:2064
	v_add_u32_e32 v181, 0x200000, v183
	global_load_dwordx4 v[56:59], v181, s[78:79]
	global_load_dwordx4 v[60:63], v181, s[78:79] offset:16
	global_load_dwordx4 v[64:67], v181, s[78:79] offset:2048
	global_load_dwordx4 v[68:71], v181, s[78:79] offset:2064
	v_add_u32_e32 v181, 0x400000, v183
	global_load_dwordx4 v[72:75], v181, s[78:79]
	global_load_dwordx4 v[76:79], v181, s[78:79] offset:16
	global_load_dwordx4 v[80:83], v181, s[78:79] offset:2048
	global_load_dwordx4 v[84:87], v181, s[78:79] offset:2064
	v_add_u32_e32 v181, 0x600000, v183
	global_load_dwordx4 v[88:91], v181, s[78:79]
	global_load_dwordx4 v[92:95], v181, s[78:79] offset:16
	global_load_dwordx4 v[96:99], v181, s[78:79] offset:2048
	global_load_dwordx4 v[100:103], v181, s[78:79] offset:2064
	v_add_u32_e32 v181, 0x800000, v183
	global_load_dwordx4 v[104:107], v181, s[78:79]
	global_load_dwordx4 v[108:111], v181, s[78:79] offset:16
	global_load_dwordx4 v[112:115], v181, s[78:79] offset:2048
	global_load_dwordx4 v[116:119], v181, s[78:79] offset:2064
	v_add_u32_e32 v181, 0xa00000, v183
	global_load_dwordx4 v[120:123], v181, s[78:79]
	global_load_dwordx4 v[124:127], v181, s[78:79] offset:16
	global_load_dwordx4 v[128:131], v181, s[78:79] offset:2048
	global_load_dwordx4 v[132:135], v181, s[78:79] offset:2064
	v_add_u32_e32 v181, 0xc00000, v183
	global_load_dwordx4 v[136:139], v181, s[78:79]
	global_load_dwordx4 v[140:143], v181, s[78:79] offset:16
	global_load_dwordx4 v[144:147], v181, s[78:79] offset:2048
	global_load_dwordx4 v[148:151], v181, s[78:79] offset:2064
	v_mov_b32_e32 v178, v183
	s_waitcnt vmcnt(34)
	v_lshlrev_b32_e32 v194, 16, v0
	v_and_b32_e32 v195, 0xffff0000, v0
	v_lshlrev_b32_e32 v196, 16, v1
	v_and_b32_e32 v197, 0xffff0000, v1
	v_lshlrev_b32_e32 v198, 16, v2
	v_and_b32_e32 v199, 0xffff0000, v2
	v_lshlrev_b32_e32 v200, 16, v3
	v_and_b32_e32 v201, 0xffff0000, v3
	v_lshlrev_b32_e32 v202, 16, v4
	v_and_b32_e32 v203, 0xffff0000, v4
	v_lshlrev_b32_e32 v204, 16, v5
	v_and_b32_e32 v205, 0xffff0000, v5
	v_lshlrev_b32_e32 v206, 16, v6
	v_and_b32_e32 v207, 0xffff0000, v6
	v_lshlrev_b32_e32 v208, 16, v7
	v_and_b32_e32 v209, 0xffff0000, v7
	v_lshlrev_b32_e32 v216, 16, v8
	v_and_b32_e32 v217, 0xffff0000, v8
	v_lshlrev_b32_e32 v218, 16, v9
	v_and_b32_e32 v219, 0xffff0000, v9
	v_lshlrev_b32_e32 v220, 16, v10
	v_and_b32_e32 v221, 0xffff0000, v10
	v_lshlrev_b32_e32 v222, 16, v11
	v_and_b32_e32 v223, 0xffff0000, v11
	v_lshlrev_b32_e32 v224, 16, v12
	v_and_b32_e32 v225, 0xffff0000, v12
	v_lshlrev_b32_e32 v226, 16, v13
	v_and_b32_e32 v227, 0xffff0000, v13
	v_lshlrev_b32_e32 v228, 16, v14
	v_and_b32_e32 v229, 0xffff0000, v14
	v_lshlrev_b32_e32 v230, 16, v15
	v_and_b32_e32 v231, 0xffff0000, v15
	v_pk_mul_f32 v[252:253], v[216:217], v[216:217]
	v_pk_mul_f32 v[254:255], v[218:219], v[218:219]
	v_pk_fma_f32 v[252:253], v[220:221], v[220:221], v[252:253]
	v_pk_fma_f32 v[254:255], v[222:223], v[222:223], v[254:255]
	v_pk_fma_f32 v[252:253], v[224:225], v[224:225], v[252:253]
	v_pk_fma_f32 v[254:255], v[226:227], v[226:227], v[254:255]
	v_pk_fma_f32 v[252:253], v[228:229], v[228:229], v[252:253]
	v_pk_fma_f32 v[254:255], v[230:231], v[230:231], v[254:255]
	v_pk_add_f32 v[252:253], v[252:253], v[254:255]
	s_nop 0
	v_add_f32_e32 v183, v252, v253
	s_nop 1
	v_add_f32_dpp v183, v183, v183 quad_perm:[1,0,3,2] row_mask:0xf bank_mask:0xf bound_ctrl:1
	s_nop 1
	v_add_f32_dpp v183, v183, v183 quad_perm:[2,3,0,1] row_mask:0xf bank_mask:0xf bound_ctrl:1
	s_nop 1
	v_add_f32_dpp v183, v183, v183 row_half_mirror row_mask:0xf bank_mask:0xf bound_ctrl:1
	s_nop 1
	v_add_f32_dpp v183, v183, v183 row_mirror row_mask:0xf bank_mask:0xf bound_ctrl:1
	s_nop 1
	v_readlane_b32 s98, v183, 0
	v_readlane_b32 s99, v183, 16
	v_readlane_b32 s100, v183, 32
	v_readlane_b32 s101, v183, 48
	s_nop 1
	v_mov_b32_e32 v183, s98
	v_add_f32_e32 v183, s99, v183
	v_add_f32_e32 v183, s100, v183
	v_add_f32_e32 v183, s101, v183
	v_fmamk_f32 v183, v183, 0x3a800000, v182
	v_cmp_gt_f32_e32 vcc, 0x800000, v183
	v_mul_f32_e32 v181, 0x4b800000, v183
	s_nop 1
	v_cndmask_b32_e32 v183, v183, v181, vcc
	v_rsq_f32_e32 v183, v183
	s_nop 0
	v_mul_f32_e32 v181, 0x45800000, v183
	v_cndmask_b32_e32 v184, v183, v181, vcc
	v_mov_b32_e32 v185, v184
	v_pk_mul_f32 v[216:217], v[216:217], v[184:185]
	v_pk_mul_f32 v[218:219], v[218:219], v[184:185]
	v_pk_mul_f32 v[220:221], v[220:221], v[184:185]
	v_pk_mul_f32 v[222:223], v[222:223], v[184:185]
	v_pk_mul_f32 v[224:225], v[224:225], v[184:185]
	v_pk_mul_f32 v[226:227], v[226:227], v[184:185]
	v_pk_mul_f32 v[228:229], v[228:229], v[184:185]
	v_pk_mul_f32 v[230:231], v[230:231], v[184:185]
	v_pk_fma_f32 v[194:195], v[216:217], v[160:161], v[194:195]
	v_pk_fma_f32 v[196:197], v[218:219], v[162:163], v[196:197]
	v_pk_fma_f32 v[198:199], v[220:221], v[164:165], v[198:199]
	v_pk_fma_f32 v[200:201], v[222:223], v[166:167], v[200:201]
	v_pk_fma_f32 v[202:203], v[224:225], v[168:169], v[202:203]
	v_pk_fma_f32 v[204:205], v[226:227], v[170:171], v[204:205]
	v_pk_fma_f32 v[206:207], v[228:229], v[172:173], v[206:207]
	v_pk_fma_f32 v[208:209], v[230:231], v[174:175], v[208:209]
	v_pk_mul_f32 v[252:253], v[194:195], v[194:195]
	v_pk_mul_f32 v[254:255], v[196:197], v[196:197]
	v_pk_fma_f32 v[252:253], v[198:199], v[198:199], v[252:253]
	v_pk_fma_f32 v[254:255], v[200:201], v[200:201], v[254:255]
	v_pk_fma_f32 v[252:253], v[202:203], v[202:203], v[252:253]
	v_pk_fma_f32 v[254:255], v[204:205], v[204:205], v[254:255]
	v_pk_fma_f32 v[252:253], v[206:207], v[206:207], v[252:253]
	v_pk_fma_f32 v[254:255], v[208:209], v[208:209], v[254:255]
	v_pk_add_f32 v[252:253], v[252:253], v[254:255]
	s_nop 0
	v_add_f32_e32 v183, v252, v253
	s_nop 1
	v_add_f32_dpp v183, v183, v183 quad_perm:[1,0,3,2] row_mask:0xf bank_mask:0xf bound_ctrl:1
	s_nop 1
	v_add_f32_dpp v183, v183, v183 quad_perm:[2,3,0,1] row_mask:0xf bank_mask:0xf bound_ctrl:1
	s_nop 1
	v_add_f32_dpp v183, v183, v183 row_half_mirror row_mask:0xf bank_mask:0xf bound_ctrl:1
	s_nop 1
	v_add_f32_dpp v183, v183, v183 row_mirror row_mask:0xf bank_mask:0xf bound_ctrl:1
	s_nop 1
	v_readlane_b32 s98, v183, 0
	v_readlane_b32 s99, v183, 16
	v_readlane_b32 s100, v183, 32
	v_readlane_b32 s101, v183, 48
	s_nop 1
	v_mov_b32_e32 v183, s98
	v_add_f32_e32 v183, s99, v183
	v_add_f32_e32 v183, s100, v183
	v_add_f32_e32 v183, s101, v183
	v_fmamk_f32 v183, v183, 0x3a800000, v182
	v_cmp_gt_f32_e32 vcc, 0x800000, v183
	v_mul_f32_e32 v181, 0x4b800000, v183
	s_nop 1
	v_cndmask_b32_e32 v183, v183, v181, vcc
	v_rsq_f32_e32 v183, v183
	s_nop 0
	v_mul_f32_e32 v181, 0x45800000, v183
	v_cndmask_b32_e32 v184, v183, v181, vcc
	v_mov_b32_e32 v185, v184
	v_cvt_pk_bf16_f32 v0, v194, v195
	v_cvt_pk_bf16_f32 v1, v196, v197
	v_cvt_pk_bf16_f32 v2, v198, v199
	v_cvt_pk_bf16_f32 v3, v200, v201
	v_cvt_pk_bf16_f32 v4, v202, v203
	v_cvt_pk_bf16_f32 v5, v204, v205
	v_cvt_pk_bf16_f32 v6, v206, v207
	v_cvt_pk_bf16_f32 v7, v208, v209
	v_add_u32_e32 v181, 0x1800000, v177
	global_store_dwordx4 v181, v[0:3], s[78:79]
	global_store_dwordx4 v181, v[4:7], s[78:79] offset:1024
	v_add_u32_e32 v236, 0x0, v237
	s_mov_b64 exec, 1
	global_store_dword v236, v184, s[78:79]
	s_mov_b64 exec, -1
	s_waitcnt vmcnt(30)
	v_lshlrev_b32_e32 v194, 16, v16
	v_and_b32_e32 v195, 0xffff0000, v16
	v_lshlrev_b32_e32 v196, 16, v17
	v_and_b32_e32 v197, 0xffff0000, v17
	v_lshlrev_b32_e32 v198, 16, v18
	v_and_b32_e32 v199, 0xffff0000, v18
	v_lshlrev_b32_e32 v200, 16, v19
	v_and_b32_e32 v201, 0xffff0000, v19
	v_lshlrev_b32_e32 v202, 16, v20
	v_and_b32_e32 v203, 0xffff0000, v20
	v_lshlrev_b32_e32 v204, 16, v21
	v_and_b32_e32 v205, 0xffff0000, v21
	v_lshlrev_b32_e32 v206, 16, v22
	v_and_b32_e32 v207, 0xffff0000, v22
	v_lshlrev_b32_e32 v208, 16, v23
	v_and_b32_e32 v209, 0xffff0000, v23
	v_lshlrev_b32_e32 v216, 16, v24
	v_and_b32_e32 v217, 0xffff0000, v24
	v_lshlrev_b32_e32 v218, 16, v25
	v_and_b32_e32 v219, 0xffff0000, v25
	v_lshlrev_b32_e32 v220, 16, v26
	v_and_b32_e32 v221, 0xffff0000, v26
	v_lshlrev_b32_e32 v222, 16, v27
	v_and_b32_e32 v223, 0xffff0000, v27
	v_lshlrev_b32_e32 v224, 16, v28
	v_and_b32_e32 v225, 0xffff0000, v28
	v_lshlrev_b32_e32 v226, 16, v29
	v_and_b32_e32 v227, 0xffff0000, v29
	v_lshlrev_b32_e32 v228, 16, v30
	v_and_b32_e32 v229, 0xffff0000, v30
	v_lshlrev_b32_e32 v230, 16, v31
	v_and_b32_e32 v231, 0xffff0000, v31
	v_pk_mul_f32 v[252:253], v[216:217], v[216:217]
	v_pk_mul_f32 v[254:255], v[218:219], v[218:219]
	v_pk_fma_f32 v[252:253], v[220:221], v[220:221], v[252:253]
	v_pk_fma_f32 v[254:255], v[222:223], v[222:223], v[254:255]
	v_pk_fma_f32 v[252:253], v[224:225], v[224:225], v[252:253]
	v_pk_fma_f32 v[254:255], v[226:227], v[226:227], v[254:255]
	v_pk_fma_f32 v[252:253], v[228:229], v[228:229], v[252:253]
	v_pk_fma_f32 v[254:255], v[230:231], v[230:231], v[254:255]
	v_pk_add_f32 v[252:253], v[252:253], v[254:255]
	s_nop 0
	v_add_f32_e32 v183, v252, v253
	s_nop 1
	v_add_f32_dpp v183, v183, v183 quad_perm:[1,0,3,2] row_mask:0xf bank_mask:0xf bound_ctrl:1
	s_nop 1
	v_add_f32_dpp v183, v183, v183 quad_perm:[2,3,0,1] row_mask:0xf bank_mask:0xf bound_ctrl:1
	s_nop 1
	v_add_f32_dpp v183, v183, v183 row_half_mirror row_mask:0xf bank_mask:0xf bound_ctrl:1
	s_nop 1
	v_add_f32_dpp v183, v183, v183 row_mirror row_mask:0xf bank_mask:0xf bound_ctrl:1
	s_nop 1
	v_readlane_b32 s98, v183, 0
	v_readlane_b32 s99, v183, 16
	v_readlane_b32 s100, v183, 32
	v_readlane_b32 s101, v183, 48
	s_nop 1
	v_mov_b32_e32 v183, s98
	v_add_f32_e32 v183, s99, v183
	v_add_f32_e32 v183, s100, v183
	v_add_f32_e32 v183, s101, v183
	v_fmamk_f32 v183, v183, 0x3a800000, v182
	v_cmp_gt_f32_e32 vcc, 0x800000, v183
	v_mul_f32_e32 v181, 0x4b800000, v183
	s_nop 1
	v_cndmask_b32_e32 v183, v183, v181, vcc
	v_rsq_f32_e32 v183, v183
	s_nop 0
	v_mul_f32_e32 v181, 0x45800000, v183
	v_cndmask_b32_e32 v184, v183, v181, vcc
	v_mov_b32_e32 v185, v184
	v_pk_mul_f32 v[216:217], v[216:217], v[184:185]
	v_pk_mul_f32 v[218:219], v[218:219], v[184:185]
	v_pk_mul_f32 v[220:221], v[220:221], v[184:185]
	v_pk_mul_f32 v[222:223], v[222:223], v[184:185]
	v_pk_mul_f32 v[224:225], v[224:225], v[184:185]
	v_pk_mul_f32 v[226:227], v[226:227], v[184:185]
	v_pk_mul_f32 v[228:229], v[228:229], v[184:185]
	v_pk_mul_f32 v[230:231], v[230:231], v[184:185]
	v_pk_fma_f32 v[194:195], v[216:217], v[160:161], v[194:195]
	v_pk_fma_f32 v[196:197], v[218:219], v[162:163], v[196:197]
	v_pk_fma_f32 v[198:199], v[220:221], v[164:165], v[198:199]
	v_pk_fma_f32 v[200:201], v[222:223], v[166:167], v[200:201]
	v_pk_fma_f32 v[202:203], v[224:225], v[168:169], v[202:203]
	v_pk_fma_f32 v[204:205], v[226:227], v[170:171], v[204:205]
	v_pk_fma_f32 v[206:207], v[228:229], v[172:173], v[206:207]
	v_pk_fma_f32 v[208:209], v[230:231], v[174:175], v[208:209]
	v_pk_mul_f32 v[252:253], v[194:195], v[194:195]
	v_pk_mul_f32 v[254:255], v[196:197], v[196:197]
	v_pk_fma_f32 v[252:253], v[198:199], v[198:199], v[252:253]
	v_pk_fma_f32 v[254:255], v[200:201], v[200:201], v[254:255]
	v_pk_fma_f32 v[252:253], v[202:203], v[202:203], v[252:253]
	v_pk_fma_f32 v[254:255], v[204:205], v[204:205], v[254:255]
	v_pk_fma_f32 v[252:253], v[206:207], v[206:207], v[252:253]
	v_pk_fma_f32 v[254:255], v[208:209], v[208:209], v[254:255]
	v_pk_add_f32 v[252:253], v[252:253], v[254:255]
	s_nop 0
	v_add_f32_e32 v183, v252, v253
	s_nop 1
	v_add_f32_dpp v183, v183, v183 quad_perm:[1,0,3,2] row_mask:0xf bank_mask:0xf bound_ctrl:1
	s_nop 1
	v_add_f32_dpp v183, v183, v183 quad_perm:[2,3,0,1] row_mask:0xf bank_mask:0xf bound_ctrl:1
	s_nop 1
	v_add_f32_dpp v183, v183, v183 row_half_mirror row_mask:0xf bank_mask:0xf bound_ctrl:1
	s_nop 1
	v_add_f32_dpp v183, v183, v183 row_mirror row_mask:0xf bank_mask:0xf bound_ctrl:1
	s_nop 1
	v_readlane_b32 s98, v183, 0
	v_readlane_b32 s99, v183, 16
	v_readlane_b32 s100, v183, 32
	v_readlane_b32 s101, v183, 48
	s_nop 1
	v_mov_b32_e32 v183, s98
	v_add_f32_e32 v183, s99, v183
	v_add_f32_e32 v183, s100, v183
	v_add_f32_e32 v183, s101, v183
	v_fmamk_f32 v183, v183, 0x3a800000, v182
	v_cmp_gt_f32_e32 vcc, 0x800000, v183
	v_mul_f32_e32 v181, 0x4b800000, v183
	s_nop 1
	v_cndmask_b32_e32 v183, v183, v181, vcc
	v_rsq_f32_e32 v183, v183
	s_nop 0
	v_mul_f32_e32 v181, 0x45800000, v183
	v_cndmask_b32_e32 v184, v183, v181, vcc
	v_mov_b32_e32 v185, v184
	v_cvt_pk_bf16_f32 v16, v194, v195
	v_cvt_pk_bf16_f32 v17, v196, v197
	v_cvt_pk_bf16_f32 v18, v198, v199
	v_cvt_pk_bf16_f32 v19, v200, v201
	v_cvt_pk_bf16_f32 v20, v202, v203
	v_cvt_pk_bf16_f32 v21, v204, v205
	v_cvt_pk_bf16_f32 v22, v206, v207
	v_cvt_pk_bf16_f32 v23, v208, v209
	v_add_u32_e32 v181, 0x1c00000, v177
	global_store_dwordx4 v181, v[16:19], s[78:79]
	global_store_dwordx4 v181, v[20:23], s[78:79] offset:1024
	v_add_u32_e32 v236, 0x2000, v237
	s_mov_b64 exec, 1
	global_store_dword v236, v184, s[78:79]
	s_mov_b64 exec, -1
	s_waitcnt vmcnt(24)
	v_pk_add_f32 v[216:217], v[40:41], 0 op_sel_hi:[1,0]
	v_pk_add_f32 v[218:219], v[42:43], 0 op_sel_hi:[1,0]
	v_pk_add_f32 v[220:221], v[44:45], 0 op_sel_hi:[1,0]
	v_pk_add_f32 v[222:223], v[46:47], 0 op_sel_hi:[1,0]
	v_pk_add_f32 v[224:225], v[48:49], 0 op_sel_hi:[1,0]
	v_pk_add_f32 v[226:227], v[50:51], 0 op_sel_hi:[1,0]
	v_pk_add_f32 v[228:229], v[52:53], 0 op_sel_hi:[1,0]
	v_pk_add_f32 v[230:231], v[54:55], 0 op_sel_hi:[1,0]
	s_waitcnt vmcnt(20)
	v_pk_add_f32 v[216:217], v[216:217], v[56:57]
	v_pk_add_f32 v[218:219], v[218:219], v[58:59]
	v_pk_add_f32 v[220:221], v[220:221], v[60:61]
	v_pk_add_f32 v[222:223], v[222:223], v[62:63]
	v_pk_add_f32 v[224:225], v[224:225], v[64:65]
	v_pk_add_f32 v[226:227], v[226:227], v[66:67]
	v_pk_add_f32 v[228:229], v[228:229], v[68:69]
	v_pk_add_f32 v[230:231], v[230:231], v[70:71]
	v_lshlrev_b32_e32 v194, 16, v32
	v_and_b32_e32 v195, 0xffff0000, v32
	v_lshlrev_b32_e32 v196, 16, v33
	v_and_b32_e32 v197, 0xffff0000, v33
	v_lshlrev_b32_e32 v198, 16, v34
	v_and_b32_e32 v199, 0xffff0000, v34
	v_lshlrev_b32_e32 v200, 16, v35
	v_and_b32_e32 v201, 0xffff0000, v35
	v_lshlrev_b32_e32 v202, 16, v36
	v_and_b32_e32 v203, 0xffff0000, v36
	v_lshlrev_b32_e32 v204, 16, v37
	v_and_b32_e32 v205, 0xffff0000, v37
	v_lshlrev_b32_e32 v206, 16, v38
	v_and_b32_e32 v207, 0xffff0000, v38
	v_lshlrev_b32_e32 v208, 16, v39
	v_and_b32_e32 v209, 0xffff0000, v39
	v_add_u32_e32 v181, 0xe00000, v178
	global_load_dwordx4 v[0:3], v181, s[78:79]
	global_load_dwordx4 v[4:7], v181, s[78:79] offset:16
	global_load_dwordx4 v[8:11], v181, s[78:79] offset:2048
	global_load_dwordx4 v[12:15], v181, s[78:79] offset:2064
	v_add_u32_e32 v181, 0x1000000, v178
	global_load_dwordx4 v[16:19], v181, s[78:79]
	global_load_dwordx4 v[20:23], v181, s[78:79] offset:16
	global_load_dwordx4 v[24:27], v181, s[78:79] offset:2048
	global_load_dwordx4 v[28:31], v181, s[78:79] offset:2064
	v_add_u32_e32 v181, 0x1200000, v178
	global_load_dwordx4 v[32:35], v181, s[78:79]
	global_load_dwordx4 v[36:39], v181, s[78:79] offset:16
	global_load_dwordx4 v[40:43], v181, s[78:79] offset:2048
	global_load_dwordx4 v[44:47], v181, s[78:79] offset:2064
	v_add_u32_e32 v181, 0x1400000, v178
	global_load_dwordx4 v[48:51], v181, s[78:79]
	global_load_dwordx4 v[52:55], v181, s[78:79] offset:16
	global_load_dwordx4 v[56:59], v181, s[78:79] offset:2048
	global_load_dwordx4 v[60:63], v181, s[78:79] offset:2064
	s_waitcnt vmcnt(32)
	v_pk_add_f32 v[216:217], v[216:217], v[72:73]
	v_pk_add_f32 v[218:219], v[218:219], v[74:75]
	v_pk_add_f32 v[220:221], v[220:221], v[76:77]
	v_pk_add_f32 v[222:223], v[222:223], v[78:79]
	v_pk_add_f32 v[224:225], v[224:225], v[80:81]
	v_pk_add_f32 v[226:227], v[226:227], v[82:83]
	v_pk_add_f32 v[228:229], v[228:229], v[84:85]
	v_pk_add_f32 v[230:231], v[230:231], v[86:87]
	s_waitcnt vmcnt(28)
	v_pk_add_f32 v[216:217], v[216:217], v[88:89]
	v_pk_add_f32 v[218:219], v[218:219], v[90:91]
	v_pk_add_f32 v[220:221], v[220:221], v[92:93]
	v_pk_add_f32 v[222:223], v[222:223], v[94:95]
	v_pk_add_f32 v[224:225], v[224:225], v[96:97]
	v_pk_add_f32 v[226:227], v[226:227], v[98:99]
	v_pk_add_f32 v[228:229], v[228:229], v[100:101]
	v_pk_add_f32 v[230:231], v[230:231], v[102:103]
	s_waitcnt vmcnt(24)
	v_pk_add_f32 v[216:217], v[216:217], v[104:105]
	v_pk_add_f32 v[218:219], v[218:219], v[106:107]
	v_pk_add_f32 v[220:221], v[220:221], v[108:109]
	v_pk_add_f32 v[222:223], v[222:223], v[110:111]
	v_pk_add_f32 v[224:225], v[224:225], v[112:113]
	v_pk_add_f32 v[226:227], v[226:227], v[114:115]
	v_pk_add_f32 v[228:229], v[228:229], v[116:117]
	v_pk_add_f32 v[230:231], v[230:231], v[118:119]
	s_waitcnt vmcnt(20)
	v_pk_add_f32 v[216:217], v[216:217], v[120:121]
	v_pk_add_f32 v[218:219], v[218:219], v[122:123]
	v_pk_add_f32 v[220:221], v[220:221], v[124:125]
	v_pk_add_f32 v[222:223], v[222:223], v[126:127]
	v_pk_add_f32 v[224:225], v[224:225], v[128:129]
	v_pk_add_f32 v[226:227], v[226:227], v[130:131]
	v_pk_add_f32 v[228:229], v[228:229], v[132:133]
	v_pk_add_f32 v[230:231], v[230:231], v[134:135]
	s_waitcnt vmcnt(16)
	v_pk_add_f32 v[216:217], v[216:217], v[136:137]
	v_pk_add_f32 v[218:219], v[218:219], v[138:139]
	v_pk_add_f32 v[220:221], v[220:221], v[140:141]
	v_pk_add_f32 v[222:223], v[222:223], v[142:143]
	v_pk_add_f32 v[224:225], v[224:225], v[144:145]
	v_pk_add_f32 v[226:227], v[226:227], v[146:147]
	v_pk_add_f32 v[228:229], v[228:229], v[148:149]
	v_pk_add_f32 v[230:231], v[230:231], v[150:151]
	s_waitcnt vmcnt(12)
	v_pk_add_f32 v[216:217], v[216:217], v[0:1]
	v_pk_add_f32 v[218:219], v[218:219], v[2:3]
	v_pk_add_f32 v[220:221], v[220:221], v[4:5]
	v_pk_add_f32 v[222:223], v[222:223], v[6:7]
	v_pk_add_f32 v[224:225], v[224:225], v[8:9]
	v_pk_add_f32 v[226:227], v[226:227], v[10:11]
	v_pk_add_f32 v[228:229], v[228:229], v[12:13]
	v_pk_add_f32 v[230:231], v[230:231], v[14:15]
	s_waitcnt vmcnt(8)
	v_pk_add_f32 v[216:217], v[216:217], v[16:17]
	v_pk_add_f32 v[218:219], v[218:219], v[18:19]
	v_pk_add_f32 v[220:221], v[220:221], v[20:21]
	v_pk_add_f32 v[222:223], v[222:223], v[22:23]
	v_pk_add_f32 v[224:225], v[224:225], v[24:25]
	v_pk_add_f32 v[226:227], v[226:227], v[26:27]
	v_pk_add_f32 v[228:229], v[228:229], v[28:29]
	v_pk_add_f32 v[230:231], v[230:231], v[30:31]
	s_waitcnt vmcnt(4)
	v_pk_add_f32 v[216:217], v[216:217], v[32:33]
	v_pk_add_f32 v[218:219], v[218:219], v[34:35]
	v_pk_add_f32 v[220:221], v[220:221], v[36:37]
	v_pk_add_f32 v[222:223], v[222:223], v[38:39]
	v_pk_add_f32 v[224:225], v[224:225], v[40:41]
	v_pk_add_f32 v[226:227], v[226:227], v[42:43]
	v_pk_add_f32 v[228:229], v[228:229], v[44:45]
	v_pk_add_f32 v[230:231], v[230:231], v[46:47]
	s_waitcnt vmcnt(0)
	v_pk_add_f32 v[216:217], v[216:217], v[48:49]
	v_pk_add_f32 v[218:219], v[218:219], v[50:51]
	v_pk_add_f32 v[220:221], v[220:221], v[52:53]
	v_pk_add_f32 v[222:223], v[222:223], v[54:55]
	v_pk_add_f32 v[224:225], v[224:225], v[56:57]
	v_pk_add_f32 v[226:227], v[226:227], v[58:59]
	v_pk_add_f32 v[228:229], v[228:229], v[60:61]
	v_pk_add_f32 v[230:231], v[230:231], v[62:63]
	v_pk_mul_f32 v[252:253], v[216:217], v[216:217]
	v_pk_mul_f32 v[254:255], v[218:219], v[218:219]
	v_pk_fma_f32 v[252:253], v[220:221], v[220:221], v[252:253]
	v_pk_fma_f32 v[254:255], v[222:223], v[222:223], v[254:255]
	v_pk_fma_f32 v[252:253], v[224:225], v[224:225], v[252:253]
	v_pk_fma_f32 v[254:255], v[226:227], v[226:227], v[254:255]
	v_pk_fma_f32 v[252:253], v[228:229], v[228:229], v[252:253]
	v_pk_fma_f32 v[254:255], v[230:231], v[230:231], v[254:255]
	v_pk_add_f32 v[252:253], v[252:253], v[254:255]
	s_nop 0
	v_add_f32_e32 v183, v252, v253
	s_nop 1
	v_add_f32_dpp v183, v183, v183 quad_perm:[1,0,3,2] row_mask:0xf bank_mask:0xf bound_ctrl:1
	s_nop 1
	v_add_f32_dpp v183, v183, v183 quad_perm:[2,3,0,1] row_mask:0xf bank_mask:0xf bound_ctrl:1
	s_nop 1
	v_add_f32_dpp v183, v183, v183 row_half_mirror row_mask:0xf bank_mask:0xf bound_ctrl:1
	s_nop 1
	v_add_f32_dpp v183, v183, v183 row_mirror row_mask:0xf bank_mask:0xf bound_ctrl:1
	s_nop 1
	v_readlane_b32 s98, v183, 0
	v_readlane_b32 s99, v183, 16
	v_readlane_b32 s100, v183, 32
	v_readlane_b32 s101, v183, 48
	s_nop 1
	v_mov_b32_e32 v183, s98
	v_add_f32_e32 v183, s99, v183
	v_add_f32_e32 v183, s100, v183
	v_add_f32_e32 v183, s101, v183
	v_fmamk_f32 v183, v183, 0x3a800000, v182
	v_cmp_gt_f32_e32 vcc, 0x800000, v183
	v_mul_f32_e32 v181, 0x4b800000, v183
	s_nop 1
	v_cndmask_b32_e32 v183, v183, v181, vcc
	v_rsq_f32_e32 v183, v183
	s_nop 0
	v_mul_f32_e32 v181, 0x45800000, v183
	v_cndmask_b32_e32 v184, v183, v181, vcc
	v_mov_b32_e32 v185, v184
	v_pk_mul_f32 v[216:217], v[216:217], v[184:185]
	v_pk_mul_f32 v[218:219], v[218:219], v[184:185]
	v_pk_mul_f32 v[220:221], v[220:221], v[184:185]
	v_pk_mul_f32 v[222:223], v[222:223], v[184:185]
	v_pk_mul_f32 v[224:225], v[224:225], v[184:185]
	v_pk_mul_f32 v[226:227], v[226:227], v[184:185]
	v_pk_mul_f32 v[228:229], v[228:229], v[184:185]
	v_pk_mul_f32 v[230:231], v[230:231], v[184:185]
	v_pk_fma_f32 v[194:195], v[216:217], v[160:161], v[194:195]
	v_pk_fma_f32 v[196:197], v[218:219], v[162:163], v[196:197]
	v_pk_fma_f32 v[198:199], v[220:221], v[164:165], v[198:199]
	v_pk_fma_f32 v[200:201], v[222:223], v[166:167], v[200:201]
	v_pk_fma_f32 v[202:203], v[224:225], v[168:169], v[202:203]
	v_pk_fma_f32 v[204:205], v[226:227], v[170:171], v[204:205]
	v_pk_fma_f32 v[206:207], v[228:229], v[172:173], v[206:207]
	v_pk_fma_f32 v[208:209], v[230:231], v[174:175], v[208:209]
	v_pk_mul_f32 v[252:253], v[194:195], v[194:195]
	v_pk_mul_f32 v[254:255], v[196:197], v[196:197]
	v_pk_fma_f32 v[252:253], v[198:199], v[198:199], v[252:253]
	v_pk_fma_f32 v[254:255], v[200:201], v[200:201], v[254:255]
	v_pk_fma_f32 v[252:253], v[202:203], v[202:203], v[252:253]
	v_pk_fma_f32 v[254:255], v[204:205], v[204:205], v[254:255]
	v_pk_fma_f32 v[252:253], v[206:207], v[206:207], v[252:253]
	v_pk_fma_f32 v[254:255], v[208:209], v[208:209], v[254:255]
	v_pk_add_f32 v[252:253], v[252:253], v[254:255]
	s_nop 0
	v_add_f32_e32 v183, v252, v253
	s_nop 1
	v_add_f32_dpp v183, v183, v183 quad_perm:[1,0,3,2] row_mask:0xf bank_mask:0xf bound_ctrl:1
	s_nop 1
	v_add_f32_dpp v183, v183, v183 quad_perm:[2,3,0,1] row_mask:0xf bank_mask:0xf bound_ctrl:1
	s_nop 1
	v_add_f32_dpp v183, v183, v183 row_half_mirror row_mask:0xf bank_mask:0xf bound_ctrl:1
	s_nop 1
	v_add_f32_dpp v183, v183, v183 row_mirror row_mask:0xf bank_mask:0xf bound_ctrl:1
	s_nop 1
	v_readlane_b32 s98, v183, 0
	v_readlane_b32 s99, v183, 16
	v_readlane_b32 s100, v183, 32
	v_readlane_b32 s101, v183, 48
	s_nop 1
	v_mov_b32_e32 v183, s98
	v_add_f32_e32 v183, s99, v183
	v_add_f32_e32 v183, s100, v183
	v_add_f32_e32 v183, s101, v183
	v_fmamk_f32 v183, v183, 0x3a800000, v182
	v_cmp_gt_f32_e32 vcc, 0x800000, v183
	v_mul_f32_e32 v181, 0x4b800000, v183
	s_nop 1
	v_cndmask_b32_e32 v183, v183, v181, vcc
	v_rsq_f32_e32 v183, v183
	s_nop 0
	v_mul_f32_e32 v181, 0x45800000, v183
	v_cndmask_b32_e32 v184, v183, v181, vcc
	v_mov_b32_e32 v185, v184
	v_cvt_pk_bf16_f32 v32, v194, v195
	v_cvt_pk_bf16_f32 v33, v196, v197
	v_cvt_pk_bf16_f32 v34, v198, v199
	v_cvt_pk_bf16_f32 v35, v200, v201
	v_cvt_pk_bf16_f32 v36, v202, v203
	v_cvt_pk_bf16_f32 v37, v204, v205
	v_cvt_pk_bf16_f32 v38, v206, v207
	v_cvt_pk_bf16_f32 v39, v208, v209
	v_add_u32_e32 v181, 0x3800000, v210
	global_store_dwordx4 v181, v[32:35], s[78:79]
	global_store_dwordx4 v181, v[36:39], s[78:79] offset:1024
	v_add_u32_e32 v236, 0x10000, v211
	s_mov_b64 exec, 1
	global_store_dword v236, v184, s[78:79]
	s_mov_b64 exec, -1

.LBB0_1154:
	v_readlane_b32 s0, v235, 52
	v_readlane_b32 s1, v235, 53
	s_and_b64 vcc, exec, s[0:1]
	s_waitcnt lgkmcnt(0)
	s_barrier
	v_mbcnt_lo_u32_b32 v0, -1, 0
	v_mbcnt_hi_u32_b32 v0, -1, v0
	s_cbranch_vccnz .LBB0_1174
	v_lshlrev_b32_e32 v2, 3, v0
	v_ashrrev_i32_e32 v3, 31, v2
	v_readlane_b32 s4, v235, 4
	v_lshlrev_b64 v[4:5], 1, v[2:3]
	v_lshlrev_b64 v[2:3], 2, v[2:3]
	v_readlane_b32 s14, v235, 14
	v_readlane_b32 s15, v235, 15
	v_lshl_add_u64 v[62:63], s[90:91], 0, v[2:3]
	v_readlane_b32 s5, v235, 5
	v_readlane_b32 s6, v235, 6
	v_readlane_b32 s7, v235, 7
	v_readlane_b32 s8, v235, 8
	v_readlane_b32 s9, v235, 9
	v_readlane_b32 s10, v235, 10
	v_readlane_b32 s11, v235, 11
	v_readlane_b32 s12, v235, 12
	v_readlane_b32 s13, v235, 13
	v_readlane_b32 s16, v235, 16
	v_readlane_b32 s17, v235, 17
	v_readlane_b32 s18, v235, 18
	v_readlane_b32 s19, v235, 19
	v_lshl_add_u64 v[2:3], s[14:15], 0, v[2:3]
	s_mov_b64 s[0:1], 0x1000
	v_lshl_add_u64 v[60:61], s[86:87], 0, v[4:5]
	v_lshl_add_u64 v[64:65], s[54:55], 0, v[4:5]
	v_lshl_add_u64 v[66:67], v[2:3], 0, s[0:1]
	s_mov_b32 s1, 0
	v_cmp_eq_u32_e64 s[12:13], 0, v0
	s_mov_b64 s[4:5], 0x200000
	s_mov_b64 s[6:7], 0x200800
	s_mov_b64 s[8:9], 0x400000
	s_mov_b64 s[10:11], 0x400800
	s_mov_b64 s[14:15], 0x600000
	s_mov_b64 s[16:17], 0x600800
	s_mov_b64 s[18:19], 0x800000
	s_mov_b32 s48, 0x800000
	s_mov_b64 s[20:21], 0x800800
	s_mov_b64 s[22:23], 0xa00000
	s_mov_b64 s[24:25], 0xa00800
	s_mov_b64 s[26:27], 0xc00000
	s_mov_b64 s[28:29], 0xc00800
	s_mov_b64 s[36:37], 0xe00000
	s_mov_b64 s[38:39], 0xe00800
	v_mov_b32_e32 v104, 0
	v_mov_b32_e32 v105, 0x358637bd
	v_readlane_b32 s42, v235, 61
	v_readlane_b32 s43, v235, 62
	v_mbcnt_lo_u32_b32 v176, -1, 0
	v_mbcnt_hi_u32_b32 v176, -1, v176
	v_readlane_b32 s98, v235, 49
	v_readlane_b32 s99, v235, 20
	v_readlane_b32 s100, v235, 14
	v_readlane_b32 s101, v235, 15
	s_nop 3
	s_lshr_b32 vcc_lo, s98, 3
	s_and_b32 vcc_hi, vcc_lo, 7
	s_lshr_b32 vcc_lo, vcc_lo, 3
	s_lshl_b32 vcc_lo, vcc_lo, 3
	s_add_i32 vcc_lo, vcc_lo, s99
	s_lshl_b32 s98, vcc_hi, 8
	s_add_i32 s98, s98, vcc_lo
	v_mov_b32_e32 v179, s98
	v_lshlrev_b32_e32 v177, 4, v176
	s_lshl_b32 s99, s98, 11
	v_add_u32_e32 v177, s99, v177
	v_lshlrev_b32_e32 v180, 5, v176
	v_add_u32_e32 v181, 0x1000, v180
	global_load_dwordx4 v[160:163], v181, s[100:101]
	global_load_dwordx4 v[164:167], v181, s[100:101] offset:16
	global_load_dwordx4 v[168:171], v181, s[100:101] offset:2048
	global_load_dwordx4 v[172:175], v181, s[100:101] offset:2064
	v_mov_b32_e32 v182, 0x358637bd
	v_lshlrev_b32_e32 v237, 2, v179
	v_add_u32_e32 v237, 0x10000, v237
	s_and_b32 s99, s98, 3
	s_cmp_eq_u32 s99, 0
	s_cbranch_scc1 .Lmyxupd_s_2
	s_mul_i32 s100, s99, 0x7ff800
	v_add_u32_e32 v210, s100, v177
	s_mul_i32 s100, s99, 16380
	v_add_u32_e32 v211, s100, v237
	v_add_u32_e32 v178, 0x1800000, v177
	v_add_u32_e32 v181, 0x9e00000, v177
	global_load_dwordx4 v[0:3], v178, s[78:79]
	global_load_dwordx4 v[4:7], v178, s[78:79] offset:1024
	global_load_dwordx4 v[8:11], v181, s[78:79]
	global_load_dwordx4 v[12:15], v181, s[78:79] offset:1024
	v_add_u32_e32 v178, 0x1c00000, v177
	v_add_u32_e32 v181, 0xa200000, v177
	global_load_dwordx4 v[16:19], v178, s[78:79]
	global_load_dwordx4 v[20:23], v178, s[78:79] offset:1024
	global_load_dwordx4 v[24:27], v181, s[78:79]
	global_load_dwordx4 v[28:31], v181, s[78:79] offset:1024
	v_add_u32_e32 v178, 0x2000000, v177
	v_add_u32_e32 v181, 0xa600000, v177
	global_load_dwordx4 v[32:35], v178, s[78:79]
	global_load_dwordx4 v[36:39], v178, s[78:79] offset:1024
	global_load_dwordx4 v[40:43], v181, s[78:79]
	global_load_dwordx4 v[44:47], v181, s[78:79] offset:1024
	v_add_u32_e32 v178, 0x2400000, v177
	v_add_u32_e32 v181, 0xaa00000, v177
	global_load_dwordx4 v[48:51], v178, s[78:79]
	global_load_dwordx4 v[52:55], v178, s[78:79] offset:1024
	global_load_dwordx4 v[56:59], v181, s[78:79]
	global_load_dwordx4 v[60:63], v181, s[78:79] offset:1024
	v_add_u32_e32 v178, 0x2800000, v177
	v_add_u32_e32 v181, 0xae00000, v177
	global_load_dwordx4 v[64:67], v178, s[78:79]
	global_load_dwordx4 v[68:71], v178, s[78:79] offset:1024
	global_load_dwordx4 v[72:75], v181, s[78:79]
	global_load_dwordx4 v[76:79], v181, s[78:79] offset:1024
	v_add_u32_e32 v178, 0x2c00000, v177
	v_add_u32_e32 v181, 0xb200000, v177
	global_load_dwordx4 v[80:83], v178, s[78:79]
	global_load_dwordx4 v[84:87], v178, s[78:79] offset:1024
	global_load_dwordx4 v[88:91], v181, s[78:79]
	global_load_dwordx4 v[92:95], v181, s[78:79] offset:1024
	v_add_u32_e32 v178, 0x3000000, v177
	v_add_u32_e32 v181, 0xb600000, v177
	global_load_dwordx4 v[96:99], v178, s[78:79]
	global_load_dwordx4 v[100:103], v178, s[78:79] offset:1024
	global_load_dwordx4 v[104:107], v181, s[78:79]
	global_load_dwordx4 v[108:111], v181, s[78:79] offset:1024
	v_add_u32_e32 v178, 0x3400000, v177
	v_add_u32_e32 v181, 0xba00000, v177
	global_load_dwordx4 v[112:115], v178, s[78:79]
	global_load_dwordx4 v[116:119], v178, s[78:79] offset:1024
	global_load_dwordx4 v[120:123], v181, s[78:79]
	global_load_dwordx4 v[124:127], v181, s[78:79] offset:1024
	v_add_u32_e32 v178, 0x1800000, v210
	v_add_u32_e32 v181, 0x9e00000, v210
	global_load_dwordx4 v[128:131], v178, s[78:79]
	global_load_dwordx4 v[132:135], v178, s[78:79] offset:1024
	global_load_dwordx4 v[136:139], v181, s[78:79]
	global_load_dwordx4 v[140:143], v181, s[78:79] offset:1024
	v_add_u32_e32 v178, 0x1c00000, v210
	v_add_u32_e32 v181, 0xa200000, v210
	global_load_dwordx4 v[144:147], v178, s[78:79]
	global_load_dwordx4 v[148:151], v178, s[78:79] offset:1024
	global_load_dwordx4 v[152:155], v181, s[78:79]
	global_load_dwordx4 v[156:159], v181, s[78:79] offset:1024
	s_waitcnt vmcnt(36)
	v_lshlrev_b32_e32 v194, 16, v0
	v_and_b32_e32 v195, 0xffff0000, v0
	v_lshlrev_b32_e32 v196, 16, v1
	v_and_b32_e32 v197, 0xffff0000, v1
	v_lshlrev_b32_e32 v198, 16, v2
	v_and_b32_e32 v199, 0xffff0000, v2
	v_lshlrev_b32_e32 v200, 16, v3
	v_and_b32_e32 v201, 0xffff0000, v3
	v_lshlrev_b32_e32 v202, 16, v4
	v_and_b32_e32 v203, 0xffff0000, v4
	v_lshlrev_b32_e32 v204, 16, v5
	v_and_b32_e32 v205, 0xffff0000, v5
	v_lshlrev_b32_e32 v206, 16, v6
	v_and_b32_e32 v207, 0xffff0000, v6
	v_lshlrev_b32_e32 v208, 16, v7
	v_and_b32_e32 v209, 0xffff0000, v7
	v_lshlrev_b32_e32 v216, 16, v8
	v_and_b32_e32 v217, 0xffff0000, v8
	v_lshlrev_b32_e32 v218, 16, v9
	v_and_b32_e32 v219, 0xffff0000, v9
	v_lshlrev_b32_e32 v220, 16, v10
	v_and_b32_e32 v221, 0xffff0000, v10
	v_lshlrev_b32_e32 v222, 16, v11
	v_and_b32_e32 v223, 0xffff0000, v11
	v_lshlrev_b32_e32 v224, 16, v12
	v_and_b32_e32 v225, 0xffff0000, v12
	v_lshlrev_b32_e32 v226, 16, v13
	v_and_b32_e32 v227, 0xffff0000, v13
	v_lshlrev_b32_e32 v228, 16, v14
	v_and_b32_e32 v229, 0xffff0000, v14
	v_lshlrev_b32_e32 v230, 16, v15
	v_and_b32_e32 v231, 0xffff0000, v15
	v_pk_mul_f32 v[252:253], v[216:217], v[216:217]
	v_pk_mul_f32 v[254:255], v[218:219], v[218:219]
	v_pk_fma_f32 v[252:253], v[220:221], v[220:221], v[252:253]
	v_pk_fma_f32 v[254:255], v[222:223], v[222:223], v[254:255]
	v_pk_fma_f32 v[252:253], v[224:225], v[224:225], v[252:253]
	v_pk_fma_f32 v[254:255], v[226:227], v[226:227], v[254:255]
	v_pk_fma_f32 v[252:253], v[228:229], v[228:229], v[252:253]
	v_pk_fma_f32 v[254:255], v[230:231], v[230:231], v[254:255]
	v_pk_add_f32 v[252:253], v[252:253], v[254:255]
	s_nop 0
	v_add_f32_e32 v183, v252, v253
	s_nop 1
	v_add_f32_dpp v183, v183, v183 quad_perm:[1,0,3,2] row_mask:0xf bank_mask:0xf bound_ctrl:1
	s_nop 1
	v_add_f32_dpp v183, v183, v183 quad_perm:[2,3,0,1] row_mask:0xf bank_mask:0xf bound_ctrl:1
	s_nop 1
	v_add_f32_dpp v183, v183, v183 row_half_mirror row_mask:0xf bank_mask:0xf bound_ctrl:1
	s_nop 1
	v_add_f32_dpp v183, v183, v183 row_mirror row_mask:0xf bank_mask:0xf bound_ctrl:1
	s_nop 1
	v_readlane_b32 s98, v183, 0
	v_readlane_b32 s99, v183, 16
	v_readlane_b32 s100, v183, 32
	v_readlane_b32 s101, v183, 48
	s_nop 1
	v_mov_b32_e32 v183, s98
	v_add_f32_e32 v183, s99, v183
	v_add_f32_e32 v183, s100, v183
	v_add_f32_e32 v183, s101, v183
	v_fmamk_f32 v183, v183, 0x3a800000, v182
	v_cmp_gt_f32_e32 vcc, 0x800000, v183
	v_mul_f32_e32 v181, 0x4b800000, v183
	s_nop 1
	v_cndmask_b32_e32 v183, v183, v181, vcc
	v_rsq_f32_e32 v183, v183
	s_nop 0
	v_mul_f32_e32 v181, 0x45800000, v183
	v_cndmask_b32_e32 v184, v183, v181, vcc
	v_mov_b32_e32 v185, v184
	v_pk_mul_f32 v[216:217], v[216:217], v[184:185]
	v_pk_mul_f32 v[218:219], v[218:219], v[184:185]
	v_pk_mul_f32 v[220:221], v[220:221], v[184:185]
	v_pk_mul_f32 v[222:223], v[222:223], v[184:185]
	v_pk_mul_f32 v[224:225], v[224:225], v[184:185]
	v_pk_mul_f32 v[226:227], v[226:227], v[184:185]
	v_pk_mul_f32 v[228:229], v[228:229], v[184:185]
	v_pk_mul_f32 v[230:231], v[230:231], v[184:185]
	v_pk_fma_f32 v[194:195], v[216:217], v[160:161], v[194:195]
	v_pk_fma_f32 v[196:197], v[218:219], v[162:163], v[196:197]
	v_pk_fma_f32 v[198:199], v[220:221], v[164:165], v[198:199]
	v_pk_fma_f32 v[200:201], v[222:223], v[166:167], v[200:201]
	v_pk_fma_f32 v[202:203], v[224:225], v[168:169], v[202:203]
	v_pk_fma_f32 v[204:205], v[226:227], v[170:171], v[204:205]
	v_pk_fma_f32 v[206:207], v[228:229], v[172:173], v[206:207]
	v_pk_fma_f32 v[208:209], v[230:231], v[174:175], v[208:209]
	v_pk_mul_f32 v[252:253], v[194:195], v[194:195]
	v_pk_mul_f32 v[254:255], v[196:197], v[196:197]
	v_pk_fma_f32 v[252:253], v[198:199], v[198:199], v[252:253]
	v_pk_fma_f32 v[254:255], v[200:201], v[200:201], v[254:255]
	v_pk_fma_f32 v[252:253], v[202:203], v[202:203], v[252:253]
	v_pk_fma_f32 v[254:255], v[204:205], v[204:205], v[254:255]
	v_pk_fma_f32 v[252:253], v[206:207], v[206:207], v[252:253]
	v_pk_fma_f32 v[254:255], v[208:209], v[208:209], v[254:255]
	v_pk_add_f32 v[252:253], v[252:253], v[254:255]
	s_nop 0
	v_add_f32_e32 v183, v252, v253
	s_nop 1
	v_add_f32_dpp v183, v183, v183 quad_perm:[1,0,3,2] row_mask:0xf bank_mask:0xf bound_ctrl:1
	s_nop 1
	v_add_f32_dpp v183, v183, v183 quad_perm:[2,3,0,1] row_mask:0xf bank_mask:0xf bound_ctrl:1
	s_nop 1
	v_add_f32_dpp v183, v183, v183 row_half_mirror row_mask:0xf bank_mask:0xf bound_ctrl:1
	s_nop 1
	v_add_f32_dpp v183, v183, v183 row_mirror row_mask:0xf bank_mask:0xf bound_ctrl:1
	s_nop 1
	v_readlane_b32 s98, v183, 0
	v_readlane_b32 s99, v183, 16
	v_readlane_b32 s100, v183, 32
	v_readlane_b32 s101, v183, 48
	s_nop 1
	v_mov_b32_e32 v183, s98
	v_add_f32_e32 v183, s99, v183
	v_add_f32_e32 v183, s100, v183
	v_add_f32_e32 v183, s101, v183
	v_fmamk_f32 v183, v183, 0x3a800000, v182
	v_cmp_gt_f32_e32 vcc, 0x800000, v183
	v_mul_f32_e32 v181, 0x4b800000, v183
	s_nop 1
	v_cndmask_b32_e32 v183, v183, v181, vcc
	v_rsq_f32_e32 v183, v183
	s_nop 0
	v_mul_f32_e32 v181, 0x45800000, v183
	v_cndmask_b32_e32 v184, v183, v181, vcc
	v_mov_b32_e32 v185, v184
	v_cvt_pk_bf16_f32 v0, v194, v195
	v_cvt_pk_bf16_f32 v1, v196, v197
	v_cvt_pk_bf16_f32 v2, v198, v199
	v_cvt_pk_bf16_f32 v3, v200, v201
	v_cvt_pk_bf16_f32 v4, v202, v203
	v_cvt_pk_bf16_f32 v5, v204, v205
	v_cvt_pk_bf16_f32 v6, v206, v207
	v_cvt_pk_bf16_f32 v7, v208, v209
	v_add_u32_e32 v181, 0x1800000, v177
	global_store_dwordx4 v181, v[0:3], s[78:79]
	global_store_dwordx4 v181, v[4:7], s[78:79] offset:1024
	v_add_u32_e32 v236, 0x0, v237
	s_mov_b64 exec, 1
	global_store_dword v236, v184, s[78:79]
	s_mov_b64 exec, -1
	s_waitcnt vmcnt(32)
	v_lshlrev_b32_e32 v194, 16, v16
	v_and_b32_e32 v195, 0xffff0000, v16
	v_lshlrev_b32_e32 v196, 16, v17
	v_and_b32_e32 v197, 0xffff0000, v17
	v_lshlrev_b32_e32 v198, 16, v18
	v_and_b32_e32 v199, 0xffff0000, v18
	v_lshlrev_b32_e32 v200, 16, v19
	v_and_b32_e32 v201, 0xffff0000, v19
	v_lshlrev_b32_e32 v202, 16, v20
	v_and_b32_e32 v203, 0xffff0000, v20
	v_lshlrev_b32_e32 v204, 16, v21
	v_and_b32_e32 v205, 0xffff0000, v21
	v_lshlrev_b32_e32 v206, 16, v22
	v_and_b32_e32 v207, 0xffff0000, v22
	v_lshlrev_b32_e32 v208, 16, v23
	v_and_b32_e32 v209, 0xffff0000, v23
	v_lshlrev_b32_e32 v216, 16, v24
	v_and_b32_e32 v217, 0xffff0000, v24
	v_lshlrev_b32_e32 v218, 16, v25
	v_and_b32_e32 v219, 0xffff0000, v25
	v_lshlrev_b32_e32 v220, 16, v26
	v_and_b32_e32 v221, 0xffff0000, v26
	v_lshlrev_b32_e32 v222, 16, v27
	v_and_b32_e32 v223, 0xffff0000, v27
	v_lshlrev_b32_e32 v224, 16, v28
	v_and_b32_e32 v225, 0xffff0000, v28
	v_lshlrev_b32_e32 v226, 16, v29
	v_and_b32_e32 v227, 0xffff0000, v29
	v_lshlrev_b32_e32 v228, 16, v30
	v_and_b32_e32 v229, 0xffff0000, v30
	v_lshlrev_b32_e32 v230, 16, v31
	v_and_b32_e32 v231, 0xffff0000, v31
	v_pk_mul_f32 v[252:253], v[216:217], v[216:217]
	v_pk_mul_f32 v[254:255], v[218:219], v[218:219]
	v_pk_fma_f32 v[252:253], v[220:221], v[220:221], v[252:253]
	v_pk_fma_f32 v[254:255], v[222:223], v[222:223], v[254:255]
	v_pk_fma_f32 v[252:253], v[224:225], v[224:225], v[252:253]
	v_pk_fma_f32 v[254:255], v[226:227], v[226:227], v[254:255]
	v_pk_fma_f32 v[252:253], v[228:229], v[228:229], v[252:253]
	v_pk_fma_f32 v[254:255], v[230:231], v[230:231], v[254:255]
	v_pk_add_f32 v[252:253], v[252:253], v[254:255]
	s_nop 0
	v_add_f32_e32 v183, v252, v253
	s_nop 1
	v_add_f32_dpp v183, v183, v183 quad_perm:[1,0,3,2] row_mask:0xf bank_mask:0xf bound_ctrl:1
	s_nop 1
	v_add_f32_dpp v183, v183, v183 quad_perm:[2,3,0,1] row_mask:0xf bank_mask:0xf bound_ctrl:1
	s_nop 1
	v_add_f32_dpp v183, v183, v183 row_half_mirror row_mask:0xf bank_mask:0xf bound_ctrl:1
	s_nop 1
	v_add_f32_dpp v183, v183, v183 row_mirror row_mask:0xf bank_mask:0xf bound_ctrl:1
	s_nop 1
	v_readlane_b32 s98, v183, 0
	v_readlane_b32 s99, v183, 16
	v_readlane_b32 s100, v183, 32
	v_readlane_b32 s101, v183, 48
	s_nop 1
	v_mov_b32_e32 v183, s98
	v_add_f32_e32 v183, s99, v183
	v_add_f32_e32 v183, s100, v183
	v_add_f32_e32 v183, s101, v183
	v_fmamk_f32 v183, v183, 0x3a800000, v182
	v_cmp_gt_f32_e32 vcc, 0x800000, v183
	v_mul_f32_e32 v181, 0x4b800000, v183
	s_nop 1
	v_cndmask_b32_e32 v183, v183, v181, vcc
	v_rsq_f32_e32 v183, v183
	s_nop 0
	v_mul_f32_e32 v181, 0x45800000, v183
	v_cndmask_b32_e32 v184, v183, v181, vcc
	v_mov_b32_e32 v185, v184
	v_pk_mul_f32 v[216:217], v[216:217], v[184:185]
	v_pk_mul_f32 v[218:219], v[218:219], v[184:185]
	v_pk_mul_f32 v[220:221], v[220:221], v[184:185]
	v_pk_mul_f32 v[222:223], v[222:223], v[184:185]
	v_pk_mul_f32 v[224:225], v[224:225], v[184:185]
	v_pk_mul_f32 v[226:227], v[226:227], v[184:185]
	v_pk_mul_f32 v[228:229], v[228:229], v[184:185]
	v_pk_mul_f32 v[230:231], v[230:231], v[184:185]
	v_pk_fma_f32 v[194:195], v[216:217], v[160:161], v[194:195]
	v_pk_fma_f32 v[196:197], v[218:219], v[162:163], v[196:197]
	v_pk_fma_f32 v[198:199], v[220:221], v[164:165], v[198:199]
	v_pk_fma_f32 v[200:201], v[222:223], v[166:167], v[200:201]
	v_pk_fma_f32 v[202:203], v[224:225], v[168:169], v[202:203]
	v_pk_fma_f32 v[204:205], v[226:227], v[170:171], v[204:205]
	v_pk_fma_f32 v[206:207], v[228:229], v[172:173], v[206:207]
	v_pk_fma_f32 v[208:209], v[230:231], v[174:175], v[208:209]
	v_pk_mul_f32 v[252:253], v[194:195], v[194:195]
	v_pk_mul_f32 v[254:255], v[196:197], v[196:197]
	v_pk_fma_f32 v[252:253], v[198:199], v[198:199], v[252:253]
	v_pk_fma_f32 v[254:255], v[200:201], v[200:201], v[254:255]
	v_pk_fma_f32 v[252:253], v[202:203], v[202:203], v[252:253]
	v_pk_fma_f32 v[254:255], v[204:205], v[204:205], v[254:255]
	v_pk_fma_f32 v[252:253], v[206:207], v[206:207], v[252:253]
	v_pk_fma_f32 v[254:255], v[208:209], v[208:209], v[254:255]
	v_pk_add_f32 v[252:253], v[252:253], v[254:255]
	s_nop 0
	v_add_f32_e32 v183, v252, v253
	s_nop 1
	v_add_f32_dpp v183, v183, v183 quad_perm:[1,0,3,2] row_mask:0xf bank_mask:0xf bound_ctrl:1
	s_nop 1
	v_add_f32_dpp v183, v183, v183 quad_perm:[2,3,0,1] row_mask:0xf bank_mask:0xf bound_ctrl:1
	s_nop 1
	v_add_f32_dpp v183, v183, v183 row_half_mirror row_mask:0xf bank_mask:0xf bound_ctrl:1
	s_nop 1
	v_add_f32_dpp v183, v183, v183 row_mirror row_mask:0xf bank_mask:0xf bound_ctrl:1
	s_nop 1
	v_readlane_b32 s98, v183, 0
	v_readlane_b32 s99, v183, 16
	v_readlane_b32 s100, v183, 32
	v_readlane_b32 s101, v183, 48
	s_nop 1
	v_mov_b32_e32 v183, s98
	v_add_f32_e32 v183, s99, v183
	v_add_f32_e32 v183, s100, v183
	v_add_f32_e32 v183, s101, v183
	v_fmamk_f32 v183, v183, 0x3a800000, v182
	v_cmp_gt_f32_e32 vcc, 0x800000, v183
	v_mul_f32_e32 v181, 0x4b800000, v183
	s_nop 1
	v_cndmask_b32_e32 v183, v183, v181, vcc
	v_rsq_f32_e32 v183, v183
	s_nop 0
	v_mul_f32_e32 v181, 0x45800000, v183
	v_cndmask_b32_e32 v184, v183, v181, vcc
	v_mov_b32_e32 v185, v184
	v_cvt_pk_bf16_f32 v16, v194, v195
	v_cvt_pk_bf16_f32 v17, v196, v197
	v_cvt_pk_bf16_f32 v18, v198, v199
	v_cvt_pk_bf16_f32 v19, v200, v201
	v_cvt_pk_bf16_f32 v20, v202, v203
	v_cvt_pk_bf16_f32 v21, v204, v205
	v_cvt_pk_bf16_f32 v22, v206, v207
	v_cvt_pk_bf16_f32 v23, v208, v209
	v_add_u32_e32 v181, 0x1c00000, v177
	global_store_dwordx4 v181, v[16:19], s[78:79]
	global_store_dwordx4 v181, v[20:23], s[78:79] offset:1024
	v_add_u32_e32 v236, 0x2000, v237
	s_mov_b64 exec, 1
	global_store_dword v236, v184, s[78:79]
	s_mov_b64 exec, -1
	s_waitcnt vmcnt(28)
	v_lshlrev_b32_e32 v194, 16, v32
	v_and_b32_e32 v195, 0xffff0000, v32
	v_lshlrev_b32_e32 v196, 16, v33
	v_and_b32_e32 v197, 0xffff0000, v33
	v_lshlrev_b32_e32 v198, 16, v34
	v_and_b32_e32 v199, 0xffff0000, v34
	v_lshlrev_b32_e32 v200, 16, v35
	v_and_b32_e32 v201, 0xffff0000, v35
	v_lshlrev_b32_e32 v202, 16, v36
	v_and_b32_e32 v203, 0xffff0000, v36
	v_lshlrev_b32_e32 v204, 16, v37
	v_and_b32_e32 v205, 0xffff0000, v37
	v_lshlrev_b32_e32 v206, 16, v38
	v_and_b32_e32 v207, 0xffff0000, v38
	v_lshlrev_b32_e32 v208, 16, v39
	v_and_b32_e32 v209, 0xffff0000, v39
	v_lshlrev_b32_e32 v216, 16, v40
	v_and_b32_e32 v217, 0xffff0000, v40
	v_lshlrev_b32_e32 v218, 16, v41
	v_and_b32_e32 v219, 0xffff0000, v41
	v_lshlrev_b32_e32 v220, 16, v42
	v_and_b32_e32 v221, 0xffff0000, v42
	v_lshlrev_b32_e32 v222, 16, v43
	v_and_b32_e32 v223, 0xffff0000, v43
	v_lshlrev_b32_e32 v224, 16, v44
	v_and_b32_e32 v225, 0xffff0000, v44
	v_lshlrev_b32_e32 v226, 16, v45
	v_and_b32_e32 v227, 0xffff0000, v45
	v_lshlrev_b32_e32 v228, 16, v46
	v_and_b32_e32 v229, 0xffff0000, v46
	v_lshlrev_b32_e32 v230, 16, v47
	v_and_b32_e32 v231, 0xffff0000, v47
	v_pk_mul_f32 v[252:253], v[216:217], v[216:217]
	v_pk_mul_f32 v[254:255], v[218:219], v[218:219]
	v_pk_fma_f32 v[252:253], v[220:221], v[220:221], v[252:253]
	v_pk_fma_f32 v[254:255], v[222:223], v[222:223], v[254:255]
	v_pk_fma_f32 v[252:253], v[224:225], v[224:225], v[252:253]
	v_pk_fma_f32 v[254:255], v[226:227], v[226:227], v[254:255]
	v_pk_fma_f32 v[252:253], v[228:229], v[228:229], v[252:253]
	v_pk_fma_f32 v[254:255], v[230:231], v[230:231], v[254:255]
	v_pk_add_f32 v[252:253], v[252:253], v[254:255]
	s_nop 0
	v_add_f32_e32 v183, v252, v253
	s_nop 1
	v_add_f32_dpp v183, v183, v183 quad_perm:[1,0,3,2] row_mask:0xf bank_mask:0xf bound_ctrl:1
	s_nop 1
	v_add_f32_dpp v183, v183, v183 quad_perm:[2,3,0,1] row_mask:0xf bank_mask:0xf bound_ctrl:1
	s_nop 1
	v_add_f32_dpp v183, v183, v183 row_half_mirror row_mask:0xf bank_mask:0xf bound_ctrl:1
	s_nop 1
	v_add_f32_dpp v183, v183, v183 row_mirror row_mask:0xf bank_mask:0xf bound_ctrl:1
	s_nop 1
	v_readlane_b32 s98, v183, 0
	v_readlane_b32 s99, v183, 16
	v_readlane_b32 s100, v183, 32
	v_readlane_b32 s101, v183, 48
	s_nop 1
	v_mov_b32_e32 v183, s98
	v_add_f32_e32 v183, s99, v183
	v_add_f32_e32 v183, s100, v183
	v_add_f32_e32 v183, s101, v183
	v_fmamk_f32 v183, v183, 0x3a800000, v182
	v_cmp_gt_f32_e32 vcc, 0x800000, v183
	v_mul_f32_e32 v181, 0x4b800000, v183
	s_nop 1
	v_cndmask_b32_e32 v183, v183, v181, vcc
	v_rsq_f32_e32 v183, v183
	s_nop 0
	v_mul_f32_e32 v181, 0x45800000, v183
	v_cndmask_b32_e32 v184, v183, v181, vcc
	v_mov_b32_e32 v185, v184
	v_pk_mul_f32 v[216:217], v[216:217], v[184:185]
	v_pk_mul_f32 v[218:219], v[218:219], v[184:185]
	v_pk_mul_f32 v[220:221], v[220:221], v[184:185]
	v_pk_mul_f32 v[222:223], v[222:223], v[184:185]
	v_pk_mul_f32 v[224:225], v[224:225], v[184:185]
	v_pk_mul_f32 v[226:227], v[226:227], v[184:185]
	v_pk_mul_f32 v[228:229], v[228:229], v[184:185]
	v_pk_mul_f32 v[230:231], v[230:231], v[184:185]
	v_pk_fma_f32 v[194:195], v[216:217], v[160:161], v[194:195]
	v_pk_fma_f32 v[196:197], v[218:219], v[162:163], v[196:197]
	v_pk_fma_f32 v[198:199], v[220:221], v[164:165], v[198:199]
	v_pk_fma_f32 v[200:201], v[222:223], v[166:167], v[200:201]
	v_pk_fma_f32 v[202:203], v[224:225], v[168:169], v[202:203]
	v_pk_fma_f32 v[204:205], v[226:227], v[170:171], v[204:205]
	v_pk_fma_f32 v[206:207], v[228:229], v[172:173], v[206:207]
	v_pk_fma_f32 v[208:209], v[230:231], v[174:175], v[208:209]
	v_pk_mul_f32 v[252:253], v[194:195], v[194:195]
	v_pk_mul_f32 v[254:255], v[196:197], v[196:197]
	v_pk_fma_f32 v[252:253], v[198:199], v[198:199], v[252:253]
	v_pk_fma_f32 v[254:255], v[200:201], v[200:201], v[254:255]
	v_pk_fma_f32 v[252:253], v[202:203], v[202:203], v[252:253]
	v_pk_fma_f32 v[254:255], v[204:205], v[204:205], v[254:255]
	v_pk_fma_f32 v[252:253], v[206:207], v[206:207], v[252:253]
	v_pk_fma_f32 v[254:255], v[208:209], v[208:209], v[254:255]
	v_pk_add_f32 v[252:253], v[252:253], v[254:255]
	s_nop 0
	v_add_f32_e32 v183, v252, v253
	s_nop 1
	v_add_f32_dpp v183, v183, v183 quad_perm:[1,0,3,2] row_mask:0xf bank_mask:0xf bound_ctrl:1
	s_nop 1
	v_add_f32_dpp v183, v183, v183 quad_perm:[2,3,0,1] row_mask:0xf bank_mask:0xf bound_ctrl:1
	s_nop 1
	v_add_f32_dpp v183, v183, v183 row_half_mirror row_mask:0xf bank_mask:0xf bound_ctrl:1
	s_nop 1
	v_add_f32_dpp v183, v183, v183 row_mirror row_mask:0xf bank_mask:0xf bound_ctrl:1
	s_nop 1
	v_readlane_b32 s98, v183, 0
	v_readlane_b32 s99, v183, 16
	v_readlane_b32 s100, v183, 32
	v_readlane_b32 s101, v183, 48
	s_nop 1
	v_mov_b32_e32 v183, s98
	v_add_f32_e32 v183, s99, v183
	v_add_f32_e32 v183, s100, v183
	v_add_f32_e32 v183, s101, v183
	v_fmamk_f32 v183, v183, 0x3a800000, v182
	v_cmp_gt_f32_e32 vcc, 0x800000, v183
	v_mul_f32_e32 v181, 0x4b800000, v183
	s_nop 1
	v_cndmask_b32_e32 v183, v183, v181, vcc
	v_rsq_f32_e32 v183, v183
	s_nop 0
	v_mul_f32_e32 v181, 0x45800000, v183
	v_cndmask_b32_e32 v184, v183, v181, vcc
	v_mov_b32_e32 v185, v184
	v_cvt_pk_bf16_f32 v32, v194, v195
	v_cvt_pk_bf16_f32 v33, v196, v197
	v_cvt_pk_bf16_f32 v34, v198, v199
	v_cvt_pk_bf16_f32 v35, v200, v201
	v_cvt_pk_bf16_f32 v36, v202, v203
	v_cvt_pk_bf16_f32 v37, v204, v205
	v_cvt_pk_bf16_f32 v38, v206, v207
	v_cvt_pk_bf16_f32 v39, v208, v209
	v_add_u32_e32 v181, 0x2000000, v177
	global_store_dwordx4 v181, v[32:35], s[78:79]
	global_store_dwordx4 v181, v[36:39], s[78:79] offset:1024
	v_add_u32_e32 v236, 0x4000, v237
	s_mov_b64 exec, 1
	global_store_dword v236, v184, s[78:79]
	s_mov_b64 exec, -1
	s_waitcnt vmcnt(24)
	v_lshlrev_b32_e32 v194, 16, v48
	v_and_b32_e32 v195, 0xffff0000, v48
	v_lshlrev_b32_e32 v196, 16, v49
	v_and_b32_e32 v197, 0xffff0000, v49
	v_lshlrev_b32_e32 v198, 16, v50
	v_and_b32_e32 v199, 0xffff0000, v50
	v_lshlrev_b32_e32 v200, 16, v51
	v_and_b32_e32 v201, 0xffff0000, v51
	v_lshlrev_b32_e32 v202, 16, v52
	v_and_b32_e32 v203, 0xffff0000, v52
	v_lshlrev_b32_e32 v204, 16, v53
	v_and_b32_e32 v205, 0xffff0000, v53
	v_lshlrev_b32_e32 v206, 16, v54
	v_and_b32_e32 v207, 0xffff0000, v54
	v_lshlrev_b32_e32 v208, 16, v55
	v_and_b32_e32 v209, 0xffff0000, v55
	v_lshlrev_b32_e32 v216, 16, v56
	v_and_b32_e32 v217, 0xffff0000, v56
	v_lshlrev_b32_e32 v218, 16, v57
	v_and_b32_e32 v219, 0xffff0000, v57
	v_lshlrev_b32_e32 v220, 16, v58
	v_and_b32_e32 v221, 0xffff0000, v58
	v_lshlrev_b32_e32 v222, 16, v59
	v_and_b32_e32 v223, 0xffff0000, v59
	v_lshlrev_b32_e32 v224, 16, v60
	v_and_b32_e32 v225, 0xffff0000, v60
	v_lshlrev_b32_e32 v226, 16, v61
	v_and_b32_e32 v227, 0xffff0000, v61
	v_lshlrev_b32_e32 v228, 16, v62
	v_and_b32_e32 v229, 0xffff0000, v62
	v_lshlrev_b32_e32 v230, 16, v63
	v_and_b32_e32 v231, 0xffff0000, v63
	v_pk_mul_f32 v[252:253], v[216:217], v[216:217]
	v_pk_mul_f32 v[254:255], v[218:219], v[218:219]
	v_pk_fma_f32 v[252:253], v[220:221], v[220:221], v[252:253]
	v_pk_fma_f32 v[254:255], v[222:223], v[222:223], v[254:255]
	v_pk_fma_f32 v[252:253], v[224:225], v[224:225], v[252:253]
	v_pk_fma_f32 v[254:255], v[226:227], v[226:227], v[254:255]
	v_pk_fma_f32 v[252:253], v[228:229], v[228:229], v[252:253]
	v_pk_fma_f32 v[254:255], v[230:231], v[230:231], v[254:255]
	v_pk_add_f32 v[252:253], v[252:253], v[254:255]
	s_nop 0
	v_add_f32_e32 v183, v252, v253
	s_nop 1
	v_add_f32_dpp v183, v183, v183 quad_perm:[1,0,3,2] row_mask:0xf bank_mask:0xf bound_ctrl:1
	s_nop 1
	v_add_f32_dpp v183, v183, v183 quad_perm:[2,3,0,1] row_mask:0xf bank_mask:0xf bound_ctrl:1
	s_nop 1
	v_add_f32_dpp v183, v183, v183 row_half_mirror row_mask:0xf bank_mask:0xf bound_ctrl:1
	s_nop 1
	v_add_f32_dpp v183, v183, v183 row_mirror row_mask:0xf bank_mask:0xf bound_ctrl:1
	s_nop 1
	v_readlane_b32 s98, v183, 0
	v_readlane_b32 s99, v183, 16
	v_readlane_b32 s100, v183, 32
	v_readlane_b32 s101, v183, 48
	s_nop 1
	v_mov_b32_e32 v183, s98
	v_add_f32_e32 v183, s99, v183
	v_add_f32_e32 v183, s100, v183
	v_add_f32_e32 v183, s101, v183
	v_fmamk_f32 v183, v183, 0x3a800000, v182
	v_cmp_gt_f32_e32 vcc, 0x800000, v183
	v_mul_f32_e32 v181, 0x4b800000, v183
	s_nop 1
	v_cndmask_b32_e32 v183, v183, v181, vcc
	v_rsq_f32_e32 v183, v183
	s_nop 0
	v_mul_f32_e32 v181, 0x45800000, v183
	v_cndmask_b32_e32 v184, v183, v181, vcc
	v_mov_b32_e32 v185, v184
	v_pk_mul_f32 v[216:217], v[216:217], v[184:185]
	v_pk_mul_f32 v[218:219], v[218:219], v[184:185]
	v_pk_mul_f32 v[220:221], v[220:221], v[184:185]
	v_pk_mul_f32 v[222:223], v[222:223], v[184:185]
	v_pk_mul_f32 v[224:225], v[224:225], v[184:185]
	v_pk_mul_f32 v[226:227], v[226:227], v[184:185]
	v_pk_mul_f32 v[228:229], v[228:229], v[184:185]
	v_pk_mul_f32 v[230:231], v[230:231], v[184:185]
	v_pk_fma_f32 v[194:195], v[216:217], v[160:161], v[194:195]
	v_pk_fma_f32 v[196:197], v[218:219], v[162:163], v[196:197]
	v_pk_fma_f32 v[198:199], v[220:221], v[164:165], v[198:199]
	v_pk_fma_f32 v[200:201], v[222:223], v[166:167], v[200:201]
	v_pk_fma_f32 v[202:203], v[224:225], v[168:169], v[202:203]
	v_pk_fma_f32 v[204:205], v[226:227], v[170:171], v[204:205]
	v_pk_fma_f32 v[206:207], v[228:229], v[172:173], v[206:207]
	v_pk_fma_f32 v[208:209], v[230:231], v[174:175], v[208:209]
	v_pk_mul_f32 v[252:253], v[194:195], v[194:195]
	v_pk_mul_f32 v[254:255], v[196:197], v[196:197]
	v_pk_fma_f32 v[252:253], v[198:199], v[198:199], v[252:253]
	v_pk_fma_f32 v[254:255], v[200:201], v[200:201], v[254:255]
	v_pk_fma_f32 v[252:253], v[202:203], v[202:203], v[252:253]
	v_pk_fma_f32 v[254:255], v[204:205], v[204:205], v[254:255]
	v_pk_fma_f32 v[252:253], v[206:207], v[206:207], v[252:253]
	v_pk_fma_f32 v[254:255], v[208:209], v[208:209], v[254:255]
	v_pk_add_f32 v[252:253], v[252:253], v[254:255]
	s_nop 0
	v_add_f32_e32 v183, v252, v253
	s_nop 1
	v_add_f32_dpp v183, v183, v183 quad_perm:[1,0,3,2] row_mask:0xf bank_mask:0xf bound_ctrl:1
	s_nop 1
	v_add_f32_dpp v183, v183, v183 quad_perm:[2,3,0,1] row_mask:0xf bank_mask:0xf bound_ctrl:1
	s_nop 1
	v_add_f32_dpp v183, v183, v183 row_half_mirror row_mask:0xf bank_mask:0xf bound_ctrl:1
	s_nop 1
	v_add_f32_dpp v183, v183, v183 row_mirror row_mask:0xf bank_mask:0xf bound_ctrl:1
	s_nop 1
	v_readlane_b32 s98, v183, 0
	v_readlane_b32 s99, v183, 16
	v_readlane_b32 s100, v183, 32
	v_readlane_b32 s101, v183, 48
	s_nop 1
	v_mov_b32_e32 v183, s98
	v_add_f32_e32 v183, s99, v183
	v_add_f32_e32 v183, s100, v183
	v_add_f32_e32 v183, s101, v183
	v_fmamk_f32 v183, v183, 0x3a800000, v182
	v_cmp_gt_f32_e32 vcc, 0x800000, v183
	v_mul_f32_e32 v181, 0x4b800000, v183
	s_nop 1
	v_cndmask_b32_e32 v183, v183, v181, vcc
	v_rsq_f32_e32 v183, v183
	s_nop 0
	v_mul_f32_e32 v181, 0x45800000, v183
	v_cndmask_b32_e32 v184, v183, v181, vcc
	v_mov_b32_e32 v185, v184
	v_cvt_pk_bf16_f32 v48, v194, v195
	v_cvt_pk_bf16_f32 v49, v196, v197
	v_cvt_pk_bf16_f32 v50, v198, v199
	v_cvt_pk_bf16_f32 v51, v200, v201
	v_cvt_pk_bf16_f32 v52, v202, v203
	v_cvt_pk_bf16_f32 v53, v204, v205
	v_cvt_pk_bf16_f32 v54, v206, v207
	v_cvt_pk_bf16_f32 v55, v208, v209
	v_add_u32_e32 v181, 0x2400000, v177
	global_store_dwordx4 v181, v[48:51], s[78:79]
	global_store_dwordx4 v181, v[52:55], s[78:79] offset:1024
	v_add_u32_e32 v236, 0x6000, v237
	s_mov_b64 exec, 1
	global_store_dword v236, v184, s[78:79]
	s_mov_b64 exec, -1
	s_waitcnt vmcnt(20)
	v_lshlrev_b32_e32 v194, 16, v64
	v_and_b32_e32 v195, 0xffff0000, v64
	v_lshlrev_b32_e32 v196, 16, v65
	v_and_b32_e32 v197, 0xffff0000, v65
	v_lshlrev_b32_e32 v198, 16, v66
	v_and_b32_e32 v199, 0xffff0000, v66
	v_lshlrev_b32_e32 v200, 16, v67
	v_and_b32_e32 v201, 0xffff0000, v67
	v_lshlrev_b32_e32 v202, 16, v68
	v_and_b32_e32 v203, 0xffff0000, v68
	v_lshlrev_b32_e32 v204, 16, v69
	v_and_b32_e32 v205, 0xffff0000, v69
	v_lshlrev_b32_e32 v206, 16, v70
	v_and_b32_e32 v207, 0xffff0000, v70
	v_lshlrev_b32_e32 v208, 16, v71
	v_and_b32_e32 v209, 0xffff0000, v71
	v_lshlrev_b32_e32 v216, 16, v72
	v_and_b32_e32 v217, 0xffff0000, v72
	v_lshlrev_b32_e32 v218, 16, v73
	v_and_b32_e32 v219, 0xffff0000, v73
	v_lshlrev_b32_e32 v220, 16, v74
	v_and_b32_e32 v221, 0xffff0000, v74
	v_lshlrev_b32_e32 v222, 16, v75
	v_and_b32_e32 v223, 0xffff0000, v75
	v_lshlrev_b32_e32 v224, 16, v76
	v_and_b32_e32 v225, 0xffff0000, v76
	v_lshlrev_b32_e32 v226, 16, v77
	v_and_b32_e32 v227, 0xffff0000, v77
	v_lshlrev_b32_e32 v228, 16, v78
	v_and_b32_e32 v229, 0xffff0000, v78
	v_lshlrev_b32_e32 v230, 16, v79
	v_and_b32_e32 v231, 0xffff0000, v79
	v_pk_mul_f32 v[252:253], v[216:217], v[216:217]
	v_pk_mul_f32 v[254:255], v[218:219], v[218:219]
	v_pk_fma_f32 v[252:253], v[220:221], v[220:221], v[252:253]
	v_pk_fma_f32 v[254:255], v[222:223], v[222:223], v[254:255]
	v_pk_fma_f32 v[252:253], v[224:225], v[224:225], v[252:253]
	v_pk_fma_f32 v[254:255], v[226:227], v[226:227], v[254:255]
	v_pk_fma_f32 v[252:253], v[228:229], v[228:229], v[252:253]
	v_pk_fma_f32 v[254:255], v[230:231], v[230:231], v[254:255]
	v_pk_add_f32 v[252:253], v[252:253], v[254:255]
	s_nop 0
	v_add_f32_e32 v183, v252, v253
	s_nop 1
	v_add_f32_dpp v183, v183, v183 quad_perm:[1,0,3,2] row_mask:0xf bank_mask:0xf bound_ctrl:1
	s_nop 1
	v_add_f32_dpp v183, v183, v183 quad_perm:[2,3,0,1] row_mask:0xf bank_mask:0xf bound_ctrl:1
	s_nop 1
	v_add_f32_dpp v183, v183, v183 row_half_mirror row_mask:0xf bank_mask:0xf bound_ctrl:1
	s_nop 1
	v_add_f32_dpp v183, v183, v183 row_mirror row_mask:0xf bank_mask:0xf bound_ctrl:1
	s_nop 1
	v_readlane_b32 s98, v183, 0
	v_readlane_b32 s99, v183, 16
	v_readlane_b32 s100, v183, 32
	v_readlane_b32 s101, v183, 48
	s_nop 1
	v_mov_b32_e32 v183, s98
	v_add_f32_e32 v183, s99, v183
	v_add_f32_e32 v183, s100, v183
	v_add_f32_e32 v183, s101, v183
	v_fmamk_f32 v183, v183, 0x3a800000, v182
	v_cmp_gt_f32_e32 vcc, 0x800000, v183
	v_mul_f32_e32 v181, 0x4b800000, v183
	s_nop 1
	v_cndmask_b32_e32 v183, v183, v181, vcc
	v_rsq_f32_e32 v183, v183
	s_nop 0
	v_mul_f32_e32 v181, 0x45800000, v183
	v_cndmask_b32_e32 v184, v183, v181, vcc
	v_mov_b32_e32 v185, v184
	v_pk_mul_f32 v[216:217], v[216:217], v[184:185]
	v_pk_mul_f32 v[218:219], v[218:219], v[184:185]
	v_pk_mul_f32 v[220:221], v[220:221], v[184:185]
	v_pk_mul_f32 v[222:223], v[222:223], v[184:185]
	v_pk_mul_f32 v[224:225], v[224:225], v[184:185]
	v_pk_mul_f32 v[226:227], v[226:227], v[184:185]
	v_pk_mul_f32 v[228:229], v[228:229], v[184:185]
	v_pk_mul_f32 v[230:231], v[230:231], v[184:185]
	v_pk_fma_f32 v[194:195], v[216:217], v[160:161], v[194:195]
	v_pk_fma_f32 v[196:197], v[218:219], v[162:163], v[196:197]
	v_pk_fma_f32 v[198:199], v[220:221], v[164:165], v[198:199]
	v_pk_fma_f32 v[200:201], v[222:223], v[166:167], v[200:201]
	v_pk_fma_f32 v[202:203], v[224:225], v[168:169], v[202:203]
	v_pk_fma_f32 v[204:205], v[226:227], v[170:171], v[204:205]
	v_pk_fma_f32 v[206:207], v[228:229], v[172:173], v[206:207]
	v_pk_fma_f32 v[208:209], v[230:231], v[174:175], v[208:209]
	v_pk_mul_f32 v[252:253], v[194:195], v[194:195]
	v_pk_mul_f32 v[254:255], v[196:197], v[196:197]
	v_pk_fma_f32 v[252:253], v[198:199], v[198:199], v[252:253]
	v_pk_fma_f32 v[254:255], v[200:201], v[200:201], v[254:255]
	v_pk_fma_f32 v[252:253], v[202:203], v[202:203], v[252:253]
	v_pk_fma_f32 v[254:255], v[204:205], v[204:205], v[254:255]
	v_pk_fma_f32 v[252:253], v[206:207], v[206:207], v[252:253]
	v_pk_fma_f32 v[254:255], v[208:209], v[208:209], v[254:255]
	v_pk_add_f32 v[252:253], v[252:253], v[254:255]
	s_nop 0
	v_add_f32_e32 v183, v252, v253
	s_nop 1
	v_add_f32_dpp v183, v183, v183 quad_perm:[1,0,3,2] row_mask:0xf bank_mask:0xf bound_ctrl:1
	s_nop 1
	v_add_f32_dpp v183, v183, v183 quad_perm:[2,3,0,1] row_mask:0xf bank_mask:0xf bound_ctrl:1
	s_nop 1
	v_add_f32_dpp v183, v183, v183 row_half_mirror row_mask:0xf bank_mask:0xf bound_ctrl:1
	s_nop 1
	v_add_f32_dpp v183, v183, v183 row_mirror row_mask:0xf bank_mask:0xf bound_ctrl:1
	s_nop 1
	v_readlane_b32 s98, v183, 0
	v_readlane_b32 s99, v183, 16
	v_readlane_b32 s100, v183, 32
	v_readlane_b32 s101, v183, 48
	s_nop 1
	v_mov_b32_e32 v183, s98
	v_add_f32_e32 v183, s99, v183
	v_add_f32_e32 v183, s100, v183
	v_add_f32_e32 v183, s101, v183
	v_fmamk_f32 v183, v183, 0x3a800000, v182
	v_cmp_gt_f32_e32 vcc, 0x800000, v183
	v_mul_f32_e32 v181, 0x4b800000, v183
	s_nop 1
	v_cndmask_b32_e32 v183, v183, v181, vcc
	v_rsq_f32_e32 v183, v183
	s_nop 0
	v_mul_f32_e32 v181, 0x45800000, v183
	v_cndmask_b32_e32 v184, v183, v181, vcc
	v_mov_b32_e32 v185, v184
	v_cvt_pk_bf16_f32 v64, v194, v195
	v_cvt_pk_bf16_f32 v65, v196, v197
	v_cvt_pk_bf16_f32 v66, v198, v199
	v_cvt_pk_bf16_f32 v67, v200, v201
	v_cvt_pk_bf16_f32 v68, v202, v203
	v_cvt_pk_bf16_f32 v69, v204, v205
	v_cvt_pk_bf16_f32 v70, v206, v207
	v_cvt_pk_bf16_f32 v71, v208, v209
	v_add_u32_e32 v181, 0x2800000, v177
	global_store_dwordx4 v181, v[64:67], s[78:79]
	global_store_dwordx4 v181, v[68:71], s[78:79] offset:1024
	v_add_u32_e32 v236, 0x8000, v237
	s_mov_b64 exec, 1
	global_store_dword v236, v184, s[78:79]
	s_mov_b64 exec, -1
	s_waitcnt vmcnt(16)
	v_lshlrev_b32_e32 v194, 16, v80
	v_and_b32_e32 v195, 0xffff0000, v80
	v_lshlrev_b32_e32 v196, 16, v81
	v_and_b32_e32 v197, 0xffff0000, v81
	v_lshlrev_b32_e32 v198, 16, v82
	v_and_b32_e32 v199, 0xffff0000, v82
	v_lshlrev_b32_e32 v200, 16, v83
	v_and_b32_e32 v201, 0xffff0000, v83
	v_lshlrev_b32_e32 v202, 16, v84
	v_and_b32_e32 v203, 0xffff0000, v84
	v_lshlrev_b32_e32 v204, 16, v85
	v_and_b32_e32 v205, 0xffff0000, v85
	v_lshlrev_b32_e32 v206, 16, v86
	v_and_b32_e32 v207, 0xffff0000, v86
	v_lshlrev_b32_e32 v208, 16, v87
	v_and_b32_e32 v209, 0xffff0000, v87
	v_lshlrev_b32_e32 v216, 16, v88
	v_and_b32_e32 v217, 0xffff0000, v88
	v_lshlrev_b32_e32 v218, 16, v89
	v_and_b32_e32 v219, 0xffff0000, v89
	v_lshlrev_b32_e32 v220, 16, v90
	v_and_b32_e32 v221, 0xffff0000, v90
	v_lshlrev_b32_e32 v222, 16, v91
	v_and_b32_e32 v223, 0xffff0000, v91
	v_lshlrev_b32_e32 v224, 16, v92
	v_and_b32_e32 v225, 0xffff0000, v92
	v_lshlrev_b32_e32 v226, 16, v93
	v_and_b32_e32 v227, 0xffff0000, v93
	v_lshlrev_b32_e32 v228, 16, v94
	v_and_b32_e32 v229, 0xffff0000, v94
	v_lshlrev_b32_e32 v230, 16, v95
	v_and_b32_e32 v231, 0xffff0000, v95
	v_pk_mul_f32 v[252:253], v[216:217], v[216:217]
	v_pk_mul_f32 v[254:255], v[218:219], v[218:219]
	v_pk_fma_f32 v[252:253], v[220:221], v[220:221], v[252:253]
	v_pk_fma_f32 v[254:255], v[222:223], v[222:223], v[254:255]
	v_pk_fma_f32 v[252:253], v[224:225], v[224:225], v[252:253]
	v_pk_fma_f32 v[254:255], v[226:227], v[226:227], v[254:255]
	v_pk_fma_f32 v[252:253], v[228:229], v[228:229], v[252:253]
	v_pk_fma_f32 v[254:255], v[230:231], v[230:231], v[254:255]
	v_pk_add_f32 v[252:253], v[252:253], v[254:255]
	s_nop 0
	v_add_f32_e32 v183, v252, v253
	s_nop 1
	v_add_f32_dpp v183, v183, v183 quad_perm:[1,0,3,2] row_mask:0xf bank_mask:0xf bound_ctrl:1
	s_nop 1
	v_add_f32_dpp v183, v183, v183 quad_perm:[2,3,0,1] row_mask:0xf bank_mask:0xf bound_ctrl:1
	s_nop 1
	v_add_f32_dpp v183, v183, v183 row_half_mirror row_mask:0xf bank_mask:0xf bound_ctrl:1
	s_nop 1
	v_add_f32_dpp v183, v183, v183 row_mirror row_mask:0xf bank_mask:0xf bound_ctrl:1
	s_nop 1
	v_readlane_b32 s98, v183, 0
	v_readlane_b32 s99, v183, 16
	v_readlane_b32 s100, v183, 32
	v_readlane_b32 s101, v183, 48
	s_nop 1
	v_mov_b32_e32 v183, s98
	v_add_f32_e32 v183, s99, v183
	v_add_f32_e32 v183, s100, v183
	v_add_f32_e32 v183, s101, v183
	v_fmamk_f32 v183, v183, 0x3a800000, v182
	v_cmp_gt_f32_e32 vcc, 0x800000, v183
	v_mul_f32_e32 v181, 0x4b800000, v183
	s_nop 1
	v_cndmask_b32_e32 v183, v183, v181, vcc
	v_rsq_f32_e32 v183, v183
	s_nop 0
	v_mul_f32_e32 v181, 0x45800000, v183
	v_cndmask_b32_e32 v184, v183, v181, vcc
	v_mov_b32_e32 v185, v184
	v_pk_mul_f32 v[216:217], v[216:217], v[184:185]
	v_pk_mul_f32 v[218:219], v[218:219], v[184:185]
	v_pk_mul_f32 v[220:221], v[220:221], v[184:185]
	v_pk_mul_f32 v[222:223], v[222:223], v[184:185]
	v_pk_mul_f32 v[224:225], v[224:225], v[184:185]
	v_pk_mul_f32 v[226:227], v[226:227], v[184:185]
	v_pk_mul_f32 v[228:229], v[228:229], v[184:185]
	v_pk_mul_f32 v[230:231], v[230:231], v[184:185]
	v_pk_fma_f32 v[194:195], v[216:217], v[160:161], v[194:195]
	v_pk_fma_f32 v[196:197], v[218:219], v[162:163], v[196:197]
	v_pk_fma_f32 v[198:199], v[220:221], v[164:165], v[198:199]
	v_pk_fma_f32 v[200:201], v[222:223], v[166:167], v[200:201]
	v_pk_fma_f32 v[202:203], v[224:225], v[168:169], v[202:203]
	v_pk_fma_f32 v[204:205], v[226:227], v[170:171], v[204:205]
	v_pk_fma_f32 v[206:207], v[228:229], v[172:173], v[206:207]
	v_pk_fma_f32 v[208:209], v[230:231], v[174:175], v[208:209]
	v_pk_mul_f32 v[252:253], v[194:195], v[194:195]
	v_pk_mul_f32 v[254:255], v[196:197], v[196:197]
	v_pk_fma_f32 v[252:253], v[198:199], v[198:199], v[252:253]
	v_pk_fma_f32 v[254:255], v[200:201], v[200:201], v[254:255]
	v_pk_fma_f32 v[252:253], v[202:203], v[202:203], v[252:253]
	v_pk_fma_f32 v[254:255], v[204:205], v[204:205], v[254:255]
	v_pk_fma_f32 v[252:253], v[206:207], v[206:207], v[252:253]
	v_pk_fma_f32 v[254:255], v[208:209], v[208:209], v[254:255]
	v_pk_add_f32 v[252:253], v[252:253], v[254:255]
	s_nop 0
	v_add_f32_e32 v183, v252, v253
	s_nop 1
	v_add_f32_dpp v183, v183, v183 quad_perm:[1,0,3,2] row_mask:0xf bank_mask:0xf bound_ctrl:1
	s_nop 1
	v_add_f32_dpp v183, v183, v183 quad_perm:[2,3,0,1] row_mask:0xf bank_mask:0xf bound_ctrl:1
	s_nop 1
	v_add_f32_dpp v183, v183, v183 row_half_mirror row_mask:0xf bank_mask:0xf bound_ctrl:1
	s_nop 1
	v_add_f32_dpp v183, v183, v183 row_mirror row_mask:0xf bank_mask:0xf bound_ctrl:1
	s_nop 1
	v_readlane_b32 s98, v183, 0
	v_readlane_b32 s99, v183, 16
	v_readlane_b32 s100, v183, 32
	v_readlane_b32 s101, v183, 48
	s_nop 1
	v_mov_b32_e32 v183, s98
	v_add_f32_e32 v183, s99, v183
	v_add_f32_e32 v183, s100, v183
	v_add_f32_e32 v183, s101, v183
	v_fmamk_f32 v183, v183, 0x3a800000, v182
	v_cmp_gt_f32_e32 vcc, 0x800000, v183
	v_mul_f32_e32 v181, 0x4b800000, v183
	s_nop 1
	v_cndmask_b32_e32 v183, v183, v181, vcc
	v_rsq_f32_e32 v183, v183
	s_nop 0
	v_mul_f32_e32 v181, 0x45800000, v183
	v_cndmask_b32_e32 v184, v183, v181, vcc
	v_mov_b32_e32 v185, v184
	v_cvt_pk_bf16_f32 v80, v194, v195
	v_cvt_pk_bf16_f32 v81, v196, v197
	v_cvt_pk_bf16_f32 v82, v198, v199
	v_cvt_pk_bf16_f32 v83, v200, v201
	v_cvt_pk_bf16_f32 v84, v202, v203
	v_cvt_pk_bf16_f32 v85, v204, v205
	v_cvt_pk_bf16_f32 v86, v206, v207
	v_cvt_pk_bf16_f32 v87, v208, v209
	v_add_u32_e32 v181, 0x2c00000, v177
	global_store_dwordx4 v181, v[80:83], s[78:79]
	global_store_dwordx4 v181, v[84:87], s[78:79] offset:1024
	v_add_u32_e32 v236, 0xa000, v237
	s_mov_b64 exec, 1
	global_store_dword v236, v184, s[78:79]
	s_mov_b64 exec, -1
	s_waitcnt vmcnt(12)
	v_lshlrev_b32_e32 v194, 16, v96
	v_and_b32_e32 v195, 0xffff0000, v96
	v_lshlrev_b32_e32 v196, 16, v97
	v_and_b32_e32 v197, 0xffff0000, v97
	v_lshlrev_b32_e32 v198, 16, v98
	v_and_b32_e32 v199, 0xffff0000, v98
	v_lshlrev_b32_e32 v200, 16, v99
	v_and_b32_e32 v201, 0xffff0000, v99
	v_lshlrev_b32_e32 v202, 16, v100
	v_and_b32_e32 v203, 0xffff0000, v100
	v_lshlrev_b32_e32 v204, 16, v101
	v_and_b32_e32 v205, 0xffff0000, v101
	v_lshlrev_b32_e32 v206, 16, v102
	v_and_b32_e32 v207, 0xffff0000, v102
	v_lshlrev_b32_e32 v208, 16, v103
	v_and_b32_e32 v209, 0xffff0000, v103
	v_lshlrev_b32_e32 v216, 16, v104
	v_and_b32_e32 v217, 0xffff0000, v104
	v_lshlrev_b32_e32 v218, 16, v105
	v_and_b32_e32 v219, 0xffff0000, v105
	v_lshlrev_b32_e32 v220, 16, v106
	v_and_b32_e32 v221, 0xffff0000, v106
	v_lshlrev_b32_e32 v222, 16, v107
	v_and_b32_e32 v223, 0xffff0000, v107
	v_lshlrev_b32_e32 v224, 16, v108
	v_and_b32_e32 v225, 0xffff0000, v108
	v_lshlrev_b32_e32 v226, 16, v109
	v_and_b32_e32 v227, 0xffff0000, v109
	v_lshlrev_b32_e32 v228, 16, v110
	v_and_b32_e32 v229, 0xffff0000, v110
	v_lshlrev_b32_e32 v230, 16, v111
	v_and_b32_e32 v231, 0xffff0000, v111
	v_pk_mul_f32 v[252:253], v[216:217], v[216:217]
	v_pk_mul_f32 v[254:255], v[218:219], v[218:219]
	v_pk_fma_f32 v[252:253], v[220:221], v[220:221], v[252:253]
	v_pk_fma_f32 v[254:255], v[222:223], v[222:223], v[254:255]
	v_pk_fma_f32 v[252:253], v[224:225], v[224:225], v[252:253]
	v_pk_fma_f32 v[254:255], v[226:227], v[226:227], v[254:255]
	v_pk_fma_f32 v[252:253], v[228:229], v[228:229], v[252:253]
	v_pk_fma_f32 v[254:255], v[230:231], v[230:231], v[254:255]
	v_pk_add_f32 v[252:253], v[252:253], v[254:255]
	s_nop 0
	v_add_f32_e32 v183, v252, v253
	s_nop 1
	v_add_f32_dpp v183, v183, v183 quad_perm:[1,0,3,2] row_mask:0xf bank_mask:0xf bound_ctrl:1
	s_nop 1
	v_add_f32_dpp v183, v183, v183 quad_perm:[2,3,0,1] row_mask:0xf bank_mask:0xf bound_ctrl:1
	s_nop 1
	v_add_f32_dpp v183, v183, v183 row_half_mirror row_mask:0xf bank_mask:0xf bound_ctrl:1
	s_nop 1
	v_add_f32_dpp v183, v183, v183 row_mirror row_mask:0xf bank_mask:0xf bound_ctrl:1
	s_nop 1
	v_readlane_b32 s98, v183, 0
	v_readlane_b32 s99, v183, 16
	v_readlane_b32 s100, v183, 32
	v_readlane_b32 s101, v183, 48
	s_nop 1
	v_mov_b32_e32 v183, s98
	v_add_f32_e32 v183, s99, v183
	v_add_f32_e32 v183, s100, v183
	v_add_f32_e32 v183, s101, v183
	v_fmamk_f32 v183, v183, 0x3a800000, v182
	v_cmp_gt_f32_e32 vcc, 0x800000, v183
	v_mul_f32_e32 v181, 0x4b800000, v183
	s_nop 1
	v_cndmask_b32_e32 v183, v183, v181, vcc
	v_rsq_f32_e32 v183, v183
	s_nop 0
	v_mul_f32_e32 v181, 0x45800000, v183
	v_cndmask_b32_e32 v184, v183, v181, vcc
	v_mov_b32_e32 v185, v184
	v_pk_mul_f32 v[216:217], v[216:217], v[184:185]
	v_pk_mul_f32 v[218:219], v[218:219], v[184:185]
	v_pk_mul_f32 v[220:221], v[220:221], v[184:185]
	v_pk_mul_f32 v[222:223], v[222:223], v[184:185]
	v_pk_mul_f32 v[224:225], v[224:225], v[184:185]
	v_pk_mul_f32 v[226:227], v[226:227], v[184:185]
	v_pk_mul_f32 v[228:229], v[228:229], v[184:185]
	v_pk_mul_f32 v[230:231], v[230:231], v[184:185]
	v_pk_fma_f32 v[194:195], v[216:217], v[160:161], v[194:195]
	v_pk_fma_f32 v[196:197], v[218:219], v[162:163], v[196:197]
	v_pk_fma_f32 v[198:199], v[220:221], v[164:165], v[198:199]
	v_pk_fma_f32 v[200:201], v[222:223], v[166:167], v[200:201]
	v_pk_fma_f32 v[202:203], v[224:225], v[168:169], v[202:203]
	v_pk_fma_f32 v[204:205], v[226:227], v[170:171], v[204:205]
	v_pk_fma_f32 v[206:207], v[228:229], v[172:173], v[206:207]
	v_pk_fma_f32 v[208:209], v[230:231], v[174:175], v[208:209]
	v_pk_mul_f32 v[252:253], v[194:195], v[194:195]
	v_pk_mul_f32 v[254:255], v[196:197], v[196:197]
	v_pk_fma_f32 v[252:253], v[198:199], v[198:199], v[252:253]
	v_pk_fma_f32 v[254:255], v[200:201], v[200:201], v[254:255]
	v_pk_fma_f32 v[252:253], v[202:203], v[202:203], v[252:253]
	v_pk_fma_f32 v[254:255], v[204:205], v[204:205], v[254:255]
	v_pk_fma_f32 v[252:253], v[206:207], v[206:207], v[252:253]
	v_pk_fma_f32 v[254:255], v[208:209], v[208:209], v[254:255]
	v_pk_add_f32 v[252:253], v[252:253], v[254:255]
	s_nop 0
	v_add_f32_e32 v183, v252, v253
	s_nop 1
	v_add_f32_dpp v183, v183, v183 quad_perm:[1,0,3,2] row_mask:0xf bank_mask:0xf bound_ctrl:1
	s_nop 1
	v_add_f32_dpp v183, v183, v183 quad_perm:[2,3,0,1] row_mask:0xf bank_mask:0xf bound_ctrl:1
	s_nop 1
	v_add_f32_dpp v183, v183, v183 row_half_mirror row_mask:0xf bank_mask:0xf bound_ctrl:1
	s_nop 1
	v_add_f32_dpp v183, v183, v183 row_mirror row_mask:0xf bank_mask:0xf bound_ctrl:1
	s_nop 1
	v_readlane_b32 s98, v183, 0
	v_readlane_b32 s99, v183, 16
	v_readlane_b32 s100, v183, 32
	v_readlane_b32 s101, v183, 48
	s_nop 1
	v_mov_b32_e32 v183, s98
	v_add_f32_e32 v183, s99, v183
	v_add_f32_e32 v183, s100, v183
	v_add_f32_e32 v183, s101, v183
	v_fmamk_f32 v183, v183, 0x3a800000, v182
	v_cmp_gt_f32_e32 vcc, 0x800000, v183
	v_mul_f32_e32 v181, 0x4b800000, v183
	s_nop 1
	v_cndmask_b32_e32 v183, v183, v181, vcc
	v_rsq_f32_e32 v183, v183
	s_nop 0
	v_mul_f32_e32 v181, 0x45800000, v183
	v_cndmask_b32_e32 v184, v183, v181, vcc
	v_mov_b32_e32 v185, v184
	v_cvt_pk_bf16_f32 v96, v194, v195
	v_cvt_pk_bf16_f32 v97, v196, v197
	v_cvt_pk_bf16_f32 v98, v198, v199
	v_cvt_pk_bf16_f32 v99, v200, v201
	v_cvt_pk_bf16_f32 v100, v202, v203
	v_cvt_pk_bf16_f32 v101, v204, v205
	v_cvt_pk_bf16_f32 v102, v206, v207
	v_cvt_pk_bf16_f32 v103, v208, v209
	v_add_u32_e32 v181, 0x3000000, v177
	global_store_dwordx4 v181, v[96:99], s[78:79]
	global_store_dwordx4 v181, v[100:103], s[78:79] offset:1024
	v_add_u32_e32 v236, 0xc000, v237
	s_mov_b64 exec, 1
	global_store_dword v236, v184, s[78:79]
	s_mov_b64 exec, -1
	s_waitcnt vmcnt(8)
	v_lshlrev_b32_e32 v194, 16, v112
	v_and_b32_e32 v195, 0xffff0000, v112
	v_lshlrev_b32_e32 v196, 16, v113
	v_and_b32_e32 v197, 0xffff0000, v113
	v_lshlrev_b32_e32 v198, 16, v114
	v_and_b32_e32 v199, 0xffff0000, v114
	v_lshlrev_b32_e32 v200, 16, v115
	v_and_b32_e32 v201, 0xffff0000, v115
	v_lshlrev_b32_e32 v202, 16, v116
	v_and_b32_e32 v203, 0xffff0000, v116
	v_lshlrev_b32_e32 v204, 16, v117
	v_and_b32_e32 v205, 0xffff0000, v117
	v_lshlrev_b32_e32 v206, 16, v118
	v_and_b32_e32 v207, 0xffff0000, v118
	v_lshlrev_b32_e32 v208, 16, v119
	v_and_b32_e32 v209, 0xffff0000, v119
	v_lshlrev_b32_e32 v216, 16, v120
	v_and_b32_e32 v217, 0xffff0000, v120
	v_lshlrev_b32_e32 v218, 16, v121
	v_and_b32_e32 v219, 0xffff0000, v121
	v_lshlrev_b32_e32 v220, 16, v122
	v_and_b32_e32 v221, 0xffff0000, v122
	v_lshlrev_b32_e32 v222, 16, v123
	v_and_b32_e32 v223, 0xffff0000, v123
	v_lshlrev_b32_e32 v224, 16, v124
	v_and_b32_e32 v225, 0xffff0000, v124
	v_lshlrev_b32_e32 v226, 16, v125
	v_and_b32_e32 v227, 0xffff0000, v125
	v_lshlrev_b32_e32 v228, 16, v126
	v_and_b32_e32 v229, 0xffff0000, v126
	v_lshlrev_b32_e32 v230, 16, v127
	v_and_b32_e32 v231, 0xffff0000, v127
	v_pk_mul_f32 v[252:253], v[216:217], v[216:217]
	v_pk_mul_f32 v[254:255], v[218:219], v[218:219]
	v_pk_fma_f32 v[252:253], v[220:221], v[220:221], v[252:253]
	v_pk_fma_f32 v[254:255], v[222:223], v[222:223], v[254:255]
	v_pk_fma_f32 v[252:253], v[224:225], v[224:225], v[252:253]
	v_pk_fma_f32 v[254:255], v[226:227], v[226:227], v[254:255]
	v_pk_fma_f32 v[252:253], v[228:229], v[228:229], v[252:253]
	v_pk_fma_f32 v[254:255], v[230:231], v[230:231], v[254:255]
	v_pk_add_f32 v[252:253], v[252:253], v[254:255]
	s_nop 0
	v_add_f32_e32 v183, v252, v253
	s_nop 1
	v_add_f32_dpp v183, v183, v183 quad_perm:[1,0,3,2] row_mask:0xf bank_mask:0xf bound_ctrl:1
	s_nop 1
	v_add_f32_dpp v183, v183, v183 quad_perm:[2,3,0,1] row_mask:0xf bank_mask:0xf bound_ctrl:1
	s_nop 1
	v_add_f32_dpp v183, v183, v183 row_half_mirror row_mask:0xf bank_mask:0xf bound_ctrl:1
	s_nop 1
	v_add_f32_dpp v183, v183, v183 row_mirror row_mask:0xf bank_mask:0xf bound_ctrl:1
	s_nop 1
	v_readlane_b32 s98, v183, 0
	v_readlane_b32 s99, v183, 16
	v_readlane_b32 s100, v183, 32
	v_readlane_b32 s101, v183, 48
	s_nop 1
	v_mov_b32_e32 v183, s98
	v_add_f32_e32 v183, s99, v183
	v_add_f32_e32 v183, s100, v183
	v_add_f32_e32 v183, s101, v183
	v_fmamk_f32 v183, v183, 0x3a800000, v182
	v_cmp_gt_f32_e32 vcc, 0x800000, v183
	v_mul_f32_e32 v181, 0x4b800000, v183
	s_nop 1
	v_cndmask_b32_e32 v183, v183, v181, vcc
	v_rsq_f32_e32 v183, v183
	s_nop 0
	v_mul_f32_e32 v181, 0x45800000, v183
	v_cndmask_b32_e32 v184, v183, v181, vcc
	v_mov_b32_e32 v185, v184
	v_pk_mul_f32 v[216:217], v[216:217], v[184:185]
	v_pk_mul_f32 v[218:219], v[218:219], v[184:185]
	v_pk_mul_f32 v[220:221], v[220:221], v[184:185]
	v_pk_mul_f32 v[222:223], v[222:223], v[184:185]
	v_pk_mul_f32 v[224:225], v[224:225], v[184:185]
	v_pk_mul_f32 v[226:227], v[226:227], v[184:185]
	v_pk_mul_f32 v[228:229], v[228:229], v[184:185]
	v_pk_mul_f32 v[230:231], v[230:231], v[184:185]
	v_pk_fma_f32 v[194:195], v[216:217], v[160:161], v[194:195]
	v_pk_fma_f32 v[196:197], v[218:219], v[162:163], v[196:197]
	v_pk_fma_f32 v[198:199], v[220:221], v[164:165], v[198:199]
	v_pk_fma_f32 v[200:201], v[222:223], v[166:167], v[200:201]
	v_pk_fma_f32 v[202:203], v[224:225], v[168:169], v[202:203]
	v_pk_fma_f32 v[204:205], v[226:227], v[170:171], v[204:205]
	v_pk_fma_f32 v[206:207], v[228:229], v[172:173], v[206:207]
	v_pk_fma_f32 v[208:209], v[230:231], v[174:175], v[208:209]
	v_pk_mul_f32 v[252:253], v[194:195], v[194:195]
	v_pk_mul_f32 v[254:255], v[196:197], v[196:197]
	v_pk_fma_f32 v[252:253], v[198:199], v[198:199], v[252:253]
	v_pk_fma_f32 v[254:255], v[200:201], v[200:201], v[254:255]
	v_pk_fma_f32 v[252:253], v[202:203], v[202:203], v[252:253]
	v_pk_fma_f32 v[254:255], v[204:205], v[204:205], v[254:255]
	v_pk_fma_f32 v[252:253], v[206:207], v[206:207], v[252:253]
	v_pk_fma_f32 v[254:255], v[208:209], v[208:209], v[254:255]
	v_pk_add_f32 v[252:253], v[252:253], v[254:255]
	s_nop 0
	v_add_f32_e32 v183, v252, v253
	s_nop 1
	v_add_f32_dpp v183, v183, v183 quad_perm:[1,0,3,2] row_mask:0xf bank_mask:0xf bound_ctrl:1
	s_nop 1
	v_add_f32_dpp v183, v183, v183 quad_perm:[2,3,0,1] row_mask:0xf bank_mask:0xf bound_ctrl:1
	s_nop 1
	v_add_f32_dpp v183, v183, v183 row_half_mirror row_mask:0xf bank_mask:0xf bound_ctrl:1
	s_nop 1
	v_add_f32_dpp v183, v183, v183 row_mirror row_mask:0xf bank_mask:0xf bound_ctrl:1
	s_nop 1
	v_readlane_b32 s98, v183, 0
	v_readlane_b32 s99, v183, 16
	v_readlane_b32 s100, v183, 32
	v_readlane_b32 s101, v183, 48
	s_nop 1
	v_mov_b32_e32 v183, s98
	v_add_f32_e32 v183, s99, v183
	v_add_f32_e32 v183, s100, v183
	v_add_f32_e32 v183, s101, v183
	v_fmamk_f32 v183, v183, 0x3a800000, v182
	v_cmp_gt_f32_e32 vcc, 0x800000, v183
	v_mul_f32_e32 v181, 0x4b800000, v183
	s_nop 1
	v_cndmask_b32_e32 v183, v183, v181, vcc
	v_rsq_f32_e32 v183, v183
	s_nop 0
	v_mul_f32_e32 v181, 0x45800000, v183
	v_cndmask_b32_e32 v184, v183, v181, vcc
	v_mov_b32_e32 v185, v184
	v_cvt_pk_bf16_f32 v112, v194, v195
	v_cvt_pk_bf16_f32 v113, v196, v197
	v_cvt_pk_bf16_f32 v114, v198, v199
	v_cvt_pk_bf16_f32 v115, v200, v201
	v_cvt_pk_bf16_f32 v116, v202, v203
	v_cvt_pk_bf16_f32 v117, v204, v205
	v_cvt_pk_bf16_f32 v118, v206, v207
	v_cvt_pk_bf16_f32 v119, v208, v209
	v_add_u32_e32 v181, 0x3400000, v177
	global_store_dwordx4 v181, v[112:115], s[78:79]
	global_store_dwordx4 v181, v[116:119], s[78:79] offset:1024
	v_add_u32_e32 v236, 0xe000, v237
	s_mov_b64 exec, 1
	global_store_dword v236, v184, s[78:79]
	s_mov_b64 exec, -1
	s_waitcnt vmcnt(4)
	v_lshlrev_b32_e32 v194, 16, v128
	v_and_b32_e32 v195, 0xffff0000, v128
	v_lshlrev_b32_e32 v196, 16, v129
	v_and_b32_e32 v197, 0xffff0000, v129
	v_lshlrev_b32_e32 v198, 16, v130
	v_and_b32_e32 v199, 0xffff0000, v130
	v_lshlrev_b32_e32 v200, 16, v131
	v_and_b32_e32 v201, 0xffff0000, v131
	v_lshlrev_b32_e32 v202, 16, v132
	v_and_b32_e32 v203, 0xffff0000, v132
	v_lshlrev_b32_e32 v204, 16, v133
	v_and_b32_e32 v205, 0xffff0000, v133
	v_lshlrev_b32_e32 v206, 16, v134
	v_and_b32_e32 v207, 0xffff0000, v134
	v_lshlrev_b32_e32 v208, 16, v135
	v_and_b32_e32 v209, 0xffff0000, v135
	v_lshlrev_b32_e32 v216, 16, v136
	v_and_b32_e32 v217, 0xffff0000, v136
	v_lshlrev_b32_e32 v218, 16, v137
	v_and_b32_e32 v219, 0xffff0000, v137
	v_lshlrev_b32_e32 v220, 16, v138
	v_and_b32_e32 v221, 0xffff0000, v138
	v_lshlrev_b32_e32 v222, 16, v139
	v_and_b32_e32 v223, 0xffff0000, v139
	v_lshlrev_b32_e32 v224, 16, v140
	v_and_b32_e32 v225, 0xffff0000, v140
	v_lshlrev_b32_e32 v226, 16, v141
	v_and_b32_e32 v227, 0xffff0000, v141
	v_lshlrev_b32_e32 v228, 16, v142
	v_and_b32_e32 v229, 0xffff0000, v142
	v_lshlrev_b32_e32 v230, 16, v143
	v_and_b32_e32 v231, 0xffff0000, v143
	v_pk_mul_f32 v[252:253], v[216:217], v[216:217]
	v_pk_mul_f32 v[254:255], v[218:219], v[218:219]
	v_pk_fma_f32 v[252:253], v[220:221], v[220:221], v[252:253]
	v_pk_fma_f32 v[254:255], v[222:223], v[222:223], v[254:255]
	v_pk_fma_f32 v[252:253], v[224:225], v[224:225], v[252:253]
	v_pk_fma_f32 v[254:255], v[226:227], v[226:227], v[254:255]
	v_pk_fma_f32 v[252:253], v[228:229], v[228:229], v[252:253]
	v_pk_fma_f32 v[254:255], v[230:231], v[230:231], v[254:255]
	v_pk_add_f32 v[252:253], v[252:253], v[254:255]
	s_nop 0
	v_add_f32_e32 v183, v252, v253
	s_nop 1
	v_add_f32_dpp v183, v183, v183 quad_perm:[1,0,3,2] row_mask:0xf bank_mask:0xf bound_ctrl:1
	s_nop 1
	v_add_f32_dpp v183, v183, v183 quad_perm:[2,3,0,1] row_mask:0xf bank_mask:0xf bound_ctrl:1
	s_nop 1
	v_add_f32_dpp v183, v183, v183 row_half_mirror row_mask:0xf bank_mask:0xf bound_ctrl:1
	s_nop 1
	v_add_f32_dpp v183, v183, v183 row_mirror row_mask:0xf bank_mask:0xf bound_ctrl:1
	s_nop 1
	v_readlane_b32 s98, v183, 0
	v_readlane_b32 s99, v183, 16
	v_readlane_b32 s100, v183, 32
	v_readlane_b32 s101, v183, 48
	s_nop 1
	v_mov_b32_e32 v183, s98
	v_add_f32_e32 v183, s99, v183
	v_add_f32_e32 v183, s100, v183
	v_add_f32_e32 v183, s101, v183
	v_fmamk_f32 v183, v183, 0x3a800000, v182
	v_cmp_gt_f32_e32 vcc, 0x800000, v183
	v_mul_f32_e32 v181, 0x4b800000, v183
	s_nop 1
	v_cndmask_b32_e32 v183, v183, v181, vcc
	v_rsq_f32_e32 v183, v183
	s_nop 0
	v_mul_f32_e32 v181, 0x45800000, v183
	v_cndmask_b32_e32 v184, v183, v181, vcc
	v_mov_b32_e32 v185, v184
	v_pk_mul_f32 v[216:217], v[216:217], v[184:185]
	v_pk_mul_f32 v[218:219], v[218:219], v[184:185]
	v_pk_mul_f32 v[220:221], v[220:221], v[184:185]
	v_pk_mul_f32 v[222:223], v[222:223], v[184:185]
	v_pk_mul_f32 v[224:225], v[224:225], v[184:185]
	v_pk_mul_f32 v[226:227], v[226:227], v[184:185]
	v_pk_mul_f32 v[228:229], v[228:229], v[184:185]
	v_pk_mul_f32 v[230:231], v[230:231], v[184:185]
	v_pk_fma_f32 v[194:195], v[216:217], v[160:161], v[194:195]
	v_pk_fma_f32 v[196:197], v[218:219], v[162:163], v[196:197]
	v_pk_fma_f32 v[198:199], v[220:221], v[164:165], v[198:199]
	v_pk_fma_f32 v[200:201], v[222:223], v[166:167], v[200:201]
	v_pk_fma_f32 v[202:203], v[224:225], v[168:169], v[202:203]
	v_pk_fma_f32 v[204:205], v[226:227], v[170:171], v[204:205]
	v_pk_fma_f32 v[206:207], v[228:229], v[172:173], v[206:207]
	v_pk_fma_f32 v[208:209], v[230:231], v[174:175], v[208:209]
	v_pk_mul_f32 v[252:253], v[194:195], v[194:195]
	v_pk_mul_f32 v[254:255], v[196:197], v[196:197]
	v_pk_fma_f32 v[252:253], v[198:199], v[198:199], v[252:253]
	v_pk_fma_f32 v[254:255], v[200:201], v[200:201], v[254:255]
	v_pk_fma_f32 v[252:253], v[202:203], v[202:203], v[252:253]
	v_pk_fma_f32 v[254:255], v[204:205], v[204:205], v[254:255]
	v_pk_fma_f32 v[252:253], v[206:207], v[206:207], v[252:253]
	v_pk_fma_f32 v[254:255], v[208:209], v[208:209], v[254:255]
	v_pk_add_f32 v[252:253], v[252:253], v[254:255]
	s_nop 0
	v_add_f32_e32 v183, v252, v253
	s_nop 1
	v_add_f32_dpp v183, v183, v183 quad_perm:[1,0,3,2] row_mask:0xf bank_mask:0xf bound_ctrl:1
	s_nop 1
	v_add_f32_dpp v183, v183, v183 quad_perm:[2,3,0,1] row_mask:0xf bank_mask:0xf bound_ctrl:1
	s_nop 1
	v_add_f32_dpp v183, v183, v183 row_half_mirror row_mask:0xf bank_mask:0xf bound_ctrl:1
	s_nop 1
	v_add_f32_dpp v183, v183, v183 row_mirror row_mask:0xf bank_mask:0xf bound_ctrl:1
	s_nop 1
	v_readlane_b32 s98, v183, 0
	v_readlane_b32 s99, v183, 16
	v_readlane_b32 s100, v183, 32
	v_readlane_b32 s101, v183, 48
	s_nop 1
	v_mov_b32_e32 v183, s98
	v_add_f32_e32 v183, s99, v183
	v_add_f32_e32 v183, s100, v183
	v_add_f32_e32 v183, s101, v183
	v_fmamk_f32 v183, v183, 0x3a800000, v182
	v_cmp_gt_f32_e32 vcc, 0x800000, v183
	v_mul_f32_e32 v181, 0x4b800000, v183
	s_nop 1
	v_cndmask_b32_e32 v183, v183, v181, vcc
	v_rsq_f32_e32 v183, v183
	s_nop 0
	v_mul_f32_e32 v181, 0x45800000, v183
	v_cndmask_b32_e32 v184, v183, v181, vcc
	v_mov_b32_e32 v185, v184
	v_cvt_pk_bf16_f32 v128, v194, v195
	v_cvt_pk_bf16_f32 v129, v196, v197
	v_cvt_pk_bf16_f32 v130, v198, v199
	v_cvt_pk_bf16_f32 v131, v200, v201
	v_cvt_pk_bf16_f32 v132, v202, v203
	v_cvt_pk_bf16_f32 v133, v204, v205
	v_cvt_pk_bf16_f32 v134, v206, v207
	v_cvt_pk_bf16_f32 v135, v208, v209
	v_add_u32_e32 v181, 0x1800000, v210
	global_store_dwordx4 v181, v[128:131], s[78:79]
	global_store_dwordx4 v181, v[132:135], s[78:79] offset:1024
	v_add_u32_e32 v236, 0x0, v211
	s_mov_b64 exec, 1
	global_store_dword v236, v184, s[78:79]
	s_mov_b64 exec, -1
	s_waitcnt vmcnt(0)
	v_lshlrev_b32_e32 v194, 16, v144
	v_and_b32_e32 v195, 0xffff0000, v144
	v_lshlrev_b32_e32 v196, 16, v145
	v_and_b32_e32 v197, 0xffff0000, v145
	v_lshlrev_b32_e32 v198, 16, v146
	v_and_b32_e32 v199, 0xffff0000, v146
	v_lshlrev_b32_e32 v200, 16, v147
	v_and_b32_e32 v201, 0xffff0000, v147
	v_lshlrev_b32_e32 v202, 16, v148
	v_and_b32_e32 v203, 0xffff0000, v148
	v_lshlrev_b32_e32 v204, 16, v149
	v_and_b32_e32 v205, 0xffff0000, v149
	v_lshlrev_b32_e32 v206, 16, v150
	v_and_b32_e32 v207, 0xffff0000, v150
	v_lshlrev_b32_e32 v208, 16, v151
	v_and_b32_e32 v209, 0xffff0000, v151
	v_lshlrev_b32_e32 v216, 16, v152
	v_and_b32_e32 v217, 0xffff0000, v152
	v_lshlrev_b32_e32 v218, 16, v153
	v_and_b32_e32 v219, 0xffff0000, v153
	v_lshlrev_b32_e32 v220, 16, v154
	v_and_b32_e32 v221, 0xffff0000, v154
	v_lshlrev_b32_e32 v222, 16, v155
	v_and_b32_e32 v223, 0xffff0000, v155
	v_lshlrev_b32_e32 v224, 16, v156
	v_and_b32_e32 v225, 0xffff0000, v156
	v_lshlrev_b32_e32 v226, 16, v157
	v_and_b32_e32 v227, 0xffff0000, v157
	v_lshlrev_b32_e32 v228, 16, v158
	v_and_b32_e32 v229, 0xffff0000, v158
	v_lshlrev_b32_e32 v230, 16, v159
	v_and_b32_e32 v231, 0xffff0000, v159
	v_pk_mul_f32 v[252:253], v[216:217], v[216:217]
	v_pk_mul_f32 v[254:255], v[218:219], v[218:219]
	v_pk_fma_f32 v[252:253], v[220:221], v[220:221], v[252:253]
	v_pk_fma_f32 v[254:255], v[222:223], v[222:223], v[254:255]
	v_pk_fma_f32 v[252:253], v[224:225], v[224:225], v[252:253]
	v_pk_fma_f32 v[254:255], v[226:227], v[226:227], v[254:255]
	v_pk_fma_f32 v[252:253], v[228:229], v[228:229], v[252:253]
	v_pk_fma_f32 v[254:255], v[230:231], v[230:231], v[254:255]
	v_pk_add_f32 v[252:253], v[252:253], v[254:255]
	s_nop 0
	v_add_f32_e32 v183, v252, v253
	s_nop 1
	v_add_f32_dpp v183, v183, v183 quad_perm:[1,0,3,2] row_mask:0xf bank_mask:0xf bound_ctrl:1
	s_nop 1
	v_add_f32_dpp v183, v183, v183 quad_perm:[2,3,0,1] row_mask:0xf bank_mask:0xf bound_ctrl:1
	s_nop 1
	v_add_f32_dpp v183, v183, v183 row_half_mirror row_mask:0xf bank_mask:0xf bound_ctrl:1
	s_nop 1
	v_add_f32_dpp v183, v183, v183 row_mirror row_mask:0xf bank_mask:0xf bound_ctrl:1
	s_nop 1
	v_readlane_b32 s98, v183, 0
	v_readlane_b32 s99, v183, 16
	v_readlane_b32 s100, v183, 32
	v_readlane_b32 s101, v183, 48
	s_nop 1
	v_mov_b32_e32 v183, s98
	v_add_f32_e32 v183, s99, v183
	v_add_f32_e32 v183, s100, v183
	v_add_f32_e32 v183, s101, v183
	v_fmamk_f32 v183, v183, 0x3a800000, v182
	v_cmp_gt_f32_e32 vcc, 0x800000, v183
	v_mul_f32_e32 v181, 0x4b800000, v183
	s_nop 1
	v_cndmask_b32_e32 v183, v183, v181, vcc
	v_rsq_f32_e32 v183, v183
	s_nop 0
	v_mul_f32_e32 v181, 0x45800000, v183
	v_cndmask_b32_e32 v184, v183, v181, vcc
	v_mov_b32_e32 v185, v184
	v_pk_mul_f32 v[216:217], v[216:217], v[184:185]
	v_pk_mul_f32 v[218:219], v[218:219], v[184:185]
	v_pk_mul_f32 v[220:221], v[220:221], v[184:185]
	v_pk_mul_f32 v[222:223], v[222:223], v[184:185]
	v_pk_mul_f32 v[224:225], v[224:225], v[184:185]
	v_pk_mul_f32 v[226:227], v[226:227], v[184:185]
	v_pk_mul_f32 v[228:229], v[228:229], v[184:185]
	v_pk_mul_f32 v[230:231], v[230:231], v[184:185]
	v_pk_fma_f32 v[194:195], v[216:217], v[160:161], v[194:195]
	v_pk_fma_f32 v[196:197], v[218:219], v[162:163], v[196:197]
	v_pk_fma_f32 v[198:199], v[220:221], v[164:165], v[198:199]
	v_pk_fma_f32 v[200:201], v[222:223], v[166:167], v[200:201]
	v_pk_fma_f32 v[202:203], v[224:225], v[168:169], v[202:203]
	v_pk_fma_f32 v[204:205], v[226:227], v[170:171], v[204:205]
	v_pk_fma_f32 v[206:207], v[228:229], v[172:173], v[206:207]
	v_pk_fma_f32 v[208:209], v[230:231], v[174:175], v[208:209]
	v_pk_mul_f32 v[252:253], v[194:195], v[194:195]
	v_pk_mul_f32 v[254:255], v[196:197], v[196:197]
	v_pk_fma_f32 v[252:253], v[198:199], v[198:199], v[252:253]
	v_pk_fma_f32 v[254:255], v[200:201], v[200:201], v[254:255]
	v_pk_fma_f32 v[252:253], v[202:203], v[202:203], v[252:253]
	v_pk_fma_f32 v[254:255], v[204:205], v[204:205], v[254:255]
	v_pk_fma_f32 v[252:253], v[206:207], v[206:207], v[252:253]
	v_pk_fma_f32 v[254:255], v[208:209], v[208:209], v[254:255]
	v_pk_add_f32 v[252:253], v[252:253], v[254:255]
	s_nop 0
	v_add_f32_e32 v183, v252, v253
	s_nop 1
	v_add_f32_dpp v183, v183, v183 quad_perm:[1,0,3,2] row_mask:0xf bank_mask:0xf bound_ctrl:1
	s_nop 1
	v_add_f32_dpp v183, v183, v183 quad_perm:[2,3,0,1] row_mask:0xf bank_mask:0xf bound_ctrl:1
	s_nop 1
	v_add_f32_dpp v183, v183, v183 row_half_mirror row_mask:0xf bank_mask:0xf bound_ctrl:1
	s_nop 1
	v_add_f32_dpp v183, v183, v183 row_mirror row_mask:0xf bank_mask:0xf bound_ctrl:1
	s_nop 1
	v_readlane_b32 s98, v183, 0
	v_readlane_b32 s99, v183, 16
	v_readlane_b32 s100, v183, 32
	v_readlane_b32 s101, v183, 48
	s_nop 1
	v_mov_b32_e32 v183, s98
	v_add_f32_e32 v183, s99, v183
	v_add_f32_e32 v183, s100, v183
	v_add_f32_e32 v183, s101, v183
	v_fmamk_f32 v183, v183, 0x3a800000, v182
	v_cmp_gt_f32_e32 vcc, 0x800000, v183
	v_mul_f32_e32 v181, 0x4b800000, v183
	s_nop 1
	v_cndmask_b32_e32 v183, v183, v181, vcc
	v_rsq_f32_e32 v183, v183
	s_nop 0
	v_mul_f32_e32 v181, 0x45800000, v183
	v_cndmask_b32_e32 v184, v183, v181, vcc
	v_mov_b32_e32 v185, v184
	v_cvt_pk_bf16_f32 v144, v194, v195
	v_cvt_pk_bf16_f32 v145, v196, v197
	v_cvt_pk_bf16_f32 v146, v198, v199
	v_cvt_pk_bf16_f32 v147, v200, v201
	v_cvt_pk_bf16_f32 v148, v202, v203
	v_cvt_pk_bf16_f32 v149, v204, v205
	v_cvt_pk_bf16_f32 v150, v206, v207
	v_cvt_pk_bf16_f32 v151, v208, v209
	v_add_u32_e32 v181, 0x1c00000, v210
	global_store_dwordx4 v181, v[144:147], s[78:79]
	global_store_dwordx4 v181, v[148:151], s[78:79] offset:1024
	v_add_u32_e32 v236, 0x2000, v211
	s_mov_b64 exec, 1
	global_store_dword v236, v184, s[78:79]
	s_mov_b64 exec, -1
	s_branch .Lmyxupd_done_2

.LBB0_1430:
	v_readlane_b32 s0, v235, 52
	v_readlane_b32 s1, v235, 53
	s_and_b64 vcc, exec, s[0:1]
	s_waitcnt lgkmcnt(0)
	s_barrier
	v_mbcnt_lo_u32_b32 v0, -1, 0
	v_mbcnt_hi_u32_b32 v0, -1, v0
	s_cbranch_vccnz .LBB0_1450
	v_lshlrev_b32_e32 v2, 3, v0
	v_readlane_b32 s4, v235, 4
	v_ashrrev_i32_e32 v3, 31, v2
	v_readlane_b32 s6, v235, 6
	v_readlane_b32 s7, v235, 7
	v_lshlrev_b64 v[4:5], 1, v[2:3]
	v_lshlrev_b64 v[2:3], 2, v[2:3]
	v_readlane_b32 s5, v235, 5
	v_readlane_b32 s10, v235, 10
	v_readlane_b32 s11, v235, 11
	v_readlane_b32 s18, v235, 18
	v_readlane_b32 s19, v235, 19
	v_readlane_b32 s6, v235, 61
	v_lshl_add_u64 v[154:155], s[90:91], 0, v[2:3]
	v_readlane_b32 s8, v235, 8
	v_lshl_add_u64 v[2:3], s[18:19], 0, v[2:3]
	s_mov_b64 s[0:1], 0x1000
	v_readlane_b32 s4, v235, 0
	v_readlane_b32 s7, v235, 62
	s_mov_b32 s10, s6
	s_ashr_i32 s11, s6, 31
	v_readlane_b32 s9, v235, 9
	v_lshl_add_u64 v[158:159], v[2:3], 0, s[0:1]
	s_lshl_b32 s4, s4, 4
	s_add_i32 s0, s6, 0xffffc000
	s_lshl_b64 s[6:7], s[10:11], 2
	s_mov_b32 s8, s10
	v_readlane_b32 s12, v235, 12
	v_readlane_b32 s13, v235, 13
	v_readlane_b32 s14, v235, 14
	v_readlane_b32 s15, v235, 15
	v_readlane_b32 s16, v235, 16
	v_readlane_b32 s17, v235, 17
	v_readlane_b32 s5, v235, 1
	s_add_u32 s80, s6, 0x10000
	v_writelane_b32 v235, s8, 61
	s_addc_u32 s12, s7, 0
	s_ashr_i32 s5, s4, 31
	v_writelane_b32 v235, s9, 62
	s_lshl_b64 s[8:9], s[10:11], 11
	v_lshl_add_u64 v[152:153], s[86:87], 0, v[4:5]
	v_lshl_add_u64 v[156:157], s[54:55], 0, v[4:5]
	s_mov_b32 s1, 0
	v_cmp_eq_u32_e64 s[16:17], 0, v0
	s_lshl_b64 s[6:7], s[4:5], 2
	v_lshl_add_u64 v[160:161], s[8:9], 0, v[4:5]
	s_lshl_b64 s[8:9], s[4:5], 11
	s_mov_b64 s[20:21], 0x600000
	s_mov_b64 s[22:23], 0x600800
	s_mov_b64 s[24:25], 0x800000
	s_mov_b32 s5, 0x800000
	s_mov_b64 s[26:27], 0x800800
	s_mov_b64 s[28:29], 0xa00000
	s_mov_b64 s[36:37], 0xa00800
	s_mov_b64 s[38:39], 0xc00000
	s_mov_b64 s[40:41], 0xc00800
	s_mov_b64 s[42:43], 0xe00000
	s_mov_b64 s[44:45], 0xe00800
	s_mov_b64 s[46:47], 0x1000000
	s_mov_b32 s13, 0x1000000
	s_mov_b64 s[48:49], 0x1000800
	s_mov_b64 s[50:51], 0x1200000
	s_mov_b32 s14, 0x1200000
	s_mov_b64 s[10:11], 0x1200800
	s_mov_b64 s[82:83], 0x1400000
	s_mov_b32 s15, 0x1400000
	s_mov_b64 s[90:91], 0x1400800
	v_mov_b32_e32 v215, 0
	v_mov_b32_e32 v216, 0x358637bd
	v_mbcnt_lo_u32_b32 v176, -1, 0
	v_mbcnt_hi_u32_b32 v176, -1, v176
	v_readlane_b32 s98, v235, 49
	v_readlane_b32 s99, v235, 20
	v_readlane_b32 s100, v235, 18
	v_readlane_b32 s101, v235, 19
	s_nop 3
	s_lshr_b32 vcc_lo, s98, 3
	s_and_b32 vcc_hi, vcc_lo, 7
	s_lshr_b32 vcc_lo, vcc_lo, 3
	s_lshl_b32 vcc_lo, vcc_lo, 3
	s_add_i32 vcc_lo, vcc_lo, s99
	s_lshl_b32 s98, vcc_hi, 8
	s_add_i32 s98, s98, vcc_lo
	v_mov_b32_e32 v179, s98
	v_lshlrev_b32_e32 v177, 4, v176
	s_lshl_b32 s99, s98, 11
	v_add_u32_e32 v177, s99, v177
	v_lshlrev_b32_e32 v180, 5, v176
	v_add_u32_e32 v181, 0x1000, v180
	global_load_dwordx4 v[160:163], v181, s[100:101]
	global_load_dwordx4 v[164:167], v181, s[100:101] offset:16
	global_load_dwordx4 v[168:171], v181, s[100:101] offset:2048
	global_load_dwordx4 v[172:175], v181, s[100:101] offset:2064
	v_mov_b32_e32 v182, 0x358637bd
	v_lshlrev_b32_e32 v237, 2, v179
	v_add_u32_e32 v237, 0x10000, v237
	s_and_b32 s99, s98, 3
	s_cmp_eq_u32 s99, 0
	s_cbranch_scc1 .Lmyxupd_s_3
	s_mul_i32 s100, s99, 0x7ff800
	v_add_u32_e32 v210, s100, v177
	s_mul_i32 s100, s99, 16380
	v_add_u32_e32 v211, s100, v237
	v_add_u32_e32 v178, 0x1800000, v177
	v_add_u32_e32 v181, 0x9e00000, v177
	global_load_dwordx4 v[0:3], v178, s[78:79]
	global_load_dwordx4 v[4:7], v178, s[78:79] offset:1024
	global_load_dwordx4 v[8:11], v181, s[78:79]
	global_load_dwordx4 v[12:15], v181, s[78:79] offset:1024
	v_add_u32_e32 v178, 0x1c00000, v177
	v_add_u32_e32 v181, 0xa200000, v177
	global_load_dwordx4 v[16:19], v178, s[78:79]
	global_load_dwordx4 v[20:23], v178, s[78:79] offset:1024
	global_load_dwordx4 v[24:27], v181, s[78:79]
	global_load_dwordx4 v[28:31], v181, s[78:79] offset:1024
	v_add_u32_e32 v178, 0x2000000, v177
	v_add_u32_e32 v181, 0xa600000, v177
	global_load_dwordx4 v[32:35], v178, s[78:79]
	global_load_dwordx4 v[36:39], v178, s[78:79] offset:1024
	global_load_dwordx4 v[40:43], v181, s[78:79]
	global_load_dwordx4 v[44:47], v181, s[78:79] offset:1024
	v_add_u32_e32 v178, 0x2400000, v177
	v_add_u32_e32 v181, 0xaa00000, v177
	global_load_dwordx4 v[48:51], v178, s[78:79]
	global_load_dwordx4 v[52:55], v178, s[78:79] offset:1024
	global_load_dwordx4 v[56:59], v181, s[78:79]
	global_load_dwordx4 v[60:63], v181, s[78:79] offset:1024
	v_add_u32_e32 v178, 0x2800000, v177
	v_add_u32_e32 v181, 0xae00000, v177
	global_load_dwordx4 v[64:67], v178, s[78:79]
	global_load_dwordx4 v[68:71], v178, s[78:79] offset:1024
	global_load_dwordx4 v[72:75], v181, s[78:79]
	global_load_dwordx4 v[76:79], v181, s[78:79] offset:1024
	v_add_u32_e32 v178, 0x2c00000, v177
	v_add_u32_e32 v181, 0xb200000, v177
	global_load_dwordx4 v[80:83], v178, s[78:79]
	global_load_dwordx4 v[84:87], v178, s[78:79] offset:1024
	global_load_dwordx4 v[88:91], v181, s[78:79]
	global_load_dwordx4 v[92:95], v181, s[78:79] offset:1024
	v_add_u32_e32 v178, 0x3000000, v177
	v_add_u32_e32 v181, 0xb600000, v177
	global_load_dwordx4 v[96:99], v178, s[78:79]
	global_load_dwordx4 v[100:103], v178, s[78:79] offset:1024
	global_load_dwordx4 v[104:107], v181, s[78:79]
	global_load_dwordx4 v[108:111], v181, s[78:79] offset:1024
	v_add_u32_e32 v178, 0x3400000, v177
	v_add_u32_e32 v181, 0xba00000, v177
	global_load_dwordx4 v[112:115], v178, s[78:79]
	global_load_dwordx4 v[116:119], v178, s[78:79] offset:1024
	global_load_dwordx4 v[120:123], v181, s[78:79]
	global_load_dwordx4 v[124:127], v181, s[78:79] offset:1024
	v_add_u32_e32 v178, 0x1800000, v210
	v_add_u32_e32 v181, 0x9e00000, v210
	global_load_dwordx4 v[128:131], v178, s[78:79]
	global_load_dwordx4 v[132:135], v178, s[78:79] offset:1024
	global_load_dwordx4 v[136:139], v181, s[78:79]
	global_load_dwordx4 v[140:143], v181, s[78:79] offset:1024
	v_add_u32_e32 v178, 0x1c00000, v210
	v_add_u32_e32 v181, 0xa200000, v210
	global_load_dwordx4 v[144:147], v178, s[78:79]
	global_load_dwordx4 v[148:151], v178, s[78:79] offset:1024
	global_load_dwordx4 v[152:155], v181, s[78:79]
	global_load_dwordx4 v[156:159], v181, s[78:79] offset:1024
	s_waitcnt vmcnt(36)
	v_lshlrev_b32_e32 v194, 16, v0
	v_and_b32_e32 v195, 0xffff0000, v0
	v_lshlrev_b32_e32 v196, 16, v1
	v_and_b32_e32 v197, 0xffff0000, v1
	v_lshlrev_b32_e32 v198, 16, v2
	v_and_b32_e32 v199, 0xffff0000, v2
	v_lshlrev_b32_e32 v200, 16, v3
	v_and_b32_e32 v201, 0xffff0000, v3
	v_lshlrev_b32_e32 v202, 16, v4
	v_and_b32_e32 v203, 0xffff0000, v4
	v_lshlrev_b32_e32 v204, 16, v5
	v_and_b32_e32 v205, 0xffff0000, v5
	v_lshlrev_b32_e32 v206, 16, v6
	v_and_b32_e32 v207, 0xffff0000, v6
	v_lshlrev_b32_e32 v208, 16, v7
	v_and_b32_e32 v209, 0xffff0000, v7
	v_lshlrev_b32_e32 v216, 16, v8
	v_and_b32_e32 v217, 0xffff0000, v8
	v_lshlrev_b32_e32 v218, 16, v9
	v_and_b32_e32 v219, 0xffff0000, v9
	v_lshlrev_b32_e32 v220, 16, v10
	v_and_b32_e32 v221, 0xffff0000, v10
	v_lshlrev_b32_e32 v222, 16, v11
	v_and_b32_e32 v223, 0xffff0000, v11
	v_lshlrev_b32_e32 v224, 16, v12
	v_and_b32_e32 v225, 0xffff0000, v12
	v_lshlrev_b32_e32 v226, 16, v13
	v_and_b32_e32 v227, 0xffff0000, v13
	v_lshlrev_b32_e32 v228, 16, v14
	v_and_b32_e32 v229, 0xffff0000, v14
	v_lshlrev_b32_e32 v230, 16, v15
	v_and_b32_e32 v231, 0xffff0000, v15
	v_pk_mul_f32 v[252:253], v[216:217], v[216:217]
	v_pk_mul_f32 v[254:255], v[218:219], v[218:219]
	v_pk_fma_f32 v[252:253], v[220:221], v[220:221], v[252:253]
	v_pk_fma_f32 v[254:255], v[222:223], v[222:223], v[254:255]
	v_pk_fma_f32 v[252:253], v[224:225], v[224:225], v[252:253]
	v_pk_fma_f32 v[254:255], v[226:227], v[226:227], v[254:255]
	v_pk_fma_f32 v[252:253], v[228:229], v[228:229], v[252:253]
	v_pk_fma_f32 v[254:255], v[230:231], v[230:231], v[254:255]
	v_pk_add_f32 v[252:253], v[252:253], v[254:255]
	s_nop 0
	v_add_f32_e32 v183, v252, v253
	s_nop 1
	v_add_f32_dpp v183, v183, v183 quad_perm:[1,0,3,2] row_mask:0xf bank_mask:0xf bound_ctrl:1
	s_nop 1
	v_add_f32_dpp v183, v183, v183 quad_perm:[2,3,0,1] row_mask:0xf bank_mask:0xf bound_ctrl:1
	s_nop 1
	v_add_f32_dpp v183, v183, v183 row_half_mirror row_mask:0xf bank_mask:0xf bound_ctrl:1
	s_nop 1
	v_add_f32_dpp v183, v183, v183 row_mirror row_mask:0xf bank_mask:0xf bound_ctrl:1
	s_nop 1
	v_readlane_b32 s98, v183, 0
	v_readlane_b32 s99, v183, 16
	v_readlane_b32 s100, v183, 32
	v_readlane_b32 s101, v183, 48
	s_nop 1
	v_mov_b32_e32 v183, s98
	v_add_f32_e32 v183, s99, v183
	v_add_f32_e32 v183, s100, v183
	v_add_f32_e32 v183, s101, v183
	v_fmamk_f32 v183, v183, 0x3a800000, v182
	v_cmp_gt_f32_e32 vcc, 0x800000, v183
	v_mul_f32_e32 v181, 0x4b800000, v183
	s_nop 1
	v_cndmask_b32_e32 v183, v183, v181, vcc
	v_rsq_f32_e32 v183, v183
	s_nop 0
	v_mul_f32_e32 v181, 0x45800000, v183
	v_cndmask_b32_e32 v184, v183, v181, vcc
	v_mov_b32_e32 v185, v184
	v_pk_mul_f32 v[216:217], v[216:217], v[184:185]
	v_pk_mul_f32 v[218:219], v[218:219], v[184:185]
	v_pk_mul_f32 v[220:221], v[220:221], v[184:185]
	v_pk_mul_f32 v[222:223], v[222:223], v[184:185]
	v_pk_mul_f32 v[224:225], v[224:225], v[184:185]
	v_pk_mul_f32 v[226:227], v[226:227], v[184:185]
	v_pk_mul_f32 v[228:229], v[228:229], v[184:185]
	v_pk_mul_f32 v[230:231], v[230:231], v[184:185]
	v_pk_fma_f32 v[194:195], v[216:217], v[160:161], v[194:195]
	v_pk_fma_f32 v[196:197], v[218:219], v[162:163], v[196:197]
	v_pk_fma_f32 v[198:199], v[220:221], v[164:165], v[198:199]
	v_pk_fma_f32 v[200:201], v[222:223], v[166:167], v[200:201]
	v_pk_fma_f32 v[202:203], v[224:225], v[168:169], v[202:203]
	v_pk_fma_f32 v[204:205], v[226:227], v[170:171], v[204:205]
	v_pk_fma_f32 v[206:207], v[228:229], v[172:173], v[206:207]
	v_pk_fma_f32 v[208:209], v[230:231], v[174:175], v[208:209]
	v_pk_mul_f32 v[252:253], v[194:195], v[194:195]
	v_pk_mul_f32 v[254:255], v[196:197], v[196:197]
	v_pk_fma_f32 v[252:253], v[198:199], v[198:199], v[252:253]
	v_pk_fma_f32 v[254:255], v[200:201], v[200:201], v[254:255]
	v_pk_fma_f32 v[252:253], v[202:203], v[202:203], v[252:253]
	v_pk_fma_f32 v[254:255], v[204:205], v[204:205], v[254:255]
	v_pk_fma_f32 v[252:253], v[206:207], v[206:207], v[252:253]
	v_pk_fma_f32 v[254:255], v[208:209], v[208:209], v[254:255]
	v_pk_add_f32 v[252:253], v[252:253], v[254:255]
	s_nop 0
	v_add_f32_e32 v183, v252, v253
	s_nop 1
	v_add_f32_dpp v183, v183, v183 quad_perm:[1,0,3,2] row_mask:0xf bank_mask:0xf bound_ctrl:1
	s_nop 1
	v_add_f32_dpp v183, v183, v183 quad_perm:[2,3,0,1] row_mask:0xf bank_mask:0xf bound_ctrl:1
	s_nop 1
	v_add_f32_dpp v183, v183, v183 row_half_mirror row_mask:0xf bank_mask:0xf bound_ctrl:1
	s_nop 1
	v_add_f32_dpp v183, v183, v183 row_mirror row_mask:0xf bank_mask:0xf bound_ctrl:1
	s_nop 1
	v_readlane_b32 s98, v183, 0
	v_readlane_b32 s99, v183, 16
	v_readlane_b32 s100, v183, 32
	v_readlane_b32 s101, v183, 48
	s_nop 1
	v_mov_b32_e32 v183, s98
	v_add_f32_e32 v183, s99, v183
	v_add_f32_e32 v183, s100, v183
	v_add_f32_e32 v183, s101, v183
	v_fmamk_f32 v183, v183, 0x3a800000, v182
	v_cmp_gt_f32_e32 vcc, 0x800000, v183
	v_mul_f32_e32 v181, 0x4b800000, v183
	s_nop 1
	v_cndmask_b32_e32 v183, v183, v181, vcc
	v_rsq_f32_e32 v183, v183
	s_nop 0
	v_mul_f32_e32 v181, 0x45800000, v183
	v_cndmask_b32_e32 v184, v183, v181, vcc
	v_mov_b32_e32 v185, v184
	v_cvt_pk_bf16_f32 v0, v194, v195
	v_cvt_pk_bf16_f32 v1, v196, v197
	v_cvt_pk_bf16_f32 v2, v198, v199
	v_cvt_pk_bf16_f32 v3, v200, v201
	v_cvt_pk_bf16_f32 v4, v202, v203
	v_cvt_pk_bf16_f32 v5, v204, v205
	v_cvt_pk_bf16_f32 v6, v206, v207
	v_cvt_pk_bf16_f32 v7, v208, v209
	v_add_u32_e32 v181, 0x1800000, v177
	global_store_dwordx4 v181, v[0:3], s[78:79]
	global_store_dwordx4 v181, v[4:7], s[78:79] offset:1024
	v_add_u32_e32 v236, 0x0, v237
	s_mov_b64 exec, 1
	global_store_dword v236, v184, s[78:79]
	s_mov_b64 exec, -1
	s_waitcnt vmcnt(32)
	v_lshlrev_b32_e32 v194, 16, v16
	v_and_b32_e32 v195, 0xffff0000, v16
	v_lshlrev_b32_e32 v196, 16, v17
	v_and_b32_e32 v197, 0xffff0000, v17
	v_lshlrev_b32_e32 v198, 16, v18
	v_and_b32_e32 v199, 0xffff0000, v18
	v_lshlrev_b32_e32 v200, 16, v19
	v_and_b32_e32 v201, 0xffff0000, v19
	v_lshlrev_b32_e32 v202, 16, v20
	v_and_b32_e32 v203, 0xffff0000, v20
	v_lshlrev_b32_e32 v204, 16, v21
	v_and_b32_e32 v205, 0xffff0000, v21
	v_lshlrev_b32_e32 v206, 16, v22
	v_and_b32_e32 v207, 0xffff0000, v22
	v_lshlrev_b32_e32 v208, 16, v23
	v_and_b32_e32 v209, 0xffff0000, v23
	v_lshlrev_b32_e32 v216, 16, v24
	v_and_b32_e32 v217, 0xffff0000, v24
	v_lshlrev_b32_e32 v218, 16, v25
	v_and_b32_e32 v219, 0xffff0000, v25
	v_lshlrev_b32_e32 v220, 16, v26
	v_and_b32_e32 v221, 0xffff0000, v26
	v_lshlrev_b32_e32 v222, 16, v27
	v_and_b32_e32 v223, 0xffff0000, v27
	v_lshlrev_b32_e32 v224, 16, v28
	v_and_b32_e32 v225, 0xffff0000, v28
	v_lshlrev_b32_e32 v226, 16, v29
	v_and_b32_e32 v227, 0xffff0000, v29
	v_lshlrev_b32_e32 v228, 16, v30
	v_and_b32_e32 v229, 0xffff0000, v30
	v_lshlrev_b32_e32 v230, 16, v31
	v_and_b32_e32 v231, 0xffff0000, v31
	v_pk_mul_f32 v[252:253], v[216:217], v[216:217]
	v_pk_mul_f32 v[254:255], v[218:219], v[218:219]
	v_pk_fma_f32 v[252:253], v[220:221], v[220:221], v[252:253]
	v_pk_fma_f32 v[254:255], v[222:223], v[222:223], v[254:255]
	v_pk_fma_f32 v[252:253], v[224:225], v[224:225], v[252:253]
	v_pk_fma_f32 v[254:255], v[226:227], v[226:227], v[254:255]
	v_pk_fma_f32 v[252:253], v[228:229], v[228:229], v[252:253]
	v_pk_fma_f32 v[254:255], v[230:231], v[230:231], v[254:255]
	v_pk_add_f32 v[252:253], v[252:253], v[254:255]
	s_nop 0
	v_add_f32_e32 v183, v252, v253
	s_nop 1
	v_add_f32_dpp v183, v183, v183 quad_perm:[1,0,3,2] row_mask:0xf bank_mask:0xf bound_ctrl:1
	s_nop 1
	v_add_f32_dpp v183, v183, v183 quad_perm:[2,3,0,1] row_mask:0xf bank_mask:0xf bound_ctrl:1
	s_nop 1
	v_add_f32_dpp v183, v183, v183 row_half_mirror row_mask:0xf bank_mask:0xf bound_ctrl:1
	s_nop 1
	v_add_f32_dpp v183, v183, v183 row_mirror row_mask:0xf bank_mask:0xf bound_ctrl:1
	s_nop 1
	v_readlane_b32 s98, v183, 0
	v_readlane_b32 s99, v183, 16
	v_readlane_b32 s100, v183, 32
	v_readlane_b32 s101, v183, 48
	s_nop 1
	v_mov_b32_e32 v183, s98
	v_add_f32_e32 v183, s99, v183
	v_add_f32_e32 v183, s100, v183
	v_add_f32_e32 v183, s101, v183
	v_fmamk_f32 v183, v183, 0x3a800000, v182
	v_cmp_gt_f32_e32 vcc, 0x800000, v183
	v_mul_f32_e32 v181, 0x4b800000, v183
	s_nop 1
	v_cndmask_b32_e32 v183, v183, v181, vcc
	v_rsq_f32_e32 v183, v183
	s_nop 0
	v_mul_f32_e32 v181, 0x45800000, v183
	v_cndmask_b32_e32 v184, v183, v181, vcc
	v_mov_b32_e32 v185, v184
	v_pk_mul_f32 v[216:217], v[216:217], v[184:185]
	v_pk_mul_f32 v[218:219], v[218:219], v[184:185]
	v_pk_mul_f32 v[220:221], v[220:221], v[184:185]
	v_pk_mul_f32 v[222:223], v[222:223], v[184:185]
	v_pk_mul_f32 v[224:225], v[224:225], v[184:185]
	v_pk_mul_f32 v[226:227], v[226:227], v[184:185]
	v_pk_mul_f32 v[228:229], v[228:229], v[184:185]
	v_pk_mul_f32 v[230:231], v[230:231], v[184:185]
	v_pk_fma_f32 v[194:195], v[216:217], v[160:161], v[194:195]
	v_pk_fma_f32 v[196:197], v[218:219], v[162:163], v[196:197]
	v_pk_fma_f32 v[198:199], v[220:221], v[164:165], v[198:199]
	v_pk_fma_f32 v[200:201], v[222:223], v[166:167], v[200:201]
	v_pk_fma_f32 v[202:203], v[224:225], v[168:169], v[202:203]
	v_pk_fma_f32 v[204:205], v[226:227], v[170:171], v[204:205]
	v_pk_fma_f32 v[206:207], v[228:229], v[172:173], v[206:207]
	v_pk_fma_f32 v[208:209], v[230:231], v[174:175], v[208:209]
	v_pk_mul_f32 v[252:253], v[194:195], v[194:195]
	v_pk_mul_f32 v[254:255], v[196:197], v[196:197]
	v_pk_fma_f32 v[252:253], v[198:199], v[198:199], v[252:253]
	v_pk_fma_f32 v[254:255], v[200:201], v[200:201], v[254:255]
	v_pk_fma_f32 v[252:253], v[202:203], v[202:203], v[252:253]
	v_pk_fma_f32 v[254:255], v[204:205], v[204:205], v[254:255]
	v_pk_fma_f32 v[252:253], v[206:207], v[206:207], v[252:253]
	v_pk_fma_f32 v[254:255], v[208:209], v[208:209], v[254:255]
	v_pk_add_f32 v[252:253], v[252:253], v[254:255]
	s_nop 0
	v_add_f32_e32 v183, v252, v253
	s_nop 1
	v_add_f32_dpp v183, v183, v183 quad_perm:[1,0,3,2] row_mask:0xf bank_mask:0xf bound_ctrl:1
	s_nop 1
	v_add_f32_dpp v183, v183, v183 quad_perm:[2,3,0,1] row_mask:0xf bank_mask:0xf bound_ctrl:1
	s_nop 1
	v_add_f32_dpp v183, v183, v183 row_half_mirror row_mask:0xf bank_mask:0xf bound_ctrl:1
	s_nop 1
	v_add_f32_dpp v183, v183, v183 row_mirror row_mask:0xf bank_mask:0xf bound_ctrl:1
	s_nop 1
	v_readlane_b32 s98, v183, 0
	v_readlane_b32 s99, v183, 16
	v_readlane_b32 s100, v183, 32
	v_readlane_b32 s101, v183, 48
	s_nop 1
	v_mov_b32_e32 v183, s98
	v_add_f32_e32 v183, s99, v183
	v_add_f32_e32 v183, s100, v183
	v_add_f32_e32 v183, s101, v183
	v_fmamk_f32 v183, v183, 0x3a800000, v182
	v_cmp_gt_f32_e32 vcc, 0x800000, v183
	v_mul_f32_e32 v181, 0x4b800000, v183
	s_nop 1
	v_cndmask_b32_e32 v183, v183, v181, vcc
	v_rsq_f32_e32 v183, v183
	s_nop 0
	v_mul_f32_e32 v181, 0x45800000, v183
	v_cndmask_b32_e32 v184, v183, v181, vcc
	v_mov_b32_e32 v185, v184
	v_cvt_pk_bf16_f32 v16, v194, v195
	v_cvt_pk_bf16_f32 v17, v196, v197
	v_cvt_pk_bf16_f32 v18, v198, v199
	v_cvt_pk_bf16_f32 v19, v200, v201
	v_cvt_pk_bf16_f32 v20, v202, v203
	v_cvt_pk_bf16_f32 v21, v204, v205
	v_cvt_pk_bf16_f32 v22, v206, v207
	v_cvt_pk_bf16_f32 v23, v208, v209
	v_add_u32_e32 v181, 0x1c00000, v177
	global_store_dwordx4 v181, v[16:19], s[78:79]
	global_store_dwordx4 v181, v[20:23], s[78:79] offset:1024
	v_add_u32_e32 v236, 0x2000, v237
	s_mov_b64 exec, 1
	global_store_dword v236, v184, s[78:79]
	s_mov_b64 exec, -1
	s_waitcnt vmcnt(28)
	v_lshlrev_b32_e32 v194, 16, v32
	v_and_b32_e32 v195, 0xffff0000, v32
	v_lshlrev_b32_e32 v196, 16, v33
	v_and_b32_e32 v197, 0xffff0000, v33
	v_lshlrev_b32_e32 v198, 16, v34
	v_and_b32_e32 v199, 0xffff0000, v34
	v_lshlrev_b32_e32 v200, 16, v35
	v_and_b32_e32 v201, 0xffff0000, v35
	v_lshlrev_b32_e32 v202, 16, v36
	v_and_b32_e32 v203, 0xffff0000, v36
	v_lshlrev_b32_e32 v204, 16, v37
	v_and_b32_e32 v205, 0xffff0000, v37
	v_lshlrev_b32_e32 v206, 16, v38
	v_and_b32_e32 v207, 0xffff0000, v38
	v_lshlrev_b32_e32 v208, 16, v39
	v_and_b32_e32 v209, 0xffff0000, v39
	v_lshlrev_b32_e32 v216, 16, v40
	v_and_b32_e32 v217, 0xffff0000, v40
	v_lshlrev_b32_e32 v218, 16, v41
	v_and_b32_e32 v219, 0xffff0000, v41
	v_lshlrev_b32_e32 v220, 16, v42
	v_and_b32_e32 v221, 0xffff0000, v42
	v_lshlrev_b32_e32 v222, 16, v43
	v_and_b32_e32 v223, 0xffff0000, v43
	v_lshlrev_b32_e32 v224, 16, v44
	v_and_b32_e32 v225, 0xffff0000, v44
	v_lshlrev_b32_e32 v226, 16, v45
	v_and_b32_e32 v227, 0xffff0000, v45
	v_lshlrev_b32_e32 v228, 16, v46
	v_and_b32_e32 v229, 0xffff0000, v46
	v_lshlrev_b32_e32 v230, 16, v47
	v_and_b32_e32 v231, 0xffff0000, v47
	v_pk_mul_f32 v[252:253], v[216:217], v[216:217]
	v_pk_mul_f32 v[254:255], v[218:219], v[218:219]
	v_pk_fma_f32 v[252:253], v[220:221], v[220:221], v[252:253]
	v_pk_fma_f32 v[254:255], v[222:223], v[222:223], v[254:255]
	v_pk_fma_f32 v[252:253], v[224:225], v[224:225], v[252:253]
	v_pk_fma_f32 v[254:255], v[226:227], v[226:227], v[254:255]
	v_pk_fma_f32 v[252:253], v[228:229], v[228:229], v[252:253]
	v_pk_fma_f32 v[254:255], v[230:231], v[230:231], v[254:255]
	v_pk_add_f32 v[252:253], v[252:253], v[254:255]
	s_nop 0
	v_add_f32_e32 v183, v252, v253
	s_nop 1
	v_add_f32_dpp v183, v183, v183 quad_perm:[1,0,3,2] row_mask:0xf bank_mask:0xf bound_ctrl:1
	s_nop 1
	v_add_f32_dpp v183, v183, v183 quad_perm:[2,3,0,1] row_mask:0xf bank_mask:0xf bound_ctrl:1
	s_nop 1
	v_add_f32_dpp v183, v183, v183 row_half_mirror row_mask:0xf bank_mask:0xf bound_ctrl:1
	s_nop 1
	v_add_f32_dpp v183, v183, v183 row_mirror row_mask:0xf bank_mask:0xf bound_ctrl:1
	s_nop 1
	v_readlane_b32 s98, v183, 0
	v_readlane_b32 s99, v183, 16
	v_readlane_b32 s100, v183, 32
	v_readlane_b32 s101, v183, 48
	s_nop 1
	v_mov_b32_e32 v183, s98
	v_add_f32_e32 v183, s99, v183
	v_add_f32_e32 v183, s100, v183
	v_add_f32_e32 v183, s101, v183
	v_fmamk_f32 v183, v183, 0x3a800000, v182
	v_cmp_gt_f32_e32 vcc, 0x800000, v183
	v_mul_f32_e32 v181, 0x4b800000, v183
	s_nop 1
	v_cndmask_b32_e32 v183, v183, v181, vcc
	v_rsq_f32_e32 v183, v183
	s_nop 0
	v_mul_f32_e32 v181, 0x45800000, v183
	v_cndmask_b32_e32 v184, v183, v181, vcc
	v_mov_b32_e32 v185, v184
	v_pk_mul_f32 v[216:217], v[216:217], v[184:185]
	v_pk_mul_f32 v[218:219], v[218:219], v[184:185]
	v_pk_mul_f32 v[220:221], v[220:221], v[184:185]
	v_pk_mul_f32 v[222:223], v[222:223], v[184:185]
	v_pk_mul_f32 v[224:225], v[224:225], v[184:185]
	v_pk_mul_f32 v[226:227], v[226:227], v[184:185]
	v_pk_mul_f32 v[228:229], v[228:229], v[184:185]
	v_pk_mul_f32 v[230:231], v[230:231], v[184:185]
	v_pk_fma_f32 v[194:195], v[216:217], v[160:161], v[194:195]
	v_pk_fma_f32 v[196:197], v[218:219], v[162:163], v[196:197]
	v_pk_fma_f32 v[198:199], v[220:221], v[164:165], v[198:199]
	v_pk_fma_f32 v[200:201], v[222:223], v[166:167], v[200:201]
	v_pk_fma_f32 v[202:203], v[224:225], v[168:169], v[202:203]
	v_pk_fma_f32 v[204:205], v[226:227], v[170:171], v[204:205]
	v_pk_fma_f32 v[206:207], v[228:229], v[172:173], v[206:207]
	v_pk_fma_f32 v[208:209], v[230:231], v[174:175], v[208:209]
	v_pk_mul_f32 v[252:253], v[194:195], v[194:195]
	v_pk_mul_f32 v[254:255], v[196:197], v[196:197]
	v_pk_fma_f32 v[252:253], v[198:199], v[198:199], v[252:253]
	v_pk_fma_f32 v[254:255], v[200:201], v[200:201], v[254:255]
	v_pk_fma_f32 v[252:253], v[202:203], v[202:203], v[252:253]
	v_pk_fma_f32 v[254:255], v[204:205], v[204:205], v[254:255]
	v_pk_fma_f32 v[252:253], v[206:207], v[206:207], v[252:253]
	v_pk_fma_f32 v[254:255], v[208:209], v[208:209], v[254:255]
	v_pk_add_f32 v[252:253], v[252:253], v[254:255]
	s_nop 0
	v_add_f32_e32 v183, v252, v253
	s_nop 1
	v_add_f32_dpp v183, v183, v183 quad_perm:[1,0,3,2] row_mask:0xf bank_mask:0xf bound_ctrl:1
	s_nop 1
	v_add_f32_dpp v183, v183, v183 quad_perm:[2,3,0,1] row_mask:0xf bank_mask:0xf bound_ctrl:1
	s_nop 1
	v_add_f32_dpp v183, v183, v183 row_half_mirror row_mask:0xf bank_mask:0xf bound_ctrl:1
	s_nop 1
	v_add_f32_dpp v183, v183, v183 row_mirror row_mask:0xf bank_mask:0xf bound_ctrl:1
	s_nop 1
	v_readlane_b32 s98, v183, 0
	v_readlane_b32 s99, v183, 16
	v_readlane_b32 s100, v183, 32
	v_readlane_b32 s101, v183, 48
	s_nop 1
	v_mov_b32_e32 v183, s98
	v_add_f32_e32 v183, s99, v183
	v_add_f32_e32 v183, s100, v183
	v_add_f32_e32 v183, s101, v183
	v_fmamk_f32 v183, v183, 0x3a800000, v182
	v_cmp_gt_f32_e32 vcc, 0x800000, v183
	v_mul_f32_e32 v181, 0x4b800000, v183
	s_nop 1
	v_cndmask_b32_e32 v183, v183, v181, vcc
	v_rsq_f32_e32 v183, v183
	s_nop 0
	v_mul_f32_e32 v181, 0x45800000, v183
	v_cndmask_b32_e32 v184, v183, v181, vcc
	v_mov_b32_e32 v185, v184
	v_cvt_pk_bf16_f32 v32, v194, v195
	v_cvt_pk_bf16_f32 v33, v196, v197
	v_cvt_pk_bf16_f32 v34, v198, v199
	v_cvt_pk_bf16_f32 v35, v200, v201
	v_cvt_pk_bf16_f32 v36, v202, v203
	v_cvt_pk_bf16_f32 v37, v204, v205
	v_cvt_pk_bf16_f32 v38, v206, v207
	v_cvt_pk_bf16_f32 v39, v208, v209
	v_add_u32_e32 v181, 0x2000000, v177
	global_store_dwordx4 v181, v[32:35], s[78:79]
	global_store_dwordx4 v181, v[36:39], s[78:79] offset:1024
	v_add_u32_e32 v236, 0x4000, v237
	s_mov_b64 exec, 1
	global_store_dword v236, v184, s[78:79]
	s_mov_b64 exec, -1
	s_waitcnt vmcnt(24)
	v_lshlrev_b32_e32 v194, 16, v48
	v_and_b32_e32 v195, 0xffff0000, v48
	v_lshlrev_b32_e32 v196, 16, v49
	v_and_b32_e32 v197, 0xffff0000, v49
	v_lshlrev_b32_e32 v198, 16, v50
	v_and_b32_e32 v199, 0xffff0000, v50
	v_lshlrev_b32_e32 v200, 16, v51
	v_and_b32_e32 v201, 0xffff0000, v51
	v_lshlrev_b32_e32 v202, 16, v52
	v_and_b32_e32 v203, 0xffff0000, v52
	v_lshlrev_b32_e32 v204, 16, v53
	v_and_b32_e32 v205, 0xffff0000, v53
	v_lshlrev_b32_e32 v206, 16, v54
	v_and_b32_e32 v207, 0xffff0000, v54
	v_lshlrev_b32_e32 v208, 16, v55
	v_and_b32_e32 v209, 0xffff0000, v55
	v_lshlrev_b32_e32 v216, 16, v56
	v_and_b32_e32 v217, 0xffff0000, v56
	v_lshlrev_b32_e32 v218, 16, v57
	v_and_b32_e32 v219, 0xffff0000, v57
	v_lshlrev_b32_e32 v220, 16, v58
	v_and_b32_e32 v221, 0xffff0000, v58
	v_lshlrev_b32_e32 v222, 16, v59
	v_and_b32_e32 v223, 0xffff0000, v59
	v_lshlrev_b32_e32 v224, 16, v60
	v_and_b32_e32 v225, 0xffff0000, v60
	v_lshlrev_b32_e32 v226, 16, v61
	v_and_b32_e32 v227, 0xffff0000, v61
	v_lshlrev_b32_e32 v228, 16, v62
	v_and_b32_e32 v229, 0xffff0000, v62
	v_lshlrev_b32_e32 v230, 16, v63
	v_and_b32_e32 v231, 0xffff0000, v63
	v_pk_mul_f32 v[252:253], v[216:217], v[216:217]
	v_pk_mul_f32 v[254:255], v[218:219], v[218:219]
	v_pk_fma_f32 v[252:253], v[220:221], v[220:221], v[252:253]
	v_pk_fma_f32 v[254:255], v[222:223], v[222:223], v[254:255]
	v_pk_fma_f32 v[252:253], v[224:225], v[224:225], v[252:253]
	v_pk_fma_f32 v[254:255], v[226:227], v[226:227], v[254:255]
	v_pk_fma_f32 v[252:253], v[228:229], v[228:229], v[252:253]
	v_pk_fma_f32 v[254:255], v[230:231], v[230:231], v[254:255]
	v_pk_add_f32 v[252:253], v[252:253], v[254:255]
	s_nop 0
	v_add_f32_e32 v183, v252, v253
	s_nop 1
	v_add_f32_dpp v183, v183, v183 quad_perm:[1,0,3,2] row_mask:0xf bank_mask:0xf bound_ctrl:1
	s_nop 1
	v_add_f32_dpp v183, v183, v183 quad_perm:[2,3,0,1] row_mask:0xf bank_mask:0xf bound_ctrl:1
	s_nop 1
	v_add_f32_dpp v183, v183, v183 row_half_mirror row_mask:0xf bank_mask:0xf bound_ctrl:1
	s_nop 1
	v_add_f32_dpp v183, v183, v183 row_mirror row_mask:0xf bank_mask:0xf bound_ctrl:1
	s_nop 1
	v_readlane_b32 s98, v183, 0
	v_readlane_b32 s99, v183, 16
	v_readlane_b32 s100, v183, 32
	v_readlane_b32 s101, v183, 48
	s_nop 1
	v_mov_b32_e32 v183, s98
	v_add_f32_e32 v183, s99, v183
	v_add_f32_e32 v183, s100, v183
	v_add_f32_e32 v183, s101, v183
	v_fmamk_f32 v183, v183, 0x3a800000, v182
	v_cmp_gt_f32_e32 vcc, 0x800000, v183
	v_mul_f32_e32 v181, 0x4b800000, v183
	s_nop 1
	v_cndmask_b32_e32 v183, v183, v181, vcc
	v_rsq_f32_e32 v183, v183
	s_nop 0
	v_mul_f32_e32 v181, 0x45800000, v183
	v_cndmask_b32_e32 v184, v183, v181, vcc
	v_mov_b32_e32 v185, v184
	v_pk_mul_f32 v[216:217], v[216:217], v[184:185]
	v_pk_mul_f32 v[218:219], v[218:219], v[184:185]
	v_pk_mul_f32 v[220:221], v[220:221], v[184:185]
	v_pk_mul_f32 v[222:223], v[222:223], v[184:185]
	v_pk_mul_f32 v[224:225], v[224:225], v[184:185]
	v_pk_mul_f32 v[226:227], v[226:227], v[184:185]
	v_pk_mul_f32 v[228:229], v[228:229], v[184:185]
	v_pk_mul_f32 v[230:231], v[230:231], v[184:185]
	v_pk_fma_f32 v[194:195], v[216:217], v[160:161], v[194:195]
	v_pk_fma_f32 v[196:197], v[218:219], v[162:163], v[196:197]
	v_pk_fma_f32 v[198:199], v[220:221], v[164:165], v[198:199]
	v_pk_fma_f32 v[200:201], v[222:223], v[166:167], v[200:201]
	v_pk_fma_f32 v[202:203], v[224:225], v[168:169], v[202:203]
	v_pk_fma_f32 v[204:205], v[226:227], v[170:171], v[204:205]
	v_pk_fma_f32 v[206:207], v[228:229], v[172:173], v[206:207]
	v_pk_fma_f32 v[208:209], v[230:231], v[174:175], v[208:209]
	v_pk_mul_f32 v[252:253], v[194:195], v[194:195]
	v_pk_mul_f32 v[254:255], v[196:197], v[196:197]
	v_pk_fma_f32 v[252:253], v[198:199], v[198:199], v[252:253]
	v_pk_fma_f32 v[254:255], v[200:201], v[200:201], v[254:255]
	v_pk_fma_f32 v[252:253], v[202:203], v[202:203], v[252:253]
	v_pk_fma_f32 v[254:255], v[204:205], v[204:205], v[254:255]
	v_pk_fma_f32 v[252:253], v[206:207], v[206:207], v[252:253]
	v_pk_fma_f32 v[254:255], v[208:209], v[208:209], v[254:255]
	v_pk_add_f32 v[252:253], v[252:253], v[254:255]
	s_nop 0
	v_add_f32_e32 v183, v252, v253
	s_nop 1
	v_add_f32_dpp v183, v183, v183 quad_perm:[1,0,3,2] row_mask:0xf bank_mask:0xf bound_ctrl:1
	s_nop 1
	v_add_f32_dpp v183, v183, v183 quad_perm:[2,3,0,1] row_mask:0xf bank_mask:0xf bound_ctrl:1
	s_nop 1
	v_add_f32_dpp v183, v183, v183 row_half_mirror row_mask:0xf bank_mask:0xf bound_ctrl:1
	s_nop 1
	v_add_f32_dpp v183, v183, v183 row_mirror row_mask:0xf bank_mask:0xf bound_ctrl:1
	s_nop 1
	v_readlane_b32 s98, v183, 0
	v_readlane_b32 s99, v183, 16
	v_readlane_b32 s100, v183, 32
	v_readlane_b32 s101, v183, 48
	s_nop 1
	v_mov_b32_e32 v183, s98
	v_add_f32_e32 v183, s99, v183
	v_add_f32_e32 v183, s100, v183
	v_add_f32_e32 v183, s101, v183
	v_fmamk_f32 v183, v183, 0x3a800000, v182
	v_cmp_gt_f32_e32 vcc, 0x800000, v183
	v_mul_f32_e32 v181, 0x4b800000, v183
	s_nop 1
	v_cndmask_b32_e32 v183, v183, v181, vcc
	v_rsq_f32_e32 v183, v183
	s_nop 0
	v_mul_f32_e32 v181, 0x45800000, v183
	v_cndmask_b32_e32 v184, v183, v181, vcc
	v_mov_b32_e32 v185, v184
	v_cvt_pk_bf16_f32 v48, v194, v195
	v_cvt_pk_bf16_f32 v49, v196, v197
	v_cvt_pk_bf16_f32 v50, v198, v199
	v_cvt_pk_bf16_f32 v51, v200, v201
	v_cvt_pk_bf16_f32 v52, v202, v203
	v_cvt_pk_bf16_f32 v53, v204, v205
	v_cvt_pk_bf16_f32 v54, v206, v207
	v_cvt_pk_bf16_f32 v55, v208, v209
	v_add_u32_e32 v181, 0x2400000, v177
	global_store_dwordx4 v181, v[48:51], s[78:79]
	global_store_dwordx4 v181, v[52:55], s[78:79] offset:1024
	v_add_u32_e32 v236, 0x6000, v237
	s_mov_b64 exec, 1
	global_store_dword v236, v184, s[78:79]
	s_mov_b64 exec, -1
	s_waitcnt vmcnt(20)
	v_lshlrev_b32_e32 v194, 16, v64
	v_and_b32_e32 v195, 0xffff0000, v64
	v_lshlrev_b32_e32 v196, 16, v65
	v_and_b32_e32 v197, 0xffff0000, v65
	v_lshlrev_b32_e32 v198, 16, v66
	v_and_b32_e32 v199, 0xffff0000, v66
	v_lshlrev_b32_e32 v200, 16, v67
	v_and_b32_e32 v201, 0xffff0000, v67
	v_lshlrev_b32_e32 v202, 16, v68
	v_and_b32_e32 v203, 0xffff0000, v68
	v_lshlrev_b32_e32 v204, 16, v69
	v_and_b32_e32 v205, 0xffff0000, v69
	v_lshlrev_b32_e32 v206, 16, v70
	v_and_b32_e32 v207, 0xffff0000, v70
	v_lshlrev_b32_e32 v208, 16, v71
	v_and_b32_e32 v209, 0xffff0000, v71
	v_lshlrev_b32_e32 v216, 16, v72
	v_and_b32_e32 v217, 0xffff0000, v72
	v_lshlrev_b32_e32 v218, 16, v73
	v_and_b32_e32 v219, 0xffff0000, v73
	v_lshlrev_b32_e32 v220, 16, v74
	v_and_b32_e32 v221, 0xffff0000, v74
	v_lshlrev_b32_e32 v222, 16, v75
	v_and_b32_e32 v223, 0xffff0000, v75
	v_lshlrev_b32_e32 v224, 16, v76
	v_and_b32_e32 v225, 0xffff0000, v76
	v_lshlrev_b32_e32 v226, 16, v77
	v_and_b32_e32 v227, 0xffff0000, v77
	v_lshlrev_b32_e32 v228, 16, v78
	v_and_b32_e32 v229, 0xffff0000, v78
	v_lshlrev_b32_e32 v230, 16, v79
	v_and_b32_e32 v231, 0xffff0000, v79
	v_pk_mul_f32 v[252:253], v[216:217], v[216:217]
	v_pk_mul_f32 v[254:255], v[218:219], v[218:219]
	v_pk_fma_f32 v[252:253], v[220:221], v[220:221], v[252:253]
	v_pk_fma_f32 v[254:255], v[222:223], v[222:223], v[254:255]
	v_pk_fma_f32 v[252:253], v[224:225], v[224:225], v[252:253]
	v_pk_fma_f32 v[254:255], v[226:227], v[226:227], v[254:255]
	v_pk_fma_f32 v[252:253], v[228:229], v[228:229], v[252:253]
	v_pk_fma_f32 v[254:255], v[230:231], v[230:231], v[254:255]
	v_pk_add_f32 v[252:253], v[252:253], v[254:255]
	s_nop 0
	v_add_f32_e32 v183, v252, v253
	s_nop 1
	v_add_f32_dpp v183, v183, v183 quad_perm:[1,0,3,2] row_mask:0xf bank_mask:0xf bound_ctrl:1
	s_nop 1
	v_add_f32_dpp v183, v183, v183 quad_perm:[2,3,0,1] row_mask:0xf bank_mask:0xf bound_ctrl:1
	s_nop 1
	v_add_f32_dpp v183, v183, v183 row_half_mirror row_mask:0xf bank_mask:0xf bound_ctrl:1
	s_nop 1
	v_add_f32_dpp v183, v183, v183 row_mirror row_mask:0xf bank_mask:0xf bound_ctrl:1
	s_nop 1
	v_readlane_b32 s98, v183, 0
	v_readlane_b32 s99, v183, 16
	v_readlane_b32 s100, v183, 32
	v_readlane_b32 s101, v183, 48
	s_nop 1
	v_mov_b32_e32 v183, s98
	v_add_f32_e32 v183, s99, v183
	v_add_f32_e32 v183, s100, v183
	v_add_f32_e32 v183, s101, v183
	v_fmamk_f32 v183, v183, 0x3a800000, v182
	v_cmp_gt_f32_e32 vcc, 0x800000, v183
	v_mul_f32_e32 v181, 0x4b800000, v183
	s_nop 1
	v_cndmask_b32_e32 v183, v183, v181, vcc
	v_rsq_f32_e32 v183, v183
	s_nop 0
	v_mul_f32_e32 v181, 0x45800000, v183
	v_cndmask_b32_e32 v184, v183, v181, vcc
	v_mov_b32_e32 v185, v184
	v_pk_mul_f32 v[216:217], v[216:217], v[184:185]
	v_pk_mul_f32 v[218:219], v[218:219], v[184:185]
	v_pk_mul_f32 v[220:221], v[220:221], v[184:185]
	v_pk_mul_f32 v[222:223], v[222:223], v[184:185]
	v_pk_mul_f32 v[224:225], v[224:225], v[184:185]
	v_pk_mul_f32 v[226:227], v[226:227], v[184:185]
	v_pk_mul_f32 v[228:229], v[228:229], v[184:185]
	v_pk_mul_f32 v[230:231], v[230:231], v[184:185]
	v_pk_fma_f32 v[194:195], v[216:217], v[160:161], v[194:195]
	v_pk_fma_f32 v[196:197], v[218:219], v[162:163], v[196:197]
	v_pk_fma_f32 v[198:199], v[220:221], v[164:165], v[198:199]
	v_pk_fma_f32 v[200:201], v[222:223], v[166:167], v[200:201]
	v_pk_fma_f32 v[202:203], v[224:225], v[168:169], v[202:203]
	v_pk_fma_f32 v[204:205], v[226:227], v[170:171], v[204:205]
	v_pk_fma_f32 v[206:207], v[228:229], v[172:173], v[206:207]
	v_pk_fma_f32 v[208:209], v[230:231], v[174:175], v[208:209]
	v_pk_mul_f32 v[252:253], v[194:195], v[194:195]
	v_pk_mul_f32 v[254:255], v[196:197], v[196:197]
	v_pk_fma_f32 v[252:253], v[198:199], v[198:199], v[252:253]
	v_pk_fma_f32 v[254:255], v[200:201], v[200:201], v[254:255]
	v_pk_fma_f32 v[252:253], v[202:203], v[202:203], v[252:253]
	v_pk_fma_f32 v[254:255], v[204:205], v[204:205], v[254:255]
	v_pk_fma_f32 v[252:253], v[206:207], v[206:207], v[252:253]
	v_pk_fma_f32 v[254:255], v[208:209], v[208:209], v[254:255]
	v_pk_add_f32 v[252:253], v[252:253], v[254:255]
	s_nop 0
	v_add_f32_e32 v183, v252, v253
	s_nop 1
	v_add_f32_dpp v183, v183, v183 quad_perm:[1,0,3,2] row_mask:0xf bank_mask:0xf bound_ctrl:1
	s_nop 1
	v_add_f32_dpp v183, v183, v183 quad_perm:[2,3,0,1] row_mask:0xf bank_mask:0xf bound_ctrl:1
	s_nop 1
	v_add_f32_dpp v183, v183, v183 row_half_mirror row_mask:0xf bank_mask:0xf bound_ctrl:1
	s_nop 1
	v_add_f32_dpp v183, v183, v183 row_mirror row_mask:0xf bank_mask:0xf bound_ctrl:1
	s_nop 1
	v_readlane_b32 s98, v183, 0
	v_readlane_b32 s99, v183, 16
	v_readlane_b32 s100, v183, 32
	v_readlane_b32 s101, v183, 48
	s_nop 1
	v_mov_b32_e32 v183, s98
	v_add_f32_e32 v183, s99, v183
	v_add_f32_e32 v183, s100, v183
	v_add_f32_e32 v183, s101, v183
	v_fmamk_f32 v183, v183, 0x3a800000, v182
	v_cmp_gt_f32_e32 vcc, 0x800000, v183
	v_mul_f32_e32 v181, 0x4b800000, v183
	s_nop 1
	v_cndmask_b32_e32 v183, v183, v181, vcc
	v_rsq_f32_e32 v183, v183
	s_nop 0
	v_mul_f32_e32 v181, 0x45800000, v183
	v_cndmask_b32_e32 v184, v183, v181, vcc
	v_mov_b32_e32 v185, v184
	v_cvt_pk_bf16_f32 v64, v194, v195
	v_cvt_pk_bf16_f32 v65, v196, v197
	v_cvt_pk_bf16_f32 v66, v198, v199
	v_cvt_pk_bf16_f32 v67, v200, v201
	v_cvt_pk_bf16_f32 v68, v202, v203
	v_cvt_pk_bf16_f32 v69, v204, v205
	v_cvt_pk_bf16_f32 v70, v206, v207
	v_cvt_pk_bf16_f32 v71, v208, v209
	v_add_u32_e32 v181, 0x2800000, v177
	global_store_dwordx4 v181, v[64:67], s[78:79]
	global_store_dwordx4 v181, v[68:71], s[78:79] offset:1024
	v_add_u32_e32 v236, 0x8000, v237
	s_mov_b64 exec, 1
	global_store_dword v236, v184, s[78:79]
	s_mov_b64 exec, -1
	s_waitcnt vmcnt(16)
	v_lshlrev_b32_e32 v194, 16, v80
	v_and_b32_e32 v195, 0xffff0000, v80
	v_lshlrev_b32_e32 v196, 16, v81
	v_and_b32_e32 v197, 0xffff0000, v81
	v_lshlrev_b32_e32 v198, 16, v82
	v_and_b32_e32 v199, 0xffff0000, v82
	v_lshlrev_b32_e32 v200, 16, v83
	v_and_b32_e32 v201, 0xffff0000, v83
	v_lshlrev_b32_e32 v202, 16, v84
	v_and_b32_e32 v203, 0xffff0000, v84
	v_lshlrev_b32_e32 v204, 16, v85
	v_and_b32_e32 v205, 0xffff0000, v85
	v_lshlrev_b32_e32 v206, 16, v86
	v_and_b32_e32 v207, 0xffff0000, v86
	v_lshlrev_b32_e32 v208, 16, v87
	v_and_b32_e32 v209, 0xffff0000, v87
	v_lshlrev_b32_e32 v216, 16, v88
	v_and_b32_e32 v217, 0xffff0000, v88
	v_lshlrev_b32_e32 v218, 16, v89
	v_and_b32_e32 v219, 0xffff0000, v89
	v_lshlrev_b32_e32 v220, 16, v90
	v_and_b32_e32 v221, 0xffff0000, v90
	v_lshlrev_b32_e32 v222, 16, v91
	v_and_b32_e32 v223, 0xffff0000, v91
	v_lshlrev_b32_e32 v224, 16, v92
	v_and_b32_e32 v225, 0xffff0000, v92
	v_lshlrev_b32_e32 v226, 16, v93
	v_and_b32_e32 v227, 0xffff0000, v93
	v_lshlrev_b32_e32 v228, 16, v94
	v_and_b32_e32 v229, 0xffff0000, v94
	v_lshlrev_b32_e32 v230, 16, v95
	v_and_b32_e32 v231, 0xffff0000, v95
	v_pk_mul_f32 v[252:253], v[216:217], v[216:217]
	v_pk_mul_f32 v[254:255], v[218:219], v[218:219]
	v_pk_fma_f32 v[252:253], v[220:221], v[220:221], v[252:253]
	v_pk_fma_f32 v[254:255], v[222:223], v[222:223], v[254:255]
	v_pk_fma_f32 v[252:253], v[224:225], v[224:225], v[252:253]
	v_pk_fma_f32 v[254:255], v[226:227], v[226:227], v[254:255]
	v_pk_fma_f32 v[252:253], v[228:229], v[228:229], v[252:253]
	v_pk_fma_f32 v[254:255], v[230:231], v[230:231], v[254:255]
	v_pk_add_f32 v[252:253], v[252:253], v[254:255]
	s_nop 0
	v_add_f32_e32 v183, v252, v253
	s_nop 1
	v_add_f32_dpp v183, v183, v183 quad_perm:[1,0,3,2] row_mask:0xf bank_mask:0xf bound_ctrl:1
	s_nop 1
	v_add_f32_dpp v183, v183, v183 quad_perm:[2,3,0,1] row_mask:0xf bank_mask:0xf bound_ctrl:1
	s_nop 1
	v_add_f32_dpp v183, v183, v183 row_half_mirror row_mask:0xf bank_mask:0xf bound_ctrl:1
	s_nop 1
	v_add_f32_dpp v183, v183, v183 row_mirror row_mask:0xf bank_mask:0xf bound_ctrl:1
	s_nop 1
	v_readlane_b32 s98, v183, 0
	v_readlane_b32 s99, v183, 16
	v_readlane_b32 s100, v183, 32
	v_readlane_b32 s101, v183, 48
	s_nop 1
	v_mov_b32_e32 v183, s98
	v_add_f32_e32 v183, s99, v183
	v_add_f32_e32 v183, s100, v183
	v_add_f32_e32 v183, s101, v183
	v_fmamk_f32 v183, v183, 0x3a800000, v182
	v_cmp_gt_f32_e32 vcc, 0x800000, v183
	v_mul_f32_e32 v181, 0x4b800000, v183
	s_nop 1
	v_cndmask_b32_e32 v183, v183, v181, vcc
	v_rsq_f32_e32 v183, v183
	s_nop 0
	v_mul_f32_e32 v181, 0x45800000, v183
	v_cndmask_b32_e32 v184, v183, v181, vcc
	v_mov_b32_e32 v185, v184
	v_pk_mul_f32 v[216:217], v[216:217], v[184:185]
	v_pk_mul_f32 v[218:219], v[218:219], v[184:185]
	v_pk_mul_f32 v[220:221], v[220:221], v[184:185]
	v_pk_mul_f32 v[222:223], v[222:223], v[184:185]
	v_pk_mul_f32 v[224:225], v[224:225], v[184:185]
	v_pk_mul_f32 v[226:227], v[226:227], v[184:185]
	v_pk_mul_f32 v[228:229], v[228:229], v[184:185]
	v_pk_mul_f32 v[230:231], v[230:231], v[184:185]
	v_pk_fma_f32 v[194:195], v[216:217], v[160:161], v[194:195]
	v_pk_fma_f32 v[196:197], v[218:219], v[162:163], v[196:197]
	v_pk_fma_f32 v[198:199], v[220:221], v[164:165], v[198:199]
	v_pk_fma_f32 v[200:201], v[222:223], v[166:167], v[200:201]
	v_pk_fma_f32 v[202:203], v[224:225], v[168:169], v[202:203]
	v_pk_fma_f32 v[204:205], v[226:227], v[170:171], v[204:205]
	v_pk_fma_f32 v[206:207], v[228:229], v[172:173], v[206:207]
	v_pk_fma_f32 v[208:209], v[230:231], v[174:175], v[208:209]
	v_pk_mul_f32 v[252:253], v[194:195], v[194:195]
	v_pk_mul_f32 v[254:255], v[196:197], v[196:197]
	v_pk_fma_f32 v[252:253], v[198:199], v[198:199], v[252:253]
	v_pk_fma_f32 v[254:255], v[200:201], v[200:201], v[254:255]
	v_pk_fma_f32 v[252:253], v[202:203], v[202:203], v[252:253]
	v_pk_fma_f32 v[254:255], v[204:205], v[204:205], v[254:255]
	v_pk_fma_f32 v[252:253], v[206:207], v[206:207], v[252:253]
	v_pk_fma_f32 v[254:255], v[208:209], v[208:209], v[254:255]
	v_pk_add_f32 v[252:253], v[252:253], v[254:255]
	s_nop 0
	v_add_f32_e32 v183, v252, v253
	s_nop 1
	v_add_f32_dpp v183, v183, v183 quad_perm:[1,0,3,2] row_mask:0xf bank_mask:0xf bound_ctrl:1
	s_nop 1
	v_add_f32_dpp v183, v183, v183 quad_perm:[2,3,0,1] row_mask:0xf bank_mask:0xf bound_ctrl:1
	s_nop 1
	v_add_f32_dpp v183, v183, v183 row_half_mirror row_mask:0xf bank_mask:0xf bound_ctrl:1
	s_nop 1
	v_add_f32_dpp v183, v183, v183 row_mirror row_mask:0xf bank_mask:0xf bound_ctrl:1
	s_nop 1
	v_readlane_b32 s98, v183, 0
	v_readlane_b32 s99, v183, 16
	v_readlane_b32 s100, v183, 32
	v_readlane_b32 s101, v183, 48
	s_nop 1
	v_mov_b32_e32 v183, s98
	v_add_f32_e32 v183, s99, v183
	v_add_f32_e32 v183, s100, v183
	v_add_f32_e32 v183, s101, v183
	v_fmamk_f32 v183, v183, 0x3a800000, v182
	v_cmp_gt_f32_e32 vcc, 0x800000, v183
	v_mul_f32_e32 v181, 0x4b800000, v183
	s_nop 1
	v_cndmask_b32_e32 v183, v183, v181, vcc
	v_rsq_f32_e32 v183, v183
	s_nop 0
	v_mul_f32_e32 v181, 0x45800000, v183
	v_cndmask_b32_e32 v184, v183, v181, vcc
	v_mov_b32_e32 v185, v184
	v_cvt_pk_bf16_f32 v80, v194, v195
	v_cvt_pk_bf16_f32 v81, v196, v197
	v_cvt_pk_bf16_f32 v82, v198, v199
	v_cvt_pk_bf16_f32 v83, v200, v201
	v_cvt_pk_bf16_f32 v84, v202, v203
	v_cvt_pk_bf16_f32 v85, v204, v205
	v_cvt_pk_bf16_f32 v86, v206, v207
	v_cvt_pk_bf16_f32 v87, v208, v209
	v_add_u32_e32 v181, 0x2c00000, v177
	global_store_dwordx4 v181, v[80:83], s[78:79]
	global_store_dwordx4 v181, v[84:87], s[78:79] offset:1024
	v_add_u32_e32 v236, 0xa000, v237
	s_mov_b64 exec, 1
	global_store_dword v236, v184, s[78:79]
	s_mov_b64 exec, -1
	s_waitcnt vmcnt(12)
	v_lshlrev_b32_e32 v194, 16, v96
	v_and_b32_e32 v195, 0xffff0000, v96
	v_lshlrev_b32_e32 v196, 16, v97
	v_and_b32_e32 v197, 0xffff0000, v97
	v_lshlrev_b32_e32 v198, 16, v98
	v_and_b32_e32 v199, 0xffff0000, v98
	v_lshlrev_b32_e32 v200, 16, v99
	v_and_b32_e32 v201, 0xffff0000, v99
	v_lshlrev_b32_e32 v202, 16, v100
	v_and_b32_e32 v203, 0xffff0000, v100
	v_lshlrev_b32_e32 v204, 16, v101
	v_and_b32_e32 v205, 0xffff0000, v101
	v_lshlrev_b32_e32 v206, 16, v102
	v_and_b32_e32 v207, 0xffff0000, v102
	v_lshlrev_b32_e32 v208, 16, v103
	v_and_b32_e32 v209, 0xffff0000, v103
	v_lshlrev_b32_e32 v216, 16, v104
	v_and_b32_e32 v217, 0xffff0000, v104
	v_lshlrev_b32_e32 v218, 16, v105
	v_and_b32_e32 v219, 0xffff0000, v105
	v_lshlrev_b32_e32 v220, 16, v106
	v_and_b32_e32 v221, 0xffff0000, v106
	v_lshlrev_b32_e32 v222, 16, v107
	v_and_b32_e32 v223, 0xffff0000, v107
	v_lshlrev_b32_e32 v224, 16, v108
	v_and_b32_e32 v225, 0xffff0000, v108
	v_lshlrev_b32_e32 v226, 16, v109
	v_and_b32_e32 v227, 0xffff0000, v109
	v_lshlrev_b32_e32 v228, 16, v110
	v_and_b32_e32 v229, 0xffff0000, v110
	v_lshlrev_b32_e32 v230, 16, v111
	v_and_b32_e32 v231, 0xffff0000, v111
	v_pk_mul_f32 v[252:253], v[216:217], v[216:217]
	v_pk_mul_f32 v[254:255], v[218:219], v[218:219]
	v_pk_fma_f32 v[252:253], v[220:221], v[220:221], v[252:253]
	v_pk_fma_f32 v[254:255], v[222:223], v[222:223], v[254:255]
	v_pk_fma_f32 v[252:253], v[224:225], v[224:225], v[252:253]
	v_pk_fma_f32 v[254:255], v[226:227], v[226:227], v[254:255]
	v_pk_fma_f32 v[252:253], v[228:229], v[228:229], v[252:253]
	v_pk_fma_f32 v[254:255], v[230:231], v[230:231], v[254:255]
	v_pk_add_f32 v[252:253], v[252:253], v[254:255]
	s_nop 0
	v_add_f32_e32 v183, v252, v253
	s_nop 1
	v_add_f32_dpp v183, v183, v183 quad_perm:[1,0,3,2] row_mask:0xf bank_mask:0xf bound_ctrl:1
	s_nop 1
	v_add_f32_dpp v183, v183, v183 quad_perm:[2,3,0,1] row_mask:0xf bank_mask:0xf bound_ctrl:1
	s_nop 1
	v_add_f32_dpp v183, v183, v183 row_half_mirror row_mask:0xf bank_mask:0xf bound_ctrl:1
	s_nop 1
	v_add_f32_dpp v183, v183, v183 row_mirror row_mask:0xf bank_mask:0xf bound_ctrl:1
	s_nop 1
	v_readlane_b32 s98, v183, 0
	v_readlane_b32 s99, v183, 16
	v_readlane_b32 s100, v183, 32
	v_readlane_b32 s101, v183, 48
	s_nop 1
	v_mov_b32_e32 v183, s98
	v_add_f32_e32 v183, s99, v183
	v_add_f32_e32 v183, s100, v183
	v_add_f32_e32 v183, s101, v183
	v_fmamk_f32 v183, v183, 0x3a800000, v182
	v_cmp_gt_f32_e32 vcc, 0x800000, v183
	v_mul_f32_e32 v181, 0x4b800000, v183
	s_nop 1
	v_cndmask_b32_e32 v183, v183, v181, vcc
	v_rsq_f32_e32 v183, v183
	s_nop 0
	v_mul_f32_e32 v181, 0x45800000, v183
	v_cndmask_b32_e32 v184, v183, v181, vcc
	v_mov_b32_e32 v185, v184
	v_pk_mul_f32 v[216:217], v[216:217], v[184:185]
	v_pk_mul_f32 v[218:219], v[218:219], v[184:185]
	v_pk_mul_f32 v[220:221], v[220:221], v[184:185]
	v_pk_mul_f32 v[222:223], v[222:223], v[184:185]
	v_pk_mul_f32 v[224:225], v[224:225], v[184:185]
	v_pk_mul_f32 v[226:227], v[226:227], v[184:185]
	v_pk_mul_f32 v[228:229], v[228:229], v[184:185]
	v_pk_mul_f32 v[230:231], v[230:231], v[184:185]
	v_pk_fma_f32 v[194:195], v[216:217], v[160:161], v[194:195]
	v_pk_fma_f32 v[196:197], v[218:219], v[162:163], v[196:197]
	v_pk_fma_f32 v[198:199], v[220:221], v[164:165], v[198:199]
	v_pk_fma_f32 v[200:201], v[222:223], v[166:167], v[200:201]
	v_pk_fma_f32 v[202:203], v[224:225], v[168:169], v[202:203]
	v_pk_fma_f32 v[204:205], v[226:227], v[170:171], v[204:205]
	v_pk_fma_f32 v[206:207], v[228:229], v[172:173], v[206:207]
	v_pk_fma_f32 v[208:209], v[230:231], v[174:175], v[208:209]
	v_pk_mul_f32 v[252:253], v[194:195], v[194:195]
	v_pk_mul_f32 v[254:255], v[196:197], v[196:197]
	v_pk_fma_f32 v[252:253], v[198:199], v[198:199], v[252:253]
	v_pk_fma_f32 v[254:255], v[200:201], v[200:201], v[254:255]
	v_pk_fma_f32 v[252:253], v[202:203], v[202:203], v[252:253]
	v_pk_fma_f32 v[254:255], v[204:205], v[204:205], v[254:255]
	v_pk_fma_f32 v[252:253], v[206:207], v[206:207], v[252:253]
	v_pk_fma_f32 v[254:255], v[208:209], v[208:209], v[254:255]
	v_pk_add_f32 v[252:253], v[252:253], v[254:255]
	s_nop 0
	v_add_f32_e32 v183, v252, v253
	s_nop 1
	v_add_f32_dpp v183, v183, v183 quad_perm:[1,0,3,2] row_mask:0xf bank_mask:0xf bound_ctrl:1
	s_nop 1
	v_add_f32_dpp v183, v183, v183 quad_perm:[2,3,0,1] row_mask:0xf bank_mask:0xf bound_ctrl:1
	s_nop 1
	v_add_f32_dpp v183, v183, v183 row_half_mirror row_mask:0xf bank_mask:0xf bound_ctrl:1
	s_nop 1
	v_add_f32_dpp v183, v183, v183 row_mirror row_mask:0xf bank_mask:0xf bound_ctrl:1
	s_nop 1
	v_readlane_b32 s98, v183, 0
	v_readlane_b32 s99, v183, 16
	v_readlane_b32 s100, v183, 32
	v_readlane_b32 s101, v183, 48
	s_nop 1
	v_mov_b32_e32 v183, s98
	v_add_f32_e32 v183, s99, v183
	v_add_f32_e32 v183, s100, v183
	v_add_f32_e32 v183, s101, v183
	v_fmamk_f32 v183, v183, 0x3a800000, v182
	v_cmp_gt_f32_e32 vcc, 0x800000, v183
	v_mul_f32_e32 v181, 0x4b800000, v183
	s_nop 1
	v_cndmask_b32_e32 v183, v183, v181, vcc
	v_rsq_f32_e32 v183, v183
	s_nop 0
	v_mul_f32_e32 v181, 0x45800000, v183
	v_cndmask_b32_e32 v184, v183, v181, vcc
	v_mov_b32_e32 v185, v184
	v_cvt_pk_bf16_f32 v96, v194, v195
	v_cvt_pk_bf16_f32 v97, v196, v197
	v_cvt_pk_bf16_f32 v98, v198, v199
	v_cvt_pk_bf16_f32 v99, v200, v201
	v_cvt_pk_bf16_f32 v100, v202, v203
	v_cvt_pk_bf16_f32 v101, v204, v205
	v_cvt_pk_bf16_f32 v102, v206, v207
	v_cvt_pk_bf16_f32 v103, v208, v209
	v_add_u32_e32 v181, 0x3000000, v177
	global_store_dwordx4 v181, v[96:99], s[78:79]
	global_store_dwordx4 v181, v[100:103], s[78:79] offset:1024
	v_add_u32_e32 v236, 0xc000, v237
	s_mov_b64 exec, 1
	global_store_dword v236, v184, s[78:79]
	s_mov_b64 exec, -1
	s_waitcnt vmcnt(8)
	v_lshlrev_b32_e32 v194, 16, v112
	v_and_b32_e32 v195, 0xffff0000, v112
	v_lshlrev_b32_e32 v196, 16, v113
	v_and_b32_e32 v197, 0xffff0000, v113
	v_lshlrev_b32_e32 v198, 16, v114
	v_and_b32_e32 v199, 0xffff0000, v114
	v_lshlrev_b32_e32 v200, 16, v115
	v_and_b32_e32 v201, 0xffff0000, v115
	v_lshlrev_b32_e32 v202, 16, v116
	v_and_b32_e32 v203, 0xffff0000, v116
	v_lshlrev_b32_e32 v204, 16, v117
	v_and_b32_e32 v205, 0xffff0000, v117
	v_lshlrev_b32_e32 v206, 16, v118
	v_and_b32_e32 v207, 0xffff0000, v118
	v_lshlrev_b32_e32 v208, 16, v119
	v_and_b32_e32 v209, 0xffff0000, v119
	v_lshlrev_b32_e32 v216, 16, v120
	v_and_b32_e32 v217, 0xffff0000, v120
	v_lshlrev_b32_e32 v218, 16, v121
	v_and_b32_e32 v219, 0xffff0000, v121
	v_lshlrev_b32_e32 v220, 16, v122
	v_and_b32_e32 v221, 0xffff0000, v122
	v_lshlrev_b32_e32 v222, 16, v123
	v_and_b32_e32 v223, 0xffff0000, v123
	v_lshlrev_b32_e32 v224, 16, v124
	v_and_b32_e32 v225, 0xffff0000, v124
	v_lshlrev_b32_e32 v226, 16, v125
	v_and_b32_e32 v227, 0xffff0000, v125
	v_lshlrev_b32_e32 v228, 16, v126
	v_and_b32_e32 v229, 0xffff0000, v126
	v_lshlrev_b32_e32 v230, 16, v127
	v_and_b32_e32 v231, 0xffff0000, v127
	v_pk_mul_f32 v[252:253], v[216:217], v[216:217]
	v_pk_mul_f32 v[254:255], v[218:219], v[218:219]
	v_pk_fma_f32 v[252:253], v[220:221], v[220:221], v[252:253]
	v_pk_fma_f32 v[254:255], v[222:223], v[222:223], v[254:255]
	v_pk_fma_f32 v[252:253], v[224:225], v[224:225], v[252:253]
	v_pk_fma_f32 v[254:255], v[226:227], v[226:227], v[254:255]
	v_pk_fma_f32 v[252:253], v[228:229], v[228:229], v[252:253]
	v_pk_fma_f32 v[254:255], v[230:231], v[230:231], v[254:255]
	v_pk_add_f32 v[252:253], v[252:253], v[254:255]
	s_nop 0
	v_add_f32_e32 v183, v252, v253
	s_nop 1
	v_add_f32_dpp v183, v183, v183 quad_perm:[1,0,3,2] row_mask:0xf bank_mask:0xf bound_ctrl:1
	s_nop 1
	v_add_f32_dpp v183, v183, v183 quad_perm:[2,3,0,1] row_mask:0xf bank_mask:0xf bound_ctrl:1
	s_nop 1
	v_add_f32_dpp v183, v183, v183 row_half_mirror row_mask:0xf bank_mask:0xf bound_ctrl:1
	s_nop 1
	v_add_f32_dpp v183, v183, v183 row_mirror row_mask:0xf bank_mask:0xf bound_ctrl:1
	s_nop 1
	v_readlane_b32 s98, v183, 0
	v_readlane_b32 s99, v183, 16
	v_readlane_b32 s100, v183, 32
	v_readlane_b32 s101, v183, 48
	s_nop 1
	v_mov_b32_e32 v183, s98
	v_add_f32_e32 v183, s99, v183
	v_add_f32_e32 v183, s100, v183
	v_add_f32_e32 v183, s101, v183
	v_fmamk_f32 v183, v183, 0x3a800000, v182
	v_cmp_gt_f32_e32 vcc, 0x800000, v183
	v_mul_f32_e32 v181, 0x4b800000, v183
	s_nop 1
	v_cndmask_b32_e32 v183, v183, v181, vcc
	v_rsq_f32_e32 v183, v183
	s_nop 0
	v_mul_f32_e32 v181, 0x45800000, v183
	v_cndmask_b32_e32 v184, v183, v181, vcc
	v_mov_b32_e32 v185, v184
	v_pk_mul_f32 v[216:217], v[216:217], v[184:185]
	v_pk_mul_f32 v[218:219], v[218:219], v[184:185]
	v_pk_mul_f32 v[220:221], v[220:221], v[184:185]
	v_pk_mul_f32 v[222:223], v[222:223], v[184:185]
	v_pk_mul_f32 v[224:225], v[224:225], v[184:185]
	v_pk_mul_f32 v[226:227], v[226:227], v[184:185]
	v_pk_mul_f32 v[228:229], v[228:229], v[184:185]
	v_pk_mul_f32 v[230:231], v[230:231], v[184:185]
	v_pk_fma_f32 v[194:195], v[216:217], v[160:161], v[194:195]
	v_pk_fma_f32 v[196:197], v[218:219], v[162:163], v[196:197]
	v_pk_fma_f32 v[198:199], v[220:221], v[164:165], v[198:199]
	v_pk_fma_f32 v[200:201], v[222:223], v[166:167], v[200:201]
	v_pk_fma_f32 v[202:203], v[224:225], v[168:169], v[202:203]
	v_pk_fma_f32 v[204:205], v[226:227], v[170:171], v[204:205]
	v_pk_fma_f32 v[206:207], v[228:229], v[172:173], v[206:207]
	v_pk_fma_f32 v[208:209], v[230:231], v[174:175], v[208:209]
	v_pk_mul_f32 v[252:253], v[194:195], v[194:195]
	v_pk_mul_f32 v[254:255], v[196:197], v[196:197]
	v_pk_fma_f32 v[252:253], v[198:199], v[198:199], v[252:253]
	v_pk_fma_f32 v[254:255], v[200:201], v[200:201], v[254:255]
	v_pk_fma_f32 v[252:253], v[202:203], v[202:203], v[252:253]
	v_pk_fma_f32 v[254:255], v[204:205], v[204:205], v[254:255]
	v_pk_fma_f32 v[252:253], v[206:207], v[206:207], v[252:253]
	v_pk_fma_f32 v[254:255], v[208:209], v[208:209], v[254:255]
	v_pk_add_f32 v[252:253], v[252:253], v[254:255]
	s_nop 0
	v_add_f32_e32 v183, v252, v253
	s_nop 1
	v_add_f32_dpp v183, v183, v183 quad_perm:[1,0,3,2] row_mask:0xf bank_mask:0xf bound_ctrl:1
	s_nop 1
	v_add_f32_dpp v183, v183, v183 quad_perm:[2,3,0,1] row_mask:0xf bank_mask:0xf bound_ctrl:1
	s_nop 1
	v_add_f32_dpp v183, v183, v183 row_half_mirror row_mask:0xf bank_mask:0xf bound_ctrl:1
	s_nop 1
	v_add_f32_dpp v183, v183, v183 row_mirror row_mask:0xf bank_mask:0xf bound_ctrl:1
	s_nop 1
	v_readlane_b32 s98, v183, 0
	v_readlane_b32 s99, v183, 16
	v_readlane_b32 s100, v183, 32
	v_readlane_b32 s101, v183, 48
	s_nop 1
	v_mov_b32_e32 v183, s98
	v_add_f32_e32 v183, s99, v183
	v_add_f32_e32 v183, s100, v183
	v_add_f32_e32 v183, s101, v183
	v_fmamk_f32 v183, v183, 0x3a800000, v182
	v_cmp_gt_f32_e32 vcc, 0x800000, v183
	v_mul_f32_e32 v181, 0x4b800000, v183
	s_nop 1
	v_cndmask_b32_e32 v183, v183, v181, vcc
	v_rsq_f32_e32 v183, v183
	s_nop 0
	v_mul_f32_e32 v181, 0x45800000, v183
	v_cndmask_b32_e32 v184, v183, v181, vcc
	v_mov_b32_e32 v185, v184
	v_cvt_pk_bf16_f32 v112, v194, v195
	v_cvt_pk_bf16_f32 v113, v196, v197
	v_cvt_pk_bf16_f32 v114, v198, v199
	v_cvt_pk_bf16_f32 v115, v200, v201
	v_cvt_pk_bf16_f32 v116, v202, v203
	v_cvt_pk_bf16_f32 v117, v204, v205
	v_cvt_pk_bf16_f32 v118, v206, v207
	v_cvt_pk_bf16_f32 v119, v208, v209
	v_add_u32_e32 v181, 0x3400000, v177
	global_store_dwordx4 v181, v[112:115], s[78:79]
	global_store_dwordx4 v181, v[116:119], s[78:79] offset:1024
	v_add_u32_e32 v236, 0xe000, v237
	s_mov_b64 exec, 1
	global_store_dword v236, v184, s[78:79]
	s_mov_b64 exec, -1
	s_waitcnt vmcnt(4)
	v_lshlrev_b32_e32 v194, 16, v128
	v_and_b32_e32 v195, 0xffff0000, v128
	v_lshlrev_b32_e32 v196, 16, v129
	v_and_b32_e32 v197, 0xffff0000, v129
	v_lshlrev_b32_e32 v198, 16, v130
	v_and_b32_e32 v199, 0xffff0000, v130
	v_lshlrev_b32_e32 v200, 16, v131
	v_and_b32_e32 v201, 0xffff0000, v131
	v_lshlrev_b32_e32 v202, 16, v132
	v_and_b32_e32 v203, 0xffff0000, v132
	v_lshlrev_b32_e32 v204, 16, v133
	v_and_b32_e32 v205, 0xffff0000, v133
	v_lshlrev_b32_e32 v206, 16, v134
	v_and_b32_e32 v207, 0xffff0000, v134
	v_lshlrev_b32_e32 v208, 16, v135
	v_and_b32_e32 v209, 0xffff0000, v135
	v_lshlrev_b32_e32 v216, 16, v136
	v_and_b32_e32 v217, 0xffff0000, v136
	v_lshlrev_b32_e32 v218, 16, v137
	v_and_b32_e32 v219, 0xffff0000, v137
	v_lshlrev_b32_e32 v220, 16, v138
	v_and_b32_e32 v221, 0xffff0000, v138
	v_lshlrev_b32_e32 v222, 16, v139
	v_and_b32_e32 v223, 0xffff0000, v139
	v_lshlrev_b32_e32 v224, 16, v140
	v_and_b32_e32 v225, 0xffff0000, v140
	v_lshlrev_b32_e32 v226, 16, v141
	v_and_b32_e32 v227, 0xffff0000, v141
	v_lshlrev_b32_e32 v228, 16, v142
	v_and_b32_e32 v229, 0xffff0000, v142
	v_lshlrev_b32_e32 v230, 16, v143
	v_and_b32_e32 v231, 0xffff0000, v143
	v_pk_mul_f32 v[252:253], v[216:217], v[216:217]
	v_pk_mul_f32 v[254:255], v[218:219], v[218:219]
	v_pk_fma_f32 v[252:253], v[220:221], v[220:221], v[252:253]
	v_pk_fma_f32 v[254:255], v[222:223], v[222:223], v[254:255]
	v_pk_fma_f32 v[252:253], v[224:225], v[224:225], v[252:253]
	v_pk_fma_f32 v[254:255], v[226:227], v[226:227], v[254:255]
	v_pk_fma_f32 v[252:253], v[228:229], v[228:229], v[252:253]
	v_pk_fma_f32 v[254:255], v[230:231], v[230:231], v[254:255]
	v_pk_add_f32 v[252:253], v[252:253], v[254:255]
	s_nop 0
	v_add_f32_e32 v183, v252, v253
	s_nop 1
	v_add_f32_dpp v183, v183, v183 quad_perm:[1,0,3,2] row_mask:0xf bank_mask:0xf bound_ctrl:1
	s_nop 1
	v_add_f32_dpp v183, v183, v183 quad_perm:[2,3,0,1] row_mask:0xf bank_mask:0xf bound_ctrl:1
	s_nop 1
	v_add_f32_dpp v183, v183, v183 row_half_mirror row_mask:0xf bank_mask:0xf bound_ctrl:1
	s_nop 1
	v_add_f32_dpp v183, v183, v183 row_mirror row_mask:0xf bank_mask:0xf bound_ctrl:1
	s_nop 1
	v_readlane_b32 s98, v183, 0
	v_readlane_b32 s99, v183, 16
	v_readlane_b32 s100, v183, 32
	v_readlane_b32 s101, v183, 48
	s_nop 1
	v_mov_b32_e32 v183, s98
	v_add_f32_e32 v183, s99, v183
	v_add_f32_e32 v183, s100, v183
	v_add_f32_e32 v183, s101, v183
	v_fmamk_f32 v183, v183, 0x3a800000, v182
	v_cmp_gt_f32_e32 vcc, 0x800000, v183
	v_mul_f32_e32 v181, 0x4b800000, v183
	s_nop 1
	v_cndmask_b32_e32 v183, v183, v181, vcc
	v_rsq_f32_e32 v183, v183
	s_nop 0
	v_mul_f32_e32 v181, 0x45800000, v183
	v_cndmask_b32_e32 v184, v183, v181, vcc
	v_mov_b32_e32 v185, v184
	v_pk_mul_f32 v[216:217], v[216:217], v[184:185]
	v_pk_mul_f32 v[218:219], v[218:219], v[184:185]
	v_pk_mul_f32 v[220:221], v[220:221], v[184:185]
	v_pk_mul_f32 v[222:223], v[222:223], v[184:185]
	v_pk_mul_f32 v[224:225], v[224:225], v[184:185]
	v_pk_mul_f32 v[226:227], v[226:227], v[184:185]
	v_pk_mul_f32 v[228:229], v[228:229], v[184:185]
	v_pk_mul_f32 v[230:231], v[230:231], v[184:185]
	v_pk_fma_f32 v[194:195], v[216:217], v[160:161], v[194:195]
	v_pk_fma_f32 v[196:197], v[218:219], v[162:163], v[196:197]
	v_pk_fma_f32 v[198:199], v[220:221], v[164:165], v[198:199]
	v_pk_fma_f32 v[200:201], v[222:223], v[166:167], v[200:201]
	v_pk_fma_f32 v[202:203], v[224:225], v[168:169], v[202:203]
	v_pk_fma_f32 v[204:205], v[226:227], v[170:171], v[204:205]
	v_pk_fma_f32 v[206:207], v[228:229], v[172:173], v[206:207]
	v_pk_fma_f32 v[208:209], v[230:231], v[174:175], v[208:209]
	v_pk_mul_f32 v[252:253], v[194:195], v[194:195]
	v_pk_mul_f32 v[254:255], v[196:197], v[196:197]
	v_pk_fma_f32 v[252:253], v[198:199], v[198:199], v[252:253]
	v_pk_fma_f32 v[254:255], v[200:201], v[200:201], v[254:255]
	v_pk_fma_f32 v[252:253], v[202:203], v[202:203], v[252:253]
	v_pk_fma_f32 v[254:255], v[204:205], v[204:205], v[254:255]
	v_pk_fma_f32 v[252:253], v[206:207], v[206:207], v[252:253]
	v_pk_fma_f32 v[254:255], v[208:209], v[208:209], v[254:255]
	v_pk_add_f32 v[252:253], v[252:253], v[254:255]
	s_nop 0
	v_add_f32_e32 v183, v252, v253
	s_nop 1
	v_add_f32_dpp v183, v183, v183 quad_perm:[1,0,3,2] row_mask:0xf bank_mask:0xf bound_ctrl:1
	s_nop 1
	v_add_f32_dpp v183, v183, v183 quad_perm:[2,3,0,1] row_mask:0xf bank_mask:0xf bound_ctrl:1
	s_nop 1
	v_add_f32_dpp v183, v183, v183 row_half_mirror row_mask:0xf bank_mask:0xf bound_ctrl:1
	s_nop 1
	v_add_f32_dpp v183, v183, v183 row_mirror row_mask:0xf bank_mask:0xf bound_ctrl:1
	s_nop 1
	v_readlane_b32 s98, v183, 0
	v_readlane_b32 s99, v183, 16
	v_readlane_b32 s100, v183, 32
	v_readlane_b32 s101, v183, 48
	s_nop 1
	v_mov_b32_e32 v183, s98
	v_add_f32_e32 v183, s99, v183
	v_add_f32_e32 v183, s100, v183
	v_add_f32_e32 v183, s101, v183
	v_fmamk_f32 v183, v183, 0x3a800000, v182
	v_cmp_gt_f32_e32 vcc, 0x800000, v183
	v_mul_f32_e32 v181, 0x4b800000, v183
	s_nop 1
	v_cndmask_b32_e32 v183, v183, v181, vcc
	v_rsq_f32_e32 v183, v183
	s_nop 0
	v_mul_f32_e32 v181, 0x45800000, v183
	v_cndmask_b32_e32 v184, v183, v181, vcc
	v_mov_b32_e32 v185, v184
	v_cvt_pk_bf16_f32 v128, v194, v195
	v_cvt_pk_bf16_f32 v129, v196, v197
	v_cvt_pk_bf16_f32 v130, v198, v199
	v_cvt_pk_bf16_f32 v131, v200, v201
	v_cvt_pk_bf16_f32 v132, v202, v203
	v_cvt_pk_bf16_f32 v133, v204, v205
	v_cvt_pk_bf16_f32 v134, v206, v207
	v_cvt_pk_bf16_f32 v135, v208, v209
	v_add_u32_e32 v181, 0x1800000, v210
	global_store_dwordx4 v181, v[128:131], s[78:79]
	global_store_dwordx4 v181, v[132:135], s[78:79] offset:1024
	v_add_u32_e32 v236, 0x0, v211
	s_mov_b64 exec, 1
	global_store_dword v236, v184, s[78:79]
	s_mov_b64 exec, -1
	s_waitcnt vmcnt(0)
	v_lshlrev_b32_e32 v194, 16, v144
	v_and_b32_e32 v195, 0xffff0000, v144
	v_lshlrev_b32_e32 v196, 16, v145
	v_and_b32_e32 v197, 0xffff0000, v145
	v_lshlrev_b32_e32 v198, 16, v146
	v_and_b32_e32 v199, 0xffff0000, v146
	v_lshlrev_b32_e32 v200, 16, v147
	v_and_b32_e32 v201, 0xffff0000, v147
	v_lshlrev_b32_e32 v202, 16, v148
	v_and_b32_e32 v203, 0xffff0000, v148
	v_lshlrev_b32_e32 v204, 16, v149
	v_and_b32_e32 v205, 0xffff0000, v149
	v_lshlrev_b32_e32 v206, 16, v150
	v_and_b32_e32 v207, 0xffff0000, v150
	v_lshlrev_b32_e32 v208, 16, v151
	v_and_b32_e32 v209, 0xffff0000, v151
	v_lshlrev_b32_e32 v216, 16, v152
	v_and_b32_e32 v217, 0xffff0000, v152
	v_lshlrev_b32_e32 v218, 16, v153
	v_and_b32_e32 v219, 0xffff0000, v153
	v_lshlrev_b32_e32 v220, 16, v154
	v_and_b32_e32 v221, 0xffff0000, v154
	v_lshlrev_b32_e32 v222, 16, v155
	v_and_b32_e32 v223, 0xffff0000, v155
	v_lshlrev_b32_e32 v224, 16, v156
	v_and_b32_e32 v225, 0xffff0000, v156
	v_lshlrev_b32_e32 v226, 16, v157
	v_and_b32_e32 v227, 0xffff0000, v157
	v_lshlrev_b32_e32 v228, 16, v158
	v_and_b32_e32 v229, 0xffff0000, v158
	v_lshlrev_b32_e32 v230, 16, v159
	v_and_b32_e32 v231, 0xffff0000, v159
	v_pk_mul_f32 v[252:253], v[216:217], v[216:217]
	v_pk_mul_f32 v[254:255], v[218:219], v[218:219]
	v_pk_fma_f32 v[252:253], v[220:221], v[220:221], v[252:253]
	v_pk_fma_f32 v[254:255], v[222:223], v[222:223], v[254:255]
	v_pk_fma_f32 v[252:253], v[224:225], v[224:225], v[252:253]
	v_pk_fma_f32 v[254:255], v[226:227], v[226:227], v[254:255]
	v_pk_fma_f32 v[252:253], v[228:229], v[228:229], v[252:253]
	v_pk_fma_f32 v[254:255], v[230:231], v[230:231], v[254:255]
	v_pk_add_f32 v[252:253], v[252:253], v[254:255]
	s_nop 0
	v_add_f32_e32 v183, v252, v253
	s_nop 1
	v_add_f32_dpp v183, v183, v183 quad_perm:[1,0,3,2] row_mask:0xf bank_mask:0xf bound_ctrl:1
	s_nop 1
	v_add_f32_dpp v183, v183, v183 quad_perm:[2,3,0,1] row_mask:0xf bank_mask:0xf bound_ctrl:1
	s_nop 1
	v_add_f32_dpp v183, v183, v183 row_half_mirror row_mask:0xf bank_mask:0xf bound_ctrl:1
	s_nop 1
	v_add_f32_dpp v183, v183, v183 row_mirror row_mask:0xf bank_mask:0xf bound_ctrl:1
	s_nop 1
	v_readlane_b32 s98, v183, 0
	v_readlane_b32 s99, v183, 16
	v_readlane_b32 s100, v183, 32
	v_readlane_b32 s101, v183, 48
	s_nop 1
	v_mov_b32_e32 v183, s98
	v_add_f32_e32 v183, s99, v183
	v_add_f32_e32 v183, s100, v183
	v_add_f32_e32 v183, s101, v183
	v_fmamk_f32 v183, v183, 0x3a800000, v182
	v_cmp_gt_f32_e32 vcc, 0x800000, v183
	v_mul_f32_e32 v181, 0x4b800000, v183
	s_nop 1
	v_cndmask_b32_e32 v183, v183, v181, vcc
	v_rsq_f32_e32 v183, v183
	s_nop 0
	v_mul_f32_e32 v181, 0x45800000, v183
	v_cndmask_b32_e32 v184, v183, v181, vcc
	v_mov_b32_e32 v185, v184
	v_pk_mul_f32 v[216:217], v[216:217], v[184:185]
	v_pk_mul_f32 v[218:219], v[218:219], v[184:185]
	v_pk_mul_f32 v[220:221], v[220:221], v[184:185]
	v_pk_mul_f32 v[222:223], v[222:223], v[184:185]
	v_pk_mul_f32 v[224:225], v[224:225], v[184:185]
	v_pk_mul_f32 v[226:227], v[226:227], v[184:185]
	v_pk_mul_f32 v[228:229], v[228:229], v[184:185]
	v_pk_mul_f32 v[230:231], v[230:231], v[184:185]
	v_pk_fma_f32 v[194:195], v[216:217], v[160:161], v[194:195]
	v_pk_fma_f32 v[196:197], v[218:219], v[162:163], v[196:197]
	v_pk_fma_f32 v[198:199], v[220:221], v[164:165], v[198:199]
	v_pk_fma_f32 v[200:201], v[222:223], v[166:167], v[200:201]
	v_pk_fma_f32 v[202:203], v[224:225], v[168:169], v[202:203]
	v_pk_fma_f32 v[204:205], v[226:227], v[170:171], v[204:205]
	v_pk_fma_f32 v[206:207], v[228:229], v[172:173], v[206:207]
	v_pk_fma_f32 v[208:209], v[230:231], v[174:175], v[208:209]
	v_pk_mul_f32 v[252:253], v[194:195], v[194:195]
	v_pk_mul_f32 v[254:255], v[196:197], v[196:197]
	v_pk_fma_f32 v[252:253], v[198:199], v[198:199], v[252:253]
	v_pk_fma_f32 v[254:255], v[200:201], v[200:201], v[254:255]
	v_pk_fma_f32 v[252:253], v[202:203], v[202:203], v[252:253]
	v_pk_fma_f32 v[254:255], v[204:205], v[204:205], v[254:255]
	v_pk_fma_f32 v[252:253], v[206:207], v[206:207], v[252:253]
	v_pk_fma_f32 v[254:255], v[208:209], v[208:209], v[254:255]
	v_pk_add_f32 v[252:253], v[252:253], v[254:255]
	s_nop 0
	v_add_f32_e32 v183, v252, v253
	s_nop 1
	v_add_f32_dpp v183, v183, v183 quad_perm:[1,0,3,2] row_mask:0xf bank_mask:0xf bound_ctrl:1
	s_nop 1
	v_add_f32_dpp v183, v183, v183 quad_perm:[2,3,0,1] row_mask:0xf bank_mask:0xf bound_ctrl:1
	s_nop 1
	v_add_f32_dpp v183, v183, v183 row_half_mirror row_mask:0xf bank_mask:0xf bound_ctrl:1
	s_nop 1
	v_add_f32_dpp v183, v183, v183 row_mirror row_mask:0xf bank_mask:0xf bound_ctrl:1
	s_nop 1
	v_readlane_b32 s98, v183, 0
	v_readlane_b32 s99, v183, 16
	v_readlane_b32 s100, v183, 32
	v_readlane_b32 s101, v183, 48
	s_nop 1
	v_mov_b32_e32 v183, s98
	v_add_f32_e32 v183, s99, v183
	v_add_f32_e32 v183, s100, v183
	v_add_f32_e32 v183, s101, v183
	v_fmamk_f32 v183, v183, 0x3a800000, v182
	v_cmp_gt_f32_e32 vcc, 0x800000, v183
	v_mul_f32_e32 v181, 0x4b800000, v183
	s_nop 1
	v_cndmask_b32_e32 v183, v183, v181, vcc
	v_rsq_f32_e32 v183, v183
	s_nop 0
	v_mul_f32_e32 v181, 0x45800000, v183
	v_cndmask_b32_e32 v184, v183, v181, vcc
	v_mov_b32_e32 v185, v184
	v_cvt_pk_bf16_f32 v144, v194, v195
	v_cvt_pk_bf16_f32 v145, v196, v197
	v_cvt_pk_bf16_f32 v146, v198, v199
	v_cvt_pk_bf16_f32 v147, v200, v201
	v_cvt_pk_bf16_f32 v148, v202, v203
	v_cvt_pk_bf16_f32 v149, v204, v205
	v_cvt_pk_bf16_f32 v150, v206, v207
	v_cvt_pk_bf16_f32 v151, v208, v209
	v_add_u32_e32 v181, 0x1c00000, v210
	global_store_dwordx4 v181, v[144:147], s[78:79]
	global_store_dwordx4 v181, v[148:151], s[78:79] offset:1024
	v_add_u32_e32 v236, 0x2000, v211
	s_mov_b64 exec, 1
	global_store_dword v236, v184, s[78:79]
	s_mov_b64 exec, -1
	s_branch .Lmyxupd_done_3

.LBB0_1863:
	v_readlane_b32 s0, v235, 52
	v_readlane_b32 s1, v235, 53
	s_and_b64 vcc, exec, s[0:1]
	s_waitcnt lgkmcnt(0)
	s_barrier
	v_mbcnt_lo_u32_b32 v0, -1, 0
	v_mbcnt_hi_u32_b32 v0, -1, v0
	s_cbranch_vccnz .LBB0_1883
	v_lshlrev_b32_e32 v2, 3, v0
	v_ashrrev_i32_e32 v3, 31, v2
	v_readlane_b32 s4, v235, 4
	v_lshlrev_b64 v[4:5], 1, v[2:3]
	v_lshlrev_b64 v[2:3], 2, v[2:3]
	v_readlane_b32 s14, v235, 14
	v_readlane_b32 s15, v235, 15
	v_lshl_add_u64 v[62:63], s[90:91], 0, v[2:3]
	v_readlane_b32 s5, v235, 5
	v_readlane_b32 s6, v235, 6
	v_readlane_b32 s7, v235, 7
	v_readlane_b32 s8, v235, 8
	v_readlane_b32 s9, v235, 9
	v_readlane_b32 s10, v235, 10
	v_readlane_b32 s11, v235, 11
	v_readlane_b32 s12, v235, 12
	v_readlane_b32 s13, v235, 13
	v_readlane_b32 s16, v235, 16
	v_readlane_b32 s17, v235, 17
	v_readlane_b32 s18, v235, 18
	v_readlane_b32 s19, v235, 19
	v_lshl_add_u64 v[2:3], s[14:15], 0, v[2:3]
	s_mov_b64 s[0:1], 0x2000
	v_lshl_add_u64 v[60:61], s[86:87], 0, v[4:5]
	v_lshl_add_u64 v[64:65], s[54:55], 0, v[4:5]
	v_lshl_add_u64 v[66:67], v[2:3], 0, s[0:1]
	s_mov_b32 s1, 0
	v_cmp_eq_u32_e64 s[16:17], 0, v0
	s_mov_b64 s[4:5], 0x200000
	s_mov_b64 s[6:7], 0x200800
	s_mov_b64 s[8:9], 0x400000
	s_mov_b64 s[10:11], 0x400800
	s_mov_b64 s[12:13], 0x600000
	s_mov_b64 s[14:15], 0x600800
	s_mov_b64 s[18:19], 0x800000
	s_mov_b32 s48, 0x800000
	s_mov_b64 s[20:21], 0x800800
	s_mov_b64 s[22:23], 0xa00000
	s_mov_b64 s[24:25], 0xa00800
	s_mov_b64 s[26:27], 0xc00000
	s_mov_b64 s[28:29], 0xc00800
	s_mov_b64 s[36:37], 0xe00000
	s_mov_b64 s[38:39], 0xe00800
	v_mov_b32_e32 v104, 0
	v_mov_b32_e32 v105, 0x358637bd
	v_readlane_b32 s42, v235, 61
	v_readlane_b32 s43, v235, 62
	v_mbcnt_lo_u32_b32 v176, -1, 0
	v_mbcnt_hi_u32_b32 v176, -1, v176
	v_readlane_b32 s98, v235, 49
	v_readlane_b32 s99, v235, 20
	v_readlane_b32 s100, v235, 14
	v_readlane_b32 s101, v235, 15
	s_nop 3
	s_lshr_b32 vcc_lo, s98, 3
	s_and_b32 vcc_hi, vcc_lo, 7
	s_lshr_b32 vcc_lo, vcc_lo, 3
	s_lshl_b32 vcc_lo, vcc_lo, 3
	s_add_i32 vcc_lo, vcc_lo, s99
	s_lshl_b32 s98, vcc_hi, 8
	s_add_i32 s98, s98, vcc_lo
	v_mov_b32_e32 v179, s98
	v_lshlrev_b32_e32 v177, 4, v176
	s_lshl_b32 s99, s98, 11
	v_add_u32_e32 v177, s99, v177
	v_lshlrev_b32_e32 v180, 5, v176
	v_add_u32_e32 v181, 0x2000, v180
	global_load_dwordx4 v[160:163], v181, s[100:101]
	global_load_dwordx4 v[164:167], v181, s[100:101] offset:16
	global_load_dwordx4 v[168:171], v181, s[100:101] offset:2048
	global_load_dwordx4 v[172:175], v181, s[100:101] offset:2064
	v_mov_b32_e32 v182, 0x358637bd
	v_lshlrev_b32_e32 v237, 2, v179
	v_add_u32_e32 v237, 0x10000, v237
	s_and_b32 s99, s98, 3
	s_cmp_eq_u32 s99, 0
	s_cbranch_scc1 .Lmyxupd_s_4
	s_mul_i32 s100, s99, 0x7ff800
	v_add_u32_e32 v210, s100, v177
	s_mul_i32 s100, s99, 16380
	v_add_u32_e32 v211, s100, v237
	v_add_u32_e32 v178, 0x1800000, v177
	v_add_u32_e32 v181, 0x9e00000, v177
	global_load_dwordx4 v[0:3], v178, s[78:79]
	global_load_dwordx4 v[4:7], v178, s[78:79] offset:1024
	global_load_dwordx4 v[8:11], v181, s[78:79]
	global_load_dwordx4 v[12:15], v181, s[78:79] offset:1024
	v_add_u32_e32 v178, 0x1c00000, v177
	v_add_u32_e32 v181, 0xa200000, v177
	global_load_dwordx4 v[16:19], v178, s[78:79]
	global_load_dwordx4 v[20:23], v178, s[78:79] offset:1024
	global_load_dwordx4 v[24:27], v181, s[78:79]
	global_load_dwordx4 v[28:31], v181, s[78:79] offset:1024
	v_add_u32_e32 v178, 0x2000000, v177
	v_add_u32_e32 v181, 0xa600000, v177
	global_load_dwordx4 v[32:35], v178, s[78:79]
	global_load_dwordx4 v[36:39], v178, s[78:79] offset:1024
	global_load_dwordx4 v[40:43], v181, s[78:79]
	global_load_dwordx4 v[44:47], v181, s[78:79] offset:1024
	v_add_u32_e32 v178, 0x2400000, v177
	v_add_u32_e32 v181, 0xaa00000, v177
	global_load_dwordx4 v[48:51], v178, s[78:79]
	global_load_dwordx4 v[52:55], v178, s[78:79] offset:1024
	global_load_dwordx4 v[56:59], v181, s[78:79]
	global_load_dwordx4 v[60:63], v181, s[78:79] offset:1024
	v_add_u32_e32 v178, 0x2800000, v177
	v_add_u32_e32 v181, 0xae00000, v177
	global_load_dwordx4 v[64:67], v178, s[78:79]
	global_load_dwordx4 v[68:71], v178, s[78:79] offset:1024
	global_load_dwordx4 v[72:75], v181, s[78:79]
	global_load_dwordx4 v[76:79], v181, s[78:79] offset:1024
	v_add_u32_e32 v178, 0x2c00000, v177
	v_add_u32_e32 v181, 0xb200000, v177
	global_load_dwordx4 v[80:83], v178, s[78:79]
	global_load_dwordx4 v[84:87], v178, s[78:79] offset:1024
	global_load_dwordx4 v[88:91], v181, s[78:79]
	global_load_dwordx4 v[92:95], v181, s[78:79] offset:1024
	v_add_u32_e32 v178, 0x3000000, v177
	v_add_u32_e32 v181, 0xb600000, v177
	global_load_dwordx4 v[96:99], v178, s[78:79]
	global_load_dwordx4 v[100:103], v178, s[78:79] offset:1024
	global_load_dwordx4 v[104:107], v181, s[78:79]
	global_load_dwordx4 v[108:111], v181, s[78:79] offset:1024
	v_add_u32_e32 v178, 0x3400000, v177
	v_add_u32_e32 v181, 0xba00000, v177
	global_load_dwordx4 v[112:115], v178, s[78:79]
	global_load_dwordx4 v[116:119], v178, s[78:79] offset:1024
	global_load_dwordx4 v[120:123], v181, s[78:79]
	global_load_dwordx4 v[124:127], v181, s[78:79] offset:1024
	v_add_u32_e32 v178, 0x1800000, v210
	v_add_u32_e32 v181, 0x9e00000, v210
	global_load_dwordx4 v[128:131], v178, s[78:79]
	global_load_dwordx4 v[132:135], v178, s[78:79] offset:1024
	global_load_dwordx4 v[136:139], v181, s[78:79]
	global_load_dwordx4 v[140:143], v181, s[78:79] offset:1024
	v_add_u32_e32 v178, 0x1c00000, v210
	v_add_u32_e32 v181, 0xa200000, v210
	global_load_dwordx4 v[144:147], v178, s[78:79]
	global_load_dwordx4 v[148:151], v178, s[78:79] offset:1024
	global_load_dwordx4 v[152:155], v181, s[78:79]
	global_load_dwordx4 v[156:159], v181, s[78:79] offset:1024
	s_waitcnt vmcnt(36)
	v_lshlrev_b32_e32 v194, 16, v0
	v_and_b32_e32 v195, 0xffff0000, v0
	v_lshlrev_b32_e32 v196, 16, v1
	v_and_b32_e32 v197, 0xffff0000, v1
	v_lshlrev_b32_e32 v198, 16, v2
	v_and_b32_e32 v199, 0xffff0000, v2
	v_lshlrev_b32_e32 v200, 16, v3
	v_and_b32_e32 v201, 0xffff0000, v3
	v_lshlrev_b32_e32 v202, 16, v4
	v_and_b32_e32 v203, 0xffff0000, v4
	v_lshlrev_b32_e32 v204, 16, v5
	v_and_b32_e32 v205, 0xffff0000, v5
	v_lshlrev_b32_e32 v206, 16, v6
	v_and_b32_e32 v207, 0xffff0000, v6
	v_lshlrev_b32_e32 v208, 16, v7
	v_and_b32_e32 v209, 0xffff0000, v7
	v_lshlrev_b32_e32 v216, 16, v8
	v_and_b32_e32 v217, 0xffff0000, v8
	v_lshlrev_b32_e32 v218, 16, v9
	v_and_b32_e32 v219, 0xffff0000, v9
	v_lshlrev_b32_e32 v220, 16, v10
	v_and_b32_e32 v221, 0xffff0000, v10
	v_lshlrev_b32_e32 v222, 16, v11
	v_and_b32_e32 v223, 0xffff0000, v11
	v_lshlrev_b32_e32 v224, 16, v12
	v_and_b32_e32 v225, 0xffff0000, v12
	v_lshlrev_b32_e32 v226, 16, v13
	v_and_b32_e32 v227, 0xffff0000, v13
	v_lshlrev_b32_e32 v228, 16, v14
	v_and_b32_e32 v229, 0xffff0000, v14
	v_lshlrev_b32_e32 v230, 16, v15
	v_and_b32_e32 v231, 0xffff0000, v15
	v_pk_mul_f32 v[252:253], v[216:217], v[216:217]
	v_pk_mul_f32 v[254:255], v[218:219], v[218:219]
	v_pk_fma_f32 v[252:253], v[220:221], v[220:221], v[252:253]
	v_pk_fma_f32 v[254:255], v[222:223], v[222:223], v[254:255]
	v_pk_fma_f32 v[252:253], v[224:225], v[224:225], v[252:253]
	v_pk_fma_f32 v[254:255], v[226:227], v[226:227], v[254:255]
	v_pk_fma_f32 v[252:253], v[228:229], v[228:229], v[252:253]
	v_pk_fma_f32 v[254:255], v[230:231], v[230:231], v[254:255]
	v_pk_add_f32 v[252:253], v[252:253], v[254:255]
	s_nop 0
	v_add_f32_e32 v183, v252, v253
	s_nop 1
	v_add_f32_dpp v183, v183, v183 quad_perm:[1,0,3,2] row_mask:0xf bank_mask:0xf bound_ctrl:1
	s_nop 1
	v_add_f32_dpp v183, v183, v183 quad_perm:[2,3,0,1] row_mask:0xf bank_mask:0xf bound_ctrl:1
	s_nop 1
	v_add_f32_dpp v183, v183, v183 row_half_mirror row_mask:0xf bank_mask:0xf bound_ctrl:1
	s_nop 1
	v_add_f32_dpp v183, v183, v183 row_mirror row_mask:0xf bank_mask:0xf bound_ctrl:1
	s_nop 1
	v_readlane_b32 s98, v183, 0
	v_readlane_b32 s99, v183, 16
	v_readlane_b32 s100, v183, 32
	v_readlane_b32 s101, v183, 48
	s_nop 1
	v_mov_b32_e32 v183, s98
	v_add_f32_e32 v183, s99, v183
	v_add_f32_e32 v183, s100, v183
	v_add_f32_e32 v183, s101, v183
	v_fmamk_f32 v183, v183, 0x3a800000, v182
	v_cmp_gt_f32_e32 vcc, 0x800000, v183
	v_mul_f32_e32 v181, 0x4b800000, v183
	s_nop 1
	v_cndmask_b32_e32 v183, v183, v181, vcc
	v_rsq_f32_e32 v183, v183
	s_nop 0
	v_mul_f32_e32 v181, 0x45800000, v183
	v_cndmask_b32_e32 v184, v183, v181, vcc
	v_mov_b32_e32 v185, v184
	v_pk_mul_f32 v[216:217], v[216:217], v[184:185]
	v_pk_mul_f32 v[218:219], v[218:219], v[184:185]
	v_pk_mul_f32 v[220:221], v[220:221], v[184:185]
	v_pk_mul_f32 v[222:223], v[222:223], v[184:185]
	v_pk_mul_f32 v[224:225], v[224:225], v[184:185]
	v_pk_mul_f32 v[226:227], v[226:227], v[184:185]
	v_pk_mul_f32 v[228:229], v[228:229], v[184:185]
	v_pk_mul_f32 v[230:231], v[230:231], v[184:185]
	v_pk_fma_f32 v[194:195], v[216:217], v[160:161], v[194:195]
	v_pk_fma_f32 v[196:197], v[218:219], v[162:163], v[196:197]
	v_pk_fma_f32 v[198:199], v[220:221], v[164:165], v[198:199]
	v_pk_fma_f32 v[200:201], v[222:223], v[166:167], v[200:201]
	v_pk_fma_f32 v[202:203], v[224:225], v[168:169], v[202:203]
	v_pk_fma_f32 v[204:205], v[226:227], v[170:171], v[204:205]
	v_pk_fma_f32 v[206:207], v[228:229], v[172:173], v[206:207]
	v_pk_fma_f32 v[208:209], v[230:231], v[174:175], v[208:209]
	v_pk_mul_f32 v[252:253], v[194:195], v[194:195]
	v_pk_mul_f32 v[254:255], v[196:197], v[196:197]
	v_pk_fma_f32 v[252:253], v[198:199], v[198:199], v[252:253]
	v_pk_fma_f32 v[254:255], v[200:201], v[200:201], v[254:255]
	v_pk_fma_f32 v[252:253], v[202:203], v[202:203], v[252:253]
	v_pk_fma_f32 v[254:255], v[204:205], v[204:205], v[254:255]
	v_pk_fma_f32 v[252:253], v[206:207], v[206:207], v[252:253]
	v_pk_fma_f32 v[254:255], v[208:209], v[208:209], v[254:255]
	v_pk_add_f32 v[252:253], v[252:253], v[254:255]
	s_nop 0
	v_add_f32_e32 v183, v252, v253
	s_nop 1
	v_add_f32_dpp v183, v183, v183 quad_perm:[1,0,3,2] row_mask:0xf bank_mask:0xf bound_ctrl:1
	s_nop 1
	v_add_f32_dpp v183, v183, v183 quad_perm:[2,3,0,1] row_mask:0xf bank_mask:0xf bound_ctrl:1
	s_nop 1
	v_add_f32_dpp v183, v183, v183 row_half_mirror row_mask:0xf bank_mask:0xf bound_ctrl:1
	s_nop 1
	v_add_f32_dpp v183, v183, v183 row_mirror row_mask:0xf bank_mask:0xf bound_ctrl:1
	s_nop 1
	v_readlane_b32 s98, v183, 0
	v_readlane_b32 s99, v183, 16
	v_readlane_b32 s100, v183, 32
	v_readlane_b32 s101, v183, 48
	s_nop 1
	v_mov_b32_e32 v183, s98
	v_add_f32_e32 v183, s99, v183
	v_add_f32_e32 v183, s100, v183
	v_add_f32_e32 v183, s101, v183
	v_fmamk_f32 v183, v183, 0x3a800000, v182
	v_cmp_gt_f32_e32 vcc, 0x800000, v183
	v_mul_f32_e32 v181, 0x4b800000, v183
	s_nop 1
	v_cndmask_b32_e32 v183, v183, v181, vcc
	v_rsq_f32_e32 v183, v183
	s_nop 0
	v_mul_f32_e32 v181, 0x45800000, v183
	v_cndmask_b32_e32 v184, v183, v181, vcc
	v_mov_b32_e32 v185, v184
	v_cvt_pk_bf16_f32 v0, v194, v195
	v_cvt_pk_bf16_f32 v1, v196, v197
	v_cvt_pk_bf16_f32 v2, v198, v199
	v_cvt_pk_bf16_f32 v3, v200, v201
	v_cvt_pk_bf16_f32 v4, v202, v203
	v_cvt_pk_bf16_f32 v5, v204, v205
	v_cvt_pk_bf16_f32 v6, v206, v207
	v_cvt_pk_bf16_f32 v7, v208, v209
	v_add_u32_e32 v181, 0x1800000, v177
	global_store_dwordx4 v181, v[0:3], s[78:79]
	global_store_dwordx4 v181, v[4:7], s[78:79] offset:1024
	v_add_u32_e32 v236, 0x0, v237
	s_mov_b64 exec, 1
	global_store_dword v236, v184, s[78:79]
	s_mov_b64 exec, -1
	s_waitcnt vmcnt(32)
	v_lshlrev_b32_e32 v194, 16, v16
	v_and_b32_e32 v195, 0xffff0000, v16
	v_lshlrev_b32_e32 v196, 16, v17
	v_and_b32_e32 v197, 0xffff0000, v17
	v_lshlrev_b32_e32 v198, 16, v18
	v_and_b32_e32 v199, 0xffff0000, v18
	v_lshlrev_b32_e32 v200, 16, v19
	v_and_b32_e32 v201, 0xffff0000, v19
	v_lshlrev_b32_e32 v202, 16, v20
	v_and_b32_e32 v203, 0xffff0000, v20
	v_lshlrev_b32_e32 v204, 16, v21
	v_and_b32_e32 v205, 0xffff0000, v21
	v_lshlrev_b32_e32 v206, 16, v22
	v_and_b32_e32 v207, 0xffff0000, v22
	v_lshlrev_b32_e32 v208, 16, v23
	v_and_b32_e32 v209, 0xffff0000, v23
	v_lshlrev_b32_e32 v216, 16, v24
	v_and_b32_e32 v217, 0xffff0000, v24
	v_lshlrev_b32_e32 v218, 16, v25
	v_and_b32_e32 v219, 0xffff0000, v25
	v_lshlrev_b32_e32 v220, 16, v26
	v_and_b32_e32 v221, 0xffff0000, v26
	v_lshlrev_b32_e32 v222, 16, v27
	v_and_b32_e32 v223, 0xffff0000, v27
	v_lshlrev_b32_e32 v224, 16, v28
	v_and_b32_e32 v225, 0xffff0000, v28
	v_lshlrev_b32_e32 v226, 16, v29
	v_and_b32_e32 v227, 0xffff0000, v29
	v_lshlrev_b32_e32 v228, 16, v30
	v_and_b32_e32 v229, 0xffff0000, v30
	v_lshlrev_b32_e32 v230, 16, v31
	v_and_b32_e32 v231, 0xffff0000, v31
	v_pk_mul_f32 v[252:253], v[216:217], v[216:217]
	v_pk_mul_f32 v[254:255], v[218:219], v[218:219]
	v_pk_fma_f32 v[252:253], v[220:221], v[220:221], v[252:253]
	v_pk_fma_f32 v[254:255], v[222:223], v[222:223], v[254:255]
	v_pk_fma_f32 v[252:253], v[224:225], v[224:225], v[252:253]
	v_pk_fma_f32 v[254:255], v[226:227], v[226:227], v[254:255]
	v_pk_fma_f32 v[252:253], v[228:229], v[228:229], v[252:253]
	v_pk_fma_f32 v[254:255], v[230:231], v[230:231], v[254:255]
	v_pk_add_f32 v[252:253], v[252:253], v[254:255]
	s_nop 0
	v_add_f32_e32 v183, v252, v253
	s_nop 1
	v_add_f32_dpp v183, v183, v183 quad_perm:[1,0,3,2] row_mask:0xf bank_mask:0xf bound_ctrl:1
	s_nop 1
	v_add_f32_dpp v183, v183, v183 quad_perm:[2,3,0,1] row_mask:0xf bank_mask:0xf bound_ctrl:1
	s_nop 1
	v_add_f32_dpp v183, v183, v183 row_half_mirror row_mask:0xf bank_mask:0xf bound_ctrl:1
	s_nop 1
	v_add_f32_dpp v183, v183, v183 row_mirror row_mask:0xf bank_mask:0xf bound_ctrl:1
	s_nop 1
	v_readlane_b32 s98, v183, 0
	v_readlane_b32 s99, v183, 16
	v_readlane_b32 s100, v183, 32
	v_readlane_b32 s101, v183, 48
	s_nop 1
	v_mov_b32_e32 v183, s98
	v_add_f32_e32 v183, s99, v183
	v_add_f32_e32 v183, s100, v183
	v_add_f32_e32 v183, s101, v183
	v_fmamk_f32 v183, v183, 0x3a800000, v182
	v_cmp_gt_f32_e32 vcc, 0x800000, v183
	v_mul_f32_e32 v181, 0x4b800000, v183
	s_nop 1
	v_cndmask_b32_e32 v183, v183, v181, vcc
	v_rsq_f32_e32 v183, v183
	s_nop 0
	v_mul_f32_e32 v181, 0x45800000, v183
	v_cndmask_b32_e32 v184, v183, v181, vcc
	v_mov_b32_e32 v185, v184
	v_pk_mul_f32 v[216:217], v[216:217], v[184:185]
	v_pk_mul_f32 v[218:219], v[218:219], v[184:185]
	v_pk_mul_f32 v[220:221], v[220:221], v[184:185]
	v_pk_mul_f32 v[222:223], v[222:223], v[184:185]
	v_pk_mul_f32 v[224:225], v[224:225], v[184:185]
	v_pk_mul_f32 v[226:227], v[226:227], v[184:185]
	v_pk_mul_f32 v[228:229], v[228:229], v[184:185]
	v_pk_mul_f32 v[230:231], v[230:231], v[184:185]
	v_pk_fma_f32 v[194:195], v[216:217], v[160:161], v[194:195]
	v_pk_fma_f32 v[196:197], v[218:219], v[162:163], v[196:197]
	v_pk_fma_f32 v[198:199], v[220:221], v[164:165], v[198:199]
	v_pk_fma_f32 v[200:201], v[222:223], v[166:167], v[200:201]
	v_pk_fma_f32 v[202:203], v[224:225], v[168:169], v[202:203]
	v_pk_fma_f32 v[204:205], v[226:227], v[170:171], v[204:205]
	v_pk_fma_f32 v[206:207], v[228:229], v[172:173], v[206:207]
	v_pk_fma_f32 v[208:209], v[230:231], v[174:175], v[208:209]
	v_pk_mul_f32 v[252:253], v[194:195], v[194:195]
	v_pk_mul_f32 v[254:255], v[196:197], v[196:197]
	v_pk_fma_f32 v[252:253], v[198:199], v[198:199], v[252:253]
	v_pk_fma_f32 v[254:255], v[200:201], v[200:201], v[254:255]
	v_pk_fma_f32 v[252:253], v[202:203], v[202:203], v[252:253]
	v_pk_fma_f32 v[254:255], v[204:205], v[204:205], v[254:255]
	v_pk_fma_f32 v[252:253], v[206:207], v[206:207], v[252:253]
	v_pk_fma_f32 v[254:255], v[208:209], v[208:209], v[254:255]
	v_pk_add_f32 v[252:253], v[252:253], v[254:255]
	s_nop 0
	v_add_f32_e32 v183, v252, v253
	s_nop 1
	v_add_f32_dpp v183, v183, v183 quad_perm:[1,0,3,2] row_mask:0xf bank_mask:0xf bound_ctrl:1
	s_nop 1
	v_add_f32_dpp v183, v183, v183 quad_perm:[2,3,0,1] row_mask:0xf bank_mask:0xf bound_ctrl:1
	s_nop 1
	v_add_f32_dpp v183, v183, v183 row_half_mirror row_mask:0xf bank_mask:0xf bound_ctrl:1
	s_nop 1
	v_add_f32_dpp v183, v183, v183 row_mirror row_mask:0xf bank_mask:0xf bound_ctrl:1
	s_nop 1
	v_readlane_b32 s98, v183, 0
	v_readlane_b32 s99, v183, 16
	v_readlane_b32 s100, v183, 32
	v_readlane_b32 s101, v183, 48
	s_nop 1
	v_mov_b32_e32 v183, s98
	v_add_f32_e32 v183, s99, v183
	v_add_f32_e32 v183, s100, v183
	v_add_f32_e32 v183, s101, v183
	v_fmamk_f32 v183, v183, 0x3a800000, v182
	v_cmp_gt_f32_e32 vcc, 0x800000, v183
	v_mul_f32_e32 v181, 0x4b800000, v183
	s_nop 1
	v_cndmask_b32_e32 v183, v183, v181, vcc
	v_rsq_f32_e32 v183, v183
	s_nop 0
	v_mul_f32_e32 v181, 0x45800000, v183
	v_cndmask_b32_e32 v184, v183, v181, vcc
	v_mov_b32_e32 v185, v184
	v_cvt_pk_bf16_f32 v16, v194, v195
	v_cvt_pk_bf16_f32 v17, v196, v197
	v_cvt_pk_bf16_f32 v18, v198, v199
	v_cvt_pk_bf16_f32 v19, v200, v201
	v_cvt_pk_bf16_f32 v20, v202, v203
	v_cvt_pk_bf16_f32 v21, v204, v205
	v_cvt_pk_bf16_f32 v22, v206, v207
	v_cvt_pk_bf16_f32 v23, v208, v209
	v_add_u32_e32 v181, 0x1c00000, v177
	global_store_dwordx4 v181, v[16:19], s[78:79]
	global_store_dwordx4 v181, v[20:23], s[78:79] offset:1024
	v_add_u32_e32 v236, 0x2000, v237
	s_mov_b64 exec, 1
	global_store_dword v236, v184, s[78:79]
	s_mov_b64 exec, -1
	s_waitcnt vmcnt(28)
	v_lshlrev_b32_e32 v194, 16, v32
	v_and_b32_e32 v195, 0xffff0000, v32
	v_lshlrev_b32_e32 v196, 16, v33
	v_and_b32_e32 v197, 0xffff0000, v33
	v_lshlrev_b32_e32 v198, 16, v34
	v_and_b32_e32 v199, 0xffff0000, v34
	v_lshlrev_b32_e32 v200, 16, v35
	v_and_b32_e32 v201, 0xffff0000, v35
	v_lshlrev_b32_e32 v202, 16, v36
	v_and_b32_e32 v203, 0xffff0000, v36
	v_lshlrev_b32_e32 v204, 16, v37
	v_and_b32_e32 v205, 0xffff0000, v37
	v_lshlrev_b32_e32 v206, 16, v38
	v_and_b32_e32 v207, 0xffff0000, v38
	v_lshlrev_b32_e32 v208, 16, v39
	v_and_b32_e32 v209, 0xffff0000, v39
	v_lshlrev_b32_e32 v216, 16, v40
	v_and_b32_e32 v217, 0xffff0000, v40
	v_lshlrev_b32_e32 v218, 16, v41
	v_and_b32_e32 v219, 0xffff0000, v41
	v_lshlrev_b32_e32 v220, 16, v42
	v_and_b32_e32 v221, 0xffff0000, v42
	v_lshlrev_b32_e32 v222, 16, v43
	v_and_b32_e32 v223, 0xffff0000, v43
	v_lshlrev_b32_e32 v224, 16, v44
	v_and_b32_e32 v225, 0xffff0000, v44
	v_lshlrev_b32_e32 v226, 16, v45
	v_and_b32_e32 v227, 0xffff0000, v45
	v_lshlrev_b32_e32 v228, 16, v46
	v_and_b32_e32 v229, 0xffff0000, v46
	v_lshlrev_b32_e32 v230, 16, v47
	v_and_b32_e32 v231, 0xffff0000, v47
	v_pk_mul_f32 v[252:253], v[216:217], v[216:217]
	v_pk_mul_f32 v[254:255], v[218:219], v[218:219]
	v_pk_fma_f32 v[252:253], v[220:221], v[220:221], v[252:253]
	v_pk_fma_f32 v[254:255], v[222:223], v[222:223], v[254:255]
	v_pk_fma_f32 v[252:253], v[224:225], v[224:225], v[252:253]
	v_pk_fma_f32 v[254:255], v[226:227], v[226:227], v[254:255]
	v_pk_fma_f32 v[252:253], v[228:229], v[228:229], v[252:253]
	v_pk_fma_f32 v[254:255], v[230:231], v[230:231], v[254:255]
	v_pk_add_f32 v[252:253], v[252:253], v[254:255]
	s_nop 0
	v_add_f32_e32 v183, v252, v253
	s_nop 1
	v_add_f32_dpp v183, v183, v183 quad_perm:[1,0,3,2] row_mask:0xf bank_mask:0xf bound_ctrl:1
	s_nop 1
	v_add_f32_dpp v183, v183, v183 quad_perm:[2,3,0,1] row_mask:0xf bank_mask:0xf bound_ctrl:1
	s_nop 1
	v_add_f32_dpp v183, v183, v183 row_half_mirror row_mask:0xf bank_mask:0xf bound_ctrl:1
	s_nop 1
	v_add_f32_dpp v183, v183, v183 row_mirror row_mask:0xf bank_mask:0xf bound_ctrl:1
	s_nop 1
	v_readlane_b32 s98, v183, 0
	v_readlane_b32 s99, v183, 16
	v_readlane_b32 s100, v183, 32
	v_readlane_b32 s101, v183, 48
	s_nop 1
	v_mov_b32_e32 v183, s98
	v_add_f32_e32 v183, s99, v183
	v_add_f32_e32 v183, s100, v183
	v_add_f32_e32 v183, s101, v183
	v_fmamk_f32 v183, v183, 0x3a800000, v182
	v_cmp_gt_f32_e32 vcc, 0x800000, v183
	v_mul_f32_e32 v181, 0x4b800000, v183
	s_nop 1
	v_cndmask_b32_e32 v183, v183, v181, vcc
	v_rsq_f32_e32 v183, v183
	s_nop 0
	v_mul_f32_e32 v181, 0x45800000, v183
	v_cndmask_b32_e32 v184, v183, v181, vcc
	v_mov_b32_e32 v185, v184
	v_pk_mul_f32 v[216:217], v[216:217], v[184:185]
	v_pk_mul_f32 v[218:219], v[218:219], v[184:185]
	v_pk_mul_f32 v[220:221], v[220:221], v[184:185]
	v_pk_mul_f32 v[222:223], v[222:223], v[184:185]
	v_pk_mul_f32 v[224:225], v[224:225], v[184:185]
	v_pk_mul_f32 v[226:227], v[226:227], v[184:185]
	v_pk_mul_f32 v[228:229], v[228:229], v[184:185]
	v_pk_mul_f32 v[230:231], v[230:231], v[184:185]
	v_pk_fma_f32 v[194:195], v[216:217], v[160:161], v[194:195]
	v_pk_fma_f32 v[196:197], v[218:219], v[162:163], v[196:197]
	v_pk_fma_f32 v[198:199], v[220:221], v[164:165], v[198:199]
	v_pk_fma_f32 v[200:201], v[222:223], v[166:167], v[200:201]
	v_pk_fma_f32 v[202:203], v[224:225], v[168:169], v[202:203]
	v_pk_fma_f32 v[204:205], v[226:227], v[170:171], v[204:205]
	v_pk_fma_f32 v[206:207], v[228:229], v[172:173], v[206:207]
	v_pk_fma_f32 v[208:209], v[230:231], v[174:175], v[208:209]
	v_pk_mul_f32 v[252:253], v[194:195], v[194:195]
	v_pk_mul_f32 v[254:255], v[196:197], v[196:197]
	v_pk_fma_f32 v[252:253], v[198:199], v[198:199], v[252:253]
	v_pk_fma_f32 v[254:255], v[200:201], v[200:201], v[254:255]
	v_pk_fma_f32 v[252:253], v[202:203], v[202:203], v[252:253]
	v_pk_fma_f32 v[254:255], v[204:205], v[204:205], v[254:255]
	v_pk_fma_f32 v[252:253], v[206:207], v[206:207], v[252:253]
	v_pk_fma_f32 v[254:255], v[208:209], v[208:209], v[254:255]
	v_pk_add_f32 v[252:253], v[252:253], v[254:255]
	s_nop 0
	v_add_f32_e32 v183, v252, v253
	s_nop 1
	v_add_f32_dpp v183, v183, v183 quad_perm:[1,0,3,2] row_mask:0xf bank_mask:0xf bound_ctrl:1
	s_nop 1
	v_add_f32_dpp v183, v183, v183 quad_perm:[2,3,0,1] row_mask:0xf bank_mask:0xf bound_ctrl:1
	s_nop 1
	v_add_f32_dpp v183, v183, v183 row_half_mirror row_mask:0xf bank_mask:0xf bound_ctrl:1
	s_nop 1
	v_add_f32_dpp v183, v183, v183 row_mirror row_mask:0xf bank_mask:0xf bound_ctrl:1
	s_nop 1
	v_readlane_b32 s98, v183, 0
	v_readlane_b32 s99, v183, 16
	v_readlane_b32 s100, v183, 32
	v_readlane_b32 s101, v183, 48
	s_nop 1
	v_mov_b32_e32 v183, s98
	v_add_f32_e32 v183, s99, v183
	v_add_f32_e32 v183, s100, v183
	v_add_f32_e32 v183, s101, v183
	v_fmamk_f32 v183, v183, 0x3a800000, v182
	v_cmp_gt_f32_e32 vcc, 0x800000, v183
	v_mul_f32_e32 v181, 0x4b800000, v183
	s_nop 1
	v_cndmask_b32_e32 v183, v183, v181, vcc
	v_rsq_f32_e32 v183, v183
	s_nop 0
	v_mul_f32_e32 v181, 0x45800000, v183
	v_cndmask_b32_e32 v184, v183, v181, vcc
	v_mov_b32_e32 v185, v184
	v_cvt_pk_bf16_f32 v32, v194, v195
	v_cvt_pk_bf16_f32 v33, v196, v197
	v_cvt_pk_bf16_f32 v34, v198, v199
	v_cvt_pk_bf16_f32 v35, v200, v201
	v_cvt_pk_bf16_f32 v36, v202, v203
	v_cvt_pk_bf16_f32 v37, v204, v205
	v_cvt_pk_bf16_f32 v38, v206, v207
	v_cvt_pk_bf16_f32 v39, v208, v209
	v_add_u32_e32 v181, 0x2000000, v177
	global_store_dwordx4 v181, v[32:35], s[78:79]
	global_store_dwordx4 v181, v[36:39], s[78:79] offset:1024
	v_add_u32_e32 v236, 0x4000, v237
	s_mov_b64 exec, 1
	global_store_dword v236, v184, s[78:79]
	s_mov_b64 exec, -1
	s_waitcnt vmcnt(24)
	v_lshlrev_b32_e32 v194, 16, v48
	v_and_b32_e32 v195, 0xffff0000, v48
	v_lshlrev_b32_e32 v196, 16, v49
	v_and_b32_e32 v197, 0xffff0000, v49
	v_lshlrev_b32_e32 v198, 16, v50
	v_and_b32_e32 v199, 0xffff0000, v50
	v_lshlrev_b32_e32 v200, 16, v51
	v_and_b32_e32 v201, 0xffff0000, v51
	v_lshlrev_b32_e32 v202, 16, v52
	v_and_b32_e32 v203, 0xffff0000, v52
	v_lshlrev_b32_e32 v204, 16, v53
	v_and_b32_e32 v205, 0xffff0000, v53
	v_lshlrev_b32_e32 v206, 16, v54
	v_and_b32_e32 v207, 0xffff0000, v54
	v_lshlrev_b32_e32 v208, 16, v55
	v_and_b32_e32 v209, 0xffff0000, v55
	v_lshlrev_b32_e32 v216, 16, v56
	v_and_b32_e32 v217, 0xffff0000, v56
	v_lshlrev_b32_e32 v218, 16, v57
	v_and_b32_e32 v219, 0xffff0000, v57
	v_lshlrev_b32_e32 v220, 16, v58
	v_and_b32_e32 v221, 0xffff0000, v58
	v_lshlrev_b32_e32 v222, 16, v59
	v_and_b32_e32 v223, 0xffff0000, v59
	v_lshlrev_b32_e32 v224, 16, v60
	v_and_b32_e32 v225, 0xffff0000, v60
	v_lshlrev_b32_e32 v226, 16, v61
	v_and_b32_e32 v227, 0xffff0000, v61
	v_lshlrev_b32_e32 v228, 16, v62
	v_and_b32_e32 v229, 0xffff0000, v62
	v_lshlrev_b32_e32 v230, 16, v63
	v_and_b32_e32 v231, 0xffff0000, v63
	v_pk_mul_f32 v[252:253], v[216:217], v[216:217]
	v_pk_mul_f32 v[254:255], v[218:219], v[218:219]
	v_pk_fma_f32 v[252:253], v[220:221], v[220:221], v[252:253]
	v_pk_fma_f32 v[254:255], v[222:223], v[222:223], v[254:255]
	v_pk_fma_f32 v[252:253], v[224:225], v[224:225], v[252:253]
	v_pk_fma_f32 v[254:255], v[226:227], v[226:227], v[254:255]
	v_pk_fma_f32 v[252:253], v[228:229], v[228:229], v[252:253]
	v_pk_fma_f32 v[254:255], v[230:231], v[230:231], v[254:255]
	v_pk_add_f32 v[252:253], v[252:253], v[254:255]
	s_nop 0
	v_add_f32_e32 v183, v252, v253
	s_nop 1
	v_add_f32_dpp v183, v183, v183 quad_perm:[1,0,3,2] row_mask:0xf bank_mask:0xf bound_ctrl:1
	s_nop 1
	v_add_f32_dpp v183, v183, v183 quad_perm:[2,3,0,1] row_mask:0xf bank_mask:0xf bound_ctrl:1
	s_nop 1
	v_add_f32_dpp v183, v183, v183 row_half_mirror row_mask:0xf bank_mask:0xf bound_ctrl:1
	s_nop 1
	v_add_f32_dpp v183, v183, v183 row_mirror row_mask:0xf bank_mask:0xf bound_ctrl:1
	s_nop 1
	v_readlane_b32 s98, v183, 0
	v_readlane_b32 s99, v183, 16
	v_readlane_b32 s100, v183, 32
	v_readlane_b32 s101, v183, 48
	s_nop 1
	v_mov_b32_e32 v183, s98
	v_add_f32_e32 v183, s99, v183
	v_add_f32_e32 v183, s100, v183
	v_add_f32_e32 v183, s101, v183
	v_fmamk_f32 v183, v183, 0x3a800000, v182
	v_cmp_gt_f32_e32 vcc, 0x800000, v183
	v_mul_f32_e32 v181, 0x4b800000, v183
	s_nop 1
	v_cndmask_b32_e32 v183, v183, v181, vcc
	v_rsq_f32_e32 v183, v183
	s_nop 0
	v_mul_f32_e32 v181, 0x45800000, v183
	v_cndmask_b32_e32 v184, v183, v181, vcc
	v_mov_b32_e32 v185, v184
	v_pk_mul_f32 v[216:217], v[216:217], v[184:185]
	v_pk_mul_f32 v[218:219], v[218:219], v[184:185]
	v_pk_mul_f32 v[220:221], v[220:221], v[184:185]
	v_pk_mul_f32 v[222:223], v[222:223], v[184:185]
	v_pk_mul_f32 v[224:225], v[224:225], v[184:185]
	v_pk_mul_f32 v[226:227], v[226:227], v[184:185]
	v_pk_mul_f32 v[228:229], v[228:229], v[184:185]
	v_pk_mul_f32 v[230:231], v[230:231], v[184:185]
	v_pk_fma_f32 v[194:195], v[216:217], v[160:161], v[194:195]
	v_pk_fma_f32 v[196:197], v[218:219], v[162:163], v[196:197]
	v_pk_fma_f32 v[198:199], v[220:221], v[164:165], v[198:199]
	v_pk_fma_f32 v[200:201], v[222:223], v[166:167], v[200:201]
	v_pk_fma_f32 v[202:203], v[224:225], v[168:169], v[202:203]
	v_pk_fma_f32 v[204:205], v[226:227], v[170:171], v[204:205]
	v_pk_fma_f32 v[206:207], v[228:229], v[172:173], v[206:207]
	v_pk_fma_f32 v[208:209], v[230:231], v[174:175], v[208:209]
	v_pk_mul_f32 v[252:253], v[194:195], v[194:195]
	v_pk_mul_f32 v[254:255], v[196:197], v[196:197]
	v_pk_fma_f32 v[252:253], v[198:199], v[198:199], v[252:253]
	v_pk_fma_f32 v[254:255], v[200:201], v[200:201], v[254:255]
	v_pk_fma_f32 v[252:253], v[202:203], v[202:203], v[252:253]
	v_pk_fma_f32 v[254:255], v[204:205], v[204:205], v[254:255]
	v_pk_fma_f32 v[252:253], v[206:207], v[206:207], v[252:253]
	v_pk_fma_f32 v[254:255], v[208:209], v[208:209], v[254:255]
	v_pk_add_f32 v[252:253], v[252:253], v[254:255]
	s_nop 0
	v_add_f32_e32 v183, v252, v253
	s_nop 1
	v_add_f32_dpp v183, v183, v183 quad_perm:[1,0,3,2] row_mask:0xf bank_mask:0xf bound_ctrl:1
	s_nop 1
	v_add_f32_dpp v183, v183, v183 quad_perm:[2,3,0,1] row_mask:0xf bank_mask:0xf bound_ctrl:1
	s_nop 1
	v_add_f32_dpp v183, v183, v183 row_half_mirror row_mask:0xf bank_mask:0xf bound_ctrl:1
	s_nop 1
	v_add_f32_dpp v183, v183, v183 row_mirror row_mask:0xf bank_mask:0xf bound_ctrl:1
	s_nop 1
	v_readlane_b32 s98, v183, 0
	v_readlane_b32 s99, v183, 16
	v_readlane_b32 s100, v183, 32
	v_readlane_b32 s101, v183, 48
	s_nop 1
	v_mov_b32_e32 v183, s98
	v_add_f32_e32 v183, s99, v183
	v_add_f32_e32 v183, s100, v183
	v_add_f32_e32 v183, s101, v183
	v_fmamk_f32 v183, v183, 0x3a800000, v182
	v_cmp_gt_f32_e32 vcc, 0x800000, v183
	v_mul_f32_e32 v181, 0x4b800000, v183
	s_nop 1
	v_cndmask_b32_e32 v183, v183, v181, vcc
	v_rsq_f32_e32 v183, v183
	s_nop 0
	v_mul_f32_e32 v181, 0x45800000, v183
	v_cndmask_b32_e32 v184, v183, v181, vcc
	v_mov_b32_e32 v185, v184
	v_cvt_pk_bf16_f32 v48, v194, v195
	v_cvt_pk_bf16_f32 v49, v196, v197
	v_cvt_pk_bf16_f32 v50, v198, v199
	v_cvt_pk_bf16_f32 v51, v200, v201
	v_cvt_pk_bf16_f32 v52, v202, v203
	v_cvt_pk_bf16_f32 v53, v204, v205
	v_cvt_pk_bf16_f32 v54, v206, v207
	v_cvt_pk_bf16_f32 v55, v208, v209
	v_add_u32_e32 v181, 0x2400000, v177
	global_store_dwordx4 v181, v[48:51], s[78:79]
	global_store_dwordx4 v181, v[52:55], s[78:79] offset:1024
	v_add_u32_e32 v236, 0x6000, v237
	s_mov_b64 exec, 1
	global_store_dword v236, v184, s[78:79]
	s_mov_b64 exec, -1
	s_waitcnt vmcnt(20)
	v_lshlrev_b32_e32 v194, 16, v64
	v_and_b32_e32 v195, 0xffff0000, v64
	v_lshlrev_b32_e32 v196, 16, v65
	v_and_b32_e32 v197, 0xffff0000, v65
	v_lshlrev_b32_e32 v198, 16, v66
	v_and_b32_e32 v199, 0xffff0000, v66
	v_lshlrev_b32_e32 v200, 16, v67
	v_and_b32_e32 v201, 0xffff0000, v67
	v_lshlrev_b32_e32 v202, 16, v68
	v_and_b32_e32 v203, 0xffff0000, v68
	v_lshlrev_b32_e32 v204, 16, v69
	v_and_b32_e32 v205, 0xffff0000, v69
	v_lshlrev_b32_e32 v206, 16, v70
	v_and_b32_e32 v207, 0xffff0000, v70
	v_lshlrev_b32_e32 v208, 16, v71
	v_and_b32_e32 v209, 0xffff0000, v71
	v_lshlrev_b32_e32 v216, 16, v72
	v_and_b32_e32 v217, 0xffff0000, v72
	v_lshlrev_b32_e32 v218, 16, v73
	v_and_b32_e32 v219, 0xffff0000, v73
	v_lshlrev_b32_e32 v220, 16, v74
	v_and_b32_e32 v221, 0xffff0000, v74
	v_lshlrev_b32_e32 v222, 16, v75
	v_and_b32_e32 v223, 0xffff0000, v75
	v_lshlrev_b32_e32 v224, 16, v76
	v_and_b32_e32 v225, 0xffff0000, v76
	v_lshlrev_b32_e32 v226, 16, v77
	v_and_b32_e32 v227, 0xffff0000, v77
	v_lshlrev_b32_e32 v228, 16, v78
	v_and_b32_e32 v229, 0xffff0000, v78
	v_lshlrev_b32_e32 v230, 16, v79
	v_and_b32_e32 v231, 0xffff0000, v79
	v_pk_mul_f32 v[252:253], v[216:217], v[216:217]
	v_pk_mul_f32 v[254:255], v[218:219], v[218:219]
	v_pk_fma_f32 v[252:253], v[220:221], v[220:221], v[252:253]
	v_pk_fma_f32 v[254:255], v[222:223], v[222:223], v[254:255]
	v_pk_fma_f32 v[252:253], v[224:225], v[224:225], v[252:253]
	v_pk_fma_f32 v[254:255], v[226:227], v[226:227], v[254:255]
	v_pk_fma_f32 v[252:253], v[228:229], v[228:229], v[252:253]
	v_pk_fma_f32 v[254:255], v[230:231], v[230:231], v[254:255]
	v_pk_add_f32 v[252:253], v[252:253], v[254:255]
	s_nop 0
	v_add_f32_e32 v183, v252, v253
	s_nop 1
	v_add_f32_dpp v183, v183, v183 quad_perm:[1,0,3,2] row_mask:0xf bank_mask:0xf bound_ctrl:1
	s_nop 1
	v_add_f32_dpp v183, v183, v183 quad_perm:[2,3,0,1] row_mask:0xf bank_mask:0xf bound_ctrl:1
	s_nop 1
	v_add_f32_dpp v183, v183, v183 row_half_mirror row_mask:0xf bank_mask:0xf bound_ctrl:1
	s_nop 1
	v_add_f32_dpp v183, v183, v183 row_mirror row_mask:0xf bank_mask:0xf bound_ctrl:1
	s_nop 1
	v_readlane_b32 s98, v183, 0
	v_readlane_b32 s99, v183, 16
	v_readlane_b32 s100, v183, 32
	v_readlane_b32 s101, v183, 48
	s_nop 1
	v_mov_b32_e32 v183, s98
	v_add_f32_e32 v183, s99, v183
	v_add_f32_e32 v183, s100, v183
	v_add_f32_e32 v183, s101, v183
	v_fmamk_f32 v183, v183, 0x3a800000, v182
	v_cmp_gt_f32_e32 vcc, 0x800000, v183
	v_mul_f32_e32 v181, 0x4b800000, v183
	s_nop 1
	v_cndmask_b32_e32 v183, v183, v181, vcc
	v_rsq_f32_e32 v183, v183
	s_nop 0
	v_mul_f32_e32 v181, 0x45800000, v183
	v_cndmask_b32_e32 v184, v183, v181, vcc
	v_mov_b32_e32 v185, v184
	v_pk_mul_f32 v[216:217], v[216:217], v[184:185]
	v_pk_mul_f32 v[218:219], v[218:219], v[184:185]
	v_pk_mul_f32 v[220:221], v[220:221], v[184:185]
	v_pk_mul_f32 v[222:223], v[222:223], v[184:185]
	v_pk_mul_f32 v[224:225], v[224:225], v[184:185]
	v_pk_mul_f32 v[226:227], v[226:227], v[184:185]
	v_pk_mul_f32 v[228:229], v[228:229], v[184:185]
	v_pk_mul_f32 v[230:231], v[230:231], v[184:185]
	v_pk_fma_f32 v[194:195], v[216:217], v[160:161], v[194:195]
	v_pk_fma_f32 v[196:197], v[218:219], v[162:163], v[196:197]
	v_pk_fma_f32 v[198:199], v[220:221], v[164:165], v[198:199]
	v_pk_fma_f32 v[200:201], v[222:223], v[166:167], v[200:201]
	v_pk_fma_f32 v[202:203], v[224:225], v[168:169], v[202:203]
	v_pk_fma_f32 v[204:205], v[226:227], v[170:171], v[204:205]
	v_pk_fma_f32 v[206:207], v[228:229], v[172:173], v[206:207]
	v_pk_fma_f32 v[208:209], v[230:231], v[174:175], v[208:209]
	v_pk_mul_f32 v[252:253], v[194:195], v[194:195]
	v_pk_mul_f32 v[254:255], v[196:197], v[196:197]
	v_pk_fma_f32 v[252:253], v[198:199], v[198:199], v[252:253]
	v_pk_fma_f32 v[254:255], v[200:201], v[200:201], v[254:255]
	v_pk_fma_f32 v[252:253], v[202:203], v[202:203], v[252:253]
	v_pk_fma_f32 v[254:255], v[204:205], v[204:205], v[254:255]
	v_pk_fma_f32 v[252:253], v[206:207], v[206:207], v[252:253]
	v_pk_fma_f32 v[254:255], v[208:209], v[208:209], v[254:255]
	v_pk_add_f32 v[252:253], v[252:253], v[254:255]
	s_nop 0
	v_add_f32_e32 v183, v252, v253
	s_nop 1
	v_add_f32_dpp v183, v183, v183 quad_perm:[1,0,3,2] row_mask:0xf bank_mask:0xf bound_ctrl:1
	s_nop 1
	v_add_f32_dpp v183, v183, v183 quad_perm:[2,3,0,1] row_mask:0xf bank_mask:0xf bound_ctrl:1
	s_nop 1
	v_add_f32_dpp v183, v183, v183 row_half_mirror row_mask:0xf bank_mask:0xf bound_ctrl:1
	s_nop 1
	v_add_f32_dpp v183, v183, v183 row_mirror row_mask:0xf bank_mask:0xf bound_ctrl:1
	s_nop 1
	v_readlane_b32 s98, v183, 0
	v_readlane_b32 s99, v183, 16
	v_readlane_b32 s100, v183, 32
	v_readlane_b32 s101, v183, 48
	s_nop 1
	v_mov_b32_e32 v183, s98
	v_add_f32_e32 v183, s99, v183
	v_add_f32_e32 v183, s100, v183
	v_add_f32_e32 v183, s101, v183
	v_fmamk_f32 v183, v183, 0x3a800000, v182
	v_cmp_gt_f32_e32 vcc, 0x800000, v183
	v_mul_f32_e32 v181, 0x4b800000, v183
	s_nop 1
	v_cndmask_b32_e32 v183, v183, v181, vcc
	v_rsq_f32_e32 v183, v183
	s_nop 0
	v_mul_f32_e32 v181, 0x45800000, v183
	v_cndmask_b32_e32 v184, v183, v181, vcc
	v_mov_b32_e32 v185, v184
	v_cvt_pk_bf16_f32 v64, v194, v195
	v_cvt_pk_bf16_f32 v65, v196, v197
	v_cvt_pk_bf16_f32 v66, v198, v199
	v_cvt_pk_bf16_f32 v67, v200, v201
	v_cvt_pk_bf16_f32 v68, v202, v203
	v_cvt_pk_bf16_f32 v69, v204, v205
	v_cvt_pk_bf16_f32 v70, v206, v207
	v_cvt_pk_bf16_f32 v71, v208, v209
	v_add_u32_e32 v181, 0x2800000, v177
	global_store_dwordx4 v181, v[64:67], s[78:79]
	global_store_dwordx4 v181, v[68:71], s[78:79] offset:1024
	v_add_u32_e32 v236, 0x8000, v237
	s_mov_b64 exec, 1
	global_store_dword v236, v184, s[78:79]
	s_mov_b64 exec, -1
	s_waitcnt vmcnt(16)
	v_lshlrev_b32_e32 v194, 16, v80
	v_and_b32_e32 v195, 0xffff0000, v80
	v_lshlrev_b32_e32 v196, 16, v81
	v_and_b32_e32 v197, 0xffff0000, v81
	v_lshlrev_b32_e32 v198, 16, v82
	v_and_b32_e32 v199, 0xffff0000, v82
	v_lshlrev_b32_e32 v200, 16, v83
	v_and_b32_e32 v201, 0xffff0000, v83
	v_lshlrev_b32_e32 v202, 16, v84
	v_and_b32_e32 v203, 0xffff0000, v84
	v_lshlrev_b32_e32 v204, 16, v85
	v_and_b32_e32 v205, 0xffff0000, v85
	v_lshlrev_b32_e32 v206, 16, v86
	v_and_b32_e32 v207, 0xffff0000, v86
	v_lshlrev_b32_e32 v208, 16, v87
	v_and_b32_e32 v209, 0xffff0000, v87
	v_lshlrev_b32_e32 v216, 16, v88
	v_and_b32_e32 v217, 0xffff0000, v88
	v_lshlrev_b32_e32 v218, 16, v89
	v_and_b32_e32 v219, 0xffff0000, v89
	v_lshlrev_b32_e32 v220, 16, v90
	v_and_b32_e32 v221, 0xffff0000, v90
	v_lshlrev_b32_e32 v222, 16, v91
	v_and_b32_e32 v223, 0xffff0000, v91
	v_lshlrev_b32_e32 v224, 16, v92
	v_and_b32_e32 v225, 0xffff0000, v92
	v_lshlrev_b32_e32 v226, 16, v93
	v_and_b32_e32 v227, 0xffff0000, v93
	v_lshlrev_b32_e32 v228, 16, v94
	v_and_b32_e32 v229, 0xffff0000, v94
	v_lshlrev_b32_e32 v230, 16, v95
	v_and_b32_e32 v231, 0xffff0000, v95
	v_pk_mul_f32 v[252:253], v[216:217], v[216:217]
	v_pk_mul_f32 v[254:255], v[218:219], v[218:219]
	v_pk_fma_f32 v[252:253], v[220:221], v[220:221], v[252:253]
	v_pk_fma_f32 v[254:255], v[222:223], v[222:223], v[254:255]
	v_pk_fma_f32 v[252:253], v[224:225], v[224:225], v[252:253]
	v_pk_fma_f32 v[254:255], v[226:227], v[226:227], v[254:255]
	v_pk_fma_f32 v[252:253], v[228:229], v[228:229], v[252:253]
	v_pk_fma_f32 v[254:255], v[230:231], v[230:231], v[254:255]
	v_pk_add_f32 v[252:253], v[252:253], v[254:255]
	s_nop 0
	v_add_f32_e32 v183, v252, v253
	s_nop 1
	v_add_f32_dpp v183, v183, v183 quad_perm:[1,0,3,2] row_mask:0xf bank_mask:0xf bound_ctrl:1
	s_nop 1
	v_add_f32_dpp v183, v183, v183 quad_perm:[2,3,0,1] row_mask:0xf bank_mask:0xf bound_ctrl:1
	s_nop 1
	v_add_f32_dpp v183, v183, v183 row_half_mirror row_mask:0xf bank_mask:0xf bound_ctrl:1
	s_nop 1
	v_add_f32_dpp v183, v183, v183 row_mirror row_mask:0xf bank_mask:0xf bound_ctrl:1
	s_nop 1
	v_readlane_b32 s98, v183, 0
	v_readlane_b32 s99, v183, 16
	v_readlane_b32 s100, v183, 32
	v_readlane_b32 s101, v183, 48
	s_nop 1
	v_mov_b32_e32 v183, s98
	v_add_f32_e32 v183, s99, v183
	v_add_f32_e32 v183, s100, v183
	v_add_f32_e32 v183, s101, v183
	v_fmamk_f32 v183, v183, 0x3a800000, v182
	v_cmp_gt_f32_e32 vcc, 0x800000, v183
	v_mul_f32_e32 v181, 0x4b800000, v183
	s_nop 1
	v_cndmask_b32_e32 v183, v183, v181, vcc
	v_rsq_f32_e32 v183, v183
	s_nop 0
	v_mul_f32_e32 v181, 0x45800000, v183
	v_cndmask_b32_e32 v184, v183, v181, vcc
	v_mov_b32_e32 v185, v184
	v_pk_mul_f32 v[216:217], v[216:217], v[184:185]
	v_pk_mul_f32 v[218:219], v[218:219], v[184:185]
	v_pk_mul_f32 v[220:221], v[220:221], v[184:185]
	v_pk_mul_f32 v[222:223], v[222:223], v[184:185]
	v_pk_mul_f32 v[224:225], v[224:225], v[184:185]
	v_pk_mul_f32 v[226:227], v[226:227], v[184:185]
	v_pk_mul_f32 v[228:229], v[228:229], v[184:185]
	v_pk_mul_f32 v[230:231], v[230:231], v[184:185]
	v_pk_fma_f32 v[194:195], v[216:217], v[160:161], v[194:195]
	v_pk_fma_f32 v[196:197], v[218:219], v[162:163], v[196:197]
	v_pk_fma_f32 v[198:199], v[220:221], v[164:165], v[198:199]
	v_pk_fma_f32 v[200:201], v[222:223], v[166:167], v[200:201]
	v_pk_fma_f32 v[202:203], v[224:225], v[168:169], v[202:203]
	v_pk_fma_f32 v[204:205], v[226:227], v[170:171], v[204:205]
	v_pk_fma_f32 v[206:207], v[228:229], v[172:173], v[206:207]
	v_pk_fma_f32 v[208:209], v[230:231], v[174:175], v[208:209]
	v_pk_mul_f32 v[252:253], v[194:195], v[194:195]
	v_pk_mul_f32 v[254:255], v[196:197], v[196:197]
	v_pk_fma_f32 v[252:253], v[198:199], v[198:199], v[252:253]
	v_pk_fma_f32 v[254:255], v[200:201], v[200:201], v[254:255]
	v_pk_fma_f32 v[252:253], v[202:203], v[202:203], v[252:253]
	v_pk_fma_f32 v[254:255], v[204:205], v[204:205], v[254:255]
	v_pk_fma_f32 v[252:253], v[206:207], v[206:207], v[252:253]
	v_pk_fma_f32 v[254:255], v[208:209], v[208:209], v[254:255]
	v_pk_add_f32 v[252:253], v[252:253], v[254:255]
	s_nop 0
	v_add_f32_e32 v183, v252, v253
	s_nop 1
	v_add_f32_dpp v183, v183, v183 quad_perm:[1,0,3,2] row_mask:0xf bank_mask:0xf bound_ctrl:1
	s_nop 1
	v_add_f32_dpp v183, v183, v183 quad_perm:[2,3,0,1] row_mask:0xf bank_mask:0xf bound_ctrl:1
	s_nop 1
	v_add_f32_dpp v183, v183, v183 row_half_mirror row_mask:0xf bank_mask:0xf bound_ctrl:1
	s_nop 1
	v_add_f32_dpp v183, v183, v183 row_mirror row_mask:0xf bank_mask:0xf bound_ctrl:1
	s_nop 1
	v_readlane_b32 s98, v183, 0
	v_readlane_b32 s99, v183, 16
	v_readlane_b32 s100, v183, 32
	v_readlane_b32 s101, v183, 48
	s_nop 1
	v_mov_b32_e32 v183, s98
	v_add_f32_e32 v183, s99, v183
	v_add_f32_e32 v183, s100, v183
	v_add_f32_e32 v183, s101, v183
	v_fmamk_f32 v183, v183, 0x3a800000, v182
	v_cmp_gt_f32_e32 vcc, 0x800000, v183
	v_mul_f32_e32 v181, 0x4b800000, v183
	s_nop 1
	v_cndmask_b32_e32 v183, v183, v181, vcc
	v_rsq_f32_e32 v183, v183
	s_nop 0
	v_mul_f32_e32 v181, 0x45800000, v183
	v_cndmask_b32_e32 v184, v183, v181, vcc
	v_mov_b32_e32 v185, v184
	v_cvt_pk_bf16_f32 v80, v194, v195
	v_cvt_pk_bf16_f32 v81, v196, v197
	v_cvt_pk_bf16_f32 v82, v198, v199
	v_cvt_pk_bf16_f32 v83, v200, v201
	v_cvt_pk_bf16_f32 v84, v202, v203
	v_cvt_pk_bf16_f32 v85, v204, v205
	v_cvt_pk_bf16_f32 v86, v206, v207
	v_cvt_pk_bf16_f32 v87, v208, v209
	v_add_u32_e32 v181, 0x2c00000, v177
	global_store_dwordx4 v181, v[80:83], s[78:79]
	global_store_dwordx4 v181, v[84:87], s[78:79] offset:1024
	v_add_u32_e32 v236, 0xa000, v237
	s_mov_b64 exec, 1
	global_store_dword v236, v184, s[78:79]
	s_mov_b64 exec, -1
	s_waitcnt vmcnt(12)
	v_lshlrev_b32_e32 v194, 16, v96
	v_and_b32_e32 v195, 0xffff0000, v96
	v_lshlrev_b32_e32 v196, 16, v97
	v_and_b32_e32 v197, 0xffff0000, v97
	v_lshlrev_b32_e32 v198, 16, v98
	v_and_b32_e32 v199, 0xffff0000, v98
	v_lshlrev_b32_e32 v200, 16, v99
	v_and_b32_e32 v201, 0xffff0000, v99
	v_lshlrev_b32_e32 v202, 16, v100
	v_and_b32_e32 v203, 0xffff0000, v100
	v_lshlrev_b32_e32 v204, 16, v101
	v_and_b32_e32 v205, 0xffff0000, v101
	v_lshlrev_b32_e32 v206, 16, v102
	v_and_b32_e32 v207, 0xffff0000, v102
	v_lshlrev_b32_e32 v208, 16, v103
	v_and_b32_e32 v209, 0xffff0000, v103
	v_lshlrev_b32_e32 v216, 16, v104
	v_and_b32_e32 v217, 0xffff0000, v104
	v_lshlrev_b32_e32 v218, 16, v105
	v_and_b32_e32 v219, 0xffff0000, v105
	v_lshlrev_b32_e32 v220, 16, v106
	v_and_b32_e32 v221, 0xffff0000, v106
	v_lshlrev_b32_e32 v222, 16, v107
	v_and_b32_e32 v223, 0xffff0000, v107
	v_lshlrev_b32_e32 v224, 16, v108
	v_and_b32_e32 v225, 0xffff0000, v108
	v_lshlrev_b32_e32 v226, 16, v109
	v_and_b32_e32 v227, 0xffff0000, v109
	v_lshlrev_b32_e32 v228, 16, v110
	v_and_b32_e32 v229, 0xffff0000, v110
	v_lshlrev_b32_e32 v230, 16, v111
	v_and_b32_e32 v231, 0xffff0000, v111
	v_pk_mul_f32 v[252:253], v[216:217], v[216:217]
	v_pk_mul_f32 v[254:255], v[218:219], v[218:219]
	v_pk_fma_f32 v[252:253], v[220:221], v[220:221], v[252:253]
	v_pk_fma_f32 v[254:255], v[222:223], v[222:223], v[254:255]
	v_pk_fma_f32 v[252:253], v[224:225], v[224:225], v[252:253]
	v_pk_fma_f32 v[254:255], v[226:227], v[226:227], v[254:255]
	v_pk_fma_f32 v[252:253], v[228:229], v[228:229], v[252:253]
	v_pk_fma_f32 v[254:255], v[230:231], v[230:231], v[254:255]
	v_pk_add_f32 v[252:253], v[252:253], v[254:255]
	s_nop 0
	v_add_f32_e32 v183, v252, v253
	s_nop 1
	v_add_f32_dpp v183, v183, v183 quad_perm:[1,0,3,2] row_mask:0xf bank_mask:0xf bound_ctrl:1
	s_nop 1
	v_add_f32_dpp v183, v183, v183 quad_perm:[2,3,0,1] row_mask:0xf bank_mask:0xf bound_ctrl:1
	s_nop 1
	v_add_f32_dpp v183, v183, v183 row_half_mirror row_mask:0xf bank_mask:0xf bound_ctrl:1
	s_nop 1
	v_add_f32_dpp v183, v183, v183 row_mirror row_mask:0xf bank_mask:0xf bound_ctrl:1
	s_nop 1
	v_readlane_b32 s98, v183, 0
	v_readlane_b32 s99, v183, 16
	v_readlane_b32 s100, v183, 32
	v_readlane_b32 s101, v183, 48
	s_nop 1
	v_mov_b32_e32 v183, s98
	v_add_f32_e32 v183, s99, v183
	v_add_f32_e32 v183, s100, v183
	v_add_f32_e32 v183, s101, v183
	v_fmamk_f32 v183, v183, 0x3a800000, v182
	v_cmp_gt_f32_e32 vcc, 0x800000, v183
	v_mul_f32_e32 v181, 0x4b800000, v183
	s_nop 1
	v_cndmask_b32_e32 v183, v183, v181, vcc
	v_rsq_f32_e32 v183, v183
	s_nop 0
	v_mul_f32_e32 v181, 0x45800000, v183
	v_cndmask_b32_e32 v184, v183, v181, vcc
	v_mov_b32_e32 v185, v184
	v_pk_mul_f32 v[216:217], v[216:217], v[184:185]
	v_pk_mul_f32 v[218:219], v[218:219], v[184:185]
	v_pk_mul_f32 v[220:221], v[220:221], v[184:185]
	v_pk_mul_f32 v[222:223], v[222:223], v[184:185]
	v_pk_mul_f32 v[224:225], v[224:225], v[184:185]
	v_pk_mul_f32 v[226:227], v[226:227], v[184:185]
	v_pk_mul_f32 v[228:229], v[228:229], v[184:185]
	v_pk_mul_f32 v[230:231], v[230:231], v[184:185]
	v_pk_fma_f32 v[194:195], v[216:217], v[160:161], v[194:195]
	v_pk_fma_f32 v[196:197], v[218:219], v[162:163], v[196:197]
	v_pk_fma_f32 v[198:199], v[220:221], v[164:165], v[198:199]
	v_pk_fma_f32 v[200:201], v[222:223], v[166:167], v[200:201]
	v_pk_fma_f32 v[202:203], v[224:225], v[168:169], v[202:203]
	v_pk_fma_f32 v[204:205], v[226:227], v[170:171], v[204:205]
	v_pk_fma_f32 v[206:207], v[228:229], v[172:173], v[206:207]
	v_pk_fma_f32 v[208:209], v[230:231], v[174:175], v[208:209]
	v_pk_mul_f32 v[252:253], v[194:195], v[194:195]
	v_pk_mul_f32 v[254:255], v[196:197], v[196:197]
	v_pk_fma_f32 v[252:253], v[198:199], v[198:199], v[252:253]
	v_pk_fma_f32 v[254:255], v[200:201], v[200:201], v[254:255]
	v_pk_fma_f32 v[252:253], v[202:203], v[202:203], v[252:253]
	v_pk_fma_f32 v[254:255], v[204:205], v[204:205], v[254:255]
	v_pk_fma_f32 v[252:253], v[206:207], v[206:207], v[252:253]
	v_pk_fma_f32 v[254:255], v[208:209], v[208:209], v[254:255]
	v_pk_add_f32 v[252:253], v[252:253], v[254:255]
	s_nop 0
	v_add_f32_e32 v183, v252, v253
	s_nop 1
	v_add_f32_dpp v183, v183, v183 quad_perm:[1,0,3,2] row_mask:0xf bank_mask:0xf bound_ctrl:1
	s_nop 1
	v_add_f32_dpp v183, v183, v183 quad_perm:[2,3,0,1] row_mask:0xf bank_mask:0xf bound_ctrl:1
	s_nop 1
	v_add_f32_dpp v183, v183, v183 row_half_mirror row_mask:0xf bank_mask:0xf bound_ctrl:1
	s_nop 1
	v_add_f32_dpp v183, v183, v183 row_mirror row_mask:0xf bank_mask:0xf bound_ctrl:1
	s_nop 1
	v_readlane_b32 s98, v183, 0
	v_readlane_b32 s99, v183, 16
	v_readlane_b32 s100, v183, 32
	v_readlane_b32 s101, v183, 48
	s_nop 1
	v_mov_b32_e32 v183, s98
	v_add_f32_e32 v183, s99, v183
	v_add_f32_e32 v183, s100, v183
	v_add_f32_e32 v183, s101, v183
	v_fmamk_f32 v183, v183, 0x3a800000, v182
	v_cmp_gt_f32_e32 vcc, 0x800000, v183
	v_mul_f32_e32 v181, 0x4b800000, v183
	s_nop 1
	v_cndmask_b32_e32 v183, v183, v181, vcc
	v_rsq_f32_e32 v183, v183
	s_nop 0
	v_mul_f32_e32 v181, 0x45800000, v183
	v_cndmask_b32_e32 v184, v183, v181, vcc
	v_mov_b32_e32 v185, v184
	v_cvt_pk_bf16_f32 v96, v194, v195
	v_cvt_pk_bf16_f32 v97, v196, v197
	v_cvt_pk_bf16_f32 v98, v198, v199
	v_cvt_pk_bf16_f32 v99, v200, v201
	v_cvt_pk_bf16_f32 v100, v202, v203
	v_cvt_pk_bf16_f32 v101, v204, v205
	v_cvt_pk_bf16_f32 v102, v206, v207
	v_cvt_pk_bf16_f32 v103, v208, v209
	v_add_u32_e32 v181, 0x3000000, v177
	global_store_dwordx4 v181, v[96:99], s[78:79]
	global_store_dwordx4 v181, v[100:103], s[78:79] offset:1024
	v_add_u32_e32 v236, 0xc000, v237
	s_mov_b64 exec, 1
	global_store_dword v236, v184, s[78:79]
	s_mov_b64 exec, -1
	s_waitcnt vmcnt(8)
	v_lshlrev_b32_e32 v194, 16, v112
	v_and_b32_e32 v195, 0xffff0000, v112
	v_lshlrev_b32_e32 v196, 16, v113
	v_and_b32_e32 v197, 0xffff0000, v113
	v_lshlrev_b32_e32 v198, 16, v114
	v_and_b32_e32 v199, 0xffff0000, v114
	v_lshlrev_b32_e32 v200, 16, v115
	v_and_b32_e32 v201, 0xffff0000, v115
	v_lshlrev_b32_e32 v202, 16, v116
	v_and_b32_e32 v203, 0xffff0000, v116
	v_lshlrev_b32_e32 v204, 16, v117
	v_and_b32_e32 v205, 0xffff0000, v117
	v_lshlrev_b32_e32 v206, 16, v118
	v_and_b32_e32 v207, 0xffff0000, v118
	v_lshlrev_b32_e32 v208, 16, v119
	v_and_b32_e32 v209, 0xffff0000, v119
	v_lshlrev_b32_e32 v216, 16, v120
	v_and_b32_e32 v217, 0xffff0000, v120
	v_lshlrev_b32_e32 v218, 16, v121
	v_and_b32_e32 v219, 0xffff0000, v121
	v_lshlrev_b32_e32 v220, 16, v122
	v_and_b32_e32 v221, 0xffff0000, v122
	v_lshlrev_b32_e32 v222, 16, v123
	v_and_b32_e32 v223, 0xffff0000, v123
	v_lshlrev_b32_e32 v224, 16, v124
	v_and_b32_e32 v225, 0xffff0000, v124
	v_lshlrev_b32_e32 v226, 16, v125
	v_and_b32_e32 v227, 0xffff0000, v125
	v_lshlrev_b32_e32 v228, 16, v126
	v_and_b32_e32 v229, 0xffff0000, v126
	v_lshlrev_b32_e32 v230, 16, v127
	v_and_b32_e32 v231, 0xffff0000, v127
	v_pk_mul_f32 v[252:253], v[216:217], v[216:217]
	v_pk_mul_f32 v[254:255], v[218:219], v[218:219]
	v_pk_fma_f32 v[252:253], v[220:221], v[220:221], v[252:253]
	v_pk_fma_f32 v[254:255], v[222:223], v[222:223], v[254:255]
	v_pk_fma_f32 v[252:253], v[224:225], v[224:225], v[252:253]
	v_pk_fma_f32 v[254:255], v[226:227], v[226:227], v[254:255]
	v_pk_fma_f32 v[252:253], v[228:229], v[228:229], v[252:253]
	v_pk_fma_f32 v[254:255], v[230:231], v[230:231], v[254:255]
	v_pk_add_f32 v[252:253], v[252:253], v[254:255]
	s_nop 0
	v_add_f32_e32 v183, v252, v253
	s_nop 1
	v_add_f32_dpp v183, v183, v183 quad_perm:[1,0,3,2] row_mask:0xf bank_mask:0xf bound_ctrl:1
	s_nop 1
	v_add_f32_dpp v183, v183, v183 quad_perm:[2,3,0,1] row_mask:0xf bank_mask:0xf bound_ctrl:1
	s_nop 1
	v_add_f32_dpp v183, v183, v183 row_half_mirror row_mask:0xf bank_mask:0xf bound_ctrl:1
	s_nop 1
	v_add_f32_dpp v183, v183, v183 row_mirror row_mask:0xf bank_mask:0xf bound_ctrl:1
	s_nop 1
	v_readlane_b32 s98, v183, 0
	v_readlane_b32 s99, v183, 16
	v_readlane_b32 s100, v183, 32
	v_readlane_b32 s101, v183, 48
	s_nop 1
	v_mov_b32_e32 v183, s98
	v_add_f32_e32 v183, s99, v183
	v_add_f32_e32 v183, s100, v183
	v_add_f32_e32 v183, s101, v183
	v_fmamk_f32 v183, v183, 0x3a800000, v182
	v_cmp_gt_f32_e32 vcc, 0x800000, v183
	v_mul_f32_e32 v181, 0x4b800000, v183
	s_nop 1
	v_cndmask_b32_e32 v183, v183, v181, vcc
	v_rsq_f32_e32 v183, v183
	s_nop 0
	v_mul_f32_e32 v181, 0x45800000, v183
	v_cndmask_b32_e32 v184, v183, v181, vcc
	v_mov_b32_e32 v185, v184
	v_pk_mul_f32 v[216:217], v[216:217], v[184:185]
	v_pk_mul_f32 v[218:219], v[218:219], v[184:185]
	v_pk_mul_f32 v[220:221], v[220:221], v[184:185]
	v_pk_mul_f32 v[222:223], v[222:223], v[184:185]
	v_pk_mul_f32 v[224:225], v[224:225], v[184:185]
	v_pk_mul_f32 v[226:227], v[226:227], v[184:185]
	v_pk_mul_f32 v[228:229], v[228:229], v[184:185]
	v_pk_mul_f32 v[230:231], v[230:231], v[184:185]
	v_pk_fma_f32 v[194:195], v[216:217], v[160:161], v[194:195]
	v_pk_fma_f32 v[196:197], v[218:219], v[162:163], v[196:197]
	v_pk_fma_f32 v[198:199], v[220:221], v[164:165], v[198:199]
	v_pk_fma_f32 v[200:201], v[222:223], v[166:167], v[200:201]
	v_pk_fma_f32 v[202:203], v[224:225], v[168:169], v[202:203]
	v_pk_fma_f32 v[204:205], v[226:227], v[170:171], v[204:205]
	v_pk_fma_f32 v[206:207], v[228:229], v[172:173], v[206:207]
	v_pk_fma_f32 v[208:209], v[230:231], v[174:175], v[208:209]
	v_pk_mul_f32 v[252:253], v[194:195], v[194:195]
	v_pk_mul_f32 v[254:255], v[196:197], v[196:197]
	v_pk_fma_f32 v[252:253], v[198:199], v[198:199], v[252:253]
	v_pk_fma_f32 v[254:255], v[200:201], v[200:201], v[254:255]
	v_pk_fma_f32 v[252:253], v[202:203], v[202:203], v[252:253]
	v_pk_fma_f32 v[254:255], v[204:205], v[204:205], v[254:255]
	v_pk_fma_f32 v[252:253], v[206:207], v[206:207], v[252:253]
	v_pk_fma_f32 v[254:255], v[208:209], v[208:209], v[254:255]
	v_pk_add_f32 v[252:253], v[252:253], v[254:255]
	s_nop 0
	v_add_f32_e32 v183, v252, v253
	s_nop 1
	v_add_f32_dpp v183, v183, v183 quad_perm:[1,0,3,2] row_mask:0xf bank_mask:0xf bound_ctrl:1
	s_nop 1
	v_add_f32_dpp v183, v183, v183 quad_perm:[2,3,0,1] row_mask:0xf bank_mask:0xf bound_ctrl:1
	s_nop 1
	v_add_f32_dpp v183, v183, v183 row_half_mirror row_mask:0xf bank_mask:0xf bound_ctrl:1
	s_nop 1
	v_add_f32_dpp v183, v183, v183 row_mirror row_mask:0xf bank_mask:0xf bound_ctrl:1
	s_nop 1
	v_readlane_b32 s98, v183, 0
	v_readlane_b32 s99, v183, 16
	v_readlane_b32 s100, v183, 32
	v_readlane_b32 s101, v183, 48
	s_nop 1
	v_mov_b32_e32 v183, s98
	v_add_f32_e32 v183, s99, v183
	v_add_f32_e32 v183, s100, v183
	v_add_f32_e32 v183, s101, v183
	v_fmamk_f32 v183, v183, 0x3a800000, v182
	v_cmp_gt_f32_e32 vcc, 0x800000, v183
	v_mul_f32_e32 v181, 0x4b800000, v183
	s_nop 1
	v_cndmask_b32_e32 v183, v183, v181, vcc
	v_rsq_f32_e32 v183, v183
	s_nop 0
	v_mul_f32_e32 v181, 0x45800000, v183
	v_cndmask_b32_e32 v184, v183, v181, vcc
	v_mov_b32_e32 v185, v184
	v_cvt_pk_bf16_f32 v112, v194, v195
	v_cvt_pk_bf16_f32 v113, v196, v197
	v_cvt_pk_bf16_f32 v114, v198, v199
	v_cvt_pk_bf16_f32 v115, v200, v201
	v_cvt_pk_bf16_f32 v116, v202, v203
	v_cvt_pk_bf16_f32 v117, v204, v205
	v_cvt_pk_bf16_f32 v118, v206, v207
	v_cvt_pk_bf16_f32 v119, v208, v209
	v_add_u32_e32 v181, 0x3400000, v177
	global_store_dwordx4 v181, v[112:115], s[78:79]
	global_store_dwordx4 v181, v[116:119], s[78:79] offset:1024
	v_add_u32_e32 v236, 0xe000, v237
	s_mov_b64 exec, 1
	global_store_dword v236, v184, s[78:79]
	s_mov_b64 exec, -1
	s_waitcnt vmcnt(4)
	v_lshlrev_b32_e32 v194, 16, v128
	v_and_b32_e32 v195, 0xffff0000, v128
	v_lshlrev_b32_e32 v196, 16, v129
	v_and_b32_e32 v197, 0xffff0000, v129
	v_lshlrev_b32_e32 v198, 16, v130
	v_and_b32_e32 v199, 0xffff0000, v130
	v_lshlrev_b32_e32 v200, 16, v131
	v_and_b32_e32 v201, 0xffff0000, v131
	v_lshlrev_b32_e32 v202, 16, v132
	v_and_b32_e32 v203, 0xffff0000, v132
	v_lshlrev_b32_e32 v204, 16, v133
	v_and_b32_e32 v205, 0xffff0000, v133
	v_lshlrev_b32_e32 v206, 16, v134
	v_and_b32_e32 v207, 0xffff0000, v134
	v_lshlrev_b32_e32 v208, 16, v135
	v_and_b32_e32 v209, 0xffff0000, v135
	v_lshlrev_b32_e32 v216, 16, v136
	v_and_b32_e32 v217, 0xffff0000, v136
	v_lshlrev_b32_e32 v218, 16, v137
	v_and_b32_e32 v219, 0xffff0000, v137
	v_lshlrev_b32_e32 v220, 16, v138
	v_and_b32_e32 v221, 0xffff0000, v138
	v_lshlrev_b32_e32 v222, 16, v139
	v_and_b32_e32 v223, 0xffff0000, v139
	v_lshlrev_b32_e32 v224, 16, v140
	v_and_b32_e32 v225, 0xffff0000, v140
	v_lshlrev_b32_e32 v226, 16, v141
	v_and_b32_e32 v227, 0xffff0000, v141
	v_lshlrev_b32_e32 v228, 16, v142
	v_and_b32_e32 v229, 0xffff0000, v142
	v_lshlrev_b32_e32 v230, 16, v143
	v_and_b32_e32 v231, 0xffff0000, v143
	v_pk_mul_f32 v[252:253], v[216:217], v[216:217]
	v_pk_mul_f32 v[254:255], v[218:219], v[218:219]
	v_pk_fma_f32 v[252:253], v[220:221], v[220:221], v[252:253]
	v_pk_fma_f32 v[254:255], v[222:223], v[222:223], v[254:255]
	v_pk_fma_f32 v[252:253], v[224:225], v[224:225], v[252:253]
	v_pk_fma_f32 v[254:255], v[226:227], v[226:227], v[254:255]
	v_pk_fma_f32 v[252:253], v[228:229], v[228:229], v[252:253]
	v_pk_fma_f32 v[254:255], v[230:231], v[230:231], v[254:255]
	v_pk_add_f32 v[252:253], v[252:253], v[254:255]
	s_nop 0
	v_add_f32_e32 v183, v252, v253
	s_nop 1
	v_add_f32_dpp v183, v183, v183 quad_perm:[1,0,3,2] row_mask:0xf bank_mask:0xf bound_ctrl:1
	s_nop 1
	v_add_f32_dpp v183, v183, v183 quad_perm:[2,3,0,1] row_mask:0xf bank_mask:0xf bound_ctrl:1
	s_nop 1
	v_add_f32_dpp v183, v183, v183 row_half_mirror row_mask:0xf bank_mask:0xf bound_ctrl:1
	s_nop 1
	v_add_f32_dpp v183, v183, v183 row_mirror row_mask:0xf bank_mask:0xf bound_ctrl:1
	s_nop 1
	v_readlane_b32 s98, v183, 0
	v_readlane_b32 s99, v183, 16
	v_readlane_b32 s100, v183, 32
	v_readlane_b32 s101, v183, 48
	s_nop 1
	v_mov_b32_e32 v183, s98
	v_add_f32_e32 v183, s99, v183
	v_add_f32_e32 v183, s100, v183
	v_add_f32_e32 v183, s101, v183
	v_fmamk_f32 v183, v183, 0x3a800000, v182
	v_cmp_gt_f32_e32 vcc, 0x800000, v183
	v_mul_f32_e32 v181, 0x4b800000, v183
	s_nop 1
	v_cndmask_b32_e32 v183, v183, v181, vcc
	v_rsq_f32_e32 v183, v183
	s_nop 0
	v_mul_f32_e32 v181, 0x45800000, v183
	v_cndmask_b32_e32 v184, v183, v181, vcc
	v_mov_b32_e32 v185, v184
	v_pk_mul_f32 v[216:217], v[216:217], v[184:185]
	v_pk_mul_f32 v[218:219], v[218:219], v[184:185]
	v_pk_mul_f32 v[220:221], v[220:221], v[184:185]
	v_pk_mul_f32 v[222:223], v[222:223], v[184:185]
	v_pk_mul_f32 v[224:225], v[224:225], v[184:185]
	v_pk_mul_f32 v[226:227], v[226:227], v[184:185]
	v_pk_mul_f32 v[228:229], v[228:229], v[184:185]
	v_pk_mul_f32 v[230:231], v[230:231], v[184:185]
	v_pk_fma_f32 v[194:195], v[216:217], v[160:161], v[194:195]
	v_pk_fma_f32 v[196:197], v[218:219], v[162:163], v[196:197]
	v_pk_fma_f32 v[198:199], v[220:221], v[164:165], v[198:199]
	v_pk_fma_f32 v[200:201], v[222:223], v[166:167], v[200:201]
	v_pk_fma_f32 v[202:203], v[224:225], v[168:169], v[202:203]
	v_pk_fma_f32 v[204:205], v[226:227], v[170:171], v[204:205]
	v_pk_fma_f32 v[206:207], v[228:229], v[172:173], v[206:207]
	v_pk_fma_f32 v[208:209], v[230:231], v[174:175], v[208:209]
	v_pk_mul_f32 v[252:253], v[194:195], v[194:195]
	v_pk_mul_f32 v[254:255], v[196:197], v[196:197]
	v_pk_fma_f32 v[252:253], v[198:199], v[198:199], v[252:253]
	v_pk_fma_f32 v[254:255], v[200:201], v[200:201], v[254:255]
	v_pk_fma_f32 v[252:253], v[202:203], v[202:203], v[252:253]
	v_pk_fma_f32 v[254:255], v[204:205], v[204:205], v[254:255]
	v_pk_fma_f32 v[252:253], v[206:207], v[206:207], v[252:253]
	v_pk_fma_f32 v[254:255], v[208:209], v[208:209], v[254:255]
	v_pk_add_f32 v[252:253], v[252:253], v[254:255]
	s_nop 0
	v_add_f32_e32 v183, v252, v253
	s_nop 1
	v_add_f32_dpp v183, v183, v183 quad_perm:[1,0,3,2] row_mask:0xf bank_mask:0xf bound_ctrl:1
	s_nop 1
	v_add_f32_dpp v183, v183, v183 quad_perm:[2,3,0,1] row_mask:0xf bank_mask:0xf bound_ctrl:1
	s_nop 1
	v_add_f32_dpp v183, v183, v183 row_half_mirror row_mask:0xf bank_mask:0xf bound_ctrl:1
	s_nop 1
	v_add_f32_dpp v183, v183, v183 row_mirror row_mask:0xf bank_mask:0xf bound_ctrl:1
	s_nop 1
	v_readlane_b32 s98, v183, 0
	v_readlane_b32 s99, v183, 16
	v_readlane_b32 s100, v183, 32
	v_readlane_b32 s101, v183, 48
	s_nop 1
	v_mov_b32_e32 v183, s98
	v_add_f32_e32 v183, s99, v183
	v_add_f32_e32 v183, s100, v183
	v_add_f32_e32 v183, s101, v183
	v_fmamk_f32 v183, v183, 0x3a800000, v182
	v_cmp_gt_f32_e32 vcc, 0x800000, v183
	v_mul_f32_e32 v181, 0x4b800000, v183
	s_nop 1
	v_cndmask_b32_e32 v183, v183, v181, vcc
	v_rsq_f32_e32 v183, v183
	s_nop 0
	v_mul_f32_e32 v181, 0x45800000, v183
	v_cndmask_b32_e32 v184, v183, v181, vcc
	v_mov_b32_e32 v185, v184
	v_cvt_pk_bf16_f32 v128, v194, v195
	v_cvt_pk_bf16_f32 v129, v196, v197
	v_cvt_pk_bf16_f32 v130, v198, v199
	v_cvt_pk_bf16_f32 v131, v200, v201
	v_cvt_pk_bf16_f32 v132, v202, v203
	v_cvt_pk_bf16_f32 v133, v204, v205
	v_cvt_pk_bf16_f32 v134, v206, v207
	v_cvt_pk_bf16_f32 v135, v208, v209
	v_add_u32_e32 v181, 0x1800000, v210
	global_store_dwordx4 v181, v[128:131], s[78:79]
	global_store_dwordx4 v181, v[132:135], s[78:79] offset:1024
	v_add_u32_e32 v236, 0x0, v211
	s_mov_b64 exec, 1
	global_store_dword v236, v184, s[78:79]
	s_mov_b64 exec, -1
	s_waitcnt vmcnt(0)
	v_lshlrev_b32_e32 v194, 16, v144
	v_and_b32_e32 v195, 0xffff0000, v144
	v_lshlrev_b32_e32 v196, 16, v145
	v_and_b32_e32 v197, 0xffff0000, v145
	v_lshlrev_b32_e32 v198, 16, v146
	v_and_b32_e32 v199, 0xffff0000, v146
	v_lshlrev_b32_e32 v200, 16, v147
	v_and_b32_e32 v201, 0xffff0000, v147
	v_lshlrev_b32_e32 v202, 16, v148
	v_and_b32_e32 v203, 0xffff0000, v148
	v_lshlrev_b32_e32 v204, 16, v149
	v_and_b32_e32 v205, 0xffff0000, v149
	v_lshlrev_b32_e32 v206, 16, v150
	v_and_b32_e32 v207, 0xffff0000, v150
	v_lshlrev_b32_e32 v208, 16, v151
	v_and_b32_e32 v209, 0xffff0000, v151
	v_lshlrev_b32_e32 v216, 16, v152
	v_and_b32_e32 v217, 0xffff0000, v152
	v_lshlrev_b32_e32 v218, 16, v153
	v_and_b32_e32 v219, 0xffff0000, v153
	v_lshlrev_b32_e32 v220, 16, v154
	v_and_b32_e32 v221, 0xffff0000, v154
	v_lshlrev_b32_e32 v222, 16, v155
	v_and_b32_e32 v223, 0xffff0000, v155
	v_lshlrev_b32_e32 v224, 16, v156
	v_and_b32_e32 v225, 0xffff0000, v156
	v_lshlrev_b32_e32 v226, 16, v157
	v_and_b32_e32 v227, 0xffff0000, v157
	v_lshlrev_b32_e32 v228, 16, v158
	v_and_b32_e32 v229, 0xffff0000, v158
	v_lshlrev_b32_e32 v230, 16, v159
	v_and_b32_e32 v231, 0xffff0000, v159
	v_pk_mul_f32 v[252:253], v[216:217], v[216:217]
	v_pk_mul_f32 v[254:255], v[218:219], v[218:219]
	v_pk_fma_f32 v[252:253], v[220:221], v[220:221], v[252:253]
	v_pk_fma_f32 v[254:255], v[222:223], v[222:223], v[254:255]
	v_pk_fma_f32 v[252:253], v[224:225], v[224:225], v[252:253]
	v_pk_fma_f32 v[254:255], v[226:227], v[226:227], v[254:255]
	v_pk_fma_f32 v[252:253], v[228:229], v[228:229], v[252:253]
	v_pk_fma_f32 v[254:255], v[230:231], v[230:231], v[254:255]
	v_pk_add_f32 v[252:253], v[252:253], v[254:255]
	s_nop 0
	v_add_f32_e32 v183, v252, v253
	s_nop 1
	v_add_f32_dpp v183, v183, v183 quad_perm:[1,0,3,2] row_mask:0xf bank_mask:0xf bound_ctrl:1
	s_nop 1
	v_add_f32_dpp v183, v183, v183 quad_perm:[2,3,0,1] row_mask:0xf bank_mask:0xf bound_ctrl:1
	s_nop 1
	v_add_f32_dpp v183, v183, v183 row_half_mirror row_mask:0xf bank_mask:0xf bound_ctrl:1
	s_nop 1
	v_add_f32_dpp v183, v183, v183 row_mirror row_mask:0xf bank_mask:0xf bound_ctrl:1
	s_nop 1
	v_readlane_b32 s98, v183, 0
	v_readlane_b32 s99, v183, 16
	v_readlane_b32 s100, v183, 32
	v_readlane_b32 s101, v183, 48
	s_nop 1
	v_mov_b32_e32 v183, s98
	v_add_f32_e32 v183, s99, v183
	v_add_f32_e32 v183, s100, v183
	v_add_f32_e32 v183, s101, v183
	v_fmamk_f32 v183, v183, 0x3a800000, v182
	v_cmp_gt_f32_e32 vcc, 0x800000, v183
	v_mul_f32_e32 v181, 0x4b800000, v183
	s_nop 1
	v_cndmask_b32_e32 v183, v183, v181, vcc
	v_rsq_f32_e32 v183, v183
	s_nop 0
	v_mul_f32_e32 v181, 0x45800000, v183
	v_cndmask_b32_e32 v184, v183, v181, vcc
	v_mov_b32_e32 v185, v184
	v_pk_mul_f32 v[216:217], v[216:217], v[184:185]
	v_pk_mul_f32 v[218:219], v[218:219], v[184:185]
	v_pk_mul_f32 v[220:221], v[220:221], v[184:185]
	v_pk_mul_f32 v[222:223], v[222:223], v[184:185]
	v_pk_mul_f32 v[224:225], v[224:225], v[184:185]
	v_pk_mul_f32 v[226:227], v[226:227], v[184:185]
	v_pk_mul_f32 v[228:229], v[228:229], v[184:185]
	v_pk_mul_f32 v[230:231], v[230:231], v[184:185]
	v_pk_fma_f32 v[194:195], v[216:217], v[160:161], v[194:195]
	v_pk_fma_f32 v[196:197], v[218:219], v[162:163], v[196:197]
	v_pk_fma_f32 v[198:199], v[220:221], v[164:165], v[198:199]
	v_pk_fma_f32 v[200:201], v[222:223], v[166:167], v[200:201]
	v_pk_fma_f32 v[202:203], v[224:225], v[168:169], v[202:203]
	v_pk_fma_f32 v[204:205], v[226:227], v[170:171], v[204:205]
	v_pk_fma_f32 v[206:207], v[228:229], v[172:173], v[206:207]
	v_pk_fma_f32 v[208:209], v[230:231], v[174:175], v[208:209]
	v_pk_mul_f32 v[252:253], v[194:195], v[194:195]
	v_pk_mul_f32 v[254:255], v[196:197], v[196:197]
	v_pk_fma_f32 v[252:253], v[198:199], v[198:199], v[252:253]
	v_pk_fma_f32 v[254:255], v[200:201], v[200:201], v[254:255]
	v_pk_fma_f32 v[252:253], v[202:203], v[202:203], v[252:253]
	v_pk_fma_f32 v[254:255], v[204:205], v[204:205], v[254:255]
	v_pk_fma_f32 v[252:253], v[206:207], v[206:207], v[252:253]
	v_pk_fma_f32 v[254:255], v[208:209], v[208:209], v[254:255]
	v_pk_add_f32 v[252:253], v[252:253], v[254:255]
	s_nop 0
	v_add_f32_e32 v183, v252, v253
	s_nop 1
	v_add_f32_dpp v183, v183, v183 quad_perm:[1,0,3,2] row_mask:0xf bank_mask:0xf bound_ctrl:1
	s_nop 1
	v_add_f32_dpp v183, v183, v183 quad_perm:[2,3,0,1] row_mask:0xf bank_mask:0xf bound_ctrl:1
	s_nop 1
	v_add_f32_dpp v183, v183, v183 row_half_mirror row_mask:0xf bank_mask:0xf bound_ctrl:1
	s_nop 1
	v_add_f32_dpp v183, v183, v183 row_mirror row_mask:0xf bank_mask:0xf bound_ctrl:1
	s_nop 1
	v_readlane_b32 s98, v183, 0
	v_readlane_b32 s99, v183, 16
	v_readlane_b32 s100, v183, 32
	v_readlane_b32 s101, v183, 48
	s_nop 1
	v_mov_b32_e32 v183, s98
	v_add_f32_e32 v183, s99, v183
	v_add_f32_e32 v183, s100, v183
	v_add_f32_e32 v183, s101, v183
	v_fmamk_f32 v183, v183, 0x3a800000, v182
	v_cmp_gt_f32_e32 vcc, 0x800000, v183
	v_mul_f32_e32 v181, 0x4b800000, v183
	s_nop 1
	v_cndmask_b32_e32 v183, v183, v181, vcc
	v_rsq_f32_e32 v183, v183
	s_nop 0
	v_mul_f32_e32 v181, 0x45800000, v183
	v_cndmask_b32_e32 v184, v183, v181, vcc
	v_mov_b32_e32 v185, v184
	v_cvt_pk_bf16_f32 v144, v194, v195
	v_cvt_pk_bf16_f32 v145, v196, v197
	v_cvt_pk_bf16_f32 v146, v198, v199
	v_cvt_pk_bf16_f32 v147, v200, v201
	v_cvt_pk_bf16_f32 v148, v202, v203
	v_cvt_pk_bf16_f32 v149, v204, v205
	v_cvt_pk_bf16_f32 v150, v206, v207
	v_cvt_pk_bf16_f32 v151, v208, v209
	v_add_u32_e32 v181, 0x1c00000, v210
	global_store_dwordx4 v181, v[144:147], s[78:79]
	global_store_dwordx4 v181, v[148:151], s[78:79] offset:1024
	v_add_u32_e32 v236, 0x2000, v211
	s_mov_b64 exec, 1
	global_store_dword v236, v184, s[78:79]
	s_mov_b64 exec, -1
	s_branch .Lmyxupd_done_4

.LBB0_2139:
	v_readlane_b32 s0, v235, 52
	v_readlane_b32 s1, v235, 53
	s_and_b64 vcc, exec, s[0:1]
	s_waitcnt lgkmcnt(0)
	s_barrier
	v_mbcnt_lo_u32_b32 v0, -1, 0
	v_mbcnt_hi_u32_b32 v0, -1, v0
	s_cbranch_vccnz .LBB0_2159
	v_lshlrev_b32_e32 v2, 3, v0
	v_readlane_b32 s4, v235, 4
	v_ashrrev_i32_e32 v3, 31, v2
	v_readlane_b32 s6, v235, 6
	v_readlane_b32 s7, v235, 7
	v_lshlrev_b64 v[4:5], 1, v[2:3]
	v_lshlrev_b64 v[2:3], 2, v[2:3]
	v_readlane_b32 s5, v235, 5
	v_readlane_b32 s10, v235, 10
	v_readlane_b32 s11, v235, 11
	v_readlane_b32 s18, v235, 18
	v_readlane_b32 s19, v235, 19
	v_readlane_b32 s6, v235, 61
	v_lshl_add_u64 v[154:155], s[90:91], 0, v[2:3]
	v_readlane_b32 s8, v235, 8
	v_lshl_add_u64 v[2:3], s[18:19], 0, v[2:3]
	s_mov_b64 s[0:1], 0x2000
	v_readlane_b32 s4, v235, 0
	v_readlane_b32 s7, v235, 62
	s_mov_b32 s10, s6
	s_ashr_i32 s11, s6, 31
	v_readlane_b32 s9, v235, 9
	v_lshl_add_u64 v[158:159], v[2:3], 0, s[0:1]
	s_lshl_b32 s4, s4, 4
	s_add_i32 s0, s6, 0xffffc000
	s_lshl_b64 s[6:7], s[10:11], 2
	s_mov_b32 s8, s10
	v_readlane_b32 s12, v235, 12
	v_readlane_b32 s13, v235, 13
	v_readlane_b32 s14, v235, 14
	v_readlane_b32 s15, v235, 15
	v_readlane_b32 s16, v235, 16
	v_readlane_b32 s17, v235, 17
	v_readlane_b32 s5, v235, 1
	s_add_u32 s80, s6, 0x10000
	v_writelane_b32 v235, s8, 61
	s_addc_u32 s12, s7, 0
	s_ashr_i32 s5, s4, 31
	v_writelane_b32 v235, s9, 62
	s_lshl_b64 s[8:9], s[10:11], 11
	v_lshl_add_u64 v[152:153], s[86:87], 0, v[4:5]
	v_lshl_add_u64 v[156:157], s[54:55], 0, v[4:5]
	s_mov_b32 s1, 0
	v_cmp_eq_u32_e64 s[16:17], 0, v0
	s_lshl_b64 s[6:7], s[4:5], 2
	v_lshl_add_u64 v[160:161], s[8:9], 0, v[4:5]
	s_lshl_b64 s[8:9], s[4:5], 11
	s_mov_b64 s[20:21], 0x600000
	s_mov_b64 s[22:23], 0x600800
	s_mov_b64 s[24:25], 0x800000
	s_mov_b32 s5, 0x800000
	s_mov_b64 s[26:27], 0x800800
	s_mov_b64 s[28:29], 0xa00000
	s_mov_b64 s[36:37], 0xa00800
	s_mov_b64 s[38:39], 0xc00000
	s_mov_b64 s[40:41], 0xc00800
	s_mov_b64 s[42:43], 0xe00000
	s_mov_b64 s[44:45], 0xe00800
	s_mov_b64 s[46:47], 0x1000000
	s_mov_b32 s13, 0x1000000
	s_mov_b64 s[48:49], 0x1000800
	s_mov_b64 s[50:51], 0x1200000
	s_mov_b32 s14, 0x1200000
	s_mov_b64 s[10:11], 0x1200800
	s_mov_b64 s[82:83], 0x1400000
	s_mov_b32 s15, 0x1400000
	s_mov_b64 s[90:91], 0x1400800
	v_mov_b32_e32 v215, 0
	v_mov_b32_e32 v216, 0x358637bd
	v_mbcnt_lo_u32_b32 v176, -1, 0
	v_mbcnt_hi_u32_b32 v176, -1, v176
	v_readlane_b32 s98, v235, 49
	v_readlane_b32 s99, v235, 20
	v_readlane_b32 s100, v235, 18
	v_readlane_b32 s101, v235, 19
	s_nop 3
	s_lshr_b32 vcc_lo, s98, 3
	s_and_b32 vcc_hi, vcc_lo, 7
	s_lshr_b32 vcc_lo, vcc_lo, 3
	s_lshl_b32 vcc_lo, vcc_lo, 3
	s_add_i32 vcc_lo, vcc_lo, s99
	s_lshl_b32 s98, vcc_hi, 8
	s_add_i32 s98, s98, vcc_lo
	v_mov_b32_e32 v179, s98
	v_lshlrev_b32_e32 v177, 4, v176
	s_lshl_b32 s99, s98, 11
	v_add_u32_e32 v177, s99, v177
	v_lshlrev_b32_e32 v180, 5, v176
	v_add_u32_e32 v181, 0x2000, v180
	global_load_dwordx4 v[160:163], v181, s[100:101]
	global_load_dwordx4 v[164:167], v181, s[100:101] offset:16
	global_load_dwordx4 v[168:171], v181, s[100:101] offset:2048
	global_load_dwordx4 v[172:175], v181, s[100:101] offset:2064
	v_mov_b32_e32 v182, 0x358637bd
	v_lshlrev_b32_e32 v237, 2, v179
	v_add_u32_e32 v237, 0x10000, v237
	s_and_b32 s99, s98, 3
	s_cmp_eq_u32 s99, 0
	s_cbranch_scc1 .Lmyxupd_s_5
	s_mul_i32 s100, s99, 0x7ff800
	v_add_u32_e32 v210, s100, v177
	s_mul_i32 s100, s99, 16380
	v_add_u32_e32 v211, s100, v237
	v_add_u32_e32 v178, 0x1800000, v177
	v_add_u32_e32 v181, 0x9e00000, v177
	global_load_dwordx4 v[0:3], v178, s[78:79]
	global_load_dwordx4 v[4:7], v178, s[78:79] offset:1024
	global_load_dwordx4 v[8:11], v181, s[78:79]
	global_load_dwordx4 v[12:15], v181, s[78:79] offset:1024
	v_add_u32_e32 v178, 0x1c00000, v177
	v_add_u32_e32 v181, 0xa200000, v177
	global_load_dwordx4 v[16:19], v178, s[78:79]
	global_load_dwordx4 v[20:23], v178, s[78:79] offset:1024
	global_load_dwordx4 v[24:27], v181, s[78:79]
	global_load_dwordx4 v[28:31], v181, s[78:79] offset:1024
	v_add_u32_e32 v178, 0x2000000, v177
	v_add_u32_e32 v181, 0xa600000, v177
	global_load_dwordx4 v[32:35], v178, s[78:79]
	global_load_dwordx4 v[36:39], v178, s[78:79] offset:1024
	global_load_dwordx4 v[40:43], v181, s[78:79]
	global_load_dwordx4 v[44:47], v181, s[78:79] offset:1024
	v_add_u32_e32 v178, 0x2400000, v177
	v_add_u32_e32 v181, 0xaa00000, v177
	global_load_dwordx4 v[48:51], v178, s[78:79]
	global_load_dwordx4 v[52:55], v178, s[78:79] offset:1024
	global_load_dwordx4 v[56:59], v181, s[78:79]
	global_load_dwordx4 v[60:63], v181, s[78:79] offset:1024
	v_add_u32_e32 v178, 0x2800000, v177
	v_add_u32_e32 v181, 0xae00000, v177
	global_load_dwordx4 v[64:67], v178, s[78:79]
	global_load_dwordx4 v[68:71], v178, s[78:79] offset:1024
	global_load_dwordx4 v[72:75], v181, s[78:79]
	global_load_dwordx4 v[76:79], v181, s[78:79] offset:1024
	v_add_u32_e32 v178, 0x2c00000, v177
	v_add_u32_e32 v181, 0xb200000, v177
	global_load_dwordx4 v[80:83], v178, s[78:79]
	global_load_dwordx4 v[84:87], v178, s[78:79] offset:1024
	global_load_dwordx4 v[88:91], v181, s[78:79]
	global_load_dwordx4 v[92:95], v181, s[78:79] offset:1024
	v_add_u32_e32 v178, 0x3000000, v177
	v_add_u32_e32 v181, 0xb600000, v177
	global_load_dwordx4 v[96:99], v178, s[78:79]
	global_load_dwordx4 v[100:103], v178, s[78:79] offset:1024
	global_load_dwordx4 v[104:107], v181, s[78:79]
	global_load_dwordx4 v[108:111], v181, s[78:79] offset:1024
	v_add_u32_e32 v178, 0x3400000, v177
	v_add_u32_e32 v181, 0xba00000, v177
	global_load_dwordx4 v[112:115], v178, s[78:79]
	global_load_dwordx4 v[116:119], v178, s[78:79] offset:1024
	global_load_dwordx4 v[120:123], v181, s[78:79]
	global_load_dwordx4 v[124:127], v181, s[78:79] offset:1024
	v_add_u32_e32 v178, 0x1800000, v210
	v_add_u32_e32 v181, 0x9e00000, v210
	global_load_dwordx4 v[128:131], v178, s[78:79]
	global_load_dwordx4 v[132:135], v178, s[78:79] offset:1024
	global_load_dwordx4 v[136:139], v181, s[78:79]
	global_load_dwordx4 v[140:143], v181, s[78:79] offset:1024
	v_add_u32_e32 v178, 0x1c00000, v210
	v_add_u32_e32 v181, 0xa200000, v210
	global_load_dwordx4 v[144:147], v178, s[78:79]
	global_load_dwordx4 v[148:151], v178, s[78:79] offset:1024
	global_load_dwordx4 v[152:155], v181, s[78:79]
	global_load_dwordx4 v[156:159], v181, s[78:79] offset:1024
	s_waitcnt vmcnt(36)
	v_lshlrev_b32_e32 v194, 16, v0
	v_and_b32_e32 v195, 0xffff0000, v0
	v_lshlrev_b32_e32 v196, 16, v1
	v_and_b32_e32 v197, 0xffff0000, v1
	v_lshlrev_b32_e32 v198, 16, v2
	v_and_b32_e32 v199, 0xffff0000, v2
	v_lshlrev_b32_e32 v200, 16, v3
	v_and_b32_e32 v201, 0xffff0000, v3
	v_lshlrev_b32_e32 v202, 16, v4
	v_and_b32_e32 v203, 0xffff0000, v4
	v_lshlrev_b32_e32 v204, 16, v5
	v_and_b32_e32 v205, 0xffff0000, v5
	v_lshlrev_b32_e32 v206, 16, v6
	v_and_b32_e32 v207, 0xffff0000, v6
	v_lshlrev_b32_e32 v208, 16, v7
	v_and_b32_e32 v209, 0xffff0000, v7
	v_lshlrev_b32_e32 v216, 16, v8
	v_and_b32_e32 v217, 0xffff0000, v8
	v_lshlrev_b32_e32 v218, 16, v9
	v_and_b32_e32 v219, 0xffff0000, v9
	v_lshlrev_b32_e32 v220, 16, v10
	v_and_b32_e32 v221, 0xffff0000, v10
	v_lshlrev_b32_e32 v222, 16, v11
	v_and_b32_e32 v223, 0xffff0000, v11
	v_lshlrev_b32_e32 v224, 16, v12
	v_and_b32_e32 v225, 0xffff0000, v12
	v_lshlrev_b32_e32 v226, 16, v13
	v_and_b32_e32 v227, 0xffff0000, v13
	v_lshlrev_b32_e32 v228, 16, v14
	v_and_b32_e32 v229, 0xffff0000, v14
	v_lshlrev_b32_e32 v230, 16, v15
	v_and_b32_e32 v231, 0xffff0000, v15
	v_pk_mul_f32 v[252:253], v[216:217], v[216:217]
	v_pk_mul_f32 v[254:255], v[218:219], v[218:219]
	v_pk_fma_f32 v[252:253], v[220:221], v[220:221], v[252:253]
	v_pk_fma_f32 v[254:255], v[222:223], v[222:223], v[254:255]
	v_pk_fma_f32 v[252:253], v[224:225], v[224:225], v[252:253]
	v_pk_fma_f32 v[254:255], v[226:227], v[226:227], v[254:255]
	v_pk_fma_f32 v[252:253], v[228:229], v[228:229], v[252:253]
	v_pk_fma_f32 v[254:255], v[230:231], v[230:231], v[254:255]
	v_pk_add_f32 v[252:253], v[252:253], v[254:255]
	s_nop 0
	v_add_f32_e32 v183, v252, v253
	s_nop 1
	v_add_f32_dpp v183, v183, v183 quad_perm:[1,0,3,2] row_mask:0xf bank_mask:0xf bound_ctrl:1
	s_nop 1
	v_add_f32_dpp v183, v183, v183 quad_perm:[2,3,0,1] row_mask:0xf bank_mask:0xf bound_ctrl:1
	s_nop 1
	v_add_f32_dpp v183, v183, v183 row_half_mirror row_mask:0xf bank_mask:0xf bound_ctrl:1
	s_nop 1
	v_add_f32_dpp v183, v183, v183 row_mirror row_mask:0xf bank_mask:0xf bound_ctrl:1
	s_nop 1
	v_readlane_b32 s98, v183, 0
	v_readlane_b32 s99, v183, 16
	v_readlane_b32 s100, v183, 32
	v_readlane_b32 s101, v183, 48
	s_nop 1
	v_mov_b32_e32 v183, s98
	v_add_f32_e32 v183, s99, v183
	v_add_f32_e32 v183, s100, v183
	v_add_f32_e32 v183, s101, v183
	v_fmamk_f32 v183, v183, 0x3a800000, v182
	v_cmp_gt_f32_e32 vcc, 0x800000, v183
	v_mul_f32_e32 v181, 0x4b800000, v183
	s_nop 1
	v_cndmask_b32_e32 v183, v183, v181, vcc
	v_rsq_f32_e32 v183, v183
	s_nop 0
	v_mul_f32_e32 v181, 0x45800000, v183
	v_cndmask_b32_e32 v184, v183, v181, vcc
	v_mov_b32_e32 v185, v184
	v_pk_mul_f32 v[216:217], v[216:217], v[184:185]
	v_pk_mul_f32 v[218:219], v[218:219], v[184:185]
	v_pk_mul_f32 v[220:221], v[220:221], v[184:185]
	v_pk_mul_f32 v[222:223], v[222:223], v[184:185]
	v_pk_mul_f32 v[224:225], v[224:225], v[184:185]
	v_pk_mul_f32 v[226:227], v[226:227], v[184:185]
	v_pk_mul_f32 v[228:229], v[228:229], v[184:185]
	v_pk_mul_f32 v[230:231], v[230:231], v[184:185]
	v_pk_fma_f32 v[194:195], v[216:217], v[160:161], v[194:195]
	v_pk_fma_f32 v[196:197], v[218:219], v[162:163], v[196:197]
	v_pk_fma_f32 v[198:199], v[220:221], v[164:165], v[198:199]
	v_pk_fma_f32 v[200:201], v[222:223], v[166:167], v[200:201]
	v_pk_fma_f32 v[202:203], v[224:225], v[168:169], v[202:203]
	v_pk_fma_f32 v[204:205], v[226:227], v[170:171], v[204:205]
	v_pk_fma_f32 v[206:207], v[228:229], v[172:173], v[206:207]
	v_pk_fma_f32 v[208:209], v[230:231], v[174:175], v[208:209]
	v_pk_mul_f32 v[252:253], v[194:195], v[194:195]
	v_pk_mul_f32 v[254:255], v[196:197], v[196:197]
	v_pk_fma_f32 v[252:253], v[198:199], v[198:199], v[252:253]
	v_pk_fma_f32 v[254:255], v[200:201], v[200:201], v[254:255]
	v_pk_fma_f32 v[252:253], v[202:203], v[202:203], v[252:253]
	v_pk_fma_f32 v[254:255], v[204:205], v[204:205], v[254:255]
	v_pk_fma_f32 v[252:253], v[206:207], v[206:207], v[252:253]
	v_pk_fma_f32 v[254:255], v[208:209], v[208:209], v[254:255]
	v_pk_add_f32 v[252:253], v[252:253], v[254:255]
	s_nop 0
	v_add_f32_e32 v183, v252, v253
	s_nop 1
	v_add_f32_dpp v183, v183, v183 quad_perm:[1,0,3,2] row_mask:0xf bank_mask:0xf bound_ctrl:1
	s_nop 1
	v_add_f32_dpp v183, v183, v183 quad_perm:[2,3,0,1] row_mask:0xf bank_mask:0xf bound_ctrl:1
	s_nop 1
	v_add_f32_dpp v183, v183, v183 row_half_mirror row_mask:0xf bank_mask:0xf bound_ctrl:1
	s_nop 1
	v_add_f32_dpp v183, v183, v183 row_mirror row_mask:0xf bank_mask:0xf bound_ctrl:1
	s_nop 1
	v_readlane_b32 s98, v183, 0
	v_readlane_b32 s99, v183, 16
	v_readlane_b32 s100, v183, 32
	v_readlane_b32 s101, v183, 48
	s_nop 1
	v_mov_b32_e32 v183, s98
	v_add_f32_e32 v183, s99, v183
	v_add_f32_e32 v183, s100, v183
	v_add_f32_e32 v183, s101, v183
	v_fmamk_f32 v183, v183, 0x3a800000, v182
	v_cmp_gt_f32_e32 vcc, 0x800000, v183
	v_mul_f32_e32 v181, 0x4b800000, v183
	s_nop 1
	v_cndmask_b32_e32 v183, v183, v181, vcc
	v_rsq_f32_e32 v183, v183
	s_nop 0
	v_mul_f32_e32 v181, 0x45800000, v183
	v_cndmask_b32_e32 v184, v183, v181, vcc
	v_mov_b32_e32 v185, v184
	v_cvt_pk_bf16_f32 v0, v194, v195
	v_cvt_pk_bf16_f32 v1, v196, v197
	v_cvt_pk_bf16_f32 v2, v198, v199
	v_cvt_pk_bf16_f32 v3, v200, v201
	v_cvt_pk_bf16_f32 v4, v202, v203
	v_cvt_pk_bf16_f32 v5, v204, v205
	v_cvt_pk_bf16_f32 v6, v206, v207
	v_cvt_pk_bf16_f32 v7, v208, v209
	v_add_u32_e32 v181, 0x1800000, v177
	global_store_dwordx4 v181, v[0:3], s[78:79]
	global_store_dwordx4 v181, v[4:7], s[78:79] offset:1024
	v_add_u32_e32 v236, 0x0, v237
	s_mov_b64 exec, 1
	global_store_dword v236, v184, s[78:79]
	s_mov_b64 exec, -1
	s_waitcnt vmcnt(32)
	v_lshlrev_b32_e32 v194, 16, v16
	v_and_b32_e32 v195, 0xffff0000, v16
	v_lshlrev_b32_e32 v196, 16, v17
	v_and_b32_e32 v197, 0xffff0000, v17
	v_lshlrev_b32_e32 v198, 16, v18
	v_and_b32_e32 v199, 0xffff0000, v18
	v_lshlrev_b32_e32 v200, 16, v19
	v_and_b32_e32 v201, 0xffff0000, v19
	v_lshlrev_b32_e32 v202, 16, v20
	v_and_b32_e32 v203, 0xffff0000, v20
	v_lshlrev_b32_e32 v204, 16, v21
	v_and_b32_e32 v205, 0xffff0000, v21
	v_lshlrev_b32_e32 v206, 16, v22
	v_and_b32_e32 v207, 0xffff0000, v22
	v_lshlrev_b32_e32 v208, 16, v23
	v_and_b32_e32 v209, 0xffff0000, v23
	v_lshlrev_b32_e32 v216, 16, v24
	v_and_b32_e32 v217, 0xffff0000, v24
	v_lshlrev_b32_e32 v218, 16, v25
	v_and_b32_e32 v219, 0xffff0000, v25
	v_lshlrev_b32_e32 v220, 16, v26
	v_and_b32_e32 v221, 0xffff0000, v26
	v_lshlrev_b32_e32 v222, 16, v27
	v_and_b32_e32 v223, 0xffff0000, v27
	v_lshlrev_b32_e32 v224, 16, v28
	v_and_b32_e32 v225, 0xffff0000, v28
	v_lshlrev_b32_e32 v226, 16, v29
	v_and_b32_e32 v227, 0xffff0000, v29
	v_lshlrev_b32_e32 v228, 16, v30
	v_and_b32_e32 v229, 0xffff0000, v30
	v_lshlrev_b32_e32 v230, 16, v31
	v_and_b32_e32 v231, 0xffff0000, v31
	v_pk_mul_f32 v[252:253], v[216:217], v[216:217]
	v_pk_mul_f32 v[254:255], v[218:219], v[218:219]
	v_pk_fma_f32 v[252:253], v[220:221], v[220:221], v[252:253]
	v_pk_fma_f32 v[254:255], v[222:223], v[222:223], v[254:255]
	v_pk_fma_f32 v[252:253], v[224:225], v[224:225], v[252:253]
	v_pk_fma_f32 v[254:255], v[226:227], v[226:227], v[254:255]
	v_pk_fma_f32 v[252:253], v[228:229], v[228:229], v[252:253]
	v_pk_fma_f32 v[254:255], v[230:231], v[230:231], v[254:255]
	v_pk_add_f32 v[252:253], v[252:253], v[254:255]
	s_nop 0
	v_add_f32_e32 v183, v252, v253
	s_nop 1
	v_add_f32_dpp v183, v183, v183 quad_perm:[1,0,3,2] row_mask:0xf bank_mask:0xf bound_ctrl:1
	s_nop 1
	v_add_f32_dpp v183, v183, v183 quad_perm:[2,3,0,1] row_mask:0xf bank_mask:0xf bound_ctrl:1
	s_nop 1
	v_add_f32_dpp v183, v183, v183 row_half_mirror row_mask:0xf bank_mask:0xf bound_ctrl:1
	s_nop 1
	v_add_f32_dpp v183, v183, v183 row_mirror row_mask:0xf bank_mask:0xf bound_ctrl:1
	s_nop 1
	v_readlane_b32 s98, v183, 0
	v_readlane_b32 s99, v183, 16
	v_readlane_b32 s100, v183, 32
	v_readlane_b32 s101, v183, 48
	s_nop 1
	v_mov_b32_e32 v183, s98
	v_add_f32_e32 v183, s99, v183
	v_add_f32_e32 v183, s100, v183
	v_add_f32_e32 v183, s101, v183
	v_fmamk_f32 v183, v183, 0x3a800000, v182
	v_cmp_gt_f32_e32 vcc, 0x800000, v183
	v_mul_f32_e32 v181, 0x4b800000, v183
	s_nop 1
	v_cndmask_b32_e32 v183, v183, v181, vcc
	v_rsq_f32_e32 v183, v183
	s_nop 0
	v_mul_f32_e32 v181, 0x45800000, v183
	v_cndmask_b32_e32 v184, v183, v181, vcc
	v_mov_b32_e32 v185, v184
	v_pk_mul_f32 v[216:217], v[216:217], v[184:185]
	v_pk_mul_f32 v[218:219], v[218:219], v[184:185]
	v_pk_mul_f32 v[220:221], v[220:221], v[184:185]
	v_pk_mul_f32 v[222:223], v[222:223], v[184:185]
	v_pk_mul_f32 v[224:225], v[224:225], v[184:185]
	v_pk_mul_f32 v[226:227], v[226:227], v[184:185]
	v_pk_mul_f32 v[228:229], v[228:229], v[184:185]
	v_pk_mul_f32 v[230:231], v[230:231], v[184:185]
	v_pk_fma_f32 v[194:195], v[216:217], v[160:161], v[194:195]
	v_pk_fma_f32 v[196:197], v[218:219], v[162:163], v[196:197]
	v_pk_fma_f32 v[198:199], v[220:221], v[164:165], v[198:199]
	v_pk_fma_f32 v[200:201], v[222:223], v[166:167], v[200:201]
	v_pk_fma_f32 v[202:203], v[224:225], v[168:169], v[202:203]
	v_pk_fma_f32 v[204:205], v[226:227], v[170:171], v[204:205]
	v_pk_fma_f32 v[206:207], v[228:229], v[172:173], v[206:207]
	v_pk_fma_f32 v[208:209], v[230:231], v[174:175], v[208:209]
	v_pk_mul_f32 v[252:253], v[194:195], v[194:195]
	v_pk_mul_f32 v[254:255], v[196:197], v[196:197]
	v_pk_fma_f32 v[252:253], v[198:199], v[198:199], v[252:253]
	v_pk_fma_f32 v[254:255], v[200:201], v[200:201], v[254:255]
	v_pk_fma_f32 v[252:253], v[202:203], v[202:203], v[252:253]
	v_pk_fma_f32 v[254:255], v[204:205], v[204:205], v[254:255]
	v_pk_fma_f32 v[252:253], v[206:207], v[206:207], v[252:253]
	v_pk_fma_f32 v[254:255], v[208:209], v[208:209], v[254:255]
	v_pk_add_f32 v[252:253], v[252:253], v[254:255]
	s_nop 0
	v_add_f32_e32 v183, v252, v253
	s_nop 1
	v_add_f32_dpp v183, v183, v183 quad_perm:[1,0,3,2] row_mask:0xf bank_mask:0xf bound_ctrl:1
	s_nop 1
	v_add_f32_dpp v183, v183, v183 quad_perm:[2,3,0,1] row_mask:0xf bank_mask:0xf bound_ctrl:1
	s_nop 1
	v_add_f32_dpp v183, v183, v183 row_half_mirror row_mask:0xf bank_mask:0xf bound_ctrl:1
	s_nop 1
	v_add_f32_dpp v183, v183, v183 row_mirror row_mask:0xf bank_mask:0xf bound_ctrl:1
	s_nop 1
	v_readlane_b32 s98, v183, 0
	v_readlane_b32 s99, v183, 16
	v_readlane_b32 s100, v183, 32
	v_readlane_b32 s101, v183, 48
	s_nop 1
	v_mov_b32_e32 v183, s98
	v_add_f32_e32 v183, s99, v183
	v_add_f32_e32 v183, s100, v183
	v_add_f32_e32 v183, s101, v183
	v_fmamk_f32 v183, v183, 0x3a800000, v182
	v_cmp_gt_f32_e32 vcc, 0x800000, v183
	v_mul_f32_e32 v181, 0x4b800000, v183
	s_nop 1
	v_cndmask_b32_e32 v183, v183, v181, vcc
	v_rsq_f32_e32 v183, v183
	s_nop 0
	v_mul_f32_e32 v181, 0x45800000, v183
	v_cndmask_b32_e32 v184, v183, v181, vcc
	v_mov_b32_e32 v185, v184
	v_cvt_pk_bf16_f32 v16, v194, v195
	v_cvt_pk_bf16_f32 v17, v196, v197
	v_cvt_pk_bf16_f32 v18, v198, v199
	v_cvt_pk_bf16_f32 v19, v200, v201
	v_cvt_pk_bf16_f32 v20, v202, v203
	v_cvt_pk_bf16_f32 v21, v204, v205
	v_cvt_pk_bf16_f32 v22, v206, v207
	v_cvt_pk_bf16_f32 v23, v208, v209
	v_add_u32_e32 v181, 0x1c00000, v177
	global_store_dwordx4 v181, v[16:19], s[78:79]
	global_store_dwordx4 v181, v[20:23], s[78:79] offset:1024
	v_add_u32_e32 v236, 0x2000, v237
	s_mov_b64 exec, 1
	global_store_dword v236, v184, s[78:79]
	s_mov_b64 exec, -1
	s_waitcnt vmcnt(28)
	v_lshlrev_b32_e32 v194, 16, v32
	v_and_b32_e32 v195, 0xffff0000, v32
	v_lshlrev_b32_e32 v196, 16, v33
	v_and_b32_e32 v197, 0xffff0000, v33
	v_lshlrev_b32_e32 v198, 16, v34
	v_and_b32_e32 v199, 0xffff0000, v34
	v_lshlrev_b32_e32 v200, 16, v35
	v_and_b32_e32 v201, 0xffff0000, v35
	v_lshlrev_b32_e32 v202, 16, v36
	v_and_b32_e32 v203, 0xffff0000, v36
	v_lshlrev_b32_e32 v204, 16, v37
	v_and_b32_e32 v205, 0xffff0000, v37
	v_lshlrev_b32_e32 v206, 16, v38
	v_and_b32_e32 v207, 0xffff0000, v38
	v_lshlrev_b32_e32 v208, 16, v39
	v_and_b32_e32 v209, 0xffff0000, v39
	v_lshlrev_b32_e32 v216, 16, v40
	v_and_b32_e32 v217, 0xffff0000, v40
	v_lshlrev_b32_e32 v218, 16, v41
	v_and_b32_e32 v219, 0xffff0000, v41
	v_lshlrev_b32_e32 v220, 16, v42
	v_and_b32_e32 v221, 0xffff0000, v42
	v_lshlrev_b32_e32 v222, 16, v43
	v_and_b32_e32 v223, 0xffff0000, v43
	v_lshlrev_b32_e32 v224, 16, v44
	v_and_b32_e32 v225, 0xffff0000, v44
	v_lshlrev_b32_e32 v226, 16, v45
	v_and_b32_e32 v227, 0xffff0000, v45
	v_lshlrev_b32_e32 v228, 16, v46
	v_and_b32_e32 v229, 0xffff0000, v46
	v_lshlrev_b32_e32 v230, 16, v47
	v_and_b32_e32 v231, 0xffff0000, v47
	v_pk_mul_f32 v[252:253], v[216:217], v[216:217]
	v_pk_mul_f32 v[254:255], v[218:219], v[218:219]
	v_pk_fma_f32 v[252:253], v[220:221], v[220:221], v[252:253]
	v_pk_fma_f32 v[254:255], v[222:223], v[222:223], v[254:255]
	v_pk_fma_f32 v[252:253], v[224:225], v[224:225], v[252:253]
	v_pk_fma_f32 v[254:255], v[226:227], v[226:227], v[254:255]
	v_pk_fma_f32 v[252:253], v[228:229], v[228:229], v[252:253]
	v_pk_fma_f32 v[254:255], v[230:231], v[230:231], v[254:255]
	v_pk_add_f32 v[252:253], v[252:253], v[254:255]
	s_nop 0
	v_add_f32_e32 v183, v252, v253
	s_nop 1
	v_add_f32_dpp v183, v183, v183 quad_perm:[1,0,3,2] row_mask:0xf bank_mask:0xf bound_ctrl:1
	s_nop 1
	v_add_f32_dpp v183, v183, v183 quad_perm:[2,3,0,1] row_mask:0xf bank_mask:0xf bound_ctrl:1
	s_nop 1
	v_add_f32_dpp v183, v183, v183 row_half_mirror row_mask:0xf bank_mask:0xf bound_ctrl:1
	s_nop 1
	v_add_f32_dpp v183, v183, v183 row_mirror row_mask:0xf bank_mask:0xf bound_ctrl:1
	s_nop 1
	v_readlane_b32 s98, v183, 0
	v_readlane_b32 s99, v183, 16
	v_readlane_b32 s100, v183, 32
	v_readlane_b32 s101, v183, 48
	s_nop 1
	v_mov_b32_e32 v183, s98
	v_add_f32_e32 v183, s99, v183
	v_add_f32_e32 v183, s100, v183
	v_add_f32_e32 v183, s101, v183
	v_fmamk_f32 v183, v183, 0x3a800000, v182
	v_cmp_gt_f32_e32 vcc, 0x800000, v183
	v_mul_f32_e32 v181, 0x4b800000, v183
	s_nop 1
	v_cndmask_b32_e32 v183, v183, v181, vcc
	v_rsq_f32_e32 v183, v183
	s_nop 0
	v_mul_f32_e32 v181, 0x45800000, v183
	v_cndmask_b32_e32 v184, v183, v181, vcc
	v_mov_b32_e32 v185, v184
	v_pk_mul_f32 v[216:217], v[216:217], v[184:185]
	v_pk_mul_f32 v[218:219], v[218:219], v[184:185]
	v_pk_mul_f32 v[220:221], v[220:221], v[184:185]
	v_pk_mul_f32 v[222:223], v[222:223], v[184:185]
	v_pk_mul_f32 v[224:225], v[224:225], v[184:185]
	v_pk_mul_f32 v[226:227], v[226:227], v[184:185]
	v_pk_mul_f32 v[228:229], v[228:229], v[184:185]
	v_pk_mul_f32 v[230:231], v[230:231], v[184:185]
	v_pk_fma_f32 v[194:195], v[216:217], v[160:161], v[194:195]
	v_pk_fma_f32 v[196:197], v[218:219], v[162:163], v[196:197]
	v_pk_fma_f32 v[198:199], v[220:221], v[164:165], v[198:199]
	v_pk_fma_f32 v[200:201], v[222:223], v[166:167], v[200:201]
	v_pk_fma_f32 v[202:203], v[224:225], v[168:169], v[202:203]
	v_pk_fma_f32 v[204:205], v[226:227], v[170:171], v[204:205]
	v_pk_fma_f32 v[206:207], v[228:229], v[172:173], v[206:207]
	v_pk_fma_f32 v[208:209], v[230:231], v[174:175], v[208:209]
	v_pk_mul_f32 v[252:253], v[194:195], v[194:195]
	v_pk_mul_f32 v[254:255], v[196:197], v[196:197]
	v_pk_fma_f32 v[252:253], v[198:199], v[198:199], v[252:253]
	v_pk_fma_f32 v[254:255], v[200:201], v[200:201], v[254:255]
	v_pk_fma_f32 v[252:253], v[202:203], v[202:203], v[252:253]
	v_pk_fma_f32 v[254:255], v[204:205], v[204:205], v[254:255]
	v_pk_fma_f32 v[252:253], v[206:207], v[206:207], v[252:253]
	v_pk_fma_f32 v[254:255], v[208:209], v[208:209], v[254:255]
	v_pk_add_f32 v[252:253], v[252:253], v[254:255]
	s_nop 0
	v_add_f32_e32 v183, v252, v253
	s_nop 1
	v_add_f32_dpp v183, v183, v183 quad_perm:[1,0,3,2] row_mask:0xf bank_mask:0xf bound_ctrl:1
	s_nop 1
	v_add_f32_dpp v183, v183, v183 quad_perm:[2,3,0,1] row_mask:0xf bank_mask:0xf bound_ctrl:1
	s_nop 1
	v_add_f32_dpp v183, v183, v183 row_half_mirror row_mask:0xf bank_mask:0xf bound_ctrl:1
	s_nop 1
	v_add_f32_dpp v183, v183, v183 row_mirror row_mask:0xf bank_mask:0xf bound_ctrl:1
	s_nop 1
	v_readlane_b32 s98, v183, 0
	v_readlane_b32 s99, v183, 16
	v_readlane_b32 s100, v183, 32
	v_readlane_b32 s101, v183, 48
	s_nop 1
	v_mov_b32_e32 v183, s98
	v_add_f32_e32 v183, s99, v183
	v_add_f32_e32 v183, s100, v183
	v_add_f32_e32 v183, s101, v183
	v_fmamk_f32 v183, v183, 0x3a800000, v182
	v_cmp_gt_f32_e32 vcc, 0x800000, v183
	v_mul_f32_e32 v181, 0x4b800000, v183
	s_nop 1
	v_cndmask_b32_e32 v183, v183, v181, vcc
	v_rsq_f32_e32 v183, v183
	s_nop 0
	v_mul_f32_e32 v181, 0x45800000, v183
	v_cndmask_b32_e32 v184, v183, v181, vcc
	v_mov_b32_e32 v185, v184
	v_cvt_pk_bf16_f32 v32, v194, v195
	v_cvt_pk_bf16_f32 v33, v196, v197
	v_cvt_pk_bf16_f32 v34, v198, v199
	v_cvt_pk_bf16_f32 v35, v200, v201
	v_cvt_pk_bf16_f32 v36, v202, v203
	v_cvt_pk_bf16_f32 v37, v204, v205
	v_cvt_pk_bf16_f32 v38, v206, v207
	v_cvt_pk_bf16_f32 v39, v208, v209
	v_add_u32_e32 v181, 0x2000000, v177
	global_store_dwordx4 v181, v[32:35], s[78:79]
	global_store_dwordx4 v181, v[36:39], s[78:79] offset:1024
	v_add_u32_e32 v236, 0x4000, v237
	s_mov_b64 exec, 1
	global_store_dword v236, v184, s[78:79]
	s_mov_b64 exec, -1
	s_waitcnt vmcnt(24)
	v_lshlrev_b32_e32 v194, 16, v48
	v_and_b32_e32 v195, 0xffff0000, v48
	v_lshlrev_b32_e32 v196, 16, v49
	v_and_b32_e32 v197, 0xffff0000, v49
	v_lshlrev_b32_e32 v198, 16, v50
	v_and_b32_e32 v199, 0xffff0000, v50
	v_lshlrev_b32_e32 v200, 16, v51
	v_and_b32_e32 v201, 0xffff0000, v51
	v_lshlrev_b32_e32 v202, 16, v52
	v_and_b32_e32 v203, 0xffff0000, v52
	v_lshlrev_b32_e32 v204, 16, v53
	v_and_b32_e32 v205, 0xffff0000, v53
	v_lshlrev_b32_e32 v206, 16, v54
	v_and_b32_e32 v207, 0xffff0000, v54
	v_lshlrev_b32_e32 v208, 16, v55
	v_and_b32_e32 v209, 0xffff0000, v55
	v_lshlrev_b32_e32 v216, 16, v56
	v_and_b32_e32 v217, 0xffff0000, v56
	v_lshlrev_b32_e32 v218, 16, v57
	v_and_b32_e32 v219, 0xffff0000, v57
	v_lshlrev_b32_e32 v220, 16, v58
	v_and_b32_e32 v221, 0xffff0000, v58
	v_lshlrev_b32_e32 v222, 16, v59
	v_and_b32_e32 v223, 0xffff0000, v59
	v_lshlrev_b32_e32 v224, 16, v60
	v_and_b32_e32 v225, 0xffff0000, v60
	v_lshlrev_b32_e32 v226, 16, v61
	v_and_b32_e32 v227, 0xffff0000, v61
	v_lshlrev_b32_e32 v228, 16, v62
	v_and_b32_e32 v229, 0xffff0000, v62
	v_lshlrev_b32_e32 v230, 16, v63
	v_and_b32_e32 v231, 0xffff0000, v63
	v_pk_mul_f32 v[252:253], v[216:217], v[216:217]
	v_pk_mul_f32 v[254:255], v[218:219], v[218:219]
	v_pk_fma_f32 v[252:253], v[220:221], v[220:221], v[252:253]
	v_pk_fma_f32 v[254:255], v[222:223], v[222:223], v[254:255]
	v_pk_fma_f32 v[252:253], v[224:225], v[224:225], v[252:253]
	v_pk_fma_f32 v[254:255], v[226:227], v[226:227], v[254:255]
	v_pk_fma_f32 v[252:253], v[228:229], v[228:229], v[252:253]
	v_pk_fma_f32 v[254:255], v[230:231], v[230:231], v[254:255]
	v_pk_add_f32 v[252:253], v[252:253], v[254:255]
	s_nop 0
	v_add_f32_e32 v183, v252, v253
	s_nop 1
	v_add_f32_dpp v183, v183, v183 quad_perm:[1,0,3,2] row_mask:0xf bank_mask:0xf bound_ctrl:1
	s_nop 1
	v_add_f32_dpp v183, v183, v183 quad_perm:[2,3,0,1] row_mask:0xf bank_mask:0xf bound_ctrl:1
	s_nop 1
	v_add_f32_dpp v183, v183, v183 row_half_mirror row_mask:0xf bank_mask:0xf bound_ctrl:1
	s_nop 1
	v_add_f32_dpp v183, v183, v183 row_mirror row_mask:0xf bank_mask:0xf bound_ctrl:1
	s_nop 1
	v_readlane_b32 s98, v183, 0
	v_readlane_b32 s99, v183, 16
	v_readlane_b32 s100, v183, 32
	v_readlane_b32 s101, v183, 48
	s_nop 1
	v_mov_b32_e32 v183, s98
	v_add_f32_e32 v183, s99, v183
	v_add_f32_e32 v183, s100, v183
	v_add_f32_e32 v183, s101, v183
	v_fmamk_f32 v183, v183, 0x3a800000, v182
	v_cmp_gt_f32_e32 vcc, 0x800000, v183
	v_mul_f32_e32 v181, 0x4b800000, v183
	s_nop 1
	v_cndmask_b32_e32 v183, v183, v181, vcc
	v_rsq_f32_e32 v183, v183
	s_nop 0
	v_mul_f32_e32 v181, 0x45800000, v183
	v_cndmask_b32_e32 v184, v183, v181, vcc
	v_mov_b32_e32 v185, v184
	v_pk_mul_f32 v[216:217], v[216:217], v[184:185]
	v_pk_mul_f32 v[218:219], v[218:219], v[184:185]
	v_pk_mul_f32 v[220:221], v[220:221], v[184:185]
	v_pk_mul_f32 v[222:223], v[222:223], v[184:185]
	v_pk_mul_f32 v[224:225], v[224:225], v[184:185]
	v_pk_mul_f32 v[226:227], v[226:227], v[184:185]
	v_pk_mul_f32 v[228:229], v[228:229], v[184:185]
	v_pk_mul_f32 v[230:231], v[230:231], v[184:185]
	v_pk_fma_f32 v[194:195], v[216:217], v[160:161], v[194:195]
	v_pk_fma_f32 v[196:197], v[218:219], v[162:163], v[196:197]
	v_pk_fma_f32 v[198:199], v[220:221], v[164:165], v[198:199]
	v_pk_fma_f32 v[200:201], v[222:223], v[166:167], v[200:201]
	v_pk_fma_f32 v[202:203], v[224:225], v[168:169], v[202:203]
	v_pk_fma_f32 v[204:205], v[226:227], v[170:171], v[204:205]
	v_pk_fma_f32 v[206:207], v[228:229], v[172:173], v[206:207]
	v_pk_fma_f32 v[208:209], v[230:231], v[174:175], v[208:209]
	v_pk_mul_f32 v[252:253], v[194:195], v[194:195]
	v_pk_mul_f32 v[254:255], v[196:197], v[196:197]
	v_pk_fma_f32 v[252:253], v[198:199], v[198:199], v[252:253]
	v_pk_fma_f32 v[254:255], v[200:201], v[200:201], v[254:255]
	v_pk_fma_f32 v[252:253], v[202:203], v[202:203], v[252:253]
	v_pk_fma_f32 v[254:255], v[204:205], v[204:205], v[254:255]
	v_pk_fma_f32 v[252:253], v[206:207], v[206:207], v[252:253]
	v_pk_fma_f32 v[254:255], v[208:209], v[208:209], v[254:255]
	v_pk_add_f32 v[252:253], v[252:253], v[254:255]
	s_nop 0
	v_add_f32_e32 v183, v252, v253
	s_nop 1
	v_add_f32_dpp v183, v183, v183 quad_perm:[1,0,3,2] row_mask:0xf bank_mask:0xf bound_ctrl:1
	s_nop 1
	v_add_f32_dpp v183, v183, v183 quad_perm:[2,3,0,1] row_mask:0xf bank_mask:0xf bound_ctrl:1
	s_nop 1
	v_add_f32_dpp v183, v183, v183 row_half_mirror row_mask:0xf bank_mask:0xf bound_ctrl:1
	s_nop 1
	v_add_f32_dpp v183, v183, v183 row_mirror row_mask:0xf bank_mask:0xf bound_ctrl:1
	s_nop 1
	v_readlane_b32 s98, v183, 0
	v_readlane_b32 s99, v183, 16
	v_readlane_b32 s100, v183, 32
	v_readlane_b32 s101, v183, 48
	s_nop 1
	v_mov_b32_e32 v183, s98
	v_add_f32_e32 v183, s99, v183
	v_add_f32_e32 v183, s100, v183
	v_add_f32_e32 v183, s101, v183
	v_fmamk_f32 v183, v183, 0x3a800000, v182
	v_cmp_gt_f32_e32 vcc, 0x800000, v183
	v_mul_f32_e32 v181, 0x4b800000, v183
	s_nop 1
	v_cndmask_b32_e32 v183, v183, v181, vcc
	v_rsq_f32_e32 v183, v183
	s_nop 0
	v_mul_f32_e32 v181, 0x45800000, v183
	v_cndmask_b32_e32 v184, v183, v181, vcc
	v_mov_b32_e32 v185, v184
	v_cvt_pk_bf16_f32 v48, v194, v195
	v_cvt_pk_bf16_f32 v49, v196, v197
	v_cvt_pk_bf16_f32 v50, v198, v199
	v_cvt_pk_bf16_f32 v51, v200, v201
	v_cvt_pk_bf16_f32 v52, v202, v203
	v_cvt_pk_bf16_f32 v53, v204, v205
	v_cvt_pk_bf16_f32 v54, v206, v207
	v_cvt_pk_bf16_f32 v55, v208, v209
	v_add_u32_e32 v181, 0x2400000, v177
	global_store_dwordx4 v181, v[48:51], s[78:79]
	global_store_dwordx4 v181, v[52:55], s[78:79] offset:1024
	v_add_u32_e32 v236, 0x6000, v237
	s_mov_b64 exec, 1
	global_store_dword v236, v184, s[78:79]
	s_mov_b64 exec, -1
	s_waitcnt vmcnt(20)
	v_lshlrev_b32_e32 v194, 16, v64
	v_and_b32_e32 v195, 0xffff0000, v64
	v_lshlrev_b32_e32 v196, 16, v65
	v_and_b32_e32 v197, 0xffff0000, v65
	v_lshlrev_b32_e32 v198, 16, v66
	v_and_b32_e32 v199, 0xffff0000, v66
	v_lshlrev_b32_e32 v200, 16, v67
	v_and_b32_e32 v201, 0xffff0000, v67
	v_lshlrev_b32_e32 v202, 16, v68
	v_and_b32_e32 v203, 0xffff0000, v68
	v_lshlrev_b32_e32 v204, 16, v69
	v_and_b32_e32 v205, 0xffff0000, v69
	v_lshlrev_b32_e32 v206, 16, v70
	v_and_b32_e32 v207, 0xffff0000, v70
	v_lshlrev_b32_e32 v208, 16, v71
	v_and_b32_e32 v209, 0xffff0000, v71
	v_lshlrev_b32_e32 v216, 16, v72
	v_and_b32_e32 v217, 0xffff0000, v72
	v_lshlrev_b32_e32 v218, 16, v73
	v_and_b32_e32 v219, 0xffff0000, v73
	v_lshlrev_b32_e32 v220, 16, v74
	v_and_b32_e32 v221, 0xffff0000, v74
	v_lshlrev_b32_e32 v222, 16, v75
	v_and_b32_e32 v223, 0xffff0000, v75
	v_lshlrev_b32_e32 v224, 16, v76
	v_and_b32_e32 v225, 0xffff0000, v76
	v_lshlrev_b32_e32 v226, 16, v77
	v_and_b32_e32 v227, 0xffff0000, v77
	v_lshlrev_b32_e32 v228, 16, v78
	v_and_b32_e32 v229, 0xffff0000, v78
	v_lshlrev_b32_e32 v230, 16, v79
	v_and_b32_e32 v231, 0xffff0000, v79
	v_pk_mul_f32 v[252:253], v[216:217], v[216:217]
	v_pk_mul_f32 v[254:255], v[218:219], v[218:219]
	v_pk_fma_f32 v[252:253], v[220:221], v[220:221], v[252:253]
	v_pk_fma_f32 v[254:255], v[222:223], v[222:223], v[254:255]
	v_pk_fma_f32 v[252:253], v[224:225], v[224:225], v[252:253]
	v_pk_fma_f32 v[254:255], v[226:227], v[226:227], v[254:255]
	v_pk_fma_f32 v[252:253], v[228:229], v[228:229], v[252:253]
	v_pk_fma_f32 v[254:255], v[230:231], v[230:231], v[254:255]
	v_pk_add_f32 v[252:253], v[252:253], v[254:255]
	s_nop 0
	v_add_f32_e32 v183, v252, v253
	s_nop 1
	v_add_f32_dpp v183, v183, v183 quad_perm:[1,0,3,2] row_mask:0xf bank_mask:0xf bound_ctrl:1
	s_nop 1
	v_add_f32_dpp v183, v183, v183 quad_perm:[2,3,0,1] row_mask:0xf bank_mask:0xf bound_ctrl:1
	s_nop 1
	v_add_f32_dpp v183, v183, v183 row_half_mirror row_mask:0xf bank_mask:0xf bound_ctrl:1
	s_nop 1
	v_add_f32_dpp v183, v183, v183 row_mirror row_mask:0xf bank_mask:0xf bound_ctrl:1
	s_nop 1
	v_readlane_b32 s98, v183, 0
	v_readlane_b32 s99, v183, 16
	v_readlane_b32 s100, v183, 32
	v_readlane_b32 s101, v183, 48
	s_nop 1
	v_mov_b32_e32 v183, s98
	v_add_f32_e32 v183, s99, v183
	v_add_f32_e32 v183, s100, v183
	v_add_f32_e32 v183, s101, v183
	v_fmamk_f32 v183, v183, 0x3a800000, v182
	v_cmp_gt_f32_e32 vcc, 0x800000, v183
	v_mul_f32_e32 v181, 0x4b800000, v183
	s_nop 1
	v_cndmask_b32_e32 v183, v183, v181, vcc
	v_rsq_f32_e32 v183, v183
	s_nop 0
	v_mul_f32_e32 v181, 0x45800000, v183
	v_cndmask_b32_e32 v184, v183, v181, vcc
	v_mov_b32_e32 v185, v184
	v_pk_mul_f32 v[216:217], v[216:217], v[184:185]
	v_pk_mul_f32 v[218:219], v[218:219], v[184:185]
	v_pk_mul_f32 v[220:221], v[220:221], v[184:185]
	v_pk_mul_f32 v[222:223], v[222:223], v[184:185]
	v_pk_mul_f32 v[224:225], v[224:225], v[184:185]
	v_pk_mul_f32 v[226:227], v[226:227], v[184:185]
	v_pk_mul_f32 v[228:229], v[228:229], v[184:185]
	v_pk_mul_f32 v[230:231], v[230:231], v[184:185]
	v_pk_fma_f32 v[194:195], v[216:217], v[160:161], v[194:195]
	v_pk_fma_f32 v[196:197], v[218:219], v[162:163], v[196:197]
	v_pk_fma_f32 v[198:199], v[220:221], v[164:165], v[198:199]
	v_pk_fma_f32 v[200:201], v[222:223], v[166:167], v[200:201]
	v_pk_fma_f32 v[202:203], v[224:225], v[168:169], v[202:203]
	v_pk_fma_f32 v[204:205], v[226:227], v[170:171], v[204:205]
	v_pk_fma_f32 v[206:207], v[228:229], v[172:173], v[206:207]
	v_pk_fma_f32 v[208:209], v[230:231], v[174:175], v[208:209]
	v_pk_mul_f32 v[252:253], v[194:195], v[194:195]
	v_pk_mul_f32 v[254:255], v[196:197], v[196:197]
	v_pk_fma_f32 v[252:253], v[198:199], v[198:199], v[252:253]
	v_pk_fma_f32 v[254:255], v[200:201], v[200:201], v[254:255]
	v_pk_fma_f32 v[252:253], v[202:203], v[202:203], v[252:253]
	v_pk_fma_f32 v[254:255], v[204:205], v[204:205], v[254:255]
	v_pk_fma_f32 v[252:253], v[206:207], v[206:207], v[252:253]
	v_pk_fma_f32 v[254:255], v[208:209], v[208:209], v[254:255]
	v_pk_add_f32 v[252:253], v[252:253], v[254:255]
	s_nop 0
	v_add_f32_e32 v183, v252, v253
	s_nop 1
	v_add_f32_dpp v183, v183, v183 quad_perm:[1,0,3,2] row_mask:0xf bank_mask:0xf bound_ctrl:1
	s_nop 1
	v_add_f32_dpp v183, v183, v183 quad_perm:[2,3,0,1] row_mask:0xf bank_mask:0xf bound_ctrl:1
	s_nop 1
	v_add_f32_dpp v183, v183, v183 row_half_mirror row_mask:0xf bank_mask:0xf bound_ctrl:1
	s_nop 1
	v_add_f32_dpp v183, v183, v183 row_mirror row_mask:0xf bank_mask:0xf bound_ctrl:1
	s_nop 1
	v_readlane_b32 s98, v183, 0
	v_readlane_b32 s99, v183, 16
	v_readlane_b32 s100, v183, 32
	v_readlane_b32 s101, v183, 48
	s_nop 1
	v_mov_b32_e32 v183, s98
	v_add_f32_e32 v183, s99, v183
	v_add_f32_e32 v183, s100, v183
	v_add_f32_e32 v183, s101, v183
	v_fmamk_f32 v183, v183, 0x3a800000, v182
	v_cmp_gt_f32_e32 vcc, 0x800000, v183
	v_mul_f32_e32 v181, 0x4b800000, v183
	s_nop 1
	v_cndmask_b32_e32 v183, v183, v181, vcc
	v_rsq_f32_e32 v183, v183
	s_nop 0
	v_mul_f32_e32 v181, 0x45800000, v183
	v_cndmask_b32_e32 v184, v183, v181, vcc
	v_mov_b32_e32 v185, v184
	v_cvt_pk_bf16_f32 v64, v194, v195
	v_cvt_pk_bf16_f32 v65, v196, v197
	v_cvt_pk_bf16_f32 v66, v198, v199
	v_cvt_pk_bf16_f32 v67, v200, v201
	v_cvt_pk_bf16_f32 v68, v202, v203
	v_cvt_pk_bf16_f32 v69, v204, v205
	v_cvt_pk_bf16_f32 v70, v206, v207
	v_cvt_pk_bf16_f32 v71, v208, v209
	v_add_u32_e32 v181, 0x2800000, v177
	global_store_dwordx4 v181, v[64:67], s[78:79]
	global_store_dwordx4 v181, v[68:71], s[78:79] offset:1024
	v_add_u32_e32 v236, 0x8000, v237
	s_mov_b64 exec, 1
	global_store_dword v236, v184, s[78:79]
	s_mov_b64 exec, -1
	s_waitcnt vmcnt(16)
	v_lshlrev_b32_e32 v194, 16, v80
	v_and_b32_e32 v195, 0xffff0000, v80
	v_lshlrev_b32_e32 v196, 16, v81
	v_and_b32_e32 v197, 0xffff0000, v81
	v_lshlrev_b32_e32 v198, 16, v82
	v_and_b32_e32 v199, 0xffff0000, v82
	v_lshlrev_b32_e32 v200, 16, v83
	v_and_b32_e32 v201, 0xffff0000, v83
	v_lshlrev_b32_e32 v202, 16, v84
	v_and_b32_e32 v203, 0xffff0000, v84
	v_lshlrev_b32_e32 v204, 16, v85
	v_and_b32_e32 v205, 0xffff0000, v85
	v_lshlrev_b32_e32 v206, 16, v86
	v_and_b32_e32 v207, 0xffff0000, v86
	v_lshlrev_b32_e32 v208, 16, v87
	v_and_b32_e32 v209, 0xffff0000, v87
	v_lshlrev_b32_e32 v216, 16, v88
	v_and_b32_e32 v217, 0xffff0000, v88
	v_lshlrev_b32_e32 v218, 16, v89
	v_and_b32_e32 v219, 0xffff0000, v89
	v_lshlrev_b32_e32 v220, 16, v90
	v_and_b32_e32 v221, 0xffff0000, v90
	v_lshlrev_b32_e32 v222, 16, v91
	v_and_b32_e32 v223, 0xffff0000, v91
	v_lshlrev_b32_e32 v224, 16, v92
	v_and_b32_e32 v225, 0xffff0000, v92
	v_lshlrev_b32_e32 v226, 16, v93
	v_and_b32_e32 v227, 0xffff0000, v93
	v_lshlrev_b32_e32 v228, 16, v94
	v_and_b32_e32 v229, 0xffff0000, v94
	v_lshlrev_b32_e32 v230, 16, v95
	v_and_b32_e32 v231, 0xffff0000, v95
	v_pk_mul_f32 v[252:253], v[216:217], v[216:217]
	v_pk_mul_f32 v[254:255], v[218:219], v[218:219]
	v_pk_fma_f32 v[252:253], v[220:221], v[220:221], v[252:253]
	v_pk_fma_f32 v[254:255], v[222:223], v[222:223], v[254:255]
	v_pk_fma_f32 v[252:253], v[224:225], v[224:225], v[252:253]
	v_pk_fma_f32 v[254:255], v[226:227], v[226:227], v[254:255]
	v_pk_fma_f32 v[252:253], v[228:229], v[228:229], v[252:253]
	v_pk_fma_f32 v[254:255], v[230:231], v[230:231], v[254:255]
	v_pk_add_f32 v[252:253], v[252:253], v[254:255]
	s_nop 0
	v_add_f32_e32 v183, v252, v253
	s_nop 1
	v_add_f32_dpp v183, v183, v183 quad_perm:[1,0,3,2] row_mask:0xf bank_mask:0xf bound_ctrl:1
	s_nop 1
	v_add_f32_dpp v183, v183, v183 quad_perm:[2,3,0,1] row_mask:0xf bank_mask:0xf bound_ctrl:1
	s_nop 1
	v_add_f32_dpp v183, v183, v183 row_half_mirror row_mask:0xf bank_mask:0xf bound_ctrl:1
	s_nop 1
	v_add_f32_dpp v183, v183, v183 row_mirror row_mask:0xf bank_mask:0xf bound_ctrl:1
	s_nop 1
	v_readlane_b32 s98, v183, 0
	v_readlane_b32 s99, v183, 16
	v_readlane_b32 s100, v183, 32
	v_readlane_b32 s101, v183, 48
	s_nop 1
	v_mov_b32_e32 v183, s98
	v_add_f32_e32 v183, s99, v183
	v_add_f32_e32 v183, s100, v183
	v_add_f32_e32 v183, s101, v183
	v_fmamk_f32 v183, v183, 0x3a800000, v182
	v_cmp_gt_f32_e32 vcc, 0x800000, v183
	v_mul_f32_e32 v181, 0x4b800000, v183
	s_nop 1
	v_cndmask_b32_e32 v183, v183, v181, vcc
	v_rsq_f32_e32 v183, v183
	s_nop 0
	v_mul_f32_e32 v181, 0x45800000, v183
	v_cndmask_b32_e32 v184, v183, v181, vcc
	v_mov_b32_e32 v185, v184
	v_pk_mul_f32 v[216:217], v[216:217], v[184:185]
	v_pk_mul_f32 v[218:219], v[218:219], v[184:185]
	v_pk_mul_f32 v[220:221], v[220:221], v[184:185]
	v_pk_mul_f32 v[222:223], v[222:223], v[184:185]
	v_pk_mul_f32 v[224:225], v[224:225], v[184:185]
	v_pk_mul_f32 v[226:227], v[226:227], v[184:185]
	v_pk_mul_f32 v[228:229], v[228:229], v[184:185]
	v_pk_mul_f32 v[230:231], v[230:231], v[184:185]
	v_pk_fma_f32 v[194:195], v[216:217], v[160:161], v[194:195]
	v_pk_fma_f32 v[196:197], v[218:219], v[162:163], v[196:197]
	v_pk_fma_f32 v[198:199], v[220:221], v[164:165], v[198:199]
	v_pk_fma_f32 v[200:201], v[222:223], v[166:167], v[200:201]
	v_pk_fma_f32 v[202:203], v[224:225], v[168:169], v[202:203]
	v_pk_fma_f32 v[204:205], v[226:227], v[170:171], v[204:205]
	v_pk_fma_f32 v[206:207], v[228:229], v[172:173], v[206:207]
	v_pk_fma_f32 v[208:209], v[230:231], v[174:175], v[208:209]
	v_pk_mul_f32 v[252:253], v[194:195], v[194:195]
	v_pk_mul_f32 v[254:255], v[196:197], v[196:197]
	v_pk_fma_f32 v[252:253], v[198:199], v[198:199], v[252:253]
	v_pk_fma_f32 v[254:255], v[200:201], v[200:201], v[254:255]
	v_pk_fma_f32 v[252:253], v[202:203], v[202:203], v[252:253]
	v_pk_fma_f32 v[254:255], v[204:205], v[204:205], v[254:255]
	v_pk_fma_f32 v[252:253], v[206:207], v[206:207], v[252:253]
	v_pk_fma_f32 v[254:255], v[208:209], v[208:209], v[254:255]
	v_pk_add_f32 v[252:253], v[252:253], v[254:255]
	s_nop 0
	v_add_f32_e32 v183, v252, v253
	s_nop 1
	v_add_f32_dpp v183, v183, v183 quad_perm:[1,0,3,2] row_mask:0xf bank_mask:0xf bound_ctrl:1
	s_nop 1
	v_add_f32_dpp v183, v183, v183 quad_perm:[2,3,0,1] row_mask:0xf bank_mask:0xf bound_ctrl:1
	s_nop 1
	v_add_f32_dpp v183, v183, v183 row_half_mirror row_mask:0xf bank_mask:0xf bound_ctrl:1
	s_nop 1
	v_add_f32_dpp v183, v183, v183 row_mirror row_mask:0xf bank_mask:0xf bound_ctrl:1
	s_nop 1
	v_readlane_b32 s98, v183, 0
	v_readlane_b32 s99, v183, 16
	v_readlane_b32 s100, v183, 32
	v_readlane_b32 s101, v183, 48
	s_nop 1
	v_mov_b32_e32 v183, s98
	v_add_f32_e32 v183, s99, v183
	v_add_f32_e32 v183, s100, v183
	v_add_f32_e32 v183, s101, v183
	v_fmamk_f32 v183, v183, 0x3a800000, v182
	v_cmp_gt_f32_e32 vcc, 0x800000, v183
	v_mul_f32_e32 v181, 0x4b800000, v183
	s_nop 1
	v_cndmask_b32_e32 v183, v183, v181, vcc
	v_rsq_f32_e32 v183, v183
	s_nop 0
	v_mul_f32_e32 v181, 0x45800000, v183
	v_cndmask_b32_e32 v184, v183, v181, vcc
	v_mov_b32_e32 v185, v184
	v_cvt_pk_bf16_f32 v80, v194, v195
	v_cvt_pk_bf16_f32 v81, v196, v197
	v_cvt_pk_bf16_f32 v82, v198, v199
	v_cvt_pk_bf16_f32 v83, v200, v201
	v_cvt_pk_bf16_f32 v84, v202, v203
	v_cvt_pk_bf16_f32 v85, v204, v205
	v_cvt_pk_bf16_f32 v86, v206, v207
	v_cvt_pk_bf16_f32 v87, v208, v209
	v_add_u32_e32 v181, 0x2c00000, v177
	global_store_dwordx4 v181, v[80:83], s[78:79]
	global_store_dwordx4 v181, v[84:87], s[78:79] offset:1024
	v_add_u32_e32 v236, 0xa000, v237
	s_mov_b64 exec, 1
	global_store_dword v236, v184, s[78:79]
	s_mov_b64 exec, -1
	s_waitcnt vmcnt(12)
	v_lshlrev_b32_e32 v194, 16, v96
	v_and_b32_e32 v195, 0xffff0000, v96
	v_lshlrev_b32_e32 v196, 16, v97
	v_and_b32_e32 v197, 0xffff0000, v97
	v_lshlrev_b32_e32 v198, 16, v98
	v_and_b32_e32 v199, 0xffff0000, v98
	v_lshlrev_b32_e32 v200, 16, v99
	v_and_b32_e32 v201, 0xffff0000, v99
	v_lshlrev_b32_e32 v202, 16, v100
	v_and_b32_e32 v203, 0xffff0000, v100
	v_lshlrev_b32_e32 v204, 16, v101
	v_and_b32_e32 v205, 0xffff0000, v101
	v_lshlrev_b32_e32 v206, 16, v102
	v_and_b32_e32 v207, 0xffff0000, v102
	v_lshlrev_b32_e32 v208, 16, v103
	v_and_b32_e32 v209, 0xffff0000, v103
	v_lshlrev_b32_e32 v216, 16, v104
	v_and_b32_e32 v217, 0xffff0000, v104
	v_lshlrev_b32_e32 v218, 16, v105
	v_and_b32_e32 v219, 0xffff0000, v105
	v_lshlrev_b32_e32 v220, 16, v106
	v_and_b32_e32 v221, 0xffff0000, v106
	v_lshlrev_b32_e32 v222, 16, v107
	v_and_b32_e32 v223, 0xffff0000, v107
	v_lshlrev_b32_e32 v224, 16, v108
	v_and_b32_e32 v225, 0xffff0000, v108
	v_lshlrev_b32_e32 v226, 16, v109
	v_and_b32_e32 v227, 0xffff0000, v109
	v_lshlrev_b32_e32 v228, 16, v110
	v_and_b32_e32 v229, 0xffff0000, v110
	v_lshlrev_b32_e32 v230, 16, v111
	v_and_b32_e32 v231, 0xffff0000, v111
	v_pk_mul_f32 v[252:253], v[216:217], v[216:217]
	v_pk_mul_f32 v[254:255], v[218:219], v[218:219]
	v_pk_fma_f32 v[252:253], v[220:221], v[220:221], v[252:253]
	v_pk_fma_f32 v[254:255], v[222:223], v[222:223], v[254:255]
	v_pk_fma_f32 v[252:253], v[224:225], v[224:225], v[252:253]
	v_pk_fma_f32 v[254:255], v[226:227], v[226:227], v[254:255]
	v_pk_fma_f32 v[252:253], v[228:229], v[228:229], v[252:253]
	v_pk_fma_f32 v[254:255], v[230:231], v[230:231], v[254:255]
	v_pk_add_f32 v[252:253], v[252:253], v[254:255]
	s_nop 0
	v_add_f32_e32 v183, v252, v253
	s_nop 1
	v_add_f32_dpp v183, v183, v183 quad_perm:[1,0,3,2] row_mask:0xf bank_mask:0xf bound_ctrl:1
	s_nop 1
	v_add_f32_dpp v183, v183, v183 quad_perm:[2,3,0,1] row_mask:0xf bank_mask:0xf bound_ctrl:1
	s_nop 1
	v_add_f32_dpp v183, v183, v183 row_half_mirror row_mask:0xf bank_mask:0xf bound_ctrl:1
	s_nop 1
	v_add_f32_dpp v183, v183, v183 row_mirror row_mask:0xf bank_mask:0xf bound_ctrl:1
	s_nop 1
	v_readlane_b32 s98, v183, 0
	v_readlane_b32 s99, v183, 16
	v_readlane_b32 s100, v183, 32
	v_readlane_b32 s101, v183, 48
	s_nop 1
	v_mov_b32_e32 v183, s98
	v_add_f32_e32 v183, s99, v183
	v_add_f32_e32 v183, s100, v183
	v_add_f32_e32 v183, s101, v183
	v_fmamk_f32 v183, v183, 0x3a800000, v182
	v_cmp_gt_f32_e32 vcc, 0x800000, v183
	v_mul_f32_e32 v181, 0x4b800000, v183
	s_nop 1
	v_cndmask_b32_e32 v183, v183, v181, vcc
	v_rsq_f32_e32 v183, v183
	s_nop 0
	v_mul_f32_e32 v181, 0x45800000, v183
	v_cndmask_b32_e32 v184, v183, v181, vcc
	v_mov_b32_e32 v185, v184
	v_pk_mul_f32 v[216:217], v[216:217], v[184:185]
	v_pk_mul_f32 v[218:219], v[218:219], v[184:185]
	v_pk_mul_f32 v[220:221], v[220:221], v[184:185]
	v_pk_mul_f32 v[222:223], v[222:223], v[184:185]
	v_pk_mul_f32 v[224:225], v[224:225], v[184:185]
	v_pk_mul_f32 v[226:227], v[226:227], v[184:185]
	v_pk_mul_f32 v[228:229], v[228:229], v[184:185]
	v_pk_mul_f32 v[230:231], v[230:231], v[184:185]
	v_pk_fma_f32 v[194:195], v[216:217], v[160:161], v[194:195]
	v_pk_fma_f32 v[196:197], v[218:219], v[162:163], v[196:197]
	v_pk_fma_f32 v[198:199], v[220:221], v[164:165], v[198:199]
	v_pk_fma_f32 v[200:201], v[222:223], v[166:167], v[200:201]
	v_pk_fma_f32 v[202:203], v[224:225], v[168:169], v[202:203]
	v_pk_fma_f32 v[204:205], v[226:227], v[170:171], v[204:205]
	v_pk_fma_f32 v[206:207], v[228:229], v[172:173], v[206:207]
	v_pk_fma_f32 v[208:209], v[230:231], v[174:175], v[208:209]
	v_pk_mul_f32 v[252:253], v[194:195], v[194:195]
	v_pk_mul_f32 v[254:255], v[196:197], v[196:197]
	v_pk_fma_f32 v[252:253], v[198:199], v[198:199], v[252:253]
	v_pk_fma_f32 v[254:255], v[200:201], v[200:201], v[254:255]
	v_pk_fma_f32 v[252:253], v[202:203], v[202:203], v[252:253]
	v_pk_fma_f32 v[254:255], v[204:205], v[204:205], v[254:255]
	v_pk_fma_f32 v[252:253], v[206:207], v[206:207], v[252:253]
	v_pk_fma_f32 v[254:255], v[208:209], v[208:209], v[254:255]
	v_pk_add_f32 v[252:253], v[252:253], v[254:255]
	s_nop 0
	v_add_f32_e32 v183, v252, v253
	s_nop 1
	v_add_f32_dpp v183, v183, v183 quad_perm:[1,0,3,2] row_mask:0xf bank_mask:0xf bound_ctrl:1
	s_nop 1
	v_add_f32_dpp v183, v183, v183 quad_perm:[2,3,0,1] row_mask:0xf bank_mask:0xf bound_ctrl:1
	s_nop 1
	v_add_f32_dpp v183, v183, v183 row_half_mirror row_mask:0xf bank_mask:0xf bound_ctrl:1
	s_nop 1
	v_add_f32_dpp v183, v183, v183 row_mirror row_mask:0xf bank_mask:0xf bound_ctrl:1
	s_nop 1
	v_readlane_b32 s98, v183, 0
	v_readlane_b32 s99, v183, 16
	v_readlane_b32 s100, v183, 32
	v_readlane_b32 s101, v183, 48
	s_nop 1
	v_mov_b32_e32 v183, s98
	v_add_f32_e32 v183, s99, v183
	v_add_f32_e32 v183, s100, v183
	v_add_f32_e32 v183, s101, v183
	v_fmamk_f32 v183, v183, 0x3a800000, v182
	v_cmp_gt_f32_e32 vcc, 0x800000, v183
	v_mul_f32_e32 v181, 0x4b800000, v183
	s_nop 1
	v_cndmask_b32_e32 v183, v183, v181, vcc
	v_rsq_f32_e32 v183, v183
	s_nop 0
	v_mul_f32_e32 v181, 0x45800000, v183
	v_cndmask_b32_e32 v184, v183, v181, vcc
	v_mov_b32_e32 v185, v184
	v_cvt_pk_bf16_f32 v96, v194, v195
	v_cvt_pk_bf16_f32 v97, v196, v197
	v_cvt_pk_bf16_f32 v98, v198, v199
	v_cvt_pk_bf16_f32 v99, v200, v201
	v_cvt_pk_bf16_f32 v100, v202, v203
	v_cvt_pk_bf16_f32 v101, v204, v205
	v_cvt_pk_bf16_f32 v102, v206, v207
	v_cvt_pk_bf16_f32 v103, v208, v209
	v_add_u32_e32 v181, 0x3000000, v177
	global_store_dwordx4 v181, v[96:99], s[78:79]
	global_store_dwordx4 v181, v[100:103], s[78:79] offset:1024
	v_add_u32_e32 v236, 0xc000, v237
	s_mov_b64 exec, 1
	global_store_dword v236, v184, s[78:79]
	s_mov_b64 exec, -1
	s_waitcnt vmcnt(8)
	v_lshlrev_b32_e32 v194, 16, v112
	v_and_b32_e32 v195, 0xffff0000, v112
	v_lshlrev_b32_e32 v196, 16, v113
	v_and_b32_e32 v197, 0xffff0000, v113
	v_lshlrev_b32_e32 v198, 16, v114
	v_and_b32_e32 v199, 0xffff0000, v114
	v_lshlrev_b32_e32 v200, 16, v115
	v_and_b32_e32 v201, 0xffff0000, v115
	v_lshlrev_b32_e32 v202, 16, v116
	v_and_b32_e32 v203, 0xffff0000, v116
	v_lshlrev_b32_e32 v204, 16, v117
	v_and_b32_e32 v205, 0xffff0000, v117
	v_lshlrev_b32_e32 v206, 16, v118
	v_and_b32_e32 v207, 0xffff0000, v118
	v_lshlrev_b32_e32 v208, 16, v119
	v_and_b32_e32 v209, 0xffff0000, v119
	v_lshlrev_b32_e32 v216, 16, v120
	v_and_b32_e32 v217, 0xffff0000, v120
	v_lshlrev_b32_e32 v218, 16, v121
	v_and_b32_e32 v219, 0xffff0000, v121
	v_lshlrev_b32_e32 v220, 16, v122
	v_and_b32_e32 v221, 0xffff0000, v122
	v_lshlrev_b32_e32 v222, 16, v123
	v_and_b32_e32 v223, 0xffff0000, v123
	v_lshlrev_b32_e32 v224, 16, v124
	v_and_b32_e32 v225, 0xffff0000, v124
	v_lshlrev_b32_e32 v226, 16, v125
	v_and_b32_e32 v227, 0xffff0000, v125
	v_lshlrev_b32_e32 v228, 16, v126
	v_and_b32_e32 v229, 0xffff0000, v126
	v_lshlrev_b32_e32 v230, 16, v127
	v_and_b32_e32 v231, 0xffff0000, v127
	v_pk_mul_f32 v[252:253], v[216:217], v[216:217]
	v_pk_mul_f32 v[254:255], v[218:219], v[218:219]
	v_pk_fma_f32 v[252:253], v[220:221], v[220:221], v[252:253]
	v_pk_fma_f32 v[254:255], v[222:223], v[222:223], v[254:255]
	v_pk_fma_f32 v[252:253], v[224:225], v[224:225], v[252:253]
	v_pk_fma_f32 v[254:255], v[226:227], v[226:227], v[254:255]
	v_pk_fma_f32 v[252:253], v[228:229], v[228:229], v[252:253]
	v_pk_fma_f32 v[254:255], v[230:231], v[230:231], v[254:255]
	v_pk_add_f32 v[252:253], v[252:253], v[254:255]
	s_nop 0
	v_add_f32_e32 v183, v252, v253
	s_nop 1
	v_add_f32_dpp v183, v183, v183 quad_perm:[1,0,3,2] row_mask:0xf bank_mask:0xf bound_ctrl:1
	s_nop 1
	v_add_f32_dpp v183, v183, v183 quad_perm:[2,3,0,1] row_mask:0xf bank_mask:0xf bound_ctrl:1
	s_nop 1
	v_add_f32_dpp v183, v183, v183 row_half_mirror row_mask:0xf bank_mask:0xf bound_ctrl:1
	s_nop 1
	v_add_f32_dpp v183, v183, v183 row_mirror row_mask:0xf bank_mask:0xf bound_ctrl:1
	s_nop 1
	v_readlane_b32 s98, v183, 0
	v_readlane_b32 s99, v183, 16
	v_readlane_b32 s100, v183, 32
	v_readlane_b32 s101, v183, 48
	s_nop 1
	v_mov_b32_e32 v183, s98
	v_add_f32_e32 v183, s99, v183
	v_add_f32_e32 v183, s100, v183
	v_add_f32_e32 v183, s101, v183
	v_fmamk_f32 v183, v183, 0x3a800000, v182
	v_cmp_gt_f32_e32 vcc, 0x800000, v183
	v_mul_f32_e32 v181, 0x4b800000, v183
	s_nop 1
	v_cndmask_b32_e32 v183, v183, v181, vcc
	v_rsq_f32_e32 v183, v183
	s_nop 0
	v_mul_f32_e32 v181, 0x45800000, v183
	v_cndmask_b32_e32 v184, v183, v181, vcc
	v_mov_b32_e32 v185, v184
	v_pk_mul_f32 v[216:217], v[216:217], v[184:185]
	v_pk_mul_f32 v[218:219], v[218:219], v[184:185]
	v_pk_mul_f32 v[220:221], v[220:221], v[184:185]
	v_pk_mul_f32 v[222:223], v[222:223], v[184:185]
	v_pk_mul_f32 v[224:225], v[224:225], v[184:185]
	v_pk_mul_f32 v[226:227], v[226:227], v[184:185]
	v_pk_mul_f32 v[228:229], v[228:229], v[184:185]
	v_pk_mul_f32 v[230:231], v[230:231], v[184:185]
	v_pk_fma_f32 v[194:195], v[216:217], v[160:161], v[194:195]
	v_pk_fma_f32 v[196:197], v[218:219], v[162:163], v[196:197]
	v_pk_fma_f32 v[198:199], v[220:221], v[164:165], v[198:199]
	v_pk_fma_f32 v[200:201], v[222:223], v[166:167], v[200:201]
	v_pk_fma_f32 v[202:203], v[224:225], v[168:169], v[202:203]
	v_pk_fma_f32 v[204:205], v[226:227], v[170:171], v[204:205]
	v_pk_fma_f32 v[206:207], v[228:229], v[172:173], v[206:207]
	v_pk_fma_f32 v[208:209], v[230:231], v[174:175], v[208:209]
	v_pk_mul_f32 v[252:253], v[194:195], v[194:195]
	v_pk_mul_f32 v[254:255], v[196:197], v[196:197]
	v_pk_fma_f32 v[252:253], v[198:199], v[198:199], v[252:253]
	v_pk_fma_f32 v[254:255], v[200:201], v[200:201], v[254:255]
	v_pk_fma_f32 v[252:253], v[202:203], v[202:203], v[252:253]
	v_pk_fma_f32 v[254:255], v[204:205], v[204:205], v[254:255]
	v_pk_fma_f32 v[252:253], v[206:207], v[206:207], v[252:253]
	v_pk_fma_f32 v[254:255], v[208:209], v[208:209], v[254:255]
	v_pk_add_f32 v[252:253], v[252:253], v[254:255]
	s_nop 0
	v_add_f32_e32 v183, v252, v253
	s_nop 1
	v_add_f32_dpp v183, v183, v183 quad_perm:[1,0,3,2] row_mask:0xf bank_mask:0xf bound_ctrl:1
	s_nop 1
	v_add_f32_dpp v183, v183, v183 quad_perm:[2,3,0,1] row_mask:0xf bank_mask:0xf bound_ctrl:1
	s_nop 1
	v_add_f32_dpp v183, v183, v183 row_half_mirror row_mask:0xf bank_mask:0xf bound_ctrl:1
	s_nop 1
	v_add_f32_dpp v183, v183, v183 row_mirror row_mask:0xf bank_mask:0xf bound_ctrl:1
	s_nop 1
	v_readlane_b32 s98, v183, 0
	v_readlane_b32 s99, v183, 16
	v_readlane_b32 s100, v183, 32
	v_readlane_b32 s101, v183, 48
	s_nop 1
	v_mov_b32_e32 v183, s98
	v_add_f32_e32 v183, s99, v183
	v_add_f32_e32 v183, s100, v183
	v_add_f32_e32 v183, s101, v183
	v_fmamk_f32 v183, v183, 0x3a800000, v182
	v_cmp_gt_f32_e32 vcc, 0x800000, v183
	v_mul_f32_e32 v181, 0x4b800000, v183
	s_nop 1
	v_cndmask_b32_e32 v183, v183, v181, vcc
	v_rsq_f32_e32 v183, v183
	s_nop 0
	v_mul_f32_e32 v181, 0x45800000, v183
	v_cndmask_b32_e32 v184, v183, v181, vcc
	v_mov_b32_e32 v185, v184
	v_cvt_pk_bf16_f32 v112, v194, v195
	v_cvt_pk_bf16_f32 v113, v196, v197
	v_cvt_pk_bf16_f32 v114, v198, v199
	v_cvt_pk_bf16_f32 v115, v200, v201
	v_cvt_pk_bf16_f32 v116, v202, v203
	v_cvt_pk_bf16_f32 v117, v204, v205
	v_cvt_pk_bf16_f32 v118, v206, v207
	v_cvt_pk_bf16_f32 v119, v208, v209
	v_add_u32_e32 v181, 0x3400000, v177
	global_store_dwordx4 v181, v[112:115], s[78:79]
	global_store_dwordx4 v181, v[116:119], s[78:79] offset:1024
	v_add_u32_e32 v236, 0xe000, v237
	s_mov_b64 exec, 1
	global_store_dword v236, v184, s[78:79]
	s_mov_b64 exec, -1
	s_waitcnt vmcnt(4)
	v_lshlrev_b32_e32 v194, 16, v128
	v_and_b32_e32 v195, 0xffff0000, v128
	v_lshlrev_b32_e32 v196, 16, v129
	v_and_b32_e32 v197, 0xffff0000, v129
	v_lshlrev_b32_e32 v198, 16, v130
	v_and_b32_e32 v199, 0xffff0000, v130
	v_lshlrev_b32_e32 v200, 16, v131
	v_and_b32_e32 v201, 0xffff0000, v131
	v_lshlrev_b32_e32 v202, 16, v132
	v_and_b32_e32 v203, 0xffff0000, v132
	v_lshlrev_b32_e32 v204, 16, v133
	v_and_b32_e32 v205, 0xffff0000, v133
	v_lshlrev_b32_e32 v206, 16, v134
	v_and_b32_e32 v207, 0xffff0000, v134
	v_lshlrev_b32_e32 v208, 16, v135
	v_and_b32_e32 v209, 0xffff0000, v135
	v_lshlrev_b32_e32 v216, 16, v136
	v_and_b32_e32 v217, 0xffff0000, v136
	v_lshlrev_b32_e32 v218, 16, v137
	v_and_b32_e32 v219, 0xffff0000, v137
	v_lshlrev_b32_e32 v220, 16, v138
	v_and_b32_e32 v221, 0xffff0000, v138
	v_lshlrev_b32_e32 v222, 16, v139
	v_and_b32_e32 v223, 0xffff0000, v139
	v_lshlrev_b32_e32 v224, 16, v140
	v_and_b32_e32 v225, 0xffff0000, v140
	v_lshlrev_b32_e32 v226, 16, v141
	v_and_b32_e32 v227, 0xffff0000, v141
	v_lshlrev_b32_e32 v228, 16, v142
	v_and_b32_e32 v229, 0xffff0000, v142
	v_lshlrev_b32_e32 v230, 16, v143
	v_and_b32_e32 v231, 0xffff0000, v143
	v_pk_mul_f32 v[252:253], v[216:217], v[216:217]
	v_pk_mul_f32 v[254:255], v[218:219], v[218:219]
	v_pk_fma_f32 v[252:253], v[220:221], v[220:221], v[252:253]
	v_pk_fma_f32 v[254:255], v[222:223], v[222:223], v[254:255]
	v_pk_fma_f32 v[252:253], v[224:225], v[224:225], v[252:253]
	v_pk_fma_f32 v[254:255], v[226:227], v[226:227], v[254:255]
	v_pk_fma_f32 v[252:253], v[228:229], v[228:229], v[252:253]
	v_pk_fma_f32 v[254:255], v[230:231], v[230:231], v[254:255]
	v_pk_add_f32 v[252:253], v[252:253], v[254:255]
	s_nop 0
	v_add_f32_e32 v183, v252, v253
	s_nop 1
	v_add_f32_dpp v183, v183, v183 quad_perm:[1,0,3,2] row_mask:0xf bank_mask:0xf bound_ctrl:1
	s_nop 1
	v_add_f32_dpp v183, v183, v183 quad_perm:[2,3,0,1] row_mask:0xf bank_mask:0xf bound_ctrl:1
	s_nop 1
	v_add_f32_dpp v183, v183, v183 row_half_mirror row_mask:0xf bank_mask:0xf bound_ctrl:1
	s_nop 1
	v_add_f32_dpp v183, v183, v183 row_mirror row_mask:0xf bank_mask:0xf bound_ctrl:1
	s_nop 1
	v_readlane_b32 s98, v183, 0
	v_readlane_b32 s99, v183, 16
	v_readlane_b32 s100, v183, 32
	v_readlane_b32 s101, v183, 48
	s_nop 1
	v_mov_b32_e32 v183, s98
	v_add_f32_e32 v183, s99, v183
	v_add_f32_e32 v183, s100, v183
	v_add_f32_e32 v183, s101, v183
	v_fmamk_f32 v183, v183, 0x3a800000, v182
	v_cmp_gt_f32_e32 vcc, 0x800000, v183
	v_mul_f32_e32 v181, 0x4b800000, v183
	s_nop 1
	v_cndmask_b32_e32 v183, v183, v181, vcc
	v_rsq_f32_e32 v183, v183
	s_nop 0
	v_mul_f32_e32 v181, 0x45800000, v183
	v_cndmask_b32_e32 v184, v183, v181, vcc
	v_mov_b32_e32 v185, v184
	v_pk_mul_f32 v[216:217], v[216:217], v[184:185]
	v_pk_mul_f32 v[218:219], v[218:219], v[184:185]
	v_pk_mul_f32 v[220:221], v[220:221], v[184:185]
	v_pk_mul_f32 v[222:223], v[222:223], v[184:185]
	v_pk_mul_f32 v[224:225], v[224:225], v[184:185]
	v_pk_mul_f32 v[226:227], v[226:227], v[184:185]
	v_pk_mul_f32 v[228:229], v[228:229], v[184:185]
	v_pk_mul_f32 v[230:231], v[230:231], v[184:185]
	v_pk_fma_f32 v[194:195], v[216:217], v[160:161], v[194:195]
	v_pk_fma_f32 v[196:197], v[218:219], v[162:163], v[196:197]
	v_pk_fma_f32 v[198:199], v[220:221], v[164:165], v[198:199]
	v_pk_fma_f32 v[200:201], v[222:223], v[166:167], v[200:201]
	v_pk_fma_f32 v[202:203], v[224:225], v[168:169], v[202:203]
	v_pk_fma_f32 v[204:205], v[226:227], v[170:171], v[204:205]
	v_pk_fma_f32 v[206:207], v[228:229], v[172:173], v[206:207]
	v_pk_fma_f32 v[208:209], v[230:231], v[174:175], v[208:209]
	v_pk_mul_f32 v[252:253], v[194:195], v[194:195]
	v_pk_mul_f32 v[254:255], v[196:197], v[196:197]
	v_pk_fma_f32 v[252:253], v[198:199], v[198:199], v[252:253]
	v_pk_fma_f32 v[254:255], v[200:201], v[200:201], v[254:255]
	v_pk_fma_f32 v[252:253], v[202:203], v[202:203], v[252:253]
	v_pk_fma_f32 v[254:255], v[204:205], v[204:205], v[254:255]
	v_pk_fma_f32 v[252:253], v[206:207], v[206:207], v[252:253]
	v_pk_fma_f32 v[254:255], v[208:209], v[208:209], v[254:255]
	v_pk_add_f32 v[252:253], v[252:253], v[254:255]
	s_nop 0
	v_add_f32_e32 v183, v252, v253
	s_nop 1
	v_add_f32_dpp v183, v183, v183 quad_perm:[1,0,3,2] row_mask:0xf bank_mask:0xf bound_ctrl:1
	s_nop 1
	v_add_f32_dpp v183, v183, v183 quad_perm:[2,3,0,1] row_mask:0xf bank_mask:0xf bound_ctrl:1
	s_nop 1
	v_add_f32_dpp v183, v183, v183 row_half_mirror row_mask:0xf bank_mask:0xf bound_ctrl:1
	s_nop 1
	v_add_f32_dpp v183, v183, v183 row_mirror row_mask:0xf bank_mask:0xf bound_ctrl:1
	s_nop 1
	v_readlane_b32 s98, v183, 0
	v_readlane_b32 s99, v183, 16
	v_readlane_b32 s100, v183, 32
	v_readlane_b32 s101, v183, 48
	s_nop 1
	v_mov_b32_e32 v183, s98
	v_add_f32_e32 v183, s99, v183
	v_add_f32_e32 v183, s100, v183
	v_add_f32_e32 v183, s101, v183
	v_fmamk_f32 v183, v183, 0x3a800000, v182
	v_cmp_gt_f32_e32 vcc, 0x800000, v183
	v_mul_f32_e32 v181, 0x4b800000, v183
	s_nop 1
	v_cndmask_b32_e32 v183, v183, v181, vcc
	v_rsq_f32_e32 v183, v183
	s_nop 0
	v_mul_f32_e32 v181, 0x45800000, v183
	v_cndmask_b32_e32 v184, v183, v181, vcc
	v_mov_b32_e32 v185, v184
	v_cvt_pk_bf16_f32 v128, v194, v195
	v_cvt_pk_bf16_f32 v129, v196, v197
	v_cvt_pk_bf16_f32 v130, v198, v199
	v_cvt_pk_bf16_f32 v131, v200, v201
	v_cvt_pk_bf16_f32 v132, v202, v203
	v_cvt_pk_bf16_f32 v133, v204, v205
	v_cvt_pk_bf16_f32 v134, v206, v207
	v_cvt_pk_bf16_f32 v135, v208, v209
	v_add_u32_e32 v181, 0x1800000, v210
	global_store_dwordx4 v181, v[128:131], s[78:79]
	global_store_dwordx4 v181, v[132:135], s[78:79] offset:1024
	v_add_u32_e32 v236, 0x0, v211
	s_mov_b64 exec, 1
	global_store_dword v236, v184, s[78:79]
	s_mov_b64 exec, -1
	s_waitcnt vmcnt(0)
	v_lshlrev_b32_e32 v194, 16, v144
	v_and_b32_e32 v195, 0xffff0000, v144
	v_lshlrev_b32_e32 v196, 16, v145
	v_and_b32_e32 v197, 0xffff0000, v145
	v_lshlrev_b32_e32 v198, 16, v146
	v_and_b32_e32 v199, 0xffff0000, v146
	v_lshlrev_b32_e32 v200, 16, v147
	v_and_b32_e32 v201, 0xffff0000, v147
	v_lshlrev_b32_e32 v202, 16, v148
	v_and_b32_e32 v203, 0xffff0000, v148
	v_lshlrev_b32_e32 v204, 16, v149
	v_and_b32_e32 v205, 0xffff0000, v149
	v_lshlrev_b32_e32 v206, 16, v150
	v_and_b32_e32 v207, 0xffff0000, v150
	v_lshlrev_b32_e32 v208, 16, v151
	v_and_b32_e32 v209, 0xffff0000, v151
	v_lshlrev_b32_e32 v216, 16, v152
	v_and_b32_e32 v217, 0xffff0000, v152
	v_lshlrev_b32_e32 v218, 16, v153
	v_and_b32_e32 v219, 0xffff0000, v153
	v_lshlrev_b32_e32 v220, 16, v154
	v_and_b32_e32 v221, 0xffff0000, v154
	v_lshlrev_b32_e32 v222, 16, v155
	v_and_b32_e32 v223, 0xffff0000, v155
	v_lshlrev_b32_e32 v224, 16, v156
	v_and_b32_e32 v225, 0xffff0000, v156
	v_lshlrev_b32_e32 v226, 16, v157
	v_and_b32_e32 v227, 0xffff0000, v157
	v_lshlrev_b32_e32 v228, 16, v158
	v_and_b32_e32 v229, 0xffff0000, v158
	v_lshlrev_b32_e32 v230, 16, v159
	v_and_b32_e32 v231, 0xffff0000, v159
	v_pk_mul_f32 v[252:253], v[216:217], v[216:217]
	v_pk_mul_f32 v[254:255], v[218:219], v[218:219]
	v_pk_fma_f32 v[252:253], v[220:221], v[220:221], v[252:253]
	v_pk_fma_f32 v[254:255], v[222:223], v[222:223], v[254:255]
	v_pk_fma_f32 v[252:253], v[224:225], v[224:225], v[252:253]
	v_pk_fma_f32 v[254:255], v[226:227], v[226:227], v[254:255]
	v_pk_fma_f32 v[252:253], v[228:229], v[228:229], v[252:253]
	v_pk_fma_f32 v[254:255], v[230:231], v[230:231], v[254:255]
	v_pk_add_f32 v[252:253], v[252:253], v[254:255]
	s_nop 0
	v_add_f32_e32 v183, v252, v253
	s_nop 1
	v_add_f32_dpp v183, v183, v183 quad_perm:[1,0,3,2] row_mask:0xf bank_mask:0xf bound_ctrl:1
	s_nop 1
	v_add_f32_dpp v183, v183, v183 quad_perm:[2,3,0,1] row_mask:0xf bank_mask:0xf bound_ctrl:1
	s_nop 1
	v_add_f32_dpp v183, v183, v183 row_half_mirror row_mask:0xf bank_mask:0xf bound_ctrl:1
	s_nop 1
	v_add_f32_dpp v183, v183, v183 row_mirror row_mask:0xf bank_mask:0xf bound_ctrl:1
	s_nop 1
	v_readlane_b32 s98, v183, 0
	v_readlane_b32 s99, v183, 16
	v_readlane_b32 s100, v183, 32
	v_readlane_b32 s101, v183, 48
	s_nop 1
	v_mov_b32_e32 v183, s98
	v_add_f32_e32 v183, s99, v183
	v_add_f32_e32 v183, s100, v183
	v_add_f32_e32 v183, s101, v183
	v_fmamk_f32 v183, v183, 0x3a800000, v182
	v_cmp_gt_f32_e32 vcc, 0x800000, v183
	v_mul_f32_e32 v181, 0x4b800000, v183
	s_nop 1
	v_cndmask_b32_e32 v183, v183, v181, vcc
	v_rsq_f32_e32 v183, v183
	s_nop 0
	v_mul_f32_e32 v181, 0x45800000, v183
	v_cndmask_b32_e32 v184, v183, v181, vcc
	v_mov_b32_e32 v185, v184
	v_pk_mul_f32 v[216:217], v[216:217], v[184:185]
	v_pk_mul_f32 v[218:219], v[218:219], v[184:185]
	v_pk_mul_f32 v[220:221], v[220:221], v[184:185]
	v_pk_mul_f32 v[222:223], v[222:223], v[184:185]
	v_pk_mul_f32 v[224:225], v[224:225], v[184:185]
	v_pk_mul_f32 v[226:227], v[226:227], v[184:185]
	v_pk_mul_f32 v[228:229], v[228:229], v[184:185]
	v_pk_mul_f32 v[230:231], v[230:231], v[184:185]
	v_pk_fma_f32 v[194:195], v[216:217], v[160:161], v[194:195]
	v_pk_fma_f32 v[196:197], v[218:219], v[162:163], v[196:197]
	v_pk_fma_f32 v[198:199], v[220:221], v[164:165], v[198:199]
	v_pk_fma_f32 v[200:201], v[222:223], v[166:167], v[200:201]
	v_pk_fma_f32 v[202:203], v[224:225], v[168:169], v[202:203]
	v_pk_fma_f32 v[204:205], v[226:227], v[170:171], v[204:205]
	v_pk_fma_f32 v[206:207], v[228:229], v[172:173], v[206:207]
	v_pk_fma_f32 v[208:209], v[230:231], v[174:175], v[208:209]
	v_pk_mul_f32 v[252:253], v[194:195], v[194:195]
	v_pk_mul_f32 v[254:255], v[196:197], v[196:197]
	v_pk_fma_f32 v[252:253], v[198:199], v[198:199], v[252:253]
	v_pk_fma_f32 v[254:255], v[200:201], v[200:201], v[254:255]
	v_pk_fma_f32 v[252:253], v[202:203], v[202:203], v[252:253]
	v_pk_fma_f32 v[254:255], v[204:205], v[204:205], v[254:255]
	v_pk_fma_f32 v[252:253], v[206:207], v[206:207], v[252:253]
	v_pk_fma_f32 v[254:255], v[208:209], v[208:209], v[254:255]
	v_pk_add_f32 v[252:253], v[252:253], v[254:255]
	s_nop 0
	v_add_f32_e32 v183, v252, v253
	s_nop 1
	v_add_f32_dpp v183, v183, v183 quad_perm:[1,0,3,2] row_mask:0xf bank_mask:0xf bound_ctrl:1
	s_nop 1
	v_add_f32_dpp v183, v183, v183 quad_perm:[2,3,0,1] row_mask:0xf bank_mask:0xf bound_ctrl:1
	s_nop 1
	v_add_f32_dpp v183, v183, v183 row_half_mirror row_mask:0xf bank_mask:0xf bound_ctrl:1
	s_nop 1
	v_add_f32_dpp v183, v183, v183 row_mirror row_mask:0xf bank_mask:0xf bound_ctrl:1
	s_nop 1
	v_readlane_b32 s98, v183, 0
	v_readlane_b32 s99, v183, 16
	v_readlane_b32 s100, v183, 32
	v_readlane_b32 s101, v183, 48
	s_nop 1
	v_mov_b32_e32 v183, s98
	v_add_f32_e32 v183, s99, v183
	v_add_f32_e32 v183, s100, v183
	v_add_f32_e32 v183, s101, v183
	v_fmamk_f32 v183, v183, 0x3a800000, v182
	v_cmp_gt_f32_e32 vcc, 0x800000, v183
	v_mul_f32_e32 v181, 0x4b800000, v183
	s_nop 1
	v_cndmask_b32_e32 v183, v183, v181, vcc
	v_rsq_f32_e32 v183, v183
	s_nop 0
	v_mul_f32_e32 v181, 0x45800000, v183
	v_cndmask_b32_e32 v184, v183, v181, vcc
	v_mov_b32_e32 v185, v184
	v_cvt_pk_bf16_f32 v144, v194, v195
	v_cvt_pk_bf16_f32 v145, v196, v197
	v_cvt_pk_bf16_f32 v146, v198, v199
	v_cvt_pk_bf16_f32 v147, v200, v201
	v_cvt_pk_bf16_f32 v148, v202, v203
	v_cvt_pk_bf16_f32 v149, v204, v205
	v_cvt_pk_bf16_f32 v150, v206, v207
	v_cvt_pk_bf16_f32 v151, v208, v209
	v_add_u32_e32 v181, 0x1c00000, v210
	global_store_dwordx4 v181, v[144:147], s[78:79]
	global_store_dwordx4 v181, v[148:151], s[78:79] offset:1024
	v_add_u32_e32 v236, 0x2000, v211
	s_mov_b64 exec, 1
	global_store_dword v236, v184, s[78:79]
	s_mov_b64 exec, -1
	s_branch .Lmyxupd_done_5

.LBB0_2573:
	v_readlane_b32 s0, v235, 52
	v_readlane_b32 s1, v235, 53
	s_and_b64 vcc, exec, s[0:1]
	s_waitcnt lgkmcnt(0)
	s_barrier
	v_mbcnt_lo_u32_b32 v0, -1, 0
	v_mbcnt_hi_u32_b32 v0, -1, v0
	s_cbranch_vccnz .LBB0_2593
	v_lshlrev_b32_e32 v2, 3, v0
	v_ashrrev_i32_e32 v3, 31, v2
	v_readlane_b32 s4, v235, 4
	v_lshlrev_b64 v[4:5], 1, v[2:3]
	v_lshlrev_b64 v[2:3], 2, v[2:3]
	v_readlane_b32 s14, v235, 14
	v_readlane_b32 s15, v235, 15
	v_lshl_add_u64 v[62:63], s[90:91], 0, v[2:3]
	v_readlane_b32 s5, v235, 5
	v_readlane_b32 s6, v235, 6
	v_readlane_b32 s7, v235, 7
	v_readlane_b32 s8, v235, 8
	v_readlane_b32 s9, v235, 9
	v_readlane_b32 s10, v235, 10
	v_readlane_b32 s11, v235, 11
	v_readlane_b32 s12, v235, 12
	v_readlane_b32 s13, v235, 13
	v_readlane_b32 s16, v235, 16
	v_readlane_b32 s17, v235, 17
	v_readlane_b32 s18, v235, 18
	v_readlane_b32 s19, v235, 19
	v_lshl_add_u64 v[2:3], s[14:15], 0, v[2:3]
	s_mov_b64 s[0:1], 0x3000
	v_lshl_add_u64 v[60:61], s[86:87], 0, v[4:5]
	v_lshl_add_u64 v[64:65], s[54:55], 0, v[4:5]
	v_lshl_add_u64 v[66:67], v[2:3], 0, s[0:1]
	s_mov_b32 s1, 0
	v_cmp_eq_u32_e64 s[4:5], 0, v0
	s_mov_b64 s[6:7], 0x200000
	s_mov_b64 s[8:9], 0x200800
	s_mov_b64 s[10:11], 0x400000
	s_mov_b64 s[12:13], 0x400800
	s_mov_b64 s[14:15], 0x600000
	s_mov_b64 s[16:17], 0x600800
	s_mov_b64 s[18:19], 0x800000
	s_mov_b32 s48, 0x800000
	s_mov_b64 s[20:21], 0x800800
	s_mov_b64 s[22:23], 0xa00000
	s_mov_b64 s[24:25], 0xa00800
	s_mov_b64 s[26:27], 0xc00000
	s_mov_b64 s[28:29], 0xc00800
	s_mov_b64 s[30:31], 0xe00000
	s_mov_b64 s[36:37], 0xe00800
	v_mov_b32_e32 v104, 0
	v_mov_b32_e32 v105, 0x358637bd
	v_readlane_b32 s38, v235, 61
	v_readlane_b32 s39, v235, 62
	v_mbcnt_lo_u32_b32 v176, -1, 0
	v_mbcnt_hi_u32_b32 v176, -1, v176
	v_readlane_b32 s98, v235, 49
	v_readlane_b32 s99, v235, 20
	v_readlane_b32 s100, v235, 14
	v_readlane_b32 s101, v235, 15
	s_nop 3
	s_lshr_b32 vcc_lo, s98, 3
	s_and_b32 vcc_hi, vcc_lo, 7
	s_lshr_b32 vcc_lo, vcc_lo, 3
	s_lshl_b32 vcc_lo, vcc_lo, 3
	s_add_i32 vcc_lo, vcc_lo, s99
	s_lshl_b32 s98, vcc_hi, 8
	s_add_i32 s98, s98, vcc_lo
	v_mov_b32_e32 v179, s98
	v_lshlrev_b32_e32 v177, 4, v176
	s_lshl_b32 s99, s98, 11
	v_add_u32_e32 v177, s99, v177
	v_lshlrev_b32_e32 v180, 5, v176
	v_add_u32_e32 v181, 0x3000, v180
	global_load_dwordx4 v[160:163], v181, s[100:101]
	global_load_dwordx4 v[164:167], v181, s[100:101] offset:16
	global_load_dwordx4 v[168:171], v181, s[100:101] offset:2048
	global_load_dwordx4 v[172:175], v181, s[100:101] offset:2064
	v_mov_b32_e32 v182, 0x358637bd
	v_lshlrev_b32_e32 v237, 2, v179
	v_add_u32_e32 v237, 0x10000, v237
	s_and_b32 s99, s98, 3
	s_cmp_eq_u32 s99, 0
	s_cbranch_scc1 .Lmyxupd_s_6
	s_mul_i32 s100, s99, 0x7ff800
	v_add_u32_e32 v210, s100, v177
	s_mul_i32 s100, s99, 16380
	v_add_u32_e32 v211, s100, v237
	v_add_u32_e32 v178, 0x1800000, v177
	v_add_u32_e32 v181, 0x9e00000, v177
	global_load_dwordx4 v[0:3], v178, s[78:79]
	global_load_dwordx4 v[4:7], v178, s[78:79] offset:1024
	global_load_dwordx4 v[8:11], v181, s[78:79]
	global_load_dwordx4 v[12:15], v181, s[78:79] offset:1024
	v_add_u32_e32 v178, 0x1c00000, v177
	v_add_u32_e32 v181, 0xa200000, v177
	global_load_dwordx4 v[16:19], v178, s[78:79]
	global_load_dwordx4 v[20:23], v178, s[78:79] offset:1024
	global_load_dwordx4 v[24:27], v181, s[78:79]
	global_load_dwordx4 v[28:31], v181, s[78:79] offset:1024
	v_add_u32_e32 v178, 0x2000000, v177
	v_add_u32_e32 v181, 0xa600000, v177
	global_load_dwordx4 v[32:35], v178, s[78:79]
	global_load_dwordx4 v[36:39], v178, s[78:79] offset:1024
	global_load_dwordx4 v[40:43], v181, s[78:79]
	global_load_dwordx4 v[44:47], v181, s[78:79] offset:1024
	v_add_u32_e32 v178, 0x2400000, v177
	v_add_u32_e32 v181, 0xaa00000, v177
	global_load_dwordx4 v[48:51], v178, s[78:79]
	global_load_dwordx4 v[52:55], v178, s[78:79] offset:1024
	global_load_dwordx4 v[56:59], v181, s[78:79]
	global_load_dwordx4 v[60:63], v181, s[78:79] offset:1024
	v_add_u32_e32 v178, 0x2800000, v177
	v_add_u32_e32 v181, 0xae00000, v177
	global_load_dwordx4 v[64:67], v178, s[78:79]
	global_load_dwordx4 v[68:71], v178, s[78:79] offset:1024
	global_load_dwordx4 v[72:75], v181, s[78:79]
	global_load_dwordx4 v[76:79], v181, s[78:79] offset:1024
	v_add_u32_e32 v178, 0x2c00000, v177
	v_add_u32_e32 v181, 0xb200000, v177
	global_load_dwordx4 v[80:83], v178, s[78:79]
	global_load_dwordx4 v[84:87], v178, s[78:79] offset:1024
	global_load_dwordx4 v[88:91], v181, s[78:79]
	global_load_dwordx4 v[92:95], v181, s[78:79] offset:1024
	v_add_u32_e32 v178, 0x3000000, v177
	v_add_u32_e32 v181, 0xb600000, v177
	global_load_dwordx4 v[96:99], v178, s[78:79]
	global_load_dwordx4 v[100:103], v178, s[78:79] offset:1024
	global_load_dwordx4 v[104:107], v181, s[78:79]
	global_load_dwordx4 v[108:111], v181, s[78:79] offset:1024
	v_add_u32_e32 v178, 0x3400000, v177
	v_add_u32_e32 v181, 0xba00000, v177
	global_load_dwordx4 v[112:115], v178, s[78:79]
	global_load_dwordx4 v[116:119], v178, s[78:79] offset:1024
	global_load_dwordx4 v[120:123], v181, s[78:79]
	global_load_dwordx4 v[124:127], v181, s[78:79] offset:1024
	v_add_u32_e32 v178, 0x1800000, v210
	v_add_u32_e32 v181, 0x9e00000, v210
	global_load_dwordx4 v[128:131], v178, s[78:79]
	global_load_dwordx4 v[132:135], v178, s[78:79] offset:1024
	global_load_dwordx4 v[136:139], v181, s[78:79]
	global_load_dwordx4 v[140:143], v181, s[78:79] offset:1024
	v_add_u32_e32 v178, 0x1c00000, v210
	v_add_u32_e32 v181, 0xa200000, v210
	global_load_dwordx4 v[144:147], v178, s[78:79]
	global_load_dwordx4 v[148:151], v178, s[78:79] offset:1024
	global_load_dwordx4 v[152:155], v181, s[78:79]
	global_load_dwordx4 v[156:159], v181, s[78:79] offset:1024
	s_waitcnt vmcnt(36)
	v_lshlrev_b32_e32 v194, 16, v0
	v_and_b32_e32 v195, 0xffff0000, v0
	v_lshlrev_b32_e32 v196, 16, v1
	v_and_b32_e32 v197, 0xffff0000, v1
	v_lshlrev_b32_e32 v198, 16, v2
	v_and_b32_e32 v199, 0xffff0000, v2
	v_lshlrev_b32_e32 v200, 16, v3
	v_and_b32_e32 v201, 0xffff0000, v3
	v_lshlrev_b32_e32 v202, 16, v4
	v_and_b32_e32 v203, 0xffff0000, v4
	v_lshlrev_b32_e32 v204, 16, v5
	v_and_b32_e32 v205, 0xffff0000, v5
	v_lshlrev_b32_e32 v206, 16, v6
	v_and_b32_e32 v207, 0xffff0000, v6
	v_lshlrev_b32_e32 v208, 16, v7
	v_and_b32_e32 v209, 0xffff0000, v7
	v_lshlrev_b32_e32 v216, 16, v8
	v_and_b32_e32 v217, 0xffff0000, v8
	v_lshlrev_b32_e32 v218, 16, v9
	v_and_b32_e32 v219, 0xffff0000, v9
	v_lshlrev_b32_e32 v220, 16, v10
	v_and_b32_e32 v221, 0xffff0000, v10
	v_lshlrev_b32_e32 v222, 16, v11
	v_and_b32_e32 v223, 0xffff0000, v11
	v_lshlrev_b32_e32 v224, 16, v12
	v_and_b32_e32 v225, 0xffff0000, v12
	v_lshlrev_b32_e32 v226, 16, v13
	v_and_b32_e32 v227, 0xffff0000, v13
	v_lshlrev_b32_e32 v228, 16, v14
	v_and_b32_e32 v229, 0xffff0000, v14
	v_lshlrev_b32_e32 v230, 16, v15
	v_and_b32_e32 v231, 0xffff0000, v15
	v_pk_mul_f32 v[252:253], v[216:217], v[216:217]
	v_pk_mul_f32 v[254:255], v[218:219], v[218:219]
	v_pk_fma_f32 v[252:253], v[220:221], v[220:221], v[252:253]
	v_pk_fma_f32 v[254:255], v[222:223], v[222:223], v[254:255]
	v_pk_fma_f32 v[252:253], v[224:225], v[224:225], v[252:253]
	v_pk_fma_f32 v[254:255], v[226:227], v[226:227], v[254:255]
	v_pk_fma_f32 v[252:253], v[228:229], v[228:229], v[252:253]
	v_pk_fma_f32 v[254:255], v[230:231], v[230:231], v[254:255]
	v_pk_add_f32 v[252:253], v[252:253], v[254:255]
	s_nop 0
	v_add_f32_e32 v183, v252, v253
	s_nop 1
	v_add_f32_dpp v183, v183, v183 quad_perm:[1,0,3,2] row_mask:0xf bank_mask:0xf bound_ctrl:1
	s_nop 1
	v_add_f32_dpp v183, v183, v183 quad_perm:[2,3,0,1] row_mask:0xf bank_mask:0xf bound_ctrl:1
	s_nop 1
	v_add_f32_dpp v183, v183, v183 row_half_mirror row_mask:0xf bank_mask:0xf bound_ctrl:1
	s_nop 1
	v_add_f32_dpp v183, v183, v183 row_mirror row_mask:0xf bank_mask:0xf bound_ctrl:1
	s_nop 1
	v_readlane_b32 s98, v183, 0
	v_readlane_b32 s99, v183, 16
	v_readlane_b32 s100, v183, 32
	v_readlane_b32 s101, v183, 48
	s_nop 1
	v_mov_b32_e32 v183, s98
	v_add_f32_e32 v183, s99, v183
	v_add_f32_e32 v183, s100, v183
	v_add_f32_e32 v183, s101, v183
	v_fmamk_f32 v183, v183, 0x3a800000, v182
	v_cmp_gt_f32_e32 vcc, 0x800000, v183
	v_mul_f32_e32 v181, 0x4b800000, v183
	s_nop 1
	v_cndmask_b32_e32 v183, v183, v181, vcc
	v_rsq_f32_e32 v183, v183
	s_nop 0
	v_mul_f32_e32 v181, 0x45800000, v183
	v_cndmask_b32_e32 v184, v183, v181, vcc
	v_mov_b32_e32 v185, v184
	v_pk_mul_f32 v[216:217], v[216:217], v[184:185]
	v_pk_mul_f32 v[218:219], v[218:219], v[184:185]
	v_pk_mul_f32 v[220:221], v[220:221], v[184:185]
	v_pk_mul_f32 v[222:223], v[222:223], v[184:185]
	v_pk_mul_f32 v[224:225], v[224:225], v[184:185]
	v_pk_mul_f32 v[226:227], v[226:227], v[184:185]
	v_pk_mul_f32 v[228:229], v[228:229], v[184:185]
	v_pk_mul_f32 v[230:231], v[230:231], v[184:185]
	v_pk_fma_f32 v[194:195], v[216:217], v[160:161], v[194:195]
	v_pk_fma_f32 v[196:197], v[218:219], v[162:163], v[196:197]
	v_pk_fma_f32 v[198:199], v[220:221], v[164:165], v[198:199]
	v_pk_fma_f32 v[200:201], v[222:223], v[166:167], v[200:201]
	v_pk_fma_f32 v[202:203], v[224:225], v[168:169], v[202:203]
	v_pk_fma_f32 v[204:205], v[226:227], v[170:171], v[204:205]
	v_pk_fma_f32 v[206:207], v[228:229], v[172:173], v[206:207]
	v_pk_fma_f32 v[208:209], v[230:231], v[174:175], v[208:209]
	v_pk_mul_f32 v[252:253], v[194:195], v[194:195]
	v_pk_mul_f32 v[254:255], v[196:197], v[196:197]
	v_pk_fma_f32 v[252:253], v[198:199], v[198:199], v[252:253]
	v_pk_fma_f32 v[254:255], v[200:201], v[200:201], v[254:255]
	v_pk_fma_f32 v[252:253], v[202:203], v[202:203], v[252:253]
	v_pk_fma_f32 v[254:255], v[204:205], v[204:205], v[254:255]
	v_pk_fma_f32 v[252:253], v[206:207], v[206:207], v[252:253]
	v_pk_fma_f32 v[254:255], v[208:209], v[208:209], v[254:255]
	v_pk_add_f32 v[252:253], v[252:253], v[254:255]
	s_nop 0
	v_add_f32_e32 v183, v252, v253
	s_nop 1
	v_add_f32_dpp v183, v183, v183 quad_perm:[1,0,3,2] row_mask:0xf bank_mask:0xf bound_ctrl:1
	s_nop 1
	v_add_f32_dpp v183, v183, v183 quad_perm:[2,3,0,1] row_mask:0xf bank_mask:0xf bound_ctrl:1
	s_nop 1
	v_add_f32_dpp v183, v183, v183 row_half_mirror row_mask:0xf bank_mask:0xf bound_ctrl:1
	s_nop 1
	v_add_f32_dpp v183, v183, v183 row_mirror row_mask:0xf bank_mask:0xf bound_ctrl:1
	s_nop 1
	v_readlane_b32 s98, v183, 0
	v_readlane_b32 s99, v183, 16
	v_readlane_b32 s100, v183, 32
	v_readlane_b32 s101, v183, 48
	s_nop 1
	v_mov_b32_e32 v183, s98
	v_add_f32_e32 v183, s99, v183
	v_add_f32_e32 v183, s100, v183
	v_add_f32_e32 v183, s101, v183
	v_fmamk_f32 v183, v183, 0x3a800000, v182
	v_cmp_gt_f32_e32 vcc, 0x800000, v183
	v_mul_f32_e32 v181, 0x4b800000, v183
	s_nop 1
	v_cndmask_b32_e32 v183, v183, v181, vcc
	v_rsq_f32_e32 v183, v183
	s_nop 0
	v_mul_f32_e32 v181, 0x45800000, v183
	v_cndmask_b32_e32 v184, v183, v181, vcc
	v_mov_b32_e32 v185, v184
	v_cvt_pk_bf16_f32 v0, v194, v195
	v_cvt_pk_bf16_f32 v1, v196, v197
	v_cvt_pk_bf16_f32 v2, v198, v199
	v_cvt_pk_bf16_f32 v3, v200, v201
	v_cvt_pk_bf16_f32 v4, v202, v203
	v_cvt_pk_bf16_f32 v5, v204, v205
	v_cvt_pk_bf16_f32 v6, v206, v207
	v_cvt_pk_bf16_f32 v7, v208, v209
	v_add_u32_e32 v181, 0x1800000, v177
	global_store_dwordx4 v181, v[0:3], s[78:79]
	global_store_dwordx4 v181, v[4:7], s[78:79] offset:1024
	v_add_u32_e32 v236, 0x0, v237
	s_mov_b64 exec, 1
	global_store_dword v236, v184, s[78:79]
	s_mov_b64 exec, -1
	s_waitcnt vmcnt(32)
	v_lshlrev_b32_e32 v194, 16, v16
	v_and_b32_e32 v195, 0xffff0000, v16
	v_lshlrev_b32_e32 v196, 16, v17
	v_and_b32_e32 v197, 0xffff0000, v17
	v_lshlrev_b32_e32 v198, 16, v18
	v_and_b32_e32 v199, 0xffff0000, v18
	v_lshlrev_b32_e32 v200, 16, v19
	v_and_b32_e32 v201, 0xffff0000, v19
	v_lshlrev_b32_e32 v202, 16, v20
	v_and_b32_e32 v203, 0xffff0000, v20
	v_lshlrev_b32_e32 v204, 16, v21
	v_and_b32_e32 v205, 0xffff0000, v21
	v_lshlrev_b32_e32 v206, 16, v22
	v_and_b32_e32 v207, 0xffff0000, v22
	v_lshlrev_b32_e32 v208, 16, v23
	v_and_b32_e32 v209, 0xffff0000, v23
	v_lshlrev_b32_e32 v216, 16, v24
	v_and_b32_e32 v217, 0xffff0000, v24
	v_lshlrev_b32_e32 v218, 16, v25
	v_and_b32_e32 v219, 0xffff0000, v25
	v_lshlrev_b32_e32 v220, 16, v26
	v_and_b32_e32 v221, 0xffff0000, v26
	v_lshlrev_b32_e32 v222, 16, v27
	v_and_b32_e32 v223, 0xffff0000, v27
	v_lshlrev_b32_e32 v224, 16, v28
	v_and_b32_e32 v225, 0xffff0000, v28
	v_lshlrev_b32_e32 v226, 16, v29
	v_and_b32_e32 v227, 0xffff0000, v29
	v_lshlrev_b32_e32 v228, 16, v30
	v_and_b32_e32 v229, 0xffff0000, v30
	v_lshlrev_b32_e32 v230, 16, v31
	v_and_b32_e32 v231, 0xffff0000, v31
	v_pk_mul_f32 v[252:253], v[216:217], v[216:217]
	v_pk_mul_f32 v[254:255], v[218:219], v[218:219]
	v_pk_fma_f32 v[252:253], v[220:221], v[220:221], v[252:253]
	v_pk_fma_f32 v[254:255], v[222:223], v[222:223], v[254:255]
	v_pk_fma_f32 v[252:253], v[224:225], v[224:225], v[252:253]
	v_pk_fma_f32 v[254:255], v[226:227], v[226:227], v[254:255]
	v_pk_fma_f32 v[252:253], v[228:229], v[228:229], v[252:253]
	v_pk_fma_f32 v[254:255], v[230:231], v[230:231], v[254:255]
	v_pk_add_f32 v[252:253], v[252:253], v[254:255]
	s_nop 0
	v_add_f32_e32 v183, v252, v253
	s_nop 1
	v_add_f32_dpp v183, v183, v183 quad_perm:[1,0,3,2] row_mask:0xf bank_mask:0xf bound_ctrl:1
	s_nop 1
	v_add_f32_dpp v183, v183, v183 quad_perm:[2,3,0,1] row_mask:0xf bank_mask:0xf bound_ctrl:1
	s_nop 1
	v_add_f32_dpp v183, v183, v183 row_half_mirror row_mask:0xf bank_mask:0xf bound_ctrl:1
	s_nop 1
	v_add_f32_dpp v183, v183, v183 row_mirror row_mask:0xf bank_mask:0xf bound_ctrl:1
	s_nop 1
	v_readlane_b32 s98, v183, 0
	v_readlane_b32 s99, v183, 16
	v_readlane_b32 s100, v183, 32
	v_readlane_b32 s101, v183, 48
	s_nop 1
	v_mov_b32_e32 v183, s98
	v_add_f32_e32 v183, s99, v183
	v_add_f32_e32 v183, s100, v183
	v_add_f32_e32 v183, s101, v183
	v_fmamk_f32 v183, v183, 0x3a800000, v182
	v_cmp_gt_f32_e32 vcc, 0x800000, v183
	v_mul_f32_e32 v181, 0x4b800000, v183
	s_nop 1
	v_cndmask_b32_e32 v183, v183, v181, vcc
	v_rsq_f32_e32 v183, v183
	s_nop 0
	v_mul_f32_e32 v181, 0x45800000, v183
	v_cndmask_b32_e32 v184, v183, v181, vcc
	v_mov_b32_e32 v185, v184
	v_pk_mul_f32 v[216:217], v[216:217], v[184:185]
	v_pk_mul_f32 v[218:219], v[218:219], v[184:185]
	v_pk_mul_f32 v[220:221], v[220:221], v[184:185]
	v_pk_mul_f32 v[222:223], v[222:223], v[184:185]
	v_pk_mul_f32 v[224:225], v[224:225], v[184:185]
	v_pk_mul_f32 v[226:227], v[226:227], v[184:185]
	v_pk_mul_f32 v[228:229], v[228:229], v[184:185]
	v_pk_mul_f32 v[230:231], v[230:231], v[184:185]
	v_pk_fma_f32 v[194:195], v[216:217], v[160:161], v[194:195]
	v_pk_fma_f32 v[196:197], v[218:219], v[162:163], v[196:197]
	v_pk_fma_f32 v[198:199], v[220:221], v[164:165], v[198:199]
	v_pk_fma_f32 v[200:201], v[222:223], v[166:167], v[200:201]
	v_pk_fma_f32 v[202:203], v[224:225], v[168:169], v[202:203]
	v_pk_fma_f32 v[204:205], v[226:227], v[170:171], v[204:205]
	v_pk_fma_f32 v[206:207], v[228:229], v[172:173], v[206:207]
	v_pk_fma_f32 v[208:209], v[230:231], v[174:175], v[208:209]
	v_pk_mul_f32 v[252:253], v[194:195], v[194:195]
	v_pk_mul_f32 v[254:255], v[196:197], v[196:197]
	v_pk_fma_f32 v[252:253], v[198:199], v[198:199], v[252:253]
	v_pk_fma_f32 v[254:255], v[200:201], v[200:201], v[254:255]
	v_pk_fma_f32 v[252:253], v[202:203], v[202:203], v[252:253]
	v_pk_fma_f32 v[254:255], v[204:205], v[204:205], v[254:255]
	v_pk_fma_f32 v[252:253], v[206:207], v[206:207], v[252:253]
	v_pk_fma_f32 v[254:255], v[208:209], v[208:209], v[254:255]
	v_pk_add_f32 v[252:253], v[252:253], v[254:255]
	s_nop 0
	v_add_f32_e32 v183, v252, v253
	s_nop 1
	v_add_f32_dpp v183, v183, v183 quad_perm:[1,0,3,2] row_mask:0xf bank_mask:0xf bound_ctrl:1
	s_nop 1
	v_add_f32_dpp v183, v183, v183 quad_perm:[2,3,0,1] row_mask:0xf bank_mask:0xf bound_ctrl:1
	s_nop 1
	v_add_f32_dpp v183, v183, v183 row_half_mirror row_mask:0xf bank_mask:0xf bound_ctrl:1
	s_nop 1
	v_add_f32_dpp v183, v183, v183 row_mirror row_mask:0xf bank_mask:0xf bound_ctrl:1
	s_nop 1
	v_readlane_b32 s98, v183, 0
	v_readlane_b32 s99, v183, 16
	v_readlane_b32 s100, v183, 32
	v_readlane_b32 s101, v183, 48
	s_nop 1
	v_mov_b32_e32 v183, s98
	v_add_f32_e32 v183, s99, v183
	v_add_f32_e32 v183, s100, v183
	v_add_f32_e32 v183, s101, v183
	v_fmamk_f32 v183, v183, 0x3a800000, v182
	v_cmp_gt_f32_e32 vcc, 0x800000, v183
	v_mul_f32_e32 v181, 0x4b800000, v183
	s_nop 1
	v_cndmask_b32_e32 v183, v183, v181, vcc
	v_rsq_f32_e32 v183, v183
	s_nop 0
	v_mul_f32_e32 v181, 0x45800000, v183
	v_cndmask_b32_e32 v184, v183, v181, vcc
	v_mov_b32_e32 v185, v184
	v_cvt_pk_bf16_f32 v16, v194, v195
	v_cvt_pk_bf16_f32 v17, v196, v197
	v_cvt_pk_bf16_f32 v18, v198, v199
	v_cvt_pk_bf16_f32 v19, v200, v201
	v_cvt_pk_bf16_f32 v20, v202, v203
	v_cvt_pk_bf16_f32 v21, v204, v205
	v_cvt_pk_bf16_f32 v22, v206, v207
	v_cvt_pk_bf16_f32 v23, v208, v209
	v_add_u32_e32 v181, 0x1c00000, v177
	global_store_dwordx4 v181, v[16:19], s[78:79]
	global_store_dwordx4 v181, v[20:23], s[78:79] offset:1024
	v_add_u32_e32 v236, 0x2000, v237
	s_mov_b64 exec, 1
	global_store_dword v236, v184, s[78:79]
	s_mov_b64 exec, -1
	s_waitcnt vmcnt(28)
	v_lshlrev_b32_e32 v194, 16, v32
	v_and_b32_e32 v195, 0xffff0000, v32
	v_lshlrev_b32_e32 v196, 16, v33
	v_and_b32_e32 v197, 0xffff0000, v33
	v_lshlrev_b32_e32 v198, 16, v34
	v_and_b32_e32 v199, 0xffff0000, v34
	v_lshlrev_b32_e32 v200, 16, v35
	v_and_b32_e32 v201, 0xffff0000, v35
	v_lshlrev_b32_e32 v202, 16, v36
	v_and_b32_e32 v203, 0xffff0000, v36
	v_lshlrev_b32_e32 v204, 16, v37
	v_and_b32_e32 v205, 0xffff0000, v37
	v_lshlrev_b32_e32 v206, 16, v38
	v_and_b32_e32 v207, 0xffff0000, v38
	v_lshlrev_b32_e32 v208, 16, v39
	v_and_b32_e32 v209, 0xffff0000, v39
	v_lshlrev_b32_e32 v216, 16, v40
	v_and_b32_e32 v217, 0xffff0000, v40
	v_lshlrev_b32_e32 v218, 16, v41
	v_and_b32_e32 v219, 0xffff0000, v41
	v_lshlrev_b32_e32 v220, 16, v42
	v_and_b32_e32 v221, 0xffff0000, v42
	v_lshlrev_b32_e32 v222, 16, v43
	v_and_b32_e32 v223, 0xffff0000, v43
	v_lshlrev_b32_e32 v224, 16, v44
	v_and_b32_e32 v225, 0xffff0000, v44
	v_lshlrev_b32_e32 v226, 16, v45
	v_and_b32_e32 v227, 0xffff0000, v45
	v_lshlrev_b32_e32 v228, 16, v46
	v_and_b32_e32 v229, 0xffff0000, v46
	v_lshlrev_b32_e32 v230, 16, v47
	v_and_b32_e32 v231, 0xffff0000, v47
	v_pk_mul_f32 v[252:253], v[216:217], v[216:217]
	v_pk_mul_f32 v[254:255], v[218:219], v[218:219]
	v_pk_fma_f32 v[252:253], v[220:221], v[220:221], v[252:253]
	v_pk_fma_f32 v[254:255], v[222:223], v[222:223], v[254:255]
	v_pk_fma_f32 v[252:253], v[224:225], v[224:225], v[252:253]
	v_pk_fma_f32 v[254:255], v[226:227], v[226:227], v[254:255]
	v_pk_fma_f32 v[252:253], v[228:229], v[228:229], v[252:253]
	v_pk_fma_f32 v[254:255], v[230:231], v[230:231], v[254:255]
	v_pk_add_f32 v[252:253], v[252:253], v[254:255]
	s_nop 0
	v_add_f32_e32 v183, v252, v253
	s_nop 1
	v_add_f32_dpp v183, v183, v183 quad_perm:[1,0,3,2] row_mask:0xf bank_mask:0xf bound_ctrl:1
	s_nop 1
	v_add_f32_dpp v183, v183, v183 quad_perm:[2,3,0,1] row_mask:0xf bank_mask:0xf bound_ctrl:1
	s_nop 1
	v_add_f32_dpp v183, v183, v183 row_half_mirror row_mask:0xf bank_mask:0xf bound_ctrl:1
	s_nop 1
	v_add_f32_dpp v183, v183, v183 row_mirror row_mask:0xf bank_mask:0xf bound_ctrl:1
	s_nop 1
	v_readlane_b32 s98, v183, 0
	v_readlane_b32 s99, v183, 16
	v_readlane_b32 s100, v183, 32
	v_readlane_b32 s101, v183, 48
	s_nop 1
	v_mov_b32_e32 v183, s98
	v_add_f32_e32 v183, s99, v183
	v_add_f32_e32 v183, s100, v183
	v_add_f32_e32 v183, s101, v183
	v_fmamk_f32 v183, v183, 0x3a800000, v182
	v_cmp_gt_f32_e32 vcc, 0x800000, v183
	v_mul_f32_e32 v181, 0x4b800000, v183
	s_nop 1
	v_cndmask_b32_e32 v183, v183, v181, vcc
	v_rsq_f32_e32 v183, v183
	s_nop 0
	v_mul_f32_e32 v181, 0x45800000, v183
	v_cndmask_b32_e32 v184, v183, v181, vcc
	v_mov_b32_e32 v185, v184
	v_pk_mul_f32 v[216:217], v[216:217], v[184:185]
	v_pk_mul_f32 v[218:219], v[218:219], v[184:185]
	v_pk_mul_f32 v[220:221], v[220:221], v[184:185]
	v_pk_mul_f32 v[222:223], v[222:223], v[184:185]
	v_pk_mul_f32 v[224:225], v[224:225], v[184:185]
	v_pk_mul_f32 v[226:227], v[226:227], v[184:185]
	v_pk_mul_f32 v[228:229], v[228:229], v[184:185]
	v_pk_mul_f32 v[230:231], v[230:231], v[184:185]
	v_pk_fma_f32 v[194:195], v[216:217], v[160:161], v[194:195]
	v_pk_fma_f32 v[196:197], v[218:219], v[162:163], v[196:197]
	v_pk_fma_f32 v[198:199], v[220:221], v[164:165], v[198:199]
	v_pk_fma_f32 v[200:201], v[222:223], v[166:167], v[200:201]
	v_pk_fma_f32 v[202:203], v[224:225], v[168:169], v[202:203]
	v_pk_fma_f32 v[204:205], v[226:227], v[170:171], v[204:205]
	v_pk_fma_f32 v[206:207], v[228:229], v[172:173], v[206:207]
	v_pk_fma_f32 v[208:209], v[230:231], v[174:175], v[208:209]
	v_pk_mul_f32 v[252:253], v[194:195], v[194:195]
	v_pk_mul_f32 v[254:255], v[196:197], v[196:197]
	v_pk_fma_f32 v[252:253], v[198:199], v[198:199], v[252:253]
	v_pk_fma_f32 v[254:255], v[200:201], v[200:201], v[254:255]
	v_pk_fma_f32 v[252:253], v[202:203], v[202:203], v[252:253]
	v_pk_fma_f32 v[254:255], v[204:205], v[204:205], v[254:255]
	v_pk_fma_f32 v[252:253], v[206:207], v[206:207], v[252:253]
	v_pk_fma_f32 v[254:255], v[208:209], v[208:209], v[254:255]
	v_pk_add_f32 v[252:253], v[252:253], v[254:255]
	s_nop 0
	v_add_f32_e32 v183, v252, v253
	s_nop 1
	v_add_f32_dpp v183, v183, v183 quad_perm:[1,0,3,2] row_mask:0xf bank_mask:0xf bound_ctrl:1
	s_nop 1
	v_add_f32_dpp v183, v183, v183 quad_perm:[2,3,0,1] row_mask:0xf bank_mask:0xf bound_ctrl:1
	s_nop 1
	v_add_f32_dpp v183, v183, v183 row_half_mirror row_mask:0xf bank_mask:0xf bound_ctrl:1
	s_nop 1
	v_add_f32_dpp v183, v183, v183 row_mirror row_mask:0xf bank_mask:0xf bound_ctrl:1
	s_nop 1
	v_readlane_b32 s98, v183, 0
	v_readlane_b32 s99, v183, 16
	v_readlane_b32 s100, v183, 32
	v_readlane_b32 s101, v183, 48
	s_nop 1
	v_mov_b32_e32 v183, s98
	v_add_f32_e32 v183, s99, v183
	v_add_f32_e32 v183, s100, v183
	v_add_f32_e32 v183, s101, v183
	v_fmamk_f32 v183, v183, 0x3a800000, v182
	v_cmp_gt_f32_e32 vcc, 0x800000, v183
	v_mul_f32_e32 v181, 0x4b800000, v183
	s_nop 1
	v_cndmask_b32_e32 v183, v183, v181, vcc
	v_rsq_f32_e32 v183, v183
	s_nop 0
	v_mul_f32_e32 v181, 0x45800000, v183
	v_cndmask_b32_e32 v184, v183, v181, vcc
	v_mov_b32_e32 v185, v184
	v_cvt_pk_bf16_f32 v32, v194, v195
	v_cvt_pk_bf16_f32 v33, v196, v197
	v_cvt_pk_bf16_f32 v34, v198, v199
	v_cvt_pk_bf16_f32 v35, v200, v201
	v_cvt_pk_bf16_f32 v36, v202, v203
	v_cvt_pk_bf16_f32 v37, v204, v205
	v_cvt_pk_bf16_f32 v38, v206, v207
	v_cvt_pk_bf16_f32 v39, v208, v209
	v_add_u32_e32 v181, 0x2000000, v177
	global_store_dwordx4 v181, v[32:35], s[78:79]
	global_store_dwordx4 v181, v[36:39], s[78:79] offset:1024
	v_add_u32_e32 v236, 0x4000, v237
	s_mov_b64 exec, 1
	global_store_dword v236, v184, s[78:79]
	s_mov_b64 exec, -1
	s_waitcnt vmcnt(24)
	v_lshlrev_b32_e32 v194, 16, v48
	v_and_b32_e32 v195, 0xffff0000, v48
	v_lshlrev_b32_e32 v196, 16, v49
	v_and_b32_e32 v197, 0xffff0000, v49
	v_lshlrev_b32_e32 v198, 16, v50
	v_and_b32_e32 v199, 0xffff0000, v50
	v_lshlrev_b32_e32 v200, 16, v51
	v_and_b32_e32 v201, 0xffff0000, v51
	v_lshlrev_b32_e32 v202, 16, v52
	v_and_b32_e32 v203, 0xffff0000, v52
	v_lshlrev_b32_e32 v204, 16, v53
	v_and_b32_e32 v205, 0xffff0000, v53
	v_lshlrev_b32_e32 v206, 16, v54
	v_and_b32_e32 v207, 0xffff0000, v54
	v_lshlrev_b32_e32 v208, 16, v55
	v_and_b32_e32 v209, 0xffff0000, v55
	v_lshlrev_b32_e32 v216, 16, v56
	v_and_b32_e32 v217, 0xffff0000, v56
	v_lshlrev_b32_e32 v218, 16, v57
	v_and_b32_e32 v219, 0xffff0000, v57
	v_lshlrev_b32_e32 v220, 16, v58
	v_and_b32_e32 v221, 0xffff0000, v58
	v_lshlrev_b32_e32 v222, 16, v59
	v_and_b32_e32 v223, 0xffff0000, v59
	v_lshlrev_b32_e32 v224, 16, v60
	v_and_b32_e32 v225, 0xffff0000, v60
	v_lshlrev_b32_e32 v226, 16, v61
	v_and_b32_e32 v227, 0xffff0000, v61
	v_lshlrev_b32_e32 v228, 16, v62
	v_and_b32_e32 v229, 0xffff0000, v62
	v_lshlrev_b32_e32 v230, 16, v63
	v_and_b32_e32 v231, 0xffff0000, v63
	v_pk_mul_f32 v[252:253], v[216:217], v[216:217]
	v_pk_mul_f32 v[254:255], v[218:219], v[218:219]
	v_pk_fma_f32 v[252:253], v[220:221], v[220:221], v[252:253]
	v_pk_fma_f32 v[254:255], v[222:223], v[222:223], v[254:255]
	v_pk_fma_f32 v[252:253], v[224:225], v[224:225], v[252:253]
	v_pk_fma_f32 v[254:255], v[226:227], v[226:227], v[254:255]
	v_pk_fma_f32 v[252:253], v[228:229], v[228:229], v[252:253]
	v_pk_fma_f32 v[254:255], v[230:231], v[230:231], v[254:255]
	v_pk_add_f32 v[252:253], v[252:253], v[254:255]
	s_nop 0
	v_add_f32_e32 v183, v252, v253
	s_nop 1
	v_add_f32_dpp v183, v183, v183 quad_perm:[1,0,3,2] row_mask:0xf bank_mask:0xf bound_ctrl:1
	s_nop 1
	v_add_f32_dpp v183, v183, v183 quad_perm:[2,3,0,1] row_mask:0xf bank_mask:0xf bound_ctrl:1
	s_nop 1
	v_add_f32_dpp v183, v183, v183 row_half_mirror row_mask:0xf bank_mask:0xf bound_ctrl:1
	s_nop 1
	v_add_f32_dpp v183, v183, v183 row_mirror row_mask:0xf bank_mask:0xf bound_ctrl:1
	s_nop 1
	v_readlane_b32 s98, v183, 0
	v_readlane_b32 s99, v183, 16
	v_readlane_b32 s100, v183, 32
	v_readlane_b32 s101, v183, 48
	s_nop 1
	v_mov_b32_e32 v183, s98
	v_add_f32_e32 v183, s99, v183
	v_add_f32_e32 v183, s100, v183
	v_add_f32_e32 v183, s101, v183
	v_fmamk_f32 v183, v183, 0x3a800000, v182
	v_cmp_gt_f32_e32 vcc, 0x800000, v183
	v_mul_f32_e32 v181, 0x4b800000, v183
	s_nop 1
	v_cndmask_b32_e32 v183, v183, v181, vcc
	v_rsq_f32_e32 v183, v183
	s_nop 0
	v_mul_f32_e32 v181, 0x45800000, v183
	v_cndmask_b32_e32 v184, v183, v181, vcc
	v_mov_b32_e32 v185, v184
	v_pk_mul_f32 v[216:217], v[216:217], v[184:185]
	v_pk_mul_f32 v[218:219], v[218:219], v[184:185]
	v_pk_mul_f32 v[220:221], v[220:221], v[184:185]
	v_pk_mul_f32 v[222:223], v[222:223], v[184:185]
	v_pk_mul_f32 v[224:225], v[224:225], v[184:185]
	v_pk_mul_f32 v[226:227], v[226:227], v[184:185]
	v_pk_mul_f32 v[228:229], v[228:229], v[184:185]
	v_pk_mul_f32 v[230:231], v[230:231], v[184:185]
	v_pk_fma_f32 v[194:195], v[216:217], v[160:161], v[194:195]
	v_pk_fma_f32 v[196:197], v[218:219], v[162:163], v[196:197]
	v_pk_fma_f32 v[198:199], v[220:221], v[164:165], v[198:199]
	v_pk_fma_f32 v[200:201], v[222:223], v[166:167], v[200:201]
	v_pk_fma_f32 v[202:203], v[224:225], v[168:169], v[202:203]
	v_pk_fma_f32 v[204:205], v[226:227], v[170:171], v[204:205]
	v_pk_fma_f32 v[206:207], v[228:229], v[172:173], v[206:207]
	v_pk_fma_f32 v[208:209], v[230:231], v[174:175], v[208:209]
	v_pk_mul_f32 v[252:253], v[194:195], v[194:195]
	v_pk_mul_f32 v[254:255], v[196:197], v[196:197]
	v_pk_fma_f32 v[252:253], v[198:199], v[198:199], v[252:253]
	v_pk_fma_f32 v[254:255], v[200:201], v[200:201], v[254:255]
	v_pk_fma_f32 v[252:253], v[202:203], v[202:203], v[252:253]
	v_pk_fma_f32 v[254:255], v[204:205], v[204:205], v[254:255]
	v_pk_fma_f32 v[252:253], v[206:207], v[206:207], v[252:253]
	v_pk_fma_f32 v[254:255], v[208:209], v[208:209], v[254:255]
	v_pk_add_f32 v[252:253], v[252:253], v[254:255]
	s_nop 0
	v_add_f32_e32 v183, v252, v253
	s_nop 1
	v_add_f32_dpp v183, v183, v183 quad_perm:[1,0,3,2] row_mask:0xf bank_mask:0xf bound_ctrl:1
	s_nop 1
	v_add_f32_dpp v183, v183, v183 quad_perm:[2,3,0,1] row_mask:0xf bank_mask:0xf bound_ctrl:1
	s_nop 1
	v_add_f32_dpp v183, v183, v183 row_half_mirror row_mask:0xf bank_mask:0xf bound_ctrl:1
	s_nop 1
	v_add_f32_dpp v183, v183, v183 row_mirror row_mask:0xf bank_mask:0xf bound_ctrl:1
	s_nop 1
	v_readlane_b32 s98, v183, 0
	v_readlane_b32 s99, v183, 16
	v_readlane_b32 s100, v183, 32
	v_readlane_b32 s101, v183, 48
	s_nop 1
	v_mov_b32_e32 v183, s98
	v_add_f32_e32 v183, s99, v183
	v_add_f32_e32 v183, s100, v183
	v_add_f32_e32 v183, s101, v183
	v_fmamk_f32 v183, v183, 0x3a800000, v182
	v_cmp_gt_f32_e32 vcc, 0x800000, v183
	v_mul_f32_e32 v181, 0x4b800000, v183
	s_nop 1
	v_cndmask_b32_e32 v183, v183, v181, vcc
	v_rsq_f32_e32 v183, v183
	s_nop 0
	v_mul_f32_e32 v181, 0x45800000, v183
	v_cndmask_b32_e32 v184, v183, v181, vcc
	v_mov_b32_e32 v185, v184
	v_cvt_pk_bf16_f32 v48, v194, v195
	v_cvt_pk_bf16_f32 v49, v196, v197
	v_cvt_pk_bf16_f32 v50, v198, v199
	v_cvt_pk_bf16_f32 v51, v200, v201
	v_cvt_pk_bf16_f32 v52, v202, v203
	v_cvt_pk_bf16_f32 v53, v204, v205
	v_cvt_pk_bf16_f32 v54, v206, v207
	v_cvt_pk_bf16_f32 v55, v208, v209
	v_add_u32_e32 v181, 0x2400000, v177
	global_store_dwordx4 v181, v[48:51], s[78:79]
	global_store_dwordx4 v181, v[52:55], s[78:79] offset:1024
	v_add_u32_e32 v236, 0x6000, v237
	s_mov_b64 exec, 1
	global_store_dword v236, v184, s[78:79]
	s_mov_b64 exec, -1
	s_waitcnt vmcnt(20)
	v_lshlrev_b32_e32 v194, 16, v64
	v_and_b32_e32 v195, 0xffff0000, v64
	v_lshlrev_b32_e32 v196, 16, v65
	v_and_b32_e32 v197, 0xffff0000, v65
	v_lshlrev_b32_e32 v198, 16, v66
	v_and_b32_e32 v199, 0xffff0000, v66
	v_lshlrev_b32_e32 v200, 16, v67
	v_and_b32_e32 v201, 0xffff0000, v67
	v_lshlrev_b32_e32 v202, 16, v68
	v_and_b32_e32 v203, 0xffff0000, v68
	v_lshlrev_b32_e32 v204, 16, v69
	v_and_b32_e32 v205, 0xffff0000, v69
	v_lshlrev_b32_e32 v206, 16, v70
	v_and_b32_e32 v207, 0xffff0000, v70
	v_lshlrev_b32_e32 v208, 16, v71
	v_and_b32_e32 v209, 0xffff0000, v71
	v_lshlrev_b32_e32 v216, 16, v72
	v_and_b32_e32 v217, 0xffff0000, v72
	v_lshlrev_b32_e32 v218, 16, v73
	v_and_b32_e32 v219, 0xffff0000, v73
	v_lshlrev_b32_e32 v220, 16, v74
	v_and_b32_e32 v221, 0xffff0000, v74
	v_lshlrev_b32_e32 v222, 16, v75
	v_and_b32_e32 v223, 0xffff0000, v75
	v_lshlrev_b32_e32 v224, 16, v76
	v_and_b32_e32 v225, 0xffff0000, v76
	v_lshlrev_b32_e32 v226, 16, v77
	v_and_b32_e32 v227, 0xffff0000, v77
	v_lshlrev_b32_e32 v228, 16, v78
	v_and_b32_e32 v229, 0xffff0000, v78
	v_lshlrev_b32_e32 v230, 16, v79
	v_and_b32_e32 v231, 0xffff0000, v79
	v_pk_mul_f32 v[252:253], v[216:217], v[216:217]
	v_pk_mul_f32 v[254:255], v[218:219], v[218:219]
	v_pk_fma_f32 v[252:253], v[220:221], v[220:221], v[252:253]
	v_pk_fma_f32 v[254:255], v[222:223], v[222:223], v[254:255]
	v_pk_fma_f32 v[252:253], v[224:225], v[224:225], v[252:253]
	v_pk_fma_f32 v[254:255], v[226:227], v[226:227], v[254:255]
	v_pk_fma_f32 v[252:253], v[228:229], v[228:229], v[252:253]
	v_pk_fma_f32 v[254:255], v[230:231], v[230:231], v[254:255]
	v_pk_add_f32 v[252:253], v[252:253], v[254:255]
	s_nop 0
	v_add_f32_e32 v183, v252, v253
	s_nop 1
	v_add_f32_dpp v183, v183, v183 quad_perm:[1,0,3,2] row_mask:0xf bank_mask:0xf bound_ctrl:1
	s_nop 1
	v_add_f32_dpp v183, v183, v183 quad_perm:[2,3,0,1] row_mask:0xf bank_mask:0xf bound_ctrl:1
	s_nop 1
	v_add_f32_dpp v183, v183, v183 row_half_mirror row_mask:0xf bank_mask:0xf bound_ctrl:1
	s_nop 1
	v_add_f32_dpp v183, v183, v183 row_mirror row_mask:0xf bank_mask:0xf bound_ctrl:1
	s_nop 1
	v_readlane_b32 s98, v183, 0
	v_readlane_b32 s99, v183, 16
	v_readlane_b32 s100, v183, 32
	v_readlane_b32 s101, v183, 48
	s_nop 1
	v_mov_b32_e32 v183, s98
	v_add_f32_e32 v183, s99, v183
	v_add_f32_e32 v183, s100, v183
	v_add_f32_e32 v183, s101, v183
	v_fmamk_f32 v183, v183, 0x3a800000, v182
	v_cmp_gt_f32_e32 vcc, 0x800000, v183
	v_mul_f32_e32 v181, 0x4b800000, v183
	s_nop 1
	v_cndmask_b32_e32 v183, v183, v181, vcc
	v_rsq_f32_e32 v183, v183
	s_nop 0
	v_mul_f32_e32 v181, 0x45800000, v183
	v_cndmask_b32_e32 v184, v183, v181, vcc
	v_mov_b32_e32 v185, v184
	v_pk_mul_f32 v[216:217], v[216:217], v[184:185]
	v_pk_mul_f32 v[218:219], v[218:219], v[184:185]
	v_pk_mul_f32 v[220:221], v[220:221], v[184:185]
	v_pk_mul_f32 v[222:223], v[222:223], v[184:185]
	v_pk_mul_f32 v[224:225], v[224:225], v[184:185]
	v_pk_mul_f32 v[226:227], v[226:227], v[184:185]
	v_pk_mul_f32 v[228:229], v[228:229], v[184:185]
	v_pk_mul_f32 v[230:231], v[230:231], v[184:185]
	v_pk_fma_f32 v[194:195], v[216:217], v[160:161], v[194:195]
	v_pk_fma_f32 v[196:197], v[218:219], v[162:163], v[196:197]
	v_pk_fma_f32 v[198:199], v[220:221], v[164:165], v[198:199]
	v_pk_fma_f32 v[200:201], v[222:223], v[166:167], v[200:201]
	v_pk_fma_f32 v[202:203], v[224:225], v[168:169], v[202:203]
	v_pk_fma_f32 v[204:205], v[226:227], v[170:171], v[204:205]
	v_pk_fma_f32 v[206:207], v[228:229], v[172:173], v[206:207]
	v_pk_fma_f32 v[208:209], v[230:231], v[174:175], v[208:209]
	v_pk_mul_f32 v[252:253], v[194:195], v[194:195]
	v_pk_mul_f32 v[254:255], v[196:197], v[196:197]
	v_pk_fma_f32 v[252:253], v[198:199], v[198:199], v[252:253]
	v_pk_fma_f32 v[254:255], v[200:201], v[200:201], v[254:255]
	v_pk_fma_f32 v[252:253], v[202:203], v[202:203], v[252:253]
	v_pk_fma_f32 v[254:255], v[204:205], v[204:205], v[254:255]
	v_pk_fma_f32 v[252:253], v[206:207], v[206:207], v[252:253]
	v_pk_fma_f32 v[254:255], v[208:209], v[208:209], v[254:255]
	v_pk_add_f32 v[252:253], v[252:253], v[254:255]
	s_nop 0
	v_add_f32_e32 v183, v252, v253
	s_nop 1
	v_add_f32_dpp v183, v183, v183 quad_perm:[1,0,3,2] row_mask:0xf bank_mask:0xf bound_ctrl:1
	s_nop 1
	v_add_f32_dpp v183, v183, v183 quad_perm:[2,3,0,1] row_mask:0xf bank_mask:0xf bound_ctrl:1
	s_nop 1
	v_add_f32_dpp v183, v183, v183 row_half_mirror row_mask:0xf bank_mask:0xf bound_ctrl:1
	s_nop 1
	v_add_f32_dpp v183, v183, v183 row_mirror row_mask:0xf bank_mask:0xf bound_ctrl:1
	s_nop 1
	v_readlane_b32 s98, v183, 0
	v_readlane_b32 s99, v183, 16
	v_readlane_b32 s100, v183, 32
	v_readlane_b32 s101, v183, 48
	s_nop 1
	v_mov_b32_e32 v183, s98
	v_add_f32_e32 v183, s99, v183
	v_add_f32_e32 v183, s100, v183
	v_add_f32_e32 v183, s101, v183
	v_fmamk_f32 v183, v183, 0x3a800000, v182
	v_cmp_gt_f32_e32 vcc, 0x800000, v183
	v_mul_f32_e32 v181, 0x4b800000, v183
	s_nop 1
	v_cndmask_b32_e32 v183, v183, v181, vcc
	v_rsq_f32_e32 v183, v183
	s_nop 0
	v_mul_f32_e32 v181, 0x45800000, v183
	v_cndmask_b32_e32 v184, v183, v181, vcc
	v_mov_b32_e32 v185, v184
	v_cvt_pk_bf16_f32 v64, v194, v195
	v_cvt_pk_bf16_f32 v65, v196, v197
	v_cvt_pk_bf16_f32 v66, v198, v199
	v_cvt_pk_bf16_f32 v67, v200, v201
	v_cvt_pk_bf16_f32 v68, v202, v203
	v_cvt_pk_bf16_f32 v69, v204, v205
	v_cvt_pk_bf16_f32 v70, v206, v207
	v_cvt_pk_bf16_f32 v71, v208, v209
	v_add_u32_e32 v181, 0x2800000, v177
	global_store_dwordx4 v181, v[64:67], s[78:79]
	global_store_dwordx4 v181, v[68:71], s[78:79] offset:1024
	v_add_u32_e32 v236, 0x8000, v237
	s_mov_b64 exec, 1
	global_store_dword v236, v184, s[78:79]
	s_mov_b64 exec, -1
	s_waitcnt vmcnt(16)
	v_lshlrev_b32_e32 v194, 16, v80
	v_and_b32_e32 v195, 0xffff0000, v80
	v_lshlrev_b32_e32 v196, 16, v81
	v_and_b32_e32 v197, 0xffff0000, v81
	v_lshlrev_b32_e32 v198, 16, v82
	v_and_b32_e32 v199, 0xffff0000, v82
	v_lshlrev_b32_e32 v200, 16, v83
	v_and_b32_e32 v201, 0xffff0000, v83
	v_lshlrev_b32_e32 v202, 16, v84
	v_and_b32_e32 v203, 0xffff0000, v84
	v_lshlrev_b32_e32 v204, 16, v85
	v_and_b32_e32 v205, 0xffff0000, v85
	v_lshlrev_b32_e32 v206, 16, v86
	v_and_b32_e32 v207, 0xffff0000, v86
	v_lshlrev_b32_e32 v208, 16, v87
	v_and_b32_e32 v209, 0xffff0000, v87
	v_lshlrev_b32_e32 v216, 16, v88
	v_and_b32_e32 v217, 0xffff0000, v88
	v_lshlrev_b32_e32 v218, 16, v89
	v_and_b32_e32 v219, 0xffff0000, v89
	v_lshlrev_b32_e32 v220, 16, v90
	v_and_b32_e32 v221, 0xffff0000, v90
	v_lshlrev_b32_e32 v222, 16, v91
	v_and_b32_e32 v223, 0xffff0000, v91
	v_lshlrev_b32_e32 v224, 16, v92
	v_and_b32_e32 v225, 0xffff0000, v92
	v_lshlrev_b32_e32 v226, 16, v93
	v_and_b32_e32 v227, 0xffff0000, v93
	v_lshlrev_b32_e32 v228, 16, v94
	v_and_b32_e32 v229, 0xffff0000, v94
	v_lshlrev_b32_e32 v230, 16, v95
	v_and_b32_e32 v231, 0xffff0000, v95
	v_pk_mul_f32 v[252:253], v[216:217], v[216:217]
	v_pk_mul_f32 v[254:255], v[218:219], v[218:219]
	v_pk_fma_f32 v[252:253], v[220:221], v[220:221], v[252:253]
	v_pk_fma_f32 v[254:255], v[222:223], v[222:223], v[254:255]
	v_pk_fma_f32 v[252:253], v[224:225], v[224:225], v[252:253]
	v_pk_fma_f32 v[254:255], v[226:227], v[226:227], v[254:255]
	v_pk_fma_f32 v[252:253], v[228:229], v[228:229], v[252:253]
	v_pk_fma_f32 v[254:255], v[230:231], v[230:231], v[254:255]
	v_pk_add_f32 v[252:253], v[252:253], v[254:255]
	s_nop 0
	v_add_f32_e32 v183, v252, v253
	s_nop 1
	v_add_f32_dpp v183, v183, v183 quad_perm:[1,0,3,2] row_mask:0xf bank_mask:0xf bound_ctrl:1
	s_nop 1
	v_add_f32_dpp v183, v183, v183 quad_perm:[2,3,0,1] row_mask:0xf bank_mask:0xf bound_ctrl:1
	s_nop 1
	v_add_f32_dpp v183, v183, v183 row_half_mirror row_mask:0xf bank_mask:0xf bound_ctrl:1
	s_nop 1
	v_add_f32_dpp v183, v183, v183 row_mirror row_mask:0xf bank_mask:0xf bound_ctrl:1
	s_nop 1
	v_readlane_b32 s98, v183, 0
	v_readlane_b32 s99, v183, 16
	v_readlane_b32 s100, v183, 32
	v_readlane_b32 s101, v183, 48
	s_nop 1
	v_mov_b32_e32 v183, s98
	v_add_f32_e32 v183, s99, v183
	v_add_f32_e32 v183, s100, v183
	v_add_f32_e32 v183, s101, v183
	v_fmamk_f32 v183, v183, 0x3a800000, v182
	v_cmp_gt_f32_e32 vcc, 0x800000, v183
	v_mul_f32_e32 v181, 0x4b800000, v183
	s_nop 1
	v_cndmask_b32_e32 v183, v183, v181, vcc
	v_rsq_f32_e32 v183, v183
	s_nop 0
	v_mul_f32_e32 v181, 0x45800000, v183
	v_cndmask_b32_e32 v184, v183, v181, vcc
	v_mov_b32_e32 v185, v184
	v_pk_mul_f32 v[216:217], v[216:217], v[184:185]
	v_pk_mul_f32 v[218:219], v[218:219], v[184:185]
	v_pk_mul_f32 v[220:221], v[220:221], v[184:185]
	v_pk_mul_f32 v[222:223], v[222:223], v[184:185]
	v_pk_mul_f32 v[224:225], v[224:225], v[184:185]
	v_pk_mul_f32 v[226:227], v[226:227], v[184:185]
	v_pk_mul_f32 v[228:229], v[228:229], v[184:185]
	v_pk_mul_f32 v[230:231], v[230:231], v[184:185]
	v_pk_fma_f32 v[194:195], v[216:217], v[160:161], v[194:195]
	v_pk_fma_f32 v[196:197], v[218:219], v[162:163], v[196:197]
	v_pk_fma_f32 v[198:199], v[220:221], v[164:165], v[198:199]
	v_pk_fma_f32 v[200:201], v[222:223], v[166:167], v[200:201]
	v_pk_fma_f32 v[202:203], v[224:225], v[168:169], v[202:203]
	v_pk_fma_f32 v[204:205], v[226:227], v[170:171], v[204:205]
	v_pk_fma_f32 v[206:207], v[228:229], v[172:173], v[206:207]
	v_pk_fma_f32 v[208:209], v[230:231], v[174:175], v[208:209]
	v_pk_mul_f32 v[252:253], v[194:195], v[194:195]
	v_pk_mul_f32 v[254:255], v[196:197], v[196:197]
	v_pk_fma_f32 v[252:253], v[198:199], v[198:199], v[252:253]
	v_pk_fma_f32 v[254:255], v[200:201], v[200:201], v[254:255]
	v_pk_fma_f32 v[252:253], v[202:203], v[202:203], v[252:253]
	v_pk_fma_f32 v[254:255], v[204:205], v[204:205], v[254:255]
	v_pk_fma_f32 v[252:253], v[206:207], v[206:207], v[252:253]
	v_pk_fma_f32 v[254:255], v[208:209], v[208:209], v[254:255]
	v_pk_add_f32 v[252:253], v[252:253], v[254:255]
	s_nop 0
	v_add_f32_e32 v183, v252, v253
	s_nop 1
	v_add_f32_dpp v183, v183, v183 quad_perm:[1,0,3,2] row_mask:0xf bank_mask:0xf bound_ctrl:1
	s_nop 1
	v_add_f32_dpp v183, v183, v183 quad_perm:[2,3,0,1] row_mask:0xf bank_mask:0xf bound_ctrl:1
	s_nop 1
	v_add_f32_dpp v183, v183, v183 row_half_mirror row_mask:0xf bank_mask:0xf bound_ctrl:1
	s_nop 1
	v_add_f32_dpp v183, v183, v183 row_mirror row_mask:0xf bank_mask:0xf bound_ctrl:1
	s_nop 1
	v_readlane_b32 s98, v183, 0
	v_readlane_b32 s99, v183, 16
	v_readlane_b32 s100, v183, 32
	v_readlane_b32 s101, v183, 48
	s_nop 1
	v_mov_b32_e32 v183, s98
	v_add_f32_e32 v183, s99, v183
	v_add_f32_e32 v183, s100, v183
	v_add_f32_e32 v183, s101, v183
	v_fmamk_f32 v183, v183, 0x3a800000, v182
	v_cmp_gt_f32_e32 vcc, 0x800000, v183
	v_mul_f32_e32 v181, 0x4b800000, v183
	s_nop 1
	v_cndmask_b32_e32 v183, v183, v181, vcc
	v_rsq_f32_e32 v183, v183
	s_nop 0
	v_mul_f32_e32 v181, 0x45800000, v183
	v_cndmask_b32_e32 v184, v183, v181, vcc
	v_mov_b32_e32 v185, v184
	v_cvt_pk_bf16_f32 v80, v194, v195
	v_cvt_pk_bf16_f32 v81, v196, v197
	v_cvt_pk_bf16_f32 v82, v198, v199
	v_cvt_pk_bf16_f32 v83, v200, v201
	v_cvt_pk_bf16_f32 v84, v202, v203
	v_cvt_pk_bf16_f32 v85, v204, v205
	v_cvt_pk_bf16_f32 v86, v206, v207
	v_cvt_pk_bf16_f32 v87, v208, v209
	v_add_u32_e32 v181, 0x2c00000, v177
	global_store_dwordx4 v181, v[80:83], s[78:79]
	global_store_dwordx4 v181, v[84:87], s[78:79] offset:1024
	v_add_u32_e32 v236, 0xa000, v237
	s_mov_b64 exec, 1
	global_store_dword v236, v184, s[78:79]
	s_mov_b64 exec, -1
	s_waitcnt vmcnt(12)
	v_lshlrev_b32_e32 v194, 16, v96
	v_and_b32_e32 v195, 0xffff0000, v96
	v_lshlrev_b32_e32 v196, 16, v97
	v_and_b32_e32 v197, 0xffff0000, v97
	v_lshlrev_b32_e32 v198, 16, v98
	v_and_b32_e32 v199, 0xffff0000, v98
	v_lshlrev_b32_e32 v200, 16, v99
	v_and_b32_e32 v201, 0xffff0000, v99
	v_lshlrev_b32_e32 v202, 16, v100
	v_and_b32_e32 v203, 0xffff0000, v100
	v_lshlrev_b32_e32 v204, 16, v101
	v_and_b32_e32 v205, 0xffff0000, v101
	v_lshlrev_b32_e32 v206, 16, v102
	v_and_b32_e32 v207, 0xffff0000, v102
	v_lshlrev_b32_e32 v208, 16, v103
	v_and_b32_e32 v209, 0xffff0000, v103
	v_lshlrev_b32_e32 v216, 16, v104
	v_and_b32_e32 v217, 0xffff0000, v104
	v_lshlrev_b32_e32 v218, 16, v105
	v_and_b32_e32 v219, 0xffff0000, v105
	v_lshlrev_b32_e32 v220, 16, v106
	v_and_b32_e32 v221, 0xffff0000, v106
	v_lshlrev_b32_e32 v222, 16, v107
	v_and_b32_e32 v223, 0xffff0000, v107
	v_lshlrev_b32_e32 v224, 16, v108
	v_and_b32_e32 v225, 0xffff0000, v108
	v_lshlrev_b32_e32 v226, 16, v109
	v_and_b32_e32 v227, 0xffff0000, v109
	v_lshlrev_b32_e32 v228, 16, v110
	v_and_b32_e32 v229, 0xffff0000, v110
	v_lshlrev_b32_e32 v230, 16, v111
	v_and_b32_e32 v231, 0xffff0000, v111
	v_pk_mul_f32 v[252:253], v[216:217], v[216:217]
	v_pk_mul_f32 v[254:255], v[218:219], v[218:219]
	v_pk_fma_f32 v[252:253], v[220:221], v[220:221], v[252:253]
	v_pk_fma_f32 v[254:255], v[222:223], v[222:223], v[254:255]
	v_pk_fma_f32 v[252:253], v[224:225], v[224:225], v[252:253]
	v_pk_fma_f32 v[254:255], v[226:227], v[226:227], v[254:255]
	v_pk_fma_f32 v[252:253], v[228:229], v[228:229], v[252:253]
	v_pk_fma_f32 v[254:255], v[230:231], v[230:231], v[254:255]
	v_pk_add_f32 v[252:253], v[252:253], v[254:255]
	s_nop 0
	v_add_f32_e32 v183, v252, v253
	s_nop 1
	v_add_f32_dpp v183, v183, v183 quad_perm:[1,0,3,2] row_mask:0xf bank_mask:0xf bound_ctrl:1
	s_nop 1
	v_add_f32_dpp v183, v183, v183 quad_perm:[2,3,0,1] row_mask:0xf bank_mask:0xf bound_ctrl:1
	s_nop 1
	v_add_f32_dpp v183, v183, v183 row_half_mirror row_mask:0xf bank_mask:0xf bound_ctrl:1
	s_nop 1
	v_add_f32_dpp v183, v183, v183 row_mirror row_mask:0xf bank_mask:0xf bound_ctrl:1
	s_nop 1
	v_readlane_b32 s98, v183, 0
	v_readlane_b32 s99, v183, 16
	v_readlane_b32 s100, v183, 32
	v_readlane_b32 s101, v183, 48
	s_nop 1
	v_mov_b32_e32 v183, s98
	v_add_f32_e32 v183, s99, v183
	v_add_f32_e32 v183, s100, v183
	v_add_f32_e32 v183, s101, v183
	v_fmamk_f32 v183, v183, 0x3a800000, v182
	v_cmp_gt_f32_e32 vcc, 0x800000, v183
	v_mul_f32_e32 v181, 0x4b800000, v183
	s_nop 1
	v_cndmask_b32_e32 v183, v183, v181, vcc
	v_rsq_f32_e32 v183, v183
	s_nop 0
	v_mul_f32_e32 v181, 0x45800000, v183
	v_cndmask_b32_e32 v184, v183, v181, vcc
	v_mov_b32_e32 v185, v184
	v_pk_mul_f32 v[216:217], v[216:217], v[184:185]
	v_pk_mul_f32 v[218:219], v[218:219], v[184:185]
	v_pk_mul_f32 v[220:221], v[220:221], v[184:185]
	v_pk_mul_f32 v[222:223], v[222:223], v[184:185]
	v_pk_mul_f32 v[224:225], v[224:225], v[184:185]
	v_pk_mul_f32 v[226:227], v[226:227], v[184:185]
	v_pk_mul_f32 v[228:229], v[228:229], v[184:185]
	v_pk_mul_f32 v[230:231], v[230:231], v[184:185]
	v_pk_fma_f32 v[194:195], v[216:217], v[160:161], v[194:195]
	v_pk_fma_f32 v[196:197], v[218:219], v[162:163], v[196:197]
	v_pk_fma_f32 v[198:199], v[220:221], v[164:165], v[198:199]
	v_pk_fma_f32 v[200:201], v[222:223], v[166:167], v[200:201]
	v_pk_fma_f32 v[202:203], v[224:225], v[168:169], v[202:203]
	v_pk_fma_f32 v[204:205], v[226:227], v[170:171], v[204:205]
	v_pk_fma_f32 v[206:207], v[228:229], v[172:173], v[206:207]
	v_pk_fma_f32 v[208:209], v[230:231], v[174:175], v[208:209]
	v_pk_mul_f32 v[252:253], v[194:195], v[194:195]
	v_pk_mul_f32 v[254:255], v[196:197], v[196:197]
	v_pk_fma_f32 v[252:253], v[198:199], v[198:199], v[252:253]
	v_pk_fma_f32 v[254:255], v[200:201], v[200:201], v[254:255]
	v_pk_fma_f32 v[252:253], v[202:203], v[202:203], v[252:253]
	v_pk_fma_f32 v[254:255], v[204:205], v[204:205], v[254:255]
	v_pk_fma_f32 v[252:253], v[206:207], v[206:207], v[252:253]
	v_pk_fma_f32 v[254:255], v[208:209], v[208:209], v[254:255]
	v_pk_add_f32 v[252:253], v[252:253], v[254:255]
	s_nop 0
	v_add_f32_e32 v183, v252, v253
	s_nop 1
	v_add_f32_dpp v183, v183, v183 quad_perm:[1,0,3,2] row_mask:0xf bank_mask:0xf bound_ctrl:1
	s_nop 1
	v_add_f32_dpp v183, v183, v183 quad_perm:[2,3,0,1] row_mask:0xf bank_mask:0xf bound_ctrl:1
	s_nop 1
	v_add_f32_dpp v183, v183, v183 row_half_mirror row_mask:0xf bank_mask:0xf bound_ctrl:1
	s_nop 1
	v_add_f32_dpp v183, v183, v183 row_mirror row_mask:0xf bank_mask:0xf bound_ctrl:1
	s_nop 1
	v_readlane_b32 s98, v183, 0
	v_readlane_b32 s99, v183, 16
	v_readlane_b32 s100, v183, 32
	v_readlane_b32 s101, v183, 48
	s_nop 1
	v_mov_b32_e32 v183, s98
	v_add_f32_e32 v183, s99, v183
	v_add_f32_e32 v183, s100, v183
	v_add_f32_e32 v183, s101, v183
	v_fmamk_f32 v183, v183, 0x3a800000, v182
	v_cmp_gt_f32_e32 vcc, 0x800000, v183
	v_mul_f32_e32 v181, 0x4b800000, v183
	s_nop 1
	v_cndmask_b32_e32 v183, v183, v181, vcc
	v_rsq_f32_e32 v183, v183
	s_nop 0
	v_mul_f32_e32 v181, 0x45800000, v183
	v_cndmask_b32_e32 v184, v183, v181, vcc
	v_mov_b32_e32 v185, v184
	v_cvt_pk_bf16_f32 v96, v194, v195
	v_cvt_pk_bf16_f32 v97, v196, v197
	v_cvt_pk_bf16_f32 v98, v198, v199
	v_cvt_pk_bf16_f32 v99, v200, v201
	v_cvt_pk_bf16_f32 v100, v202, v203
	v_cvt_pk_bf16_f32 v101, v204, v205
	v_cvt_pk_bf16_f32 v102, v206, v207
	v_cvt_pk_bf16_f32 v103, v208, v209
	v_add_u32_e32 v181, 0x3000000, v177
	global_store_dwordx4 v181, v[96:99], s[78:79]
	global_store_dwordx4 v181, v[100:103], s[78:79] offset:1024
	v_add_u32_e32 v236, 0xc000, v237
	s_mov_b64 exec, 1
	global_store_dword v236, v184, s[78:79]
	s_mov_b64 exec, -1
	s_waitcnt vmcnt(8)
	v_lshlrev_b32_e32 v194, 16, v112
	v_and_b32_e32 v195, 0xffff0000, v112
	v_lshlrev_b32_e32 v196, 16, v113
	v_and_b32_e32 v197, 0xffff0000, v113
	v_lshlrev_b32_e32 v198, 16, v114
	v_and_b32_e32 v199, 0xffff0000, v114
	v_lshlrev_b32_e32 v200, 16, v115
	v_and_b32_e32 v201, 0xffff0000, v115
	v_lshlrev_b32_e32 v202, 16, v116
	v_and_b32_e32 v203, 0xffff0000, v116
	v_lshlrev_b32_e32 v204, 16, v117
	v_and_b32_e32 v205, 0xffff0000, v117
	v_lshlrev_b32_e32 v206, 16, v118
	v_and_b32_e32 v207, 0xffff0000, v118
	v_lshlrev_b32_e32 v208, 16, v119
	v_and_b32_e32 v209, 0xffff0000, v119
	v_lshlrev_b32_e32 v216, 16, v120
	v_and_b32_e32 v217, 0xffff0000, v120
	v_lshlrev_b32_e32 v218, 16, v121
	v_and_b32_e32 v219, 0xffff0000, v121
	v_lshlrev_b32_e32 v220, 16, v122
	v_and_b32_e32 v221, 0xffff0000, v122
	v_lshlrev_b32_e32 v222, 16, v123
	v_and_b32_e32 v223, 0xffff0000, v123
	v_lshlrev_b32_e32 v224, 16, v124
	v_and_b32_e32 v225, 0xffff0000, v124
	v_lshlrev_b32_e32 v226, 16, v125
	v_and_b32_e32 v227, 0xffff0000, v125
	v_lshlrev_b32_e32 v228, 16, v126
	v_and_b32_e32 v229, 0xffff0000, v126
	v_lshlrev_b32_e32 v230, 16, v127
	v_and_b32_e32 v231, 0xffff0000, v127
	v_pk_mul_f32 v[252:253], v[216:217], v[216:217]
	v_pk_mul_f32 v[254:255], v[218:219], v[218:219]
	v_pk_fma_f32 v[252:253], v[220:221], v[220:221], v[252:253]
	v_pk_fma_f32 v[254:255], v[222:223], v[222:223], v[254:255]
	v_pk_fma_f32 v[252:253], v[224:225], v[224:225], v[252:253]
	v_pk_fma_f32 v[254:255], v[226:227], v[226:227], v[254:255]
	v_pk_fma_f32 v[252:253], v[228:229], v[228:229], v[252:253]
	v_pk_fma_f32 v[254:255], v[230:231], v[230:231], v[254:255]
	v_pk_add_f32 v[252:253], v[252:253], v[254:255]
	s_nop 0
	v_add_f32_e32 v183, v252, v253
	s_nop 1
	v_add_f32_dpp v183, v183, v183 quad_perm:[1,0,3,2] row_mask:0xf bank_mask:0xf bound_ctrl:1
	s_nop 1
	v_add_f32_dpp v183, v183, v183 quad_perm:[2,3,0,1] row_mask:0xf bank_mask:0xf bound_ctrl:1
	s_nop 1
	v_add_f32_dpp v183, v183, v183 row_half_mirror row_mask:0xf bank_mask:0xf bound_ctrl:1
	s_nop 1
	v_add_f32_dpp v183, v183, v183 row_mirror row_mask:0xf bank_mask:0xf bound_ctrl:1
	s_nop 1
	v_readlane_b32 s98, v183, 0
	v_readlane_b32 s99, v183, 16
	v_readlane_b32 s100, v183, 32
	v_readlane_b32 s101, v183, 48
	s_nop 1
	v_mov_b32_e32 v183, s98
	v_add_f32_e32 v183, s99, v183
	v_add_f32_e32 v183, s100, v183
	v_add_f32_e32 v183, s101, v183
	v_fmamk_f32 v183, v183, 0x3a800000, v182
	v_cmp_gt_f32_e32 vcc, 0x800000, v183
	v_mul_f32_e32 v181, 0x4b800000, v183
	s_nop 1
	v_cndmask_b32_e32 v183, v183, v181, vcc
	v_rsq_f32_e32 v183, v183
	s_nop 0
	v_mul_f32_e32 v181, 0x45800000, v183
	v_cndmask_b32_e32 v184, v183, v181, vcc
	v_mov_b32_e32 v185, v184
	v_pk_mul_f32 v[216:217], v[216:217], v[184:185]
	v_pk_mul_f32 v[218:219], v[218:219], v[184:185]
	v_pk_mul_f32 v[220:221], v[220:221], v[184:185]
	v_pk_mul_f32 v[222:223], v[222:223], v[184:185]
	v_pk_mul_f32 v[224:225], v[224:225], v[184:185]
	v_pk_mul_f32 v[226:227], v[226:227], v[184:185]
	v_pk_mul_f32 v[228:229], v[228:229], v[184:185]
	v_pk_mul_f32 v[230:231], v[230:231], v[184:185]
	v_pk_fma_f32 v[194:195], v[216:217], v[160:161], v[194:195]
	v_pk_fma_f32 v[196:197], v[218:219], v[162:163], v[196:197]
	v_pk_fma_f32 v[198:199], v[220:221], v[164:165], v[198:199]
	v_pk_fma_f32 v[200:201], v[222:223], v[166:167], v[200:201]
	v_pk_fma_f32 v[202:203], v[224:225], v[168:169], v[202:203]
	v_pk_fma_f32 v[204:205], v[226:227], v[170:171], v[204:205]
	v_pk_fma_f32 v[206:207], v[228:229], v[172:173], v[206:207]
	v_pk_fma_f32 v[208:209], v[230:231], v[174:175], v[208:209]
	v_pk_mul_f32 v[252:253], v[194:195], v[194:195]
	v_pk_mul_f32 v[254:255], v[196:197], v[196:197]
	v_pk_fma_f32 v[252:253], v[198:199], v[198:199], v[252:253]
	v_pk_fma_f32 v[254:255], v[200:201], v[200:201], v[254:255]
	v_pk_fma_f32 v[252:253], v[202:203], v[202:203], v[252:253]
	v_pk_fma_f32 v[254:255], v[204:205], v[204:205], v[254:255]
	v_pk_fma_f32 v[252:253], v[206:207], v[206:207], v[252:253]
	v_pk_fma_f32 v[254:255], v[208:209], v[208:209], v[254:255]
	v_pk_add_f32 v[252:253], v[252:253], v[254:255]
	s_nop 0
	v_add_f32_e32 v183, v252, v253
	s_nop 1
	v_add_f32_dpp v183, v183, v183 quad_perm:[1,0,3,2] row_mask:0xf bank_mask:0xf bound_ctrl:1
	s_nop 1
	v_add_f32_dpp v183, v183, v183 quad_perm:[2,3,0,1] row_mask:0xf bank_mask:0xf bound_ctrl:1
	s_nop 1
	v_add_f32_dpp v183, v183, v183 row_half_mirror row_mask:0xf bank_mask:0xf bound_ctrl:1
	s_nop 1
	v_add_f32_dpp v183, v183, v183 row_mirror row_mask:0xf bank_mask:0xf bound_ctrl:1
	s_nop 1
	v_readlane_b32 s98, v183, 0
	v_readlane_b32 s99, v183, 16
	v_readlane_b32 s100, v183, 32
	v_readlane_b32 s101, v183, 48
	s_nop 1
	v_mov_b32_e32 v183, s98
	v_add_f32_e32 v183, s99, v183
	v_add_f32_e32 v183, s100, v183
	v_add_f32_e32 v183, s101, v183
	v_fmamk_f32 v183, v183, 0x3a800000, v182
	v_cmp_gt_f32_e32 vcc, 0x800000, v183
	v_mul_f32_e32 v181, 0x4b800000, v183
	s_nop 1
	v_cndmask_b32_e32 v183, v183, v181, vcc
	v_rsq_f32_e32 v183, v183
	s_nop 0
	v_mul_f32_e32 v181, 0x45800000, v183
	v_cndmask_b32_e32 v184, v183, v181, vcc
	v_mov_b32_e32 v185, v184
	v_cvt_pk_bf16_f32 v112, v194, v195
	v_cvt_pk_bf16_f32 v113, v196, v197
	v_cvt_pk_bf16_f32 v114, v198, v199
	v_cvt_pk_bf16_f32 v115, v200, v201
	v_cvt_pk_bf16_f32 v116, v202, v203
	v_cvt_pk_bf16_f32 v117, v204, v205
	v_cvt_pk_bf16_f32 v118, v206, v207
	v_cvt_pk_bf16_f32 v119, v208, v209
	v_add_u32_e32 v181, 0x3400000, v177
	global_store_dwordx4 v181, v[112:115], s[78:79]
	global_store_dwordx4 v181, v[116:119], s[78:79] offset:1024
	v_add_u32_e32 v236, 0xe000, v237
	s_mov_b64 exec, 1
	global_store_dword v236, v184, s[78:79]
	s_mov_b64 exec, -1
	s_waitcnt vmcnt(4)
	v_lshlrev_b32_e32 v194, 16, v128
	v_and_b32_e32 v195, 0xffff0000, v128
	v_lshlrev_b32_e32 v196, 16, v129
	v_and_b32_e32 v197, 0xffff0000, v129
	v_lshlrev_b32_e32 v198, 16, v130
	v_and_b32_e32 v199, 0xffff0000, v130
	v_lshlrev_b32_e32 v200, 16, v131
	v_and_b32_e32 v201, 0xffff0000, v131
	v_lshlrev_b32_e32 v202, 16, v132
	v_and_b32_e32 v203, 0xffff0000, v132
	v_lshlrev_b32_e32 v204, 16, v133
	v_and_b32_e32 v205, 0xffff0000, v133
	v_lshlrev_b32_e32 v206, 16, v134
	v_and_b32_e32 v207, 0xffff0000, v134
	v_lshlrev_b32_e32 v208, 16, v135
	v_and_b32_e32 v209, 0xffff0000, v135
	v_lshlrev_b32_e32 v216, 16, v136
	v_and_b32_e32 v217, 0xffff0000, v136
	v_lshlrev_b32_e32 v218, 16, v137
	v_and_b32_e32 v219, 0xffff0000, v137
	v_lshlrev_b32_e32 v220, 16, v138
	v_and_b32_e32 v221, 0xffff0000, v138
	v_lshlrev_b32_e32 v222, 16, v139
	v_and_b32_e32 v223, 0xffff0000, v139
	v_lshlrev_b32_e32 v224, 16, v140
	v_and_b32_e32 v225, 0xffff0000, v140
	v_lshlrev_b32_e32 v226, 16, v141
	v_and_b32_e32 v227, 0xffff0000, v141
	v_lshlrev_b32_e32 v228, 16, v142
	v_and_b32_e32 v229, 0xffff0000, v142
	v_lshlrev_b32_e32 v230, 16, v143
	v_and_b32_e32 v231, 0xffff0000, v143
	v_pk_mul_f32 v[252:253], v[216:217], v[216:217]
	v_pk_mul_f32 v[254:255], v[218:219], v[218:219]
	v_pk_fma_f32 v[252:253], v[220:221], v[220:221], v[252:253]
	v_pk_fma_f32 v[254:255], v[222:223], v[222:223], v[254:255]
	v_pk_fma_f32 v[252:253], v[224:225], v[224:225], v[252:253]
	v_pk_fma_f32 v[254:255], v[226:227], v[226:227], v[254:255]
	v_pk_fma_f32 v[252:253], v[228:229], v[228:229], v[252:253]
	v_pk_fma_f32 v[254:255], v[230:231], v[230:231], v[254:255]
	v_pk_add_f32 v[252:253], v[252:253], v[254:255]
	s_nop 0
	v_add_f32_e32 v183, v252, v253
	s_nop 1
	v_add_f32_dpp v183, v183, v183 quad_perm:[1,0,3,2] row_mask:0xf bank_mask:0xf bound_ctrl:1
	s_nop 1
	v_add_f32_dpp v183, v183, v183 quad_perm:[2,3,0,1] row_mask:0xf bank_mask:0xf bound_ctrl:1
	s_nop 1
	v_add_f32_dpp v183, v183, v183 row_half_mirror row_mask:0xf bank_mask:0xf bound_ctrl:1
	s_nop 1
	v_add_f32_dpp v183, v183, v183 row_mirror row_mask:0xf bank_mask:0xf bound_ctrl:1
	s_nop 1
	v_readlane_b32 s98, v183, 0
	v_readlane_b32 s99, v183, 16
	v_readlane_b32 s100, v183, 32
	v_readlane_b32 s101, v183, 48
	s_nop 1
	v_mov_b32_e32 v183, s98
	v_add_f32_e32 v183, s99, v183
	v_add_f32_e32 v183, s100, v183
	v_add_f32_e32 v183, s101, v183
	v_fmamk_f32 v183, v183, 0x3a800000, v182
	v_cmp_gt_f32_e32 vcc, 0x800000, v183
	v_mul_f32_e32 v181, 0x4b800000, v183
	s_nop 1
	v_cndmask_b32_e32 v183, v183, v181, vcc
	v_rsq_f32_e32 v183, v183
	s_nop 0
	v_mul_f32_e32 v181, 0x45800000, v183
	v_cndmask_b32_e32 v184, v183, v181, vcc
	v_mov_b32_e32 v185, v184
	v_pk_mul_f32 v[216:217], v[216:217], v[184:185]
	v_pk_mul_f32 v[218:219], v[218:219], v[184:185]
	v_pk_mul_f32 v[220:221], v[220:221], v[184:185]
	v_pk_mul_f32 v[222:223], v[222:223], v[184:185]
	v_pk_mul_f32 v[224:225], v[224:225], v[184:185]
	v_pk_mul_f32 v[226:227], v[226:227], v[184:185]
	v_pk_mul_f32 v[228:229], v[228:229], v[184:185]
	v_pk_mul_f32 v[230:231], v[230:231], v[184:185]
	v_pk_fma_f32 v[194:195], v[216:217], v[160:161], v[194:195]
	v_pk_fma_f32 v[196:197], v[218:219], v[162:163], v[196:197]
	v_pk_fma_f32 v[198:199], v[220:221], v[164:165], v[198:199]
	v_pk_fma_f32 v[200:201], v[222:223], v[166:167], v[200:201]
	v_pk_fma_f32 v[202:203], v[224:225], v[168:169], v[202:203]
	v_pk_fma_f32 v[204:205], v[226:227], v[170:171], v[204:205]
	v_pk_fma_f32 v[206:207], v[228:229], v[172:173], v[206:207]
	v_pk_fma_f32 v[208:209], v[230:231], v[174:175], v[208:209]
	v_pk_mul_f32 v[252:253], v[194:195], v[194:195]
	v_pk_mul_f32 v[254:255], v[196:197], v[196:197]
	v_pk_fma_f32 v[252:253], v[198:199], v[198:199], v[252:253]
	v_pk_fma_f32 v[254:255], v[200:201], v[200:201], v[254:255]
	v_pk_fma_f32 v[252:253], v[202:203], v[202:203], v[252:253]
	v_pk_fma_f32 v[254:255], v[204:205], v[204:205], v[254:255]
	v_pk_fma_f32 v[252:253], v[206:207], v[206:207], v[252:253]
	v_pk_fma_f32 v[254:255], v[208:209], v[208:209], v[254:255]
	v_pk_add_f32 v[252:253], v[252:253], v[254:255]
	s_nop 0
	v_add_f32_e32 v183, v252, v253
	s_nop 1
	v_add_f32_dpp v183, v183, v183 quad_perm:[1,0,3,2] row_mask:0xf bank_mask:0xf bound_ctrl:1
	s_nop 1
	v_add_f32_dpp v183, v183, v183 quad_perm:[2,3,0,1] row_mask:0xf bank_mask:0xf bound_ctrl:1
	s_nop 1
	v_add_f32_dpp v183, v183, v183 row_half_mirror row_mask:0xf bank_mask:0xf bound_ctrl:1
	s_nop 1
	v_add_f32_dpp v183, v183, v183 row_mirror row_mask:0xf bank_mask:0xf bound_ctrl:1
	s_nop 1
	v_readlane_b32 s98, v183, 0
	v_readlane_b32 s99, v183, 16
	v_readlane_b32 s100, v183, 32
	v_readlane_b32 s101, v183, 48
	s_nop 1
	v_mov_b32_e32 v183, s98
	v_add_f32_e32 v183, s99, v183
	v_add_f32_e32 v183, s100, v183
	v_add_f32_e32 v183, s101, v183
	v_fmamk_f32 v183, v183, 0x3a800000, v182
	v_cmp_gt_f32_e32 vcc, 0x800000, v183
	v_mul_f32_e32 v181, 0x4b800000, v183
	s_nop 1
	v_cndmask_b32_e32 v183, v183, v181, vcc
	v_rsq_f32_e32 v183, v183
	s_nop 0
	v_mul_f32_e32 v181, 0x45800000, v183
	v_cndmask_b32_e32 v184, v183, v181, vcc
	v_mov_b32_e32 v185, v184
	v_cvt_pk_bf16_f32 v128, v194, v195
	v_cvt_pk_bf16_f32 v129, v196, v197
	v_cvt_pk_bf16_f32 v130, v198, v199
	v_cvt_pk_bf16_f32 v131, v200, v201
	v_cvt_pk_bf16_f32 v132, v202, v203
	v_cvt_pk_bf16_f32 v133, v204, v205
	v_cvt_pk_bf16_f32 v134, v206, v207
	v_cvt_pk_bf16_f32 v135, v208, v209
	v_add_u32_e32 v181, 0x1800000, v210
	global_store_dwordx4 v181, v[128:131], s[78:79]
	global_store_dwordx4 v181, v[132:135], s[78:79] offset:1024
	v_add_u32_e32 v236, 0x0, v211
	s_mov_b64 exec, 1
	global_store_dword v236, v184, s[78:79]
	s_mov_b64 exec, -1
	s_waitcnt vmcnt(0)
	v_lshlrev_b32_e32 v194, 16, v144
	v_and_b32_e32 v195, 0xffff0000, v144
	v_lshlrev_b32_e32 v196, 16, v145
	v_and_b32_e32 v197, 0xffff0000, v145
	v_lshlrev_b32_e32 v198, 16, v146
	v_and_b32_e32 v199, 0xffff0000, v146
	v_lshlrev_b32_e32 v200, 16, v147
	v_and_b32_e32 v201, 0xffff0000, v147
	v_lshlrev_b32_e32 v202, 16, v148
	v_and_b32_e32 v203, 0xffff0000, v148
	v_lshlrev_b32_e32 v204, 16, v149
	v_and_b32_e32 v205, 0xffff0000, v149
	v_lshlrev_b32_e32 v206, 16, v150
	v_and_b32_e32 v207, 0xffff0000, v150
	v_lshlrev_b32_e32 v208, 16, v151
	v_and_b32_e32 v209, 0xffff0000, v151
	v_lshlrev_b32_e32 v216, 16, v152
	v_and_b32_e32 v217, 0xffff0000, v152
	v_lshlrev_b32_e32 v218, 16, v153
	v_and_b32_e32 v219, 0xffff0000, v153
	v_lshlrev_b32_e32 v220, 16, v154
	v_and_b32_e32 v221, 0xffff0000, v154
	v_lshlrev_b32_e32 v222, 16, v155
	v_and_b32_e32 v223, 0xffff0000, v155
	v_lshlrev_b32_e32 v224, 16, v156
	v_and_b32_e32 v225, 0xffff0000, v156
	v_lshlrev_b32_e32 v226, 16, v157
	v_and_b32_e32 v227, 0xffff0000, v157
	v_lshlrev_b32_e32 v228, 16, v158
	v_and_b32_e32 v229, 0xffff0000, v158
	v_lshlrev_b32_e32 v230, 16, v159
	v_and_b32_e32 v231, 0xffff0000, v159
	v_pk_mul_f32 v[252:253], v[216:217], v[216:217]
	v_pk_mul_f32 v[254:255], v[218:219], v[218:219]
	v_pk_fma_f32 v[252:253], v[220:221], v[220:221], v[252:253]
	v_pk_fma_f32 v[254:255], v[222:223], v[222:223], v[254:255]
	v_pk_fma_f32 v[252:253], v[224:225], v[224:225], v[252:253]
	v_pk_fma_f32 v[254:255], v[226:227], v[226:227], v[254:255]
	v_pk_fma_f32 v[252:253], v[228:229], v[228:229], v[252:253]
	v_pk_fma_f32 v[254:255], v[230:231], v[230:231], v[254:255]
	v_pk_add_f32 v[252:253], v[252:253], v[254:255]
	s_nop 0
	v_add_f32_e32 v183, v252, v253
	s_nop 1
	v_add_f32_dpp v183, v183, v183 quad_perm:[1,0,3,2] row_mask:0xf bank_mask:0xf bound_ctrl:1
	s_nop 1
	v_add_f32_dpp v183, v183, v183 quad_perm:[2,3,0,1] row_mask:0xf bank_mask:0xf bound_ctrl:1
	s_nop 1
	v_add_f32_dpp v183, v183, v183 row_half_mirror row_mask:0xf bank_mask:0xf bound_ctrl:1
	s_nop 1
	v_add_f32_dpp v183, v183, v183 row_mirror row_mask:0xf bank_mask:0xf bound_ctrl:1
	s_nop 1
	v_readlane_b32 s98, v183, 0
	v_readlane_b32 s99, v183, 16
	v_readlane_b32 s100, v183, 32
	v_readlane_b32 s101, v183, 48
	s_nop 1
	v_mov_b32_e32 v183, s98
	v_add_f32_e32 v183, s99, v183
	v_add_f32_e32 v183, s100, v183
	v_add_f32_e32 v183, s101, v183
	v_fmamk_f32 v183, v183, 0x3a800000, v182
	v_cmp_gt_f32_e32 vcc, 0x800000, v183
	v_mul_f32_e32 v181, 0x4b800000, v183
	s_nop 1
	v_cndmask_b32_e32 v183, v183, v181, vcc
	v_rsq_f32_e32 v183, v183
	s_nop 0
	v_mul_f32_e32 v181, 0x45800000, v183
	v_cndmask_b32_e32 v184, v183, v181, vcc
	v_mov_b32_e32 v185, v184
	v_pk_mul_f32 v[216:217], v[216:217], v[184:185]
	v_pk_mul_f32 v[218:219], v[218:219], v[184:185]
	v_pk_mul_f32 v[220:221], v[220:221], v[184:185]
	v_pk_mul_f32 v[222:223], v[222:223], v[184:185]
	v_pk_mul_f32 v[224:225], v[224:225], v[184:185]
	v_pk_mul_f32 v[226:227], v[226:227], v[184:185]
	v_pk_mul_f32 v[228:229], v[228:229], v[184:185]
	v_pk_mul_f32 v[230:231], v[230:231], v[184:185]
	v_pk_fma_f32 v[194:195], v[216:217], v[160:161], v[194:195]
	v_pk_fma_f32 v[196:197], v[218:219], v[162:163], v[196:197]
	v_pk_fma_f32 v[198:199], v[220:221], v[164:165], v[198:199]
	v_pk_fma_f32 v[200:201], v[222:223], v[166:167], v[200:201]
	v_pk_fma_f32 v[202:203], v[224:225], v[168:169], v[202:203]
	v_pk_fma_f32 v[204:205], v[226:227], v[170:171], v[204:205]
	v_pk_fma_f32 v[206:207], v[228:229], v[172:173], v[206:207]
	v_pk_fma_f32 v[208:209], v[230:231], v[174:175], v[208:209]
	v_pk_mul_f32 v[252:253], v[194:195], v[194:195]
	v_pk_mul_f32 v[254:255], v[196:197], v[196:197]
	v_pk_fma_f32 v[252:253], v[198:199], v[198:199], v[252:253]
	v_pk_fma_f32 v[254:255], v[200:201], v[200:201], v[254:255]
	v_pk_fma_f32 v[252:253], v[202:203], v[202:203], v[252:253]
	v_pk_fma_f32 v[254:255], v[204:205], v[204:205], v[254:255]
	v_pk_fma_f32 v[252:253], v[206:207], v[206:207], v[252:253]
	v_pk_fma_f32 v[254:255], v[208:209], v[208:209], v[254:255]
	v_pk_add_f32 v[252:253], v[252:253], v[254:255]
	s_nop 0
	v_add_f32_e32 v183, v252, v253
	s_nop 1
	v_add_f32_dpp v183, v183, v183 quad_perm:[1,0,3,2] row_mask:0xf bank_mask:0xf bound_ctrl:1
	s_nop 1
	v_add_f32_dpp v183, v183, v183 quad_perm:[2,3,0,1] row_mask:0xf bank_mask:0xf bound_ctrl:1
	s_nop 1
	v_add_f32_dpp v183, v183, v183 row_half_mirror row_mask:0xf bank_mask:0xf bound_ctrl:1
	s_nop 1
	v_add_f32_dpp v183, v183, v183 row_mirror row_mask:0xf bank_mask:0xf bound_ctrl:1
	s_nop 1
	v_readlane_b32 s98, v183, 0
	v_readlane_b32 s99, v183, 16
	v_readlane_b32 s100, v183, 32
	v_readlane_b32 s101, v183, 48
	s_nop 1
	v_mov_b32_e32 v183, s98
	v_add_f32_e32 v183, s99, v183
	v_add_f32_e32 v183, s100, v183
	v_add_f32_e32 v183, s101, v183
	v_fmamk_f32 v183, v183, 0x3a800000, v182
	v_cmp_gt_f32_e32 vcc, 0x800000, v183
	v_mul_f32_e32 v181, 0x4b800000, v183
	s_nop 1
	v_cndmask_b32_e32 v183, v183, v181, vcc
	v_rsq_f32_e32 v183, v183
	s_nop 0
	v_mul_f32_e32 v181, 0x45800000, v183
	v_cndmask_b32_e32 v184, v183, v181, vcc
	v_mov_b32_e32 v185, v184
	v_cvt_pk_bf16_f32 v144, v194, v195
	v_cvt_pk_bf16_f32 v145, v196, v197
	v_cvt_pk_bf16_f32 v146, v198, v199
	v_cvt_pk_bf16_f32 v147, v200, v201
	v_cvt_pk_bf16_f32 v148, v202, v203
	v_cvt_pk_bf16_f32 v149, v204, v205
	v_cvt_pk_bf16_f32 v150, v206, v207
	v_cvt_pk_bf16_f32 v151, v208, v209
	v_add_u32_e32 v181, 0x1c00000, v210
	global_store_dwordx4 v181, v[144:147], s[78:79]
	global_store_dwordx4 v181, v[148:151], s[78:79] offset:1024
	v_add_u32_e32 v236, 0x2000, v211
	s_mov_b64 exec, 1
	global_store_dword v236, v184, s[78:79]
	s_mov_b64 exec, -1
	s_branch .Lmyxupd_done_6

.LBB0_2849:
	v_readlane_b32 s0, v235, 52
	v_readlane_b32 s1, v235, 53
	s_and_b64 vcc, exec, s[0:1]
	s_waitcnt lgkmcnt(0)
	s_barrier
	v_mbcnt_lo_u32_b32 v0, -1, 0
	v_mbcnt_hi_u32_b32 v0, -1, v0
	s_cbranch_vccnz .LBB0_2864
	v_lshlrev_b32_e32 v0, 3, v0
	v_ashrrev_i32_e32 v1, 31, v0
	v_readlane_b32 s0, v235, 4
	v_lshlrev_b64 v[2:3], 1, v[0:1]
	v_lshlrev_b64 v[0:1], 2, v[0:1]
	v_readlane_b32 s1, v235, 5
	v_readlane_b32 s14, v235, 18
	v_readlane_b32 s15, v235, 19
	s_mov_b64 s[0:1], 0x3000
	v_readlane_b32 s2, v235, 6
	v_lshl_add_u64 v[4:5], s[14:15], 0, v[0:1]
	v_readlane_b32 s4, v235, 8
	v_readlane_b32 s5, v235, 9
	v_lshl_add_u64 v[50:51], v[4:5], 0, s[0:1]
	v_readlane_b32 s0, v235, 0
	s_ashr_i32 s25, s24, 31
	s_lshl_b32 s0, s0, 4
	s_add_i32 s2, s24, 0xffffc000
	s_lshl_b64 s[4:5], s[24:25], 11
	s_add_u32 s4, s78, s4
	v_readlane_b32 s1, v235, 1
	s_addc_u32 s5, s79, s5
	v_lshl_add_u64 v[44:45], s[86:87], 0, v[2:3]
	v_lshl_add_u64 v[48:49], s[54:55], 0, v[2:3]
	v_readlane_b32 s6, v235, 10
	v_readlane_b32 s7, v235, 11
	v_lshl_add_u64 v[2:3], s[4:5], 0, v[2:3]
	s_mov_b64 s[4:5], 0x9e00000
	s_ashr_i32 s1, s0, 31
	v_lshl_add_u64 v[56:57], v[2:3], 0, s[4:5]
	s_lshl_b64 s[4:5], s[0:1], 11
	s_lshl_b64 s[6:7], s[24:25], 12
	s_add_u32 s6, s76, s6
	s_addc_u32 s7, s77, s7
	v_lshl_add_u64 v[46:47], s[90:91], 0, v[0:1]
	v_readlane_b32 s3, v235, 7
	v_readlane_b32 s8, v235, 12
	v_readlane_b32 s9, v235, 13
	v_readlane_b32 s10, v235, 14
	v_readlane_b32 s11, v235, 15
	v_readlane_b32 s12, v235, 16
	v_readlane_b32 s13, v235, 17
	v_lshl_add_u64 v[52:53], s[74:75], 0, v[0:1]
	v_lshl_add_u64 v[54:55], s[76:77], 0, v[0:1]
	v_lshl_add_u64 v[0:1], s[6:7], 0, v[0:1]
	s_mov_b64 s[6:7], 0x810
	v_lshl_add_u64 v[58:59], v[0:1], 0, s[6:7]
	s_lshl_b64 s[6:7], s[0:1], 12
	s_mov_b32 s3, 0
	s_mov_b64 s[8:9], 0x200000
	s_mov_b64 s[10:11], 0x200800
	s_mov_b64 s[12:13], 0x400000
	s_mov_b64 s[14:15], 0x400800
	s_mov_b64 s[16:17], 0x600000
	s_mov_b64 s[18:19], 0x600800
	s_mov_b64 s[20:21], 0x800000
	s_mov_b32 s1, 0x800000
	s_mov_b64 s[22:23], 0x800800
	s_mov_b64 s[24:25], 0xa00000
	s_mov_b64 s[26:27], 0xa00800
	s_mov_b64 s[28:29], 0xc00000
	s_mov_b64 s[30:31], 0xc00800
	s_mov_b64 s[34:35], 0xe00000
	s_mov_b64 s[36:37], 0xe00800
	s_mov_b64 s[38:39], 0x1000000
	s_mov_b32 s60, 0x1000000
	s_mov_b64 s[40:41], 0x1000800
	s_mov_b64 s[42:43], 0x1200000
	s_mov_b32 s61, 0x1200000
	s_mov_b64 s[44:45], 0x1200800
	s_mov_b64 s[46:47], 0x1400000
	s_mov_b32 s62, 0x1400000
	s_mov_b64 s[48:49], 0x1400800
	v_mov_b32_e32 v100, 0x358637bd
	v_mbcnt_lo_u32_b32 v176, -1, 0
	v_mbcnt_hi_u32_b32 v176, -1, v176
	v_readlane_b32 s98, v235, 49
	v_readlane_b32 s99, v235, 20
	v_readlane_b32 s100, v235, 18
	v_readlane_b32 s101, v235, 19
	s_nop 3
	s_lshr_b32 vcc_lo, s98, 3
	s_and_b32 vcc_hi, vcc_lo, 7
	s_lshr_b32 vcc_lo, vcc_lo, 3
	s_lshl_b32 vcc_lo, vcc_lo, 3
	s_add_i32 vcc_lo, vcc_lo, s99
	s_lshl_b32 s98, vcc_hi, 8
	s_add_i32 s98, s98, vcc_lo
	v_mov_b32_e32 v179, s98
	v_lshlrev_b32_e32 v177, 4, v176
	s_lshl_b32 s99, s98, 11
	v_add_u32_e32 v177, s99, v177
	v_lshlrev_b32_e32 v180, 5, v176
	v_add_u32_e32 v181, 0x3000, v180
	global_load_dwordx4 v[160:163], v181, s[100:101]
	global_load_dwordx4 v[164:167], v181, s[100:101] offset:16
	global_load_dwordx4 v[168:171], v181, s[100:101] offset:2048
	global_load_dwordx4 v[172:175], v181, s[100:101] offset:2064
	global_load_dwordx4 v[236:239], v180, s[74:75]
	global_load_dwordx4 v[240:243], v180, s[74:75] offset:16
	global_load_dwordx4 v[244:247], v180, s[74:75] offset:2048
	global_load_dwordx4 v[248:251], v180, s[74:75] offset:2064
	v_mov_b32_e32 v182, 0x358637bd
	v_lshl_add_u32 v233, v179, 12, v180
	s_and_b32 s99, s98, 3
	s_cmp_eq_u32 s99, 0
	s_cbranch_scc1 .Lmyxupd_s_7
	s_mul_i32 s100, s99, 0x7ff800
	v_add_u32_e32 v210, s100, v177
	s_mul_i32 s100, s99, 0xfff000
	v_add_u32_e32 v211, s100, v233
	v_add_u32_e32 v178, 0x1800000, v177
	v_add_u32_e32 v181, 0x9e00000, v177
	global_load_dwordx4 v[0:3], v178, s[78:79]
	global_load_dwordx4 v[4:7], v178, s[78:79] offset:1024
	global_load_dwordx4 v[8:11], v181, s[78:79]
	global_load_dwordx4 v[12:15], v181, s[78:79] offset:1024
	v_add_u32_e32 v178, 0x1c00000, v177
	v_add_u32_e32 v181, 0xa200000, v177
	global_load_dwordx4 v[16:19], v178, s[78:79]
	global_load_dwordx4 v[20:23], v178, s[78:79] offset:1024
	global_load_dwordx4 v[24:27], v181, s[78:79]
	global_load_dwordx4 v[28:31], v181, s[78:79] offset:1024
	v_add_u32_e32 v178, 0x2000000, v177
	v_add_u32_e32 v181, 0xa600000, v177
	global_load_dwordx4 v[32:35], v178, s[78:79]
	global_load_dwordx4 v[36:39], v178, s[78:79] offset:1024
	global_load_dwordx4 v[40:43], v181, s[78:79]
	global_load_dwordx4 v[44:47], v181, s[78:79] offset:1024
	v_add_u32_e32 v178, 0x2400000, v177
	v_add_u32_e32 v181, 0xaa00000, v177
	global_load_dwordx4 v[48:51], v178, s[78:79]
	global_load_dwordx4 v[52:55], v178, s[78:79] offset:1024
	global_load_dwordx4 v[56:59], v181, s[78:79]
	global_load_dwordx4 v[60:63], v181, s[78:79] offset:1024
	v_add_u32_e32 v178, 0x2800000, v177
	v_add_u32_e32 v181, 0xae00000, v177
	global_load_dwordx4 v[64:67], v178, s[78:79]
	global_load_dwordx4 v[68:71], v178, s[78:79] offset:1024
	global_load_dwordx4 v[72:75], v181, s[78:79]
	global_load_dwordx4 v[76:79], v181, s[78:79] offset:1024
	v_add_u32_e32 v178, 0x2c00000, v177
	v_add_u32_e32 v181, 0xb200000, v177
	global_load_dwordx4 v[80:83], v178, s[78:79]
	global_load_dwordx4 v[84:87], v178, s[78:79] offset:1024
	global_load_dwordx4 v[88:91], v181, s[78:79]
	global_load_dwordx4 v[92:95], v181, s[78:79] offset:1024
	v_add_u32_e32 v178, 0x3000000, v177
	v_add_u32_e32 v181, 0xb600000, v177
	global_load_dwordx4 v[96:99], v178, s[78:79]
	global_load_dwordx4 v[100:103], v178, s[78:79] offset:1024
	global_load_dwordx4 v[104:107], v181, s[78:79]
	global_load_dwordx4 v[108:111], v181, s[78:79] offset:1024
	v_add_u32_e32 v178, 0x3400000, v177
	v_add_u32_e32 v181, 0xba00000, v177
	global_load_dwordx4 v[112:115], v178, s[78:79]
	global_load_dwordx4 v[116:119], v178, s[78:79] offset:1024
	global_load_dwordx4 v[120:123], v181, s[78:79]
	global_load_dwordx4 v[124:127], v181, s[78:79] offset:1024
	v_add_u32_e32 v178, 0x1800000, v210
	v_add_u32_e32 v181, 0x9e00000, v210
	global_load_dwordx4 v[128:131], v178, s[78:79]
	global_load_dwordx4 v[132:135], v178, s[78:79] offset:1024
	global_load_dwordx4 v[136:139], v181, s[78:79]
	global_load_dwordx4 v[140:143], v181, s[78:79] offset:1024
	v_add_u32_e32 v178, 0x1c00000, v210
	v_add_u32_e32 v181, 0xa200000, v210
	global_load_dwordx4 v[144:147], v178, s[78:79]
	global_load_dwordx4 v[148:151], v178, s[78:79] offset:1024
	global_load_dwordx4 v[152:155], v181, s[78:79]
	global_load_dwordx4 v[156:159], v181, s[78:79] offset:1024
	s_waitcnt vmcnt(36)
	v_lshlrev_b32_e32 v194, 16, v0
	v_and_b32_e32 v195, 0xffff0000, v0
	v_lshlrev_b32_e32 v196, 16, v1
	v_and_b32_e32 v197, 0xffff0000, v1
	v_lshlrev_b32_e32 v198, 16, v2
	v_and_b32_e32 v199, 0xffff0000, v2
	v_lshlrev_b32_e32 v200, 16, v3
	v_and_b32_e32 v201, 0xffff0000, v3
	v_lshlrev_b32_e32 v202, 16, v4
	v_and_b32_e32 v203, 0xffff0000, v4
	v_lshlrev_b32_e32 v204, 16, v5
	v_and_b32_e32 v205, 0xffff0000, v5
	v_lshlrev_b32_e32 v206, 16, v6
	v_and_b32_e32 v207, 0xffff0000, v6
	v_lshlrev_b32_e32 v208, 16, v7
	v_and_b32_e32 v209, 0xffff0000, v7
	v_lshlrev_b32_e32 v216, 16, v8
	v_and_b32_e32 v217, 0xffff0000, v8
	v_lshlrev_b32_e32 v218, 16, v9
	v_and_b32_e32 v219, 0xffff0000, v9
	v_lshlrev_b32_e32 v220, 16, v10
	v_and_b32_e32 v221, 0xffff0000, v10
	v_lshlrev_b32_e32 v222, 16, v11
	v_and_b32_e32 v223, 0xffff0000, v11
	v_lshlrev_b32_e32 v224, 16, v12
	v_and_b32_e32 v225, 0xffff0000, v12
	v_lshlrev_b32_e32 v226, 16, v13
	v_and_b32_e32 v227, 0xffff0000, v13
	v_lshlrev_b32_e32 v228, 16, v14
	v_and_b32_e32 v229, 0xffff0000, v14
	v_lshlrev_b32_e32 v230, 16, v15
	v_and_b32_e32 v231, 0xffff0000, v15
	v_pk_mul_f32 v[252:253], v[216:217], v[216:217]
	v_pk_mul_f32 v[254:255], v[218:219], v[218:219]
	v_pk_fma_f32 v[252:253], v[220:221], v[220:221], v[252:253]
	v_pk_fma_f32 v[254:255], v[222:223], v[222:223], v[254:255]
	v_pk_fma_f32 v[252:253], v[224:225], v[224:225], v[252:253]
	v_pk_fma_f32 v[254:255], v[226:227], v[226:227], v[254:255]
	v_pk_fma_f32 v[252:253], v[228:229], v[228:229], v[252:253]
	v_pk_fma_f32 v[254:255], v[230:231], v[230:231], v[254:255]
	v_pk_add_f32 v[252:253], v[252:253], v[254:255]
	s_nop 0
	v_add_f32_e32 v183, v252, v253
	s_nop 1
	v_add_f32_dpp v183, v183, v183 quad_perm:[1,0,3,2] row_mask:0xf bank_mask:0xf bound_ctrl:1
	s_nop 1
	v_add_f32_dpp v183, v183, v183 quad_perm:[2,3,0,1] row_mask:0xf bank_mask:0xf bound_ctrl:1
	s_nop 1
	v_add_f32_dpp v183, v183, v183 row_half_mirror row_mask:0xf bank_mask:0xf bound_ctrl:1
	s_nop 1
	v_add_f32_dpp v183, v183, v183 row_mirror row_mask:0xf bank_mask:0xf bound_ctrl:1
	s_nop 1
	v_readlane_b32 s98, v183, 0
	v_readlane_b32 s99, v183, 16
	v_readlane_b32 s100, v183, 32
	v_readlane_b32 s101, v183, 48
	s_nop 1
	v_mov_b32_e32 v183, s98
	v_add_f32_e32 v183, s99, v183
	v_add_f32_e32 v183, s100, v183
	v_add_f32_e32 v183, s101, v183
	v_fmamk_f32 v183, v183, 0x3a800000, v182
	v_cmp_gt_f32_e32 vcc, 0x800000, v183
	v_mul_f32_e32 v181, 0x4b800000, v183
	s_nop 1
	v_cndmask_b32_e32 v183, v183, v181, vcc
	v_rsq_f32_e32 v183, v183
	s_nop 0
	v_mul_f32_e32 v181, 0x45800000, v183
	v_cndmask_b32_e32 v184, v183, v181, vcc
	v_mov_b32_e32 v185, v184
	v_pk_mul_f32 v[216:217], v[216:217], v[184:185]
	v_pk_mul_f32 v[218:219], v[218:219], v[184:185]
	v_pk_mul_f32 v[220:221], v[220:221], v[184:185]
	v_pk_mul_f32 v[222:223], v[222:223], v[184:185]
	v_pk_mul_f32 v[224:225], v[224:225], v[184:185]
	v_pk_mul_f32 v[226:227], v[226:227], v[184:185]
	v_pk_mul_f32 v[228:229], v[228:229], v[184:185]
	v_pk_mul_f32 v[230:231], v[230:231], v[184:185]
	v_pk_fma_f32 v[194:195], v[216:217], v[160:161], v[194:195]
	v_pk_fma_f32 v[196:197], v[218:219], v[162:163], v[196:197]
	v_pk_fma_f32 v[198:199], v[220:221], v[164:165], v[198:199]
	v_pk_fma_f32 v[200:201], v[222:223], v[166:167], v[200:201]
	v_pk_fma_f32 v[202:203], v[224:225], v[168:169], v[202:203]
	v_pk_fma_f32 v[204:205], v[226:227], v[170:171], v[204:205]
	v_pk_fma_f32 v[206:207], v[228:229], v[172:173], v[206:207]
	v_pk_fma_f32 v[208:209], v[230:231], v[174:175], v[208:209]
	v_pk_mul_f32 v[252:253], v[194:195], v[194:195]
	v_pk_mul_f32 v[254:255], v[196:197], v[196:197]
	v_pk_fma_f32 v[252:253], v[198:199], v[198:199], v[252:253]
	v_pk_fma_f32 v[254:255], v[200:201], v[200:201], v[254:255]
	v_pk_fma_f32 v[252:253], v[202:203], v[202:203], v[252:253]
	v_pk_fma_f32 v[254:255], v[204:205], v[204:205], v[254:255]
	v_pk_fma_f32 v[252:253], v[206:207], v[206:207], v[252:253]
	v_pk_fma_f32 v[254:255], v[208:209], v[208:209], v[254:255]
	v_pk_add_f32 v[252:253], v[252:253], v[254:255]
	s_nop 0
	v_add_f32_e32 v183, v252, v253
	s_nop 1
	v_add_f32_dpp v183, v183, v183 quad_perm:[1,0,3,2] row_mask:0xf bank_mask:0xf bound_ctrl:1
	s_nop 1
	v_add_f32_dpp v183, v183, v183 quad_perm:[2,3,0,1] row_mask:0xf bank_mask:0xf bound_ctrl:1
	s_nop 1
	v_add_f32_dpp v183, v183, v183 row_half_mirror row_mask:0xf bank_mask:0xf bound_ctrl:1
	s_nop 1
	v_add_f32_dpp v183, v183, v183 row_mirror row_mask:0xf bank_mask:0xf bound_ctrl:1
	s_nop 1
	v_readlane_b32 s98, v183, 0
	v_readlane_b32 s99, v183, 16
	v_readlane_b32 s100, v183, 32
	v_readlane_b32 s101, v183, 48
	s_nop 1
	v_mov_b32_e32 v183, s98
	v_add_f32_e32 v183, s99, v183
	v_add_f32_e32 v183, s100, v183
	v_add_f32_e32 v183, s101, v183
	v_fmamk_f32 v183, v183, 0x3a800000, v182
	v_cmp_gt_f32_e32 vcc, 0x800000, v183
	v_mul_f32_e32 v181, 0x4b800000, v183
	s_nop 1
	v_cndmask_b32_e32 v183, v183, v181, vcc
	v_rsq_f32_e32 v183, v183
	s_nop 0
	v_mul_f32_e32 v181, 0x45800000, v183
	v_cndmask_b32_e32 v184, v183, v181, vcc
	v_mov_b32_e32 v185, v184
	v_pk_mul_f32 v[194:195], v[194:195], v[184:185]
	v_pk_mul_f32 v[196:197], v[196:197], v[184:185]
	v_pk_mul_f32 v[198:199], v[198:199], v[184:185]
	v_pk_mul_f32 v[200:201], v[200:201], v[184:185]
	v_pk_mul_f32 v[202:203], v[202:203], v[184:185]
	v_pk_mul_f32 v[204:205], v[204:205], v[184:185]
	v_pk_mul_f32 v[206:207], v[206:207], v[184:185]
	v_pk_mul_f32 v[208:209], v[208:209], v[184:185]
	v_pk_mul_f32 v[194:195], v[194:195], v[236:237]
	v_pk_mul_f32 v[196:197], v[196:197], v[238:239]
	v_pk_mul_f32 v[198:199], v[198:199], v[240:241]
	v_pk_mul_f32 v[200:201], v[200:201], v[242:243]
	v_pk_mul_f32 v[202:203], v[202:203], v[244:245]
	v_pk_mul_f32 v[204:205], v[204:205], v[246:247]
	v_pk_mul_f32 v[206:207], v[206:207], v[248:249]
	v_pk_mul_f32 v[208:209], v[208:209], v[250:251]
	v_add_u32_e32 v181, 0x0, v233
	global_store_dwordx4 v181, v[194:197], s[76:77]
	global_store_dwordx4 v181, v[198:201], s[76:77] offset:16
	global_store_dwordx4 v181, v[202:205], s[76:77] offset:2048
	global_store_dwordx4 v181, v[206:209], s[76:77] offset:2064
	s_nop 1
	s_waitcnt vmcnt(32)
	v_lshlrev_b32_e32 v194, 16, v16
	v_and_b32_e32 v195, 0xffff0000, v16
	v_lshlrev_b32_e32 v196, 16, v17
	v_and_b32_e32 v197, 0xffff0000, v17
	v_lshlrev_b32_e32 v198, 16, v18
	v_and_b32_e32 v199, 0xffff0000, v18
	v_lshlrev_b32_e32 v200, 16, v19
	v_and_b32_e32 v201, 0xffff0000, v19
	v_lshlrev_b32_e32 v202, 16, v20
	v_and_b32_e32 v203, 0xffff0000, v20
	v_lshlrev_b32_e32 v204, 16, v21
	v_and_b32_e32 v205, 0xffff0000, v21
	v_lshlrev_b32_e32 v206, 16, v22
	v_and_b32_e32 v207, 0xffff0000, v22
	v_lshlrev_b32_e32 v208, 16, v23
	v_and_b32_e32 v209, 0xffff0000, v23
	v_lshlrev_b32_e32 v216, 16, v24
	v_and_b32_e32 v217, 0xffff0000, v24
	v_lshlrev_b32_e32 v218, 16, v25
	v_and_b32_e32 v219, 0xffff0000, v25
	v_lshlrev_b32_e32 v220, 16, v26
	v_and_b32_e32 v221, 0xffff0000, v26
	v_lshlrev_b32_e32 v222, 16, v27
	v_and_b32_e32 v223, 0xffff0000, v27
	v_lshlrev_b32_e32 v224, 16, v28
	v_and_b32_e32 v225, 0xffff0000, v28
	v_lshlrev_b32_e32 v226, 16, v29
	v_and_b32_e32 v227, 0xffff0000, v29
	v_lshlrev_b32_e32 v228, 16, v30
	v_and_b32_e32 v229, 0xffff0000, v30
	v_lshlrev_b32_e32 v230, 16, v31
	v_and_b32_e32 v231, 0xffff0000, v31
	v_pk_mul_f32 v[252:253], v[216:217], v[216:217]
	v_pk_mul_f32 v[254:255], v[218:219], v[218:219]
	v_pk_fma_f32 v[252:253], v[220:221], v[220:221], v[252:253]
	v_pk_fma_f32 v[254:255], v[222:223], v[222:223], v[254:255]
	v_pk_fma_f32 v[252:253], v[224:225], v[224:225], v[252:253]
	v_pk_fma_f32 v[254:255], v[226:227], v[226:227], v[254:255]
	v_pk_fma_f32 v[252:253], v[228:229], v[228:229], v[252:253]
	v_pk_fma_f32 v[254:255], v[230:231], v[230:231], v[254:255]
	v_pk_add_f32 v[252:253], v[252:253], v[254:255]
	s_nop 0
	v_add_f32_e32 v183, v252, v253
	s_nop 1
	v_add_f32_dpp v183, v183, v183 quad_perm:[1,0,3,2] row_mask:0xf bank_mask:0xf bound_ctrl:1
	s_nop 1
	v_add_f32_dpp v183, v183, v183 quad_perm:[2,3,0,1] row_mask:0xf bank_mask:0xf bound_ctrl:1
	s_nop 1
	v_add_f32_dpp v183, v183, v183 row_half_mirror row_mask:0xf bank_mask:0xf bound_ctrl:1
	s_nop 1
	v_add_f32_dpp v183, v183, v183 row_mirror row_mask:0xf bank_mask:0xf bound_ctrl:1
	s_nop 1
	v_readlane_b32 s98, v183, 0
	v_readlane_b32 s99, v183, 16
	v_readlane_b32 s100, v183, 32
	v_readlane_b32 s101, v183, 48
	s_nop 1
	v_mov_b32_e32 v183, s98
	v_add_f32_e32 v183, s99, v183
	v_add_f32_e32 v183, s100, v183
	v_add_f32_e32 v183, s101, v183
	v_fmamk_f32 v183, v183, 0x3a800000, v182
	v_cmp_gt_f32_e32 vcc, 0x800000, v183
	v_mul_f32_e32 v181, 0x4b800000, v183
	s_nop 1
	v_cndmask_b32_e32 v183, v183, v181, vcc
	v_rsq_f32_e32 v183, v183
	s_nop 0
	v_mul_f32_e32 v181, 0x45800000, v183
	v_cndmask_b32_e32 v184, v183, v181, vcc
	v_mov_b32_e32 v185, v184
	v_pk_mul_f32 v[216:217], v[216:217], v[184:185]
	v_pk_mul_f32 v[218:219], v[218:219], v[184:185]
	v_pk_mul_f32 v[220:221], v[220:221], v[184:185]
	v_pk_mul_f32 v[222:223], v[222:223], v[184:185]
	v_pk_mul_f32 v[224:225], v[224:225], v[184:185]
	v_pk_mul_f32 v[226:227], v[226:227], v[184:185]
	v_pk_mul_f32 v[228:229], v[228:229], v[184:185]
	v_pk_mul_f32 v[230:231], v[230:231], v[184:185]
	v_pk_fma_f32 v[194:195], v[216:217], v[160:161], v[194:195]
	v_pk_fma_f32 v[196:197], v[218:219], v[162:163], v[196:197]
	v_pk_fma_f32 v[198:199], v[220:221], v[164:165], v[198:199]
	v_pk_fma_f32 v[200:201], v[222:223], v[166:167], v[200:201]
	v_pk_fma_f32 v[202:203], v[224:225], v[168:169], v[202:203]
	v_pk_fma_f32 v[204:205], v[226:227], v[170:171], v[204:205]
	v_pk_fma_f32 v[206:207], v[228:229], v[172:173], v[206:207]
	v_pk_fma_f32 v[208:209], v[230:231], v[174:175], v[208:209]
	v_pk_mul_f32 v[252:253], v[194:195], v[194:195]
	v_pk_mul_f32 v[254:255], v[196:197], v[196:197]
	v_pk_fma_f32 v[252:253], v[198:199], v[198:199], v[252:253]
	v_pk_fma_f32 v[254:255], v[200:201], v[200:201], v[254:255]
	v_pk_fma_f32 v[252:253], v[202:203], v[202:203], v[252:253]
	v_pk_fma_f32 v[254:255], v[204:205], v[204:205], v[254:255]
	v_pk_fma_f32 v[252:253], v[206:207], v[206:207], v[252:253]
	v_pk_fma_f32 v[254:255], v[208:209], v[208:209], v[254:255]
	v_pk_add_f32 v[252:253], v[252:253], v[254:255]
	s_nop 0
	v_add_f32_e32 v183, v252, v253
	s_nop 1
	v_add_f32_dpp v183, v183, v183 quad_perm:[1,0,3,2] row_mask:0xf bank_mask:0xf bound_ctrl:1
	s_nop 1
	v_add_f32_dpp v183, v183, v183 quad_perm:[2,3,0,1] row_mask:0xf bank_mask:0xf bound_ctrl:1
	s_nop 1
	v_add_f32_dpp v183, v183, v183 row_half_mirror row_mask:0xf bank_mask:0xf bound_ctrl:1
	s_nop 1
	v_add_f32_dpp v183, v183, v183 row_mirror row_mask:0xf bank_mask:0xf bound_ctrl:1
	s_nop 1
	v_readlane_b32 s98, v183, 0
	v_readlane_b32 s99, v183, 16
	v_readlane_b32 s100, v183, 32
	v_readlane_b32 s101, v183, 48
	s_nop 1
	v_mov_b32_e32 v183, s98
	v_add_f32_e32 v183, s99, v183
	v_add_f32_e32 v183, s100, v183
	v_add_f32_e32 v183, s101, v183
	v_fmamk_f32 v183, v183, 0x3a800000, v182
	v_cmp_gt_f32_e32 vcc, 0x800000, v183
	v_mul_f32_e32 v181, 0x4b800000, v183
	s_nop 1
	v_cndmask_b32_e32 v183, v183, v181, vcc
	v_rsq_f32_e32 v183, v183
	s_nop 0
	v_mul_f32_e32 v181, 0x45800000, v183
	v_cndmask_b32_e32 v184, v183, v181, vcc
	v_mov_b32_e32 v185, v184
	v_pk_mul_f32 v[194:195], v[194:195], v[184:185]
	v_pk_mul_f32 v[196:197], v[196:197], v[184:185]
	v_pk_mul_f32 v[198:199], v[198:199], v[184:185]
	v_pk_mul_f32 v[200:201], v[200:201], v[184:185]
	v_pk_mul_f32 v[202:203], v[202:203], v[184:185]
	v_pk_mul_f32 v[204:205], v[204:205], v[184:185]
	v_pk_mul_f32 v[206:207], v[206:207], v[184:185]
	v_pk_mul_f32 v[208:209], v[208:209], v[184:185]
	v_pk_mul_f32 v[194:195], v[194:195], v[236:237]
	v_pk_mul_f32 v[196:197], v[196:197], v[238:239]
	v_pk_mul_f32 v[198:199], v[198:199], v[240:241]
	v_pk_mul_f32 v[200:201], v[200:201], v[242:243]
	v_pk_mul_f32 v[202:203], v[202:203], v[244:245]
	v_pk_mul_f32 v[204:205], v[204:205], v[246:247]
	v_pk_mul_f32 v[206:207], v[206:207], v[248:249]
	v_pk_mul_f32 v[208:209], v[208:209], v[250:251]
	v_add_u32_e32 v181, 0x800000, v233
	global_store_dwordx4 v181, v[194:197], s[76:77]
	global_store_dwordx4 v181, v[198:201], s[76:77] offset:16
	global_store_dwordx4 v181, v[202:205], s[76:77] offset:2048
	global_store_dwordx4 v181, v[206:209], s[76:77] offset:2064
	s_nop 1
	s_waitcnt vmcnt(28)
	v_lshlrev_b32_e32 v194, 16, v32
	v_and_b32_e32 v195, 0xffff0000, v32
	v_lshlrev_b32_e32 v196, 16, v33
	v_and_b32_e32 v197, 0xffff0000, v33
	v_lshlrev_b32_e32 v198, 16, v34
	v_and_b32_e32 v199, 0xffff0000, v34
	v_lshlrev_b32_e32 v200, 16, v35
	v_and_b32_e32 v201, 0xffff0000, v35
	v_lshlrev_b32_e32 v202, 16, v36
	v_and_b32_e32 v203, 0xffff0000, v36
	v_lshlrev_b32_e32 v204, 16, v37
	v_and_b32_e32 v205, 0xffff0000, v37
	v_lshlrev_b32_e32 v206, 16, v38
	v_and_b32_e32 v207, 0xffff0000, v38
	v_lshlrev_b32_e32 v208, 16, v39
	v_and_b32_e32 v209, 0xffff0000, v39
	v_lshlrev_b32_e32 v216, 16, v40
	v_and_b32_e32 v217, 0xffff0000, v40
	v_lshlrev_b32_e32 v218, 16, v41
	v_and_b32_e32 v219, 0xffff0000, v41
	v_lshlrev_b32_e32 v220, 16, v42
	v_and_b32_e32 v221, 0xffff0000, v42
	v_lshlrev_b32_e32 v222, 16, v43
	v_and_b32_e32 v223, 0xffff0000, v43
	v_lshlrev_b32_e32 v224, 16, v44
	v_and_b32_e32 v225, 0xffff0000, v44
	v_lshlrev_b32_e32 v226, 16, v45
	v_and_b32_e32 v227, 0xffff0000, v45
	v_lshlrev_b32_e32 v228, 16, v46
	v_and_b32_e32 v229, 0xffff0000, v46
	v_lshlrev_b32_e32 v230, 16, v47
	v_and_b32_e32 v231, 0xffff0000, v47
	v_pk_mul_f32 v[252:253], v[216:217], v[216:217]
	v_pk_mul_f32 v[254:255], v[218:219], v[218:219]
	v_pk_fma_f32 v[252:253], v[220:221], v[220:221], v[252:253]
	v_pk_fma_f32 v[254:255], v[222:223], v[222:223], v[254:255]
	v_pk_fma_f32 v[252:253], v[224:225], v[224:225], v[252:253]
	v_pk_fma_f32 v[254:255], v[226:227], v[226:227], v[254:255]
	v_pk_fma_f32 v[252:253], v[228:229], v[228:229], v[252:253]
	v_pk_fma_f32 v[254:255], v[230:231], v[230:231], v[254:255]
	v_pk_add_f32 v[252:253], v[252:253], v[254:255]
	s_nop 0
	v_add_f32_e32 v183, v252, v253
	s_nop 1
	v_add_f32_dpp v183, v183, v183 quad_perm:[1,0,3,2] row_mask:0xf bank_mask:0xf bound_ctrl:1
	s_nop 1
	v_add_f32_dpp v183, v183, v183 quad_perm:[2,3,0,1] row_mask:0xf bank_mask:0xf bound_ctrl:1
	s_nop 1
	v_add_f32_dpp v183, v183, v183 row_half_mirror row_mask:0xf bank_mask:0xf bound_ctrl:1
	s_nop 1
	v_add_f32_dpp v183, v183, v183 row_mirror row_mask:0xf bank_mask:0xf bound_ctrl:1
	s_nop 1
	v_readlane_b32 s98, v183, 0
	v_readlane_b32 s99, v183, 16
	v_readlane_b32 s100, v183, 32
	v_readlane_b32 s101, v183, 48
	s_nop 1
	v_mov_b32_e32 v183, s98
	v_add_f32_e32 v183, s99, v183
	v_add_f32_e32 v183, s100, v183
	v_add_f32_e32 v183, s101, v183
	v_fmamk_f32 v183, v183, 0x3a800000, v182
	v_cmp_gt_f32_e32 vcc, 0x800000, v183
	v_mul_f32_e32 v181, 0x4b800000, v183
	s_nop 1
	v_cndmask_b32_e32 v183, v183, v181, vcc
	v_rsq_f32_e32 v183, v183
	s_nop 0
	v_mul_f32_e32 v181, 0x45800000, v183
	v_cndmask_b32_e32 v184, v183, v181, vcc
	v_mov_b32_e32 v185, v184
	v_pk_mul_f32 v[216:217], v[216:217], v[184:185]
	v_pk_mul_f32 v[218:219], v[218:219], v[184:185]
	v_pk_mul_f32 v[220:221], v[220:221], v[184:185]
	v_pk_mul_f32 v[222:223], v[222:223], v[184:185]
	v_pk_mul_f32 v[224:225], v[224:225], v[184:185]
	v_pk_mul_f32 v[226:227], v[226:227], v[184:185]
	v_pk_mul_f32 v[228:229], v[228:229], v[184:185]
	v_pk_mul_f32 v[230:231], v[230:231], v[184:185]
	v_pk_fma_f32 v[194:195], v[216:217], v[160:161], v[194:195]
	v_pk_fma_f32 v[196:197], v[218:219], v[162:163], v[196:197]
	v_pk_fma_f32 v[198:199], v[220:221], v[164:165], v[198:199]
	v_pk_fma_f32 v[200:201], v[222:223], v[166:167], v[200:201]
	v_pk_fma_f32 v[202:203], v[224:225], v[168:169], v[202:203]
	v_pk_fma_f32 v[204:205], v[226:227], v[170:171], v[204:205]
	v_pk_fma_f32 v[206:207], v[228:229], v[172:173], v[206:207]
	v_pk_fma_f32 v[208:209], v[230:231], v[174:175], v[208:209]
	v_pk_mul_f32 v[252:253], v[194:195], v[194:195]
	v_pk_mul_f32 v[254:255], v[196:197], v[196:197]
	v_pk_fma_f32 v[252:253], v[198:199], v[198:199], v[252:253]
	v_pk_fma_f32 v[254:255], v[200:201], v[200:201], v[254:255]
	v_pk_fma_f32 v[252:253], v[202:203], v[202:203], v[252:253]
	v_pk_fma_f32 v[254:255], v[204:205], v[204:205], v[254:255]
	v_pk_fma_f32 v[252:253], v[206:207], v[206:207], v[252:253]
	v_pk_fma_f32 v[254:255], v[208:209], v[208:209], v[254:255]
	v_pk_add_f32 v[252:253], v[252:253], v[254:255]
	s_nop 0
	v_add_f32_e32 v183, v252, v253
	s_nop 1
	v_add_f32_dpp v183, v183, v183 quad_perm:[1,0,3,2] row_mask:0xf bank_mask:0xf bound_ctrl:1
	s_nop 1
	v_add_f32_dpp v183, v183, v183 quad_perm:[2,3,0,1] row_mask:0xf bank_mask:0xf bound_ctrl:1
	s_nop 1
	v_add_f32_dpp v183, v183, v183 row_half_mirror row_mask:0xf bank_mask:0xf bound_ctrl:1
	s_nop 1
	v_add_f32_dpp v183, v183, v183 row_mirror row_mask:0xf bank_mask:0xf bound_ctrl:1
	s_nop 1
	v_readlane_b32 s98, v183, 0
	v_readlane_b32 s99, v183, 16
	v_readlane_b32 s100, v183, 32
	v_readlane_b32 s101, v183, 48
	s_nop 1
	v_mov_b32_e32 v183, s98
	v_add_f32_e32 v183, s99, v183
	v_add_f32_e32 v183, s100, v183
	v_add_f32_e32 v183, s101, v183
	v_fmamk_f32 v183, v183, 0x3a800000, v182
	v_cmp_gt_f32_e32 vcc, 0x800000, v183
	v_mul_f32_e32 v181, 0x4b800000, v183
	s_nop 1
	v_cndmask_b32_e32 v183, v183, v181, vcc
	v_rsq_f32_e32 v183, v183
	s_nop 0
	v_mul_f32_e32 v181, 0x45800000, v183
	v_cndmask_b32_e32 v184, v183, v181, vcc
	v_mov_b32_e32 v185, v184
	v_pk_mul_f32 v[194:195], v[194:195], v[184:185]
	v_pk_mul_f32 v[196:197], v[196:197], v[184:185]
	v_pk_mul_f32 v[198:199], v[198:199], v[184:185]
	v_pk_mul_f32 v[200:201], v[200:201], v[184:185]
	v_pk_mul_f32 v[202:203], v[202:203], v[184:185]
	v_pk_mul_f32 v[204:205], v[204:205], v[184:185]
	v_pk_mul_f32 v[206:207], v[206:207], v[184:185]
	v_pk_mul_f32 v[208:209], v[208:209], v[184:185]
	v_pk_mul_f32 v[194:195], v[194:195], v[236:237]
	v_pk_mul_f32 v[196:197], v[196:197], v[238:239]
	v_pk_mul_f32 v[198:199], v[198:199], v[240:241]
	v_pk_mul_f32 v[200:201], v[200:201], v[242:243]
	v_pk_mul_f32 v[202:203], v[202:203], v[244:245]
	v_pk_mul_f32 v[204:205], v[204:205], v[246:247]
	v_pk_mul_f32 v[206:207], v[206:207], v[248:249]
	v_pk_mul_f32 v[208:209], v[208:209], v[250:251]
	v_add_u32_e32 v181, 0x1000000, v233
	global_store_dwordx4 v181, v[194:197], s[76:77]
	global_store_dwordx4 v181, v[198:201], s[76:77] offset:16
	global_store_dwordx4 v181, v[202:205], s[76:77] offset:2048
	global_store_dwordx4 v181, v[206:209], s[76:77] offset:2064
	s_nop 1
	s_waitcnt vmcnt(24)
	v_lshlrev_b32_e32 v194, 16, v48
	v_and_b32_e32 v195, 0xffff0000, v48
	v_lshlrev_b32_e32 v196, 16, v49
	v_and_b32_e32 v197, 0xffff0000, v49
	v_lshlrev_b32_e32 v198, 16, v50
	v_and_b32_e32 v199, 0xffff0000, v50
	v_lshlrev_b32_e32 v200, 16, v51
	v_and_b32_e32 v201, 0xffff0000, v51
	v_lshlrev_b32_e32 v202, 16, v52
	v_and_b32_e32 v203, 0xffff0000, v52
	v_lshlrev_b32_e32 v204, 16, v53
	v_and_b32_e32 v205, 0xffff0000, v53
	v_lshlrev_b32_e32 v206, 16, v54
	v_and_b32_e32 v207, 0xffff0000, v54
	v_lshlrev_b32_e32 v208, 16, v55
	v_and_b32_e32 v209, 0xffff0000, v55
	v_lshlrev_b32_e32 v216, 16, v56
	v_and_b32_e32 v217, 0xffff0000, v56
	v_lshlrev_b32_e32 v218, 16, v57
	v_and_b32_e32 v219, 0xffff0000, v57
	v_lshlrev_b32_e32 v220, 16, v58
	v_and_b32_e32 v221, 0xffff0000, v58
	v_lshlrev_b32_e32 v222, 16, v59
	v_and_b32_e32 v223, 0xffff0000, v59
	v_lshlrev_b32_e32 v224, 16, v60
	v_and_b32_e32 v225, 0xffff0000, v60
	v_lshlrev_b32_e32 v226, 16, v61
	v_and_b32_e32 v227, 0xffff0000, v61
	v_lshlrev_b32_e32 v228, 16, v62
	v_and_b32_e32 v229, 0xffff0000, v62
	v_lshlrev_b32_e32 v230, 16, v63
	v_and_b32_e32 v231, 0xffff0000, v63
	v_pk_mul_f32 v[252:253], v[216:217], v[216:217]
	v_pk_mul_f32 v[254:255], v[218:219], v[218:219]
	v_pk_fma_f32 v[252:253], v[220:221], v[220:221], v[252:253]
	v_pk_fma_f32 v[254:255], v[222:223], v[222:223], v[254:255]
	v_pk_fma_f32 v[252:253], v[224:225], v[224:225], v[252:253]
	v_pk_fma_f32 v[254:255], v[226:227], v[226:227], v[254:255]
	v_pk_fma_f32 v[252:253], v[228:229], v[228:229], v[252:253]
	v_pk_fma_f32 v[254:255], v[230:231], v[230:231], v[254:255]
	v_pk_add_f32 v[252:253], v[252:253], v[254:255]
	s_nop 0
	v_add_f32_e32 v183, v252, v253
	s_nop 1
	v_add_f32_dpp v183, v183, v183 quad_perm:[1,0,3,2] row_mask:0xf bank_mask:0xf bound_ctrl:1
	s_nop 1
	v_add_f32_dpp v183, v183, v183 quad_perm:[2,3,0,1] row_mask:0xf bank_mask:0xf bound_ctrl:1
	s_nop 1
	v_add_f32_dpp v183, v183, v183 row_half_mirror row_mask:0xf bank_mask:0xf bound_ctrl:1
	s_nop 1
	v_add_f32_dpp v183, v183, v183 row_mirror row_mask:0xf bank_mask:0xf bound_ctrl:1
	s_nop 1
	v_readlane_b32 s98, v183, 0
	v_readlane_b32 s99, v183, 16
	v_readlane_b32 s100, v183, 32
	v_readlane_b32 s101, v183, 48
	s_nop 1
	v_mov_b32_e32 v183, s98
	v_add_f32_e32 v183, s99, v183
	v_add_f32_e32 v183, s100, v183
	v_add_f32_e32 v183, s101, v183
	v_fmamk_f32 v183, v183, 0x3a800000, v182
	v_cmp_gt_f32_e32 vcc, 0x800000, v183
	v_mul_f32_e32 v181, 0x4b800000, v183
	s_nop 1
	v_cndmask_b32_e32 v183, v183, v181, vcc
	v_rsq_f32_e32 v183, v183
	s_nop 0
	v_mul_f32_e32 v181, 0x45800000, v183
	v_cndmask_b32_e32 v184, v183, v181, vcc
	v_mov_b32_e32 v185, v184
	v_pk_mul_f32 v[216:217], v[216:217], v[184:185]
	v_pk_mul_f32 v[218:219], v[218:219], v[184:185]
	v_pk_mul_f32 v[220:221], v[220:221], v[184:185]
	v_pk_mul_f32 v[222:223], v[222:223], v[184:185]
	v_pk_mul_f32 v[224:225], v[224:225], v[184:185]
	v_pk_mul_f32 v[226:227], v[226:227], v[184:185]
	v_pk_mul_f32 v[228:229], v[228:229], v[184:185]
	v_pk_mul_f32 v[230:231], v[230:231], v[184:185]
	v_pk_fma_f32 v[194:195], v[216:217], v[160:161], v[194:195]
	v_pk_fma_f32 v[196:197], v[218:219], v[162:163], v[196:197]
	v_pk_fma_f32 v[198:199], v[220:221], v[164:165], v[198:199]
	v_pk_fma_f32 v[200:201], v[222:223], v[166:167], v[200:201]
	v_pk_fma_f32 v[202:203], v[224:225], v[168:169], v[202:203]
	v_pk_fma_f32 v[204:205], v[226:227], v[170:171], v[204:205]
	v_pk_fma_f32 v[206:207], v[228:229], v[172:173], v[206:207]
	v_pk_fma_f32 v[208:209], v[230:231], v[174:175], v[208:209]
	v_pk_mul_f32 v[252:253], v[194:195], v[194:195]
	v_pk_mul_f32 v[254:255], v[196:197], v[196:197]
	v_pk_fma_f32 v[252:253], v[198:199], v[198:199], v[252:253]
	v_pk_fma_f32 v[254:255], v[200:201], v[200:201], v[254:255]
	v_pk_fma_f32 v[252:253], v[202:203], v[202:203], v[252:253]
	v_pk_fma_f32 v[254:255], v[204:205], v[204:205], v[254:255]
	v_pk_fma_f32 v[252:253], v[206:207], v[206:207], v[252:253]
	v_pk_fma_f32 v[254:255], v[208:209], v[208:209], v[254:255]
	v_pk_add_f32 v[252:253], v[252:253], v[254:255]
	s_nop 0
	v_add_f32_e32 v183, v252, v253
	s_nop 1
	v_add_f32_dpp v183, v183, v183 quad_perm:[1,0,3,2] row_mask:0xf bank_mask:0xf bound_ctrl:1
	s_nop 1
	v_add_f32_dpp v183, v183, v183 quad_perm:[2,3,0,1] row_mask:0xf bank_mask:0xf bound_ctrl:1
	s_nop 1
	v_add_f32_dpp v183, v183, v183 row_half_mirror row_mask:0xf bank_mask:0xf bound_ctrl:1
	s_nop 1
	v_add_f32_dpp v183, v183, v183 row_mirror row_mask:0xf bank_mask:0xf bound_ctrl:1
	s_nop 1
	v_readlane_b32 s98, v183, 0
	v_readlane_b32 s99, v183, 16
	v_readlane_b32 s100, v183, 32
	v_readlane_b32 s101, v183, 48
	s_nop 1
	v_mov_b32_e32 v183, s98
	v_add_f32_e32 v183, s99, v183
	v_add_f32_e32 v183, s100, v183
	v_add_f32_e32 v183, s101, v183
	v_fmamk_f32 v183, v183, 0x3a800000, v182
	v_cmp_gt_f32_e32 vcc, 0x800000, v183
	v_mul_f32_e32 v181, 0x4b800000, v183
	s_nop 1
	v_cndmask_b32_e32 v183, v183, v181, vcc
	v_rsq_f32_e32 v183, v183
	s_nop 0
	v_mul_f32_e32 v181, 0x45800000, v183
	v_cndmask_b32_e32 v184, v183, v181, vcc
	v_mov_b32_e32 v185, v184
	v_pk_mul_f32 v[194:195], v[194:195], v[184:185]
	v_pk_mul_f32 v[196:197], v[196:197], v[184:185]
	v_pk_mul_f32 v[198:199], v[198:199], v[184:185]
	v_pk_mul_f32 v[200:201], v[200:201], v[184:185]
	v_pk_mul_f32 v[202:203], v[202:203], v[184:185]
	v_pk_mul_f32 v[204:205], v[204:205], v[184:185]
	v_pk_mul_f32 v[206:207], v[206:207], v[184:185]
	v_pk_mul_f32 v[208:209], v[208:209], v[184:185]
	v_pk_mul_f32 v[194:195], v[194:195], v[236:237]
	v_pk_mul_f32 v[196:197], v[196:197], v[238:239]
	v_pk_mul_f32 v[198:199], v[198:199], v[240:241]
	v_pk_mul_f32 v[200:201], v[200:201], v[242:243]
	v_pk_mul_f32 v[202:203], v[202:203], v[244:245]
	v_pk_mul_f32 v[204:205], v[204:205], v[246:247]
	v_pk_mul_f32 v[206:207], v[206:207], v[248:249]
	v_pk_mul_f32 v[208:209], v[208:209], v[250:251]
	v_add_u32_e32 v181, 0x1800000, v233
	global_store_dwordx4 v181, v[194:197], s[76:77]
	global_store_dwordx4 v181, v[198:201], s[76:77] offset:16
	global_store_dwordx4 v181, v[202:205], s[76:77] offset:2048
	global_store_dwordx4 v181, v[206:209], s[76:77] offset:2064
	s_nop 1
	s_waitcnt vmcnt(20)
	v_lshlrev_b32_e32 v194, 16, v64
	v_and_b32_e32 v195, 0xffff0000, v64
	v_lshlrev_b32_e32 v196, 16, v65
	v_and_b32_e32 v197, 0xffff0000, v65
	v_lshlrev_b32_e32 v198, 16, v66
	v_and_b32_e32 v199, 0xffff0000, v66
	v_lshlrev_b32_e32 v200, 16, v67
	v_and_b32_e32 v201, 0xffff0000, v67
	v_lshlrev_b32_e32 v202, 16, v68
	v_and_b32_e32 v203, 0xffff0000, v68
	v_lshlrev_b32_e32 v204, 16, v69
	v_and_b32_e32 v205, 0xffff0000, v69
	v_lshlrev_b32_e32 v206, 16, v70
	v_and_b32_e32 v207, 0xffff0000, v70
	v_lshlrev_b32_e32 v208, 16, v71
	v_and_b32_e32 v209, 0xffff0000, v71
	v_lshlrev_b32_e32 v216, 16, v72
	v_and_b32_e32 v217, 0xffff0000, v72
	v_lshlrev_b32_e32 v218, 16, v73
	v_and_b32_e32 v219, 0xffff0000, v73
	v_lshlrev_b32_e32 v220, 16, v74
	v_and_b32_e32 v221, 0xffff0000, v74
	v_lshlrev_b32_e32 v222, 16, v75
	v_and_b32_e32 v223, 0xffff0000, v75
	v_lshlrev_b32_e32 v224, 16, v76
	v_and_b32_e32 v225, 0xffff0000, v76
	v_lshlrev_b32_e32 v226, 16, v77
	v_and_b32_e32 v227, 0xffff0000, v77
	v_lshlrev_b32_e32 v228, 16, v78
	v_and_b32_e32 v229, 0xffff0000, v78
	v_lshlrev_b32_e32 v230, 16, v79
	v_and_b32_e32 v231, 0xffff0000, v79
	v_pk_mul_f32 v[252:253], v[216:217], v[216:217]
	v_pk_mul_f32 v[254:255], v[218:219], v[218:219]
	v_pk_fma_f32 v[252:253], v[220:221], v[220:221], v[252:253]
	v_pk_fma_f32 v[254:255], v[222:223], v[222:223], v[254:255]
	v_pk_fma_f32 v[252:253], v[224:225], v[224:225], v[252:253]
	v_pk_fma_f32 v[254:255], v[226:227], v[226:227], v[254:255]
	v_pk_fma_f32 v[252:253], v[228:229], v[228:229], v[252:253]
	v_pk_fma_f32 v[254:255], v[230:231], v[230:231], v[254:255]
	v_pk_add_f32 v[252:253], v[252:253], v[254:255]
	s_nop 0
	v_add_f32_e32 v183, v252, v253
	s_nop 1
	v_add_f32_dpp v183, v183, v183 quad_perm:[1,0,3,2] row_mask:0xf bank_mask:0xf bound_ctrl:1
	s_nop 1
	v_add_f32_dpp v183, v183, v183 quad_perm:[2,3,0,1] row_mask:0xf bank_mask:0xf bound_ctrl:1
	s_nop 1
	v_add_f32_dpp v183, v183, v183 row_half_mirror row_mask:0xf bank_mask:0xf bound_ctrl:1
	s_nop 1
	v_add_f32_dpp v183, v183, v183 row_mirror row_mask:0xf bank_mask:0xf bound_ctrl:1
	s_nop 1
	v_readlane_b32 s98, v183, 0
	v_readlane_b32 s99, v183, 16
	v_readlane_b32 s100, v183, 32
	v_readlane_b32 s101, v183, 48
	s_nop 1
	v_mov_b32_e32 v183, s98
	v_add_f32_e32 v183, s99, v183
	v_add_f32_e32 v183, s100, v183
	v_add_f32_e32 v183, s101, v183
	v_fmamk_f32 v183, v183, 0x3a800000, v182
	v_cmp_gt_f32_e32 vcc, 0x800000, v183
	v_mul_f32_e32 v181, 0x4b800000, v183
	s_nop 1
	v_cndmask_b32_e32 v183, v183, v181, vcc
	v_rsq_f32_e32 v183, v183
	s_nop 0
	v_mul_f32_e32 v181, 0x45800000, v183
	v_cndmask_b32_e32 v184, v183, v181, vcc
	v_mov_b32_e32 v185, v184
	v_pk_mul_f32 v[216:217], v[216:217], v[184:185]
	v_pk_mul_f32 v[218:219], v[218:219], v[184:185]
	v_pk_mul_f32 v[220:221], v[220:221], v[184:185]
	v_pk_mul_f32 v[222:223], v[222:223], v[184:185]
	v_pk_mul_f32 v[224:225], v[224:225], v[184:185]
	v_pk_mul_f32 v[226:227], v[226:227], v[184:185]
	v_pk_mul_f32 v[228:229], v[228:229], v[184:185]
	v_pk_mul_f32 v[230:231], v[230:231], v[184:185]
	v_pk_fma_f32 v[194:195], v[216:217], v[160:161], v[194:195]
	v_pk_fma_f32 v[196:197], v[218:219], v[162:163], v[196:197]
	v_pk_fma_f32 v[198:199], v[220:221], v[164:165], v[198:199]
	v_pk_fma_f32 v[200:201], v[222:223], v[166:167], v[200:201]
	v_pk_fma_f32 v[202:203], v[224:225], v[168:169], v[202:203]
	v_pk_fma_f32 v[204:205], v[226:227], v[170:171], v[204:205]
	v_pk_fma_f32 v[206:207], v[228:229], v[172:173], v[206:207]
	v_pk_fma_f32 v[208:209], v[230:231], v[174:175], v[208:209]
	v_pk_mul_f32 v[252:253], v[194:195], v[194:195]
	v_pk_mul_f32 v[254:255], v[196:197], v[196:197]
	v_pk_fma_f32 v[252:253], v[198:199], v[198:199], v[252:253]
	v_pk_fma_f32 v[254:255], v[200:201], v[200:201], v[254:255]
	v_pk_fma_f32 v[252:253], v[202:203], v[202:203], v[252:253]
	v_pk_fma_f32 v[254:255], v[204:205], v[204:205], v[254:255]
	v_pk_fma_f32 v[252:253], v[206:207], v[206:207], v[252:253]
	v_pk_fma_f32 v[254:255], v[208:209], v[208:209], v[254:255]
	v_pk_add_f32 v[252:253], v[252:253], v[254:255]
	s_nop 0
	v_add_f32_e32 v183, v252, v253
	s_nop 1
	v_add_f32_dpp v183, v183, v183 quad_perm:[1,0,3,2] row_mask:0xf bank_mask:0xf bound_ctrl:1
	s_nop 1
	v_add_f32_dpp v183, v183, v183 quad_perm:[2,3,0,1] row_mask:0xf bank_mask:0xf bound_ctrl:1
	s_nop 1
	v_add_f32_dpp v183, v183, v183 row_half_mirror row_mask:0xf bank_mask:0xf bound_ctrl:1
	s_nop 1
	v_add_f32_dpp v183, v183, v183 row_mirror row_mask:0xf bank_mask:0xf bound_ctrl:1
	s_nop 1
	v_readlane_b32 s98, v183, 0
	v_readlane_b32 s99, v183, 16
	v_readlane_b32 s100, v183, 32
	v_readlane_b32 s101, v183, 48
	s_nop 1
	v_mov_b32_e32 v183, s98
	v_add_f32_e32 v183, s99, v183
	v_add_f32_e32 v183, s100, v183
	v_add_f32_e32 v183, s101, v183
	v_fmamk_f32 v183, v183, 0x3a800000, v182
	v_cmp_gt_f32_e32 vcc, 0x800000, v183
	v_mul_f32_e32 v181, 0x4b800000, v183
	s_nop 1
	v_cndmask_b32_e32 v183, v183, v181, vcc
	v_rsq_f32_e32 v183, v183
	s_nop 0
	v_mul_f32_e32 v181, 0x45800000, v183
	v_cndmask_b32_e32 v184, v183, v181, vcc
	v_mov_b32_e32 v185, v184
	v_pk_mul_f32 v[194:195], v[194:195], v[184:185]
	v_pk_mul_f32 v[196:197], v[196:197], v[184:185]
	v_pk_mul_f32 v[198:199], v[198:199], v[184:185]
	v_pk_mul_f32 v[200:201], v[200:201], v[184:185]
	v_pk_mul_f32 v[202:203], v[202:203], v[184:185]
	v_pk_mul_f32 v[204:205], v[204:205], v[184:185]
	v_pk_mul_f32 v[206:207], v[206:207], v[184:185]
	v_pk_mul_f32 v[208:209], v[208:209], v[184:185]
	v_pk_mul_f32 v[194:195], v[194:195], v[236:237]
	v_pk_mul_f32 v[196:197], v[196:197], v[238:239]
	v_pk_mul_f32 v[198:199], v[198:199], v[240:241]
	v_pk_mul_f32 v[200:201], v[200:201], v[242:243]
	v_pk_mul_f32 v[202:203], v[202:203], v[244:245]
	v_pk_mul_f32 v[204:205], v[204:205], v[246:247]
	v_pk_mul_f32 v[206:207], v[206:207], v[248:249]
	v_pk_mul_f32 v[208:209], v[208:209], v[250:251]
	v_add_u32_e32 v181, 0x2000000, v233
	global_store_dwordx4 v181, v[194:197], s[76:77]
	global_store_dwordx4 v181, v[198:201], s[76:77] offset:16
	global_store_dwordx4 v181, v[202:205], s[76:77] offset:2048
	global_store_dwordx4 v181, v[206:209], s[76:77] offset:2064
	s_nop 1
	s_waitcnt vmcnt(16)
	v_lshlrev_b32_e32 v194, 16, v80
	v_and_b32_e32 v195, 0xffff0000, v80
	v_lshlrev_b32_e32 v196, 16, v81
	v_and_b32_e32 v197, 0xffff0000, v81
	v_lshlrev_b32_e32 v198, 16, v82
	v_and_b32_e32 v199, 0xffff0000, v82
	v_lshlrev_b32_e32 v200, 16, v83
	v_and_b32_e32 v201, 0xffff0000, v83
	v_lshlrev_b32_e32 v202, 16, v84
	v_and_b32_e32 v203, 0xffff0000, v84
	v_lshlrev_b32_e32 v204, 16, v85
	v_and_b32_e32 v205, 0xffff0000, v85
	v_lshlrev_b32_e32 v206, 16, v86
	v_and_b32_e32 v207, 0xffff0000, v86
	v_lshlrev_b32_e32 v208, 16, v87
	v_and_b32_e32 v209, 0xffff0000, v87
	v_lshlrev_b32_e32 v216, 16, v88
	v_and_b32_e32 v217, 0xffff0000, v88
	v_lshlrev_b32_e32 v218, 16, v89
	v_and_b32_e32 v219, 0xffff0000, v89
	v_lshlrev_b32_e32 v220, 16, v90
	v_and_b32_e32 v221, 0xffff0000, v90
	v_lshlrev_b32_e32 v222, 16, v91
	v_and_b32_e32 v223, 0xffff0000, v91
	v_lshlrev_b32_e32 v224, 16, v92
	v_and_b32_e32 v225, 0xffff0000, v92
	v_lshlrev_b32_e32 v226, 16, v93
	v_and_b32_e32 v227, 0xffff0000, v93
	v_lshlrev_b32_e32 v228, 16, v94
	v_and_b32_e32 v229, 0xffff0000, v94
	v_lshlrev_b32_e32 v230, 16, v95
	v_and_b32_e32 v231, 0xffff0000, v95
	v_pk_mul_f32 v[252:253], v[216:217], v[216:217]
	v_pk_mul_f32 v[254:255], v[218:219], v[218:219]
	v_pk_fma_f32 v[252:253], v[220:221], v[220:221], v[252:253]
	v_pk_fma_f32 v[254:255], v[222:223], v[222:223], v[254:255]
	v_pk_fma_f32 v[252:253], v[224:225], v[224:225], v[252:253]
	v_pk_fma_f32 v[254:255], v[226:227], v[226:227], v[254:255]
	v_pk_fma_f32 v[252:253], v[228:229], v[228:229], v[252:253]
	v_pk_fma_f32 v[254:255], v[230:231], v[230:231], v[254:255]
	v_pk_add_f32 v[252:253], v[252:253], v[254:255]
	s_nop 0
	v_add_f32_e32 v183, v252, v253
	s_nop 1
	v_add_f32_dpp v183, v183, v183 quad_perm:[1,0,3,2] row_mask:0xf bank_mask:0xf bound_ctrl:1
	s_nop 1
	v_add_f32_dpp v183, v183, v183 quad_perm:[2,3,0,1] row_mask:0xf bank_mask:0xf bound_ctrl:1
	s_nop 1
	v_add_f32_dpp v183, v183, v183 row_half_mirror row_mask:0xf bank_mask:0xf bound_ctrl:1
	s_nop 1
	v_add_f32_dpp v183, v183, v183 row_mirror row_mask:0xf bank_mask:0xf bound_ctrl:1
	s_nop 1
	v_readlane_b32 s98, v183, 0
	v_readlane_b32 s99, v183, 16
	v_readlane_b32 s100, v183, 32
	v_readlane_b32 s101, v183, 48
	s_nop 1
	v_mov_b32_e32 v183, s98
	v_add_f32_e32 v183, s99, v183
	v_add_f32_e32 v183, s100, v183
	v_add_f32_e32 v183, s101, v183
	v_fmamk_f32 v183, v183, 0x3a800000, v182
	v_cmp_gt_f32_e32 vcc, 0x800000, v183
	v_mul_f32_e32 v181, 0x4b800000, v183
	s_nop 1
	v_cndmask_b32_e32 v183, v183, v181, vcc
	v_rsq_f32_e32 v183, v183
	s_nop 0
	v_mul_f32_e32 v181, 0x45800000, v183
	v_cndmask_b32_e32 v184, v183, v181, vcc
	v_mov_b32_e32 v185, v184
	v_pk_mul_f32 v[216:217], v[216:217], v[184:185]
	v_pk_mul_f32 v[218:219], v[218:219], v[184:185]
	v_pk_mul_f32 v[220:221], v[220:221], v[184:185]
	v_pk_mul_f32 v[222:223], v[222:223], v[184:185]
	v_pk_mul_f32 v[224:225], v[224:225], v[184:185]
	v_pk_mul_f32 v[226:227], v[226:227], v[184:185]
	v_pk_mul_f32 v[228:229], v[228:229], v[184:185]
	v_pk_mul_f32 v[230:231], v[230:231], v[184:185]
	v_pk_fma_f32 v[194:195], v[216:217], v[160:161], v[194:195]
	v_pk_fma_f32 v[196:197], v[218:219], v[162:163], v[196:197]
	v_pk_fma_f32 v[198:199], v[220:221], v[164:165], v[198:199]
	v_pk_fma_f32 v[200:201], v[222:223], v[166:167], v[200:201]
	v_pk_fma_f32 v[202:203], v[224:225], v[168:169], v[202:203]
	v_pk_fma_f32 v[204:205], v[226:227], v[170:171], v[204:205]
	v_pk_fma_f32 v[206:207], v[228:229], v[172:173], v[206:207]
	v_pk_fma_f32 v[208:209], v[230:231], v[174:175], v[208:209]
	v_pk_mul_f32 v[252:253], v[194:195], v[194:195]
	v_pk_mul_f32 v[254:255], v[196:197], v[196:197]
	v_pk_fma_f32 v[252:253], v[198:199], v[198:199], v[252:253]
	v_pk_fma_f32 v[254:255], v[200:201], v[200:201], v[254:255]
	v_pk_fma_f32 v[252:253], v[202:203], v[202:203], v[252:253]
	v_pk_fma_f32 v[254:255], v[204:205], v[204:205], v[254:255]
	v_pk_fma_f32 v[252:253], v[206:207], v[206:207], v[252:253]
	v_pk_fma_f32 v[254:255], v[208:209], v[208:209], v[254:255]
	v_pk_add_f32 v[252:253], v[252:253], v[254:255]
	s_nop 0
	v_add_f32_e32 v183, v252, v253
	s_nop 1
	v_add_f32_dpp v183, v183, v183 quad_perm:[1,0,3,2] row_mask:0xf bank_mask:0xf bound_ctrl:1
	s_nop 1
	v_add_f32_dpp v183, v183, v183 quad_perm:[2,3,0,1] row_mask:0xf bank_mask:0xf bound_ctrl:1
	s_nop 1
	v_add_f32_dpp v183, v183, v183 row_half_mirror row_mask:0xf bank_mask:0xf bound_ctrl:1
	s_nop 1
	v_add_f32_dpp v183, v183, v183 row_mirror row_mask:0xf bank_mask:0xf bound_ctrl:1
	s_nop 1
	v_readlane_b32 s98, v183, 0
	v_readlane_b32 s99, v183, 16
	v_readlane_b32 s100, v183, 32
	v_readlane_b32 s101, v183, 48
	s_nop 1
	v_mov_b32_e32 v183, s98
	v_add_f32_e32 v183, s99, v183
	v_add_f32_e32 v183, s100, v183
	v_add_f32_e32 v183, s101, v183
	v_fmamk_f32 v183, v183, 0x3a800000, v182
	v_cmp_gt_f32_e32 vcc, 0x800000, v183
	v_mul_f32_e32 v181, 0x4b800000, v183
	s_nop 1
	v_cndmask_b32_e32 v183, v183, v181, vcc
	v_rsq_f32_e32 v183, v183
	s_nop 0
	v_mul_f32_e32 v181, 0x45800000, v183
	v_cndmask_b32_e32 v184, v183, v181, vcc
	v_mov_b32_e32 v185, v184
	v_pk_mul_f32 v[194:195], v[194:195], v[184:185]
	v_pk_mul_f32 v[196:197], v[196:197], v[184:185]
	v_pk_mul_f32 v[198:199], v[198:199], v[184:185]
	v_pk_mul_f32 v[200:201], v[200:201], v[184:185]
	v_pk_mul_f32 v[202:203], v[202:203], v[184:185]
	v_pk_mul_f32 v[204:205], v[204:205], v[184:185]
	v_pk_mul_f32 v[206:207], v[206:207], v[184:185]
	v_pk_mul_f32 v[208:209], v[208:209], v[184:185]
	v_pk_mul_f32 v[194:195], v[194:195], v[236:237]
	v_pk_mul_f32 v[196:197], v[196:197], v[238:239]
	v_pk_mul_f32 v[198:199], v[198:199], v[240:241]
	v_pk_mul_f32 v[200:201], v[200:201], v[242:243]
	v_pk_mul_f32 v[202:203], v[202:203], v[244:245]
	v_pk_mul_f32 v[204:205], v[204:205], v[246:247]
	v_pk_mul_f32 v[206:207], v[206:207], v[248:249]
	v_pk_mul_f32 v[208:209], v[208:209], v[250:251]
	v_add_u32_e32 v181, 0x2800000, v233
	global_store_dwordx4 v181, v[194:197], s[76:77]
	global_store_dwordx4 v181, v[198:201], s[76:77] offset:16
	global_store_dwordx4 v181, v[202:205], s[76:77] offset:2048
	global_store_dwordx4 v181, v[206:209], s[76:77] offset:2064
	s_nop 1
	s_waitcnt vmcnt(12)
	v_lshlrev_b32_e32 v194, 16, v96
	v_and_b32_e32 v195, 0xffff0000, v96
	v_lshlrev_b32_e32 v196, 16, v97
	v_and_b32_e32 v197, 0xffff0000, v97
	v_lshlrev_b32_e32 v198, 16, v98
	v_and_b32_e32 v199, 0xffff0000, v98
	v_lshlrev_b32_e32 v200, 16, v99
	v_and_b32_e32 v201, 0xffff0000, v99
	v_lshlrev_b32_e32 v202, 16, v100
	v_and_b32_e32 v203, 0xffff0000, v100
	v_lshlrev_b32_e32 v204, 16, v101
	v_and_b32_e32 v205, 0xffff0000, v101
	v_lshlrev_b32_e32 v206, 16, v102
	v_and_b32_e32 v207, 0xffff0000, v102
	v_lshlrev_b32_e32 v208, 16, v103
	v_and_b32_e32 v209, 0xffff0000, v103
	v_lshlrev_b32_e32 v216, 16, v104
	v_and_b32_e32 v217, 0xffff0000, v104
	v_lshlrev_b32_e32 v218, 16, v105
	v_and_b32_e32 v219, 0xffff0000, v105
	v_lshlrev_b32_e32 v220, 16, v106
	v_and_b32_e32 v221, 0xffff0000, v106
	v_lshlrev_b32_e32 v222, 16, v107
	v_and_b32_e32 v223, 0xffff0000, v107
	v_lshlrev_b32_e32 v224, 16, v108
	v_and_b32_e32 v225, 0xffff0000, v108
	v_lshlrev_b32_e32 v226, 16, v109
	v_and_b32_e32 v227, 0xffff0000, v109
	v_lshlrev_b32_e32 v228, 16, v110
	v_and_b32_e32 v229, 0xffff0000, v110
	v_lshlrev_b32_e32 v230, 16, v111
	v_and_b32_e32 v231, 0xffff0000, v111
	v_pk_mul_f32 v[252:253], v[216:217], v[216:217]
	v_pk_mul_f32 v[254:255], v[218:219], v[218:219]
	v_pk_fma_f32 v[252:253], v[220:221], v[220:221], v[252:253]
	v_pk_fma_f32 v[254:255], v[222:223], v[222:223], v[254:255]
	v_pk_fma_f32 v[252:253], v[224:225], v[224:225], v[252:253]
	v_pk_fma_f32 v[254:255], v[226:227], v[226:227], v[254:255]
	v_pk_fma_f32 v[252:253], v[228:229], v[228:229], v[252:253]
	v_pk_fma_f32 v[254:255], v[230:231], v[230:231], v[254:255]
	v_pk_add_f32 v[252:253], v[252:253], v[254:255]
	s_nop 0
	v_add_f32_e32 v183, v252, v253
	s_nop 1
	v_add_f32_dpp v183, v183, v183 quad_perm:[1,0,3,2] row_mask:0xf bank_mask:0xf bound_ctrl:1
	s_nop 1
	v_add_f32_dpp v183, v183, v183 quad_perm:[2,3,0,1] row_mask:0xf bank_mask:0xf bound_ctrl:1
	s_nop 1
	v_add_f32_dpp v183, v183, v183 row_half_mirror row_mask:0xf bank_mask:0xf bound_ctrl:1
	s_nop 1
	v_add_f32_dpp v183, v183, v183 row_mirror row_mask:0xf bank_mask:0xf bound_ctrl:1
	s_nop 1
	v_readlane_b32 s98, v183, 0
	v_readlane_b32 s99, v183, 16
	v_readlane_b32 s100, v183, 32
	v_readlane_b32 s101, v183, 48
	s_nop 1
	v_mov_b32_e32 v183, s98
	v_add_f32_e32 v183, s99, v183
	v_add_f32_e32 v183, s100, v183
	v_add_f32_e32 v183, s101, v183
	v_fmamk_f32 v183, v183, 0x3a800000, v182
	v_cmp_gt_f32_e32 vcc, 0x800000, v183
	v_mul_f32_e32 v181, 0x4b800000, v183
	s_nop 1
	v_cndmask_b32_e32 v183, v183, v181, vcc
	v_rsq_f32_e32 v183, v183
	s_nop 0
	v_mul_f32_e32 v181, 0x45800000, v183
	v_cndmask_b32_e32 v184, v183, v181, vcc
	v_mov_b32_e32 v185, v184
	v_pk_mul_f32 v[216:217], v[216:217], v[184:185]
	v_pk_mul_f32 v[218:219], v[218:219], v[184:185]
	v_pk_mul_f32 v[220:221], v[220:221], v[184:185]
	v_pk_mul_f32 v[222:223], v[222:223], v[184:185]
	v_pk_mul_f32 v[224:225], v[224:225], v[184:185]
	v_pk_mul_f32 v[226:227], v[226:227], v[184:185]
	v_pk_mul_f32 v[228:229], v[228:229], v[184:185]
	v_pk_mul_f32 v[230:231], v[230:231], v[184:185]
	v_pk_fma_f32 v[194:195], v[216:217], v[160:161], v[194:195]
	v_pk_fma_f32 v[196:197], v[218:219], v[162:163], v[196:197]
	v_pk_fma_f32 v[198:199], v[220:221], v[164:165], v[198:199]
	v_pk_fma_f32 v[200:201], v[222:223], v[166:167], v[200:201]
	v_pk_fma_f32 v[202:203], v[224:225], v[168:169], v[202:203]
	v_pk_fma_f32 v[204:205], v[226:227], v[170:171], v[204:205]
	v_pk_fma_f32 v[206:207], v[228:229], v[172:173], v[206:207]
	v_pk_fma_f32 v[208:209], v[230:231], v[174:175], v[208:209]
	v_pk_mul_f32 v[252:253], v[194:195], v[194:195]
	v_pk_mul_f32 v[254:255], v[196:197], v[196:197]
	v_pk_fma_f32 v[252:253], v[198:199], v[198:199], v[252:253]
	v_pk_fma_f32 v[254:255], v[200:201], v[200:201], v[254:255]
	v_pk_fma_f32 v[252:253], v[202:203], v[202:203], v[252:253]
	v_pk_fma_f32 v[254:255], v[204:205], v[204:205], v[254:255]
	v_pk_fma_f32 v[252:253], v[206:207], v[206:207], v[252:253]
	v_pk_fma_f32 v[254:255], v[208:209], v[208:209], v[254:255]
	v_pk_add_f32 v[252:253], v[252:253], v[254:255]
	s_nop 0
	v_add_f32_e32 v183, v252, v253
	s_nop 1
	v_add_f32_dpp v183, v183, v183 quad_perm:[1,0,3,2] row_mask:0xf bank_mask:0xf bound_ctrl:1
	s_nop 1
	v_add_f32_dpp v183, v183, v183 quad_perm:[2,3,0,1] row_mask:0xf bank_mask:0xf bound_ctrl:1
	s_nop 1
	v_add_f32_dpp v183, v183, v183 row_half_mirror row_mask:0xf bank_mask:0xf bound_ctrl:1
	s_nop 1
	v_add_f32_dpp v183, v183, v183 row_mirror row_mask:0xf bank_mask:0xf bound_ctrl:1
	s_nop 1
	v_readlane_b32 s98, v183, 0
	v_readlane_b32 s99, v183, 16
	v_readlane_b32 s100, v183, 32
	v_readlane_b32 s101, v183, 48
	s_nop 1
	v_mov_b32_e32 v183, s98
	v_add_f32_e32 v183, s99, v183
	v_add_f32_e32 v183, s100, v183
	v_add_f32_e32 v183, s101, v183
	v_fmamk_f32 v183, v183, 0x3a800000, v182
	v_cmp_gt_f32_e32 vcc, 0x800000, v183
	v_mul_f32_e32 v181, 0x4b800000, v183
	s_nop 1
	v_cndmask_b32_e32 v183, v183, v181, vcc
	v_rsq_f32_e32 v183, v183
	s_nop 0
	v_mul_f32_e32 v181, 0x45800000, v183
	v_cndmask_b32_e32 v184, v183, v181, vcc
	v_mov_b32_e32 v185, v184
	v_pk_mul_f32 v[194:195], v[194:195], v[184:185]
	v_pk_mul_f32 v[196:197], v[196:197], v[184:185]
	v_pk_mul_f32 v[198:199], v[198:199], v[184:185]
	v_pk_mul_f32 v[200:201], v[200:201], v[184:185]
	v_pk_mul_f32 v[202:203], v[202:203], v[184:185]
	v_pk_mul_f32 v[204:205], v[204:205], v[184:185]
	v_pk_mul_f32 v[206:207], v[206:207], v[184:185]
	v_pk_mul_f32 v[208:209], v[208:209], v[184:185]
	v_pk_mul_f32 v[194:195], v[194:195], v[236:237]
	v_pk_mul_f32 v[196:197], v[196:197], v[238:239]
	v_pk_mul_f32 v[198:199], v[198:199], v[240:241]
	v_pk_mul_f32 v[200:201], v[200:201], v[242:243]
	v_pk_mul_f32 v[202:203], v[202:203], v[244:245]
	v_pk_mul_f32 v[204:205], v[204:205], v[246:247]
	v_pk_mul_f32 v[206:207], v[206:207], v[248:249]
	v_pk_mul_f32 v[208:209], v[208:209], v[250:251]
	v_add_u32_e32 v181, 0x3000000, v233
	global_store_dwordx4 v181, v[194:197], s[76:77]
	global_store_dwordx4 v181, v[198:201], s[76:77] offset:16
	global_store_dwordx4 v181, v[202:205], s[76:77] offset:2048
	global_store_dwordx4 v181, v[206:209], s[76:77] offset:2064
	s_nop 1
	s_waitcnt vmcnt(8)
	v_lshlrev_b32_e32 v194, 16, v112
	v_and_b32_e32 v195, 0xffff0000, v112
	v_lshlrev_b32_e32 v196, 16, v113
	v_and_b32_e32 v197, 0xffff0000, v113
	v_lshlrev_b32_e32 v198, 16, v114
	v_and_b32_e32 v199, 0xffff0000, v114
	v_lshlrev_b32_e32 v200, 16, v115
	v_and_b32_e32 v201, 0xffff0000, v115
	v_lshlrev_b32_e32 v202, 16, v116
	v_and_b32_e32 v203, 0xffff0000, v116
	v_lshlrev_b32_e32 v204, 16, v117
	v_and_b32_e32 v205, 0xffff0000, v117
	v_lshlrev_b32_e32 v206, 16, v118
	v_and_b32_e32 v207, 0xffff0000, v118
	v_lshlrev_b32_e32 v208, 16, v119
	v_and_b32_e32 v209, 0xffff0000, v119
	v_lshlrev_b32_e32 v216, 16, v120
	v_and_b32_e32 v217, 0xffff0000, v120
	v_lshlrev_b32_e32 v218, 16, v121
	v_and_b32_e32 v219, 0xffff0000, v121
	v_lshlrev_b32_e32 v220, 16, v122
	v_and_b32_e32 v221, 0xffff0000, v122
	v_lshlrev_b32_e32 v222, 16, v123
	v_and_b32_e32 v223, 0xffff0000, v123
	v_lshlrev_b32_e32 v224, 16, v124
	v_and_b32_e32 v225, 0xffff0000, v124
	v_lshlrev_b32_e32 v226, 16, v125
	v_and_b32_e32 v227, 0xffff0000, v125
	v_lshlrev_b32_e32 v228, 16, v126
	v_and_b32_e32 v229, 0xffff0000, v126
	v_lshlrev_b32_e32 v230, 16, v127
	v_and_b32_e32 v231, 0xffff0000, v127
	v_pk_mul_f32 v[252:253], v[216:217], v[216:217]
	v_pk_mul_f32 v[254:255], v[218:219], v[218:219]
	v_pk_fma_f32 v[252:253], v[220:221], v[220:221], v[252:253]
	v_pk_fma_f32 v[254:255], v[222:223], v[222:223], v[254:255]
	v_pk_fma_f32 v[252:253], v[224:225], v[224:225], v[252:253]
	v_pk_fma_f32 v[254:255], v[226:227], v[226:227], v[254:255]
	v_pk_fma_f32 v[252:253], v[228:229], v[228:229], v[252:253]
	v_pk_fma_f32 v[254:255], v[230:231], v[230:231], v[254:255]
	v_pk_add_f32 v[252:253], v[252:253], v[254:255]
	s_nop 0
	v_add_f32_e32 v183, v252, v253
	s_nop 1
	v_add_f32_dpp v183, v183, v183 quad_perm:[1,0,3,2] row_mask:0xf bank_mask:0xf bound_ctrl:1
	s_nop 1
	v_add_f32_dpp v183, v183, v183 quad_perm:[2,3,0,1] row_mask:0xf bank_mask:0xf bound_ctrl:1
	s_nop 1
	v_add_f32_dpp v183, v183, v183 row_half_mirror row_mask:0xf bank_mask:0xf bound_ctrl:1
	s_nop 1
	v_add_f32_dpp v183, v183, v183 row_mirror row_mask:0xf bank_mask:0xf bound_ctrl:1
	s_nop 1
	v_readlane_b32 s98, v183, 0
	v_readlane_b32 s99, v183, 16
	v_readlane_b32 s100, v183, 32
	v_readlane_b32 s101, v183, 48
	s_nop 1
	v_mov_b32_e32 v183, s98
	v_add_f32_e32 v183, s99, v183
	v_add_f32_e32 v183, s100, v183
	v_add_f32_e32 v183, s101, v183
	v_fmamk_f32 v183, v183, 0x3a800000, v182
	v_cmp_gt_f32_e32 vcc, 0x800000, v183
	v_mul_f32_e32 v181, 0x4b800000, v183
	s_nop 1
	v_cndmask_b32_e32 v183, v183, v181, vcc
	v_rsq_f32_e32 v183, v183
	s_nop 0
	v_mul_f32_e32 v181, 0x45800000, v183
	v_cndmask_b32_e32 v184, v183, v181, vcc
	v_mov_b32_e32 v185, v184
	v_pk_mul_f32 v[216:217], v[216:217], v[184:185]
	v_pk_mul_f32 v[218:219], v[218:219], v[184:185]
	v_pk_mul_f32 v[220:221], v[220:221], v[184:185]
	v_pk_mul_f32 v[222:223], v[222:223], v[184:185]
	v_pk_mul_f32 v[224:225], v[224:225], v[184:185]
	v_pk_mul_f32 v[226:227], v[226:227], v[184:185]
	v_pk_mul_f32 v[228:229], v[228:229], v[184:185]
	v_pk_mul_f32 v[230:231], v[230:231], v[184:185]
	v_pk_fma_f32 v[194:195], v[216:217], v[160:161], v[194:195]
	v_pk_fma_f32 v[196:197], v[218:219], v[162:163], v[196:197]
	v_pk_fma_f32 v[198:199], v[220:221], v[164:165], v[198:199]
	v_pk_fma_f32 v[200:201], v[222:223], v[166:167], v[200:201]
	v_pk_fma_f32 v[202:203], v[224:225], v[168:169], v[202:203]
	v_pk_fma_f32 v[204:205], v[226:227], v[170:171], v[204:205]
	v_pk_fma_f32 v[206:207], v[228:229], v[172:173], v[206:207]
	v_pk_fma_f32 v[208:209], v[230:231], v[174:175], v[208:209]
	v_pk_mul_f32 v[252:253], v[194:195], v[194:195]
	v_pk_mul_f32 v[254:255], v[196:197], v[196:197]
	v_pk_fma_f32 v[252:253], v[198:199], v[198:199], v[252:253]
	v_pk_fma_f32 v[254:255], v[200:201], v[200:201], v[254:255]
	v_pk_fma_f32 v[252:253], v[202:203], v[202:203], v[252:253]
	v_pk_fma_f32 v[254:255], v[204:205], v[204:205], v[254:255]
	v_pk_fma_f32 v[252:253], v[206:207], v[206:207], v[252:253]
	v_pk_fma_f32 v[254:255], v[208:209], v[208:209], v[254:255]
	v_pk_add_f32 v[252:253], v[252:253], v[254:255]
	s_nop 0
	v_add_f32_e32 v183, v252, v253
	s_nop 1
	v_add_f32_dpp v183, v183, v183 quad_perm:[1,0,3,2] row_mask:0xf bank_mask:0xf bound_ctrl:1
	s_nop 1
	v_add_f32_dpp v183, v183, v183 quad_perm:[2,3,0,1] row_mask:0xf bank_mask:0xf bound_ctrl:1
	s_nop 1
	v_add_f32_dpp v183, v183, v183 row_half_mirror row_mask:0xf bank_mask:0xf bound_ctrl:1
	s_nop 1
	v_add_f32_dpp v183, v183, v183 row_mirror row_mask:0xf bank_mask:0xf bound_ctrl:1
	s_nop 1
	v_readlane_b32 s98, v183, 0
	v_readlane_b32 s99, v183, 16
	v_readlane_b32 s100, v183, 32
	v_readlane_b32 s101, v183, 48
	s_nop 1
	v_mov_b32_e32 v183, s98
	v_add_f32_e32 v183, s99, v183
	v_add_f32_e32 v183, s100, v183
	v_add_f32_e32 v183, s101, v183
	v_fmamk_f32 v183, v183, 0x3a800000, v182
	v_cmp_gt_f32_e32 vcc, 0x800000, v183
	v_mul_f32_e32 v181, 0x4b800000, v183
	s_nop 1
	v_cndmask_b32_e32 v183, v183, v181, vcc
	v_rsq_f32_e32 v183, v183
	s_nop 0
	v_mul_f32_e32 v181, 0x45800000, v183
	v_cndmask_b32_e32 v184, v183, v181, vcc
	v_mov_b32_e32 v185, v184
	v_pk_mul_f32 v[194:195], v[194:195], v[184:185]
	v_pk_mul_f32 v[196:197], v[196:197], v[184:185]
	v_pk_mul_f32 v[198:199], v[198:199], v[184:185]
	v_pk_mul_f32 v[200:201], v[200:201], v[184:185]
	v_pk_mul_f32 v[202:203], v[202:203], v[184:185]
	v_pk_mul_f32 v[204:205], v[204:205], v[184:185]
	v_pk_mul_f32 v[206:207], v[206:207], v[184:185]
	v_pk_mul_f32 v[208:209], v[208:209], v[184:185]
	v_pk_mul_f32 v[194:195], v[194:195], v[236:237]
	v_pk_mul_f32 v[196:197], v[196:197], v[238:239]
	v_pk_mul_f32 v[198:199], v[198:199], v[240:241]
	v_pk_mul_f32 v[200:201], v[200:201], v[242:243]
	v_pk_mul_f32 v[202:203], v[202:203], v[244:245]
	v_pk_mul_f32 v[204:205], v[204:205], v[246:247]
	v_pk_mul_f32 v[206:207], v[206:207], v[248:249]
	v_pk_mul_f32 v[208:209], v[208:209], v[250:251]
	v_add_u32_e32 v181, 0x3800000, v233
	global_store_dwordx4 v181, v[194:197], s[76:77]
	global_store_dwordx4 v181, v[198:201], s[76:77] offset:16
	global_store_dwordx4 v181, v[202:205], s[76:77] offset:2048
	global_store_dwordx4 v181, v[206:209], s[76:77] offset:2064
	s_nop 1
	s_waitcnt vmcnt(4)
	v_lshlrev_b32_e32 v194, 16, v128
	v_and_b32_e32 v195, 0xffff0000, v128
	v_lshlrev_b32_e32 v196, 16, v129
	v_and_b32_e32 v197, 0xffff0000, v129
	v_lshlrev_b32_e32 v198, 16, v130
	v_and_b32_e32 v199, 0xffff0000, v130
	v_lshlrev_b32_e32 v200, 16, v131
	v_and_b32_e32 v201, 0xffff0000, v131
	v_lshlrev_b32_e32 v202, 16, v132
	v_and_b32_e32 v203, 0xffff0000, v132
	v_lshlrev_b32_e32 v204, 16, v133
	v_and_b32_e32 v205, 0xffff0000, v133
	v_lshlrev_b32_e32 v206, 16, v134
	v_and_b32_e32 v207, 0xffff0000, v134
	v_lshlrev_b32_e32 v208, 16, v135
	v_and_b32_e32 v209, 0xffff0000, v135
	v_lshlrev_b32_e32 v216, 16, v136
	v_and_b32_e32 v217, 0xffff0000, v136
	v_lshlrev_b32_e32 v218, 16, v137
	v_and_b32_e32 v219, 0xffff0000, v137
	v_lshlrev_b32_e32 v220, 16, v138
	v_and_b32_e32 v221, 0xffff0000, v138
	v_lshlrev_b32_e32 v222, 16, v139
	v_and_b32_e32 v223, 0xffff0000, v139
	v_lshlrev_b32_e32 v224, 16, v140
	v_and_b32_e32 v225, 0xffff0000, v140
	v_lshlrev_b32_e32 v226, 16, v141
	v_and_b32_e32 v227, 0xffff0000, v141
	v_lshlrev_b32_e32 v228, 16, v142
	v_and_b32_e32 v229, 0xffff0000, v142
	v_lshlrev_b32_e32 v230, 16, v143
	v_and_b32_e32 v231, 0xffff0000, v143
	v_pk_mul_f32 v[252:253], v[216:217], v[216:217]
	v_pk_mul_f32 v[254:255], v[218:219], v[218:219]
	v_pk_fma_f32 v[252:253], v[220:221], v[220:221], v[252:253]
	v_pk_fma_f32 v[254:255], v[222:223], v[222:223], v[254:255]
	v_pk_fma_f32 v[252:253], v[224:225], v[224:225], v[252:253]
	v_pk_fma_f32 v[254:255], v[226:227], v[226:227], v[254:255]
	v_pk_fma_f32 v[252:253], v[228:229], v[228:229], v[252:253]
	v_pk_fma_f32 v[254:255], v[230:231], v[230:231], v[254:255]
	v_pk_add_f32 v[252:253], v[252:253], v[254:255]
	s_nop 0
	v_add_f32_e32 v183, v252, v253
	s_nop 1
	v_add_f32_dpp v183, v183, v183 quad_perm:[1,0,3,2] row_mask:0xf bank_mask:0xf bound_ctrl:1
	s_nop 1
	v_add_f32_dpp v183, v183, v183 quad_perm:[2,3,0,1] row_mask:0xf bank_mask:0xf bound_ctrl:1
	s_nop 1
	v_add_f32_dpp v183, v183, v183 row_half_mirror row_mask:0xf bank_mask:0xf bound_ctrl:1
	s_nop 1
	v_add_f32_dpp v183, v183, v183 row_mirror row_mask:0xf bank_mask:0xf bound_ctrl:1
	s_nop 1
	v_readlane_b32 s98, v183, 0
	v_readlane_b32 s99, v183, 16
	v_readlane_b32 s100, v183, 32
	v_readlane_b32 s101, v183, 48
	s_nop 1
	v_mov_b32_e32 v183, s98
	v_add_f32_e32 v183, s99, v183
	v_add_f32_e32 v183, s100, v183
	v_add_f32_e32 v183, s101, v183
	v_fmamk_f32 v183, v183, 0x3a800000, v182
	v_cmp_gt_f32_e32 vcc, 0x800000, v183
	v_mul_f32_e32 v181, 0x4b800000, v183
	s_nop 1
	v_cndmask_b32_e32 v183, v183, v181, vcc
	v_rsq_f32_e32 v183, v183
	s_nop 0
	v_mul_f32_e32 v181, 0x45800000, v183
	v_cndmask_b32_e32 v184, v183, v181, vcc
	v_mov_b32_e32 v185, v184
	v_pk_mul_f32 v[216:217], v[216:217], v[184:185]
	v_pk_mul_f32 v[218:219], v[218:219], v[184:185]
	v_pk_mul_f32 v[220:221], v[220:221], v[184:185]
	v_pk_mul_f32 v[222:223], v[222:223], v[184:185]
	v_pk_mul_f32 v[224:225], v[224:225], v[184:185]
	v_pk_mul_f32 v[226:227], v[226:227], v[184:185]
	v_pk_mul_f32 v[228:229], v[228:229], v[184:185]
	v_pk_mul_f32 v[230:231], v[230:231], v[184:185]
	v_pk_fma_f32 v[194:195], v[216:217], v[160:161], v[194:195]
	v_pk_fma_f32 v[196:197], v[218:219], v[162:163], v[196:197]
	v_pk_fma_f32 v[198:199], v[220:221], v[164:165], v[198:199]
	v_pk_fma_f32 v[200:201], v[222:223], v[166:167], v[200:201]
	v_pk_fma_f32 v[202:203], v[224:225], v[168:169], v[202:203]
	v_pk_fma_f32 v[204:205], v[226:227], v[170:171], v[204:205]
	v_pk_fma_f32 v[206:207], v[228:229], v[172:173], v[206:207]
	v_pk_fma_f32 v[208:209], v[230:231], v[174:175], v[208:209]
	v_pk_mul_f32 v[252:253], v[194:195], v[194:195]
	v_pk_mul_f32 v[254:255], v[196:197], v[196:197]
	v_pk_fma_f32 v[252:253], v[198:199], v[198:199], v[252:253]
	v_pk_fma_f32 v[254:255], v[200:201], v[200:201], v[254:255]
	v_pk_fma_f32 v[252:253], v[202:203], v[202:203], v[252:253]
	v_pk_fma_f32 v[254:255], v[204:205], v[204:205], v[254:255]
	v_pk_fma_f32 v[252:253], v[206:207], v[206:207], v[252:253]
	v_pk_fma_f32 v[254:255], v[208:209], v[208:209], v[254:255]
	v_pk_add_f32 v[252:253], v[252:253], v[254:255]
	s_nop 0
	v_add_f32_e32 v183, v252, v253
	s_nop 1
	v_add_f32_dpp v183, v183, v183 quad_perm:[1,0,3,2] row_mask:0xf bank_mask:0xf bound_ctrl:1
	s_nop 1
	v_add_f32_dpp v183, v183, v183 quad_perm:[2,3,0,1] row_mask:0xf bank_mask:0xf bound_ctrl:1
	s_nop 1
	v_add_f32_dpp v183, v183, v183 row_half_mirror row_mask:0xf bank_mask:0xf bound_ctrl:1
	s_nop 1
	v_add_f32_dpp v183, v183, v183 row_mirror row_mask:0xf bank_mask:0xf bound_ctrl:1
	s_nop 1
	v_readlane_b32 s98, v183, 0
	v_readlane_b32 s99, v183, 16
	v_readlane_b32 s100, v183, 32
	v_readlane_b32 s101, v183, 48
	s_nop 1
	v_mov_b32_e32 v183, s98
	v_add_f32_e32 v183, s99, v183
	v_add_f32_e32 v183, s100, v183
	v_add_f32_e32 v183, s101, v183
	v_fmamk_f32 v183, v183, 0x3a800000, v182
	v_cmp_gt_f32_e32 vcc, 0x800000, v183
	v_mul_f32_e32 v181, 0x4b800000, v183
	s_nop 1
	v_cndmask_b32_e32 v183, v183, v181, vcc
	v_rsq_f32_e32 v183, v183
	s_nop 0
	v_mul_f32_e32 v181, 0x45800000, v183
	v_cndmask_b32_e32 v184, v183, v181, vcc
	v_mov_b32_e32 v185, v184
	v_pk_mul_f32 v[194:195], v[194:195], v[184:185]
	v_pk_mul_f32 v[196:197], v[196:197], v[184:185]
	v_pk_mul_f32 v[198:199], v[198:199], v[184:185]
	v_pk_mul_f32 v[200:201], v[200:201], v[184:185]
	v_pk_mul_f32 v[202:203], v[202:203], v[184:185]
	v_pk_mul_f32 v[204:205], v[204:205], v[184:185]
	v_pk_mul_f32 v[206:207], v[206:207], v[184:185]
	v_pk_mul_f32 v[208:209], v[208:209], v[184:185]
	v_pk_mul_f32 v[194:195], v[194:195], v[236:237]
	v_pk_mul_f32 v[196:197], v[196:197], v[238:239]
	v_pk_mul_f32 v[198:199], v[198:199], v[240:241]
	v_pk_mul_f32 v[200:201], v[200:201], v[242:243]
	v_pk_mul_f32 v[202:203], v[202:203], v[244:245]
	v_pk_mul_f32 v[204:205], v[204:205], v[246:247]
	v_pk_mul_f32 v[206:207], v[206:207], v[248:249]
	v_pk_mul_f32 v[208:209], v[208:209], v[250:251]
	v_add_u32_e32 v181, 0x0, v211
	global_store_dwordx4 v181, v[194:197], s[76:77]
	global_store_dwordx4 v181, v[198:201], s[76:77] offset:16
	global_store_dwordx4 v181, v[202:205], s[76:77] offset:2048
	global_store_dwordx4 v181, v[206:209], s[76:77] offset:2064
	s_nop 1
	s_waitcnt vmcnt(0)
	v_lshlrev_b32_e32 v194, 16, v144
	v_and_b32_e32 v195, 0xffff0000, v144
	v_lshlrev_b32_e32 v196, 16, v145
	v_and_b32_e32 v197, 0xffff0000, v145
	v_lshlrev_b32_e32 v198, 16, v146
	v_and_b32_e32 v199, 0xffff0000, v146
	v_lshlrev_b32_e32 v200, 16, v147
	v_and_b32_e32 v201, 0xffff0000, v147
	v_lshlrev_b32_e32 v202, 16, v148
	v_and_b32_e32 v203, 0xffff0000, v148
	v_lshlrev_b32_e32 v204, 16, v149
	v_and_b32_e32 v205, 0xffff0000, v149
	v_lshlrev_b32_e32 v206, 16, v150
	v_and_b32_e32 v207, 0xffff0000, v150
	v_lshlrev_b32_e32 v208, 16, v151
	v_and_b32_e32 v209, 0xffff0000, v151
	v_lshlrev_b32_e32 v216, 16, v152
	v_and_b32_e32 v217, 0xffff0000, v152
	v_lshlrev_b32_e32 v218, 16, v153
	v_and_b32_e32 v219, 0xffff0000, v153
	v_lshlrev_b32_e32 v220, 16, v154
	v_and_b32_e32 v221, 0xffff0000, v154
	v_lshlrev_b32_e32 v222, 16, v155
	v_and_b32_e32 v223, 0xffff0000, v155
	v_lshlrev_b32_e32 v224, 16, v156
	v_and_b32_e32 v225, 0xffff0000, v156
	v_lshlrev_b32_e32 v226, 16, v157
	v_and_b32_e32 v227, 0xffff0000, v157
	v_lshlrev_b32_e32 v228, 16, v158
	v_and_b32_e32 v229, 0xffff0000, v158
	v_lshlrev_b32_e32 v230, 16, v159
	v_and_b32_e32 v231, 0xffff0000, v159
	v_pk_mul_f32 v[252:253], v[216:217], v[216:217]
	v_pk_mul_f32 v[254:255], v[218:219], v[218:219]
	v_pk_fma_f32 v[252:253], v[220:221], v[220:221], v[252:253]
	v_pk_fma_f32 v[254:255], v[222:223], v[222:223], v[254:255]
	v_pk_fma_f32 v[252:253], v[224:225], v[224:225], v[252:253]
	v_pk_fma_f32 v[254:255], v[226:227], v[226:227], v[254:255]
	v_pk_fma_f32 v[252:253], v[228:229], v[228:229], v[252:253]
	v_pk_fma_f32 v[254:255], v[230:231], v[230:231], v[254:255]
	v_pk_add_f32 v[252:253], v[252:253], v[254:255]
	s_nop 0
	v_add_f32_e32 v183, v252, v253
	s_nop 1
	v_add_f32_dpp v183, v183, v183 quad_perm:[1,0,3,2] row_mask:0xf bank_mask:0xf bound_ctrl:1
	s_nop 1
	v_add_f32_dpp v183, v183, v183 quad_perm:[2,3,0,1] row_mask:0xf bank_mask:0xf bound_ctrl:1
	s_nop 1
	v_add_f32_dpp v183, v183, v183 row_half_mirror row_mask:0xf bank_mask:0xf bound_ctrl:1
	s_nop 1
	v_add_f32_dpp v183, v183, v183 row_mirror row_mask:0xf bank_mask:0xf bound_ctrl:1
	s_nop 1
	v_readlane_b32 s98, v183, 0
	v_readlane_b32 s99, v183, 16
	v_readlane_b32 s100, v183, 32
	v_readlane_b32 s101, v183, 48
	s_nop 1
	v_mov_b32_e32 v183, s98
	v_add_f32_e32 v183, s99, v183
	v_add_f32_e32 v183, s100, v183
	v_add_f32_e32 v183, s101, v183
	v_fmamk_f32 v183, v183, 0x3a800000, v182
	v_cmp_gt_f32_e32 vcc, 0x800000, v183
	v_mul_f32_e32 v181, 0x4b800000, v183
	s_nop 1
	v_cndmask_b32_e32 v183, v183, v181, vcc
	v_rsq_f32_e32 v183, v183
	s_nop 0
	v_mul_f32_e32 v181, 0x45800000, v183
	v_cndmask_b32_e32 v184, v183, v181, vcc
	v_mov_b32_e32 v185, v184
	v_pk_mul_f32 v[216:217], v[216:217], v[184:185]
	v_pk_mul_f32 v[218:219], v[218:219], v[184:185]
	v_pk_mul_f32 v[220:221], v[220:221], v[184:185]
	v_pk_mul_f32 v[222:223], v[222:223], v[184:185]
	v_pk_mul_f32 v[224:225], v[224:225], v[184:185]
	v_pk_mul_f32 v[226:227], v[226:227], v[184:185]
	v_pk_mul_f32 v[228:229], v[228:229], v[184:185]
	v_pk_mul_f32 v[230:231], v[230:231], v[184:185]
	v_pk_fma_f32 v[194:195], v[216:217], v[160:161], v[194:195]
	v_pk_fma_f32 v[196:197], v[218:219], v[162:163], v[196:197]
	v_pk_fma_f32 v[198:199], v[220:221], v[164:165], v[198:199]
	v_pk_fma_f32 v[200:201], v[222:223], v[166:167], v[200:201]
	v_pk_fma_f32 v[202:203], v[224:225], v[168:169], v[202:203]
	v_pk_fma_f32 v[204:205], v[226:227], v[170:171], v[204:205]
	v_pk_fma_f32 v[206:207], v[228:229], v[172:173], v[206:207]
	v_pk_fma_f32 v[208:209], v[230:231], v[174:175], v[208:209]
	v_pk_mul_f32 v[252:253], v[194:195], v[194:195]
	v_pk_mul_f32 v[254:255], v[196:197], v[196:197]
	v_pk_fma_f32 v[252:253], v[198:199], v[198:199], v[252:253]
	v_pk_fma_f32 v[254:255], v[200:201], v[200:201], v[254:255]
	v_pk_fma_f32 v[252:253], v[202:203], v[202:203], v[252:253]
	v_pk_fma_f32 v[254:255], v[204:205], v[204:205], v[254:255]
	v_pk_fma_f32 v[252:253], v[206:207], v[206:207], v[252:253]
	v_pk_fma_f32 v[254:255], v[208:209], v[208:209], v[254:255]
	v_pk_add_f32 v[252:253], v[252:253], v[254:255]
	s_nop 0
	v_add_f32_e32 v183, v252, v253
	s_nop 1
	v_add_f32_dpp v183, v183, v183 quad_perm:[1,0,3,2] row_mask:0xf bank_mask:0xf bound_ctrl:1
	s_nop 1
	v_add_f32_dpp v183, v183, v183 quad_perm:[2,3,0,1] row_mask:0xf bank_mask:0xf bound_ctrl:1
	s_nop 1
	v_add_f32_dpp v183, v183, v183 row_half_mirror row_mask:0xf bank_mask:0xf bound_ctrl:1
	s_nop 1
	v_add_f32_dpp v183, v183, v183 row_mirror row_mask:0xf bank_mask:0xf bound_ctrl:1
	s_nop 1
	v_readlane_b32 s98, v183, 0
	v_readlane_b32 s99, v183, 16
	v_readlane_b32 s100, v183, 32
	v_readlane_b32 s101, v183, 48
	s_nop 1
	v_mov_b32_e32 v183, s98
	v_add_f32_e32 v183, s99, v183
	v_add_f32_e32 v183, s100, v183
	v_add_f32_e32 v183, s101, v183
	v_fmamk_f32 v183, v183, 0x3a800000, v182
	v_cmp_gt_f32_e32 vcc, 0x800000, v183
	v_mul_f32_e32 v181, 0x4b800000, v183
	s_nop 1
	v_cndmask_b32_e32 v183, v183, v181, vcc
	v_rsq_f32_e32 v183, v183
	s_nop 0
	v_mul_f32_e32 v181, 0x45800000, v183
	v_cndmask_b32_e32 v184, v183, v181, vcc
	v_mov_b32_e32 v185, v184
	v_pk_mul_f32 v[194:195], v[194:195], v[184:185]
	v_pk_mul_f32 v[196:197], v[196:197], v[184:185]
	v_pk_mul_f32 v[198:199], v[198:199], v[184:185]
	v_pk_mul_f32 v[200:201], v[200:201], v[184:185]
	v_pk_mul_f32 v[202:203], v[202:203], v[184:185]
	v_pk_mul_f32 v[204:205], v[204:205], v[184:185]
	v_pk_mul_f32 v[206:207], v[206:207], v[184:185]
	v_pk_mul_f32 v[208:209], v[208:209], v[184:185]
	v_pk_mul_f32 v[194:195], v[194:195], v[236:237]
	v_pk_mul_f32 v[196:197], v[196:197], v[238:239]
	v_pk_mul_f32 v[198:199], v[198:199], v[240:241]
	v_pk_mul_f32 v[200:201], v[200:201], v[242:243]
	v_pk_mul_f32 v[202:203], v[202:203], v[244:245]
	v_pk_mul_f32 v[204:205], v[204:205], v[246:247]
	v_pk_mul_f32 v[206:207], v[206:207], v[248:249]
	v_pk_mul_f32 v[208:209], v[208:209], v[250:251]
	v_add_u32_e32 v181, 0x800000, v211
	global_store_dwordx4 v181, v[194:197], s[76:77]
	global_store_dwordx4 v181, v[198:201], s[76:77] offset:16
	global_store_dwordx4 v181, v[202:205], s[76:77] offset:2048
	global_store_dwordx4 v181, v[206:209], s[76:77] offset:2064
	s_nop 1
	s_branch .Lmyxupd_done_7
.Lmyxupd_s_7:
	v_add_u32_e32 v178, 0x1800000, v177
	v_add_u32_e32 v181, 0x9e00000, v177
	global_load_dwordx4 v[0:3], v178, s[78:79]
	global_load_dwordx4 v[4:7], v178, s[78:79] offset:1024
	global_load_dwordx4 v[8:11], v181, s[78:79]
	global_load_dwordx4 v[12:15], v181, s[78:79] offset:1024
	v_add_u32_e32 v178, 0x1c00000, v177
	v_add_u32_e32 v181, 0xa200000, v177
	global_load_dwordx4 v[16:19], v178, s[78:79]
	global_load_dwordx4 v[20:23], v178, s[78:79] offset:1024
	global_load_dwordx4 v[24:27], v181, s[78:79]
	global_load_dwordx4 v[28:31], v181, s[78:79] offset:1024
	v_lshrrev_b32_e32 v179, 2, v179
	v_lshlrev_b32_e32 v210, 4, v176
	v_lshl_add_u32 v210, v179, 11, v210
	v_lshl_add_u32 v211, v179, 12, v180
	v_add_u32_e32 v181, 0x3800000, v210
	global_load_dwordx4 v[32:35], v181, s[78:79]
	global_load_dwordx4 v[36:39], v181, s[78:79] offset:1024
	v_lshl_add_u32 v183, v179, 12, v180
	v_add_u32_e32 v183, 0xbf00000, v183
	v_add_u32_e32 v181, 0x0, v183
	global_load_dwordx4 v[40:43], v181, s[78:79]
	global_load_dwordx4 v[44:47], v181, s[78:79] offset:16
	global_load_dwordx4 v[48:51], v181, s[78:79] offset:2048
	global_load_dwordx4 v[52:55], v181, s[78:79] offset:2064
	v_add_u32_e32 v181, 0x200000, v183
	global_load_dwordx4 v[56:59], v181, s[78:79]
	global_load_dwordx4 v[60:63], v181, s[78:79] offset:16
	global_load_dwordx4 v[64:67], v181, s[78:79] offset:2048
	global_load_dwordx4 v[68:71], v181, s[78:79] offset:2064
	v_add_u32_e32 v181, 0x400000, v183
	global_load_dwordx4 v[72:75], v181, s[78:79]
	global_load_dwordx4 v[76:79], v181, s[78:79] offset:16
	global_load_dwordx4 v[80:83], v181, s[78:79] offset:2048
	global_load_dwordx4 v[84:87], v181, s[78:79] offset:2064
	v_add_u32_e32 v181, 0x600000, v183
	global_load_dwordx4 v[88:91], v181, s[78:79]
	global_load_dwordx4 v[92:95], v181, s[78:79] offset:16
	global_load_dwordx4 v[96:99], v181, s[78:79] offset:2048
	global_load_dwordx4 v[100:103], v181, s[78:79] offset:2064
	v_add_u32_e32 v181, 0x800000, v183
	global_load_dwordx4 v[104:107], v181, s[78:79]
	global_load_dwordx4 v[108:111], v181, s[78:79] offset:16
	global_load_dwordx4 v[112:115], v181, s[78:79] offset:2048
	global_load_dwordx4 v[116:119], v181, s[78:79] offset:2064
	v_add_u32_e32 v181, 0xa00000, v183
	global_load_dwordx4 v[120:123], v181, s[78:79]
	global_load_dwordx4 v[124:127], v181, s[78:79] offset:16
	global_load_dwordx4 v[128:131], v181, s[78:79] offset:2048
	global_load_dwordx4 v[132:135], v181, s[78:79] offset:2064
	v_add_u32_e32 v181, 0xc00000, v183
	global_load_dwordx4 v[136:139], v181, s[78:79]
	global_load_dwordx4 v[140:143], v181, s[78:79] offset:16
	global_load_dwordx4 v[144:147], v181, s[78:79] offset:2048
	global_load_dwordx4 v[148:151], v181, s[78:79] offset:2064
	v_mov_b32_e32 v178, v183
	s_waitcnt vmcnt(34)
	v_lshlrev_b32_e32 v194, 16, v0
	v_and_b32_e32 v195, 0xffff0000, v0
	v_lshlrev_b32_e32 v196, 16, v1
	v_and_b32_e32 v197, 0xffff0000, v1
	v_lshlrev_b32_e32 v198, 16, v2
	v_and_b32_e32 v199, 0xffff0000, v2
	v_lshlrev_b32_e32 v200, 16, v3
	v_and_b32_e32 v201, 0xffff0000, v3
	v_lshlrev_b32_e32 v202, 16, v4
	v_and_b32_e32 v203, 0xffff0000, v4
	v_lshlrev_b32_e32 v204, 16, v5
	v_and_b32_e32 v205, 0xffff0000, v5
	v_lshlrev_b32_e32 v206, 16, v6
	v_and_b32_e32 v207, 0xffff0000, v6
	v_lshlrev_b32_e32 v208, 16, v7
	v_and_b32_e32 v209, 0xffff0000, v7
	v_lshlrev_b32_e32 v216, 16, v8
	v_and_b32_e32 v217, 0xffff0000, v8
	v_lshlrev_b32_e32 v218, 16, v9
	v_and_b32_e32 v219, 0xffff0000, v9
	v_lshlrev_b32_e32 v220, 16, v10
	v_and_b32_e32 v221, 0xffff0000, v10
	v_lshlrev_b32_e32 v222, 16, v11
	v_and_b32_e32 v223, 0xffff0000, v11
	v_lshlrev_b32_e32 v224, 16, v12
	v_and_b32_e32 v225, 0xffff0000, v12
	v_lshlrev_b32_e32 v226, 16, v13
	v_and_b32_e32 v227, 0xffff0000, v13
	v_lshlrev_b32_e32 v228, 16, v14
	v_and_b32_e32 v229, 0xffff0000, v14
	v_lshlrev_b32_e32 v230, 16, v15
	v_and_b32_e32 v231, 0xffff0000, v15
	v_pk_mul_f32 v[252:253], v[216:217], v[216:217]
	v_pk_mul_f32 v[254:255], v[218:219], v[218:219]
	v_pk_fma_f32 v[252:253], v[220:221], v[220:221], v[252:253]
	v_pk_fma_f32 v[254:255], v[222:223], v[222:223], v[254:255]
	v_pk_fma_f32 v[252:253], v[224:225], v[224:225], v[252:253]
	v_pk_fma_f32 v[254:255], v[226:227], v[226:227], v[254:255]
	v_pk_fma_f32 v[252:253], v[228:229], v[228:229], v[252:253]
	v_pk_fma_f32 v[254:255], v[230:231], v[230:231], v[254:255]
	v_pk_add_f32 v[252:253], v[252:253], v[254:255]
	s_nop 0
	v_add_f32_e32 v183, v252, v253
	s_nop 1
	v_add_f32_dpp v183, v183, v183 quad_perm:[1,0,3,2] row_mask:0xf bank_mask:0xf bound_ctrl:1
	s_nop 1
	v_add_f32_dpp v183, v183, v183 quad_perm:[2,3,0,1] row_mask:0xf bank_mask:0xf bound_ctrl:1
	s_nop 1
	v_add_f32_dpp v183, v183, v183 row_half_mirror row_mask:0xf bank_mask:0xf bound_ctrl:1
	s_nop 1
	v_add_f32_dpp v183, v183, v183 row_mirror row_mask:0xf bank_mask:0xf bound_ctrl:1
	s_nop 1
	v_readlane_b32 s98, v183, 0
	v_readlane_b32 s99, v183, 16
	v_readlane_b32 s100, v183, 32
	v_readlane_b32 s101, v183, 48
	s_nop 1
	v_mov_b32_e32 v183, s98
	v_add_f32_e32 v183, s99, v183
	v_add_f32_e32 v183, s100, v183
	v_add_f32_e32 v183, s101, v183
	v_fmamk_f32 v183, v183, 0x3a800000, v182
	v_cmp_gt_f32_e32 vcc, 0x800000, v183
	v_mul_f32_e32 v181, 0x4b800000, v183
	s_nop 1
	v_cndmask_b32_e32 v183, v183, v181, vcc
	v_rsq_f32_e32 v183, v183
	s_nop 0
	v_mul_f32_e32 v181, 0x45800000, v183
	v_cndmask_b32_e32 v184, v183, v181, vcc
	v_mov_b32_e32 v185, v184
	v_pk_mul_f32 v[216:217], v[216:217], v[184:185]
	v_pk_mul_f32 v[218:219], v[218:219], v[184:185]
	v_pk_mul_f32 v[220:221], v[220:221], v[184:185]
	v_pk_mul_f32 v[222:223], v[222:223], v[184:185]
	v_pk_mul_f32 v[224:225], v[224:225], v[184:185]
	v_pk_mul_f32 v[226:227], v[226:227], v[184:185]
	v_pk_mul_f32 v[228:229], v[228:229], v[184:185]
	v_pk_mul_f32 v[230:231], v[230:231], v[184:185]
	v_pk_fma_f32 v[194:195], v[216:217], v[160:161], v[194:195]
	v_pk_fma_f32 v[196:197], v[218:219], v[162:163], v[196:197]
	v_pk_fma_f32 v[198:199], v[220:221], v[164:165], v[198:199]
	v_pk_fma_f32 v[200:201], v[222:223], v[166:167], v[200:201]
	v_pk_fma_f32 v[202:203], v[224:225], v[168:169], v[202:203]
	v_pk_fma_f32 v[204:205], v[226:227], v[170:171], v[204:205]
	v_pk_fma_f32 v[206:207], v[228:229], v[172:173], v[206:207]
	v_pk_fma_f32 v[208:209], v[230:231], v[174:175], v[208:209]
	v_pk_mul_f32 v[252:253], v[194:195], v[194:195]
	v_pk_mul_f32 v[254:255], v[196:197], v[196:197]
	v_pk_fma_f32 v[252:253], v[198:199], v[198:199], v[252:253]
	v_pk_fma_f32 v[254:255], v[200:201], v[200:201], v[254:255]
	v_pk_fma_f32 v[252:253], v[202:203], v[202:203], v[252:253]
	v_pk_fma_f32 v[254:255], v[204:205], v[204:205], v[254:255]
	v_pk_fma_f32 v[252:253], v[206:207], v[206:207], v[252:253]
	v_pk_fma_f32 v[254:255], v[208:209], v[208:209], v[254:255]
	v_pk_add_f32 v[252:253], v[252:253], v[254:255]
	s_nop 0
	v_add_f32_e32 v183, v252, v253
	s_nop 1
	v_add_f32_dpp v183, v183, v183 quad_perm:[1,0,3,2] row_mask:0xf bank_mask:0xf bound_ctrl:1
	s_nop 1
	v_add_f32_dpp v183, v183, v183 quad_perm:[2,3,0,1] row_mask:0xf bank_mask:0xf bound_ctrl:1
	s_nop 1
	v_add_f32_dpp v183, v183, v183 row_half_mirror row_mask:0xf bank_mask:0xf bound_ctrl:1
	s_nop 1
	v_add_f32_dpp v183, v183, v183 row_mirror row_mask:0xf bank_mask:0xf bound_ctrl:1
	s_nop 1
	v_readlane_b32 s98, v183, 0
	v_readlane_b32 s99, v183, 16
	v_readlane_b32 s100, v183, 32
	v_readlane_b32 s101, v183, 48
	s_nop 1
	v_mov_b32_e32 v183, s98
	v_add_f32_e32 v183, s99, v183
	v_add_f32_e32 v183, s100, v183
	v_add_f32_e32 v183, s101, v183
	v_fmamk_f32 v183, v183, 0x3a800000, v182
	v_cmp_gt_f32_e32 vcc, 0x800000, v183
	v_mul_f32_e32 v181, 0x4b800000, v183
	s_nop 1
	v_cndmask_b32_e32 v183, v183, v181, vcc
	v_rsq_f32_e32 v183, v183
	s_nop 0
	v_mul_f32_e32 v181, 0x45800000, v183
	v_cndmask_b32_e32 v184, v183, v181, vcc
	v_mov_b32_e32 v185, v184
	v_pk_mul_f32 v[194:195], v[194:195], v[184:185]
	v_pk_mul_f32 v[196:197], v[196:197], v[184:185]
	v_pk_mul_f32 v[198:199], v[198:199], v[184:185]
	v_pk_mul_f32 v[200:201], v[200:201], v[184:185]
	v_pk_mul_f32 v[202:203], v[202:203], v[184:185]
	v_pk_mul_f32 v[204:205], v[204:205], v[184:185]
	v_pk_mul_f32 v[206:207], v[206:207], v[184:185]
	v_pk_mul_f32 v[208:209], v[208:209], v[184:185]
	v_pk_mul_f32 v[194:195], v[194:195], v[236:237]
	v_pk_mul_f32 v[196:197], v[196:197], v[238:239]
	v_pk_mul_f32 v[198:199], v[198:199], v[240:241]
	v_pk_mul_f32 v[200:201], v[200:201], v[242:243]
	v_pk_mul_f32 v[202:203], v[202:203], v[244:245]
	v_pk_mul_f32 v[204:205], v[204:205], v[246:247]
	v_pk_mul_f32 v[206:207], v[206:207], v[248:249]
	v_pk_mul_f32 v[208:209], v[208:209], v[250:251]
	v_add_u32_e32 v181, 0x0, v233
	global_store_dwordx4 v181, v[194:197], s[76:77]
	global_store_dwordx4 v181, v[198:201], s[76:77] offset:16
	global_store_dwordx4 v181, v[202:205], s[76:77] offset:2048
	global_store_dwordx4 v181, v[206:209], s[76:77] offset:2064
	s_nop 1
	s_waitcnt vmcnt(30)
	v_lshlrev_b32_e32 v194, 16, v16
	v_and_b32_e32 v195, 0xffff0000, v16
	v_lshlrev_b32_e32 v196, 16, v17
	v_and_b32_e32 v197, 0xffff0000, v17
	v_lshlrev_b32_e32 v198, 16, v18
	v_and_b32_e32 v199, 0xffff0000, v18
	v_lshlrev_b32_e32 v200, 16, v19
	v_and_b32_e32 v201, 0xffff0000, v19
	v_lshlrev_b32_e32 v202, 16, v20
	v_and_b32_e32 v203, 0xffff0000, v20
	v_lshlrev_b32_e32 v204, 16, v21
	v_and_b32_e32 v205, 0xffff0000, v21
	v_lshlrev_b32_e32 v206, 16, v22
	v_and_b32_e32 v207, 0xffff0000, v22
	v_lshlrev_b32_e32 v208, 16, v23
	v_and_b32_e32 v209, 0xffff0000, v23
	v_lshlrev_b32_e32 v216, 16, v24
	v_and_b32_e32 v217, 0xffff0000, v24
	v_lshlrev_b32_e32 v218, 16, v25
	v_and_b32_e32 v219, 0xffff0000, v25
	v_lshlrev_b32_e32 v220, 16, v26
	v_and_b32_e32 v221, 0xffff0000, v26
	v_lshlrev_b32_e32 v222, 16, v27
	v_and_b32_e32 v223, 0xffff0000, v27
	v_lshlrev_b32_e32 v224, 16, v28
	v_and_b32_e32 v225, 0xffff0000, v28
	v_lshlrev_b32_e32 v226, 16, v29
	v_and_b32_e32 v227, 0xffff0000, v29
	v_lshlrev_b32_e32 v228, 16, v30
	v_and_b32_e32 v229, 0xffff0000, v30
	v_lshlrev_b32_e32 v230, 16, v31
	v_and_b32_e32 v231, 0xffff0000, v31
	v_pk_mul_f32 v[252:253], v[216:217], v[216:217]
	v_pk_mul_f32 v[254:255], v[218:219], v[218:219]
	v_pk_fma_f32 v[252:253], v[220:221], v[220:221], v[252:253]
	v_pk_fma_f32 v[254:255], v[222:223], v[222:223], v[254:255]
	v_pk_fma_f32 v[252:253], v[224:225], v[224:225], v[252:253]
	v_pk_fma_f32 v[254:255], v[226:227], v[226:227], v[254:255]
	v_pk_fma_f32 v[252:253], v[228:229], v[228:229], v[252:253]
	v_pk_fma_f32 v[254:255], v[230:231], v[230:231], v[254:255]
	v_pk_add_f32 v[252:253], v[252:253], v[254:255]
	s_nop 0
	v_add_f32_e32 v183, v252, v253
	s_nop 1
	v_add_f32_dpp v183, v183, v183 quad_perm:[1,0,3,2] row_mask:0xf bank_mask:0xf bound_ctrl:1
	s_nop 1
	v_add_f32_dpp v183, v183, v183 quad_perm:[2,3,0,1] row_mask:0xf bank_mask:0xf bound_ctrl:1
	s_nop 1
	v_add_f32_dpp v183, v183, v183 row_half_mirror row_mask:0xf bank_mask:0xf bound_ctrl:1
	s_nop 1
	v_add_f32_dpp v183, v183, v183 row_mirror row_mask:0xf bank_mask:0xf bound_ctrl:1
	s_nop 1
	v_readlane_b32 s98, v183, 0
	v_readlane_b32 s99, v183, 16
	v_readlane_b32 s100, v183, 32
	v_readlane_b32 s101, v183, 48
	s_nop 1
	v_mov_b32_e32 v183, s98
	v_add_f32_e32 v183, s99, v183
	v_add_f32_e32 v183, s100, v183
	v_add_f32_e32 v183, s101, v183
	v_fmamk_f32 v183, v183, 0x3a800000, v182
	v_cmp_gt_f32_e32 vcc, 0x800000, v183
	v_mul_f32_e32 v181, 0x4b800000, v183
	s_nop 1
	v_cndmask_b32_e32 v183, v183, v181, vcc
	v_rsq_f32_e32 v183, v183
	s_nop 0
	v_mul_f32_e32 v181, 0x45800000, v183
	v_cndmask_b32_e32 v184, v183, v181, vcc
	v_mov_b32_e32 v185, v184
	v_pk_mul_f32 v[216:217], v[216:217], v[184:185]
	v_pk_mul_f32 v[218:219], v[218:219], v[184:185]
	v_pk_mul_f32 v[220:221], v[220:221], v[184:185]
	v_pk_mul_f32 v[222:223], v[222:223], v[184:185]
	v_pk_mul_f32 v[224:225], v[224:225], v[184:185]
	v_pk_mul_f32 v[226:227], v[226:227], v[184:185]
	v_pk_mul_f32 v[228:229], v[228:229], v[184:185]
	v_pk_mul_f32 v[230:231], v[230:231], v[184:185]
	v_pk_fma_f32 v[194:195], v[216:217], v[160:161], v[194:195]
	v_pk_fma_f32 v[196:197], v[218:219], v[162:163], v[196:197]
	v_pk_fma_f32 v[198:199], v[220:221], v[164:165], v[198:199]
	v_pk_fma_f32 v[200:201], v[222:223], v[166:167], v[200:201]
	v_pk_fma_f32 v[202:203], v[224:225], v[168:169], v[202:203]
	v_pk_fma_f32 v[204:205], v[226:227], v[170:171], v[204:205]
	v_pk_fma_f32 v[206:207], v[228:229], v[172:173], v[206:207]
	v_pk_fma_f32 v[208:209], v[230:231], v[174:175], v[208:209]
	v_pk_mul_f32 v[252:253], v[194:195], v[194:195]
	v_pk_mul_f32 v[254:255], v[196:197], v[196:197]
	v_pk_fma_f32 v[252:253], v[198:199], v[198:199], v[252:253]
	v_pk_fma_f32 v[254:255], v[200:201], v[200:201], v[254:255]
	v_pk_fma_f32 v[252:253], v[202:203], v[202:203], v[252:253]
	v_pk_fma_f32 v[254:255], v[204:205], v[204:205], v[254:255]
	v_pk_fma_f32 v[252:253], v[206:207], v[206:207], v[252:253]
	v_pk_fma_f32 v[254:255], v[208:209], v[208:209], v[254:255]
	v_pk_add_f32 v[252:253], v[252:253], v[254:255]
	s_nop 0
	v_add_f32_e32 v183, v252, v253
	s_nop 1
	v_add_f32_dpp v183, v183, v183 quad_perm:[1,0,3,2] row_mask:0xf bank_mask:0xf bound_ctrl:1
	s_nop 1
	v_add_f32_dpp v183, v183, v183 quad_perm:[2,3,0,1] row_mask:0xf bank_mask:0xf bound_ctrl:1
	s_nop 1
	v_add_f32_dpp v183, v183, v183 row_half_mirror row_mask:0xf bank_mask:0xf bound_ctrl:1
	s_nop 1
	v_add_f32_dpp v183, v183, v183 row_mirror row_mask:0xf bank_mask:0xf bound_ctrl:1
	s_nop 1
	v_readlane_b32 s98, v183, 0
	v_readlane_b32 s99, v183, 16
	v_readlane_b32 s100, v183, 32
	v_readlane_b32 s101, v183, 48
	s_nop 1
	v_mov_b32_e32 v183, s98
	v_add_f32_e32 v183, s99, v183
	v_add_f32_e32 v183, s100, v183
	v_add_f32_e32 v183, s101, v183
	v_fmamk_f32 v183, v183, 0x3a800000, v182
	v_cmp_gt_f32_e32 vcc, 0x800000, v183
	v_mul_f32_e32 v181, 0x4b800000, v183
	s_nop 1
	v_cndmask_b32_e32 v183, v183, v181, vcc
	v_rsq_f32_e32 v183, v183
	s_nop 0
	v_mul_f32_e32 v181, 0x45800000, v183
	v_cndmask_b32_e32 v184, v183, v181, vcc
	v_mov_b32_e32 v185, v184
	v_pk_mul_f32 v[194:195], v[194:195], v[184:185]
	v_pk_mul_f32 v[196:197], v[196:197], v[184:185]
	v_pk_mul_f32 v[198:199], v[198:199], v[184:185]
	v_pk_mul_f32 v[200:201], v[200:201], v[184:185]
	v_pk_mul_f32 v[202:203], v[202:203], v[184:185]
	v_pk_mul_f32 v[204:205], v[204:205], v[184:185]
	v_pk_mul_f32 v[206:207], v[206:207], v[184:185]
	v_pk_mul_f32 v[208:209], v[208:209], v[184:185]
	v_pk_mul_f32 v[194:195], v[194:195], v[236:237]
	v_pk_mul_f32 v[196:197], v[196:197], v[238:239]
	v_pk_mul_f32 v[198:199], v[198:199], v[240:241]
	v_pk_mul_f32 v[200:201], v[200:201], v[242:243]
	v_pk_mul_f32 v[202:203], v[202:203], v[244:245]
	v_pk_mul_f32 v[204:205], v[204:205], v[246:247]
	v_pk_mul_f32 v[206:207], v[206:207], v[248:249]
	v_pk_mul_f32 v[208:209], v[208:209], v[250:251]
	v_add_u32_e32 v181, 0x800000, v233
	global_store_dwordx4 v181, v[194:197], s[76:77]
	global_store_dwordx4 v181, v[198:201], s[76:77] offset:16
	global_store_dwordx4 v181, v[202:205], s[76:77] offset:2048
	global_store_dwordx4 v181, v[206:209], s[76:77] offset:2064
	s_nop 1
	s_waitcnt vmcnt(24)
	v_pk_add_f32 v[216:217], v[40:41], 0 op_sel_hi:[1,0]
	v_pk_add_f32 v[218:219], v[42:43], 0 op_sel_hi:[1,0]
	v_pk_add_f32 v[220:221], v[44:45], 0 op_sel_hi:[1,0]
	v_pk_add_f32 v[222:223], v[46:47], 0 op_sel_hi:[1,0]
	v_pk_add_f32 v[224:225], v[48:49], 0 op_sel_hi:[1,0]
	v_pk_add_f32 v[226:227], v[50:51], 0 op_sel_hi:[1,0]
	v_pk_add_f32 v[228:229], v[52:53], 0 op_sel_hi:[1,0]
	v_pk_add_f32 v[230:231], v[54:55], 0 op_sel_hi:[1,0]
	s_waitcnt vmcnt(20)
	v_pk_add_f32 v[216:217], v[216:217], v[56:57]
	v_pk_add_f32 v[218:219], v[218:219], v[58:59]
	v_pk_add_f32 v[220:221], v[220:221], v[60:61]
	v_pk_add_f32 v[222:223], v[222:223], v[62:63]
	v_pk_add_f32 v[224:225], v[224:225], v[64:65]
	v_pk_add_f32 v[226:227], v[226:227], v[66:67]
	v_pk_add_f32 v[228:229], v[228:229], v[68:69]
	v_pk_add_f32 v[230:231], v[230:231], v[70:71]
	v_lshlrev_b32_e32 v194, 16, v32
	v_and_b32_e32 v195, 0xffff0000, v32
	v_lshlrev_b32_e32 v196, 16, v33
	v_and_b32_e32 v197, 0xffff0000, v33
	v_lshlrev_b32_e32 v198, 16, v34
	v_and_b32_e32 v199, 0xffff0000, v34
	v_lshlrev_b32_e32 v200, 16, v35
	v_and_b32_e32 v201, 0xffff0000, v35
	v_lshlrev_b32_e32 v202, 16, v36
	v_and_b32_e32 v203, 0xffff0000, v36
	v_lshlrev_b32_e32 v204, 16, v37
	v_and_b32_e32 v205, 0xffff0000, v37
	v_lshlrev_b32_e32 v206, 16, v38
	v_and_b32_e32 v207, 0xffff0000, v38
	v_lshlrev_b32_e32 v208, 16, v39
	v_and_b32_e32 v209, 0xffff0000, v39
	v_add_u32_e32 v181, 0xe00000, v178
	global_load_dwordx4 v[0:3], v181, s[78:79]
	global_load_dwordx4 v[4:7], v181, s[78:79] offset:16
	global_load_dwordx4 v[8:11], v181, s[78:79] offset:2048
	global_load_dwordx4 v[12:15], v181, s[78:79] offset:2064
	v_add_u32_e32 v181, 0x1000000, v178
	global_load_dwordx4 v[16:19], v181, s[78:79]
	global_load_dwordx4 v[20:23], v181, s[78:79] offset:16
	global_load_dwordx4 v[24:27], v181, s[78:79] offset:2048
	global_load_dwordx4 v[28:31], v181, s[78:79] offset:2064
	v_add_u32_e32 v181, 0x1200000, v178
	global_load_dwordx4 v[32:35], v181, s[78:79]
	global_load_dwordx4 v[36:39], v181, s[78:79] offset:16
	global_load_dwordx4 v[40:43], v181, s[78:79] offset:2048
	global_load_dwordx4 v[44:47], v181, s[78:79] offset:2064
	v_add_u32_e32 v181, 0x1400000, v178
	global_load_dwordx4 v[48:51], v181, s[78:79]
	global_load_dwordx4 v[52:55], v181, s[78:79] offset:16
	global_load_dwordx4 v[56:59], v181, s[78:79] offset:2048
	global_load_dwordx4 v[60:63], v181, s[78:79] offset:2064
	s_waitcnt vmcnt(32)
	v_pk_add_f32 v[216:217], v[216:217], v[72:73]
	v_pk_add_f32 v[218:219], v[218:219], v[74:75]
	v_pk_add_f32 v[220:221], v[220:221], v[76:77]
	v_pk_add_f32 v[222:223], v[222:223], v[78:79]
	v_pk_add_f32 v[224:225], v[224:225], v[80:81]
	v_pk_add_f32 v[226:227], v[226:227], v[82:83]
	v_pk_add_f32 v[228:229], v[228:229], v[84:85]
	v_pk_add_f32 v[230:231], v[230:231], v[86:87]
	s_waitcnt vmcnt(28)
	v_pk_add_f32 v[216:217], v[216:217], v[88:89]
	v_pk_add_f32 v[218:219], v[218:219], v[90:91]
	v_pk_add_f32 v[220:221], v[220:221], v[92:93]
	v_pk_add_f32 v[222:223], v[222:223], v[94:95]
	v_pk_add_f32 v[224:225], v[224:225], v[96:97]
	v_pk_add_f32 v[226:227], v[226:227], v[98:99]
	v_pk_add_f32 v[228:229], v[228:229], v[100:101]
	v_pk_add_f32 v[230:231], v[230:231], v[102:103]
	s_waitcnt vmcnt(24)
	v_pk_add_f32 v[216:217], v[216:217], v[104:105]
	v_pk_add_f32 v[218:219], v[218:219], v[106:107]
	v_pk_add_f32 v[220:221], v[220:221], v[108:109]
	v_pk_add_f32 v[222:223], v[222:223], v[110:111]
	v_pk_add_f32 v[224:225], v[224:225], v[112:113]
	v_pk_add_f32 v[226:227], v[226:227], v[114:115]
	v_pk_add_f32 v[228:229], v[228:229], v[116:117]
	v_pk_add_f32 v[230:231], v[230:231], v[118:119]
	s_waitcnt vmcnt(20)
	v_pk_add_f32 v[216:217], v[216:217], v[120:121]
	v_pk_add_f32 v[218:219], v[218:219], v[122:123]
	v_pk_add_f32 v[220:221], v[220:221], v[124:125]
	v_pk_add_f32 v[222:223], v[222:223], v[126:127]
	v_pk_add_f32 v[224:225], v[224:225], v[128:129]
	v_pk_add_f32 v[226:227], v[226:227], v[130:131]
	v_pk_add_f32 v[228:229], v[228:229], v[132:133]
	v_pk_add_f32 v[230:231], v[230:231], v[134:135]
	s_waitcnt vmcnt(16)
	v_pk_add_f32 v[216:217], v[216:217], v[136:137]
	v_pk_add_f32 v[218:219], v[218:219], v[138:139]
	v_pk_add_f32 v[220:221], v[220:221], v[140:141]
	v_pk_add_f32 v[222:223], v[222:223], v[142:143]
	v_pk_add_f32 v[224:225], v[224:225], v[144:145]
	v_pk_add_f32 v[226:227], v[226:227], v[146:147]
	v_pk_add_f32 v[228:229], v[228:229], v[148:149]
	v_pk_add_f32 v[230:231], v[230:231], v[150:151]
	s_waitcnt vmcnt(12)
	v_pk_add_f32 v[216:217], v[216:217], v[0:1]
	v_pk_add_f32 v[218:219], v[218:219], v[2:3]
	v_pk_add_f32 v[220:221], v[220:221], v[4:5]
	v_pk_add_f32 v[222:223], v[222:223], v[6:7]
	v_pk_add_f32 v[224:225], v[224:225], v[8:9]
	v_pk_add_f32 v[226:227], v[226:227], v[10:11]
	v_pk_add_f32 v[228:229], v[228:229], v[12:13]
	v_pk_add_f32 v[230:231], v[230:231], v[14:15]
	s_waitcnt vmcnt(8)
	v_pk_add_f32 v[216:217], v[216:217], v[16:17]
	v_pk_add_f32 v[218:219], v[218:219], v[18:19]
	v_pk_add_f32 v[220:221], v[220:221], v[20:21]
	v_pk_add_f32 v[222:223], v[222:223], v[22:23]
	v_pk_add_f32 v[224:225], v[224:225], v[24:25]
	v_pk_add_f32 v[226:227], v[226:227], v[26:27]
	v_pk_add_f32 v[228:229], v[228:229], v[28:29]
	v_pk_add_f32 v[230:231], v[230:231], v[30:31]
	s_waitcnt vmcnt(4)
	v_pk_add_f32 v[216:217], v[216:217], v[32:33]
	v_pk_add_f32 v[218:219], v[218:219], v[34:35]
	v_pk_add_f32 v[220:221], v[220:221], v[36:37]
	v_pk_add_f32 v[222:223], v[222:223], v[38:39]
	v_pk_add_f32 v[224:225], v[224:225], v[40:41]
	v_pk_add_f32 v[226:227], v[226:227], v[42:43]
	v_pk_add_f32 v[228:229], v[228:229], v[44:45]
	v_pk_add_f32 v[230:231], v[230:231], v[46:47]
	s_waitcnt vmcnt(0)
	v_pk_add_f32 v[216:217], v[216:217], v[48:49]
	v_pk_add_f32 v[218:219], v[218:219], v[50:51]
	v_pk_add_f32 v[220:221], v[220:221], v[52:53]
	v_pk_add_f32 v[222:223], v[222:223], v[54:55]
	v_pk_add_f32 v[224:225], v[224:225], v[56:57]
	v_pk_add_f32 v[226:227], v[226:227], v[58:59]
	v_pk_add_f32 v[228:229], v[228:229], v[60:61]
	v_pk_add_f32 v[230:231], v[230:231], v[62:63]
	v_pk_mul_f32 v[252:253], v[216:217], v[216:217]
	v_pk_mul_f32 v[254:255], v[218:219], v[218:219]
	v_pk_fma_f32 v[252:253], v[220:221], v[220:221], v[252:253]
	v_pk_fma_f32 v[254:255], v[222:223], v[222:223], v[254:255]
	v_pk_fma_f32 v[252:253], v[224:225], v[224:225], v[252:253]
	v_pk_fma_f32 v[254:255], v[226:227], v[226:227], v[254:255]
	v_pk_fma_f32 v[252:253], v[228:229], v[228:229], v[252:253]
	v_pk_fma_f32 v[254:255], v[230:231], v[230:231], v[254:255]
	v_pk_add_f32 v[252:253], v[252:253], v[254:255]
	s_nop 0
	v_add_f32_e32 v183, v252, v253
	s_nop 1
	v_add_f32_dpp v183, v183, v183 quad_perm:[1,0,3,2] row_mask:0xf bank_mask:0xf bound_ctrl:1
	s_nop 1
	v_add_f32_dpp v183, v183, v183 quad_perm:[2,3,0,1] row_mask:0xf bank_mask:0xf bound_ctrl:1
	s_nop 1
	v_add_f32_dpp v183, v183, v183 row_half_mirror row_mask:0xf bank_mask:0xf bound_ctrl:1
	s_nop 1
	v_add_f32_dpp v183, v183, v183 row_mirror row_mask:0xf bank_mask:0xf bound_ctrl:1
	s_nop 1
	v_readlane_b32 s98, v183, 0
	v_readlane_b32 s99, v183, 16
	v_readlane_b32 s100, v183, 32
	v_readlane_b32 s101, v183, 48
	s_nop 1
	v_mov_b32_e32 v183, s98
	v_add_f32_e32 v183, s99, v183
	v_add_f32_e32 v183, s100, v183
	v_add_f32_e32 v183, s101, v183
	v_fmamk_f32 v183, v183, 0x3a800000, v182
	v_cmp_gt_f32_e32 vcc, 0x800000, v183
	v_mul_f32_e32 v181, 0x4b800000, v183
	s_nop 1
	v_cndmask_b32_e32 v183, v183, v181, vcc
	v_rsq_f32_e32 v183, v183
	s_nop 0
	v_mul_f32_e32 v181, 0x45800000, v183
	v_cndmask_b32_e32 v184, v183, v181, vcc
	v_mov_b32_e32 v185, v184
	v_pk_mul_f32 v[216:217], v[216:217], v[184:185]
	v_pk_mul_f32 v[218:219], v[218:219], v[184:185]
	v_pk_mul_f32 v[220:221], v[220:221], v[184:185]
	v_pk_mul_f32 v[222:223], v[222:223], v[184:185]
	v_pk_mul_f32 v[224:225], v[224:225], v[184:185]
	v_pk_mul_f32 v[226:227], v[226:227], v[184:185]
	v_pk_mul_f32 v[228:229], v[228:229], v[184:185]
	v_pk_mul_f32 v[230:231], v[230:231], v[184:185]
	v_pk_fma_f32 v[194:195], v[216:217], v[160:161], v[194:195]
	v_pk_fma_f32 v[196:197], v[218:219], v[162:163], v[196:197]
	v_pk_fma_f32 v[198:199], v[220:221], v[164:165], v[198:199]
	v_pk_fma_f32 v[200:201], v[222:223], v[166:167], v[200:201]
	v_pk_fma_f32 v[202:203], v[224:225], v[168:169], v[202:203]
	v_pk_fma_f32 v[204:205], v[226:227], v[170:171], v[204:205]
	v_pk_fma_f32 v[206:207], v[228:229], v[172:173], v[206:207]
	v_pk_fma_f32 v[208:209], v[230:231], v[174:175], v[208:209]
	v_pk_mul_f32 v[252:253], v[194:195], v[194:195]
	v_pk_mul_f32 v[254:255], v[196:197], v[196:197]
	v_pk_fma_f32 v[252:253], v[198:199], v[198:199], v[252:253]
	v_pk_fma_f32 v[254:255], v[200:201], v[200:201], v[254:255]
	v_pk_fma_f32 v[252:253], v[202:203], v[202:203], v[252:253]
	v_pk_fma_f32 v[254:255], v[204:205], v[204:205], v[254:255]
	v_pk_fma_f32 v[252:253], v[206:207], v[206:207], v[252:253]
	v_pk_fma_f32 v[254:255], v[208:209], v[208:209], v[254:255]
	v_pk_add_f32 v[252:253], v[252:253], v[254:255]
	s_nop 0
	v_add_f32_e32 v183, v252, v253
	s_nop 1
	v_add_f32_dpp v183, v183, v183 quad_perm:[1,0,3,2] row_mask:0xf bank_mask:0xf bound_ctrl:1
	s_nop 1
	v_add_f32_dpp v183, v183, v183 quad_perm:[2,3,0,1] row_mask:0xf bank_mask:0xf bound_ctrl:1
	s_nop 1
	v_add_f32_dpp v183, v183, v183 row_half_mirror row_mask:0xf bank_mask:0xf bound_ctrl:1
	s_nop 1
	v_add_f32_dpp v183, v183, v183 row_mirror row_mask:0xf bank_mask:0xf bound_ctrl:1
	s_nop 1
	v_readlane_b32 s98, v183, 0
	v_readlane_b32 s99, v183, 16
	v_readlane_b32 s100, v183, 32
	v_readlane_b32 s101, v183, 48
	s_nop 1
	v_mov_b32_e32 v183, s98
	v_add_f32_e32 v183, s99, v183
	v_add_f32_e32 v183, s100, v183
	v_add_f32_e32 v183, s101, v183
	v_fmamk_f32 v183, v183, 0x3a800000, v182
	v_cmp_gt_f32_e32 vcc, 0x800000, v183
	v_mul_f32_e32 v181, 0x4b800000, v183
	s_nop 1
	v_cndmask_b32_e32 v183, v183, v181, vcc
	v_rsq_f32_e32 v183, v183
	s_nop 0
	v_mul_f32_e32 v181, 0x45800000, v183
	v_cndmask_b32_e32 v184, v183, v181, vcc
	v_mov_b32_e32 v185, v184
	v_pk_mul_f32 v[194:195], v[194:195], v[184:185]
	v_pk_mul_f32 v[196:197], v[196:197], v[184:185]
	v_pk_mul_f32 v[198:199], v[198:199], v[184:185]
	v_pk_mul_f32 v[200:201], v[200:201], v[184:185]
	v_pk_mul_f32 v[202:203], v[202:203], v[184:185]
	v_pk_mul_f32 v[204:205], v[204:205], v[184:185]
	v_pk_mul_f32 v[206:207], v[206:207], v[184:185]
	v_pk_mul_f32 v[208:209], v[208:209], v[184:185]
	v_pk_mul_f32 v[194:195], v[194:195], v[236:237]
	v_pk_mul_f32 v[196:197], v[196:197], v[238:239]
	v_pk_mul_f32 v[198:199], v[198:199], v[240:241]
	v_pk_mul_f32 v[200:201], v[200:201], v[242:243]
	v_pk_mul_f32 v[202:203], v[202:203], v[244:245]
	v_pk_mul_f32 v[204:205], v[204:205], v[246:247]
	v_pk_mul_f32 v[206:207], v[206:207], v[248:249]
	v_pk_mul_f32 v[208:209], v[208:209], v[250:251]
	v_add_u32_e32 v181, 0x4000000, v211
	global_store_dwordx4 v181, v[194:197], s[76:77]
	global_store_dwordx4 v181, v[198:201], s[76:77] offset:16
	global_store_dwordx4 v181, v[202:205], s[76:77] offset:2048
	global_store_dwordx4 v181, v[206:209], s[76:77] offset:2064
	s_nop 1
